# epilogues: 697 dead zero-initialisations of full-mask quad_perm DPP destinations replaced by s_nop 0 (one issue cycle instead of a 4-cycle VALU op; hazard spacing unchanged)
# speedup vs baseline: 1.0083x; 1.0083x over previous
; __device__ __forceinline__ u32x4 pack8f(f32x4 a, f32x4 b) { u32x4 w; w.x = cvt_pk_bf16(a[0], a[1]); w.y = cvt_pk_bf16(a[2], a[3]); w.z = cvt_pk_bf16(b[0], b[1]); w.w = cvt_pk_bf16(b[2], b[3]); return w; }
; #define EPI_OPAQUE(x) asm volatile("" : "+v"(x))
;     __device__ __forceinline__ void operator()(const f32x4 (&acc)[2][2][4][2], const Unit& u, int wr, int wc, int fr, int fq, const EpiCtx& X) const {
;     ...
;             char* base = (char*)(QKV + (size_t)u.pm * BM * QKV0_LD + (u.pn * BM - W_SSM));
;             unsigned lo = (unsigned)((wr * 64 + fe) * QKV0_LD + wc * 64 + o32 + 8 * fq) * 2u; EPI_OPAQUE(lo);
;             EPI_PIECES({ const unsigned off = lo + (unsigned)(rl * QKV0_LD) * 2u; *(u32x4*)(base + off) = pack8f(p1a, p1b); *(u32x4*)(base + off + QKV0_LD * 2) = pack8f(p2a, p2b); })
.LBB0_172:
	s_mul_i32 s17, s22, 0x300000
	s_mul_hi_i32 s15, s22, 0x300000
	s_add_u32 s17, s12, s17
	s_addc_u32 s15, s13, s15
	s_lshl_b32 s24, s23, 9
	s_add_u32 s17, s17, s24
	s_addc_u32 s15, s15, 0
	s_add_u32 s24, s17, 0x3f7ff000
	s_nop 0
	s_nop 0
	s_addc_u32 s25, s15, 0
	v_mov_b32_e32 v136, v147
	v_mov_b32_dpp v220, v213 quad_perm:[1,0,3,2] row_mask:0xf bank_mask:0xf
	v_mov_b32_dpp v221, v211 quad_perm:[1,0,3,2] row_mask:0xf bank_mask:0xf
	s_nop 0
	s_nop 0
	s_nop 0
	s_nop 0
	s_nop 0
	s_nop 0
	v_cndmask_b32_e64 v230, v220, v120, s[6:7]
	v_cndmask_b32_e64 v231, v221, v121, s[6:7]
	v_cndmask_b32_e64 v236, v112, v220, s[6:7]
	v_cndmask_b32_e64 v237, v113, v221, s[6:7]
	v_lshl_add_u64 v[220:221], s[24:25], 0, v[136:137]
	v_mov_b32_dpp v216, v215 quad_perm:[1,0,3,2] row_mask:0xf bank_mask:0xf
	v_mov_b32_dpp v217, v214 quad_perm:[1,0,3,2] row_mask:0xf bank_mask:0xf
	v_mov_b32_dpp v218, v212 quad_perm:[1,0,3,2] row_mask:0xf bank_mask:0xf
	v_mov_b32_dpp v219, v210 quad_perm:[1,0,3,2] row_mask:0xf bank_mask:0xf
	v_mov_b32_dpp v222, v209 quad_perm:[1,0,3,2] row_mask:0xf bank_mask:0xf
	v_mov_b32_dpp v223, v208 quad_perm:[1,0,3,2] row_mask:0xf bank_mask:0xf
	v_add_co_u32_e32 v220, vcc, s60, v220
	v_cndmask_b32_e64 v224, v218, v126, s[6:7]
	v_cndmask_b32_e64 v225, v219, v127, s[6:7]
	v_cndmask_b32_e64 v226, v216, v124, s[6:7]
	v_cndmask_b32_e64 v227, v217, v125, s[6:7]
	v_cndmask_b32_e64 v228, v222, v122, s[6:7]
	v_cndmask_b32_e64 v229, v223, v123, s[6:7]
	v_cndmask_b32_e64 v232, v118, v218, s[6:7]
	v_cndmask_b32_e64 v233, v119, v219, s[6:7]
	v_cndmask_b32_e64 v234, v116, v216, s[6:7]
	v_cndmask_b32_e64 v235, v117, v217, s[6:7]
	v_cvt_pk_bf16_f32 v216, v226, v227
	v_cvt_pk_bf16_f32 v217, v224, v225
	v_cvt_pk_bf16_f32 v218, v230, v231
	v_cvt_pk_bf16_f32 v219, v228, v229
	v_addc_co_u32_e32 v221, vcc, 0, v221, vcc
	v_cndmask_b32_e64 v222, v114, v222, s[6:7]
	v_cndmask_b32_e64 v223, v115, v223, s[6:7]
	global_store_dwordx4 v136, v[216:219], s[24:25]
	s_nop 1
	v_cvt_pk_bf16_f32 v216, v234, v235
	v_cvt_pk_bf16_f32 v217, v232, v233
	v_cvt_pk_bf16_f32 v218, v236, v237
	v_cvt_pk_bf16_f32 v219, v222, v223
	global_store_dwordx4 v[220:221], v[216:219], off
	v_mov_b32_e32 v220, v137
	v_mov_b32_e32 v221, v137
	v_mov_b32_e32 v222, v137
	v_mov_b32_dpp v220, v205 quad_perm:[1,0,3,2] row_mask:0xf bank_mask:0xf
	v_mov_b32_dpp v221, v203 quad_perm:[1,0,3,2] row_mask:0xf bank_mask:0xf
	v_mov_b32_e32 v223, v137
	v_mov_b32_e32 v216, v137
	v_mov_b32_e32 v217, v137
	v_mov_b32_e32 v218, v137
	v_mov_b32_e32 v219, v137
	v_mov_b32_dpp v222, v201 quad_perm:[1,0,3,2] row_mask:0xf bank_mask:0xf
	v_mov_b32_dpp v223, v200 quad_perm:[1,0,3,2] row_mask:0xf bank_mask:0xf
	v_cndmask_b32_e64 v230, v220, v104, s[6:7]
	v_cndmask_b32_e64 v231, v221, v105, s[6:7]
	v_cndmask_b32_e64 v238, v96, v220, s[6:7]
	v_cndmask_b32_e64 v239, v97, v221, s[6:7]
	v_add_u32_e32 v220, 0x30000, v136
	v_mov_b32_e32 v221, v137
	v_mov_b32_dpp v216, v207 quad_perm:[1,0,3,2] row_mask:0xf bank_mask:0xf
	v_mov_b32_dpp v217, v206 quad_perm:[1,0,3,2] row_mask:0xf bank_mask:0xf
	v_mov_b32_dpp v218, v204 quad_perm:[1,0,3,2] row_mask:0xf bank_mask:0xf
	v_mov_b32_dpp v219, v202 quad_perm:[1,0,3,2] row_mask:0xf bank_mask:0xf
	v_cndmask_b32_e64 v228, v222, v106, s[6:7]
	v_cndmask_b32_e64 v229, v223, v107, s[6:7]
	v_cndmask_b32_e64 v236, v98, v222, s[6:7]
	v_cndmask_b32_e64 v237, v99, v223, s[6:7]
	v_lshl_add_u64 v[222:223], s[24:25], 0, v[220:221]
	v_cndmask_b32_e64 v224, v218, v110, s[6:7]
	v_cndmask_b32_e64 v225, v219, v111, s[6:7]
	v_cndmask_b32_e64 v226, v216, v108, s[6:7]
	v_cndmask_b32_e64 v227, v217, v109, s[6:7]
	v_cndmask_b32_e64 v232, v102, v218, s[6:7]
	v_cndmask_b32_e64 v233, v103, v219, s[6:7]
	v_cndmask_b32_e64 v234, v100, v216, s[6:7]
	v_cndmask_b32_e64 v235, v101, v217, s[6:7]
	v_cvt_pk_bf16_f32 v216, v226, v227
	v_cvt_pk_bf16_f32 v217, v224, v225
	v_cvt_pk_bf16_f32 v218, v230, v231
	v_cvt_pk_bf16_f32 v219, v228, v229
	global_store_dwordx4 v220, v[216:219], s[24:25]
	v_add_co_u32_e32 v220, vcc, s60, v222
	s_nop 0
	v_cvt_pk_bf16_f32 v216, v234, v235
	v_cvt_pk_bf16_f32 v217, v232, v233
	v_cvt_pk_bf16_f32 v218, v238, v239
	v_cvt_pk_bf16_f32 v219, v236, v237
	s_nop 0
	v_addc_co_u32_e32 v221, vcc, 0, v223, vcc
	global_store_dwordx4 v[220:221], v[216:219], off
	v_mov_b32_e32 v220, v137
	v_mov_b32_e32 v221, v137
	v_mov_b32_e32 v222, v137
	v_mov_b32_dpp v220, v197 quad_perm:[1,0,3,2] row_mask:0xf bank_mask:0xf
	v_mov_b32_dpp v221, v195 quad_perm:[1,0,3,2] row_mask:0xf bank_mask:0xf
	v_mov_b32_e32 v223, v137
	v_mov_b32_e32 v216, v137
	v_mov_b32_e32 v217, v137
	v_mov_b32_e32 v218, v137
	v_mov_b32_e32 v219, v137
	v_mov_b32_dpp v222, v193 quad_perm:[1,0,3,2] row_mask:0xf bank_mask:0xf
	v_mov_b32_dpp v223, v192 quad_perm:[1,0,3,2] row_mask:0xf bank_mask:0xf
	v_cndmask_b32_e64 v230, v220, v88, s[6:7]
	v_cndmask_b32_e64 v231, v221, v89, s[6:7]
	v_cndmask_b32_e64 v238, v80, v220, s[6:7]
	v_cndmask_b32_e64 v239, v81, v221, s[6:7]
	v_add_u32_e32 v220, 0x60000, v136
	v_mov_b32_e32 v221, v137
	v_mov_b32_dpp v216, v199 quad_perm:[1,0,3,2] row_mask:0xf bank_mask:0xf
	v_mov_b32_dpp v217, v198 quad_perm:[1,0,3,2] row_mask:0xf bank_mask:0xf
	v_mov_b32_dpp v218, v196 quad_perm:[1,0,3,2] row_mask:0xf bank_mask:0xf
	v_mov_b32_dpp v219, v194 quad_perm:[1,0,3,2] row_mask:0xf bank_mask:0xf
	v_cndmask_b32_e64 v228, v222, v90, s[6:7]
	v_cndmask_b32_e64 v229, v223, v91, s[6:7]
	v_cndmask_b32_e64 v236, v82, v222, s[6:7]
	v_cndmask_b32_e64 v237, v83, v223, s[6:7]
	v_lshl_add_u64 v[222:223], s[24:25], 0, v[220:221]
	v_cndmask_b32_e64 v224, v218, v94, s[6:7]
	v_cndmask_b32_e64 v225, v219, v95, s[6:7]
	v_cndmask_b32_e64 v226, v216, v92, s[6:7]
; __device__ __forceinline__ u32x4 pack8f(f32x4 a, f32x4 b) { u32x4 w; w.x = cvt_pk_bf16(a[0], a[1]); w.y = cvt_pk_bf16(a[2], a[3]); w.z = cvt_pk_bf16(b[0], b[1]); w.w = cvt_pk_bf16(b[2], b[3]); return w; }
; #define EPI_OPAQUE(x) asm volatile("" : "+v"(x))
; __device__ __forceinline__ float dpp_x1(float x) { return __builtin_bit_cast(float, __builtin_amdgcn_update_dpp(0, __builtin_bit_cast(int, x), 0xB1, 0xF, 0xF, false)); }
; __device__ __forceinline__ f32x4 dpp_swap1(f32x4 v) { f32x4 r; r[0] = dpp_x1(v[0]); r[1] = dpp_x1(v[1]); r[2] = dpp_x1(v[2]); r[3] = dpp_x1(v[3]); return r; }
;     __device__ __forceinline__ void operator()(const f32x4 (&acc)[2][2][4][2], const Unit& u, int wr, int wc, int fr, int fq, const EpiCtx& X) const {
;     ...
;             char* base = (char*)(QKV + (size_t)u.pm * BM * QKV0_LD + (u.pn * BM - W_SSM));
;             unsigned lo = (unsigned)((wr * 64 + fe) * QKV0_LD + wc * 64 + o32 + 8 * fq) * 2u; EPI_OPAQUE(lo);
;             EPI_PIECES({ const unsigned off = lo + (unsigned)(rl * QKV0_LD) * 2u; *(u32x4*)(base + off) = pack8f(p1a, p1b); *(u32x4*)(base + off + QKV0_LD * 2) = pack8f(p2a, p2b); })
	v_cndmask_b32_e64 v227, v217, v93, s[6:7]
	v_cndmask_b32_e64 v232, v86, v218, s[6:7]
	v_cndmask_b32_e64 v233, v87, v219, s[6:7]
	v_cndmask_b32_e64 v234, v84, v216, s[6:7]
	v_cndmask_b32_e64 v235, v85, v217, s[6:7]
	v_cvt_pk_bf16_f32 v216, v226, v227
	v_cvt_pk_bf16_f32 v217, v224, v225
	v_cvt_pk_bf16_f32 v218, v230, v231
	v_cvt_pk_bf16_f32 v219, v228, v229
	global_store_dwordx4 v220, v[216:219], s[24:25]
	v_add_co_u32_e32 v220, vcc, s60, v222
	s_nop 0
	v_cvt_pk_bf16_f32 v216, v234, v235
	v_cvt_pk_bf16_f32 v217, v232, v233
	v_cvt_pk_bf16_f32 v218, v238, v239
	v_cvt_pk_bf16_f32 v219, v236, v237
	s_nop 0
	v_addc_co_u32_e32 v221, vcc, 0, v223, vcc
	global_store_dwordx4 v[220:221], v[216:219], off
	v_mov_b32_e32 v220, v137
	v_mov_b32_e32 v221, v137
	v_mov_b32_e32 v222, v137
	v_mov_b32_dpp v220, v189 quad_perm:[1,0,3,2] row_mask:0xf bank_mask:0xf
	v_mov_b32_dpp v221, v187 quad_perm:[1,0,3,2] row_mask:0xf bank_mask:0xf
	v_mov_b32_e32 v223, v137
	v_mov_b32_e32 v216, v137
	v_mov_b32_e32 v217, v137
	v_mov_b32_e32 v218, v137
	v_mov_b32_e32 v219, v137
	v_mov_b32_dpp v222, v185 quad_perm:[1,0,3,2] row_mask:0xf bank_mask:0xf
	v_mov_b32_dpp v223, v184 quad_perm:[1,0,3,2] row_mask:0xf bank_mask:0xf
	v_cndmask_b32_e64 v230, v220, v72, s[6:7]
	v_cndmask_b32_e64 v231, v221, v73, s[6:7]
	v_cndmask_b32_e64 v238, v64, v220, s[6:7]
	v_cndmask_b32_e64 v239, v65, v221, s[6:7]
	v_add_u32_e32 v220, 0x90000, v136
	v_mov_b32_e32 v221, v137
	v_mov_b32_dpp v216, v191 quad_perm:[1,0,3,2] row_mask:0xf bank_mask:0xf
	v_mov_b32_dpp v217, v190 quad_perm:[1,0,3,2] row_mask:0xf bank_mask:0xf
	v_mov_b32_dpp v218, v188 quad_perm:[1,0,3,2] row_mask:0xf bank_mask:0xf
	v_mov_b32_dpp v219, v186 quad_perm:[1,0,3,2] row_mask:0xf bank_mask:0xf
	v_cndmask_b32_e64 v228, v222, v74, s[6:7]
	v_cndmask_b32_e64 v229, v223, v75, s[6:7]
	v_cndmask_b32_e64 v236, v66, v222, s[6:7]
	v_cndmask_b32_e64 v237, v67, v223, s[6:7]
	v_lshl_add_u64 v[222:223], s[24:25], 0, v[220:221]
	v_cndmask_b32_e64 v224, v218, v78, s[6:7]
	v_cndmask_b32_e64 v225, v219, v79, s[6:7]
	v_cndmask_b32_e64 v226, v216, v76, s[6:7]
	v_cndmask_b32_e64 v227, v217, v77, s[6:7]
	v_cndmask_b32_e64 v232, v70, v218, s[6:7]
	v_cndmask_b32_e64 v233, v71, v219, s[6:7]
	v_cndmask_b32_e64 v234, v68, v216, s[6:7]
	v_cndmask_b32_e64 v235, v69, v217, s[6:7]
	v_cvt_pk_bf16_f32 v216, v226, v227
	v_cvt_pk_bf16_f32 v217, v224, v225
	v_cvt_pk_bf16_f32 v218, v230, v231
	v_cvt_pk_bf16_f32 v219, v228, v229
	global_store_dwordx4 v220, v[216:219], s[24:25]
	v_add_co_u32_e32 v220, vcc, s60, v222
	s_nop 0
	v_cvt_pk_bf16_f32 v216, v234, v235
	v_cvt_pk_bf16_f32 v217, v232, v233
	v_cvt_pk_bf16_f32 v218, v238, v239
	v_cvt_pk_bf16_f32 v219, v236, v237
	s_nop 0
	v_addc_co_u32_e32 v221, vcc, 0, v223, vcc
	global_store_dwordx4 v[220:221], v[216:219], off
	v_mov_b32_e32 v220, v137
	v_mov_b32_e32 v221, v137
	v_mov_b32_e32 v222, v137
	v_mov_b32_dpp v220, v181 quad_perm:[1,0,3,2] row_mask:0xf bank_mask:0xf
	v_mov_b32_dpp v221, v179 quad_perm:[1,0,3,2] row_mask:0xf bank_mask:0xf
	v_mov_b32_e32 v223, v137
	v_mov_b32_e32 v216, v137
	v_mov_b32_e32 v217, v137
	v_mov_b32_e32 v218, v137
	v_mov_b32_e32 v219, v137
	v_mov_b32_dpp v222, v177 quad_perm:[1,0,3,2] row_mask:0xf bank_mask:0xf
	v_mov_b32_dpp v223, v176 quad_perm:[1,0,3,2] row_mask:0xf bank_mask:0xf
	v_cndmask_b32_e64 v230, v220, v56, s[6:7]
	v_cndmask_b32_e64 v231, v221, v57, s[6:7]
	v_cndmask_b32_e64 v238, v48, v220, s[6:7]
	v_cndmask_b32_e64 v239, v49, v221, s[6:7]
	v_add_u32_e32 v220, 0x180000, v136
	v_mov_b32_e32 v221, v137
	v_mov_b32_dpp v216, v183 quad_perm:[1,0,3,2] row_mask:0xf bank_mask:0xf
	v_mov_b32_dpp v217, v182 quad_perm:[1,0,3,2] row_mask:0xf bank_mask:0xf
	v_mov_b32_dpp v218, v180 quad_perm:[1,0,3,2] row_mask:0xf bank_mask:0xf
	v_mov_b32_dpp v219, v178 quad_perm:[1,0,3,2] row_mask:0xf bank_mask:0xf
	v_cndmask_b32_e64 v228, v222, v58, s[6:7]
	v_cndmask_b32_e64 v229, v223, v59, s[6:7]
	v_cndmask_b32_e64 v236, v50, v222, s[6:7]
	v_cndmask_b32_e64 v237, v51, v223, s[6:7]
	v_lshl_add_u64 v[222:223], s[24:25], 0, v[220:221]
	v_cndmask_b32_e64 v224, v218, v62, s[6:7]
	v_cndmask_b32_e64 v225, v219, v63, s[6:7]
	v_cndmask_b32_e64 v226, v216, v60, s[6:7]
	v_cndmask_b32_e64 v227, v217, v61, s[6:7]
	v_cndmask_b32_e64 v232, v54, v218, s[6:7]
	v_cndmask_b32_e64 v233, v55, v219, s[6:7]
	v_cndmask_b32_e64 v234, v52, v216, s[6:7]
	v_cndmask_b32_e64 v235, v53, v217, s[6:7]
	v_cvt_pk_bf16_f32 v216, v226, v227
	v_cvt_pk_bf16_f32 v217, v224, v225
	v_cvt_pk_bf16_f32 v218, v230, v231
	v_cvt_pk_bf16_f32 v219, v228, v229
	global_store_dwordx4 v220, v[216:219], s[24:25]
	v_add_co_u32_e32 v220, vcc, s60, v222
	s_nop 0
	v_cvt_pk_bf16_f32 v216, v234, v235
	v_cvt_pk_bf16_f32 v217, v232, v233
	v_cvt_pk_bf16_f32 v218, v238, v239
	v_cvt_pk_bf16_f32 v219, v236, v237
	s_nop 0
	v_addc_co_u32_e32 v221, vcc, 0, v223, vcc
	global_store_dwordx4 v[220:221], v[216:219], off
	v_mov_b32_e32 v220, v137
	v_mov_b32_e32 v221, v137
	v_mov_b32_e32 v222, v137
	v_mov_b32_dpp v220, v173 quad_perm:[1,0,3,2] row_mask:0xf bank_mask:0xf
	v_mov_b32_dpp v221, v171 quad_perm:[1,0,3,2] row_mask:0xf bank_mask:0xf
	v_mov_b32_e32 v223, v137
	v_mov_b32_e32 v216, v137
	v_mov_b32_e32 v217, v137
	v_mov_b32_e32 v218, v137
	v_mov_b32_e32 v219, v137
	v_mov_b32_dpp v222, v169 quad_perm:[1,0,3,2] row_mask:0xf bank_mask:0xf
	v_mov_b32_dpp v223, v168 quad_perm:[1,0,3,2] row_mask:0xf bank_mask:0xf
	v_cndmask_b32_e64 v230, v220, v40, s[6:7]
	v_cndmask_b32_e64 v231, v221, v41, s[6:7]
	v_cndmask_b32_e64 v238, v32, v220, s[6:7]
	v_cndmask_b32_e64 v239, v33, v221, s[6:7]
	v_add_u32_e32 v220, 0x1b0000, v136
	v_mov_b32_e32 v221, v137
	v_mov_b32_dpp v216, v175 quad_perm:[1,0,3,2] row_mask:0xf bank_mask:0xf
; __device__ __forceinline__ u32x4 pack8f(f32x4 a, f32x4 b) { u32x4 w; w.x = cvt_pk_bf16(a[0], a[1]); w.y = cvt_pk_bf16(a[2], a[3]); w.z = cvt_pk_bf16(b[0], b[1]); w.w = cvt_pk_bf16(b[2], b[3]); return w; }
; #define EPI_OPAQUE(x) asm volatile("" : "+v"(x))
; __device__ __forceinline__ float dpp_x1(float x) { return __builtin_bit_cast(float, __builtin_amdgcn_update_dpp(0, __builtin_bit_cast(int, x), 0xB1, 0xF, 0xF, false)); }
; __device__ __forceinline__ f32x4 dpp_swap1(f32x4 v) { f32x4 r; r[0] = dpp_x1(v[0]); r[1] = dpp_x1(v[1]); r[2] = dpp_x1(v[2]); r[3] = dpp_x1(v[3]); return r; }
;     __device__ __forceinline__ void operator()(const f32x4 (&acc)[2][2][4][2], const Unit& u, int wr, int wc, int fr, int fq, const EpiCtx& X) const {
;     ...
;             char* base = (char*)(QKV + (size_t)u.pm * BM * QKV0_LD + (u.pn * BM - W_SSM));
;             unsigned lo = (unsigned)((wr * 64 + fe) * QKV0_LD + wc * 64 + o32 + 8 * fq) * 2u; EPI_OPAQUE(lo);
;             EPI_PIECES({ const unsigned off = lo + (unsigned)(rl * QKV0_LD) * 2u; *(u32x4*)(base + off) = pack8f(p1a, p1b); *(u32x4*)(base + off + QKV0_LD * 2) = pack8f(p2a, p2b); })
	v_mov_b32_dpp v217, v174 quad_perm:[1,0,3,2] row_mask:0xf bank_mask:0xf
	v_mov_b32_dpp v218, v172 quad_perm:[1,0,3,2] row_mask:0xf bank_mask:0xf
	v_mov_b32_dpp v219, v170 quad_perm:[1,0,3,2] row_mask:0xf bank_mask:0xf
	v_cndmask_b32_e64 v228, v222, v42, s[6:7]
	v_cndmask_b32_e64 v229, v223, v43, s[6:7]
	v_cndmask_b32_e64 v236, v34, v222, s[6:7]
	v_cndmask_b32_e64 v237, v35, v223, s[6:7]
	v_lshl_add_u64 v[222:223], s[24:25], 0, v[220:221]
	v_cndmask_b32_e64 v224, v218, v46, s[6:7]
	v_cndmask_b32_e64 v225, v219, v47, s[6:7]
	v_cndmask_b32_e64 v226, v216, v44, s[6:7]
	v_cndmask_b32_e64 v227, v217, v45, s[6:7]
	v_cndmask_b32_e64 v232, v38, v218, s[6:7]
	v_cndmask_b32_e64 v233, v39, v219, s[6:7]
	v_cndmask_b32_e64 v234, v36, v216, s[6:7]
	v_cndmask_b32_e64 v235, v37, v217, s[6:7]
	v_cvt_pk_bf16_f32 v216, v226, v227
	v_cvt_pk_bf16_f32 v217, v224, v225
	v_cvt_pk_bf16_f32 v218, v230, v231
	v_cvt_pk_bf16_f32 v219, v228, v229
	global_store_dwordx4 v220, v[216:219], s[24:25]
	v_add_co_u32_e32 v220, vcc, s60, v222
	s_nop 0
	v_cvt_pk_bf16_f32 v216, v234, v235
	v_cvt_pk_bf16_f32 v217, v232, v233
	v_cvt_pk_bf16_f32 v218, v238, v239
	v_cvt_pk_bf16_f32 v219, v236, v237
	s_nop 0
	v_addc_co_u32_e32 v221, vcc, 0, v223, vcc
	global_store_dwordx4 v[220:221], v[216:219], off
	v_mov_b32_e32 v220, v137
	v_mov_b32_e32 v221, v137
	v_mov_b32_e32 v222, v137
	v_mov_b32_dpp v220, v165 quad_perm:[1,0,3,2] row_mask:0xf bank_mask:0xf
	v_mov_b32_dpp v221, v163 quad_perm:[1,0,3,2] row_mask:0xf bank_mask:0xf
	v_mov_b32_e32 v223, v137
	v_mov_b32_e32 v216, v137
	v_mov_b32_e32 v217, v137
	v_mov_b32_e32 v218, v137
	v_mov_b32_e32 v219, v137
	v_mov_b32_dpp v222, v161 quad_perm:[1,0,3,2] row_mask:0xf bank_mask:0xf
	v_mov_b32_dpp v223, v160 quad_perm:[1,0,3,2] row_mask:0xf bank_mask:0xf
	v_cndmask_b32_e64 v230, v220, v24, s[6:7]
	v_cndmask_b32_e64 v231, v221, v25, s[6:7]
	v_cndmask_b32_e64 v238, v16, v220, s[6:7]
	v_cndmask_b32_e64 v239, v17, v221, s[6:7]
	v_add_u32_e32 v220, 0x1e0000, v136
	v_mov_b32_e32 v221, v137
	v_mov_b32_dpp v216, v167 quad_perm:[1,0,3,2] row_mask:0xf bank_mask:0xf
	v_mov_b32_dpp v217, v166 quad_perm:[1,0,3,2] row_mask:0xf bank_mask:0xf
	v_mov_b32_dpp v218, v164 quad_perm:[1,0,3,2] row_mask:0xf bank_mask:0xf
	v_mov_b32_dpp v219, v162 quad_perm:[1,0,3,2] row_mask:0xf bank_mask:0xf
	v_cndmask_b32_e64 v228, v222, v26, s[6:7]
	v_cndmask_b32_e64 v229, v223, v27, s[6:7]
	v_cndmask_b32_e64 v236, v18, v222, s[6:7]
	v_cndmask_b32_e64 v237, v19, v223, s[6:7]
	v_lshl_add_u64 v[222:223], s[24:25], 0, v[220:221]
	v_cndmask_b32_e64 v224, v218, v30, s[6:7]
	v_cndmask_b32_e64 v225, v219, v31, s[6:7]
	v_cndmask_b32_e64 v226, v216, v28, s[6:7]
	v_cndmask_b32_e64 v227, v217, v29, s[6:7]
	v_cndmask_b32_e64 v232, v22, v218, s[6:7]
	v_cndmask_b32_e64 v233, v23, v219, s[6:7]
	v_cndmask_b32_e64 v234, v20, v216, s[6:7]
	v_cndmask_b32_e64 v235, v21, v217, s[6:7]
	v_cvt_pk_bf16_f32 v216, v226, v227
	v_cvt_pk_bf16_f32 v217, v224, v225
	v_cvt_pk_bf16_f32 v218, v230, v231
	v_cvt_pk_bf16_f32 v219, v228, v229
	global_store_dwordx4 v220, v[216:219], s[24:25]
	v_add_co_u32_e32 v220, vcc, s60, v222
	s_nop 0
	v_cvt_pk_bf16_f32 v216, v234, v235
	v_cvt_pk_bf16_f32 v217, v232, v233
	v_cvt_pk_bf16_f32 v218, v238, v239
	v_cvt_pk_bf16_f32 v219, v236, v237
	s_nop 0
	v_addc_co_u32_e32 v221, vcc, 0, v223, vcc
	global_store_dwordx4 v[220:221], v[216:219], off
	v_mov_b32_e32 v220, v137
	v_mov_b32_e32 v221, v137
	v_add_u32_e32 v136, 0x210000, v136
	v_mov_b32_dpp v220, v157 quad_perm:[1,0,3,2] row_mask:0xf bank_mask:0xf
	v_mov_b32_dpp v221, v155 quad_perm:[1,0,3,2] row_mask:0xf bank_mask:0xf
	v_mov_b32_e32 v216, v137
	v_mov_b32_e32 v217, v137
	v_mov_b32_e32 v218, v137
	v_mov_b32_e32 v219, v137
	v_mov_b32_e32 v222, v137
	v_mov_b32_e32 v223, v137
	v_cndmask_b32_e64 v230, v220, v8, s[6:7]
	v_cndmask_b32_e64 v231, v221, v9, s[6:7]
	v_cndmask_b32_e64 v236, v0, v220, s[6:7]
	v_cndmask_b32_e64 v237, v1, v221, s[6:7]
	v_lshl_add_u64 v[220:221], s[24:25], 0, v[136:137]
	v_mov_b32_dpp v216, v159 quad_perm:[1,0,3,2] row_mask:0xf bank_mask:0xf
	v_mov_b32_dpp v217, v158 quad_perm:[1,0,3,2] row_mask:0xf bank_mask:0xf
	v_mov_b32_dpp v218, v156 quad_perm:[1,0,3,2] row_mask:0xf bank_mask:0xf
	v_mov_b32_dpp v219, v154 quad_perm:[1,0,3,2] row_mask:0xf bank_mask:0xf
	v_mov_b32_dpp v222, v153 quad_perm:[1,0,3,2] row_mask:0xf bank_mask:0xf
	v_mov_b32_dpp v223, v152 quad_perm:[1,0,3,2] row_mask:0xf bank_mask:0xf
	v_add_co_u32_e32 v220, vcc, 0x3000, v220
	v_cndmask_b32_e64 v224, v218, v14, s[6:7]
	v_cndmask_b32_e64 v225, v219, v15, s[6:7]
	v_cndmask_b32_e64 v226, v216, v12, s[6:7]
	v_cndmask_b32_e64 v227, v217, v13, s[6:7]
	v_cndmask_b32_e64 v228, v222, v10, s[6:7]
	v_cndmask_b32_e64 v229, v223, v11, s[6:7]
	v_cndmask_b32_e64 v232, v6, v218, s[6:7]
	v_cndmask_b32_e64 v233, v7, v219, s[6:7]
	v_cndmask_b32_e64 v234, v4, v216, s[6:7]
	v_cndmask_b32_e64 v235, v5, v217, s[6:7]
	v_cvt_pk_bf16_f32 v216, v226, v227
	v_cvt_pk_bf16_f32 v217, v224, v225
	v_cvt_pk_bf16_f32 v218, v230, v231
	v_cvt_pk_bf16_f32 v219, v228, v229
	v_addc_co_u32_e32 v221, vcc, 0, v221, vcc
	v_cndmask_b32_e64 v222, v2, v222, s[6:7]
	v_cndmask_b32_e64 v223, v3, v223, s[6:7]
	global_store_dwordx4 v136, v[216:219], s[24:25]
	s_nop 1
	v_cvt_pk_bf16_f32 v216, v234, v235
	v_cvt_pk_bf16_f32 v217, v232, v233
	v_cvt_pk_bf16_f32 v218, v236, v237
	v_cvt_pk_bf16_f32 v219, v222, v223
	global_store_dwordx4 v[220:221], v[216:219], off
	s_cbranch_execnz .LBB0_171
; __device__ __forceinline__ u32x4 pack8f(f32x4 a, f32x4 b) { u32x4 w; w.x = cvt_pk_bf16(a[0], a[1]); w.y = cvt_pk_bf16(a[2], a[3]); w.z = cvt_pk_bf16(b[0], b[1]); w.w = cvt_pk_bf16(b[2], b[3]); return w; }
; #define EPI_OPAQUE(x) asm volatile("" : "+v"(x))
; __device__ __forceinline__ float dpp_x1(float x) { return __builtin_bit_cast(float, __builtin_amdgcn_update_dpp(0, __builtin_bit_cast(int, x), 0xB1, 0xF, 0xF, false)); }
; __device__ __forceinline__ f32x4 dpp_swap1(f32x4 v) { f32x4 r; r[0] = dpp_x1(v[0]); r[1] = dpp_x1(v[1]); r[2] = dpp_x1(v[2]); r[3] = dpp_x1(v[3]); return r; }
;     __device__ __forceinline__ void operator()(const f32x4 (&acc)[2][2][4][2], const Unit& u, int wr, int wc, int fr, int fq, const EpiCtx& X) const {
;     ...
;         if (u.pn < 8) {
;             char* base = (char*)(UA + ((size_t)u.pn * 16 * 1024 + (size_t)u.pm * 16) * UA_LD);
;             unsigned lo = (unsigned)(((wc * 4 + (fr & 1) * 2 + (fq >> 1)) * 1024 + wr * 4) * UA_LD + fe * 16 + 8 * (fq & 1)) * 2u; EPI_OPAQUE(lo);
;             EPI_PIECES({ const unsigned off = lo + (unsigned)((rl >> 4) * UA_LD) * 2u; *(u32x4*)(base + off) = pack8f(p1a, p1b); *(u32x4*)(base + off + 32) = pack8f(p2a, p2b); })
.LBB0_173:
	s_nop 0
	s_nop 0
	s_mul_i32 s17, s23, 0xc00000
	s_mul_hi_i32 s15, s23, 0xc00000
	v_mov_b32_dpp v216, v215 quad_perm:[1,0,3,2] row_mask:0xf bank_mask:0xf
	s_nop 0
	s_add_u32 s17, s56, s17
	s_mul_hi_i32 s23, s22, 0x3000
	v_mov_b32_dpp v215, v214 quad_perm:[1,0,3,2] row_mask:0xf bank_mask:0xf
	s_nop 0
	s_mulk_i32 s22, 0x3000
	s_addc_u32 s15, s57, s15
	v_mov_b32_dpp v214, v212 quad_perm:[1,0,3,2] row_mask:0xf bank_mask:0xf
	s_nop 0
	s_add_u32 s22, s17, s22
	v_mov_b32_e32 v136, v148
	v_mov_b32_dpp v212, v210 quad_perm:[1,0,3,2] row_mask:0xf bank_mask:0xf
	s_nop 0
	s_addc_u32 s23, s15, s23
	v_cndmask_b32_e64 v126, v214, v126, s[6:7]
	v_mov_b32_dpp v210, v213 quad_perm:[1,0,3,2] row_mask:0xf bank_mask:0xf
	s_nop 0
	v_cndmask_b32_e64 v127, v212, v127, s[6:7]
	v_cndmask_b32_e64 v124, v216, v124, s[6:7]
	v_mov_b32_dpp v213, v211 quad_perm:[1,0,3,2] row_mask:0xf bank_mask:0xf
	s_nop 0
	v_cndmask_b32_e64 v125, v215, v125, s[6:7]
	v_cndmask_b32_e64 v120, v210, v120, s[6:7]
	v_mov_b32_dpp v211, v209 quad_perm:[1,0,3,2] row_mask:0xf bank_mask:0xf
	s_nop 0
	v_cndmask_b32_e64 v122, v211, v122, s[6:7]
	v_cndmask_b32_e64 v121, v213, v121, s[6:7]
	v_mov_b32_dpp v209, v208 quad_perm:[1,0,3,2] row_mask:0xf bank_mask:0xf
	v_cndmask_b32_e64 v123, v209, v123, s[6:7]
	v_cndmask_b32_e64 v208, v114, v211, s[6:7]
	v_cndmask_b32_e64 v209, v115, v209, s[6:7]
	v_cndmask_b32_e64 v210, v112, v210, s[6:7]
	v_cndmask_b32_e64 v211, v113, v213, s[6:7]
	v_cvt_pk_bf16_f32 v112, v124, v125
	v_cvt_pk_bf16_f32 v113, v126, v127
	v_cvt_pk_bf16_f32 v114, v120, v121
	v_cvt_pk_bf16_f32 v115, v122, v123
	v_cndmask_b32_e64 v118, v118, v214, s[6:7]
	v_cndmask_b32_e64 v119, v119, v212, s[6:7]
	v_cndmask_b32_e64 v116, v116, v216, s[6:7]
	v_cndmask_b32_e64 v117, v117, v215, s[6:7]
	global_store_dwordx4 v136, v[112:115], s[22:23]
	s_nop 1
	v_cvt_pk_bf16_f32 v112, v116, v117
	v_cvt_pk_bf16_f32 v113, v118, v119
	v_cvt_pk_bf16_f32 v114, v210, v211
	v_cvt_pk_bf16_f32 v115, v208, v209
	global_store_dwordx4 v136, v[112:115], s[22:23] offset:32
	s_nop 0
	s_nop 0
	s_nop 0
	s_nop 0
	s_nop 0
	s_nop 0
	s_nop 0
	s_nop 0
	v_mov_b32_dpp v112, v207 quad_perm:[1,0,3,2] row_mask:0xf bank_mask:0xf
	v_mov_b32_dpp v113, v206 quad_perm:[1,0,3,2] row_mask:0xf bank_mask:0xf
	v_mov_b32_dpp v114, v204 quad_perm:[1,0,3,2] row_mask:0xf bank_mask:0xf
	v_mov_b32_dpp v115, v202 quad_perm:[1,0,3,2] row_mask:0xf bank_mask:0xf
	v_mov_b32_dpp v116, v205 quad_perm:[1,0,3,2] row_mask:0xf bank_mask:0xf
	v_mov_b32_dpp v117, v203 quad_perm:[1,0,3,2] row_mask:0xf bank_mask:0xf
	v_mov_b32_dpp v118, v201 quad_perm:[1,0,3,2] row_mask:0xf bank_mask:0xf
	v_mov_b32_dpp v119, v200 quad_perm:[1,0,3,2] row_mask:0xf bank_mask:0xf
	v_cndmask_b32_e64 v110, v114, v110, s[6:7]
	v_cndmask_b32_e64 v111, v115, v111, s[6:7]
	v_cndmask_b32_e64 v108, v112, v108, s[6:7]
	v_cndmask_b32_e64 v109, v113, v109, s[6:7]
	v_cndmask_b32_e64 v106, v118, v106, s[6:7]
	v_cndmask_b32_e64 v107, v119, v107, s[6:7]
	v_cndmask_b32_e64 v104, v116, v104, s[6:7]
	v_cndmask_b32_e64 v105, v117, v105, s[6:7]
	v_cndmask_b32_e64 v102, v102, v114, s[6:7]
	v_cndmask_b32_e64 v103, v103, v115, s[6:7]
	v_cndmask_b32_e64 v100, v100, v112, s[6:7]
	v_cndmask_b32_e64 v101, v101, v113, s[6:7]
	v_cndmask_b32_e64 v112, v98, v118, s[6:7]
	v_cndmask_b32_e64 v113, v99, v119, s[6:7]
	v_cndmask_b32_e64 v114, v96, v116, s[6:7]
	v_cndmask_b32_e64 v115, v97, v117, s[6:7]
	v_add_u32_e32 v116, 0x300, v136
	v_cvt_pk_bf16_f32 v96, v108, v109
	v_cvt_pk_bf16_f32 v97, v110, v111
	v_cvt_pk_bf16_f32 v98, v104, v105
	v_cvt_pk_bf16_f32 v99, v106, v107
	global_store_dwordx4 v116, v[96:99], s[22:23]
	s_nop 1
	v_cvt_pk_bf16_f32 v96, v100, v101
	v_cvt_pk_bf16_f32 v97, v102, v103
	v_cvt_pk_bf16_f32 v98, v114, v115
	v_cvt_pk_bf16_f32 v99, v112, v113
	global_store_dwordx4 v116, v[96:99], s[22:23] offset:32
	s_nop 0
	s_nop 0
	s_nop 0
	s_nop 0
	s_nop 0
	s_nop 0
	s_nop 0
	s_nop 0
	v_mov_b32_dpp v96, v199 quad_perm:[1,0,3,2] row_mask:0xf bank_mask:0xf
	v_mov_b32_dpp v97, v198 quad_perm:[1,0,3,2] row_mask:0xf bank_mask:0xf
	v_mov_b32_dpp v98, v196 quad_perm:[1,0,3,2] row_mask:0xf bank_mask:0xf
	v_mov_b32_dpp v99, v194 quad_perm:[1,0,3,2] row_mask:0xf bank_mask:0xf
	v_mov_b32_dpp v100, v197 quad_perm:[1,0,3,2] row_mask:0xf bank_mask:0xf
	v_mov_b32_dpp v101, v195 quad_perm:[1,0,3,2] row_mask:0xf bank_mask:0xf
	v_mov_b32_dpp v102, v193 quad_perm:[1,0,3,2] row_mask:0xf bank_mask:0xf
	v_mov_b32_dpp v103, v192 quad_perm:[1,0,3,2] row_mask:0xf bank_mask:0xf
	v_cndmask_b32_e64 v94, v98, v94, s[6:7]
	v_cndmask_b32_e64 v95, v99, v95, s[6:7]
	v_cndmask_b32_e64 v92, v96, v92, s[6:7]
	v_cndmask_b32_e64 v93, v97, v93, s[6:7]
	v_cndmask_b32_e64 v90, v102, v90, s[6:7]
	v_cndmask_b32_e64 v91, v103, v91, s[6:7]
	v_cndmask_b32_e64 v88, v100, v88, s[6:7]
	v_cndmask_b32_e64 v89, v101, v89, s[6:7]
	v_cndmask_b32_e64 v86, v86, v98, s[6:7]
	v_cndmask_b32_e64 v87, v87, v99, s[6:7]
	v_cndmask_b32_e64 v84, v84, v96, s[6:7]
	v_cndmask_b32_e64 v85, v85, v97, s[6:7]
	v_cndmask_b32_e64 v96, v82, v102, s[6:7]
	v_cndmask_b32_e64 v97, v83, v103, s[6:7]
	v_cndmask_b32_e64 v98, v80, v100, s[6:7]
	v_cndmask_b32_e64 v99, v81, v101, s[6:7]
	v_add_u32_e32 v100, 0x600, v136
	v_cvt_pk_bf16_f32 v80, v92, v93
	v_cvt_pk_bf16_f32 v81, v94, v95
	v_cvt_pk_bf16_f32 v82, v88, v89
	v_cvt_pk_bf16_f32 v83, v90, v91
	global_store_dwordx4 v100, v[80:83], s[22:23]
	s_nop 1
	v_cvt_pk_bf16_f32 v80, v84, v85
	v_cvt_pk_bf16_f32 v81, v86, v87
	v_cvt_pk_bf16_f32 v82, v98, v99
	v_cvt_pk_bf16_f32 v83, v96, v97
	global_store_dwordx4 v100, v[80:83], s[22:23] offset:32
	s_nop 0
	s_nop 0
	s_nop 0
	s_nop 0
	s_nop 0
	s_nop 0
	s_nop 0
	s_nop 0
; __device__ __forceinline__ u32x4 pack8f(f32x4 a, f32x4 b) { u32x4 w; w.x = cvt_pk_bf16(a[0], a[1]); w.y = cvt_pk_bf16(a[2], a[3]); w.z = cvt_pk_bf16(b[0], b[1]); w.w = cvt_pk_bf16(b[2], b[3]); return w; }
; #define EPI_OPAQUE(x) asm volatile("" : "+v"(x))
; __device__ __forceinline__ float dpp_x1(float x) { return __builtin_bit_cast(float, __builtin_amdgcn_update_dpp(0, __builtin_bit_cast(int, x), 0xB1, 0xF, 0xF, false)); }
; __device__ __forceinline__ f32x4 dpp_swap1(f32x4 v) { f32x4 r; r[0] = dpp_x1(v[0]); r[1] = dpp_x1(v[1]); r[2] = dpp_x1(v[2]); r[3] = dpp_x1(v[3]); return r; }
;     __device__ __forceinline__ void operator()(const f32x4 (&acc)[2][2][4][2], const Unit& u, int wr, int wc, int fr, int fq, const EpiCtx& X) const {
;     ...
;         if (u.pn < 8) {
;             char* base = (char*)(UA + ((size_t)u.pn * 16 * 1024 + (size_t)u.pm * 16) * UA_LD);
;             unsigned lo = (unsigned)(((wc * 4 + (fr & 1) * 2 + (fq >> 1)) * 1024 + wr * 4) * UA_LD + fe * 16 + 8 * (fq & 1)) * 2u; EPI_OPAQUE(lo);
;             EPI_PIECES({ const unsigned off = lo + (unsigned)((rl >> 4) * UA_LD) * 2u; *(u32x4*)(base + off) = pack8f(p1a, p1b); *(u32x4*)(base + off + 32) = pack8f(p2a, p2b); })
	v_mov_b32_dpp v80, v191 quad_perm:[1,0,3,2] row_mask:0xf bank_mask:0xf
	v_mov_b32_dpp v81, v190 quad_perm:[1,0,3,2] row_mask:0xf bank_mask:0xf
	v_mov_b32_dpp v82, v188 quad_perm:[1,0,3,2] row_mask:0xf bank_mask:0xf
	v_mov_b32_dpp v83, v186 quad_perm:[1,0,3,2] row_mask:0xf bank_mask:0xf
	v_mov_b32_dpp v84, v189 quad_perm:[1,0,3,2] row_mask:0xf bank_mask:0xf
	v_mov_b32_dpp v85, v187 quad_perm:[1,0,3,2] row_mask:0xf bank_mask:0xf
	v_mov_b32_dpp v86, v185 quad_perm:[1,0,3,2] row_mask:0xf bank_mask:0xf
	v_mov_b32_dpp v87, v184 quad_perm:[1,0,3,2] row_mask:0xf bank_mask:0xf
	v_cndmask_b32_e64 v78, v82, v78, s[6:7]
	v_cndmask_b32_e64 v79, v83, v79, s[6:7]
	v_cndmask_b32_e64 v76, v80, v76, s[6:7]
	v_cndmask_b32_e64 v77, v81, v77, s[6:7]
	v_cndmask_b32_e64 v74, v86, v74, s[6:7]
	v_cndmask_b32_e64 v75, v87, v75, s[6:7]
	v_cndmask_b32_e64 v72, v84, v72, s[6:7]
	v_cndmask_b32_e64 v73, v85, v73, s[6:7]
	v_cndmask_b32_e64 v70, v70, v82, s[6:7]
	v_cndmask_b32_e64 v71, v71, v83, s[6:7]
	v_cndmask_b32_e64 v68, v68, v80, s[6:7]
	v_cndmask_b32_e64 v69, v69, v81, s[6:7]
	v_cndmask_b32_e64 v80, v66, v86, s[6:7]
	v_cndmask_b32_e64 v81, v67, v87, s[6:7]
	v_cndmask_b32_e64 v82, v64, v84, s[6:7]
	v_cndmask_b32_e64 v83, v65, v85, s[6:7]
	v_add_u32_e32 v84, 0x900, v136
	v_cvt_pk_bf16_f32 v64, v76, v77
	v_cvt_pk_bf16_f32 v65, v78, v79
	v_cvt_pk_bf16_f32 v66, v72, v73
	v_cvt_pk_bf16_f32 v67, v74, v75
	global_store_dwordx4 v84, v[64:67], s[22:23]
	s_nop 1
	v_cvt_pk_bf16_f32 v64, v68, v69
	v_cvt_pk_bf16_f32 v65, v70, v71
	v_cvt_pk_bf16_f32 v66, v82, v83
	v_cvt_pk_bf16_f32 v67, v80, v81
	global_store_dwordx4 v84, v[64:67], s[22:23] offset:32
	s_nop 0
	s_nop 0
	s_nop 0
	s_nop 0
	s_nop 0
	s_nop 0
	s_nop 0
	s_nop 0
	v_mov_b32_dpp v64, v183 quad_perm:[1,0,3,2] row_mask:0xf bank_mask:0xf
	v_mov_b32_dpp v65, v182 quad_perm:[1,0,3,2] row_mask:0xf bank_mask:0xf
	v_mov_b32_dpp v66, v180 quad_perm:[1,0,3,2] row_mask:0xf bank_mask:0xf
	v_mov_b32_dpp v67, v178 quad_perm:[1,0,3,2] row_mask:0xf bank_mask:0xf
	v_mov_b32_dpp v68, v181 quad_perm:[1,0,3,2] row_mask:0xf bank_mask:0xf
	v_mov_b32_dpp v69, v179 quad_perm:[1,0,3,2] row_mask:0xf bank_mask:0xf
	v_mov_b32_dpp v70, v177 quad_perm:[1,0,3,2] row_mask:0xf bank_mask:0xf
	v_mov_b32_dpp v71, v176 quad_perm:[1,0,3,2] row_mask:0xf bank_mask:0xf
	v_cndmask_b32_e64 v62, v66, v62, s[6:7]
	v_cndmask_b32_e64 v63, v67, v63, s[6:7]
	v_cndmask_b32_e64 v60, v64, v60, s[6:7]
	v_cndmask_b32_e64 v61, v65, v61, s[6:7]
	v_cndmask_b32_e64 v58, v70, v58, s[6:7]
	v_cndmask_b32_e64 v59, v71, v59, s[6:7]
	v_cndmask_b32_e64 v56, v68, v56, s[6:7]
	v_cndmask_b32_e64 v57, v69, v57, s[6:7]
	v_cndmask_b32_e64 v54, v54, v66, s[6:7]
	v_cndmask_b32_e64 v55, v55, v67, s[6:7]
	v_cndmask_b32_e64 v52, v52, v64, s[6:7]
	v_cndmask_b32_e64 v53, v53, v65, s[6:7]
	v_cndmask_b32_e64 v64, v50, v70, s[6:7]
	v_cndmask_b32_e64 v65, v51, v71, s[6:7]
	v_cndmask_b32_e64 v66, v48, v68, s[6:7]
	v_cndmask_b32_e64 v67, v49, v69, s[6:7]
	v_add_u32_e32 v68, 0x1800, v136
	v_cvt_pk_bf16_f32 v48, v60, v61
	v_cvt_pk_bf16_f32 v49, v62, v63
	v_cvt_pk_bf16_f32 v50, v56, v57
	v_cvt_pk_bf16_f32 v51, v58, v59
	global_store_dwordx4 v68, v[48:51], s[22:23]
	s_nop 1
	v_cvt_pk_bf16_f32 v48, v52, v53
	v_cvt_pk_bf16_f32 v49, v54, v55
	v_cvt_pk_bf16_f32 v50, v66, v67
	v_cvt_pk_bf16_f32 v51, v64, v65
	global_store_dwordx4 v68, v[48:51], s[22:23] offset:32
	s_nop 0
	s_nop 0
	s_nop 0
	s_nop 0
	s_nop 0
	s_nop 0
	s_nop 0
	s_nop 0
	v_mov_b32_dpp v48, v175 quad_perm:[1,0,3,2] row_mask:0xf bank_mask:0xf
	v_mov_b32_dpp v49, v174 quad_perm:[1,0,3,2] row_mask:0xf bank_mask:0xf
	v_mov_b32_dpp v50, v172 quad_perm:[1,0,3,2] row_mask:0xf bank_mask:0xf
	v_mov_b32_dpp v51, v170 quad_perm:[1,0,3,2] row_mask:0xf bank_mask:0xf
	v_mov_b32_dpp v52, v173 quad_perm:[1,0,3,2] row_mask:0xf bank_mask:0xf
	v_mov_b32_dpp v53, v171 quad_perm:[1,0,3,2] row_mask:0xf bank_mask:0xf
	v_mov_b32_dpp v54, v169 quad_perm:[1,0,3,2] row_mask:0xf bank_mask:0xf
	v_mov_b32_dpp v55, v168 quad_perm:[1,0,3,2] row_mask:0xf bank_mask:0xf
	v_cndmask_b32_e64 v46, v50, v46, s[6:7]
	v_cndmask_b32_e64 v47, v51, v47, s[6:7]
	v_cndmask_b32_e64 v44, v48, v44, s[6:7]
	v_cndmask_b32_e64 v45, v49, v45, s[6:7]
	v_cndmask_b32_e64 v42, v54, v42, s[6:7]
	v_cndmask_b32_e64 v43, v55, v43, s[6:7]
	v_cndmask_b32_e64 v40, v52, v40, s[6:7]
; __device__ __forceinline__ u32x4 pack8f(f32x4 a, f32x4 b) { u32x4 w; w.x = cvt_pk_bf16(a[0], a[1]); w.y = cvt_pk_bf16(a[2], a[3]); w.z = cvt_pk_bf16(b[0], b[1]); w.w = cvt_pk_bf16(b[2], b[3]); return w; }
; #define EPI_OPAQUE(x) asm volatile("" : "+v"(x))
; __device__ __forceinline__ float dpp_x1(float x) { return __builtin_bit_cast(float, __builtin_amdgcn_update_dpp(0, __builtin_bit_cast(int, x), 0xB1, 0xF, 0xF, false)); }
; __device__ __forceinline__ f32x4 dpp_swap1(f32x4 v) { f32x4 r; r[0] = dpp_x1(v[0]); r[1] = dpp_x1(v[1]); r[2] = dpp_x1(v[2]); r[3] = dpp_x1(v[3]); return r; }
;     __device__ __forceinline__ void operator()(const f32x4 (&acc)[2][2][4][2], const Unit& u, int wr, int wc, int fr, int fq, const EpiCtx& X) const {
;     ...
;         if (u.pn < 8) {
;             char* base = (char*)(UA + ((size_t)u.pn * 16 * 1024 + (size_t)u.pm * 16) * UA_LD);
;             unsigned lo = (unsigned)(((wc * 4 + (fr & 1) * 2 + (fq >> 1)) * 1024 + wr * 4) * UA_LD + fe * 16 + 8 * (fq & 1)) * 2u; EPI_OPAQUE(lo);
;             EPI_PIECES({ const unsigned off = lo + (unsigned)((rl >> 4) * UA_LD) * 2u; *(u32x4*)(base + off) = pack8f(p1a, p1b); *(u32x4*)(base + off + 32) = pack8f(p2a, p2b); })
	v_cndmask_b32_e64 v41, v53, v41, s[6:7]
	v_cndmask_b32_e64 v38, v38, v50, s[6:7]
	v_cndmask_b32_e64 v39, v39, v51, s[6:7]
	v_cndmask_b32_e64 v36, v36, v48, s[6:7]
	v_cndmask_b32_e64 v37, v37, v49, s[6:7]
	v_cndmask_b32_e64 v48, v34, v54, s[6:7]
	v_cndmask_b32_e64 v49, v35, v55, s[6:7]
	v_cndmask_b32_e64 v50, v32, v52, s[6:7]
	v_cndmask_b32_e64 v51, v33, v53, s[6:7]
	v_add_u32_e32 v52, 0x1b00, v136
	v_cvt_pk_bf16_f32 v32, v44, v45
	v_cvt_pk_bf16_f32 v33, v46, v47
	v_cvt_pk_bf16_f32 v34, v40, v41
	v_cvt_pk_bf16_f32 v35, v42, v43
	global_store_dwordx4 v52, v[32:35], s[22:23]
	s_nop 1
	v_cvt_pk_bf16_f32 v32, v36, v37
	v_cvt_pk_bf16_f32 v33, v38, v39
	v_cvt_pk_bf16_f32 v34, v50, v51
	v_cvt_pk_bf16_f32 v35, v48, v49
	global_store_dwordx4 v52, v[32:35], s[22:23] offset:32
	s_nop 0
	s_nop 0
	s_nop 0
	s_nop 0
	s_nop 0
	s_nop 0
	s_nop 0
	s_nop 0
	v_mov_b32_dpp v32, v167 quad_perm:[1,0,3,2] row_mask:0xf bank_mask:0xf
	v_mov_b32_dpp v33, v166 quad_perm:[1,0,3,2] row_mask:0xf bank_mask:0xf
	v_mov_b32_dpp v34, v164 quad_perm:[1,0,3,2] row_mask:0xf bank_mask:0xf
	v_mov_b32_dpp v35, v162 quad_perm:[1,0,3,2] row_mask:0xf bank_mask:0xf
	v_mov_b32_dpp v36, v165 quad_perm:[1,0,3,2] row_mask:0xf bank_mask:0xf
	v_mov_b32_dpp v37, v163 quad_perm:[1,0,3,2] row_mask:0xf bank_mask:0xf
	v_mov_b32_dpp v38, v161 quad_perm:[1,0,3,2] row_mask:0xf bank_mask:0xf
	v_mov_b32_dpp v39, v160 quad_perm:[1,0,3,2] row_mask:0xf bank_mask:0xf
	v_cndmask_b32_e64 v30, v34, v30, s[6:7]
	v_cndmask_b32_e64 v31, v35, v31, s[6:7]
	v_cndmask_b32_e64 v28, v32, v28, s[6:7]
	v_cndmask_b32_e64 v29, v33, v29, s[6:7]
	v_cndmask_b32_e64 v26, v38, v26, s[6:7]
	v_cndmask_b32_e64 v27, v39, v27, s[6:7]
	v_cndmask_b32_e64 v24, v36, v24, s[6:7]
	v_cndmask_b32_e64 v25, v37, v25, s[6:7]
	v_cndmask_b32_e64 v22, v22, v34, s[6:7]
	v_cndmask_b32_e64 v23, v23, v35, s[6:7]
	v_cndmask_b32_e64 v20, v20, v32, s[6:7]
	v_cndmask_b32_e64 v21, v21, v33, s[6:7]
	v_cndmask_b32_e64 v32, v18, v38, s[6:7]
	v_cndmask_b32_e64 v33, v19, v39, s[6:7]
	v_cndmask_b32_e64 v34, v16, v36, s[6:7]
	v_cndmask_b32_e64 v35, v17, v37, s[6:7]
	v_add_u32_e32 v36, 0x1e00, v136
	v_cvt_pk_bf16_f32 v16, v28, v29
	v_cvt_pk_bf16_f32 v17, v30, v31
	v_cvt_pk_bf16_f32 v18, v24, v25
	v_cvt_pk_bf16_f32 v19, v26, v27
	global_store_dwordx4 v36, v[16:19], s[22:23]
	s_nop 1
	v_cvt_pk_bf16_f32 v16, v20, v21
	v_cvt_pk_bf16_f32 v17, v22, v23
	v_cvt_pk_bf16_f32 v18, v34, v35
	v_cvt_pk_bf16_f32 v19, v32, v33
	global_store_dwordx4 v36, v[16:19], s[22:23] offset:32
	s_nop 0
	s_nop 0
	s_nop 0
	s_nop 0
	s_nop 0
	s_nop 0
	s_nop 0
	s_nop 0
	v_mov_b32_dpp v16, v159 quad_perm:[1,0,3,2] row_mask:0xf bank_mask:0xf
	v_mov_b32_dpp v17, v158 quad_perm:[1,0,3,2] row_mask:0xf bank_mask:0xf
	v_mov_b32_dpp v18, v156 quad_perm:[1,0,3,2] row_mask:0xf bank_mask:0xf
	v_mov_b32_dpp v19, v154 quad_perm:[1,0,3,2] row_mask:0xf bank_mask:0xf
	v_mov_b32_dpp v20, v157 quad_perm:[1,0,3,2] row_mask:0xf bank_mask:0xf
	v_mov_b32_dpp v21, v155 quad_perm:[1,0,3,2] row_mask:0xf bank_mask:0xf
	v_mov_b32_dpp v22, v153 quad_perm:[1,0,3,2] row_mask:0xf bank_mask:0xf
	v_mov_b32_dpp v23, v152 quad_perm:[1,0,3,2] row_mask:0xf bank_mask:0xf
	v_cndmask_b32_e64 v14, v18, v14, s[6:7]
	v_cndmask_b32_e64 v15, v19, v15, s[6:7]
	v_cndmask_b32_e64 v12, v16, v12, s[6:7]
	v_cndmask_b32_e64 v13, v17, v13, s[6:7]
	v_cndmask_b32_e64 v10, v22, v10, s[6:7]
	v_cndmask_b32_e64 v11, v23, v11, s[6:7]
	v_cndmask_b32_e64 v8, v20, v8, s[6:7]
	v_cndmask_b32_e64 v9, v21, v9, s[6:7]
	v_cndmask_b32_e64 v6, v6, v18, s[6:7]
	v_cndmask_b32_e64 v7, v7, v19, s[6:7]
	v_cndmask_b32_e64 v4, v4, v16, s[6:7]
	v_cndmask_b32_e64 v5, v5, v17, s[6:7]
	v_cndmask_b32_e64 v16, v2, v22, s[6:7]
	v_cndmask_b32_e64 v17, v3, v23, s[6:7]
	v_cndmask_b32_e64 v18, v0, v20, s[6:7]
	v_cndmask_b32_e64 v19, v1, v21, s[6:7]
	v_add_u32_e32 v20, 0x2100, v136
	v_cvt_pk_bf16_f32 v0, v12, v13
	v_cvt_pk_bf16_f32 v1, v14, v15
	v_cvt_pk_bf16_f32 v2, v8, v9
	v_cvt_pk_bf16_f32 v3, v10, v11
	global_store_dwordx4 v20, v[0:3], s[22:23]
	s_nop 1
	v_cvt_pk_bf16_f32 v0, v4, v5
	v_cvt_pk_bf16_f32 v1, v6, v7
	v_cvt_pk_bf16_f32 v2, v18, v19
	v_cvt_pk_bf16_f32 v3, v16, v17
	global_store_dwordx4 v20, v[0:3], s[22:23] offset:32
	s_andn2_b64 vcc, exec, s[8:9]
	s_mov_b64 s[8:9], -1
	s_cbranch_vccnz .LBB0_158

; #define EPI_OPAQUE(x) asm volatile("" : "+v"(x))
; __device__ __forceinline__ float dpp_x1(float x) { return __builtin_bit_cast(float, __builtin_amdgcn_update_dpp(0, __builtin_bit_cast(int, x), 0xB1, 0xF, 0xF, false)); }
; __device__ __forceinline__ f32x4 dpp_swap1(f32x4 v) { f32x4 r; r[0] = dpp_x1(v[0]); r[1] = dpp_x1(v[1]); r[2] = dpp_x1(v[2]); r[3] = dpp_x1(v[3]); return r; }
;     __device__ __forceinline__ void operator()(const f32x4 (&acc)[2][2][4][2], const Unit& u, int wr, int wc, int fr, int fq, const EpiCtx& X) const {
;         const bool odd = fr & 1; const int fe = fr - (fr & 1), o32 = (fr & 1) * 32;
;         char* base = (char*)(XLOC + (size_t)u.pm * BM * 128);
;         unsigned lo = (unsigned)((wr * 64 + fe) * 128 + wc * 64 + o32 + 8 * fq) * 4u; EPI_OPAQUE(lo);
;         EPI_PIECES({ if (wc < 2) { float* p = (float*)(base + (lo + (unsigned)(rl * 128) * 4u)); *(f32x4*)p = p1a; *(f32x4*)(p + 4) = p1b; *(f32x4*)(p + 128) = p2a; *(f32x4*)(p + 132) = p2b; } })
.LBB0_246:
	v_cndmask_b32_e64 v144, v124, v116, s[8:9]
	s_nop 0
	v_cndmask_b32_e64 v145, v125, v117, s[8:9]
	v_cndmask_b32_e64 v146, v126, v118, s[8:9]
	v_mov_b32_dpp v143, v144 quad_perm:[1,0,3,2] row_mask:0xf bank_mask:0xf
	s_nop 0
	v_cndmask_b32_e64 v147, v127, v119, s[8:9]
	v_cndmask_b32_e64 v148, v120, v112, s[8:9]
	v_mov_b32_dpp v144, v145 quad_perm:[1,0,3,2] row_mask:0xf bank_mask:0xf
	s_nop 0
	s_ashr_i32 s55, s54, 31
	v_cndmask_b32_e64 v149, v121, v113, s[8:9]
	v_mov_b32_dpp v145, v146 quad_perm:[1,0,3,2] row_mask:0xf bank_mask:0xf
	s_nop 0
	s_lshl_b64 s[10:11], s[54:55], 17
	v_cndmask_b32_e64 v150, v122, v114, s[8:9]
	v_mov_b32_dpp v146, v147 quad_perm:[1,0,3,2] row_mask:0xf bank_mask:0xf
	s_nop 0
	s_add_u32 s26, s73, s10
	v_cndmask_b32_e64 v151, v123, v115, s[8:9]
	v_mov_b32_dpp v147, v148 quad_perm:[1,0,3,2] row_mask:0xf bank_mask:0xf
	s_nop 0
	v_cndmask_b32_e64 v152, 0, 1, s[16:17]
	s_addc_u32 s27, s74, s11
	v_mov_b32_dpp v148, v149 quad_perm:[1,0,3,2] row_mask:0xf bank_mask:0xf
	s_nop 0
	v_mov_b32_e32 v142, v136
	v_cmp_ne_u32_e64 s[10:11], 1, v152
	v_mov_b32_dpp v149, v150 quad_perm:[1,0,3,2] row_mask:0xf bank_mask:0xf
	v_mov_b32_e32 v150, 0
	s_andn2_b64 vcc, exec, s[16:17]
	s_nop 0
	v_mov_b32_dpp v150, v151 quad_perm:[1,0,3,2] row_mask:0xf bank_mask:0xf
	s_cbranch_vccnz .LBB0_248
	v_cndmask_b32_e64 v127, v146, v127, s[8:9]
	v_cndmask_b32_e64 v126, v145, v126, s[8:9]
	v_cndmask_b32_e64 v125, v144, v125, s[8:9]
	v_cndmask_b32_e64 v124, v143, v124, s[8:9]
	v_cndmask_b32_e64 v115, v115, v150, s[8:9]
	v_cndmask_b32_e64 v114, v114, v149, s[8:9]
	v_cndmask_b32_e64 v113, v113, v148, s[8:9]
	v_cndmask_b32_e64 v112, v112, v147, s[8:9]
	v_cndmask_b32_e64 v119, v119, v146, s[8:9]
	v_cndmask_b32_e64 v118, v118, v145, s[8:9]
	v_cndmask_b32_e64 v117, v117, v144, s[8:9]
	v_cndmask_b32_e64 v116, v116, v143, s[8:9]
	v_cndmask_b32_e64 v123, v150, v123, s[8:9]
	v_cndmask_b32_e64 v122, v149, v122, s[8:9]
	v_cndmask_b32_e64 v121, v148, v121, s[8:9]
	v_cndmask_b32_e64 v120, v147, v120, s[8:9]
	global_store_dwordx4 v142, v[124:127], s[26:27]
	global_store_dwordx4 v142, v[120:123], s[26:27] offset:16
	global_store_dwordx4 v142, v[116:119], s[26:27] offset:512
	global_store_dwordx4 v142, v[112:115], s[26:27] offset:528
.LBB0_248:
	s_nop 1
	v_cndmask_b32_e64 v113, v108, v100, s[8:9]
	s_nop 0
	v_cndmask_b32_e64 v114, v109, v101, s[8:9]
	v_cndmask_b32_e64 v115, v110, v102, s[8:9]
	v_mov_b32_dpp v112, v113 quad_perm:[1,0,3,2] row_mask:0xf bank_mask:0xf
	s_nop 0
	v_cndmask_b32_e64 v116, v111, v103, s[8:9]
	v_cndmask_b32_e64 v117, v104, v96, s[8:9]
	v_mov_b32_dpp v113, v114 quad_perm:[1,0,3,2] row_mask:0xf bank_mask:0xf
	s_nop 0
	v_cndmask_b32_e64 v118, v105, v97, s[8:9]
	v_cndmask_b32_e64 v119, v106, v98, s[8:9]
	v_mov_b32_dpp v114, v115 quad_perm:[1,0,3,2] row_mask:0xf bank_mask:0xf
	v_mov_b32_e32 v115, 0
	v_cndmask_b32_e64 v120, v107, v99, s[8:9]
	s_and_b64 vcc, exec, s[10:11]
	v_mov_b32_dpp v115, v116 quad_perm:[1,0,3,2] row_mask:0xf bank_mask:0xf
	s_nop 0
	s_nop 1
	v_mov_b32_dpp v116, v117 quad_perm:[1,0,3,2] row_mask:0xf bank_mask:0xf
	s_nop 0
	s_nop 1
	v_mov_b32_dpp v117, v118 quad_perm:[1,0,3,2] row_mask:0xf bank_mask:0xf
	s_nop 0
	s_nop 1
	v_mov_b32_dpp v118, v119 quad_perm:[1,0,3,2] row_mask:0xf bank_mask:0xf
	s_nop 0
	s_nop 1
	v_mov_b32_dpp v119, v120 quad_perm:[1,0,3,2] row_mask:0xf bank_mask:0xf
	s_cbranch_vccnz .LBB0_250
	v_cndmask_b32_e64 v100, v100, v112, s[8:9]
	v_cndmask_b32_e64 v111, v115, v111, s[8:9]
	v_cndmask_b32_e64 v110, v114, v110, s[8:9]
	v_cndmask_b32_e64 v109, v113, v109, s[8:9]
	v_cndmask_b32_e64 v108, v112, v108, s[8:9]
	v_add_u32_e32 v112, 0x2000, v142
	v_cndmask_b32_e64 v99, v99, v119, s[8:9]
	v_cndmask_b32_e64 v98, v98, v118, s[8:9]
	v_cndmask_b32_e64 v97, v97, v117, s[8:9]
	v_cndmask_b32_e64 v96, v96, v116, s[8:9]
	v_cndmask_b32_e64 v103, v103, v115, s[8:9]
	v_cndmask_b32_e64 v102, v102, v114, s[8:9]
	v_cndmask_b32_e64 v101, v101, v113, s[8:9]
	v_cndmask_b32_e64 v107, v119, v107, s[8:9]
	v_cndmask_b32_e64 v106, v118, v106, s[8:9]
	v_cndmask_b32_e64 v105, v117, v105, s[8:9]
	v_cndmask_b32_e64 v104, v116, v104, s[8:9]
	global_store_dwordx4 v112, v[108:111], s[26:27]
	global_store_dwordx4 v112, v[104:107], s[26:27] offset:16
	global_store_dwordx4 v112, v[100:103], s[26:27] offset:512
	global_store_dwordx4 v112, v[96:99], s[26:27] offset:528
.LBB0_250:
	s_nop 1
	v_cndmask_b32_e64 v97, v92, v84, s[8:9]
	s_nop 0
	v_cndmask_b32_e64 v98, v93, v85, s[8:9]
	v_cndmask_b32_e64 v99, v94, v86, s[8:9]
	v_mov_b32_dpp v96, v97 quad_perm:[1,0,3,2] row_mask:0xf bank_mask:0xf
	s_nop 0
	v_cndmask_b32_e64 v100, v95, v87, s[8:9]
	v_cndmask_b32_e64 v101, v88, v80, s[8:9]
	v_mov_b32_dpp v97, v98 quad_perm:[1,0,3,2] row_mask:0xf bank_mask:0xf
	s_nop 0
	v_cndmask_b32_e64 v102, v89, v81, s[8:9]
	v_cndmask_b32_e64 v103, v90, v82, s[8:9]
	v_mov_b32_dpp v98, v99 quad_perm:[1,0,3,2] row_mask:0xf bank_mask:0xf
	v_mov_b32_e32 v99, 0
	v_cndmask_b32_e64 v104, v91, v83, s[8:9]
	s_and_b64 vcc, exec, s[10:11]
	v_mov_b32_dpp v99, v100 quad_perm:[1,0,3,2] row_mask:0xf bank_mask:0xf
	s_nop 0
	s_nop 1
	v_mov_b32_dpp v100, v101 quad_perm:[1,0,3,2] row_mask:0xf bank_mask:0xf
	s_nop 0
	s_nop 1
	v_mov_b32_dpp v101, v102 quad_perm:[1,0,3,2] row_mask:0xf bank_mask:0xf
	s_nop 0
	s_nop 1
	v_mov_b32_dpp v102, v103 quad_perm:[1,0,3,2] row_mask:0xf bank_mask:0xf
	s_nop 0
	s_nop 1
	v_mov_b32_dpp v103, v104 quad_perm:[1,0,3,2] row_mask:0xf bank_mask:0xf
	s_cbranch_vccnz .LBB0_252
	v_cndmask_b32_e64 v84, v84, v96, s[8:9]
	v_cndmask_b32_e64 v95, v99, v95, s[8:9]
	v_cndmask_b32_e64 v94, v98, v94, s[8:9]
	v_cndmask_b32_e64 v93, v97, v93, s[8:9]
	v_cndmask_b32_e64 v92, v96, v92, s[8:9]
	v_add_u32_e32 v96, 0x4000, v142
	v_cndmask_b32_e64 v83, v83, v103, s[8:9]
	v_cndmask_b32_e64 v82, v82, v102, s[8:9]
	v_cndmask_b32_e64 v81, v81, v101, s[8:9]
	v_cndmask_b32_e64 v80, v80, v100, s[8:9]
	v_cndmask_b32_e64 v87, v87, v99, s[8:9]
	v_cndmask_b32_e64 v86, v86, v98, s[8:9]
	v_cndmask_b32_e64 v85, v85, v97, s[8:9]
	v_cndmask_b32_e64 v91, v103, v91, s[8:9]
	v_cndmask_b32_e64 v90, v102, v90, s[8:9]
	v_cndmask_b32_e64 v89, v101, v89, s[8:9]
	v_cndmask_b32_e64 v88, v100, v88, s[8:9]
	global_store_dwordx4 v96, v[92:95], s[26:27]
	global_store_dwordx4 v96, v[88:91], s[26:27] offset:16
	global_store_dwordx4 v96, v[84:87], s[26:27] offset:512
	global_store_dwordx4 v96, v[80:83], s[26:27] offset:528
; #define EPI_OPAQUE(x) asm volatile("" : "+v"(x))
; __device__ __forceinline__ float dpp_x1(float x) { return __builtin_bit_cast(float, __builtin_amdgcn_update_dpp(0, __builtin_bit_cast(int, x), 0xB1, 0xF, 0xF, false)); }
; __device__ __forceinline__ f32x4 dpp_swap1(f32x4 v) { f32x4 r; r[0] = dpp_x1(v[0]); r[1] = dpp_x1(v[1]); r[2] = dpp_x1(v[2]); r[3] = dpp_x1(v[3]); return r; }
;     __device__ __forceinline__ void operator()(const f32x4 (&acc)[2][2][4][2], const Unit& u, int wr, int wc, int fr, int fq, const EpiCtx& X) const {
;         const bool odd = fr & 1; const int fe = fr - (fr & 1), o32 = (fr & 1) * 32;
;         char* base = (char*)(XLOC + (size_t)u.pm * BM * 128);
;         unsigned lo = (unsigned)((wr * 64 + fe) * 128 + wc * 64 + o32 + 8 * fq) * 4u; EPI_OPAQUE(lo);
;         EPI_PIECES({ if (wc < 2) { float* p = (float*)(base + (lo + (unsigned)(rl * 128) * 4u)); *(f32x4*)p = p1a; *(f32x4*)(p + 4) = p1b; *(f32x4*)(p + 128) = p2a; *(f32x4*)(p + 132) = p2b; } })
.LBB0_252:
	s_nop 1
	v_cndmask_b32_e64 v81, v76, v68, s[8:9]
	s_nop 0
	v_cndmask_b32_e64 v82, v77, v69, s[8:9]
	v_cndmask_b32_e64 v83, v78, v70, s[8:9]
	v_mov_b32_dpp v80, v81 quad_perm:[1,0,3,2] row_mask:0xf bank_mask:0xf
	s_nop 0
	v_cndmask_b32_e64 v84, v79, v71, s[8:9]
	v_cndmask_b32_e64 v85, v72, v64, s[8:9]
	v_mov_b32_dpp v81, v82 quad_perm:[1,0,3,2] row_mask:0xf bank_mask:0xf
	s_nop 0
	v_cndmask_b32_e64 v86, v73, v65, s[8:9]
	v_cndmask_b32_e64 v87, v74, v66, s[8:9]
	v_mov_b32_dpp v82, v83 quad_perm:[1,0,3,2] row_mask:0xf bank_mask:0xf
	v_mov_b32_e32 v83, 0
	v_cndmask_b32_e64 v88, v75, v67, s[8:9]
	s_and_b64 vcc, exec, s[10:11]
	v_mov_b32_dpp v83, v84 quad_perm:[1,0,3,2] row_mask:0xf bank_mask:0xf
	s_nop 0
	s_nop 1
	v_mov_b32_dpp v84, v85 quad_perm:[1,0,3,2] row_mask:0xf bank_mask:0xf
	s_nop 0
	s_nop 1
	v_mov_b32_dpp v85, v86 quad_perm:[1,0,3,2] row_mask:0xf bank_mask:0xf
	s_nop 0
	s_nop 1
	v_mov_b32_dpp v86, v87 quad_perm:[1,0,3,2] row_mask:0xf bank_mask:0xf
	s_nop 0
	s_nop 1
	v_mov_b32_dpp v87, v88 quad_perm:[1,0,3,2] row_mask:0xf bank_mask:0xf
	s_cbranch_vccnz .LBB0_254
	v_cndmask_b32_e64 v68, v68, v80, s[8:9]
	v_cndmask_b32_e64 v79, v83, v79, s[8:9]
	v_cndmask_b32_e64 v78, v82, v78, s[8:9]
	v_cndmask_b32_e64 v77, v81, v77, s[8:9]
	v_cndmask_b32_e64 v76, v80, v76, s[8:9]
	v_add_u32_e32 v80, 0x6000, v142
	v_cndmask_b32_e64 v67, v67, v87, s[8:9]
	v_cndmask_b32_e64 v66, v66, v86, s[8:9]
	v_cndmask_b32_e64 v65, v65, v85, s[8:9]
	v_cndmask_b32_e64 v64, v64, v84, s[8:9]
	v_cndmask_b32_e64 v71, v71, v83, s[8:9]
	v_cndmask_b32_e64 v70, v70, v82, s[8:9]
	v_cndmask_b32_e64 v69, v69, v81, s[8:9]
	v_cndmask_b32_e64 v75, v87, v75, s[8:9]
	v_cndmask_b32_e64 v74, v86, v74, s[8:9]
	v_cndmask_b32_e64 v73, v85, v73, s[8:9]
	v_cndmask_b32_e64 v72, v84, v72, s[8:9]
	global_store_dwordx4 v80, v[76:79], s[26:27]
	global_store_dwordx4 v80, v[72:75], s[26:27] offset:16
	global_store_dwordx4 v80, v[68:71], s[26:27] offset:512
	global_store_dwordx4 v80, v[64:67], s[26:27] offset:528
.LBB0_254:
	s_nop 1
	v_cndmask_b32_e64 v65, v60, v52, s[8:9]
	s_nop 0
	v_cndmask_b32_e64 v66, v61, v53, s[8:9]
	v_cndmask_b32_e64 v67, v62, v54, s[8:9]
	v_mov_b32_dpp v64, v65 quad_perm:[1,0,3,2] row_mask:0xf bank_mask:0xf
	s_nop 0
	v_cndmask_b32_e64 v68, v63, v55, s[8:9]
	v_cndmask_b32_e64 v69, v56, v48, s[8:9]
	v_mov_b32_dpp v65, v66 quad_perm:[1,0,3,2] row_mask:0xf bank_mask:0xf
	s_nop 0
	v_cndmask_b32_e64 v70, v57, v49, s[8:9]
	v_cndmask_b32_e64 v71, v58, v50, s[8:9]
	v_mov_b32_dpp v66, v67 quad_perm:[1,0,3,2] row_mask:0xf bank_mask:0xf
	v_mov_b32_e32 v67, 0
	v_cndmask_b32_e64 v72, v59, v51, s[8:9]
	s_and_b64 vcc, exec, s[10:11]
	v_mov_b32_dpp v67, v68 quad_perm:[1,0,3,2] row_mask:0xf bank_mask:0xf
	s_nop 0
	s_nop 1
	v_mov_b32_dpp v68, v69 quad_perm:[1,0,3,2] row_mask:0xf bank_mask:0xf
	s_nop 0
	s_nop 1
	v_mov_b32_dpp v69, v70 quad_perm:[1,0,3,2] row_mask:0xf bank_mask:0xf
	s_nop 0
	s_nop 1
	v_mov_b32_dpp v70, v71 quad_perm:[1,0,3,2] row_mask:0xf bank_mask:0xf
	s_nop 0
	s_nop 1
	v_mov_b32_dpp v71, v72 quad_perm:[1,0,3,2] row_mask:0xf bank_mask:0xf
	s_cbranch_vccnz .LBB0_256
	v_cndmask_b32_e64 v52, v52, v64, s[8:9]
	v_cndmask_b32_e64 v63, v67, v63, s[8:9]
	v_cndmask_b32_e64 v62, v66, v62, s[8:9]
	v_cndmask_b32_e64 v61, v65, v61, s[8:9]
	v_cndmask_b32_e64 v60, v64, v60, s[8:9]
	v_add_u32_e32 v64, 0x10000, v142
	v_cndmask_b32_e64 v51, v51, v71, s[8:9]
	v_cndmask_b32_e64 v50, v50, v70, s[8:9]
	v_cndmask_b32_e64 v49, v49, v69, s[8:9]
	v_cndmask_b32_e64 v48, v48, v68, s[8:9]
	v_cndmask_b32_e64 v55, v55, v67, s[8:9]
	v_cndmask_b32_e64 v54, v54, v66, s[8:9]
	v_cndmask_b32_e64 v53, v53, v65, s[8:9]
	v_cndmask_b32_e64 v59, v71, v59, s[8:9]
	v_cndmask_b32_e64 v58, v70, v58, s[8:9]
	v_cndmask_b32_e64 v57, v69, v57, s[8:9]
	v_cndmask_b32_e64 v56, v68, v56, s[8:9]
	global_store_dwordx4 v64, v[60:63], s[26:27]
	global_store_dwordx4 v64, v[56:59], s[26:27] offset:16
	global_store_dwordx4 v64, v[52:55], s[26:27] offset:512
	global_store_dwordx4 v64, v[48:51], s[26:27] offset:528
; #define EPI_OPAQUE(x) asm volatile("" : "+v"(x))
; __device__ __forceinline__ float dpp_x1(float x) { return __builtin_bit_cast(float, __builtin_amdgcn_update_dpp(0, __builtin_bit_cast(int, x), 0xB1, 0xF, 0xF, false)); }
; __device__ __forceinline__ f32x4 dpp_swap1(f32x4 v) { f32x4 r; r[0] = dpp_x1(v[0]); r[1] = dpp_x1(v[1]); r[2] = dpp_x1(v[2]); r[3] = dpp_x1(v[3]); return r; }
;     __device__ __forceinline__ void operator()(const f32x4 (&acc)[2][2][4][2], const Unit& u, int wr, int wc, int fr, int fq, const EpiCtx& X) const {
;         const bool odd = fr & 1; const int fe = fr - (fr & 1), o32 = (fr & 1) * 32;
;         char* base = (char*)(XLOC + (size_t)u.pm * BM * 128);
;         unsigned lo = (unsigned)((wr * 64 + fe) * 128 + wc * 64 + o32 + 8 * fq) * 4u; EPI_OPAQUE(lo);
;         EPI_PIECES({ if (wc < 2) { float* p = (float*)(base + (lo + (unsigned)(rl * 128) * 4u)); *(f32x4*)p = p1a; *(f32x4*)(p + 4) = p1b; *(f32x4*)(p + 128) = p2a; *(f32x4*)(p + 132) = p2b; } })
.LBB0_256:
	s_nop 1
	v_cndmask_b32_e64 v49, v44, v36, s[8:9]
	s_nop 0
	v_cndmask_b32_e64 v50, v45, v37, s[8:9]
	v_cndmask_b32_e64 v51, v46, v38, s[8:9]
	v_mov_b32_dpp v48, v49 quad_perm:[1,0,3,2] row_mask:0xf bank_mask:0xf
	s_nop 0
	v_cndmask_b32_e64 v52, v47, v39, s[8:9]
	v_cndmask_b32_e64 v53, v40, v32, s[8:9]
	v_mov_b32_dpp v49, v50 quad_perm:[1,0,3,2] row_mask:0xf bank_mask:0xf
	s_nop 0
	v_cndmask_b32_e64 v54, v41, v33, s[8:9]
	v_cndmask_b32_e64 v55, v42, v34, s[8:9]
	v_mov_b32_dpp v50, v51 quad_perm:[1,0,3,2] row_mask:0xf bank_mask:0xf
	v_mov_b32_e32 v51, 0
	v_cndmask_b32_e64 v56, v43, v35, s[8:9]
	s_and_b64 vcc, exec, s[10:11]
	v_mov_b32_dpp v51, v52 quad_perm:[1,0,3,2] row_mask:0xf bank_mask:0xf
	s_nop 0
	s_nop 1
	v_mov_b32_dpp v52, v53 quad_perm:[1,0,3,2] row_mask:0xf bank_mask:0xf
	s_nop 0
	s_nop 1
	v_mov_b32_dpp v53, v54 quad_perm:[1,0,3,2] row_mask:0xf bank_mask:0xf
	s_nop 0
	s_nop 1
	v_mov_b32_dpp v54, v55 quad_perm:[1,0,3,2] row_mask:0xf bank_mask:0xf
	s_nop 0
	s_nop 1
	v_mov_b32_dpp v55, v56 quad_perm:[1,0,3,2] row_mask:0xf bank_mask:0xf
	s_cbranch_vccnz .LBB0_258
	v_cndmask_b32_e64 v36, v36, v48, s[8:9]
	v_cndmask_b32_e64 v47, v51, v47, s[8:9]
	v_cndmask_b32_e64 v46, v50, v46, s[8:9]
	v_cndmask_b32_e64 v45, v49, v45, s[8:9]
	v_cndmask_b32_e64 v44, v48, v44, s[8:9]
	v_add_u32_e32 v48, 0x12000, v142
	v_cndmask_b32_e64 v35, v35, v55, s[8:9]
	v_cndmask_b32_e64 v34, v34, v54, s[8:9]
	v_cndmask_b32_e64 v33, v33, v53, s[8:9]
	v_cndmask_b32_e64 v32, v32, v52, s[8:9]
	v_cndmask_b32_e64 v39, v39, v51, s[8:9]
	v_cndmask_b32_e64 v38, v38, v50, s[8:9]
	v_cndmask_b32_e64 v37, v37, v49, s[8:9]
	v_cndmask_b32_e64 v43, v55, v43, s[8:9]
	v_cndmask_b32_e64 v42, v54, v42, s[8:9]
	v_cndmask_b32_e64 v41, v53, v41, s[8:9]
	v_cndmask_b32_e64 v40, v52, v40, s[8:9]
	global_store_dwordx4 v48, v[44:47], s[26:27]
	global_store_dwordx4 v48, v[40:43], s[26:27] offset:16
	global_store_dwordx4 v48, v[36:39], s[26:27] offset:512
	global_store_dwordx4 v48, v[32:35], s[26:27] offset:528
.LBB0_258:
	s_nop 1
	v_cndmask_b32_e64 v33, v28, v20, s[8:9]
	s_nop 0
	v_cndmask_b32_e64 v34, v29, v21, s[8:9]
	v_cndmask_b32_e64 v35, v30, v22, s[8:9]
	v_mov_b32_dpp v32, v33 quad_perm:[1,0,3,2] row_mask:0xf bank_mask:0xf
	s_nop 0
	v_cndmask_b32_e64 v36, v31, v23, s[8:9]
	v_cndmask_b32_e64 v37, v24, v16, s[8:9]
	v_mov_b32_dpp v33, v34 quad_perm:[1,0,3,2] row_mask:0xf bank_mask:0xf
	s_nop 0
	v_cndmask_b32_e64 v38, v25, v17, s[8:9]
	v_cndmask_b32_e64 v39, v26, v18, s[8:9]
	v_mov_b32_dpp v34, v35 quad_perm:[1,0,3,2] row_mask:0xf bank_mask:0xf
	v_mov_b32_e32 v35, 0
	v_cndmask_b32_e64 v40, v27, v19, s[8:9]
	s_and_b64 vcc, exec, s[10:11]
	v_mov_b32_dpp v35, v36 quad_perm:[1,0,3,2] row_mask:0xf bank_mask:0xf
	s_nop 0
	s_nop 1
	v_mov_b32_dpp v36, v37 quad_perm:[1,0,3,2] row_mask:0xf bank_mask:0xf
	s_nop 0
	s_nop 1
	v_mov_b32_dpp v37, v38 quad_perm:[1,0,3,2] row_mask:0xf bank_mask:0xf
	s_nop 0
	s_nop 1
	v_mov_b32_dpp v38, v39 quad_perm:[1,0,3,2] row_mask:0xf bank_mask:0xf
	s_nop 0
	s_nop 1
	v_mov_b32_dpp v39, v40 quad_perm:[1,0,3,2] row_mask:0xf bank_mask:0xf
	s_cbranch_vccnz .LBB0_260
	v_cndmask_b32_e64 v20, v20, v32, s[8:9]
	v_cndmask_b32_e64 v31, v35, v31, s[8:9]
	v_cndmask_b32_e64 v30, v34, v30, s[8:9]
	v_cndmask_b32_e64 v29, v33, v29, s[8:9]
	v_cndmask_b32_e64 v28, v32, v28, s[8:9]
	v_add_u32_e32 v32, 0x14000, v142
	v_cndmask_b32_e64 v19, v19, v39, s[8:9]
	v_cndmask_b32_e64 v18, v18, v38, s[8:9]
	v_cndmask_b32_e64 v17, v17, v37, s[8:9]
	v_cndmask_b32_e64 v16, v16, v36, s[8:9]
	v_cndmask_b32_e64 v23, v23, v35, s[8:9]
	v_cndmask_b32_e64 v22, v22, v34, s[8:9]
	v_cndmask_b32_e64 v21, v21, v33, s[8:9]
	v_cndmask_b32_e64 v27, v39, v27, s[8:9]
	v_cndmask_b32_e64 v26, v38, v26, s[8:9]
	v_cndmask_b32_e64 v25, v37, v25, s[8:9]
	v_cndmask_b32_e64 v24, v36, v24, s[8:9]
	global_store_dwordx4 v32, v[28:31], s[26:27]
	global_store_dwordx4 v32, v[24:27], s[26:27] offset:16
	global_store_dwordx4 v32, v[20:23], s[26:27] offset:512
	global_store_dwordx4 v32, v[16:19], s[26:27] offset:528
.LBB0_260:
	s_nop 1
	v_cndmask_b32_e64 v17, v12, v4, s[8:9]
	s_nop 0
	v_cndmask_b32_e64 v18, v13, v5, s[8:9]
	v_cndmask_b32_e64 v19, v14, v6, s[8:9]
	v_mov_b32_dpp v16, v17 quad_perm:[1,0,3,2] row_mask:0xf bank_mask:0xf
	s_nop 0
	v_cndmask_b32_e64 v20, v15, v7, s[8:9]
	v_cndmask_b32_e64 v21, v8, v0, s[8:9]
	v_mov_b32_dpp v17, v18 quad_perm:[1,0,3,2] row_mask:0xf bank_mask:0xf
	s_nop 0
	v_cndmask_b32_e64 v22, v9, v1, s[8:9]
	v_cndmask_b32_e64 v23, v10, v2, s[8:9]
	v_mov_b32_dpp v18, v19 quad_perm:[1,0,3,2] row_mask:0xf bank_mask:0xf
	v_mov_b32_e32 v19, 0
	v_cndmask_b32_e64 v24, v11, v3, s[8:9]
	s_and_b64 vcc, exec, s[10:11]
	v_mov_b32_dpp v19, v20 quad_perm:[1,0,3,2] row_mask:0xf bank_mask:0xf
	s_nop 0
	s_nop 1
	v_mov_b32_dpp v20, v21 quad_perm:[1,0,3,2] row_mask:0xf bank_mask:0xf
	s_nop 0
	s_nop 1
	v_mov_b32_dpp v21, v22 quad_perm:[1,0,3,2] row_mask:0xf bank_mask:0xf
	s_nop 0
	s_nop 1
	v_mov_b32_dpp v22, v23 quad_perm:[1,0,3,2] row_mask:0xf bank_mask:0xf
	s_nop 0
	s_nop 1
	v_mov_b32_dpp v23, v24 quad_perm:[1,0,3,2] row_mask:0xf bank_mask:0xf
	s_cbranch_vccnz .LBB0_262
	v_cndmask_b32_e64 v4, v4, v16, s[8:9]
	v_cndmask_b32_e64 v15, v19, v15, s[8:9]
	v_cndmask_b32_e64 v14, v18, v14, s[8:9]
	v_cndmask_b32_e64 v13, v17, v13, s[8:9]
	v_cndmask_b32_e64 v12, v16, v12, s[8:9]
	v_add_u32_e32 v16, 0x16000, v142
	v_cndmask_b32_e64 v3, v3, v23, s[8:9]
	v_cndmask_b32_e64 v2, v2, v22, s[8:9]
	v_cndmask_b32_e64 v1, v1, v21, s[8:9]
	v_cndmask_b32_e64 v0, v0, v20, s[8:9]
	v_cndmask_b32_e64 v7, v7, v19, s[8:9]
	v_cndmask_b32_e64 v6, v6, v18, s[8:9]
	v_cndmask_b32_e64 v5, v5, v17, s[8:9]
	v_cndmask_b32_e64 v11, v23, v11, s[8:9]
	v_cndmask_b32_e64 v10, v22, v10, s[8:9]
	v_cndmask_b32_e64 v9, v21, v9, s[8:9]
	v_cndmask_b32_e64 v8, v20, v8, s[8:9]
	global_store_dwordx4 v16, v[12:15], s[26:27]
	global_store_dwordx4 v16, v[8:11], s[26:27] offset:16
	global_store_dwordx4 v16, v[4:7], s[26:27] offset:512
	global_store_dwordx4 v16, v[0:3], s[26:27] offset:528

; #define EPI_OPAQUE(x) asm volatile("" : "+v"(x))
; __device__ __forceinline__ float fast_exp(float x) { return __builtin_amdgcn_exp2f(x * 1.4426950408889634f); }
; __device__ __forceinline__ float fast_sigmoid(float x) { return __builtin_amdgcn_rcpf(1.0f + fast_exp(-x)); }
; __device__ __forceinline__ float gelu_tanh(float x) {
;     const float a = 0.7978845608028654f * (x + 0.044715f * x * x * x);
;     return x * fast_sigmoid(2.0f * a);
; }
;     __device__ __forceinline__ void operator()(const f32x4 (&acc)[2][2][4][2], const Unit& u, int wr, int wc, int fr, int fq, const EpiCtx& X) const {
;         const bool odd = fr & 1; const int fe = fr - (fr & 1), o32 = (fr & 1) * 32;
;         const int g = u.pn; const int p0 = 8 * (fq & 1);
;         const f32x4 d0 = *(const f32x4*)(dvec + g * 16 + p0), d1 = *(const f32x4*)(dvec + g * 16 + p0 + 4);
;         const char* ub = (const char*)(UA + (size_t)u.pm * BM * UA_LD);
;         unsigned ulo = (unsigned)((wr * 64 + fe) * UA_LD + wc * 64 + o32 + 8 * fq) * 2u; EPI_OPAQUE(ulo);
;         char* gb = (char*)(GACT + (size_t)(u.pm & 3) * 256 * 16 * W_SSM + g * 16);
;         unsigned glo = (unsigned)(((wr * 64 + fe) * 16 + wc * 4 + (fr & 1) * 2 + (fq >> 1)) * W_SSM + p0) * 2u; EPI_OPAQUE(glo);
;     ...
;         EPI_PIECES({ const unsigned uoff = ulo + (unsigned)(rl * UA_LD) * 2u, goff = glo + (unsigned)(rl * 16 * W_SSM) * 2u;
;             S2_ONE(p1a, p1b, uoff, goff); S2_ONE(p2a, p2b, uoff + UA_LD * 2, goff + 16 * W_SSM * 2); })
.LBB0_285:
	s_lshl_b32 s12, s12, 4
	s_ashr_i32 s13, s12, 31
	s_mul_i32 s22, s35, 0x30000
	s_mul_hi_i32 s23, s35, 0x30000
	s_add_u32 s22, s44, s22
	v_lshl_add_u64 v[44:45], s[12:13], 2, v[144:145]
	s_addc_u32 s23, s45, s23
	v_mov_b32_e32 v157, v151
	v_mov_b32_e32 v156, v152
	global_load_dwordx4 v[40:43], v[44:45], off offset:16
	s_nop 0
	global_load_dwordx4 v[44:47], v[44:45], off
	global_load_dwordx4 v[158:161], v157, s[22:23]
	v_add_u32_e32 v178, 0x300, v157
	global_load_dwordx4 v[180:183], v178, s[22:23]
	v_add_u32_e32 v179, 0x3000, v157
	global_load_dwordx4 v[184:187], v179, s[22:23]
	v_add_u32_e32 v178, 0x3300, v157
	global_load_dwordx4 v[188:191], v178, s[22:23]
	v_add_u32_e32 v179, 0x6000, v157
	global_load_dwordx4 v[192:195], v179, s[22:23]
	v_add_u32_e32 v178, 0x6300, v157
	global_load_dwordx4 v[196:199], v178, s[22:23]
	v_add_u32_e32 v179, 0x9000, v157
	global_load_dwordx4 v[200:203], v179, s[22:23]
	v_add_u32_e32 v178, 0x9300, v157
	global_load_dwordx4 v[204:207], v178, s[22:23]
	v_add_u32_e32 v179, 0x18000, v157
	global_load_dwordx4 v[208:211], v179, s[22:23]
	v_add_u32_e32 v178, 0x18300, v157
	global_load_dwordx4 v[220:223], v178, s[22:23]
	v_add_u32_e32 v179, 0x1b000, v157
	global_load_dwordx4 v[224:227], v179, s[22:23]
	v_add_u32_e32 v178, 0x1b300, v157
	global_load_dwordx4 v[228:231], v178, s[22:23]
	v_add_u32_e32 v179, 0x1e000, v157
	global_load_dwordx4 v[232:235], v179, s[22:23]
	v_add_u32_e32 v178, 0x1e300, v157
	global_load_dwordx4 v[236:239], v178, s[22:23]
	v_add_u32_e32 v179, 0x21000, v157
	global_load_dwordx4 v[240:243], v179, s[22:23]
	v_add_u32_e32 v178, 0x21300, v157
	global_load_dwordx4 v[244:247], v178, s[22:23]
	v_cndmask_b32_e64 v164, v133, v125, s[8:9]
	s_nop 0
	v_cndmask_b32_e64 v162, v135, v127, s[8:9]
	s_nop 0
	v_mov_b32_dpp v167, v164 quad_perm:[1,0,3,2] row_mask:0xf bank_mask:0xf
	v_cndmask_b32_e64 v163, v134, v126, s[8:9]
	v_cndmask_b32_e64 v165, v132, v124, s[8:9]
	s_nop 0
	s_nop 0
	v_mov_b32_dpp v169, v162 quad_perm:[1,0,3,2] row_mask:0xf bank_mask:0xf
	v_cndmask_b32_e64 v133, v167, v133, s[8:9]
	v_mov_b32_dpp v166, v165 quad_perm:[1,0,3,2] row_mask:0xf bank_mask:0xf
	v_mov_b32_dpp v168, v163 quad_perm:[1,0,3,2] row_mask:0xf bank_mask:0xf
	v_cndmask_b32_e64 v135, v169, v135, s[8:9]
	v_cndmask_b32_e64 v132, v166, v132, s[8:9]
	v_cndmask_b32_e64 v170, v131, v123, s[8:9]
	v_cndmask_b32_e64 v173, v128, v120, s[8:9]
	s_nop 0
	s_nop 0
	v_cndmask_b32_e64 v171, v130, v122, s[8:9]
	v_cndmask_b32_e64 v172, v129, v121, s[8:9]
	s_nop 0
	s_nop 0
	v_mov_b32_dpp v174, v173 quad_perm:[1,0,3,2] row_mask:0xf bank_mask:0xf
	v_mov_b32_dpp v177, v170 quad_perm:[1,0,3,2] row_mask:0xf bank_mask:0xf
	v_mov_b32_dpp v175, v172 quad_perm:[1,0,3,2] row_mask:0xf bank_mask:0xf
	v_mov_b32_dpp v176, v171 quad_perm:[1,0,3,2] row_mask:0xf bank_mask:0xf
	v_cndmask_b32_e64 v131, v177, v131, s[8:9]
	v_cndmask_b32_e64 v128, v174, v128, s[8:9]
	v_cndmask_b32_e64 v134, v168, v134, s[8:9]
	v_cndmask_b32_e64 v130, v176, v130, s[8:9]
	v_cndmask_b32_e64 v129, v175, v129, s[8:9]
	s_lshl_b32 s24, s35, 24
	s_and_b32 s24, s24, 0x3000000
	s_add_u32 s24, s59, s24
	s_addc_u32 s25, s60, 0
	s_lshl_b64 s[12:13], s[12:13], 1
	s_add_u32 s12, s24, s12
	s_addc_u32 s13, s25, s13
	v_cndmask_b32_e64 v124, v124, v166, s[8:9]
	v_cndmask_b32_e64 v125, v125, v167, s[8:9]
	v_cndmask_b32_e64 v127, v127, v169, s[8:9]
	v_cndmask_b32_e64 v121, v121, v175, s[8:9]
	v_cndmask_b32_e64 v120, v120, v174, s[8:9]
	v_cndmask_b32_e64 v123, v123, v177, s[8:9]
	v_cndmask_b32_e64 v126, v126, v168, s[8:9]
	v_cndmask_b32_e64 v122, v122, v176, s[8:9]
	s_and_b64 vcc, exec, s[10:11]
	s_mov_b64 s[10:11], -1
	s_waitcnt vmcnt(15)
	v_lshlrev_b32_e32 v162, 16, v158
	v_and_b32_e32 v158, 0xffff0000, v158
	v_lshlrev_b32_e32 v163, 16, v159
	v_and_b32_e32 v159, 0xffff0000, v159
	v_fmac_f32_e32 v133, v45, v158
	v_fmac_f32_e32 v135, v47, v159
	v_mul_f32_e32 v159, 0x3d372713, v133
	v_fmac_f32_e32 v132, v44, v162
	v_mul_f32_e32 v159, v133, v159
	v_mul_f32_e32 v158, 0x3d372713, v132
	v_fma_f32 v159, v133, v159, v133
	v_mul_f32_e32 v158, v132, v158
	v_mul_f32_e32 v159, 0x3f4c422a, v159
	v_fma_f32 v158, v132, v158, v132
	v_add_f32_e32 v159, v159, v159
	v_mul_f32_e32 v158, 0x3f4c422a, v158
	v_mul_f32_e32 v159, 0xbfb8aa3b, v159
	v_add_f32_e32 v158, v158, v158
	v_exp_f32_e32 v159, v159
	v_mul_f32_e32 v158, 0xbfb8aa3b, v158
	v_exp_f32_e32 v158, v158
	v_lshlrev_b32_e32 v164, 16, v160
	v_add_f32_e32 v159, 1.0, v159
	v_rcp_f32_e32 v159, v159
	v_add_f32_e32 v158, 1.0, v158
	v_rcp_f32_e32 v158, v158
	v_fmac_f32_e32 v128, v40, v164
	v_mul_f32_e32 v133, v133, v159
	v_and_b32_e32 v159, 0xffff0000, v160
	v_lshlrev_b32_e32 v160, 16, v161
	v_and_b32_e32 v161, 0xffff0000, v161
	v_fmac_f32_e32 v131, v43, v161
	v_fmac_f32_e32 v134, v46, v163
	v_mul_f32_e32 v132, v132, v158
	v_mul_f32_e32 v158, 0x3d372713, v128
	v_fmac_f32_e32 v129, v41, v159
	v_fmac_f32_e32 v130, v42, v160
	v_mul_f32_e32 v161, 0x3d372713, v131
	v_mul_f32_e32 v162, 0x3d372713, v134
	v_mul_f32_e32 v163, 0x3d372713, v135
	v_mul_f32_e32 v158, v128, v158
	v_mul_f32_e32 v159, 0x3d372713, v129
	v_mul_f32_e32 v160, 0x3d372713, v130
	v_mul_f32_e32 v161, v131, v161
	v_mul_f32_e32 v162, v134, v162
	v_mul_f32_e32 v163, v135, v163
	v_fma_f32 v158, v128, v158, v128
	v_mul_f32_e32 v159, v129, v159
	v_mul_f32_e32 v160, v130, v160
	v_fma_f32 v161, v131, v161, v131
	v_fma_f32 v162, v134, v162, v134
	v_fma_f32 v163, v135, v163, v135
	v_mul_f32_e32 v158, 0x3f4c422a, v158
	v_fma_f32 v159, v129, v159, v129
	v_fma_f32 v160, v130, v160, v130
	v_mul_f32_e32 v161, 0x3f4c422a, v161
	v_mul_f32_e32 v162, 0x3f4c422a, v162
	v_mul_f32_e32 v163, 0x3f4c422a, v163
	v_add_f32_e32 v158, v158, v158
; #define EPI_OPAQUE(x) asm volatile("" : "+v"(x))
; __device__ __forceinline__ float fast_exp(float x) { return __builtin_amdgcn_exp2f(x * 1.4426950408889634f); }
; __device__ __forceinline__ float fast_sigmoid(float x) { return __builtin_amdgcn_rcpf(1.0f + fast_exp(-x)); }
; __device__ __forceinline__ float gelu_tanh(float x) {
;     const float a = 0.7978845608028654f * (x + 0.044715f * x * x * x);
;     return x * fast_sigmoid(2.0f * a);
; }
;     __device__ __forceinline__ void operator()(const f32x4 (&acc)[2][2][4][2], const Unit& u, int wr, int wc, int fr, int fq, const EpiCtx& X) const {
;         const bool odd = fr & 1; const int fe = fr - (fr & 1), o32 = (fr & 1) * 32;
;         const int g = u.pn; const int p0 = 8 * (fq & 1);
;         const f32x4 d0 = *(const f32x4*)(dvec + g * 16 + p0), d1 = *(const f32x4*)(dvec + g * 16 + p0 + 4);
;         const char* ub = (const char*)(UA + (size_t)u.pm * BM * UA_LD);
;         unsigned ulo = (unsigned)((wr * 64 + fe) * UA_LD + wc * 64 + o32 + 8 * fq) * 2u; EPI_OPAQUE(ulo);
;         char* gb = (char*)(GACT + (size_t)(u.pm & 3) * 256 * 16 * W_SSM + g * 16);
;         unsigned glo = (unsigned)(((wr * 64 + fe) * 16 + wc * 4 + (fr & 1) * 2 + (fq >> 1)) * W_SSM + p0) * 2u; EPI_OPAQUE(glo);
;     ...
;         EPI_PIECES({ const unsigned uoff = ulo + (unsigned)(rl * UA_LD) * 2u, goff = glo + (unsigned)(rl * 16 * W_SSM) * 2u;
;             S2_ONE(p1a, p1b, uoff, goff); S2_ONE(p2a, p2b, uoff + UA_LD * 2, goff + 16 * W_SSM * 2); })
	v_mul_f32_e32 v159, 0x3f4c422a, v159
	v_mul_f32_e32 v160, 0x3f4c422a, v160
	v_add_f32_e32 v161, v161, v161
	v_add_f32_e32 v162, v162, v162
	v_add_f32_e32 v163, v163, v163
	v_mul_f32_e32 v158, 0xbfb8aa3b, v158
	v_add_f32_e32 v159, v159, v159
	v_add_f32_e32 v160, v160, v160
	v_mul_f32_e32 v161, 0xbfb8aa3b, v161
	v_mul_f32_e32 v162, 0xbfb8aa3b, v162
	v_mul_f32_e32 v163, 0xbfb8aa3b, v163
	v_exp_f32_e32 v158, v158
	v_mul_f32_e32 v159, 0xbfb8aa3b, v159
	v_mul_f32_e32 v160, 0xbfb8aa3b, v160
	v_exp_f32_e32 v161, v161
	v_exp_f32_e32 v162, v162
	v_exp_f32_e32 v163, v163
	v_exp_f32_e32 v159, v159
	v_exp_f32_e32 v160, v160
	v_add_f32_e32 v158, 1.0, v158
	v_add_f32_e32 v161, 1.0, v161
	v_add_f32_e32 v162, 1.0, v162
	v_add_f32_e32 v163, 1.0, v163
	v_rcp_f32_e32 v158, v158
	v_add_f32_e32 v159, 1.0, v159
	v_add_f32_e32 v160, 1.0, v160
	v_rcp_f32_e32 v161, v161
	v_rcp_f32_e32 v162, v162
	v_rcp_f32_e32 v163, v163
	v_rcp_f32_e32 v159, v159
	v_rcp_f32_e32 v160, v160
	v_mul_f32_e32 v158, v128, v158
	v_mul_f32_e32 v131, v131, v161
	v_cvt_pk_bf16_f32 v128, v132, v133
	v_mul_f32_e32 v134, v134, v162
	v_mul_f32_e32 v135, v135, v163
	v_mul_f32_e32 v159, v129, v159
	v_mul_f32_e32 v160, v130, v160
	v_cvt_pk_bf16_f32 v129, v134, v135
	v_cvt_pk_bf16_f32 v130, v158, v159
	v_cvt_pk_bf16_f32 v131, v160, v131
	global_store_dwordx4 v156, v[128:131], s[12:13]
	s_nop 1
	v_add_u32_e32 v128, 0x300, v157
	s_waitcnt vmcnt(15)
	s_nop 1
	v_mov_b32_e32 v128, v180
	v_mov_b32_e32 v129, v181
	v_mov_b32_e32 v130, v182
	v_mov_b32_e32 v131, v183
	v_lshlrev_b32_e32 v132, 16, v128
	v_and_b32_e32 v128, 0xffff0000, v128
	v_fmac_f32_e32 v124, v44, v132
	v_fmac_f32_e32 v125, v45, v128
	v_mul_f32_e32 v128, 0x3d372713, v124
	v_mul_f32_e32 v128, v124, v128
	v_fma_f32 v128, v124, v128, v124
	v_lshlrev_b32_e32 v133, 16, v129
	v_mul_f32_e32 v128, 0x3f4c422a, v128
	v_and_b32_e32 v129, 0xffff0000, v129
	v_add_f32_e32 v128, v128, v128
	v_fmac_f32_e32 v127, v47, v129
	v_mul_f32_e32 v128, 0xbfb8aa3b, v128
	v_mul_f32_e32 v129, 0x3d372713, v127
	v_exp_f32_e32 v128, v128
	v_mul_f32_e32 v129, v127, v129
	v_fma_f32 v129, v127, v129, v127
	v_mul_f32_e32 v129, 0x3f4c422a, v129
	v_add_f32_e32 v129, v129, v129
	v_add_f32_e32 v128, 1.0, v128
	v_mul_f32_e32 v129, 0xbfb8aa3b, v129
	v_rcp_f32_e32 v128, v128
	v_exp_f32_e32 v129, v129
	v_fmac_f32_e32 v126, v46, v133
	v_mul_f32_e32 v132, 0x3d372713, v125
	v_mul_f32_e32 v124, v124, v128
	v_add_f32_e32 v128, 1.0, v129
	v_lshlrev_b32_e32 v129, 16, v130
	v_and_b32_e32 v130, 0xffff0000, v130
	v_fmac_f32_e32 v120, v40, v129
	v_fmac_f32_e32 v121, v41, v130
	v_mul_f32_e32 v129, 0x3d372713, v120
	v_mul_f32_e32 v130, 0x3d372713, v121
	v_mul_f32_e32 v129, v120, v129
	v_mul_f32_e32 v130, v121, v130
	v_fma_f32 v129, v120, v129, v120
	v_fma_f32 v130, v121, v130, v121
	v_mul_f32_e32 v129, 0x3f4c422a, v129
	v_mul_f32_e32 v130, 0x3f4c422a, v130
	v_add_f32_e32 v129, v129, v129
	v_add_f32_e32 v130, v130, v130
	v_mul_f32_e32 v129, 0xbfb8aa3b, v129
	v_mul_f32_e32 v130, 0xbfb8aa3b, v130
	v_rcp_f32_e32 v128, v128
	v_exp_f32_e32 v129, v129
	v_exp_f32_e32 v130, v130
	v_mul_f32_e32 v133, 0x3d372713, v126
	v_mul_f32_e32 v127, v127, v128
	v_add_f32_e32 v128, 1.0, v129
	v_add_f32_e32 v129, 1.0, v130
	v_lshlrev_b32_e32 v130, 16, v131
	v_and_b32_e32 v131, 0xffff0000, v131
	v_fmac_f32_e32 v123, v43, v131
	v_fmac_f32_e32 v122, v42, v130
	v_mul_f32_e32 v131, 0x3d372713, v123
	v_mul_f32_e32 v132, v125, v132
	v_mul_f32_e32 v130, 0x3d372713, v122
	v_mul_f32_e32 v131, v123, v131
	v_mul_f32_e32 v133, v126, v133
	v_fma_f32 v132, v125, v132, v125
	v_mul_f32_e32 v130, v122, v130
	v_fma_f32 v131, v123, v131, v123
	v_fma_f32 v133, v126, v133, v126
	v_mul_f32_e32 v132, 0x3f4c422a, v132
	v_fma_f32 v130, v122, v130, v122
	v_mul_f32_e32 v131, 0x3f4c422a, v131
	v_mul_f32_e32 v133, 0x3f4c422a, v133
	v_add_f32_e32 v132, v132, v132
	v_mul_f32_e32 v130, 0x3f4c422a, v130
	v_add_f32_e32 v131, v131, v131
	v_add_f32_e32 v133, v133, v133
	v_mul_f32_e32 v132, 0xbfb8aa3b, v132
	v_add_f32_e32 v130, v130, v130
	v_mul_f32_e32 v131, 0xbfb8aa3b, v131
	v_mul_f32_e32 v133, 0xbfb8aa3b, v133
	v_exp_f32_e32 v132, v132
	v_mul_f32_e32 v130, 0xbfb8aa3b, v130
	v_exp_f32_e32 v131, v131
	v_exp_f32_e32 v133, v133
	v_exp_f32_e32 v130, v130
	v_add_f32_e32 v132, 1.0, v132
	v_add_f32_e32 v131, 1.0, v131
	v_add_f32_e32 v133, 1.0, v133
	v_rcp_f32_e32 v132, v132
	v_rcp_f32_e32 v128, v128
	v_add_f32_e32 v130, 1.0, v130
	v_rcp_f32_e32 v131, v131
	v_rcp_f32_e32 v133, v133
	v_rcp_f32_e32 v129, v129
	v_rcp_f32_e32 v130, v130
	v_mul_f32_e32 v125, v125, v132
	v_mul_f32_e32 v128, v120, v128
	v_mul_f32_e32 v123, v123, v131
	v_cvt_pk_bf16_f32 v120, v124, v125
	v_add_u32_e32 v124, 0x10000, v156
	v_mul_f32_e32 v126, v126, v133
	v_mul_f32_e32 v129, v121, v129
	v_mul_f32_e32 v130, v122, v130
	v_cvt_pk_bf16_f32 v121, v126, v127
	v_cvt_pk_bf16_f32 v122, v128, v129
	v_cvt_pk_bf16_f32 v123, v130, v123
	global_store_dwordx4 v124, v[120:123], s[12:13]
	v_cndmask_b32_e64 v127, v116, v108, s[8:9]
	s_nop 0
	v_add_u32_e32 v120, 0x3000, v157
	s_waitcnt vmcnt(15)
; #define EPI_OPAQUE(x) asm volatile("" : "+v"(x))
; __device__ __forceinline__ float fast_exp(float x) { return __builtin_amdgcn_exp2f(x * 1.4426950408889634f); }
; __device__ __forceinline__ float fast_sigmoid(float x) { return __builtin_amdgcn_rcpf(1.0f + fast_exp(-x)); }
; __device__ __forceinline__ float gelu_tanh(float x) {
;     const float a = 0.7978845608028654f * (x + 0.044715f * x * x * x);
;     return x * fast_sigmoid(2.0f * a);
; }
;     __device__ __forceinline__ void operator()(const f32x4 (&acc)[2][2][4][2], const Unit& u, int wr, int wc, int fr, int fq, const EpiCtx& X) const {
;         const bool odd = fr & 1; const int fe = fr - (fr & 1), o32 = (fr & 1) * 32;
;         const int g = u.pn; const int p0 = 8 * (fq & 1);
;         const f32x4 d0 = *(const f32x4*)(dvec + g * 16 + p0), d1 = *(const f32x4*)(dvec + g * 16 + p0 + 4);
;         const char* ub = (const char*)(UA + (size_t)u.pm * BM * UA_LD);
;         unsigned ulo = (unsigned)((wr * 64 + fe) * UA_LD + wc * 64 + o32 + 8 * fq) * 2u; EPI_OPAQUE(ulo);
;         char* gb = (char*)(GACT + (size_t)(u.pm & 3) * 256 * 16 * W_SSM + g * 16);
;         unsigned glo = (unsigned)(((wr * 64 + fe) * 16 + wc * 4 + (fr & 1) * 2 + (fq >> 1)) * W_SSM + p0) * 2u; EPI_OPAQUE(glo);
;     ...
;         EPI_PIECES({ const unsigned uoff = ulo + (unsigned)(rl * UA_LD) * 2u, goff = glo + (unsigned)(rl * 16 * W_SSM) * 2u;
;             S2_ONE(p1a, p1b, uoff, goff); S2_ONE(p2a, p2b, uoff + UA_LD * 2, goff + 16 * W_SSM * 2); })
	s_nop 1
	v_mov_b32_e32 v120, v184
	v_mov_b32_e32 v121, v185
	v_mov_b32_e32 v122, v186
	v_mov_b32_e32 v123, v187
	v_cndmask_b32_e64 v126, v117, v109, s[8:9]
	v_mov_b32_dpp v128, v127 quad_perm:[1,0,3,2] row_mask:0xf bank_mask:0xf
	s_nop 0
	v_cndmask_b32_e64 v131, v112, v104, s[8:9]
	s_nop 0
	v_cndmask_b32_e64 v125, v118, v110, s[8:9]
	v_mov_b32_dpp v127, v126 quad_perm:[1,0,3,2] row_mask:0xf bank_mask:0xf
	s_nop 0
	v_cndmask_b32_e64 v130, v113, v105, s[8:9]
	v_mov_b32_dpp v132, v131 quad_perm:[1,0,3,2] row_mask:0xf bank_mask:0xf
	s_nop 0
	v_cndmask_b32_e64 v124, v119, v111, s[8:9]
	v_mov_b32_dpp v126, v125 quad_perm:[1,0,3,2] row_mask:0xf bank_mask:0xf
	s_nop 0
	v_cndmask_b32_e64 v129, v114, v106, s[8:9]
	v_mov_b32_dpp v131, v130 quad_perm:[1,0,3,2] row_mask:0xf bank_mask:0xf
	s_nop 0
	v_mov_b32_dpp v125, v124 quad_perm:[1,0,3,2] row_mask:0xf bank_mask:0xf
	v_cndmask_b32_e64 v124, v115, v107, s[8:9]
	v_mov_b32_dpp v130, v129 quad_perm:[1,0,3,2] row_mask:0xf bank_mask:0xf
	s_nop 0
	v_cndmask_b32_e64 v117, v127, v117, s[8:9]
	v_cndmask_b32_e64 v119, v125, v119, s[8:9]
	v_mov_b32_dpp v129, v124 quad_perm:[1,0,3,2] row_mask:0xf bank_mask:0xf
	v_cndmask_b32_e64 v113, v131, v113, s[8:9]
	v_cndmask_b32_e64 v112, v132, v112, s[8:9]
	v_cndmask_b32_e64 v116, v128, v116, s[8:9]
	v_cndmask_b32_e64 v115, v129, v115, s[8:9]
	v_cndmask_b32_e64 v118, v126, v118, s[8:9]
	v_cndmask_b32_e64 v114, v130, v114, s[8:9]
	v_add_u32_e32 v133, 0x100000, v156
	v_cndmask_b32_e64 v109, v109, v127, s[8:9]
	v_cndmask_b32_e64 v111, v111, v125, s[8:9]
	v_cndmask_b32_e64 v105, v105, v131, s[8:9]
	v_cndmask_b32_e64 v104, v104, v132, s[8:9]
	v_cndmask_b32_e64 v108, v108, v128, s[8:9]
	v_cndmask_b32_e64 v107, v107, v129, s[8:9]
	v_cndmask_b32_e64 v110, v110, v126, s[8:9]
	v_cndmask_b32_e64 v106, v106, v130, s[8:9]
	v_lshlrev_b32_e32 v124, 16, v120
	v_and_b32_e32 v120, 0xffff0000, v120
	v_fmac_f32_e32 v117, v45, v120
	v_mul_f32_e32 v120, 0x3d372713, v117
	v_mul_f32_e32 v120, v117, v120
	v_fma_f32 v120, v117, v120, v117
	v_mul_f32_e32 v120, 0x3f4c422a, v120
	v_lshlrev_b32_e32 v134, 16, v121
	v_and_b32_e32 v121, 0xffff0000, v121
	v_add_f32_e32 v120, v120, v120
	v_fmac_f32_e32 v119, v47, v121
	v_mul_f32_e32 v120, 0xbfb8aa3b, v120
	v_mul_f32_e32 v121, 0x3d372713, v119
	v_exp_f32_e32 v120, v120
	v_mul_f32_e32 v121, v119, v121
	v_fma_f32 v121, v119, v121, v119
	v_mul_f32_e32 v121, 0x3f4c422a, v121
	v_add_f32_e32 v121, v121, v121
	v_add_f32_e32 v120, 1.0, v120
	v_mul_f32_e32 v121, 0xbfb8aa3b, v121
	v_rcp_f32_e32 v120, v120
	v_exp_f32_e32 v121, v121
	v_fmac_f32_e32 v116, v44, v124
	v_mul_f32_e32 v124, 0x3d372713, v116
	v_mul_f32_e32 v117, v117, v120
	v_add_f32_e32 v120, 1.0, v121
	v_lshlrev_b32_e32 v121, 16, v122
	v_and_b32_e32 v122, 0xffff0000, v122
	v_fmac_f32_e32 v112, v40, v121
	v_fmac_f32_e32 v113, v41, v122
	v_mul_f32_e32 v121, 0x3d372713, v112
	v_mul_f32_e32 v122, 0x3d372713, v113
	v_mul_f32_e32 v121, v112, v121
	v_mul_f32_e32 v122, v113, v122
	v_fma_f32 v121, v112, v121, v112
	v_fma_f32 v122, v113, v122, v113
	v_mul_f32_e32 v121, 0x3f4c422a, v121
	v_mul_f32_e32 v122, 0x3f4c422a, v122
	v_add_f32_e32 v121, v121, v121
	v_add_f32_e32 v122, v122, v122
	v_mul_f32_e32 v121, 0xbfb8aa3b, v121
	v_mul_f32_e32 v122, 0xbfb8aa3b, v122
	v_rcp_f32_e32 v120, v120
	v_exp_f32_e32 v121, v121
	v_exp_f32_e32 v122, v122
	v_fmac_f32_e32 v118, v46, v134
	v_mul_f32_e32 v119, v119, v120
	v_add_f32_e32 v120, 1.0, v121
	v_add_f32_e32 v121, 1.0, v122
	v_lshlrev_b32_e32 v122, 16, v123
	v_and_b32_e32 v123, 0xffff0000, v123
	v_fmac_f32_e32 v115, v43, v123
	v_fmac_f32_e32 v114, v42, v122
	v_mul_f32_e32 v123, 0x3d372713, v115
	v_mul_f32_e32 v124, v116, v124
	v_mul_f32_e32 v134, 0x3d372713, v118
	v_mul_f32_e32 v122, 0x3d372713, v114
	v_mul_f32_e32 v123, v115, v123
	v_fma_f32 v124, v116, v124, v116
	v_mul_f32_e32 v134, v118, v134
	v_mul_f32_e32 v122, v114, v122
	v_fma_f32 v123, v115, v123, v115
	v_mul_f32_e32 v124, 0x3f4c422a, v124
	v_fma_f32 v134, v118, v134, v118
	v_fma_f32 v122, v114, v122, v114
	v_mul_f32_e32 v123, 0x3f4c422a, v123
	v_add_f32_e32 v124, v124, v124
	v_mul_f32_e32 v134, 0x3f4c422a, v134
	v_mul_f32_e32 v122, 0x3f4c422a, v122
	v_add_f32_e32 v123, v123, v123
	v_mul_f32_e32 v124, 0xbfb8aa3b, v124
	v_add_f32_e32 v134, v134, v134
	v_add_f32_e32 v122, v122, v122
	v_mul_f32_e32 v123, 0xbfb8aa3b, v123
	v_exp_f32_e32 v124, v124
	v_mul_f32_e32 v134, 0xbfb8aa3b, v134
	v_mul_f32_e32 v122, 0xbfb8aa3b, v122
	v_exp_f32_e32 v123, v123
	v_exp_f32_e32 v134, v134
	v_exp_f32_e32 v122, v122
	v_add_f32_e32 v124, 1.0, v124
	v_add_f32_e32 v123, 1.0, v123
	v_rcp_f32_e32 v124, v124
	v_add_f32_e32 v134, 1.0, v134
	v_rcp_f32_e32 v120, v120
	v_add_f32_e32 v122, 1.0, v122
	v_rcp_f32_e32 v123, v123
	v_rcp_f32_e32 v134, v134
	v_rcp_f32_e32 v121, v121
	v_rcp_f32_e32 v122, v122
	v_mul_f32_e32 v116, v116, v124
	v_mul_f32_e32 v120, v112, v120
	v_mul_f32_e32 v115, v115, v123
	v_cvt_pk_bf16_f32 v112, v116, v117
	v_mul_f32_e32 v118, v118, v134
	v_mul_f32_e32 v121, v113, v121
	v_mul_f32_e32 v122, v114, v122
	v_cvt_pk_bf16_f32 v113, v118, v119
	v_cvt_pk_bf16_f32 v114, v120, v121
	v_cvt_pk_bf16_f32 v115, v122, v115
	global_store_dwordx4 v133, v[112:115], s[12:13]
	s_nop 1
	v_add_u32_e32 v112, 0x3300, v157
	s_waitcnt vmcnt(15)
; #define EPI_OPAQUE(x) asm volatile("" : "+v"(x))
; __device__ __forceinline__ float fast_exp(float x) { return __builtin_amdgcn_exp2f(x * 1.4426950408889634f); }
; __device__ __forceinline__ float fast_sigmoid(float x) { return __builtin_amdgcn_rcpf(1.0f + fast_exp(-x)); }
; __device__ __forceinline__ float gelu_tanh(float x) {
;     const float a = 0.7978845608028654f * (x + 0.044715f * x * x * x);
;     return x * fast_sigmoid(2.0f * a);
; }
;     __device__ __forceinline__ void operator()(const f32x4 (&acc)[2][2][4][2], const Unit& u, int wr, int wc, int fr, int fq, const EpiCtx& X) const {
;         const bool odd = fr & 1; const int fe = fr - (fr & 1), o32 = (fr & 1) * 32;
;         const int g = u.pn; const int p0 = 8 * (fq & 1);
;         const f32x4 d0 = *(const f32x4*)(dvec + g * 16 + p0), d1 = *(const f32x4*)(dvec + g * 16 + p0 + 4);
;         const char* ub = (const char*)(UA + (size_t)u.pm * BM * UA_LD);
;         unsigned ulo = (unsigned)((wr * 64 + fe) * UA_LD + wc * 64 + o32 + 8 * fq) * 2u; EPI_OPAQUE(ulo);
;         char* gb = (char*)(GACT + (size_t)(u.pm & 3) * 256 * 16 * W_SSM + g * 16);
;         unsigned glo = (unsigned)(((wr * 64 + fe) * 16 + wc * 4 + (fr & 1) * 2 + (fq >> 1)) * W_SSM + p0) * 2u; EPI_OPAQUE(glo);
;     ...
;         EPI_PIECES({ const unsigned uoff = ulo + (unsigned)(rl * UA_LD) * 2u, goff = glo + (unsigned)(rl * 16 * W_SSM) * 2u;
;             S2_ONE(p1a, p1b, uoff, goff); S2_ONE(p2a, p2b, uoff + UA_LD * 2, goff + 16 * W_SSM * 2); })
	s_nop 1
	v_mov_b32_e32 v112, v188
	v_mov_b32_e32 v113, v189
	v_mov_b32_e32 v114, v190
	v_mov_b32_e32 v115, v191
	v_lshlrev_b32_e32 v116, 16, v112
	v_and_b32_e32 v112, 0xffff0000, v112
	v_fmac_f32_e32 v109, v45, v112
	v_mul_f32_e32 v112, 0x3d372713, v109
	v_mul_f32_e32 v112, v109, v112
	v_fma_f32 v112, v109, v112, v109
	v_mul_f32_e32 v112, 0x3f4c422a, v112
	v_lshlrev_b32_e32 v117, 16, v113
	v_and_b32_e32 v113, 0xffff0000, v113
	v_add_f32_e32 v112, v112, v112
	v_fmac_f32_e32 v111, v47, v113
	v_mul_f32_e32 v112, 0xbfb8aa3b, v112
	v_mul_f32_e32 v113, 0x3d372713, v111
	v_exp_f32_e32 v112, v112
	v_mul_f32_e32 v113, v111, v113
	v_fma_f32 v113, v111, v113, v111
	v_mul_f32_e32 v113, 0x3f4c422a, v113
	v_add_f32_e32 v113, v113, v113
	v_add_f32_e32 v112, 1.0, v112
	v_mul_f32_e32 v113, 0xbfb8aa3b, v113
	v_rcp_f32_e32 v112, v112
	v_exp_f32_e32 v113, v113
	v_fmac_f32_e32 v108, v44, v116
	v_mul_f32_e32 v116, 0x3d372713, v108
	v_mul_f32_e32 v109, v109, v112
	v_add_f32_e32 v112, 1.0, v113
	v_lshlrev_b32_e32 v113, 16, v114
	v_and_b32_e32 v114, 0xffff0000, v114
	v_fmac_f32_e32 v104, v40, v113
	v_fmac_f32_e32 v105, v41, v114
	v_mul_f32_e32 v113, 0x3d372713, v104
	v_mul_f32_e32 v114, 0x3d372713, v105
	v_mul_f32_e32 v113, v104, v113
	v_mul_f32_e32 v114, v105, v114
	v_fma_f32 v113, v104, v113, v104
	v_fma_f32 v114, v105, v114, v105
	v_mul_f32_e32 v113, 0x3f4c422a, v113
	v_mul_f32_e32 v114, 0x3f4c422a, v114
	v_add_f32_e32 v113, v113, v113
	v_add_f32_e32 v114, v114, v114
	v_mul_f32_e32 v113, 0xbfb8aa3b, v113
	v_mul_f32_e32 v114, 0xbfb8aa3b, v114
	v_rcp_f32_e32 v112, v112
	v_exp_f32_e32 v113, v113
	v_exp_f32_e32 v114, v114
	v_mul_f32_e32 v116, v108, v116
	v_mul_f32_e32 v111, v111, v112
	v_add_f32_e32 v112, 1.0, v113
	v_add_f32_e32 v113, 1.0, v114
	v_lshlrev_b32_e32 v114, 16, v115
	v_and_b32_e32 v115, 0xffff0000, v115
	v_fmac_f32_e32 v107, v43, v115
	v_fmac_f32_e32 v110, v46, v117
	v_fmac_f32_e32 v106, v42, v114
	v_mul_f32_e32 v115, 0x3d372713, v107
	v_fma_f32 v116, v108, v116, v108
	v_mul_f32_e32 v117, 0x3d372713, v110
	v_mul_f32_e32 v114, 0x3d372713, v106
	v_mul_f32_e32 v115, v107, v115
	v_mul_f32_e32 v116, 0x3f4c422a, v116
	v_mul_f32_e32 v117, v110, v117
	v_mul_f32_e32 v114, v106, v114
	v_fma_f32 v115, v107, v115, v107
	v_add_f32_e32 v116, v116, v116
	v_fma_f32 v117, v110, v117, v110
	v_fma_f32 v114, v106, v114, v106
	v_mul_f32_e32 v115, 0x3f4c422a, v115
	v_mul_f32_e32 v116, 0xbfb8aa3b, v116
	v_mul_f32_e32 v117, 0x3f4c422a, v117
	v_mul_f32_e32 v114, 0x3f4c422a, v114
	v_add_f32_e32 v115, v115, v115
	v_exp_f32_e32 v116, v116
	v_add_f32_e32 v117, v117, v117
	v_add_f32_e32 v114, v114, v114
	v_mul_f32_e32 v115, 0xbfb8aa3b, v115
	v_mul_f32_e32 v117, 0xbfb8aa3b, v117
	v_mul_f32_e32 v114, 0xbfb8aa3b, v114
	v_exp_f32_e32 v115, v115
	v_exp_f32_e32 v117, v117
	v_exp_f32_e32 v114, v114
	v_add_f32_e32 v116, 1.0, v116
	v_rcp_f32_e32 v116, v116
	v_add_f32_e32 v115, 1.0, v115
	v_add_f32_e32 v117, 1.0, v117
	v_rcp_f32_e32 v112, v112
	v_add_f32_e32 v114, 1.0, v114
	v_rcp_f32_e32 v115, v115
	v_rcp_f32_e32 v117, v117
	v_rcp_f32_e32 v113, v113
	v_rcp_f32_e32 v114, v114
	v_mul_f32_e32 v108, v108, v116
	v_mul_f32_e32 v112, v104, v112
	v_mul_f32_e32 v107, v107, v115
	v_cvt_pk_bf16_f32 v104, v108, v109
	v_add_u32_e32 v108, 0x110000, v156
	v_mul_f32_e32 v110, v110, v117
	v_mul_f32_e32 v113, v105, v113
	v_mul_f32_e32 v114, v106, v114
	v_cvt_pk_bf16_f32 v105, v110, v111
	v_cvt_pk_bf16_f32 v106, v112, v113
	v_cvt_pk_bf16_f32 v107, v114, v107
	global_store_dwordx4 v108, v[104:107], s[12:13]
	v_cndmask_b32_e64 v111, v100, v92, s[8:9]
	s_nop 0
	v_add_u32_e32 v104, 0x6000, v157
	s_waitcnt vmcnt(15)
	s_nop 1
	v_mov_b32_e32 v104, v192
	v_mov_b32_e32 v105, v193
	v_mov_b32_e32 v106, v194
	v_mov_b32_e32 v107, v195
	v_cndmask_b32_e64 v110, v101, v93, s[8:9]
	v_mov_b32_dpp v112, v111 quad_perm:[1,0,3,2] row_mask:0xf bank_mask:0xf
	s_nop 0
	v_cndmask_b32_e64 v115, v96, v88, s[8:9]
	s_nop 0
	v_cndmask_b32_e64 v109, v102, v94, s[8:9]
	v_mov_b32_dpp v111, v110 quad_perm:[1,0,3,2] row_mask:0xf bank_mask:0xf
	s_nop 0
	v_cndmask_b32_e64 v114, v97, v89, s[8:9]
	v_mov_b32_dpp v116, v115 quad_perm:[1,0,3,2] row_mask:0xf bank_mask:0xf
	s_nop 0
	v_cndmask_b32_e64 v108, v103, v95, s[8:9]
	v_mov_b32_dpp v110, v109 quad_perm:[1,0,3,2] row_mask:0xf bank_mask:0xf
	s_nop 0
	v_cndmask_b32_e64 v113, v98, v90, s[8:9]
	v_mov_b32_dpp v115, v114 quad_perm:[1,0,3,2] row_mask:0xf bank_mask:0xf
	s_nop 0
	v_mov_b32_dpp v109, v108 quad_perm:[1,0,3,2] row_mask:0xf bank_mask:0xf
	v_cndmask_b32_e64 v108, v99, v91, s[8:9]
	v_mov_b32_dpp v114, v113 quad_perm:[1,0,3,2] row_mask:0xf bank_mask:0xf
	s_nop 0
	v_cndmask_b32_e64 v101, v111, v101, s[8:9]
	v_cndmask_b32_e64 v103, v109, v103, s[8:9]
	v_mov_b32_dpp v113, v108 quad_perm:[1,0,3,2] row_mask:0xf bank_mask:0xf
	v_cndmask_b32_e64 v97, v115, v97, s[8:9]
	v_cndmask_b32_e64 v96, v116, v96, s[8:9]
	v_cndmask_b32_e64 v100, v112, v100, s[8:9]
	v_cndmask_b32_e64 v99, v113, v99, s[8:9]
	v_cndmask_b32_e64 v102, v110, v102, s[8:9]
	v_cndmask_b32_e64 v98, v114, v98, s[8:9]
	v_add_u32_e32 v117, 0x200000, v156
	v_cndmask_b32_e64 v93, v93, v111, s[8:9]
	v_cndmask_b32_e64 v95, v95, v109, s[8:9]
	v_cndmask_b32_e64 v89, v89, v115, s[8:9]
	v_cndmask_b32_e64 v88, v88, v116, s[8:9]
	v_cndmask_b32_e64 v92, v92, v112, s[8:9]
	v_cndmask_b32_e64 v91, v91, v113, s[8:9]
	v_cndmask_b32_e64 v94, v94, v110, s[8:9]
	v_cndmask_b32_e64 v90, v90, v114, s[8:9]
	v_lshlrev_b32_e32 v108, 16, v104
	v_and_b32_e32 v104, 0xffff0000, v104
	v_fmac_f32_e32 v101, v45, v104
	v_mul_f32_e32 v104, 0x3d372713, v101
	v_mul_f32_e32 v104, v101, v104
	v_fma_f32 v104, v101, v104, v101
	v_mul_f32_e32 v104, 0x3f4c422a, v104
; #define EPI_OPAQUE(x) asm volatile("" : "+v"(x))
; __device__ __forceinline__ float fast_exp(float x) { return __builtin_amdgcn_exp2f(x * 1.4426950408889634f); }
; __device__ __forceinline__ float fast_sigmoid(float x) { return __builtin_amdgcn_rcpf(1.0f + fast_exp(-x)); }
; __device__ __forceinline__ float gelu_tanh(float x) {
;     const float a = 0.7978845608028654f * (x + 0.044715f * x * x * x);
;     return x * fast_sigmoid(2.0f * a);
; }
;     __device__ __forceinline__ void operator()(const f32x4 (&acc)[2][2][4][2], const Unit& u, int wr, int wc, int fr, int fq, const EpiCtx& X) const {
;         const bool odd = fr & 1; const int fe = fr - (fr & 1), o32 = (fr & 1) * 32;
;         const int g = u.pn; const int p0 = 8 * (fq & 1);
;         const f32x4 d0 = *(const f32x4*)(dvec + g * 16 + p0), d1 = *(const f32x4*)(dvec + g * 16 + p0 + 4);
;         const char* ub = (const char*)(UA + (size_t)u.pm * BM * UA_LD);
;         unsigned ulo = (unsigned)((wr * 64 + fe) * UA_LD + wc * 64 + o32 + 8 * fq) * 2u; EPI_OPAQUE(ulo);
;         char* gb = (char*)(GACT + (size_t)(u.pm & 3) * 256 * 16 * W_SSM + g * 16);
;         unsigned glo = (unsigned)(((wr * 64 + fe) * 16 + wc * 4 + (fr & 1) * 2 + (fq >> 1)) * W_SSM + p0) * 2u; EPI_OPAQUE(glo);
;     ...
;         EPI_PIECES({ const unsigned uoff = ulo + (unsigned)(rl * UA_LD) * 2u, goff = glo + (unsigned)(rl * 16 * W_SSM) * 2u;
;             S2_ONE(p1a, p1b, uoff, goff); S2_ONE(p2a, p2b, uoff + UA_LD * 2, goff + 16 * W_SSM * 2); })
	v_lshlrev_b32_e32 v118, 16, v105
	v_and_b32_e32 v105, 0xffff0000, v105
	v_add_f32_e32 v104, v104, v104
	v_fmac_f32_e32 v103, v47, v105
	v_mul_f32_e32 v104, 0xbfb8aa3b, v104
	v_mul_f32_e32 v105, 0x3d372713, v103
	v_exp_f32_e32 v104, v104
	v_mul_f32_e32 v105, v103, v105
	v_fma_f32 v105, v103, v105, v103
	v_mul_f32_e32 v105, 0x3f4c422a, v105
	v_add_f32_e32 v105, v105, v105
	v_add_f32_e32 v104, 1.0, v104
	v_mul_f32_e32 v105, 0xbfb8aa3b, v105
	v_rcp_f32_e32 v104, v104
	v_exp_f32_e32 v105, v105
	v_fmac_f32_e32 v100, v44, v108
	v_mul_f32_e32 v108, 0x3d372713, v100
	v_mul_f32_e32 v101, v101, v104
	v_add_f32_e32 v104, 1.0, v105
	v_lshlrev_b32_e32 v105, 16, v106
	v_and_b32_e32 v106, 0xffff0000, v106
	v_fmac_f32_e32 v96, v40, v105
	v_fmac_f32_e32 v97, v41, v106
	v_mul_f32_e32 v105, 0x3d372713, v96
	v_mul_f32_e32 v106, 0x3d372713, v97
	v_mul_f32_e32 v105, v96, v105
	v_mul_f32_e32 v106, v97, v106
	v_fma_f32 v105, v96, v105, v96
	v_fma_f32 v106, v97, v106, v97
	v_mul_f32_e32 v105, 0x3f4c422a, v105
	v_mul_f32_e32 v106, 0x3f4c422a, v106
	v_add_f32_e32 v105, v105, v105
	v_add_f32_e32 v106, v106, v106
	v_mul_f32_e32 v105, 0xbfb8aa3b, v105
	v_mul_f32_e32 v106, 0xbfb8aa3b, v106
	v_rcp_f32_e32 v104, v104
	v_exp_f32_e32 v105, v105
	v_exp_f32_e32 v106, v106
	v_fmac_f32_e32 v102, v46, v118
	v_mul_f32_e32 v103, v103, v104
	v_add_f32_e32 v104, 1.0, v105
	v_add_f32_e32 v105, 1.0, v106
	v_lshlrev_b32_e32 v106, 16, v107
	v_and_b32_e32 v107, 0xffff0000, v107
	v_fmac_f32_e32 v99, v43, v107
	v_fmac_f32_e32 v98, v42, v106
	v_mul_f32_e32 v107, 0x3d372713, v99
	v_mul_f32_e32 v108, v100, v108
	v_mul_f32_e32 v118, 0x3d372713, v102
	v_mul_f32_e32 v106, 0x3d372713, v98
	v_mul_f32_e32 v107, v99, v107
	v_fma_f32 v108, v100, v108, v100
	v_mul_f32_e32 v118, v102, v118
	v_mul_f32_e32 v106, v98, v106
	v_fma_f32 v107, v99, v107, v99
	v_mul_f32_e32 v108, 0x3f4c422a, v108
	v_fma_f32 v118, v102, v118, v102
	v_fma_f32 v106, v98, v106, v98
	v_mul_f32_e32 v107, 0x3f4c422a, v107
	v_add_f32_e32 v108, v108, v108
	v_mul_f32_e32 v118, 0x3f4c422a, v118
	v_mul_f32_e32 v106, 0x3f4c422a, v106
	v_add_f32_e32 v107, v107, v107
	v_mul_f32_e32 v108, 0xbfb8aa3b, v108
	v_add_f32_e32 v118, v118, v118
	v_add_f32_e32 v106, v106, v106
	v_mul_f32_e32 v107, 0xbfb8aa3b, v107
	v_exp_f32_e32 v108, v108
	v_mul_f32_e32 v118, 0xbfb8aa3b, v118
	v_mul_f32_e32 v106, 0xbfb8aa3b, v106
	v_exp_f32_e32 v107, v107
	v_exp_f32_e32 v118, v118
	v_exp_f32_e32 v106, v106
	v_add_f32_e32 v108, 1.0, v108
	v_add_f32_e32 v107, 1.0, v107
	v_rcp_f32_e32 v108, v108
	v_add_f32_e32 v118, 1.0, v118
	v_rcp_f32_e32 v104, v104
	v_add_f32_e32 v106, 1.0, v106
	v_rcp_f32_e32 v107, v107
	v_rcp_f32_e32 v118, v118
	v_rcp_f32_e32 v105, v105
	v_rcp_f32_e32 v106, v106
	v_mul_f32_e32 v100, v100, v108
	v_mul_f32_e32 v104, v96, v104
	v_mul_f32_e32 v99, v99, v107
	v_cvt_pk_bf16_f32 v96, v100, v101
	v_mul_f32_e32 v102, v102, v118
	v_mul_f32_e32 v105, v97, v105
	v_mul_f32_e32 v106, v98, v106
	v_cvt_pk_bf16_f32 v97, v102, v103
	v_cvt_pk_bf16_f32 v98, v104, v105
	v_cvt_pk_bf16_f32 v99, v106, v99
	global_store_dwordx4 v117, v[96:99], s[12:13]
	s_nop 1
	v_add_u32_e32 v96, 0x6300, v157
	s_waitcnt vmcnt(15)
	s_nop 1
	v_mov_b32_e32 v96, v196
	v_mov_b32_e32 v97, v197
	v_mov_b32_e32 v98, v198
	v_mov_b32_e32 v99, v199
	v_lshlrev_b32_e32 v100, 16, v96
	v_and_b32_e32 v96, 0xffff0000, v96
	v_fmac_f32_e32 v93, v45, v96
	v_mul_f32_e32 v96, 0x3d372713, v93
	v_mul_f32_e32 v96, v93, v96
	v_fma_f32 v96, v93, v96, v93
	v_mul_f32_e32 v96, 0x3f4c422a, v96
	v_lshlrev_b32_e32 v101, 16, v97
	v_and_b32_e32 v97, 0xffff0000, v97
	v_add_f32_e32 v96, v96, v96
	v_fmac_f32_e32 v95, v47, v97
	v_mul_f32_e32 v96, 0xbfb8aa3b, v96
	v_mul_f32_e32 v97, 0x3d372713, v95
	v_exp_f32_e32 v96, v96
	v_mul_f32_e32 v97, v95, v97
	v_fma_f32 v97, v95, v97, v95
	v_mul_f32_e32 v97, 0x3f4c422a, v97
	v_add_f32_e32 v97, v97, v97
	v_add_f32_e32 v96, 1.0, v96
	v_mul_f32_e32 v97, 0xbfb8aa3b, v97
	v_rcp_f32_e32 v96, v96
	v_exp_f32_e32 v97, v97
	v_fmac_f32_e32 v92, v44, v100
	v_mul_f32_e32 v100, 0x3d372713, v92
	v_mul_f32_e32 v93, v93, v96
	v_add_f32_e32 v96, 1.0, v97
	v_lshlrev_b32_e32 v97, 16, v98
	v_and_b32_e32 v98, 0xffff0000, v98
	v_fmac_f32_e32 v88, v40, v97
	v_fmac_f32_e32 v89, v41, v98
	v_mul_f32_e32 v97, 0x3d372713, v88
	v_mul_f32_e32 v98, 0x3d372713, v89
	v_mul_f32_e32 v97, v88, v97
	v_mul_f32_e32 v98, v89, v98
	v_fma_f32 v97, v88, v97, v88
	v_fma_f32 v98, v89, v98, v89
	v_mul_f32_e32 v97, 0x3f4c422a, v97
	v_mul_f32_e32 v98, 0x3f4c422a, v98
	v_add_f32_e32 v97, v97, v97
	v_add_f32_e32 v98, v98, v98
	v_mul_f32_e32 v97, 0xbfb8aa3b, v97
	v_mul_f32_e32 v98, 0xbfb8aa3b, v98
	v_rcp_f32_e32 v96, v96
	v_exp_f32_e32 v97, v97
	v_exp_f32_e32 v98, v98
	v_mul_f32_e32 v100, v92, v100
	v_mul_f32_e32 v95, v95, v96
	v_add_f32_e32 v96, 1.0, v97
	v_add_f32_e32 v97, 1.0, v98
	v_lshlrev_b32_e32 v98, 16, v99
	v_and_b32_e32 v99, 0xffff0000, v99
	v_fmac_f32_e32 v91, v43, v99
	v_fmac_f32_e32 v94, v46, v101
	v_fmac_f32_e32 v90, v42, v98
	v_mul_f32_e32 v99, 0x3d372713, v91
	v_fma_f32 v100, v92, v100, v92
	v_mul_f32_e32 v101, 0x3d372713, v94
	v_mul_f32_e32 v98, 0x3d372713, v90
	v_mul_f32_e32 v99, v91, v99
	v_mul_f32_e32 v100, 0x3f4c422a, v100
	v_mul_f32_e32 v101, v94, v101
	v_mul_f32_e32 v98, v90, v98
	v_fma_f32 v99, v91, v99, v91
	v_add_f32_e32 v100, v100, v100
	v_fma_f32 v101, v94, v101, v94
	v_fma_f32 v98, v90, v98, v90
	v_mul_f32_e32 v99, 0x3f4c422a, v99
	v_mul_f32_e32 v100, 0xbfb8aa3b, v100
	v_mul_f32_e32 v101, 0x3f4c422a, v101
	v_mul_f32_e32 v98, 0x3f4c422a, v98
	v_add_f32_e32 v99, v99, v99
	v_exp_f32_e32 v100, v100
	v_add_f32_e32 v101, v101, v101
	v_add_f32_e32 v98, v98, v98
	v_mul_f32_e32 v99, 0xbfb8aa3b, v99
	v_mul_f32_e32 v101, 0xbfb8aa3b, v101
	v_mul_f32_e32 v98, 0xbfb8aa3b, v98
	v_exp_f32_e32 v99, v99
	v_exp_f32_e32 v101, v101
	v_exp_f32_e32 v98, v98
	v_add_f32_e32 v100, 1.0, v100
	v_rcp_f32_e32 v100, v100
	v_add_f32_e32 v99, 1.0, v99
	v_add_f32_e32 v101, 1.0, v101
	v_rcp_f32_e32 v96, v96
	v_add_f32_e32 v98, 1.0, v98
	v_rcp_f32_e32 v99, v99
	v_rcp_f32_e32 v101, v101
	v_rcp_f32_e32 v97, v97
	v_rcp_f32_e32 v98, v98
	v_mul_f32_e32 v92, v92, v100
	v_mul_f32_e32 v96, v88, v96
	v_mul_f32_e32 v91, v91, v99
	v_cvt_pk_bf16_f32 v88, v92, v93
	v_add_u32_e32 v92, 0x210000, v156
	v_mul_f32_e32 v94, v94, v101
	v_mul_f32_e32 v97, v89, v97
	v_mul_f32_e32 v98, v90, v98
	v_cvt_pk_bf16_f32 v89, v94, v95
	v_cvt_pk_bf16_f32 v90, v96, v97
	v_cvt_pk_bf16_f32 v91, v98, v91
	global_store_dwordx4 v92, v[88:91], s[12:13]
	v_cndmask_b32_e64 v95, v84, v76, s[8:9]
	s_nop 0
	v_add_u32_e32 v88, 0x9000, v157
	s_waitcnt vmcnt(15)
; #define EPI_OPAQUE(x) asm volatile("" : "+v"(x))
; __device__ __forceinline__ float fast_exp(float x) { return __builtin_amdgcn_exp2f(x * 1.4426950408889634f); }
; __device__ __forceinline__ float fast_sigmoid(float x) { return __builtin_amdgcn_rcpf(1.0f + fast_exp(-x)); }
; __device__ __forceinline__ float gelu_tanh(float x) {
;     const float a = 0.7978845608028654f * (x + 0.044715f * x * x * x);
;     return x * fast_sigmoid(2.0f * a);
; }
;     __device__ __forceinline__ void operator()(const f32x4 (&acc)[2][2][4][2], const Unit& u, int wr, int wc, int fr, int fq, const EpiCtx& X) const {
;         const bool odd = fr & 1; const int fe = fr - (fr & 1), o32 = (fr & 1) * 32;
;         const int g = u.pn; const int p0 = 8 * (fq & 1);
;         const f32x4 d0 = *(const f32x4*)(dvec + g * 16 + p0), d1 = *(const f32x4*)(dvec + g * 16 + p0 + 4);
;         const char* ub = (const char*)(UA + (size_t)u.pm * BM * UA_LD);
;         unsigned ulo = (unsigned)((wr * 64 + fe) * UA_LD + wc * 64 + o32 + 8 * fq) * 2u; EPI_OPAQUE(ulo);
;         char* gb = (char*)(GACT + (size_t)(u.pm & 3) * 256 * 16 * W_SSM + g * 16);
;         unsigned glo = (unsigned)(((wr * 64 + fe) * 16 + wc * 4 + (fr & 1) * 2 + (fq >> 1)) * W_SSM + p0) * 2u; EPI_OPAQUE(glo);
;     ...
;         EPI_PIECES({ const unsigned uoff = ulo + (unsigned)(rl * UA_LD) * 2u, goff = glo + (unsigned)(rl * 16 * W_SSM) * 2u;
;             S2_ONE(p1a, p1b, uoff, goff); S2_ONE(p2a, p2b, uoff + UA_LD * 2, goff + 16 * W_SSM * 2); })
	s_nop 1
	v_mov_b32_e32 v88, v200
	v_mov_b32_e32 v89, v201
	v_mov_b32_e32 v90, v202
	v_mov_b32_e32 v91, v203
	v_cndmask_b32_e64 v94, v85, v77, s[8:9]
	v_mov_b32_dpp v96, v95 quad_perm:[1,0,3,2] row_mask:0xf bank_mask:0xf
	s_nop 0
	v_cndmask_b32_e64 v99, v80, v72, s[8:9]
	s_nop 0
	v_cndmask_b32_e64 v93, v86, v78, s[8:9]
	v_mov_b32_dpp v95, v94 quad_perm:[1,0,3,2] row_mask:0xf bank_mask:0xf
	s_nop 0
	v_cndmask_b32_e64 v98, v81, v73, s[8:9]
	v_mov_b32_dpp v100, v99 quad_perm:[1,0,3,2] row_mask:0xf bank_mask:0xf
	s_nop 0
	v_cndmask_b32_e64 v92, v87, v79, s[8:9]
	v_mov_b32_dpp v94, v93 quad_perm:[1,0,3,2] row_mask:0xf bank_mask:0xf
	s_nop 0
	v_cndmask_b32_e64 v97, v82, v74, s[8:9]
	v_mov_b32_dpp v99, v98 quad_perm:[1,0,3,2] row_mask:0xf bank_mask:0xf
	s_nop 0
	v_mov_b32_dpp v93, v92 quad_perm:[1,0,3,2] row_mask:0xf bank_mask:0xf
	v_cndmask_b32_e64 v92, v83, v75, s[8:9]
	v_mov_b32_dpp v98, v97 quad_perm:[1,0,3,2] row_mask:0xf bank_mask:0xf
	s_nop 0
	v_cndmask_b32_e64 v85, v95, v85, s[8:9]
	v_cndmask_b32_e64 v87, v93, v87, s[8:9]
	v_mov_b32_dpp v97, v92 quad_perm:[1,0,3,2] row_mask:0xf bank_mask:0xf
	v_cndmask_b32_e64 v81, v99, v81, s[8:9]
	v_cndmask_b32_e64 v80, v100, v80, s[8:9]
	v_cndmask_b32_e64 v84, v96, v84, s[8:9]
	v_cndmask_b32_e64 v83, v97, v83, s[8:9]
	v_cndmask_b32_e64 v86, v94, v86, s[8:9]
	v_cndmask_b32_e64 v82, v98, v82, s[8:9]
	v_add_u32_e32 v101, 0x300000, v156
	v_cndmask_b32_e64 v77, v77, v95, s[8:9]
	v_cndmask_b32_e64 v79, v79, v93, s[8:9]
	v_cndmask_b32_e64 v73, v73, v99, s[8:9]
	v_cndmask_b32_e64 v72, v72, v100, s[8:9]
	v_cndmask_b32_e64 v76, v76, v96, s[8:9]
	v_cndmask_b32_e64 v75, v75, v97, s[8:9]
	v_cndmask_b32_e64 v78, v78, v94, s[8:9]
	v_cndmask_b32_e64 v74, v74, v98, s[8:9]
	v_lshlrev_b32_e32 v92, 16, v88
	v_and_b32_e32 v88, 0xffff0000, v88
	v_fmac_f32_e32 v85, v45, v88
	v_mul_f32_e32 v88, 0x3d372713, v85
	v_mul_f32_e32 v88, v85, v88
	v_fma_f32 v88, v85, v88, v85
	v_mul_f32_e32 v88, 0x3f4c422a, v88
	v_lshlrev_b32_e32 v102, 16, v89
	v_and_b32_e32 v89, 0xffff0000, v89
	v_add_f32_e32 v88, v88, v88
	v_fmac_f32_e32 v87, v47, v89
	v_mul_f32_e32 v88, 0xbfb8aa3b, v88
	v_mul_f32_e32 v89, 0x3d372713, v87
	v_exp_f32_e32 v88, v88
	v_mul_f32_e32 v89, v87, v89
	v_fma_f32 v89, v87, v89, v87
	v_mul_f32_e32 v89, 0x3f4c422a, v89
	v_add_f32_e32 v89, v89, v89
	v_add_f32_e32 v88, 1.0, v88
	v_mul_f32_e32 v89, 0xbfb8aa3b, v89
	v_rcp_f32_e32 v88, v88
	v_exp_f32_e32 v89, v89
	v_fmac_f32_e32 v84, v44, v92
	v_mul_f32_e32 v92, 0x3d372713, v84
	v_mul_f32_e32 v85, v85, v88
	v_add_f32_e32 v88, 1.0, v89
	v_lshlrev_b32_e32 v89, 16, v90
	v_and_b32_e32 v90, 0xffff0000, v90
	v_fmac_f32_e32 v80, v40, v89
	v_fmac_f32_e32 v81, v41, v90
	v_mul_f32_e32 v89, 0x3d372713, v80
	v_mul_f32_e32 v90, 0x3d372713, v81
	v_mul_f32_e32 v89, v80, v89
	v_mul_f32_e32 v90, v81, v90
	v_fma_f32 v89, v80, v89, v80
	v_fma_f32 v90, v81, v90, v81
	v_mul_f32_e32 v89, 0x3f4c422a, v89
	v_mul_f32_e32 v90, 0x3f4c422a, v90
	v_add_f32_e32 v89, v89, v89
	v_add_f32_e32 v90, v90, v90
	v_mul_f32_e32 v89, 0xbfb8aa3b, v89
	v_mul_f32_e32 v90, 0xbfb8aa3b, v90
	v_rcp_f32_e32 v88, v88
	v_exp_f32_e32 v89, v89
	v_exp_f32_e32 v90, v90
	v_fmac_f32_e32 v86, v46, v102
	v_mul_f32_e32 v87, v87, v88
	v_add_f32_e32 v88, 1.0, v89
	v_add_f32_e32 v89, 1.0, v90
	v_lshlrev_b32_e32 v90, 16, v91
	v_and_b32_e32 v91, 0xffff0000, v91
	v_fmac_f32_e32 v83, v43, v91
	v_fmac_f32_e32 v82, v42, v90
	v_mul_f32_e32 v91, 0x3d372713, v83
	v_mul_f32_e32 v92, v84, v92
	v_mul_f32_e32 v102, 0x3d372713, v86
	v_mul_f32_e32 v90, 0x3d372713, v82
	v_mul_f32_e32 v91, v83, v91
	v_fma_f32 v92, v84, v92, v84
	v_mul_f32_e32 v102, v86, v102
	v_mul_f32_e32 v90, v82, v90
	v_fma_f32 v91, v83, v91, v83
	v_mul_f32_e32 v92, 0x3f4c422a, v92
	v_fma_f32 v102, v86, v102, v86
	v_fma_f32 v90, v82, v90, v82
	v_mul_f32_e32 v91, 0x3f4c422a, v91
	v_add_f32_e32 v92, v92, v92
	v_mul_f32_e32 v102, 0x3f4c422a, v102
	v_mul_f32_e32 v90, 0x3f4c422a, v90
	v_add_f32_e32 v91, v91, v91
	v_mul_f32_e32 v92, 0xbfb8aa3b, v92
	v_add_f32_e32 v102, v102, v102
	v_add_f32_e32 v90, v90, v90
	v_mul_f32_e32 v91, 0xbfb8aa3b, v91
	v_exp_f32_e32 v92, v92
	v_mul_f32_e32 v102, 0xbfb8aa3b, v102
	v_mul_f32_e32 v90, 0xbfb8aa3b, v90
	v_exp_f32_e32 v91, v91
	v_exp_f32_e32 v102, v102
	v_exp_f32_e32 v90, v90
	v_add_f32_e32 v92, 1.0, v92
	v_add_f32_e32 v91, 1.0, v91
	v_rcp_f32_e32 v92, v92
	v_add_f32_e32 v102, 1.0, v102
	v_rcp_f32_e32 v88, v88
	v_add_f32_e32 v90, 1.0, v90
	v_rcp_f32_e32 v91, v91
	v_rcp_f32_e32 v102, v102
	v_rcp_f32_e32 v89, v89
	v_rcp_f32_e32 v90, v90
	v_mul_f32_e32 v84, v84, v92
	v_mul_f32_e32 v88, v80, v88
	v_mul_f32_e32 v83, v83, v91
	v_cvt_pk_bf16_f32 v80, v84, v85
	v_mul_f32_e32 v86, v86, v102
	v_mul_f32_e32 v89, v81, v89
	v_mul_f32_e32 v90, v82, v90
	v_cvt_pk_bf16_f32 v81, v86, v87
	v_cvt_pk_bf16_f32 v82, v88, v89
	v_cvt_pk_bf16_f32 v83, v90, v83
	global_store_dwordx4 v101, v[80:83], s[12:13]
	s_nop 1
	v_add_u32_e32 v80, 0x9300, v157
	s_waitcnt vmcnt(15)
; #define EPI_OPAQUE(x) asm volatile("" : "+v"(x))
; __device__ __forceinline__ float fast_exp(float x) { return __builtin_amdgcn_exp2f(x * 1.4426950408889634f); }
; __device__ __forceinline__ float fast_sigmoid(float x) { return __builtin_amdgcn_rcpf(1.0f + fast_exp(-x)); }
; __device__ __forceinline__ float gelu_tanh(float x) {
;     const float a = 0.7978845608028654f * (x + 0.044715f * x * x * x);
;     return x * fast_sigmoid(2.0f * a);
; }
;     __device__ __forceinline__ void operator()(const f32x4 (&acc)[2][2][4][2], const Unit& u, int wr, int wc, int fr, int fq, const EpiCtx& X) const {
;         const bool odd = fr & 1; const int fe = fr - (fr & 1), o32 = (fr & 1) * 32;
;         const int g = u.pn; const int p0 = 8 * (fq & 1);
;         const f32x4 d0 = *(const f32x4*)(dvec + g * 16 + p0), d1 = *(const f32x4*)(dvec + g * 16 + p0 + 4);
;         const char* ub = (const char*)(UA + (size_t)u.pm * BM * UA_LD);
;         unsigned ulo = (unsigned)((wr * 64 + fe) * UA_LD + wc * 64 + o32 + 8 * fq) * 2u; EPI_OPAQUE(ulo);
;         char* gb = (char*)(GACT + (size_t)(u.pm & 3) * 256 * 16 * W_SSM + g * 16);
;         unsigned glo = (unsigned)(((wr * 64 + fe) * 16 + wc * 4 + (fr & 1) * 2 + (fq >> 1)) * W_SSM + p0) * 2u; EPI_OPAQUE(glo);
;     ...
;         EPI_PIECES({ const unsigned uoff = ulo + (unsigned)(rl * UA_LD) * 2u, goff = glo + (unsigned)(rl * 16 * W_SSM) * 2u;
;             S2_ONE(p1a, p1b, uoff, goff); S2_ONE(p2a, p2b, uoff + UA_LD * 2, goff + 16 * W_SSM * 2); })
	s_nop 1
	v_mov_b32_e32 v80, v204
	v_mov_b32_e32 v81, v205
	v_mov_b32_e32 v82, v206
	v_mov_b32_e32 v83, v207
	v_lshlrev_b32_e32 v84, 16, v80
	v_and_b32_e32 v80, 0xffff0000, v80
	v_fmac_f32_e32 v77, v45, v80
	v_mul_f32_e32 v80, 0x3d372713, v77
	v_mul_f32_e32 v80, v77, v80
	v_fma_f32 v80, v77, v80, v77
	v_mul_f32_e32 v80, 0x3f4c422a, v80
	v_lshlrev_b32_e32 v85, 16, v81
	v_and_b32_e32 v81, 0xffff0000, v81
	v_add_f32_e32 v80, v80, v80
	v_fmac_f32_e32 v79, v47, v81
	v_mul_f32_e32 v80, 0xbfb8aa3b, v80
	v_mul_f32_e32 v81, 0x3d372713, v79
	v_exp_f32_e32 v80, v80
	v_mul_f32_e32 v81, v79, v81
	v_fma_f32 v81, v79, v81, v79
	v_mul_f32_e32 v81, 0x3f4c422a, v81
	v_add_f32_e32 v81, v81, v81
	v_add_f32_e32 v80, 1.0, v80
	v_mul_f32_e32 v81, 0xbfb8aa3b, v81
	v_rcp_f32_e32 v80, v80
	v_exp_f32_e32 v81, v81
	v_fmac_f32_e32 v76, v44, v84
	v_mul_f32_e32 v84, 0x3d372713, v76
	v_mul_f32_e32 v77, v77, v80
	v_add_f32_e32 v80, 1.0, v81
	v_lshlrev_b32_e32 v81, 16, v82
	v_and_b32_e32 v82, 0xffff0000, v82
	v_fmac_f32_e32 v72, v40, v81
	v_fmac_f32_e32 v73, v41, v82
	v_mul_f32_e32 v81, 0x3d372713, v72
	v_mul_f32_e32 v82, 0x3d372713, v73
	v_mul_f32_e32 v81, v72, v81
	v_mul_f32_e32 v82, v73, v82
	v_fma_f32 v81, v72, v81, v72
	v_fma_f32 v82, v73, v82, v73
	v_mul_f32_e32 v81, 0x3f4c422a, v81
	v_mul_f32_e32 v82, 0x3f4c422a, v82
	v_add_f32_e32 v81, v81, v81
	v_add_f32_e32 v82, v82, v82
	v_mul_f32_e32 v81, 0xbfb8aa3b, v81
	v_mul_f32_e32 v82, 0xbfb8aa3b, v82
	v_rcp_f32_e32 v80, v80
	v_exp_f32_e32 v81, v81
	v_exp_f32_e32 v82, v82
	v_mul_f32_e32 v84, v76, v84
	v_mul_f32_e32 v79, v79, v80
	v_add_f32_e32 v80, 1.0, v81
	v_add_f32_e32 v81, 1.0, v82
	v_lshlrev_b32_e32 v82, 16, v83
	v_and_b32_e32 v83, 0xffff0000, v83
	v_fmac_f32_e32 v75, v43, v83
	v_fmac_f32_e32 v78, v46, v85
	v_fmac_f32_e32 v74, v42, v82
	v_mul_f32_e32 v83, 0x3d372713, v75
	v_fma_f32 v84, v76, v84, v76
	v_mul_f32_e32 v85, 0x3d372713, v78
	v_mul_f32_e32 v82, 0x3d372713, v74
	v_mul_f32_e32 v83, v75, v83
	v_mul_f32_e32 v84, 0x3f4c422a, v84
	v_mul_f32_e32 v85, v78, v85
	v_mul_f32_e32 v82, v74, v82
	v_fma_f32 v83, v75, v83, v75
	v_add_f32_e32 v84, v84, v84
	v_fma_f32 v85, v78, v85, v78
	v_fma_f32 v82, v74, v82, v74
	v_mul_f32_e32 v83, 0x3f4c422a, v83
	v_mul_f32_e32 v84, 0xbfb8aa3b, v84
	v_mul_f32_e32 v85, 0x3f4c422a, v85
	v_mul_f32_e32 v82, 0x3f4c422a, v82
	v_add_f32_e32 v83, v83, v83
	v_exp_f32_e32 v84, v84
	v_add_f32_e32 v85, v85, v85
	v_add_f32_e32 v82, v82, v82
	v_mul_f32_e32 v83, 0xbfb8aa3b, v83
	v_mul_f32_e32 v85, 0xbfb8aa3b, v85
	v_mul_f32_e32 v82, 0xbfb8aa3b, v82
	v_exp_f32_e32 v83, v83
	v_exp_f32_e32 v85, v85
	v_exp_f32_e32 v82, v82
	v_add_f32_e32 v84, 1.0, v84
	v_rcp_f32_e32 v84, v84
	v_add_f32_e32 v83, 1.0, v83
	v_add_f32_e32 v85, 1.0, v85
	v_rcp_f32_e32 v80, v80
	v_add_f32_e32 v82, 1.0, v82
	v_rcp_f32_e32 v83, v83
	v_rcp_f32_e32 v85, v85
	v_rcp_f32_e32 v81, v81
	v_rcp_f32_e32 v82, v82
	v_mul_f32_e32 v76, v76, v84
	v_mul_f32_e32 v80, v72, v80
	v_mul_f32_e32 v75, v75, v83
	v_cvt_pk_bf16_f32 v72, v76, v77
	v_add_u32_e32 v76, 0x310000, v156
	v_mul_f32_e32 v78, v78, v85
	v_mul_f32_e32 v81, v73, v81
	v_mul_f32_e32 v82, v74, v82
	v_cvt_pk_bf16_f32 v73, v78, v79
	v_cvt_pk_bf16_f32 v74, v80, v81
	v_cvt_pk_bf16_f32 v75, v82, v75
	global_store_dwordx4 v76, v[72:75], s[12:13]
	v_cndmask_b32_e64 v79, v68, v60, s[8:9]
	s_nop 0
	v_add_u32_e32 v72, 0x18000, v157
	s_waitcnt vmcnt(15)
	s_nop 1
	v_mov_b32_e32 v72, v208
	v_mov_b32_e32 v73, v209
	v_mov_b32_e32 v74, v210
	v_mov_b32_e32 v75, v211
	v_cndmask_b32_e64 v78, v69, v61, s[8:9]
	v_mov_b32_dpp v80, v79 quad_perm:[1,0,3,2] row_mask:0xf bank_mask:0xf
	s_nop 0
	v_cndmask_b32_e64 v83, v64, v56, s[8:9]
	s_nop 0
	v_cndmask_b32_e64 v77, v70, v62, s[8:9]
	v_mov_b32_dpp v79, v78 quad_perm:[1,0,3,2] row_mask:0xf bank_mask:0xf
	s_nop 0
	v_cndmask_b32_e64 v82, v65, v57, s[8:9]
	v_mov_b32_dpp v84, v83 quad_perm:[1,0,3,2] row_mask:0xf bank_mask:0xf
	s_nop 0
	v_cndmask_b32_e64 v76, v71, v63, s[8:9]
	v_mov_b32_dpp v78, v77 quad_perm:[1,0,3,2] row_mask:0xf bank_mask:0xf
	s_nop 0
	v_cndmask_b32_e64 v81, v66, v58, s[8:9]
	v_mov_b32_dpp v83, v82 quad_perm:[1,0,3,2] row_mask:0xf bank_mask:0xf
	s_nop 0
	v_mov_b32_dpp v77, v76 quad_perm:[1,0,3,2] row_mask:0xf bank_mask:0xf
	v_cndmask_b32_e64 v76, v67, v59, s[8:9]
	v_mov_b32_dpp v82, v81 quad_perm:[1,0,3,2] row_mask:0xf bank_mask:0xf
	s_nop 0
	v_cndmask_b32_e64 v69, v79, v69, s[8:9]
	v_cndmask_b32_e64 v71, v77, v71, s[8:9]
	v_mov_b32_dpp v81, v76 quad_perm:[1,0,3,2] row_mask:0xf bank_mask:0xf
	v_cndmask_b32_e64 v65, v83, v65, s[8:9]
	v_cndmask_b32_e64 v64, v84, v64, s[8:9]
	v_cndmask_b32_e64 v68, v80, v68, s[8:9]
	v_cndmask_b32_e64 v67, v81, v67, s[8:9]
	v_cndmask_b32_e64 v70, v78, v70, s[8:9]
	v_cndmask_b32_e64 v66, v82, v66, s[8:9]
	v_add_u32_e32 v85, 0x800000, v156
	v_cndmask_b32_e64 v61, v61, v79, s[8:9]
	v_cndmask_b32_e64 v63, v63, v77, s[8:9]
	v_cndmask_b32_e64 v57, v57, v83, s[8:9]
	v_cndmask_b32_e64 v56, v56, v84, s[8:9]
	v_cndmask_b32_e64 v60, v60, v80, s[8:9]
	v_cndmask_b32_e64 v59, v59, v81, s[8:9]
	v_cndmask_b32_e64 v62, v62, v78, s[8:9]
	v_cndmask_b32_e64 v58, v58, v82, s[8:9]
	v_lshlrev_b32_e32 v76, 16, v72
	v_and_b32_e32 v72, 0xffff0000, v72
	v_fmac_f32_e32 v69, v45, v72
	v_mul_f32_e32 v72, 0x3d372713, v69
	v_mul_f32_e32 v72, v69, v72
	v_fma_f32 v72, v69, v72, v69
	v_mul_f32_e32 v72, 0x3f4c422a, v72
	v_lshlrev_b32_e32 v86, 16, v73
	v_and_b32_e32 v73, 0xffff0000, v73
	v_add_f32_e32 v72, v72, v72
	v_fmac_f32_e32 v71, v47, v73
	v_mul_f32_e32 v72, 0xbfb8aa3b, v72
	v_mul_f32_e32 v73, 0x3d372713, v71
	v_exp_f32_e32 v72, v72
	v_mul_f32_e32 v73, v71, v73
	v_fma_f32 v73, v71, v73, v71
	v_mul_f32_e32 v73, 0x3f4c422a, v73
	v_add_f32_e32 v73, v73, v73
; #define EPI_OPAQUE(x) asm volatile("" : "+v"(x))
; __device__ __forceinline__ float fast_exp(float x) { return __builtin_amdgcn_exp2f(x * 1.4426950408889634f); }
; __device__ __forceinline__ float fast_sigmoid(float x) { return __builtin_amdgcn_rcpf(1.0f + fast_exp(-x)); }
; __device__ __forceinline__ float gelu_tanh(float x) {
;     const float a = 0.7978845608028654f * (x + 0.044715f * x * x * x);
;     return x * fast_sigmoid(2.0f * a);
; }
;     __device__ __forceinline__ void operator()(const f32x4 (&acc)[2][2][4][2], const Unit& u, int wr, int wc, int fr, int fq, const EpiCtx& X) const {
;         const bool odd = fr & 1; const int fe = fr - (fr & 1), o32 = (fr & 1) * 32;
;         const int g = u.pn; const int p0 = 8 * (fq & 1);
;         const f32x4 d0 = *(const f32x4*)(dvec + g * 16 + p0), d1 = *(const f32x4*)(dvec + g * 16 + p0 + 4);
;         const char* ub = (const char*)(UA + (size_t)u.pm * BM * UA_LD);
;         unsigned ulo = (unsigned)((wr * 64 + fe) * UA_LD + wc * 64 + o32 + 8 * fq) * 2u; EPI_OPAQUE(ulo);
;         char* gb = (char*)(GACT + (size_t)(u.pm & 3) * 256 * 16 * W_SSM + g * 16);
;         unsigned glo = (unsigned)(((wr * 64 + fe) * 16 + wc * 4 + (fr & 1) * 2 + (fq >> 1)) * W_SSM + p0) * 2u; EPI_OPAQUE(glo);
;     ...
;         EPI_PIECES({ const unsigned uoff = ulo + (unsigned)(rl * UA_LD) * 2u, goff = glo + (unsigned)(rl * 16 * W_SSM) * 2u;
;             S2_ONE(p1a, p1b, uoff, goff); S2_ONE(p2a, p2b, uoff + UA_LD * 2, goff + 16 * W_SSM * 2); })
	v_add_f32_e32 v72, 1.0, v72
	v_mul_f32_e32 v73, 0xbfb8aa3b, v73
	v_rcp_f32_e32 v72, v72
	v_exp_f32_e32 v73, v73
	v_fmac_f32_e32 v68, v44, v76
	v_mul_f32_e32 v76, 0x3d372713, v68
	v_mul_f32_e32 v69, v69, v72
	v_add_f32_e32 v72, 1.0, v73
	v_lshlrev_b32_e32 v73, 16, v74
	v_and_b32_e32 v74, 0xffff0000, v74
	v_fmac_f32_e32 v64, v40, v73
	v_fmac_f32_e32 v65, v41, v74
	v_mul_f32_e32 v73, 0x3d372713, v64
	v_mul_f32_e32 v74, 0x3d372713, v65
	v_mul_f32_e32 v73, v64, v73
	v_mul_f32_e32 v74, v65, v74
	v_fma_f32 v73, v64, v73, v64
	v_fma_f32 v74, v65, v74, v65
	v_mul_f32_e32 v73, 0x3f4c422a, v73
	v_mul_f32_e32 v74, 0x3f4c422a, v74
	v_add_f32_e32 v73, v73, v73
	v_add_f32_e32 v74, v74, v74
	v_mul_f32_e32 v73, 0xbfb8aa3b, v73
	v_mul_f32_e32 v74, 0xbfb8aa3b, v74
	v_rcp_f32_e32 v72, v72
	v_exp_f32_e32 v73, v73
	v_exp_f32_e32 v74, v74
	v_fmac_f32_e32 v70, v46, v86
	v_mul_f32_e32 v71, v71, v72
	v_add_f32_e32 v72, 1.0, v73
	v_add_f32_e32 v73, 1.0, v74
	v_lshlrev_b32_e32 v74, 16, v75
	v_and_b32_e32 v75, 0xffff0000, v75
	v_fmac_f32_e32 v67, v43, v75
	v_fmac_f32_e32 v66, v42, v74
	v_mul_f32_e32 v75, 0x3d372713, v67
	v_mul_f32_e32 v76, v68, v76
	v_mul_f32_e32 v86, 0x3d372713, v70
	v_mul_f32_e32 v74, 0x3d372713, v66
	v_mul_f32_e32 v75, v67, v75
	v_fma_f32 v76, v68, v76, v68
	v_mul_f32_e32 v86, v70, v86
	v_mul_f32_e32 v74, v66, v74
	v_fma_f32 v75, v67, v75, v67
	v_mul_f32_e32 v76, 0x3f4c422a, v76
	v_fma_f32 v86, v70, v86, v70
	v_fma_f32 v74, v66, v74, v66
	v_mul_f32_e32 v75, 0x3f4c422a, v75
	v_add_f32_e32 v76, v76, v76
	v_mul_f32_e32 v86, 0x3f4c422a, v86
	v_mul_f32_e32 v74, 0x3f4c422a, v74
	v_add_f32_e32 v75, v75, v75
	v_mul_f32_e32 v76, 0xbfb8aa3b, v76
	v_add_f32_e32 v86, v86, v86
	v_add_f32_e32 v74, v74, v74
	v_mul_f32_e32 v75, 0xbfb8aa3b, v75
	v_exp_f32_e32 v76, v76
	v_mul_f32_e32 v86, 0xbfb8aa3b, v86
	v_mul_f32_e32 v74, 0xbfb8aa3b, v74
	v_exp_f32_e32 v75, v75
	v_exp_f32_e32 v86, v86
	v_exp_f32_e32 v74, v74
	v_add_f32_e32 v76, 1.0, v76
	v_add_f32_e32 v75, 1.0, v75
	v_rcp_f32_e32 v76, v76
	v_add_f32_e32 v86, 1.0, v86
	v_rcp_f32_e32 v72, v72
	v_add_f32_e32 v74, 1.0, v74
	v_rcp_f32_e32 v75, v75
	v_rcp_f32_e32 v86, v86
	v_rcp_f32_e32 v73, v73
	v_rcp_f32_e32 v74, v74
	v_mul_f32_e32 v68, v68, v76
	v_mul_f32_e32 v72, v64, v72
	v_mul_f32_e32 v67, v67, v75
	v_cvt_pk_bf16_f32 v64, v68, v69
	v_mul_f32_e32 v70, v70, v86
	v_mul_f32_e32 v73, v65, v73
	v_mul_f32_e32 v74, v66, v74
	v_cvt_pk_bf16_f32 v65, v70, v71
	v_cvt_pk_bf16_f32 v66, v72, v73
	v_cvt_pk_bf16_f32 v67, v74, v67
	global_store_dwordx4 v85, v[64:67], s[12:13]
	s_nop 1
	v_add_u32_e32 v64, 0x18300, v157
	s_waitcnt vmcnt(15)
	s_nop 1
	v_mov_b32_e32 v64, v220
	v_mov_b32_e32 v65, v221
	v_mov_b32_e32 v66, v222
	v_mov_b32_e32 v67, v223
	v_lshlrev_b32_e32 v68, 16, v64
	v_and_b32_e32 v64, 0xffff0000, v64
	v_fmac_f32_e32 v61, v45, v64
	v_mul_f32_e32 v64, 0x3d372713, v61
	v_mul_f32_e32 v64, v61, v64
	v_fma_f32 v64, v61, v64, v61
	v_mul_f32_e32 v64, 0x3f4c422a, v64
	v_lshlrev_b32_e32 v69, 16, v65
	v_and_b32_e32 v65, 0xffff0000, v65
	v_add_f32_e32 v64, v64, v64
	v_fmac_f32_e32 v63, v47, v65
	v_mul_f32_e32 v64, 0xbfb8aa3b, v64
	v_mul_f32_e32 v65, 0x3d372713, v63
	v_exp_f32_e32 v64, v64
	v_mul_f32_e32 v65, v63, v65
	v_fma_f32 v65, v63, v65, v63
	v_mul_f32_e32 v65, 0x3f4c422a, v65
	v_add_f32_e32 v65, v65, v65
	v_add_f32_e32 v64, 1.0, v64
	v_mul_f32_e32 v65, 0xbfb8aa3b, v65
	v_rcp_f32_e32 v64, v64
	v_exp_f32_e32 v65, v65
	v_fmac_f32_e32 v60, v44, v68
	v_mul_f32_e32 v68, 0x3d372713, v60
	v_mul_f32_e32 v61, v61, v64
	v_add_f32_e32 v64, 1.0, v65
	v_lshlrev_b32_e32 v65, 16, v66
	v_and_b32_e32 v66, 0xffff0000, v66
	v_fmac_f32_e32 v56, v40, v65
	v_fmac_f32_e32 v57, v41, v66
	v_mul_f32_e32 v65, 0x3d372713, v56
	v_mul_f32_e32 v66, 0x3d372713, v57
	v_mul_f32_e32 v65, v56, v65
	v_mul_f32_e32 v66, v57, v66
	v_fma_f32 v65, v56, v65, v56
	v_fma_f32 v66, v57, v66, v57
	v_mul_f32_e32 v65, 0x3f4c422a, v65
	v_mul_f32_e32 v66, 0x3f4c422a, v66
	v_add_f32_e32 v65, v65, v65
	v_add_f32_e32 v66, v66, v66
	v_mul_f32_e32 v65, 0xbfb8aa3b, v65
	v_mul_f32_e32 v66, 0xbfb8aa3b, v66
	v_rcp_f32_e32 v64, v64
	v_exp_f32_e32 v65, v65
	v_exp_f32_e32 v66, v66
	v_mul_f32_e32 v68, v60, v68
	v_mul_f32_e32 v63, v63, v64
	v_add_f32_e32 v64, 1.0, v65
	v_add_f32_e32 v65, 1.0, v66
	v_lshlrev_b32_e32 v66, 16, v67
	v_and_b32_e32 v67, 0xffff0000, v67
	v_fmac_f32_e32 v59, v43, v67
	v_fmac_f32_e32 v62, v46, v69
	v_fmac_f32_e32 v58, v42, v66
	v_mul_f32_e32 v67, 0x3d372713, v59
	v_fma_f32 v68, v60, v68, v60
	v_mul_f32_e32 v69, 0x3d372713, v62
	v_mul_f32_e32 v66, 0x3d372713, v58
	v_mul_f32_e32 v67, v59, v67
	v_mul_f32_e32 v68, 0x3f4c422a, v68
	v_mul_f32_e32 v69, v62, v69
	v_mul_f32_e32 v66, v58, v66
	v_fma_f32 v67, v59, v67, v59
	v_add_f32_e32 v68, v68, v68
	v_fma_f32 v69, v62, v69, v62
	v_fma_f32 v66, v58, v66, v58
	v_mul_f32_e32 v67, 0x3f4c422a, v67
	v_mul_f32_e32 v68, 0xbfb8aa3b, v68
	v_mul_f32_e32 v69, 0x3f4c422a, v69
	v_mul_f32_e32 v66, 0x3f4c422a, v66
	v_add_f32_e32 v67, v67, v67
	v_exp_f32_e32 v68, v68
	v_add_f32_e32 v69, v69, v69
	v_add_f32_e32 v66, v66, v66
	v_mul_f32_e32 v67, 0xbfb8aa3b, v67
	v_mul_f32_e32 v69, 0xbfb8aa3b, v69
	v_mul_f32_e32 v66, 0xbfb8aa3b, v66
	v_exp_f32_e32 v67, v67
	v_exp_f32_e32 v69, v69
	v_exp_f32_e32 v66, v66
	v_add_f32_e32 v68, 1.0, v68
	v_rcp_f32_e32 v68, v68
	v_add_f32_e32 v67, 1.0, v67
	v_add_f32_e32 v69, 1.0, v69
	v_rcp_f32_e32 v64, v64
	v_add_f32_e32 v66, 1.0, v66
	v_rcp_f32_e32 v67, v67
	v_rcp_f32_e32 v69, v69
	v_rcp_f32_e32 v65, v65
	v_rcp_f32_e32 v66, v66
	v_mul_f32_e32 v60, v60, v68
	v_mul_f32_e32 v64, v56, v64
	v_mul_f32_e32 v59, v59, v67
	v_cvt_pk_bf16_f32 v56, v60, v61
	v_add_u32_e32 v60, 0x810000, v156
	v_mul_f32_e32 v62, v62, v69
	v_mul_f32_e32 v65, v57, v65
	v_mul_f32_e32 v66, v58, v66
	v_cvt_pk_bf16_f32 v57, v62, v63
	v_cvt_pk_bf16_f32 v58, v64, v65
	v_cvt_pk_bf16_f32 v59, v66, v59
	global_store_dwordx4 v60, v[56:59], s[12:13]
	v_cndmask_b32_e64 v63, v52, v36, s[8:9]
	s_nop 0
	v_add_u32_e32 v56, 0x1b000, v157
	s_waitcnt vmcnt(15)
; #define EPI_OPAQUE(x) asm volatile("" : "+v"(x))
; __device__ __forceinline__ float fast_exp(float x) { return __builtin_amdgcn_exp2f(x * 1.4426950408889634f); }
; __device__ __forceinline__ float fast_sigmoid(float x) { return __builtin_amdgcn_rcpf(1.0f + fast_exp(-x)); }
; __device__ __forceinline__ float gelu_tanh(float x) {
;     const float a = 0.7978845608028654f * (x + 0.044715f * x * x * x);
;     return x * fast_sigmoid(2.0f * a);
; }
;     __device__ __forceinline__ void operator()(const f32x4 (&acc)[2][2][4][2], const Unit& u, int wr, int wc, int fr, int fq, const EpiCtx& X) const {
;         const bool odd = fr & 1; const int fe = fr - (fr & 1), o32 = (fr & 1) * 32;
;         const int g = u.pn; const int p0 = 8 * (fq & 1);
;         const f32x4 d0 = *(const f32x4*)(dvec + g * 16 + p0), d1 = *(const f32x4*)(dvec + g * 16 + p0 + 4);
;         const char* ub = (const char*)(UA + (size_t)u.pm * BM * UA_LD);
;         unsigned ulo = (unsigned)((wr * 64 + fe) * UA_LD + wc * 64 + o32 + 8 * fq) * 2u; EPI_OPAQUE(ulo);
;         char* gb = (char*)(GACT + (size_t)(u.pm & 3) * 256 * 16 * W_SSM + g * 16);
;         unsigned glo = (unsigned)(((wr * 64 + fe) * 16 + wc * 4 + (fr & 1) * 2 + (fq >> 1)) * W_SSM + p0) * 2u; EPI_OPAQUE(glo);
;     ...
;         EPI_PIECES({ const unsigned uoff = ulo + (unsigned)(rl * UA_LD) * 2u, goff = glo + (unsigned)(rl * 16 * W_SSM) * 2u;
;             S2_ONE(p1a, p1b, uoff, goff); S2_ONE(p2a, p2b, uoff + UA_LD * 2, goff + 16 * W_SSM * 2); })
	s_nop 1
	v_mov_b32_e32 v56, v224
	v_mov_b32_e32 v57, v225
	v_mov_b32_e32 v58, v226
	v_mov_b32_e32 v59, v227
	v_cndmask_b32_e64 v62, v53, v37, s[8:9]
	v_mov_b32_dpp v64, v63 quad_perm:[1,0,3,2] row_mask:0xf bank_mask:0xf
	s_nop 0
	v_cndmask_b32_e64 v67, v48, v32, s[8:9]
	s_nop 0
	v_cndmask_b32_e64 v61, v54, v38, s[8:9]
	v_mov_b32_dpp v63, v62 quad_perm:[1,0,3,2] row_mask:0xf bank_mask:0xf
	s_nop 0
	v_cndmask_b32_e64 v66, v49, v33, s[8:9]
	v_mov_b32_dpp v68, v67 quad_perm:[1,0,3,2] row_mask:0xf bank_mask:0xf
	s_nop 0
	v_cndmask_b32_e64 v60, v55, v39, s[8:9]
	v_mov_b32_dpp v62, v61 quad_perm:[1,0,3,2] row_mask:0xf bank_mask:0xf
	s_nop 0
	v_cndmask_b32_e64 v65, v50, v34, s[8:9]
	v_mov_b32_dpp v67, v66 quad_perm:[1,0,3,2] row_mask:0xf bank_mask:0xf
	s_nop 0
	v_mov_b32_dpp v61, v60 quad_perm:[1,0,3,2] row_mask:0xf bank_mask:0xf
	v_cndmask_b32_e64 v60, v51, v35, s[8:9]
	v_mov_b32_dpp v66, v65 quad_perm:[1,0,3,2] row_mask:0xf bank_mask:0xf
	s_nop 0
	v_cndmask_b32_e64 v53, v63, v53, s[8:9]
	v_cndmask_b32_e64 v55, v61, v55, s[8:9]
	v_mov_b32_dpp v65, v60 quad_perm:[1,0,3,2] row_mask:0xf bank_mask:0xf
	v_cndmask_b32_e64 v49, v67, v49, s[8:9]
	v_cndmask_b32_e64 v48, v68, v48, s[8:9]
	v_cndmask_b32_e64 v52, v64, v52, s[8:9]
	v_cndmask_b32_e64 v51, v65, v51, s[8:9]
	v_cndmask_b32_e64 v54, v62, v54, s[8:9]
	v_cndmask_b32_e64 v50, v66, v50, s[8:9]
	v_add_u32_e32 v69, 0x900000, v156
	v_cndmask_b32_e64 v37, v37, v63, s[8:9]
	v_cndmask_b32_e64 v39, v39, v61, s[8:9]
	v_cndmask_b32_e64 v33, v33, v67, s[8:9]
	v_cndmask_b32_e64 v32, v32, v68, s[8:9]
	v_cndmask_b32_e64 v36, v36, v64, s[8:9]
	v_cndmask_b32_e64 v35, v35, v65, s[8:9]
	v_cndmask_b32_e64 v38, v38, v62, s[8:9]
	v_cndmask_b32_e64 v34, v34, v66, s[8:9]
	v_lshlrev_b32_e32 v60, 16, v56
	v_and_b32_e32 v56, 0xffff0000, v56
	v_fmac_f32_e32 v53, v45, v56
	v_mul_f32_e32 v56, 0x3d372713, v53
	v_mul_f32_e32 v56, v53, v56
	v_fma_f32 v56, v53, v56, v53
	v_mul_f32_e32 v56, 0x3f4c422a, v56
	v_lshlrev_b32_e32 v70, 16, v57
	v_and_b32_e32 v57, 0xffff0000, v57
	v_add_f32_e32 v56, v56, v56
	v_fmac_f32_e32 v55, v47, v57
	v_mul_f32_e32 v56, 0xbfb8aa3b, v56
	v_mul_f32_e32 v57, 0x3d372713, v55
	v_exp_f32_e32 v56, v56
	v_mul_f32_e32 v57, v55, v57
	v_fma_f32 v57, v55, v57, v55
	v_mul_f32_e32 v57, 0x3f4c422a, v57
	v_add_f32_e32 v57, v57, v57
	v_add_f32_e32 v56, 1.0, v56
	v_mul_f32_e32 v57, 0xbfb8aa3b, v57
	v_rcp_f32_e32 v56, v56
	v_exp_f32_e32 v57, v57
	v_fmac_f32_e32 v52, v44, v60
	v_mul_f32_e32 v60, 0x3d372713, v52
	v_mul_f32_e32 v53, v53, v56
	v_add_f32_e32 v56, 1.0, v57
	v_lshlrev_b32_e32 v57, 16, v58
	v_and_b32_e32 v58, 0xffff0000, v58
	v_fmac_f32_e32 v48, v40, v57
	v_fmac_f32_e32 v49, v41, v58
	v_mul_f32_e32 v57, 0x3d372713, v48
	v_mul_f32_e32 v58, 0x3d372713, v49
	v_mul_f32_e32 v57, v48, v57
	v_mul_f32_e32 v58, v49, v58
	v_fma_f32 v57, v48, v57, v48
	v_fma_f32 v58, v49, v58, v49
	v_mul_f32_e32 v57, 0x3f4c422a, v57
	v_mul_f32_e32 v58, 0x3f4c422a, v58
	v_add_f32_e32 v57, v57, v57
	v_add_f32_e32 v58, v58, v58
	v_mul_f32_e32 v57, 0xbfb8aa3b, v57
	v_mul_f32_e32 v58, 0xbfb8aa3b, v58
	v_rcp_f32_e32 v56, v56
	v_exp_f32_e32 v57, v57
	v_exp_f32_e32 v58, v58
	v_fmac_f32_e32 v54, v46, v70
	v_mul_f32_e32 v55, v55, v56
	v_add_f32_e32 v56, 1.0, v57
	v_add_f32_e32 v57, 1.0, v58
	v_lshlrev_b32_e32 v58, 16, v59
	v_and_b32_e32 v59, 0xffff0000, v59
	v_fmac_f32_e32 v51, v43, v59
	v_fmac_f32_e32 v50, v42, v58
	v_mul_f32_e32 v59, 0x3d372713, v51
	v_mul_f32_e32 v60, v52, v60
	v_mul_f32_e32 v70, 0x3d372713, v54
	v_mul_f32_e32 v58, 0x3d372713, v50
	v_mul_f32_e32 v59, v51, v59
	v_fma_f32 v60, v52, v60, v52
	v_mul_f32_e32 v70, v54, v70
	v_mul_f32_e32 v58, v50, v58
	v_fma_f32 v59, v51, v59, v51
	v_mul_f32_e32 v60, 0x3f4c422a, v60
	v_fma_f32 v70, v54, v70, v54
	v_fma_f32 v58, v50, v58, v50
	v_mul_f32_e32 v59, 0x3f4c422a, v59
	v_add_f32_e32 v60, v60, v60
	v_mul_f32_e32 v70, 0x3f4c422a, v70
	v_mul_f32_e32 v58, 0x3f4c422a, v58
	v_add_f32_e32 v59, v59, v59
	v_mul_f32_e32 v60, 0xbfb8aa3b, v60
	v_add_f32_e32 v70, v70, v70
	v_add_f32_e32 v58, v58, v58
	v_mul_f32_e32 v59, 0xbfb8aa3b, v59
	v_exp_f32_e32 v60, v60
	v_mul_f32_e32 v70, 0xbfb8aa3b, v70
	v_mul_f32_e32 v58, 0xbfb8aa3b, v58
	v_exp_f32_e32 v59, v59
	v_exp_f32_e32 v70, v70
	v_exp_f32_e32 v58, v58
	v_add_f32_e32 v60, 1.0, v60
	v_add_f32_e32 v59, 1.0, v59
	v_rcp_f32_e32 v60, v60
	v_add_f32_e32 v70, 1.0, v70
	v_rcp_f32_e32 v56, v56
	v_add_f32_e32 v58, 1.0, v58
	v_rcp_f32_e32 v59, v59
	v_rcp_f32_e32 v70, v70
	v_rcp_f32_e32 v57, v57
	v_rcp_f32_e32 v58, v58
	v_mul_f32_e32 v52, v52, v60
	v_mul_f32_e32 v56, v48, v56
	v_mul_f32_e32 v51, v51, v59
	v_cvt_pk_bf16_f32 v48, v52, v53
	v_mul_f32_e32 v54, v54, v70
	v_mul_f32_e32 v57, v49, v57
	v_mul_f32_e32 v58, v50, v58
	v_cvt_pk_bf16_f32 v49, v54, v55
	v_cvt_pk_bf16_f32 v50, v56, v57
	v_cvt_pk_bf16_f32 v51, v58, v51
	global_store_dwordx4 v69, v[48:51], s[12:13]
	s_nop 1
	v_add_u32_e32 v48, 0x1b300, v157
	s_waitcnt vmcnt(15)
; #define EPI_OPAQUE(x) asm volatile("" : "+v"(x))
; __device__ __forceinline__ float fast_exp(float x) { return __builtin_amdgcn_exp2f(x * 1.4426950408889634f); }
; __device__ __forceinline__ float fast_sigmoid(float x) { return __builtin_amdgcn_rcpf(1.0f + fast_exp(-x)); }
; __device__ __forceinline__ float gelu_tanh(float x) {
;     const float a = 0.7978845608028654f * (x + 0.044715f * x * x * x);
;     return x * fast_sigmoid(2.0f * a);
; }
;     __device__ __forceinline__ void operator()(const f32x4 (&acc)[2][2][4][2], const Unit& u, int wr, int wc, int fr, int fq, const EpiCtx& X) const {
;         const bool odd = fr & 1; const int fe = fr - (fr & 1), o32 = (fr & 1) * 32;
;         const int g = u.pn; const int p0 = 8 * (fq & 1);
;         const f32x4 d0 = *(const f32x4*)(dvec + g * 16 + p0), d1 = *(const f32x4*)(dvec + g * 16 + p0 + 4);
;         const char* ub = (const char*)(UA + (size_t)u.pm * BM * UA_LD);
;         unsigned ulo = (unsigned)((wr * 64 + fe) * UA_LD + wc * 64 + o32 + 8 * fq) * 2u; EPI_OPAQUE(ulo);
;         char* gb = (char*)(GACT + (size_t)(u.pm & 3) * 256 * 16 * W_SSM + g * 16);
;         unsigned glo = (unsigned)(((wr * 64 + fe) * 16 + wc * 4 + (fr & 1) * 2 + (fq >> 1)) * W_SSM + p0) * 2u; EPI_OPAQUE(glo);
;     ...
;         EPI_PIECES({ const unsigned uoff = ulo + (unsigned)(rl * UA_LD) * 2u, goff = glo + (unsigned)(rl * 16 * W_SSM) * 2u;
;             S2_ONE(p1a, p1b, uoff, goff); S2_ONE(p2a, p2b, uoff + UA_LD * 2, goff + 16 * W_SSM * 2); })
	s_nop 1
	v_mov_b32_e32 v48, v228
	v_mov_b32_e32 v49, v229
	v_mov_b32_e32 v50, v230
	v_mov_b32_e32 v51, v231
	v_lshlrev_b32_e32 v52, 16, v48
	v_and_b32_e32 v48, 0xffff0000, v48
	v_fmac_f32_e32 v37, v45, v48
	v_mul_f32_e32 v48, 0x3d372713, v37
	v_mul_f32_e32 v48, v37, v48
	v_fma_f32 v48, v37, v48, v37
	v_mul_f32_e32 v48, 0x3f4c422a, v48
	v_lshlrev_b32_e32 v53, 16, v49
	v_and_b32_e32 v49, 0xffff0000, v49
	v_add_f32_e32 v48, v48, v48
	v_fmac_f32_e32 v39, v47, v49
	v_mul_f32_e32 v48, 0xbfb8aa3b, v48
	v_mul_f32_e32 v49, 0x3d372713, v39
	v_exp_f32_e32 v48, v48
	v_mul_f32_e32 v49, v39, v49
	v_fma_f32 v49, v39, v49, v39
	v_mul_f32_e32 v49, 0x3f4c422a, v49
	v_add_f32_e32 v49, v49, v49
	v_add_f32_e32 v48, 1.0, v48
	v_mul_f32_e32 v49, 0xbfb8aa3b, v49
	v_rcp_f32_e32 v48, v48
	v_exp_f32_e32 v49, v49
	v_fmac_f32_e32 v36, v44, v52
	v_mul_f32_e32 v52, 0x3d372713, v36
	v_mul_f32_e32 v37, v37, v48
	v_add_f32_e32 v48, 1.0, v49
	v_lshlrev_b32_e32 v49, 16, v50
	v_and_b32_e32 v50, 0xffff0000, v50
	v_fmac_f32_e32 v32, v40, v49
	v_fmac_f32_e32 v33, v41, v50
	v_mul_f32_e32 v49, 0x3d372713, v32
	v_mul_f32_e32 v50, 0x3d372713, v33
	v_mul_f32_e32 v49, v32, v49
	v_mul_f32_e32 v50, v33, v50
	v_fma_f32 v49, v32, v49, v32
	v_fma_f32 v50, v33, v50, v33
	v_mul_f32_e32 v49, 0x3f4c422a, v49
	v_mul_f32_e32 v50, 0x3f4c422a, v50
	v_add_f32_e32 v49, v49, v49
	v_add_f32_e32 v50, v50, v50
	v_mul_f32_e32 v49, 0xbfb8aa3b, v49
	v_mul_f32_e32 v50, 0xbfb8aa3b, v50
	v_rcp_f32_e32 v48, v48
	v_exp_f32_e32 v49, v49
	v_exp_f32_e32 v50, v50
	v_mul_f32_e32 v52, v36, v52
	v_mul_f32_e32 v39, v39, v48
	v_add_f32_e32 v48, 1.0, v49
	v_add_f32_e32 v49, 1.0, v50
	v_lshlrev_b32_e32 v50, 16, v51
	v_and_b32_e32 v51, 0xffff0000, v51
	v_fmac_f32_e32 v35, v43, v51
	v_fmac_f32_e32 v38, v46, v53
	v_fmac_f32_e32 v34, v42, v50
	v_mul_f32_e32 v51, 0x3d372713, v35
	v_fma_f32 v52, v36, v52, v36
	v_mul_f32_e32 v53, 0x3d372713, v38
	v_mul_f32_e32 v50, 0x3d372713, v34
	v_mul_f32_e32 v51, v35, v51
	v_mul_f32_e32 v52, 0x3f4c422a, v52
	v_mul_f32_e32 v53, v38, v53
	v_mul_f32_e32 v50, v34, v50
	v_fma_f32 v51, v35, v51, v35
	v_add_f32_e32 v52, v52, v52
	v_fma_f32 v53, v38, v53, v38
	v_fma_f32 v50, v34, v50, v34
	v_mul_f32_e32 v51, 0x3f4c422a, v51
	v_mul_f32_e32 v52, 0xbfb8aa3b, v52
	v_mul_f32_e32 v53, 0x3f4c422a, v53
	v_mul_f32_e32 v50, 0x3f4c422a, v50
	v_add_f32_e32 v51, v51, v51
	v_exp_f32_e32 v52, v52
	v_add_f32_e32 v53, v53, v53
	v_add_f32_e32 v50, v50, v50
	v_mul_f32_e32 v51, 0xbfb8aa3b, v51
	v_mul_f32_e32 v53, 0xbfb8aa3b, v53
	v_mul_f32_e32 v50, 0xbfb8aa3b, v50
	v_exp_f32_e32 v51, v51
	v_exp_f32_e32 v53, v53
	v_exp_f32_e32 v50, v50
	v_add_f32_e32 v52, 1.0, v52
	v_rcp_f32_e32 v52, v52
	v_add_f32_e32 v51, 1.0, v51
	v_add_f32_e32 v53, 1.0, v53
	v_rcp_f32_e32 v48, v48
	v_add_f32_e32 v50, 1.0, v50
	v_rcp_f32_e32 v51, v51
	v_rcp_f32_e32 v53, v53
	v_rcp_f32_e32 v49, v49
	v_rcp_f32_e32 v50, v50
	v_mul_f32_e32 v36, v36, v52
	v_mul_f32_e32 v48, v32, v48
	v_mul_f32_e32 v35, v35, v51
	v_cvt_pk_bf16_f32 v32, v36, v37
	v_add_u32_e32 v36, 0x910000, v156
	v_mul_f32_e32 v38, v38, v53
	v_mul_f32_e32 v49, v33, v49
	v_mul_f32_e32 v50, v34, v50
	v_cvt_pk_bf16_f32 v33, v38, v39
	v_cvt_pk_bf16_f32 v34, v48, v49
	v_cvt_pk_bf16_f32 v35, v50, v35
	global_store_dwordx4 v36, v[32:35], s[12:13]
	v_cndmask_b32_e64 v39, v28, v20, s[8:9]
	s_nop 0
	v_add_u32_e32 v32, 0x1e000, v157
	s_waitcnt vmcnt(15)
	s_nop 1
	v_mov_b32_e32 v32, v232
	v_mov_b32_e32 v33, v233
	v_mov_b32_e32 v34, v234
	v_mov_b32_e32 v35, v235
	v_cndmask_b32_e64 v38, v29, v21, s[8:9]
	v_mov_b32_dpp v48, v39 quad_perm:[1,0,3,2] row_mask:0xf bank_mask:0xf
	s_nop 0
	v_cndmask_b32_e64 v51, v24, v16, s[8:9]
	s_nop 0
	v_cndmask_b32_e64 v37, v30, v22, s[8:9]
	v_mov_b32_dpp v39, v38 quad_perm:[1,0,3,2] row_mask:0xf bank_mask:0xf
	s_nop 0
	v_cndmask_b32_e64 v50, v25, v17, s[8:9]
	v_mov_b32_dpp v52, v51 quad_perm:[1,0,3,2] row_mask:0xf bank_mask:0xf
	s_nop 0
	v_cndmask_b32_e64 v36, v31, v23, s[8:9]
	v_mov_b32_dpp v38, v37 quad_perm:[1,0,3,2] row_mask:0xf bank_mask:0xf
	s_nop 0
	v_cndmask_b32_e64 v49, v26, v18, s[8:9]
	v_mov_b32_dpp v51, v50 quad_perm:[1,0,3,2] row_mask:0xf bank_mask:0xf
	s_nop 0
	v_mov_b32_dpp v37, v36 quad_perm:[1,0,3,2] row_mask:0xf bank_mask:0xf
	v_cndmask_b32_e64 v36, v27, v19, s[8:9]
	v_mov_b32_dpp v50, v49 quad_perm:[1,0,3,2] row_mask:0xf bank_mask:0xf
	s_nop 0
	v_cndmask_b32_e64 v29, v39, v29, s[8:9]
	v_cndmask_b32_e64 v31, v37, v31, s[8:9]
	v_mov_b32_dpp v49, v36 quad_perm:[1,0,3,2] row_mask:0xf bank_mask:0xf
	v_cndmask_b32_e64 v25, v51, v25, s[8:9]
	v_cndmask_b32_e64 v24, v52, v24, s[8:9]
	v_cndmask_b32_e64 v28, v48, v28, s[8:9]
	v_cndmask_b32_e64 v27, v49, v27, s[8:9]
	v_cndmask_b32_e64 v30, v38, v30, s[8:9]
	v_cndmask_b32_e64 v26, v50, v26, s[8:9]
	v_add_u32_e32 v53, 0xa00000, v156
	v_cndmask_b32_e64 v21, v21, v39, s[8:9]
	v_cndmask_b32_e64 v23, v23, v37, s[8:9]
	v_cndmask_b32_e64 v17, v17, v51, s[8:9]
	v_cndmask_b32_e64 v16, v16, v52, s[8:9]
	v_cndmask_b32_e64 v20, v20, v48, s[8:9]
	v_cndmask_b32_e64 v19, v19, v49, s[8:9]
	v_cndmask_b32_e64 v22, v22, v38, s[8:9]
	v_cndmask_b32_e64 v18, v18, v50, s[8:9]
	v_lshlrev_b32_e32 v36, 16, v32
	v_and_b32_e32 v32, 0xffff0000, v32
	v_fmac_f32_e32 v29, v45, v32
	v_mul_f32_e32 v32, 0x3d372713, v29
	v_mul_f32_e32 v32, v29, v32
	v_fma_f32 v32, v29, v32, v29
	v_mul_f32_e32 v32, 0x3f4c422a, v32
	v_lshlrev_b32_e32 v54, 16, v33
	v_and_b32_e32 v33, 0xffff0000, v33
	v_add_f32_e32 v32, v32, v32
	v_fmac_f32_e32 v31, v47, v33
	v_mul_f32_e32 v32, 0xbfb8aa3b, v32
	v_mul_f32_e32 v33, 0x3d372713, v31
	v_exp_f32_e32 v32, v32
	v_mul_f32_e32 v33, v31, v33
	v_fma_f32 v33, v31, v33, v31
	v_mul_f32_e32 v33, 0x3f4c422a, v33
	v_add_f32_e32 v33, v33, v33
; #define EPI_OPAQUE(x) asm volatile("" : "+v"(x))
; __device__ __forceinline__ float fast_exp(float x) { return __builtin_amdgcn_exp2f(x * 1.4426950408889634f); }
; __device__ __forceinline__ float fast_sigmoid(float x) { return __builtin_amdgcn_rcpf(1.0f + fast_exp(-x)); }
; __device__ __forceinline__ float gelu_tanh(float x) {
;     const float a = 0.7978845608028654f * (x + 0.044715f * x * x * x);
;     return x * fast_sigmoid(2.0f * a);
; }
;     __device__ __forceinline__ void operator()(const f32x4 (&acc)[2][2][4][2], const Unit& u, int wr, int wc, int fr, int fq, const EpiCtx& X) const {
;         const bool odd = fr & 1; const int fe = fr - (fr & 1), o32 = (fr & 1) * 32;
;         const int g = u.pn; const int p0 = 8 * (fq & 1);
;         const f32x4 d0 = *(const f32x4*)(dvec + g * 16 + p0), d1 = *(const f32x4*)(dvec + g * 16 + p0 + 4);
;         const char* ub = (const char*)(UA + (size_t)u.pm * BM * UA_LD);
;         unsigned ulo = (unsigned)((wr * 64 + fe) * UA_LD + wc * 64 + o32 + 8 * fq) * 2u; EPI_OPAQUE(ulo);
;         char* gb = (char*)(GACT + (size_t)(u.pm & 3) * 256 * 16 * W_SSM + g * 16);
;         unsigned glo = (unsigned)(((wr * 64 + fe) * 16 + wc * 4 + (fr & 1) * 2 + (fq >> 1)) * W_SSM + p0) * 2u; EPI_OPAQUE(glo);
;     ...
;         EPI_PIECES({ const unsigned uoff = ulo + (unsigned)(rl * UA_LD) * 2u, goff = glo + (unsigned)(rl * 16 * W_SSM) * 2u;
;             S2_ONE(p1a, p1b, uoff, goff); S2_ONE(p2a, p2b, uoff + UA_LD * 2, goff + 16 * W_SSM * 2); })
	v_add_f32_e32 v32, 1.0, v32
	v_mul_f32_e32 v33, 0xbfb8aa3b, v33
	v_rcp_f32_e32 v32, v32
	v_exp_f32_e32 v33, v33
	v_fmac_f32_e32 v28, v44, v36
	v_mul_f32_e32 v36, 0x3d372713, v28
	v_mul_f32_e32 v29, v29, v32
	v_add_f32_e32 v32, 1.0, v33
	v_lshlrev_b32_e32 v33, 16, v34
	v_and_b32_e32 v34, 0xffff0000, v34
	v_fmac_f32_e32 v24, v40, v33
	v_fmac_f32_e32 v25, v41, v34
	v_mul_f32_e32 v33, 0x3d372713, v24
	v_mul_f32_e32 v34, 0x3d372713, v25
	v_mul_f32_e32 v33, v24, v33
	v_mul_f32_e32 v34, v25, v34
	v_fma_f32 v33, v24, v33, v24
	v_fma_f32 v34, v25, v34, v25
	v_mul_f32_e32 v33, 0x3f4c422a, v33
	v_mul_f32_e32 v34, 0x3f4c422a, v34
	v_add_f32_e32 v33, v33, v33
	v_add_f32_e32 v34, v34, v34
	v_mul_f32_e32 v33, 0xbfb8aa3b, v33
	v_mul_f32_e32 v34, 0xbfb8aa3b, v34
	v_rcp_f32_e32 v32, v32
	v_exp_f32_e32 v33, v33
	v_exp_f32_e32 v34, v34
	v_fmac_f32_e32 v30, v46, v54
	v_mul_f32_e32 v31, v31, v32
	v_add_f32_e32 v32, 1.0, v33
	v_add_f32_e32 v33, 1.0, v34
	v_lshlrev_b32_e32 v34, 16, v35
	v_and_b32_e32 v35, 0xffff0000, v35
	v_fmac_f32_e32 v27, v43, v35
	v_fmac_f32_e32 v26, v42, v34
	v_mul_f32_e32 v35, 0x3d372713, v27
	v_mul_f32_e32 v36, v28, v36
	v_mul_f32_e32 v54, 0x3d372713, v30
	v_mul_f32_e32 v34, 0x3d372713, v26
	v_mul_f32_e32 v35, v27, v35
	v_fma_f32 v36, v28, v36, v28
	v_mul_f32_e32 v54, v30, v54
	v_mul_f32_e32 v34, v26, v34
	v_fma_f32 v35, v27, v35, v27
	v_mul_f32_e32 v36, 0x3f4c422a, v36
	v_fma_f32 v54, v30, v54, v30
	v_fma_f32 v34, v26, v34, v26
	v_mul_f32_e32 v35, 0x3f4c422a, v35
	v_add_f32_e32 v36, v36, v36
	v_mul_f32_e32 v54, 0x3f4c422a, v54
	v_mul_f32_e32 v34, 0x3f4c422a, v34
	v_add_f32_e32 v35, v35, v35
	v_mul_f32_e32 v36, 0xbfb8aa3b, v36
	v_add_f32_e32 v54, v54, v54
	v_add_f32_e32 v34, v34, v34
	v_mul_f32_e32 v35, 0xbfb8aa3b, v35
	v_exp_f32_e32 v36, v36
	v_mul_f32_e32 v54, 0xbfb8aa3b, v54
	v_mul_f32_e32 v34, 0xbfb8aa3b, v34
	v_exp_f32_e32 v35, v35
	v_exp_f32_e32 v54, v54
	v_exp_f32_e32 v34, v34
	v_add_f32_e32 v36, 1.0, v36
	v_add_f32_e32 v35, 1.0, v35
	v_rcp_f32_e32 v36, v36
	v_add_f32_e32 v54, 1.0, v54
	v_rcp_f32_e32 v32, v32
	v_add_f32_e32 v34, 1.0, v34
	v_rcp_f32_e32 v35, v35
	v_rcp_f32_e32 v54, v54
	v_rcp_f32_e32 v33, v33
	v_rcp_f32_e32 v34, v34
	v_mul_f32_e32 v28, v28, v36
	v_mul_f32_e32 v32, v24, v32
	v_mul_f32_e32 v27, v27, v35
	v_cvt_pk_bf16_f32 v24, v28, v29
	v_mul_f32_e32 v30, v30, v54
	v_mul_f32_e32 v33, v25, v33
	v_mul_f32_e32 v34, v26, v34
	v_cvt_pk_bf16_f32 v25, v30, v31
	v_cvt_pk_bf16_f32 v26, v32, v33
	v_cvt_pk_bf16_f32 v27, v34, v27
	global_store_dwordx4 v53, v[24:27], s[12:13]
	s_nop 1
	v_add_u32_e32 v24, 0x1e300, v157
	s_waitcnt vmcnt(15)
	s_nop 1
	v_mov_b32_e32 v24, v236
	v_mov_b32_e32 v25, v237
	v_mov_b32_e32 v26, v238
	v_mov_b32_e32 v27, v239
	v_lshlrev_b32_e32 v28, 16, v24
	v_and_b32_e32 v24, 0xffff0000, v24
	v_fmac_f32_e32 v21, v45, v24
	v_mul_f32_e32 v24, 0x3d372713, v21
	v_mul_f32_e32 v24, v21, v24
	v_fma_f32 v24, v21, v24, v21
	v_mul_f32_e32 v24, 0x3f4c422a, v24
	v_lshlrev_b32_e32 v29, 16, v25
	v_and_b32_e32 v25, 0xffff0000, v25
	v_add_f32_e32 v24, v24, v24
	v_fmac_f32_e32 v23, v47, v25
	v_mul_f32_e32 v24, 0xbfb8aa3b, v24
	v_mul_f32_e32 v25, 0x3d372713, v23
	v_exp_f32_e32 v24, v24
	v_mul_f32_e32 v25, v23, v25
	v_fma_f32 v25, v23, v25, v23
	v_mul_f32_e32 v25, 0x3f4c422a, v25
	v_add_f32_e32 v25, v25, v25
	v_add_f32_e32 v24, 1.0, v24
	v_mul_f32_e32 v25, 0xbfb8aa3b, v25
	v_rcp_f32_e32 v24, v24
	v_exp_f32_e32 v25, v25
	v_fmac_f32_e32 v20, v44, v28
	v_mul_f32_e32 v28, 0x3d372713, v20
	v_mul_f32_e32 v21, v21, v24
	v_add_f32_e32 v24, 1.0, v25
	v_lshlrev_b32_e32 v25, 16, v26
	v_and_b32_e32 v26, 0xffff0000, v26
	v_fmac_f32_e32 v16, v40, v25
	v_fmac_f32_e32 v17, v41, v26
	v_mul_f32_e32 v25, 0x3d372713, v16
	v_mul_f32_e32 v26, 0x3d372713, v17
	v_mul_f32_e32 v25, v16, v25
	v_mul_f32_e32 v26, v17, v26
	v_fma_f32 v25, v16, v25, v16
	v_fma_f32 v26, v17, v26, v17
	v_mul_f32_e32 v25, 0x3f4c422a, v25
	v_mul_f32_e32 v26, 0x3f4c422a, v26
	v_add_f32_e32 v25, v25, v25
	v_add_f32_e32 v26, v26, v26
	v_mul_f32_e32 v25, 0xbfb8aa3b, v25
	v_mul_f32_e32 v26, 0xbfb8aa3b, v26
	v_rcp_f32_e32 v24, v24
	v_exp_f32_e32 v25, v25
	v_exp_f32_e32 v26, v26
	v_mul_f32_e32 v28, v20, v28
	v_mul_f32_e32 v23, v23, v24
	v_add_f32_e32 v24, 1.0, v25
	v_add_f32_e32 v25, 1.0, v26
	v_lshlrev_b32_e32 v26, 16, v27
	v_and_b32_e32 v27, 0xffff0000, v27
	v_fmac_f32_e32 v19, v43, v27
	v_fmac_f32_e32 v22, v46, v29
	v_fmac_f32_e32 v18, v42, v26
	v_mul_f32_e32 v27, 0x3d372713, v19
	v_fma_f32 v28, v20, v28, v20
	v_mul_f32_e32 v29, 0x3d372713, v22
	v_mul_f32_e32 v26, 0x3d372713, v18
	v_mul_f32_e32 v27, v19, v27
	v_mul_f32_e32 v28, 0x3f4c422a, v28
	v_mul_f32_e32 v29, v22, v29
	v_mul_f32_e32 v26, v18, v26
	v_fma_f32 v27, v19, v27, v19
	v_add_f32_e32 v28, v28, v28
	v_fma_f32 v29, v22, v29, v22
	v_fma_f32 v26, v18, v26, v18
	v_mul_f32_e32 v27, 0x3f4c422a, v27
	v_mul_f32_e32 v28, 0xbfb8aa3b, v28
	v_mul_f32_e32 v29, 0x3f4c422a, v29
	v_mul_f32_e32 v26, 0x3f4c422a, v26
	v_add_f32_e32 v27, v27, v27
	v_exp_f32_e32 v28, v28
	v_add_f32_e32 v29, v29, v29
	v_add_f32_e32 v26, v26, v26
	v_mul_f32_e32 v27, 0xbfb8aa3b, v27
	v_mul_f32_e32 v29, 0xbfb8aa3b, v29
	v_mul_f32_e32 v26, 0xbfb8aa3b, v26
	v_exp_f32_e32 v27, v27
	v_exp_f32_e32 v29, v29
	v_exp_f32_e32 v26, v26
	v_add_f32_e32 v28, 1.0, v28
	v_rcp_f32_e32 v28, v28
	v_add_f32_e32 v27, 1.0, v27
	v_add_f32_e32 v29, 1.0, v29
	v_rcp_f32_e32 v24, v24
	v_add_f32_e32 v26, 1.0, v26
	v_rcp_f32_e32 v27, v27
	v_rcp_f32_e32 v29, v29
	v_rcp_f32_e32 v25, v25
	v_rcp_f32_e32 v26, v26
	v_mul_f32_e32 v20, v20, v28
	v_mul_f32_e32 v24, v16, v24
	v_mul_f32_e32 v19, v19, v27
	v_cvt_pk_bf16_f32 v16, v20, v21
	v_add_u32_e32 v20, 0xa10000, v156
	v_mul_f32_e32 v22, v22, v29
	v_mul_f32_e32 v25, v17, v25
	v_mul_f32_e32 v26, v18, v26
	v_cvt_pk_bf16_f32 v17, v22, v23
	v_cvt_pk_bf16_f32 v18, v24, v25
	v_cvt_pk_bf16_f32 v19, v26, v19
	global_store_dwordx4 v20, v[16:19], s[12:13]
	v_cndmask_b32_e64 v23, v12, v4, s[8:9]
	s_nop 0
	v_add_u32_e32 v16, 0x21000, v157
	s_waitcnt vmcnt(15)
; #define EPI_OPAQUE(x) asm volatile("" : "+v"(x))
; __device__ __forceinline__ float fast_exp(float x) { return __builtin_amdgcn_exp2f(x * 1.4426950408889634f); }
; __device__ __forceinline__ float fast_sigmoid(float x) { return __builtin_amdgcn_rcpf(1.0f + fast_exp(-x)); }
; __device__ __forceinline__ float gelu_tanh(float x) {
;     const float a = 0.7978845608028654f * (x + 0.044715f * x * x * x);
;     return x * fast_sigmoid(2.0f * a);
; }
;     __device__ __forceinline__ void operator()(const f32x4 (&acc)[2][2][4][2], const Unit& u, int wr, int wc, int fr, int fq, const EpiCtx& X) const {
;         const bool odd = fr & 1; const int fe = fr - (fr & 1), o32 = (fr & 1) * 32;
;         const int g = u.pn; const int p0 = 8 * (fq & 1);
;         const f32x4 d0 = *(const f32x4*)(dvec + g * 16 + p0), d1 = *(const f32x4*)(dvec + g * 16 + p0 + 4);
;         const char* ub = (const char*)(UA + (size_t)u.pm * BM * UA_LD);
;         unsigned ulo = (unsigned)((wr * 64 + fe) * UA_LD + wc * 64 + o32 + 8 * fq) * 2u; EPI_OPAQUE(ulo);
;         char* gb = (char*)(GACT + (size_t)(u.pm & 3) * 256 * 16 * W_SSM + g * 16);
;         unsigned glo = (unsigned)(((wr * 64 + fe) * 16 + wc * 4 + (fr & 1) * 2 + (fq >> 1)) * W_SSM + p0) * 2u; EPI_OPAQUE(glo);
;     ...
;         EPI_PIECES({ const unsigned uoff = ulo + (unsigned)(rl * UA_LD) * 2u, goff = glo + (unsigned)(rl * 16 * W_SSM) * 2u;
;             S2_ONE(p1a, p1b, uoff, goff); S2_ONE(p2a, p2b, uoff + UA_LD * 2, goff + 16 * W_SSM * 2); })
	s_nop 1
	v_mov_b32_e32 v16, v240
	v_mov_b32_e32 v17, v241
	v_mov_b32_e32 v18, v242
	v_mov_b32_e32 v19, v243
	v_cndmask_b32_e64 v22, v13, v5, s[8:9]
	v_mov_b32_dpp v24, v23 quad_perm:[1,0,3,2] row_mask:0xf bank_mask:0xf
	s_nop 0
	v_cndmask_b32_e64 v27, v8, v0, s[8:9]
	s_nop 0
	v_cndmask_b32_e64 v21, v14, v6, s[8:9]
	v_mov_b32_dpp v23, v22 quad_perm:[1,0,3,2] row_mask:0xf bank_mask:0xf
	s_nop 0
	v_cndmask_b32_e64 v26, v9, v1, s[8:9]
	v_mov_b32_dpp v28, v27 quad_perm:[1,0,3,2] row_mask:0xf bank_mask:0xf
	s_nop 0
	v_cndmask_b32_e64 v20, v15, v7, s[8:9]
	v_mov_b32_dpp v22, v21 quad_perm:[1,0,3,2] row_mask:0xf bank_mask:0xf
	s_nop 0
	v_cndmask_b32_e64 v25, v10, v2, s[8:9]
	v_mov_b32_dpp v27, v26 quad_perm:[1,0,3,2] row_mask:0xf bank_mask:0xf
	s_nop 0
	v_mov_b32_dpp v21, v20 quad_perm:[1,0,3,2] row_mask:0xf bank_mask:0xf
	v_cndmask_b32_e64 v20, v11, v3, s[8:9]
	v_mov_b32_dpp v26, v25 quad_perm:[1,0,3,2] row_mask:0xf bank_mask:0xf
	s_nop 0
	v_cndmask_b32_e64 v13, v23, v13, s[8:9]
	v_cndmask_b32_e64 v15, v21, v15, s[8:9]
	v_mov_b32_dpp v25, v20 quad_perm:[1,0,3,2] row_mask:0xf bank_mask:0xf
	v_cndmask_b32_e64 v9, v27, v9, s[8:9]
	v_cndmask_b32_e64 v8, v28, v8, s[8:9]
	v_cndmask_b32_e64 v12, v24, v12, s[8:9]
	v_cndmask_b32_e64 v11, v25, v11, s[8:9]
	v_cndmask_b32_e64 v14, v22, v14, s[8:9]
	v_cndmask_b32_e64 v10, v26, v10, s[8:9]
	v_add_u32_e32 v29, 0xb00000, v156
	v_cndmask_b32_e64 v5, v5, v23, s[8:9]
	v_cndmask_b32_e64 v7, v7, v21, s[8:9]
	v_cndmask_b32_e64 v1, v1, v27, s[8:9]
	v_cndmask_b32_e64 v0, v0, v28, s[8:9]
	v_cndmask_b32_e64 v4, v4, v24, s[8:9]
	v_cndmask_b32_e64 v3, v3, v25, s[8:9]
	v_cndmask_b32_e64 v6, v6, v22, s[8:9]
	v_cndmask_b32_e64 v2, v2, v26, s[8:9]
	v_lshlrev_b32_e32 v20, 16, v16
	v_and_b32_e32 v16, 0xffff0000, v16
	v_fmac_f32_e32 v13, v45, v16
	v_mul_f32_e32 v16, 0x3d372713, v13
	v_mul_f32_e32 v16, v13, v16
	v_fma_f32 v16, v13, v16, v13
	v_mul_f32_e32 v16, 0x3f4c422a, v16
	v_lshlrev_b32_e32 v30, 16, v17
	v_and_b32_e32 v17, 0xffff0000, v17
	v_add_f32_e32 v16, v16, v16
	v_fmac_f32_e32 v15, v47, v17
	v_mul_f32_e32 v16, 0xbfb8aa3b, v16
	v_mul_f32_e32 v17, 0x3d372713, v15
	v_exp_f32_e32 v16, v16
	v_mul_f32_e32 v17, v15, v17
	v_fma_f32 v17, v15, v17, v15
	v_mul_f32_e32 v17, 0x3f4c422a, v17
	v_add_f32_e32 v17, v17, v17
	v_add_f32_e32 v16, 1.0, v16
	v_mul_f32_e32 v17, 0xbfb8aa3b, v17
	v_rcp_f32_e32 v16, v16
	v_exp_f32_e32 v17, v17
	v_fmac_f32_e32 v12, v44, v20
	v_mul_f32_e32 v20, 0x3d372713, v12
	v_mul_f32_e32 v13, v13, v16
	v_add_f32_e32 v16, 1.0, v17
	v_lshlrev_b32_e32 v17, 16, v18
	v_and_b32_e32 v18, 0xffff0000, v18
	v_fmac_f32_e32 v8, v40, v17
	v_fmac_f32_e32 v9, v41, v18
	v_mul_f32_e32 v17, 0x3d372713, v8
	v_mul_f32_e32 v18, 0x3d372713, v9
	v_mul_f32_e32 v17, v8, v17
	v_mul_f32_e32 v18, v9, v18
	v_fma_f32 v17, v8, v17, v8
	v_fma_f32 v18, v9, v18, v9
	v_mul_f32_e32 v17, 0x3f4c422a, v17
	v_mul_f32_e32 v18, 0x3f4c422a, v18
	v_add_f32_e32 v17, v17, v17
	v_add_f32_e32 v18, v18, v18
	v_mul_f32_e32 v17, 0xbfb8aa3b, v17
	v_mul_f32_e32 v18, 0xbfb8aa3b, v18
	v_rcp_f32_e32 v16, v16
	v_exp_f32_e32 v17, v17
	v_exp_f32_e32 v18, v18
	v_fmac_f32_e32 v14, v46, v30
	v_mul_f32_e32 v15, v15, v16
	v_add_f32_e32 v16, 1.0, v17
	v_add_f32_e32 v17, 1.0, v18
	v_lshlrev_b32_e32 v18, 16, v19
	v_and_b32_e32 v19, 0xffff0000, v19
	v_fmac_f32_e32 v11, v43, v19
	v_fmac_f32_e32 v10, v42, v18
	v_mul_f32_e32 v19, 0x3d372713, v11
	v_mul_f32_e32 v20, v12, v20
	v_mul_f32_e32 v30, 0x3d372713, v14
	v_mul_f32_e32 v18, 0x3d372713, v10
	v_mul_f32_e32 v19, v11, v19
	v_fma_f32 v20, v12, v20, v12
	v_mul_f32_e32 v30, v14, v30
	v_mul_f32_e32 v18, v10, v18
	v_fma_f32 v19, v11, v19, v11
	v_mul_f32_e32 v20, 0x3f4c422a, v20
	v_fma_f32 v30, v14, v30, v14
	v_fma_f32 v18, v10, v18, v10
	v_mul_f32_e32 v19, 0x3f4c422a, v19
	v_add_f32_e32 v20, v20, v20
	v_mul_f32_e32 v30, 0x3f4c422a, v30
	v_mul_f32_e32 v18, 0x3f4c422a, v18
	v_add_f32_e32 v19, v19, v19
	v_mul_f32_e32 v20, 0xbfb8aa3b, v20
	v_add_f32_e32 v30, v30, v30
	v_add_f32_e32 v18, v18, v18
	v_mul_f32_e32 v19, 0xbfb8aa3b, v19
	v_exp_f32_e32 v20, v20
	v_mul_f32_e32 v30, 0xbfb8aa3b, v30
	v_mul_f32_e32 v18, 0xbfb8aa3b, v18
	v_exp_f32_e32 v19, v19
	v_exp_f32_e32 v30, v30
	v_exp_f32_e32 v18, v18
	v_add_f32_e32 v20, 1.0, v20
	v_add_f32_e32 v19, 1.0, v19
	v_rcp_f32_e32 v20, v20
	v_add_f32_e32 v30, 1.0, v30
	v_rcp_f32_e32 v16, v16
	v_add_f32_e32 v18, 1.0, v18
	v_rcp_f32_e32 v19, v19
	v_rcp_f32_e32 v30, v30
	v_rcp_f32_e32 v17, v17
	v_rcp_f32_e32 v18, v18
	v_mul_f32_e32 v12, v12, v20
	v_mul_f32_e32 v16, v8, v16
	v_mul_f32_e32 v11, v11, v19
	v_cvt_pk_bf16_f32 v8, v12, v13
	v_mul_f32_e32 v14, v14, v30
	v_mul_f32_e32 v17, v9, v17
	v_mul_f32_e32 v18, v10, v18
	v_cvt_pk_bf16_f32 v9, v14, v15
	v_cvt_pk_bf16_f32 v10, v16, v17
	v_cvt_pk_bf16_f32 v11, v18, v11
	global_store_dwordx4 v29, v[8:11], s[12:13]
	s_nop 1
	v_add_u32_e32 v8, 0x21300, v157
	s_waitcnt vmcnt(15)
; #define EPI_OPAQUE(x) asm volatile("" : "+v"(x))
; __device__ __forceinline__ float fast_exp(float x) { return __builtin_amdgcn_exp2f(x * 1.4426950408889634f); }
; __device__ __forceinline__ float fast_sigmoid(float x) { return __builtin_amdgcn_rcpf(1.0f + fast_exp(-x)); }
; __device__ __forceinline__ float gelu_tanh(float x) {
;     const float a = 0.7978845608028654f * (x + 0.044715f * x * x * x);
;     return x * fast_sigmoid(2.0f * a);
; }
;     __device__ __forceinline__ void operator()(const f32x4 (&acc)[2][2][4][2], const Unit& u, int wr, int wc, int fr, int fq, const EpiCtx& X) const {
;         const bool odd = fr & 1; const int fe = fr - (fr & 1), o32 = (fr & 1) * 32;
;         const int g = u.pn; const int p0 = 8 * (fq & 1);
;         const f32x4 d0 = *(const f32x4*)(dvec + g * 16 + p0), d1 = *(const f32x4*)(dvec + g * 16 + p0 + 4);
;         const char* ub = (const char*)(UA + (size_t)u.pm * BM * UA_LD);
;         unsigned ulo = (unsigned)((wr * 64 + fe) * UA_LD + wc * 64 + o32 + 8 * fq) * 2u; EPI_OPAQUE(ulo);
;         char* gb = (char*)(GACT + (size_t)(u.pm & 3) * 256 * 16 * W_SSM + g * 16);
;         unsigned glo = (unsigned)(((wr * 64 + fe) * 16 + wc * 4 + (fr & 1) * 2 + (fq >> 1)) * W_SSM + p0) * 2u; EPI_OPAQUE(glo);
;     ...
;         EPI_PIECES({ const unsigned uoff = ulo + (unsigned)(rl * UA_LD) * 2u, goff = glo + (unsigned)(rl * 16 * W_SSM) * 2u;
;             S2_ONE(p1a, p1b, uoff, goff); S2_ONE(p2a, p2b, uoff + UA_LD * 2, goff + 16 * W_SSM * 2); })
	s_nop 1
	v_mov_b32_e32 v8, v244
	v_mov_b32_e32 v9, v245
	v_mov_b32_e32 v10, v246
	v_mov_b32_e32 v11, v247
	v_lshlrev_b32_e32 v12, 16, v8
	v_and_b32_e32 v8, 0xffff0000, v8
	v_fmac_f32_e32 v5, v45, v8
	v_mul_f32_e32 v8, 0x3d372713, v5
	v_mul_f32_e32 v8, v5, v8
	v_fma_f32 v8, v5, v8, v5
	v_mul_f32_e32 v8, 0x3f4c422a, v8
	v_lshlrev_b32_e32 v13, 16, v9
	v_and_b32_e32 v9, 0xffff0000, v9
	v_add_f32_e32 v8, v8, v8
	v_fmac_f32_e32 v7, v47, v9
	v_mul_f32_e32 v8, 0xbfb8aa3b, v8
	v_mul_f32_e32 v9, 0x3d372713, v7
	v_exp_f32_e32 v8, v8
	v_mul_f32_e32 v9, v7, v9
	v_fma_f32 v9, v7, v9, v7
	v_mul_f32_e32 v9, 0x3f4c422a, v9
	v_add_f32_e32 v9, v9, v9
	v_add_f32_e32 v8, 1.0, v8
	v_mul_f32_e32 v9, 0xbfb8aa3b, v9
	v_rcp_f32_e32 v8, v8
	v_exp_f32_e32 v9, v9
	v_fmac_f32_e32 v4, v44, v12
	v_mul_f32_e32 v12, 0x3d372713, v4
	v_mul_f32_e32 v5, v5, v8
	v_add_f32_e32 v8, 1.0, v9
	v_lshlrev_b32_e32 v9, 16, v10
	v_and_b32_e32 v10, 0xffff0000, v10
	v_fmac_f32_e32 v0, v40, v9
	v_fmac_f32_e32 v1, v41, v10
	v_mul_f32_e32 v9, 0x3d372713, v0
	v_mul_f32_e32 v10, 0x3d372713, v1
	v_mul_f32_e32 v9, v0, v9
	v_mul_f32_e32 v10, v1, v10
	v_fma_f32 v9, v0, v9, v0
	v_fma_f32 v10, v1, v10, v1
	v_mul_f32_e32 v9, 0x3f4c422a, v9
	v_mul_f32_e32 v10, 0x3f4c422a, v10
	v_add_f32_e32 v9, v9, v9
	v_add_f32_e32 v10, v10, v10
	v_mul_f32_e32 v9, 0xbfb8aa3b, v9
	v_mul_f32_e32 v10, 0xbfb8aa3b, v10
	v_rcp_f32_e32 v8, v8
	v_exp_f32_e32 v9, v9
	v_exp_f32_e32 v10, v10
	v_mul_f32_e32 v12, v4, v12
	v_mul_f32_e32 v7, v7, v8
	v_add_f32_e32 v8, 1.0, v9
	v_add_f32_e32 v9, 1.0, v10
	v_lshlrev_b32_e32 v10, 16, v11
	v_and_b32_e32 v11, 0xffff0000, v11
	v_fmac_f32_e32 v3, v43, v11
	v_fmac_f32_e32 v6, v46, v13
	v_fmac_f32_e32 v2, v42, v10
	v_mul_f32_e32 v11, 0x3d372713, v3
	v_fma_f32 v12, v4, v12, v4
	v_mul_f32_e32 v13, 0x3d372713, v6
	v_mul_f32_e32 v10, 0x3d372713, v2
	v_mul_f32_e32 v11, v3, v11
	v_mul_f32_e32 v12, 0x3f4c422a, v12
	v_mul_f32_e32 v13, v6, v13
	v_mul_f32_e32 v10, v2, v10
	v_fma_f32 v11, v3, v11, v3
	v_add_f32_e32 v12, v12, v12
	v_fma_f32 v13, v6, v13, v6
	v_fma_f32 v10, v2, v10, v2
	v_mul_f32_e32 v11, 0x3f4c422a, v11
	v_mul_f32_e32 v12, 0xbfb8aa3b, v12
	v_mul_f32_e32 v13, 0x3f4c422a, v13
	v_mul_f32_e32 v10, 0x3f4c422a, v10
	v_add_f32_e32 v11, v11, v11
	v_exp_f32_e32 v12, v12
	v_add_f32_e32 v13, v13, v13
	v_add_f32_e32 v10, v10, v10
	v_mul_f32_e32 v11, 0xbfb8aa3b, v11
	v_mul_f32_e32 v13, 0xbfb8aa3b, v13
	v_mul_f32_e32 v10, 0xbfb8aa3b, v10
	v_exp_f32_e32 v11, v11
	v_exp_f32_e32 v13, v13
	v_exp_f32_e32 v10, v10
	v_add_f32_e32 v12, 1.0, v12
	v_rcp_f32_e32 v12, v12
	v_add_f32_e32 v11, 1.0, v11
	v_add_f32_e32 v13, 1.0, v13
	v_rcp_f32_e32 v8, v8
	v_add_f32_e32 v10, 1.0, v10
	v_rcp_f32_e32 v11, v11
	v_rcp_f32_e32 v13, v13
	v_rcp_f32_e32 v9, v9
	v_rcp_f32_e32 v10, v10
	v_mul_f32_e32 v4, v4, v12
	v_mul_f32_e32 v8, v0, v8
	v_mul_f32_e32 v3, v3, v11
	v_cvt_pk_bf16_f32 v0, v4, v5
	v_add_u32_e32 v4, 0xb10000, v156
	v_mul_f32_e32 v6, v6, v13
	v_mul_f32_e32 v9, v1, v9
	v_mul_f32_e32 v10, v2, v10
	v_cvt_pk_bf16_f32 v1, v6, v7
	v_cvt_pk_bf16_f32 v2, v8, v9
	v_cvt_pk_bf16_f32 v3, v10, v3
	global_store_dwordx4 v4, v[0:3], s[12:13]
	s_cbranch_vccnz .LBB0_276
	s_and_b64 vcc, exec, s[6:7]
	s_cbranch_vccnz .LBB0_275
	s_barrier
	s_branch .LBB0_275

; #define EPI_OPAQUE(x) asm volatile("" : "+v"(x))
;     __device__ __forceinline__ void operator()(const f32x4 (&acc)[2][2][4][2], const Unit& u, int wr, int wc, int fr, int fq, const EpiCtx& X) const {
;         const bool odd = fr & 1; const int fe = fr - (fr & 1), o32 = (fr & 1) * 32;
;         const char* gb = (const char*)(GACT + (size_t)u.pm * BM * W_SSM + u.pn * BM);
;         unsigned glo = (unsigned)((wr * 64 + fe) * W_SSM + wc * 64 + o32 + 8 * fq) * 2u; EPI_OPAQUE(glo);
;         char* cb = (char*)(CC + (size_t)u.pm * BM * DM + u.pn * BM);
;         unsigned clo = (unsigned)((wr * 64 + fe) * DM + wc * 64 + o32 + 8 * fq) * 2u; EPI_OPAQUE(clo);
;     ...
;         EPI_PIECES({ const unsigned goff = glo + (unsigned)(rl * W_SSM) * 2u, coff = clo + (unsigned)(rl * DM) * 2u;
;             GLU_ONE(p1a, p1b, goff, coff); GLU_ONE(p2a, p2b, goff + W_SSM * 2, coff + DM * 2); })
.LBB0_502:
	s_ashr_i32 s27, s26, 31
	s_lshl_b64 s[24:25], s[26:27], 20
	s_add_u32 s17, s30, s24
	s_addc_u32 s19, s31, s25
	s_lshl_b32 s24, s35, 8
	s_ashr_i32 s25, s24, 31
	s_lshl_b64 s[54:55], s[24:25], 1
	s_add_u32 s24, s17, s54
	s_addc_u32 s25, s19, s55
	v_mov_b32_e32 v151, v145
	v_mov_b32_e32 v150, v146
	global_load_dwordx4 v[152:155], v151, s[24:25]
	v_add_u32_e32 v212, 0x1000, v151
	global_load_dwordx4 v[172:175], v212, s[24:25]
	v_add_u32_e32 v213, 0x10000, v151
	global_load_dwordx4 v[176:179], v213, s[24:25]
	v_add_u32_e32 v218, 0x11000, v151
	global_load_dwordx4 v[180:183], v218, s[24:25]
	v_add_u32_e32 v219, 0x20000, v151
	global_load_dwordx4 v[184:187], v219, s[24:25]
	v_add_u32_e32 v212, 0x21000, v151
	global_load_dwordx4 v[188:191], v212, s[24:25]
	v_add_u32_e32 v213, 0x30000, v151
	global_load_dwordx4 v[192:195], v213, s[24:25]
	v_add_u32_e32 v218, 0x31000, v151
	global_load_dwordx4 v[196:199], v218, s[24:25]
	v_add_u32_e32 v219, 0x80000, v151
	global_load_dwordx4 v[200:203], v219, s[24:25]
	v_add_u32_e32 v212, 0x81000, v151
	global_load_dwordx4 v[204:207], v212, s[24:25]
	v_add_u32_e32 v213, 0x90000, v151
	global_load_dwordx4 v[208:211], v213, s[24:25]
	v_add_u32_e32 v218, 0x91000, v151
	global_load_dwordx4 v[220:223], v218, s[24:25]
	v_add_u32_e32 v219, 0xa0000, v151
	global_load_dwordx4 v[224:227], v219, s[24:25]
	v_add_u32_e32 v212, 0xa1000, v151
	global_load_dwordx4 v[228:231], v212, s[24:25]
	v_add_u32_e32 v213, 0xb0000, v151
	global_load_dwordx4 v[232:235], v213, s[24:25]
	v_add_u32_e32 v218, 0xb1000, v151
	global_load_dwordx4 v[236:239], v218, s[24:25]
	v_cndmask_b32_e64 v158, v125, v117, s[6:7]
	s_nop 0
	v_cndmask_b32_e64 v167, v120, v112, s[6:7]
	s_nop 0
	v_cndmask_b32_e64 v156, v127, v119, s[6:7]
	s_nop 0
	v_cndmask_b32_e64 v166, v121, v113, s[6:7]
	s_nop 0
	v_mov_b32_dpp v161, v158 quad_perm:[1,0,3,2] row_mask:0xf bank_mask:0xf
	v_mov_b32_dpp v168, v167 quad_perm:[1,0,3,2] row_mask:0xf bank_mask:0xf
	v_mov_b32_dpp v163, v156 quad_perm:[1,0,3,2] row_mask:0xf bank_mask:0xf
	v_mov_b32_dpp v169, v166 quad_perm:[1,0,3,2] row_mask:0xf bank_mask:0xf
	v_cndmask_b32_e64 v125, v161, v125, s[6:7]
	v_cndmask_b32_e64 v120, v168, v120, s[6:7]
	v_cndmask_b32_e64 v127, v163, v127, s[6:7]
	v_cndmask_b32_e64 v121, v169, v121, s[6:7]
	v_mul_f32_e32 v125, 0xbfb8aa3b, v125
	v_mul_f32_e32 v120, 0xbfb8aa3b, v120
	v_mul_f32_e32 v127, 0xbfb8aa3b, v127
	v_mul_f32_e32 v121, 0xbfb8aa3b, v121
	v_exp_f32_e32 v125, v125
	v_exp_f32_e32 v120, v120
	v_cndmask_b32_e64 v165, v122, v114, s[6:7]
	s_nop 0
	v_exp_f32_e32 v127, v127
	v_exp_f32_e32 v121, v121
	v_cndmask_b32_e64 v159, v124, v116, s[6:7]
	s_nop 0
	v_cndmask_b32_e64 v164, v123, v115, s[6:7]
	s_nop 0
	v_mov_b32_dpp v170, v165 quad_perm:[1,0,3,2] row_mask:0xf bank_mask:0xf
	v_cndmask_b32_e64 v157, v126, v118, s[6:7]
	s_nop 0
	v_mov_b32_dpp v160, v159 quad_perm:[1,0,3,2] row_mask:0xf bank_mask:0xf
	v_mov_b32_dpp v171, v164 quad_perm:[1,0,3,2] row_mask:0xf bank_mask:0xf
	v_cndmask_b32_e64 v122, v170, v122, s[6:7]
	v_mov_b32_dpp v162, v157 quad_perm:[1,0,3,2] row_mask:0xf bank_mask:0xf
	v_cndmask_b32_e64 v124, v160, v124, s[6:7]
	v_cndmask_b32_e64 v123, v171, v123, s[6:7]
	v_mul_f32_e32 v122, 0xbfb8aa3b, v122
	v_add_f32_e32 v125, 1.0, v125
	v_add_f32_e32 v120, 1.0, v120
	v_cndmask_b32_e64 v126, v162, v126, s[6:7]
	v_mul_f32_e32 v124, 0xbfb8aa3b, v124
	v_mul_f32_e32 v123, 0xbfb8aa3b, v123
	v_exp_f32_e32 v122, v122
	v_add_f32_e32 v127, 1.0, v127
	v_add_f32_e32 v121, 1.0, v121
	v_rcp_f32_e32 v125, v125
	v_rcp_f32_e32 v120, v120
	v_mul_f32_e32 v126, 0xbfb8aa3b, v126
	v_exp_f32_e32 v124, v124
	v_exp_f32_e32 v123, v123
	v_rcp_f32_e32 v127, v127
	v_rcp_f32_e32 v121, v121
	v_exp_f32_e32 v126, v126
	v_add_f32_e32 v124, 1.0, v124
	s_lshl_b64 s[26:27], s[26:27], 21
	v_rcp_f32_e32 v124, v124
	v_add_f32_e32 v126, 1.0, v126
	s_add_u32 s17, s59, s26
	v_rcp_f32_e32 v126, v126
	s_addc_u32 s19, s60, s27
	s_add_u32 s26, s17, s54
	s_addc_u32 s27, s19, s55
	v_cndmask_b32_e64 v115, v115, v171, s[6:7]
	v_cndmask_b32_e64 v119, v119, v163, s[6:7]
	v_cndmask_b32_e64 v118, v118, v162, s[6:7]
	v_cndmask_b32_e64 v117, v117, v161, s[6:7]
	v_cndmask_b32_e64 v116, v116, v160, s[6:7]
	v_cndmask_b32_e64 v114, v114, v170, s[6:7]
	v_cndmask_b32_e64 v113, v113, v169, s[6:7]
	v_cndmask_b32_e64 v112, v112, v168, s[6:7]
	v_mul_f32_e32 v115, 0xbfb8aa3b, v115
	v_mul_f32_e32 v116, 0xbfb8aa3b, v116
	v_mul_f32_e32 v117, 0xbfb8aa3b, v117
	v_mul_f32_e32 v118, 0xbfb8aa3b, v118
	v_mul_f32_e32 v119, 0xbfb8aa3b, v119
	v_mul_f32_e32 v112, 0xbfb8aa3b, v112
	s_waitcnt vmcnt(15)
	v_lshlrev_b32_e32 v156, 16, v152
	v_and_b32_e32 v152, 0xffff0000, v152
	v_lshlrev_b32_e32 v158, 16, v154
	v_lshlrev_b32_e32 v157, 16, v153
	v_and_b32_e32 v153, 0xffff0000, v153
	v_and_b32_e32 v154, 0xffff0000, v154
	v_mul_f32_e32 v125, v125, v152
	v_mul_f32_e32 v152, v120, v158
	v_add_f32_e32 v120, 1.0, v122
	v_mul_f32_e32 v127, v127, v153
	v_mul_f32_e32 v153, v121, v154
	v_rcp_f32_e32 v120, v120
	v_add_f32_e32 v121, 1.0, v123
	v_rcp_f32_e32 v121, v121
	v_lshlrev_b32_e32 v122, 16, v155
	v_mul_f32_e32 v123, v120, v122
	v_and_b32_e32 v120, 0xffff0000, v155
	v_mul_f32_e32 v124, v124, v156
	v_mul_f32_e32 v154, v121, v120
	v_cvt_pk_bf16_f32 v120, v124, v125
	v_mul_f32_e32 v126, v126, v157
	v_cvt_pk_bf16_f32 v121, v126, v127
	v_cvt_pk_bf16_f32 v122, v152, v153
	v_cvt_pk_bf16_f32 v123, v123, v154
	global_store_dwordx4 v150, v[120:123], s[26:27]
	v_mul_f32_e32 v113, 0xbfb8aa3b, v113
	v_mul_f32_e32 v114, 0xbfb8aa3b, v114
	v_add_u32_e32 v120, 0x1000, v151
	s_waitcnt vmcnt(15)
; __device__ __forceinline__ float dpp_x1(float x) { return __builtin_bit_cast(float, __builtin_amdgcn_update_dpp(0, __builtin_bit_cast(int, x), 0xB1, 0xF, 0xF, false)); }
; __device__ __forceinline__ f32x4 dpp_swap1(f32x4 v) { f32x4 r; r[0] = dpp_x1(v[0]); r[1] = dpp_x1(v[1]); r[2] = dpp_x1(v[2]); r[3] = dpp_x1(v[3]); return r; }
;     __device__ __forceinline__ void operator()(const f32x4 (&acc)[2][2][4][2], const Unit& u, int wr, int wc, int fr, int fq, const EpiCtx& X) const {
;     ...
;         EPI_PIECES({ const unsigned goff = glo + (unsigned)(rl * W_SSM) * 2u, coff = clo + (unsigned)(rl * DM) * 2u;
;             GLU_ONE(p1a, p1b, goff, coff); GLU_ONE(p2a, p2b, goff + W_SSM * 2, coff + DM * 2); })
	s_nop 1
	v_mov_b32_e32 v120, v172
	v_mov_b32_e32 v121, v173
	v_mov_b32_e32 v122, v174
	v_mov_b32_e32 v123, v175
	v_exp_f32_e32 v115, v115
	v_exp_f32_e32 v116, v116
	v_exp_f32_e32 v117, v117
	v_exp_f32_e32 v118, v118
	v_exp_f32_e32 v119, v119
	v_exp_f32_e32 v112, v112
	v_exp_f32_e32 v113, v113
	v_exp_f32_e32 v114, v114
	v_add_f32_e32 v115, 1.0, v115
	v_add_f32_e32 v116, 1.0, v116
	v_add_f32_e32 v117, 1.0, v117
	v_add_f32_e32 v118, 1.0, v118
	v_add_f32_e32 v119, 1.0, v119
	v_add_f32_e32 v112, 1.0, v112
	v_add_f32_e32 v113, 1.0, v113
	v_add_f32_e32 v114, 1.0, v114
	v_rcp_f32_e32 v115, v115
	v_rcp_f32_e32 v116, v116
	v_rcp_f32_e32 v117, v117
	v_rcp_f32_e32 v118, v118
	v_rcp_f32_e32 v119, v119
	v_rcp_f32_e32 v112, v112
	v_rcp_f32_e32 v113, v113
	v_rcp_f32_e32 v114, v114
	v_add_u32_e32 v124, 0x2000, v150
	v_add_u32_e32 v125, 0x10000, v151
	v_mov_b32_e32 v155, 0
	v_mov_b32_e32 v154, 0
	s_andn2_b64 vcc, exec, s[8:9]
	s_mov_b64 s[8:9], -1
	v_lshlrev_b32_e32 v153, 16, v123
	v_and_b32_e32 v123, 0xffff0000, v123
	v_lshlrev_b32_e32 v126, 16, v120
	v_and_b32_e32 v120, 0xffff0000, v120
	v_lshlrev_b32_e32 v127, 16, v121
	v_and_b32_e32 v121, 0xffff0000, v121
	v_lshlrev_b32_e32 v152, 16, v122
	v_and_b32_e32 v122, 0xffff0000, v122
	v_mul_f32_e32 v115, v115, v123
	v_mul_f32_e32 v116, v116, v126
	v_mul_f32_e32 v117, v117, v120
	v_mul_f32_e32 v118, v118, v127
	v_mul_f32_e32 v119, v119, v121
	v_mul_f32_e32 v120, v112, v152
	v_mul_f32_e32 v121, v113, v122
	v_mul_f32_e32 v122, v114, v153
	v_cvt_pk_bf16_f32 v112, v116, v117
	v_cvt_pk_bf16_f32 v113, v118, v119
	v_cvt_pk_bf16_f32 v114, v120, v121
	v_cvt_pk_bf16_f32 v115, v122, v115
	global_store_dwordx4 v124, v[112:115], s[26:27]
	s_waitcnt vmcnt(15)
	s_nop 1
	v_mov_b32_e32 v112, v176
	v_mov_b32_e32 v113, v177
	v_mov_b32_e32 v114, v178
	v_mov_b32_e32 v115, v179
	v_cndmask_b32_e64 v124, v107, v99, s[6:7]
	v_cndmask_b32_e64 v116, v111, v103, s[6:7]
	v_cndmask_b32_e64 v117, v110, v102, s[6:7]
	v_cndmask_b32_e64 v118, v109, v101, s[6:7]
	v_cndmask_b32_e64 v119, v108, v100, s[6:7]
	s_nop 0
	s_nop 0
	s_nop 0
	s_nop 0
	v_cndmask_b32_e64 v125, v106, v98, s[6:7]
	v_cndmask_b32_e64 v126, v105, v97, s[6:7]
	v_cndmask_b32_e64 v127, v104, v96, s[6:7]
	s_nop 0
	s_nop 0
	v_mov_b32_dpp v155, v124 quad_perm:[1,0,3,2] row_mask:0xf bank_mask:0xf
	v_mov_b32_dpp v120, v119 quad_perm:[1,0,3,2] row_mask:0xf bank_mask:0xf
	v_mov_b32_dpp v121, v118 quad_perm:[1,0,3,2] row_mask:0xf bank_mask:0xf
	v_mov_b32_dpp v122, v117 quad_perm:[1,0,3,2] row_mask:0xf bank_mask:0xf
	v_mov_b32_dpp v123, v116 quad_perm:[1,0,3,2] row_mask:0xf bank_mask:0xf
	v_mov_b32_dpp v152, v127 quad_perm:[1,0,3,2] row_mask:0xf bank_mask:0xf
	v_mov_b32_dpp v153, v126 quad_perm:[1,0,3,2] row_mask:0xf bank_mask:0xf
	v_mov_b32_dpp v154, v125 quad_perm:[1,0,3,2] row_mask:0xf bank_mask:0xf
	v_cndmask_b32_e64 v107, v155, v107, s[6:7]
	v_cndmask_b32_e64 v111, v123, v111, s[6:7]
	v_cndmask_b32_e64 v110, v122, v110, s[6:7]
	v_cndmask_b32_e64 v109, v121, v109, s[6:7]
	v_cndmask_b32_e64 v108, v120, v108, s[6:7]
	v_cndmask_b32_e64 v106, v154, v106, s[6:7]
	v_cndmask_b32_e64 v105, v153, v105, s[6:7]
	v_cndmask_b32_e64 v104, v152, v104, s[6:7]
	v_mul_f32_e32 v107, 0xbfb8aa3b, v107
	v_mul_f32_e32 v108, 0xbfb8aa3b, v108
	v_mul_f32_e32 v109, 0xbfb8aa3b, v109
	v_mul_f32_e32 v110, 0xbfb8aa3b, v110
	v_mul_f32_e32 v111, 0xbfb8aa3b, v111
	v_mul_f32_e32 v104, 0xbfb8aa3b, v104
	v_mul_f32_e32 v105, 0xbfb8aa3b, v105
	v_mul_f32_e32 v106, 0xbfb8aa3b, v106
	v_exp_f32_e32 v107, v107
	v_exp_f32_e32 v108, v108
	v_exp_f32_e32 v109, v109
	v_exp_f32_e32 v110, v110
	v_exp_f32_e32 v111, v111
	v_exp_f32_e32 v104, v104
	v_exp_f32_e32 v105, v105
	v_exp_f32_e32 v106, v106
	v_add_f32_e32 v107, 1.0, v107
	v_add_f32_e32 v108, 1.0, v108
	v_add_f32_e32 v109, 1.0, v109
	v_add_f32_e32 v110, 1.0, v110
	v_add_f32_e32 v111, 1.0, v111
	v_add_f32_e32 v104, 1.0, v104
	v_add_f32_e32 v105, 1.0, v105
	v_add_f32_e32 v106, 1.0, v106
	v_rcp_f32_e32 v107, v107
	v_rcp_f32_e32 v108, v108
	v_rcp_f32_e32 v109, v109
	v_rcp_f32_e32 v110, v110
	v_rcp_f32_e32 v111, v111
	v_rcp_f32_e32 v104, v104
	v_rcp_f32_e32 v105, v105
	v_rcp_f32_e32 v106, v106
	v_add_u32_e32 v116, 0x20000, v150
	v_add_u32_e32 v117, 0x11000, v151
	v_cndmask_b32_e64 v99, v99, v155, s[6:7]
	v_cndmask_b32_e64 v103, v103, v123, s[6:7]
	v_cndmask_b32_e64 v102, v102, v122, s[6:7]
	v_cndmask_b32_e64 v101, v101, v121, s[6:7]
	v_cndmask_b32_e64 v100, v100, v120, s[6:7]
	v_cndmask_b32_e64 v98, v98, v154, s[6:7]
	v_cndmask_b32_e64 v97, v97, v153, s[6:7]
	v_cndmask_b32_e64 v96, v96, v152, s[6:7]
	v_mul_f32_e32 v99, 0xbfb8aa3b, v99
	v_mul_f32_e32 v100, 0xbfb8aa3b, v100
	v_mul_f32_e32 v101, 0xbfb8aa3b, v101
	v_mul_f32_e32 v102, 0xbfb8aa3b, v102
	v_mul_f32_e32 v103, 0xbfb8aa3b, v103
	v_mul_f32_e32 v96, 0xbfb8aa3b, v96
	v_mul_f32_e32 v97, 0xbfb8aa3b, v97
	v_lshlrev_b32_e32 v125, 16, v115
	v_and_b32_e32 v115, 0xffff0000, v115
	v_lshlrev_b32_e32 v118, 16, v112
	v_and_b32_e32 v112, 0xffff0000, v112
	v_lshlrev_b32_e32 v119, 16, v113
	v_and_b32_e32 v113, 0xffff0000, v113
	v_lshlrev_b32_e32 v124, 16, v114
	v_and_b32_e32 v114, 0xffff0000, v114
	v_mul_f32_e32 v107, v107, v115
	v_mul_f32_e32 v108, v108, v118
	v_mul_f32_e32 v109, v109, v112
	v_mul_f32_e32 v110, v110, v119
	v_mul_f32_e32 v111, v111, v113
	v_mul_f32_e32 v112, v104, v124
	v_mul_f32_e32 v113, v105, v114
	v_mul_f32_e32 v114, v106, v125
	v_cvt_pk_bf16_f32 v104, v108, v109
	v_cvt_pk_bf16_f32 v105, v110, v111
	v_cvt_pk_bf16_f32 v106, v112, v113
	v_cvt_pk_bf16_f32 v107, v114, v107
	global_store_dwordx4 v116, v[104:107], s[26:27]
	s_waitcnt vmcnt(15)
; __device__ __forceinline__ float dpp_x1(float x) { return __builtin_bit_cast(float, __builtin_amdgcn_update_dpp(0, __builtin_bit_cast(int, x), 0xB1, 0xF, 0xF, false)); }
; __device__ __forceinline__ f32x4 dpp_swap1(f32x4 v) { f32x4 r; r[0] = dpp_x1(v[0]); r[1] = dpp_x1(v[1]); r[2] = dpp_x1(v[2]); r[3] = dpp_x1(v[3]); return r; }
;     __device__ __forceinline__ void operator()(const f32x4 (&acc)[2][2][4][2], const Unit& u, int wr, int wc, int fr, int fq, const EpiCtx& X) const {
;     ...
;         EPI_PIECES({ const unsigned goff = glo + (unsigned)(rl * W_SSM) * 2u, coff = clo + (unsigned)(rl * DM) * 2u;
;             GLU_ONE(p1a, p1b, goff, coff); GLU_ONE(p2a, p2b, goff + W_SSM * 2, coff + DM * 2); })
	s_nop 1
	v_mov_b32_e32 v104, v180
	v_mov_b32_e32 v105, v181
	v_mov_b32_e32 v106, v182
	v_mov_b32_e32 v107, v183
	v_mul_f32_e32 v98, 0xbfb8aa3b, v98
	v_exp_f32_e32 v99, v99
	v_exp_f32_e32 v100, v100
	v_exp_f32_e32 v101, v101
	v_exp_f32_e32 v102, v102
	v_exp_f32_e32 v103, v103
	v_exp_f32_e32 v96, v96
	v_exp_f32_e32 v97, v97
	v_exp_f32_e32 v98, v98
	v_add_f32_e32 v99, 1.0, v99
	v_add_f32_e32 v100, 1.0, v100
	v_add_f32_e32 v101, 1.0, v101
	v_add_f32_e32 v102, 1.0, v102
	v_add_f32_e32 v103, 1.0, v103
	v_add_f32_e32 v96, 1.0, v96
	v_add_f32_e32 v97, 1.0, v97
	v_add_f32_e32 v98, 1.0, v98
	v_rcp_f32_e32 v99, v99
	v_rcp_f32_e32 v100, v100
	v_rcp_f32_e32 v101, v101
	v_rcp_f32_e32 v102, v102
	v_rcp_f32_e32 v103, v103
	v_rcp_f32_e32 v96, v96
	v_rcp_f32_e32 v97, v97
	v_rcp_f32_e32 v98, v98
	v_add_u32_e32 v108, 0x22000, v150
	v_add_u32_e32 v109, 0x20000, v151
	v_mov_b32_e32 v115, 0
	v_mov_b32_e32 v114, 0
	v_lshlrev_b32_e32 v113, 16, v107
	v_and_b32_e32 v107, 0xffff0000, v107
	v_lshlrev_b32_e32 v110, 16, v104
	v_and_b32_e32 v104, 0xffff0000, v104
	v_lshlrev_b32_e32 v111, 16, v105
	v_and_b32_e32 v105, 0xffff0000, v105
	v_lshlrev_b32_e32 v112, 16, v106
	v_and_b32_e32 v106, 0xffff0000, v106
	v_mul_f32_e32 v99, v99, v107
	v_mul_f32_e32 v100, v100, v110
	v_mul_f32_e32 v101, v101, v104
	v_mul_f32_e32 v102, v102, v111
	v_mul_f32_e32 v103, v103, v105
	v_mul_f32_e32 v104, v96, v112
	v_mul_f32_e32 v105, v97, v106
	v_mul_f32_e32 v106, v98, v113
	v_cvt_pk_bf16_f32 v96, v100, v101
	v_cvt_pk_bf16_f32 v97, v102, v103
	v_cvt_pk_bf16_f32 v98, v104, v105
	v_cvt_pk_bf16_f32 v99, v106, v99
	global_store_dwordx4 v108, v[96:99], s[26:27]
	s_waitcnt vmcnt(15)
	s_nop 1
	v_mov_b32_e32 v96, v184
	v_mov_b32_e32 v97, v185
	v_mov_b32_e32 v98, v186
	v_mov_b32_e32 v99, v187
	v_cndmask_b32_e64 v108, v91, v83, s[6:7]
	v_cndmask_b32_e64 v100, v95, v87, s[6:7]
	v_cndmask_b32_e64 v101, v94, v86, s[6:7]
	v_cndmask_b32_e64 v102, v93, v85, s[6:7]
	v_cndmask_b32_e64 v103, v92, v84, s[6:7]
	s_nop 0
	s_nop 0
	s_nop 0
	s_nop 0
	v_cndmask_b32_e64 v109, v90, v82, s[6:7]
	v_cndmask_b32_e64 v110, v89, v81, s[6:7]
	v_cndmask_b32_e64 v111, v88, v80, s[6:7]
	s_nop 0
	s_nop 0
	v_mov_b32_dpp v115, v108 quad_perm:[1,0,3,2] row_mask:0xf bank_mask:0xf
	v_mov_b32_dpp v104, v103 quad_perm:[1,0,3,2] row_mask:0xf bank_mask:0xf
	v_mov_b32_dpp v105, v102 quad_perm:[1,0,3,2] row_mask:0xf bank_mask:0xf
	v_mov_b32_dpp v106, v101 quad_perm:[1,0,3,2] row_mask:0xf bank_mask:0xf
	v_mov_b32_dpp v107, v100 quad_perm:[1,0,3,2] row_mask:0xf bank_mask:0xf
	v_mov_b32_dpp v112, v111 quad_perm:[1,0,3,2] row_mask:0xf bank_mask:0xf
	v_mov_b32_dpp v113, v110 quad_perm:[1,0,3,2] row_mask:0xf bank_mask:0xf
	v_mov_b32_dpp v114, v109 quad_perm:[1,0,3,2] row_mask:0xf bank_mask:0xf
	v_cndmask_b32_e64 v91, v115, v91, s[6:7]
	v_cndmask_b32_e64 v95, v107, v95, s[6:7]
	v_cndmask_b32_e64 v94, v106, v94, s[6:7]
	v_cndmask_b32_e64 v93, v105, v93, s[6:7]
	v_cndmask_b32_e64 v92, v104, v92, s[6:7]
	v_cndmask_b32_e64 v90, v114, v90, s[6:7]
	v_cndmask_b32_e64 v89, v113, v89, s[6:7]
	v_cndmask_b32_e64 v88, v112, v88, s[6:7]
	v_mul_f32_e32 v91, 0xbfb8aa3b, v91
	v_mul_f32_e32 v92, 0xbfb8aa3b, v92
	v_mul_f32_e32 v93, 0xbfb8aa3b, v93
	v_mul_f32_e32 v94, 0xbfb8aa3b, v94
	v_mul_f32_e32 v95, 0xbfb8aa3b, v95
	v_mul_f32_e32 v88, 0xbfb8aa3b, v88
	v_mul_f32_e32 v89, 0xbfb8aa3b, v89
	v_mul_f32_e32 v90, 0xbfb8aa3b, v90
	v_exp_f32_e32 v91, v91
	v_exp_f32_e32 v92, v92
	v_exp_f32_e32 v93, v93
	v_exp_f32_e32 v94, v94
	v_exp_f32_e32 v95, v95
	v_exp_f32_e32 v88, v88
	v_exp_f32_e32 v89, v89
	v_exp_f32_e32 v90, v90
	v_add_f32_e32 v91, 1.0, v91
	v_add_f32_e32 v92, 1.0, v92
	v_add_f32_e32 v93, 1.0, v93
	v_add_f32_e32 v94, 1.0, v94
	v_add_f32_e32 v95, 1.0, v95
	v_add_f32_e32 v88, 1.0, v88
	v_add_f32_e32 v89, 1.0, v89
	v_add_f32_e32 v90, 1.0, v90
	v_rcp_f32_e32 v91, v91
	v_rcp_f32_e32 v92, v92
	v_rcp_f32_e32 v93, v93
	v_rcp_f32_e32 v94, v94
	v_rcp_f32_e32 v95, v95
	v_rcp_f32_e32 v88, v88
	v_rcp_f32_e32 v89, v89
	v_rcp_f32_e32 v90, v90
	v_add_u32_e32 v100, 0x40000, v150
	v_add_u32_e32 v101, 0x21000, v151
	v_cndmask_b32_e64 v83, v83, v115, s[6:7]
	v_cndmask_b32_e64 v87, v87, v107, s[6:7]
	v_cndmask_b32_e64 v86, v86, v106, s[6:7]
	v_cndmask_b32_e64 v85, v85, v105, s[6:7]
	v_cndmask_b32_e64 v84, v84, v104, s[6:7]
	v_cndmask_b32_e64 v82, v82, v114, s[6:7]
	v_cndmask_b32_e64 v81, v81, v113, s[6:7]
	v_cndmask_b32_e64 v80, v80, v112, s[6:7]
	v_mul_f32_e32 v83, 0xbfb8aa3b, v83
	v_mul_f32_e32 v84, 0xbfb8aa3b, v84
	v_mul_f32_e32 v85, 0xbfb8aa3b, v85
	v_mul_f32_e32 v86, 0xbfb8aa3b, v86
	v_mul_f32_e32 v87, 0xbfb8aa3b, v87
	v_mul_f32_e32 v80, 0xbfb8aa3b, v80
	v_mul_f32_e32 v81, 0xbfb8aa3b, v81
	v_lshlrev_b32_e32 v109, 16, v99
	v_and_b32_e32 v99, 0xffff0000, v99
	v_lshlrev_b32_e32 v102, 16, v96
	v_and_b32_e32 v96, 0xffff0000, v96
	v_lshlrev_b32_e32 v103, 16, v97
	v_and_b32_e32 v97, 0xffff0000, v97
	v_lshlrev_b32_e32 v108, 16, v98
	v_and_b32_e32 v98, 0xffff0000, v98
	v_mul_f32_e32 v91, v91, v99
	v_mul_f32_e32 v92, v92, v102
	v_mul_f32_e32 v93, v93, v96
	v_mul_f32_e32 v94, v94, v103
	v_mul_f32_e32 v95, v95, v97
	v_mul_f32_e32 v96, v88, v108
	v_mul_f32_e32 v97, v89, v98
	v_mul_f32_e32 v98, v90, v109
	v_cvt_pk_bf16_f32 v88, v92, v93
	v_cvt_pk_bf16_f32 v89, v94, v95
	v_cvt_pk_bf16_f32 v90, v96, v97
	v_cvt_pk_bf16_f32 v91, v98, v91
	global_store_dwordx4 v100, v[88:91], s[26:27]
	s_waitcnt vmcnt(15)
; __device__ __forceinline__ float dpp_x1(float x) { return __builtin_bit_cast(float, __builtin_amdgcn_update_dpp(0, __builtin_bit_cast(int, x), 0xB1, 0xF, 0xF, false)); }
; __device__ __forceinline__ f32x4 dpp_swap1(f32x4 v) { f32x4 r; r[0] = dpp_x1(v[0]); r[1] = dpp_x1(v[1]); r[2] = dpp_x1(v[2]); r[3] = dpp_x1(v[3]); return r; }
;     __device__ __forceinline__ void operator()(const f32x4 (&acc)[2][2][4][2], const Unit& u, int wr, int wc, int fr, int fq, const EpiCtx& X) const {
;     ...
;         EPI_PIECES({ const unsigned goff = glo + (unsigned)(rl * W_SSM) * 2u, coff = clo + (unsigned)(rl * DM) * 2u;
;             GLU_ONE(p1a, p1b, goff, coff); GLU_ONE(p2a, p2b, goff + W_SSM * 2, coff + DM * 2); })
	s_nop 1
	v_mov_b32_e32 v88, v188
	v_mov_b32_e32 v89, v189
	v_mov_b32_e32 v90, v190
	v_mov_b32_e32 v91, v191
	v_mul_f32_e32 v82, 0xbfb8aa3b, v82
	v_exp_f32_e32 v83, v83
	v_exp_f32_e32 v84, v84
	v_exp_f32_e32 v85, v85
	v_exp_f32_e32 v86, v86
	v_exp_f32_e32 v87, v87
	v_exp_f32_e32 v80, v80
	v_exp_f32_e32 v81, v81
	v_exp_f32_e32 v82, v82
	v_add_f32_e32 v83, 1.0, v83
	v_add_f32_e32 v84, 1.0, v84
	v_add_f32_e32 v85, 1.0, v85
	v_add_f32_e32 v86, 1.0, v86
	v_add_f32_e32 v87, 1.0, v87
	v_add_f32_e32 v80, 1.0, v80
	v_add_f32_e32 v81, 1.0, v81
	v_add_f32_e32 v82, 1.0, v82
	v_rcp_f32_e32 v83, v83
	v_rcp_f32_e32 v84, v84
	v_rcp_f32_e32 v85, v85
	v_rcp_f32_e32 v86, v86
	v_rcp_f32_e32 v87, v87
	v_rcp_f32_e32 v80, v80
	v_rcp_f32_e32 v81, v81
	v_rcp_f32_e32 v82, v82
	v_add_u32_e32 v92, 0x42000, v150
	v_add_u32_e32 v93, 0x30000, v151
	v_mov_b32_e32 v99, 0
	v_mov_b32_e32 v98, 0
	v_lshlrev_b32_e32 v97, 16, v91
	v_and_b32_e32 v91, 0xffff0000, v91
	v_lshlrev_b32_e32 v94, 16, v88
	v_and_b32_e32 v88, 0xffff0000, v88
	v_lshlrev_b32_e32 v95, 16, v89
	v_and_b32_e32 v89, 0xffff0000, v89
	v_lshlrev_b32_e32 v96, 16, v90
	v_and_b32_e32 v90, 0xffff0000, v90
	v_mul_f32_e32 v83, v83, v91
	v_mul_f32_e32 v84, v84, v94
	v_mul_f32_e32 v85, v85, v88
	v_mul_f32_e32 v86, v86, v95
	v_mul_f32_e32 v87, v87, v89
	v_mul_f32_e32 v88, v80, v96
	v_mul_f32_e32 v89, v81, v90
	v_mul_f32_e32 v90, v82, v97
	v_cvt_pk_bf16_f32 v80, v84, v85
	v_cvt_pk_bf16_f32 v81, v86, v87
	v_cvt_pk_bf16_f32 v82, v88, v89
	v_cvt_pk_bf16_f32 v83, v90, v83
	global_store_dwordx4 v92, v[80:83], s[26:27]
	s_waitcnt vmcnt(15)
	s_nop 1
	v_mov_b32_e32 v80, v192
	v_mov_b32_e32 v81, v193
	v_mov_b32_e32 v82, v194
	v_mov_b32_e32 v83, v195
	v_cndmask_b32_e64 v92, v75, v67, s[6:7]
	v_cndmask_b32_e64 v84, v79, v71, s[6:7]
	v_cndmask_b32_e64 v85, v78, v70, s[6:7]
	v_cndmask_b32_e64 v86, v77, v69, s[6:7]
	v_cndmask_b32_e64 v87, v76, v68, s[6:7]
	s_nop 0
	s_nop 0
	s_nop 0
	s_nop 0
	v_cndmask_b32_e64 v93, v74, v66, s[6:7]
	v_cndmask_b32_e64 v94, v73, v65, s[6:7]
	v_cndmask_b32_e64 v95, v72, v64, s[6:7]
	s_nop 0
	s_nop 0
	v_mov_b32_dpp v99, v92 quad_perm:[1,0,3,2] row_mask:0xf bank_mask:0xf
	v_mov_b32_dpp v88, v87 quad_perm:[1,0,3,2] row_mask:0xf bank_mask:0xf
	v_mov_b32_dpp v89, v86 quad_perm:[1,0,3,2] row_mask:0xf bank_mask:0xf
	v_mov_b32_dpp v90, v85 quad_perm:[1,0,3,2] row_mask:0xf bank_mask:0xf
	v_mov_b32_dpp v91, v84 quad_perm:[1,0,3,2] row_mask:0xf bank_mask:0xf
	v_mov_b32_dpp v96, v95 quad_perm:[1,0,3,2] row_mask:0xf bank_mask:0xf
	v_mov_b32_dpp v97, v94 quad_perm:[1,0,3,2] row_mask:0xf bank_mask:0xf
	v_mov_b32_dpp v98, v93 quad_perm:[1,0,3,2] row_mask:0xf bank_mask:0xf
	v_cndmask_b32_e64 v75, v99, v75, s[6:7]
	v_cndmask_b32_e64 v79, v91, v79, s[6:7]
	v_cndmask_b32_e64 v78, v90, v78, s[6:7]
	v_cndmask_b32_e64 v77, v89, v77, s[6:7]
	v_cndmask_b32_e64 v76, v88, v76, s[6:7]
	v_cndmask_b32_e64 v74, v98, v74, s[6:7]
	v_cndmask_b32_e64 v73, v97, v73, s[6:7]
	v_cndmask_b32_e64 v72, v96, v72, s[6:7]
	v_mul_f32_e32 v75, 0xbfb8aa3b, v75
	v_mul_f32_e32 v76, 0xbfb8aa3b, v76
	v_mul_f32_e32 v77, 0xbfb8aa3b, v77
	v_mul_f32_e32 v78, 0xbfb8aa3b, v78
	v_mul_f32_e32 v79, 0xbfb8aa3b, v79
	v_mul_f32_e32 v72, 0xbfb8aa3b, v72
	v_mul_f32_e32 v73, 0xbfb8aa3b, v73
	v_mul_f32_e32 v74, 0xbfb8aa3b, v74
	v_exp_f32_e32 v75, v75
	v_exp_f32_e32 v76, v76
	v_exp_f32_e32 v77, v77
	v_exp_f32_e32 v78, v78
	v_exp_f32_e32 v79, v79
	v_exp_f32_e32 v72, v72
	v_exp_f32_e32 v73, v73
	v_exp_f32_e32 v74, v74
	v_add_f32_e32 v75, 1.0, v75
	v_add_f32_e32 v76, 1.0, v76
	v_add_f32_e32 v77, 1.0, v77
	v_add_f32_e32 v78, 1.0, v78
	v_add_f32_e32 v79, 1.0, v79
	v_add_f32_e32 v72, 1.0, v72
	v_add_f32_e32 v73, 1.0, v73
	v_add_f32_e32 v74, 1.0, v74
	v_rcp_f32_e32 v75, v75
	v_rcp_f32_e32 v76, v76
	v_rcp_f32_e32 v77, v77
	v_rcp_f32_e32 v78, v78
	v_rcp_f32_e32 v79, v79
	v_rcp_f32_e32 v72, v72
	v_rcp_f32_e32 v73, v73
	v_rcp_f32_e32 v74, v74
	v_add_u32_e32 v84, 0x60000, v150
	v_add_u32_e32 v85, 0x31000, v151
	v_cndmask_b32_e64 v67, v67, v99, s[6:7]
	v_cndmask_b32_e64 v71, v71, v91, s[6:7]
	v_cndmask_b32_e64 v70, v70, v90, s[6:7]
	v_cndmask_b32_e64 v69, v69, v89, s[6:7]
	v_cndmask_b32_e64 v68, v68, v88, s[6:7]
	v_cndmask_b32_e64 v66, v66, v98, s[6:7]
	v_cndmask_b32_e64 v65, v65, v97, s[6:7]
	v_cndmask_b32_e64 v64, v64, v96, s[6:7]
	v_mul_f32_e32 v67, 0xbfb8aa3b, v67
	v_mul_f32_e32 v68, 0xbfb8aa3b, v68
	v_mul_f32_e32 v69, 0xbfb8aa3b, v69
	v_mul_f32_e32 v70, 0xbfb8aa3b, v70
	v_mul_f32_e32 v71, 0xbfb8aa3b, v71
	v_mul_f32_e32 v64, 0xbfb8aa3b, v64
	v_mul_f32_e32 v65, 0xbfb8aa3b, v65
	v_lshlrev_b32_e32 v93, 16, v83
	v_and_b32_e32 v83, 0xffff0000, v83
	v_lshlrev_b32_e32 v86, 16, v80
	v_and_b32_e32 v80, 0xffff0000, v80
	v_lshlrev_b32_e32 v87, 16, v81
	v_and_b32_e32 v81, 0xffff0000, v81
	v_lshlrev_b32_e32 v92, 16, v82
	v_and_b32_e32 v82, 0xffff0000, v82
	v_mul_f32_e32 v75, v75, v83
	v_mul_f32_e32 v76, v76, v86
	v_mul_f32_e32 v77, v77, v80
	v_mul_f32_e32 v78, v78, v87
	v_mul_f32_e32 v79, v79, v81
	v_mul_f32_e32 v80, v72, v92
	v_mul_f32_e32 v81, v73, v82
	v_mul_f32_e32 v82, v74, v93
	v_cvt_pk_bf16_f32 v72, v76, v77
	v_cvt_pk_bf16_f32 v73, v78, v79
	v_cvt_pk_bf16_f32 v74, v80, v81
	v_cvt_pk_bf16_f32 v75, v82, v75
	global_store_dwordx4 v84, v[72:75], s[26:27]
	s_waitcnt vmcnt(15)
; __device__ __forceinline__ float dpp_x1(float x) { return __builtin_bit_cast(float, __builtin_amdgcn_update_dpp(0, __builtin_bit_cast(int, x), 0xB1, 0xF, 0xF, false)); }
; __device__ __forceinline__ f32x4 dpp_swap1(f32x4 v) { f32x4 r; r[0] = dpp_x1(v[0]); r[1] = dpp_x1(v[1]); r[2] = dpp_x1(v[2]); r[3] = dpp_x1(v[3]); return r; }
;     __device__ __forceinline__ void operator()(const f32x4 (&acc)[2][2][4][2], const Unit& u, int wr, int wc, int fr, int fq, const EpiCtx& X) const {
;     ...
;         EPI_PIECES({ const unsigned goff = glo + (unsigned)(rl * W_SSM) * 2u, coff = clo + (unsigned)(rl * DM) * 2u;
;             GLU_ONE(p1a, p1b, goff, coff); GLU_ONE(p2a, p2b, goff + W_SSM * 2, coff + DM * 2); })
	s_nop 1
	v_mov_b32_e32 v72, v196
	v_mov_b32_e32 v73, v197
	v_mov_b32_e32 v74, v198
	v_mov_b32_e32 v75, v199
	v_mul_f32_e32 v66, 0xbfb8aa3b, v66
	v_exp_f32_e32 v67, v67
	v_exp_f32_e32 v68, v68
	v_exp_f32_e32 v69, v69
	v_exp_f32_e32 v70, v70
	v_exp_f32_e32 v71, v71
	v_exp_f32_e32 v64, v64
	v_exp_f32_e32 v65, v65
	v_exp_f32_e32 v66, v66
	v_add_f32_e32 v67, 1.0, v67
	v_add_f32_e32 v68, 1.0, v68
	v_add_f32_e32 v69, 1.0, v69
	v_add_f32_e32 v70, 1.0, v70
	v_add_f32_e32 v71, 1.0, v71
	v_add_f32_e32 v64, 1.0, v64
	v_add_f32_e32 v65, 1.0, v65
	v_add_f32_e32 v66, 1.0, v66
	v_rcp_f32_e32 v67, v67
	v_rcp_f32_e32 v68, v68
	v_rcp_f32_e32 v69, v69
	v_rcp_f32_e32 v70, v70
	v_rcp_f32_e32 v71, v71
	v_rcp_f32_e32 v64, v64
	v_rcp_f32_e32 v65, v65
	v_rcp_f32_e32 v66, v66
	v_add_u32_e32 v76, 0x62000, v150
	v_add_u32_e32 v77, 0x80000, v151
	v_mov_b32_e32 v83, 0
	v_mov_b32_e32 v82, 0
	v_lshlrev_b32_e32 v81, 16, v75
	v_and_b32_e32 v75, 0xffff0000, v75
	v_lshlrev_b32_e32 v78, 16, v72
	v_and_b32_e32 v72, 0xffff0000, v72
	v_lshlrev_b32_e32 v79, 16, v73
	v_and_b32_e32 v73, 0xffff0000, v73
	v_lshlrev_b32_e32 v80, 16, v74
	v_and_b32_e32 v74, 0xffff0000, v74
	v_mul_f32_e32 v67, v67, v75
	v_mul_f32_e32 v68, v68, v78
	v_mul_f32_e32 v69, v69, v72
	v_mul_f32_e32 v70, v70, v79
	v_mul_f32_e32 v71, v71, v73
	v_mul_f32_e32 v72, v64, v80
	v_mul_f32_e32 v73, v65, v74
	v_mul_f32_e32 v74, v66, v81
	v_cvt_pk_bf16_f32 v64, v68, v69
	v_cvt_pk_bf16_f32 v65, v70, v71
	v_cvt_pk_bf16_f32 v66, v72, v73
	v_cvt_pk_bf16_f32 v67, v74, v67
	global_store_dwordx4 v76, v[64:67], s[26:27]
	s_waitcnt vmcnt(15)
	s_nop 1
	v_mov_b32_e32 v64, v200
	v_mov_b32_e32 v65, v201
	v_mov_b32_e32 v66, v202
	v_mov_b32_e32 v67, v203
	v_cndmask_b32_e64 v76, v59, v51, s[6:7]
	v_cndmask_b32_e64 v68, v63, v55, s[6:7]
	v_cndmask_b32_e64 v69, v62, v54, s[6:7]
	v_cndmask_b32_e64 v70, v61, v53, s[6:7]
	v_cndmask_b32_e64 v71, v60, v52, s[6:7]
	s_nop 0
	s_nop 0
	s_nop 0
	s_nop 0
	v_cndmask_b32_e64 v77, v58, v50, s[6:7]
	v_cndmask_b32_e64 v78, v57, v49, s[6:7]
	v_cndmask_b32_e64 v79, v56, v48, s[6:7]
	s_nop 0
	s_nop 0
	v_mov_b32_dpp v83, v76 quad_perm:[1,0,3,2] row_mask:0xf bank_mask:0xf
	v_mov_b32_dpp v72, v71 quad_perm:[1,0,3,2] row_mask:0xf bank_mask:0xf
	v_mov_b32_dpp v73, v70 quad_perm:[1,0,3,2] row_mask:0xf bank_mask:0xf
	v_mov_b32_dpp v74, v69 quad_perm:[1,0,3,2] row_mask:0xf bank_mask:0xf
	v_mov_b32_dpp v75, v68 quad_perm:[1,0,3,2] row_mask:0xf bank_mask:0xf
	v_mov_b32_dpp v80, v79 quad_perm:[1,0,3,2] row_mask:0xf bank_mask:0xf
	v_mov_b32_dpp v81, v78 quad_perm:[1,0,3,2] row_mask:0xf bank_mask:0xf
	v_mov_b32_dpp v82, v77 quad_perm:[1,0,3,2] row_mask:0xf bank_mask:0xf
	v_cndmask_b32_e64 v59, v83, v59, s[6:7]
	v_cndmask_b32_e64 v63, v75, v63, s[6:7]
	v_cndmask_b32_e64 v62, v74, v62, s[6:7]
	v_cndmask_b32_e64 v61, v73, v61, s[6:7]
	v_cndmask_b32_e64 v60, v72, v60, s[6:7]
	v_cndmask_b32_e64 v58, v82, v58, s[6:7]
	v_cndmask_b32_e64 v57, v81, v57, s[6:7]
	v_cndmask_b32_e64 v56, v80, v56, s[6:7]
	v_mul_f32_e32 v59, 0xbfb8aa3b, v59
	v_mul_f32_e32 v60, 0xbfb8aa3b, v60
	v_mul_f32_e32 v61, 0xbfb8aa3b, v61
	v_mul_f32_e32 v62, 0xbfb8aa3b, v62
	v_mul_f32_e32 v63, 0xbfb8aa3b, v63
	v_mul_f32_e32 v56, 0xbfb8aa3b, v56
	v_mul_f32_e32 v57, 0xbfb8aa3b, v57
	v_mul_f32_e32 v58, 0xbfb8aa3b, v58
	v_exp_f32_e32 v59, v59
	v_exp_f32_e32 v60, v60
	v_exp_f32_e32 v61, v61
	v_exp_f32_e32 v62, v62
	v_exp_f32_e32 v63, v63
	v_exp_f32_e32 v56, v56
	v_exp_f32_e32 v57, v57
	v_exp_f32_e32 v58, v58
	v_add_f32_e32 v59, 1.0, v59
	v_add_f32_e32 v60, 1.0, v60
	v_add_f32_e32 v61, 1.0, v61
	v_add_f32_e32 v62, 1.0, v62
	v_add_f32_e32 v63, 1.0, v63
	v_add_f32_e32 v56, 1.0, v56
	v_add_f32_e32 v57, 1.0, v57
	v_add_f32_e32 v58, 1.0, v58
	v_rcp_f32_e32 v59, v59
	v_rcp_f32_e32 v60, v60
	v_rcp_f32_e32 v61, v61
	v_rcp_f32_e32 v62, v62
	v_rcp_f32_e32 v63, v63
	v_rcp_f32_e32 v56, v56
	v_rcp_f32_e32 v57, v57
	v_rcp_f32_e32 v58, v58
	v_add_u32_e32 v68, 0x100000, v150
	v_add_u32_e32 v69, 0x81000, v151
	v_cndmask_b32_e64 v51, v51, v83, s[6:7]
	v_cndmask_b32_e64 v55, v55, v75, s[6:7]
	v_cndmask_b32_e64 v54, v54, v74, s[6:7]
	v_cndmask_b32_e64 v53, v53, v73, s[6:7]
	v_cndmask_b32_e64 v52, v52, v72, s[6:7]
	v_cndmask_b32_e64 v50, v50, v82, s[6:7]
	v_cndmask_b32_e64 v49, v49, v81, s[6:7]
	v_cndmask_b32_e64 v48, v48, v80, s[6:7]
	v_mul_f32_e32 v51, 0xbfb8aa3b, v51
	v_mul_f32_e32 v52, 0xbfb8aa3b, v52
	v_mul_f32_e32 v53, 0xbfb8aa3b, v53
	v_mul_f32_e32 v54, 0xbfb8aa3b, v54
	v_mul_f32_e32 v55, 0xbfb8aa3b, v55
	v_mul_f32_e32 v48, 0xbfb8aa3b, v48
	v_mul_f32_e32 v49, 0xbfb8aa3b, v49
	v_lshlrev_b32_e32 v77, 16, v67
	v_and_b32_e32 v67, 0xffff0000, v67
	v_lshlrev_b32_e32 v70, 16, v64
	v_and_b32_e32 v64, 0xffff0000, v64
	v_lshlrev_b32_e32 v71, 16, v65
	v_and_b32_e32 v65, 0xffff0000, v65
	v_lshlrev_b32_e32 v76, 16, v66
	v_and_b32_e32 v66, 0xffff0000, v66
	v_mul_f32_e32 v59, v59, v67
	v_mul_f32_e32 v60, v60, v70
	v_mul_f32_e32 v61, v61, v64
	v_mul_f32_e32 v62, v62, v71
	v_mul_f32_e32 v63, v63, v65
	v_mul_f32_e32 v64, v56, v76
	v_mul_f32_e32 v65, v57, v66
	v_mul_f32_e32 v66, v58, v77
	v_cvt_pk_bf16_f32 v56, v60, v61
	v_cvt_pk_bf16_f32 v57, v62, v63
	v_cvt_pk_bf16_f32 v58, v64, v65
	v_cvt_pk_bf16_f32 v59, v66, v59
	global_store_dwordx4 v68, v[56:59], s[26:27]
	s_waitcnt vmcnt(15)
; __device__ __forceinline__ float dpp_x1(float x) { return __builtin_bit_cast(float, __builtin_amdgcn_update_dpp(0, __builtin_bit_cast(int, x), 0xB1, 0xF, 0xF, false)); }
; __device__ __forceinline__ f32x4 dpp_swap1(f32x4 v) { f32x4 r; r[0] = dpp_x1(v[0]); r[1] = dpp_x1(v[1]); r[2] = dpp_x1(v[2]); r[3] = dpp_x1(v[3]); return r; }
;     __device__ __forceinline__ void operator()(const f32x4 (&acc)[2][2][4][2], const Unit& u, int wr, int wc, int fr, int fq, const EpiCtx& X) const {
;     ...
;         EPI_PIECES({ const unsigned goff = glo + (unsigned)(rl * W_SSM) * 2u, coff = clo + (unsigned)(rl * DM) * 2u;
;             GLU_ONE(p1a, p1b, goff, coff); GLU_ONE(p2a, p2b, goff + W_SSM * 2, coff + DM * 2); })
	s_nop 1
	v_mov_b32_e32 v56, v204
	v_mov_b32_e32 v57, v205
	v_mov_b32_e32 v58, v206
	v_mov_b32_e32 v59, v207
	v_mul_f32_e32 v50, 0xbfb8aa3b, v50
	v_exp_f32_e32 v51, v51
	v_exp_f32_e32 v52, v52
	v_exp_f32_e32 v53, v53
	v_exp_f32_e32 v54, v54
	v_exp_f32_e32 v55, v55
	v_exp_f32_e32 v48, v48
	v_exp_f32_e32 v49, v49
	v_exp_f32_e32 v50, v50
	v_add_f32_e32 v51, 1.0, v51
	v_add_f32_e32 v52, 1.0, v52
	v_add_f32_e32 v53, 1.0, v53
	v_add_f32_e32 v54, 1.0, v54
	v_add_f32_e32 v55, 1.0, v55
	v_add_f32_e32 v48, 1.0, v48
	v_add_f32_e32 v49, 1.0, v49
	v_add_f32_e32 v50, 1.0, v50
	v_rcp_f32_e32 v51, v51
	v_rcp_f32_e32 v52, v52
	v_rcp_f32_e32 v53, v53
	v_rcp_f32_e32 v54, v54
	v_rcp_f32_e32 v55, v55
	v_rcp_f32_e32 v48, v48
	v_rcp_f32_e32 v49, v49
	v_rcp_f32_e32 v50, v50
	v_add_u32_e32 v60, 0x102000, v150
	v_add_u32_e32 v61, 0x90000, v151
	v_mov_b32_e32 v67, 0
	v_mov_b32_e32 v66, 0
	v_lshlrev_b32_e32 v65, 16, v59
	v_and_b32_e32 v59, 0xffff0000, v59
	v_lshlrev_b32_e32 v62, 16, v56
	v_and_b32_e32 v56, 0xffff0000, v56
	v_lshlrev_b32_e32 v63, 16, v57
	v_and_b32_e32 v57, 0xffff0000, v57
	v_lshlrev_b32_e32 v64, 16, v58
	v_and_b32_e32 v58, 0xffff0000, v58
	v_mul_f32_e32 v51, v51, v59
	v_mul_f32_e32 v52, v52, v62
	v_mul_f32_e32 v53, v53, v56
	v_mul_f32_e32 v54, v54, v63
	v_mul_f32_e32 v55, v55, v57
	v_mul_f32_e32 v56, v48, v64
	v_mul_f32_e32 v57, v49, v58
	v_mul_f32_e32 v58, v50, v65
	v_cvt_pk_bf16_f32 v48, v52, v53
	v_cvt_pk_bf16_f32 v49, v54, v55
	v_cvt_pk_bf16_f32 v50, v56, v57
	v_cvt_pk_bf16_f32 v51, v58, v51
	global_store_dwordx4 v60, v[48:51], s[26:27]
	s_waitcnt vmcnt(15)
	s_nop 1
	v_mov_b32_e32 v48, v208
	v_mov_b32_e32 v49, v209
	v_mov_b32_e32 v50, v210
	v_mov_b32_e32 v51, v211
	v_cndmask_b32_e64 v60, v43, v35, s[6:7]
	v_cndmask_b32_e64 v52, v47, v39, s[6:7]
	v_cndmask_b32_e64 v53, v46, v38, s[6:7]
	v_cndmask_b32_e64 v54, v45, v37, s[6:7]
	v_cndmask_b32_e64 v55, v44, v36, s[6:7]
	s_nop 0
	s_nop 0
	s_nop 0
	s_nop 0
	v_cndmask_b32_e64 v61, v42, v34, s[6:7]
	v_cndmask_b32_e64 v62, v41, v33, s[6:7]
	v_cndmask_b32_e64 v63, v40, v32, s[6:7]
	s_nop 0
	s_nop 0
	v_mov_b32_dpp v67, v60 quad_perm:[1,0,3,2] row_mask:0xf bank_mask:0xf
	v_mov_b32_dpp v56, v55 quad_perm:[1,0,3,2] row_mask:0xf bank_mask:0xf
	v_mov_b32_dpp v57, v54 quad_perm:[1,0,3,2] row_mask:0xf bank_mask:0xf
	v_mov_b32_dpp v58, v53 quad_perm:[1,0,3,2] row_mask:0xf bank_mask:0xf
	v_mov_b32_dpp v59, v52 quad_perm:[1,0,3,2] row_mask:0xf bank_mask:0xf
	v_mov_b32_dpp v64, v63 quad_perm:[1,0,3,2] row_mask:0xf bank_mask:0xf
	v_mov_b32_dpp v65, v62 quad_perm:[1,0,3,2] row_mask:0xf bank_mask:0xf
	v_mov_b32_dpp v66, v61 quad_perm:[1,0,3,2] row_mask:0xf bank_mask:0xf
	v_cndmask_b32_e64 v43, v67, v43, s[6:7]
	v_cndmask_b32_e64 v47, v59, v47, s[6:7]
	v_cndmask_b32_e64 v46, v58, v46, s[6:7]
	v_cndmask_b32_e64 v45, v57, v45, s[6:7]
	v_cndmask_b32_e64 v44, v56, v44, s[6:7]
	v_cndmask_b32_e64 v42, v66, v42, s[6:7]
	v_cndmask_b32_e64 v41, v65, v41, s[6:7]
	v_cndmask_b32_e64 v40, v64, v40, s[6:7]
	v_mul_f32_e32 v43, 0xbfb8aa3b, v43
	v_mul_f32_e32 v44, 0xbfb8aa3b, v44
	v_mul_f32_e32 v45, 0xbfb8aa3b, v45
	v_mul_f32_e32 v46, 0xbfb8aa3b, v46
	v_mul_f32_e32 v47, 0xbfb8aa3b, v47
	v_mul_f32_e32 v40, 0xbfb8aa3b, v40
	v_mul_f32_e32 v41, 0xbfb8aa3b, v41
	v_mul_f32_e32 v42, 0xbfb8aa3b, v42
	v_exp_f32_e32 v43, v43
	v_exp_f32_e32 v44, v44
	v_exp_f32_e32 v45, v45
	v_exp_f32_e32 v46, v46
	v_exp_f32_e32 v47, v47
	v_exp_f32_e32 v40, v40
	v_exp_f32_e32 v41, v41
	v_exp_f32_e32 v42, v42
	v_add_f32_e32 v43, 1.0, v43
	v_add_f32_e32 v44, 1.0, v44
	v_add_f32_e32 v45, 1.0, v45
	v_add_f32_e32 v46, 1.0, v46
	v_add_f32_e32 v47, 1.0, v47
	v_add_f32_e32 v40, 1.0, v40
	v_add_f32_e32 v41, 1.0, v41
	v_add_f32_e32 v42, 1.0, v42
	v_rcp_f32_e32 v43, v43
	v_rcp_f32_e32 v44, v44
	v_rcp_f32_e32 v45, v45
	v_rcp_f32_e32 v46, v46
	v_rcp_f32_e32 v47, v47
	v_rcp_f32_e32 v40, v40
	v_rcp_f32_e32 v41, v41
	v_rcp_f32_e32 v42, v42
	v_add_u32_e32 v52, 0x120000, v150
	v_add_u32_e32 v53, 0x91000, v151
	v_cndmask_b32_e64 v35, v35, v67, s[6:7]
	v_cndmask_b32_e64 v39, v39, v59, s[6:7]
	v_cndmask_b32_e64 v38, v38, v58, s[6:7]
	v_cndmask_b32_e64 v37, v37, v57, s[6:7]
	v_cndmask_b32_e64 v36, v36, v56, s[6:7]
	v_cndmask_b32_e64 v34, v34, v66, s[6:7]
	v_cndmask_b32_e64 v33, v33, v65, s[6:7]
	v_cndmask_b32_e64 v32, v32, v64, s[6:7]
	v_mul_f32_e32 v35, 0xbfb8aa3b, v35
	v_mul_f32_e32 v36, 0xbfb8aa3b, v36
	v_mul_f32_e32 v37, 0xbfb8aa3b, v37
	v_mul_f32_e32 v38, 0xbfb8aa3b, v38
	v_mul_f32_e32 v39, 0xbfb8aa3b, v39
	v_mul_f32_e32 v32, 0xbfb8aa3b, v32
	v_mul_f32_e32 v33, 0xbfb8aa3b, v33
	v_lshlrev_b32_e32 v61, 16, v51
	v_and_b32_e32 v51, 0xffff0000, v51
	v_lshlrev_b32_e32 v54, 16, v48
	v_and_b32_e32 v48, 0xffff0000, v48
	v_lshlrev_b32_e32 v55, 16, v49
	v_and_b32_e32 v49, 0xffff0000, v49
	v_lshlrev_b32_e32 v60, 16, v50
	v_and_b32_e32 v50, 0xffff0000, v50
	v_mul_f32_e32 v43, v43, v51
	v_mul_f32_e32 v44, v44, v54
	v_mul_f32_e32 v45, v45, v48
	v_mul_f32_e32 v46, v46, v55
	v_mul_f32_e32 v47, v47, v49
	v_mul_f32_e32 v48, v40, v60
	v_mul_f32_e32 v49, v41, v50
	v_mul_f32_e32 v50, v42, v61
	v_cvt_pk_bf16_f32 v40, v44, v45
	v_cvt_pk_bf16_f32 v41, v46, v47
	v_cvt_pk_bf16_f32 v42, v48, v49
	v_cvt_pk_bf16_f32 v43, v50, v43
	global_store_dwordx4 v52, v[40:43], s[26:27]
	s_waitcnt vmcnt(15)
; __device__ __forceinline__ float dpp_x1(float x) { return __builtin_bit_cast(float, __builtin_amdgcn_update_dpp(0, __builtin_bit_cast(int, x), 0xB1, 0xF, 0xF, false)); }
; __device__ __forceinline__ f32x4 dpp_swap1(f32x4 v) { f32x4 r; r[0] = dpp_x1(v[0]); r[1] = dpp_x1(v[1]); r[2] = dpp_x1(v[2]); r[3] = dpp_x1(v[3]); return r; }
;     __device__ __forceinline__ void operator()(const f32x4 (&acc)[2][2][4][2], const Unit& u, int wr, int wc, int fr, int fq, const EpiCtx& X) const {
;     ...
;         EPI_PIECES({ const unsigned goff = glo + (unsigned)(rl * W_SSM) * 2u, coff = clo + (unsigned)(rl * DM) * 2u;
;             GLU_ONE(p1a, p1b, goff, coff); GLU_ONE(p2a, p2b, goff + W_SSM * 2, coff + DM * 2); })
	s_nop 1
	v_mov_b32_e32 v40, v220
	v_mov_b32_e32 v41, v221
	v_mov_b32_e32 v42, v222
	v_mov_b32_e32 v43, v223
	v_mul_f32_e32 v34, 0xbfb8aa3b, v34
	v_exp_f32_e32 v35, v35
	v_exp_f32_e32 v36, v36
	v_exp_f32_e32 v37, v37
	v_exp_f32_e32 v38, v38
	v_exp_f32_e32 v39, v39
	v_exp_f32_e32 v32, v32
	v_exp_f32_e32 v33, v33
	v_exp_f32_e32 v34, v34
	v_add_f32_e32 v35, 1.0, v35
	v_add_f32_e32 v36, 1.0, v36
	v_add_f32_e32 v37, 1.0, v37
	v_add_f32_e32 v38, 1.0, v38
	v_add_f32_e32 v39, 1.0, v39
	v_add_f32_e32 v32, 1.0, v32
	v_add_f32_e32 v33, 1.0, v33
	v_add_f32_e32 v34, 1.0, v34
	v_rcp_f32_e32 v35, v35
	v_rcp_f32_e32 v36, v36
	v_rcp_f32_e32 v37, v37
	v_rcp_f32_e32 v38, v38
	v_rcp_f32_e32 v39, v39
	v_rcp_f32_e32 v32, v32
	v_rcp_f32_e32 v33, v33
	v_rcp_f32_e32 v34, v34
	v_add_u32_e32 v44, 0x122000, v150
	v_add_u32_e32 v45, 0xa0000, v151
	v_mov_b32_e32 v51, 0
	v_mov_b32_e32 v50, 0
	v_lshlrev_b32_e32 v49, 16, v43
	v_and_b32_e32 v43, 0xffff0000, v43
	v_lshlrev_b32_e32 v46, 16, v40
	v_and_b32_e32 v40, 0xffff0000, v40
	v_lshlrev_b32_e32 v47, 16, v41
	v_and_b32_e32 v41, 0xffff0000, v41
	v_lshlrev_b32_e32 v48, 16, v42
	v_and_b32_e32 v42, 0xffff0000, v42
	v_mul_f32_e32 v35, v35, v43
	v_mul_f32_e32 v36, v36, v46
	v_mul_f32_e32 v37, v37, v40
	v_mul_f32_e32 v38, v38, v47
	v_mul_f32_e32 v39, v39, v41
	v_mul_f32_e32 v40, v32, v48
	v_mul_f32_e32 v41, v33, v42
	v_mul_f32_e32 v42, v34, v49
	v_cvt_pk_bf16_f32 v32, v36, v37
	v_cvt_pk_bf16_f32 v33, v38, v39
	v_cvt_pk_bf16_f32 v34, v40, v41
	v_cvt_pk_bf16_f32 v35, v42, v35
	global_store_dwordx4 v44, v[32:35], s[26:27]
	s_waitcnt vmcnt(15)
	s_nop 1
	v_mov_b32_e32 v32, v224
	v_mov_b32_e32 v33, v225
	v_mov_b32_e32 v34, v226
	v_mov_b32_e32 v35, v227
	v_cndmask_b32_e64 v44, v27, v19, s[6:7]
	v_cndmask_b32_e64 v36, v31, v23, s[6:7]
	v_cndmask_b32_e64 v37, v30, v22, s[6:7]
	v_cndmask_b32_e64 v38, v29, v21, s[6:7]
	v_cndmask_b32_e64 v39, v28, v20, s[6:7]
	s_nop 0
	s_nop 0
	s_nop 0
	s_nop 0
	v_cndmask_b32_e64 v45, v26, v18, s[6:7]
	v_cndmask_b32_e64 v46, v25, v17, s[6:7]
	v_cndmask_b32_e64 v47, v24, v16, s[6:7]
	s_nop 0
	s_nop 0
	v_mov_b32_dpp v51, v44 quad_perm:[1,0,3,2] row_mask:0xf bank_mask:0xf
	v_mov_b32_dpp v40, v39 quad_perm:[1,0,3,2] row_mask:0xf bank_mask:0xf
	v_mov_b32_dpp v41, v38 quad_perm:[1,0,3,2] row_mask:0xf bank_mask:0xf
	v_mov_b32_dpp v42, v37 quad_perm:[1,0,3,2] row_mask:0xf bank_mask:0xf
	v_mov_b32_dpp v43, v36 quad_perm:[1,0,3,2] row_mask:0xf bank_mask:0xf
	v_mov_b32_dpp v48, v47 quad_perm:[1,0,3,2] row_mask:0xf bank_mask:0xf
	v_mov_b32_dpp v49, v46 quad_perm:[1,0,3,2] row_mask:0xf bank_mask:0xf
	v_mov_b32_dpp v50, v45 quad_perm:[1,0,3,2] row_mask:0xf bank_mask:0xf
	v_cndmask_b32_e64 v27, v51, v27, s[6:7]
	v_cndmask_b32_e64 v31, v43, v31, s[6:7]
	v_cndmask_b32_e64 v30, v42, v30, s[6:7]
	v_cndmask_b32_e64 v29, v41, v29, s[6:7]
	v_cndmask_b32_e64 v28, v40, v28, s[6:7]
	v_cndmask_b32_e64 v26, v50, v26, s[6:7]
	v_cndmask_b32_e64 v25, v49, v25, s[6:7]
	v_cndmask_b32_e64 v24, v48, v24, s[6:7]
	v_mul_f32_e32 v27, 0xbfb8aa3b, v27
	v_mul_f32_e32 v28, 0xbfb8aa3b, v28
	v_mul_f32_e32 v29, 0xbfb8aa3b, v29
	v_mul_f32_e32 v30, 0xbfb8aa3b, v30
	v_mul_f32_e32 v31, 0xbfb8aa3b, v31
	v_mul_f32_e32 v24, 0xbfb8aa3b, v24
	v_mul_f32_e32 v25, 0xbfb8aa3b, v25
	v_mul_f32_e32 v26, 0xbfb8aa3b, v26
	v_exp_f32_e32 v27, v27
	v_exp_f32_e32 v28, v28
	v_exp_f32_e32 v29, v29
	v_exp_f32_e32 v30, v30
	v_exp_f32_e32 v31, v31
	v_exp_f32_e32 v24, v24
	v_exp_f32_e32 v25, v25
	v_exp_f32_e32 v26, v26
	v_add_f32_e32 v27, 1.0, v27
	v_add_f32_e32 v28, 1.0, v28
	v_add_f32_e32 v29, 1.0, v29
	v_add_f32_e32 v30, 1.0, v30
	v_add_f32_e32 v31, 1.0, v31
	v_add_f32_e32 v24, 1.0, v24
	v_add_f32_e32 v25, 1.0, v25
	v_add_f32_e32 v26, 1.0, v26
	v_rcp_f32_e32 v27, v27
	v_rcp_f32_e32 v28, v28
	v_rcp_f32_e32 v29, v29
	v_rcp_f32_e32 v30, v30
	v_rcp_f32_e32 v31, v31
	v_rcp_f32_e32 v24, v24
	v_rcp_f32_e32 v25, v25
	v_rcp_f32_e32 v26, v26
	v_add_u32_e32 v36, 0x140000, v150
	v_add_u32_e32 v37, 0xa1000, v151
	v_cndmask_b32_e64 v19, v19, v51, s[6:7]
	v_cndmask_b32_e64 v23, v23, v43, s[6:7]
	v_cndmask_b32_e64 v22, v22, v42, s[6:7]
	v_cndmask_b32_e64 v21, v21, v41, s[6:7]
	v_cndmask_b32_e64 v20, v20, v40, s[6:7]
	v_cndmask_b32_e64 v18, v18, v50, s[6:7]
	v_cndmask_b32_e64 v17, v17, v49, s[6:7]
	v_cndmask_b32_e64 v16, v16, v48, s[6:7]
	v_mul_f32_e32 v19, 0xbfb8aa3b, v19
	v_mul_f32_e32 v20, 0xbfb8aa3b, v20
	v_mul_f32_e32 v21, 0xbfb8aa3b, v21
	v_mul_f32_e32 v22, 0xbfb8aa3b, v22
	v_mul_f32_e32 v23, 0xbfb8aa3b, v23
	v_mul_f32_e32 v16, 0xbfb8aa3b, v16
	v_mul_f32_e32 v17, 0xbfb8aa3b, v17
	v_lshlrev_b32_e32 v45, 16, v35
	v_and_b32_e32 v35, 0xffff0000, v35
	v_lshlrev_b32_e32 v38, 16, v32
	v_and_b32_e32 v32, 0xffff0000, v32
	v_lshlrev_b32_e32 v39, 16, v33
	v_and_b32_e32 v33, 0xffff0000, v33
	v_lshlrev_b32_e32 v44, 16, v34
	v_and_b32_e32 v34, 0xffff0000, v34
	v_mul_f32_e32 v27, v27, v35
	v_mul_f32_e32 v28, v28, v38
	v_mul_f32_e32 v29, v29, v32
	v_mul_f32_e32 v30, v30, v39
	v_mul_f32_e32 v31, v31, v33
	v_mul_f32_e32 v32, v24, v44
	v_mul_f32_e32 v33, v25, v34
	v_mul_f32_e32 v34, v26, v45
	v_cvt_pk_bf16_f32 v24, v28, v29
	v_cvt_pk_bf16_f32 v25, v30, v31
	v_cvt_pk_bf16_f32 v26, v32, v33
	v_cvt_pk_bf16_f32 v27, v34, v27
	global_store_dwordx4 v36, v[24:27], s[26:27]
	s_waitcnt vmcnt(15)
; __device__ __forceinline__ float dpp_x1(float x) { return __builtin_bit_cast(float, __builtin_amdgcn_update_dpp(0, __builtin_bit_cast(int, x), 0xB1, 0xF, 0xF, false)); }
; __device__ __forceinline__ f32x4 dpp_swap1(f32x4 v) { f32x4 r; r[0] = dpp_x1(v[0]); r[1] = dpp_x1(v[1]); r[2] = dpp_x1(v[2]); r[3] = dpp_x1(v[3]); return r; }
;     __device__ __forceinline__ void operator()(const f32x4 (&acc)[2][2][4][2], const Unit& u, int wr, int wc, int fr, int fq, const EpiCtx& X) const {
;     ...
;         EPI_PIECES({ const unsigned goff = glo + (unsigned)(rl * W_SSM) * 2u, coff = clo + (unsigned)(rl * DM) * 2u;
;             GLU_ONE(p1a, p1b, goff, coff); GLU_ONE(p2a, p2b, goff + W_SSM * 2, coff + DM * 2); })
	s_nop 1
	v_mov_b32_e32 v24, v228
	v_mov_b32_e32 v25, v229
	v_mov_b32_e32 v26, v230
	v_mov_b32_e32 v27, v231
	v_mul_f32_e32 v18, 0xbfb8aa3b, v18
	v_exp_f32_e32 v19, v19
	v_exp_f32_e32 v20, v20
	v_exp_f32_e32 v21, v21
	v_exp_f32_e32 v22, v22
	v_exp_f32_e32 v23, v23
	v_exp_f32_e32 v16, v16
	v_exp_f32_e32 v17, v17
	v_exp_f32_e32 v18, v18
	v_add_f32_e32 v19, 1.0, v19
	v_add_f32_e32 v20, 1.0, v20
	v_add_f32_e32 v21, 1.0, v21
	v_add_f32_e32 v22, 1.0, v22
	v_add_f32_e32 v23, 1.0, v23
	v_add_f32_e32 v16, 1.0, v16
	v_add_f32_e32 v17, 1.0, v17
	v_add_f32_e32 v18, 1.0, v18
	v_rcp_f32_e32 v19, v19
	v_rcp_f32_e32 v20, v20
	v_rcp_f32_e32 v21, v21
	v_rcp_f32_e32 v22, v22
	v_rcp_f32_e32 v23, v23
	v_rcp_f32_e32 v16, v16
	v_rcp_f32_e32 v17, v17
	v_rcp_f32_e32 v18, v18
	v_add_u32_e32 v28, 0x142000, v150
	v_add_u32_e32 v29, 0xb0000, v151
	v_mov_b32_e32 v35, 0
	v_mov_b32_e32 v34, 0
	v_lshlrev_b32_e32 v33, 16, v27
	v_and_b32_e32 v27, 0xffff0000, v27
	v_lshlrev_b32_e32 v30, 16, v24
	v_and_b32_e32 v24, 0xffff0000, v24
	v_lshlrev_b32_e32 v31, 16, v25
	v_and_b32_e32 v25, 0xffff0000, v25
	v_lshlrev_b32_e32 v32, 16, v26
	v_and_b32_e32 v26, 0xffff0000, v26
	v_mul_f32_e32 v19, v19, v27
	v_mul_f32_e32 v20, v20, v30
	v_mul_f32_e32 v21, v21, v24
	v_mul_f32_e32 v22, v22, v31
	v_mul_f32_e32 v23, v23, v25
	v_mul_f32_e32 v24, v16, v32
	v_mul_f32_e32 v25, v17, v26
	v_mul_f32_e32 v26, v18, v33
	v_cvt_pk_bf16_f32 v16, v20, v21
	v_cvt_pk_bf16_f32 v17, v22, v23
	v_cvt_pk_bf16_f32 v18, v24, v25
	v_cvt_pk_bf16_f32 v19, v26, v19
	global_store_dwordx4 v28, v[16:19], s[26:27]
	s_waitcnt vmcnt(15)
	s_nop 1
	v_mov_b32_e32 v16, v232
	v_mov_b32_e32 v17, v233
	v_mov_b32_e32 v18, v234
	v_mov_b32_e32 v19, v235
	v_cndmask_b32_e64 v28, v11, v3, s[6:7]
	v_cndmask_b32_e64 v20, v15, v7, s[6:7]
	v_cndmask_b32_e64 v21, v14, v6, s[6:7]
	v_cndmask_b32_e64 v22, v13, v5, s[6:7]
	v_cndmask_b32_e64 v23, v12, v4, s[6:7]
	s_nop 0
	s_nop 0
	s_nop 0
	s_nop 0
	v_cndmask_b32_e64 v29, v10, v2, s[6:7]
	v_cndmask_b32_e64 v30, v9, v1, s[6:7]
	v_cndmask_b32_e64 v31, v8, v0, s[6:7]
	s_nop 0
	s_nop 0
	v_mov_b32_dpp v35, v28 quad_perm:[1,0,3,2] row_mask:0xf bank_mask:0xf
	v_mov_b32_dpp v24, v23 quad_perm:[1,0,3,2] row_mask:0xf bank_mask:0xf
	v_mov_b32_dpp v25, v22 quad_perm:[1,0,3,2] row_mask:0xf bank_mask:0xf
	v_mov_b32_dpp v26, v21 quad_perm:[1,0,3,2] row_mask:0xf bank_mask:0xf
	v_mov_b32_dpp v27, v20 quad_perm:[1,0,3,2] row_mask:0xf bank_mask:0xf
	v_mov_b32_dpp v32, v31 quad_perm:[1,0,3,2] row_mask:0xf bank_mask:0xf
	v_mov_b32_dpp v33, v30 quad_perm:[1,0,3,2] row_mask:0xf bank_mask:0xf
	v_mov_b32_dpp v34, v29 quad_perm:[1,0,3,2] row_mask:0xf bank_mask:0xf
	v_cndmask_b32_e64 v11, v35, v11, s[6:7]
	v_cndmask_b32_e64 v15, v27, v15, s[6:7]
	v_cndmask_b32_e64 v14, v26, v14, s[6:7]
	v_cndmask_b32_e64 v13, v25, v13, s[6:7]
	v_cndmask_b32_e64 v12, v24, v12, s[6:7]
	v_cndmask_b32_e64 v10, v34, v10, s[6:7]
	v_cndmask_b32_e64 v9, v33, v9, s[6:7]
	v_cndmask_b32_e64 v8, v32, v8, s[6:7]
	v_mul_f32_e32 v11, 0xbfb8aa3b, v11
	v_mul_f32_e32 v12, 0xbfb8aa3b, v12
	v_mul_f32_e32 v13, 0xbfb8aa3b, v13
	v_mul_f32_e32 v14, 0xbfb8aa3b, v14
	v_mul_f32_e32 v15, 0xbfb8aa3b, v15
	v_mul_f32_e32 v8, 0xbfb8aa3b, v8
	v_mul_f32_e32 v9, 0xbfb8aa3b, v9
	v_mul_f32_e32 v10, 0xbfb8aa3b, v10
	v_exp_f32_e32 v11, v11
	v_exp_f32_e32 v12, v12
	v_exp_f32_e32 v13, v13
	v_exp_f32_e32 v14, v14
	v_exp_f32_e32 v15, v15
	v_exp_f32_e32 v8, v8
	v_exp_f32_e32 v9, v9
	v_exp_f32_e32 v10, v10
	v_add_f32_e32 v11, 1.0, v11
	v_add_f32_e32 v12, 1.0, v12
	v_add_f32_e32 v13, 1.0, v13
	v_add_f32_e32 v14, 1.0, v14
	v_add_f32_e32 v15, 1.0, v15
	v_add_f32_e32 v8, 1.0, v8
	v_add_f32_e32 v9, 1.0, v9
	v_add_f32_e32 v10, 1.0, v10
	v_rcp_f32_e32 v11, v11
	v_rcp_f32_e32 v12, v12
	v_rcp_f32_e32 v13, v13
	v_rcp_f32_e32 v14, v14
	v_rcp_f32_e32 v15, v15
	v_rcp_f32_e32 v8, v8
	v_rcp_f32_e32 v9, v9
	v_rcp_f32_e32 v10, v10
	v_add_u32_e32 v20, 0x160000, v150
	v_add_u32_e32 v21, 0xb1000, v151
	v_cndmask_b32_e64 v3, v3, v35, s[6:7]
	v_cndmask_b32_e64 v7, v7, v27, s[6:7]
	v_cndmask_b32_e64 v6, v6, v26, s[6:7]
	v_cndmask_b32_e64 v5, v5, v25, s[6:7]
	v_cndmask_b32_e64 v4, v4, v24, s[6:7]
	v_cndmask_b32_e64 v2, v2, v34, s[6:7]
	v_cndmask_b32_e64 v1, v1, v33, s[6:7]
	v_cndmask_b32_e64 v0, v0, v32, s[6:7]
	v_mul_f32_e32 v3, 0xbfb8aa3b, v3
	v_mul_f32_e32 v4, 0xbfb8aa3b, v4
	v_mul_f32_e32 v5, 0xbfb8aa3b, v5
	v_mul_f32_e32 v6, 0xbfb8aa3b, v6
	v_mul_f32_e32 v7, 0xbfb8aa3b, v7
	v_mul_f32_e32 v0, 0xbfb8aa3b, v0
	v_mul_f32_e32 v1, 0xbfb8aa3b, v1
	v_lshlrev_b32_e32 v29, 16, v19
	v_and_b32_e32 v19, 0xffff0000, v19
	v_lshlrev_b32_e32 v22, 16, v16
	v_and_b32_e32 v16, 0xffff0000, v16
	v_lshlrev_b32_e32 v23, 16, v17
	v_and_b32_e32 v17, 0xffff0000, v17
	v_lshlrev_b32_e32 v28, 16, v18
	v_and_b32_e32 v18, 0xffff0000, v18
	v_mul_f32_e32 v11, v11, v19
	v_mul_f32_e32 v12, v12, v22
	v_mul_f32_e32 v13, v13, v16
	v_mul_f32_e32 v14, v14, v23
	v_mul_f32_e32 v15, v15, v17
	v_mul_f32_e32 v16, v8, v28
	v_mul_f32_e32 v17, v9, v18
	v_mul_f32_e32 v18, v10, v29
	v_cvt_pk_bf16_f32 v8, v12, v13
	v_cvt_pk_bf16_f32 v9, v14, v15
	v_cvt_pk_bf16_f32 v10, v16, v17
	v_cvt_pk_bf16_f32 v11, v18, v11
	global_store_dwordx4 v20, v[8:11], s[26:27]
	s_waitcnt vmcnt(15)
	s_nop 1
	v_mov_b32_e32 v8, v236
	v_mov_b32_e32 v9, v237
	v_mov_b32_e32 v10, v238
	v_mov_b32_e32 v11, v239
	v_mul_f32_e32 v2, 0xbfb8aa3b, v2
	v_exp_f32_e32 v3, v3
	v_exp_f32_e32 v4, v4
	v_exp_f32_e32 v5, v5
	v_exp_f32_e32 v6, v6
	v_exp_f32_e32 v7, v7
	v_exp_f32_e32 v0, v0
	v_exp_f32_e32 v1, v1
	v_exp_f32_e32 v2, v2
	v_add_f32_e32 v3, 1.0, v3
	v_add_f32_e32 v4, 1.0, v4
	v_add_f32_e32 v5, 1.0, v5
	v_add_f32_e32 v6, 1.0, v6
	v_add_f32_e32 v7, 1.0, v7
	v_add_f32_e32 v0, 1.0, v0
	v_add_f32_e32 v1, 1.0, v1
	v_add_f32_e32 v2, 1.0, v2
	v_rcp_f32_e32 v3, v3
	v_rcp_f32_e32 v4, v4
	v_rcp_f32_e32 v5, v5
	v_rcp_f32_e32 v6, v6
	v_rcp_f32_e32 v7, v7
	v_rcp_f32_e32 v0, v0
	v_rcp_f32_e32 v1, v1
	v_rcp_f32_e32 v2, v2
	v_add_u32_e32 v12, 0x162000, v150
	v_lshlrev_b32_e32 v16, 16, v11
	v_and_b32_e32 v11, 0xffff0000, v11
	v_lshlrev_b32_e32 v13, 16, v8
	v_and_b32_e32 v8, 0xffff0000, v8
	v_lshlrev_b32_e32 v14, 16, v9
	v_and_b32_e32 v9, 0xffff0000, v9
	v_lshlrev_b32_e32 v15, 16, v10
	v_and_b32_e32 v10, 0xffff0000, v10
	v_mul_f32_e32 v3, v3, v11
	v_mul_f32_e32 v4, v4, v13
	v_mul_f32_e32 v5, v5, v8
	v_mul_f32_e32 v6, v6, v14
	v_mul_f32_e32 v7, v7, v9
	v_mul_f32_e32 v8, v0, v15
	v_mul_f32_e32 v9, v1, v10
	v_mul_f32_e32 v10, v2, v16
	v_cvt_pk_bf16_f32 v0, v4, v5
	v_cvt_pk_bf16_f32 v1, v6, v7
	v_cvt_pk_bf16_f32 v2, v8, v9
	v_cvt_pk_bf16_f32 v3, v10, v3
	global_store_dwordx4 v12, v[0:3], s[26:27]
	s_cbranch_vccnz .LBB0_491
	s_and_b64 vcc, exec, s[4:5]
	s_cbranch_vccnz .LBB0_490
	s_barrier
	s_branch .LBB0_490

; #define LAS __attribute__((address_space(3)))
;     __device__ __forceinline__ void operator()(const f32x4 (&acc)[2][2][4][2], const Unit& u, int wr, int wc, int fr, int fq, const EpiCtx& X) const {
;     ...
;         char* yb = nullptr; char* xb = (char*)(XB + (size_t)u.pm * BM * DM + (size_t)(u.pn * 4 + wc) * (BM * 64));
;         unsigned lo = (unsigned)((wr * 64 + fe) * 64 + o32 + 8 * fq) * 2u; EPI_OPAQUE(lo);
;         const int col = u.pn * BM + wc * 64 + o32 + 8 * fq;
;         f32x4 g0, g1, b0, b1;
;         if (RESN) { ensure_tbl(PSp, sidp, u.pm, X);
;             g0 = *(const f32x4*)(gp + col); g1 = *(const f32x4*)(gp + col + 4); b0 = *(const f32x4*)(bp + col) * ALPHA; b1 = *(const f32x4*)(bp + col + 4) * ALPHA; }
;         const LAS f32x2* tbl = (const LAS f32x2*)(X.lds + TBL_OFF) + wr * 64 + fe;
;         f32x2* ps = PSn + ((size_t)u.pm * BM + wr * 64 + fe) * 64 + u.pn * 4 + wc;
; #pragma unroll
;         for (int ai = 0; ai < 2; ++ai) {
;             u32x4 raw[8];
; #pragma unroll
;             for (int m = 0; m < 4; ++m) { const unsigned off = lo + (unsigned)((ai * HALF + m * 16) * 64) * 2u; raw[2 * m] = *(const u32x4*)(xb + off); raw[2 * m + 1] = *(const u32x4*)(xb + off + 128); }
; #pragma unroll
;             for (int m = 0; m < 4; ++m) {
;                 const int rl = ai * HALF + m * 16; const unsigned off = lo + (unsigned)(rl * 64) * 2u;
;                 const f32x4 o0a = acc[ai][0][m][0], o0b = acc[ai][0][m][1], o1a = acc[ai][1][m][0], o1b = acc[ai][1][m][1];
;                 const f32x4 ra_ = dpp_swap1(odd ? o0a : o1a), rb_ = dpp_swap1(odd ? o0b : o1b);
;                 const f32x4 pa[2] = {odd ? ra_ : o0a, odd ? o1a : ra_}, pb[2] = {odd ? rb_ : o0b, odd ? o1b : rb_};
; #pragma unroll
;                 for (int q = 0; q < 2; ++q) {
;                     const u32x4 w0 = raw[2 * m + q];
;                     const f32x4 r0 = (f32x4){bf_lo(w0.x), bf_hi(w0.x), bf_lo(w0.y), bf_hi(w0.y)}, r1 = (f32x4){bf_lo(w0.z), bf_hi(w0.z), bf_lo(w0.w), bf_hi(w0.w)};
;                     f32x4 y0, y1;
;                     if (RESN) { const f32x2 t = tbl[rl + q]; const float mu = t.x, ra = t.y * ALPHA; y0 = (r0 - mu) * ra * g0 + b0 + pa[q]; y1 = (r1 - mu) * ra * g1 + b1 + pb[q]; }
;                     else { y0 = r0 * ALPHA + pa[q]; y1 = r1 * ALPHA + pb[q]; }
;                     { const u32x4 w = pack8f(y0, y1); *(u32x4*)(xb + off + q * 128) = w;
.LBB0_582:
	s_ashr_i32 s57, s56, 31
	s_lshl_b64 s[52:53], s[56:57], 21
	s_add_u32 s21, s46, s52
	s_addc_u32 s23, s47, s53
	s_lshl_b32 s58, s54, 2
	s_or_b32 s52, s58, s41
	s_ashr_i32 s53, s52, 31
	s_lshl_b64 s[52:53], s[52:53], 15
	s_add_u32 s54, s21, s52
	s_addc_u32 s55, s23, s53
	v_mov_b32_e32 v164, v183
	global_load_dwordx4 v[194:197], v164, s[54:55]
	v_add_u32_e32 v180, 0x800, v164
	v_add_u32_e32 v178, 0x1000, v164
	v_add_u32_e32 v176, 0x1800, v164
	global_load_dwordx4 v[152:155], v164, s[54:55] offset:128
	global_load_dwordx4 v[148:151], v180, s[54:55]
	global_load_dwordx4 v[144:147], v180, s[54:55] offset:128
	global_load_dwordx4 v[140:143], v178, s[54:55]
	global_load_dwordx4 v[136:139], v178, s[54:55] offset:128
	global_load_dwordx4 v[132:135], v176, s[54:55]
	global_load_dwordx4 v[120:123], v176, s[54:55] offset:128
	v_cndmask_b32_e64 v199, v129, v117, s[8:9]
	v_cndmask_b32_e64 v200, v128, v116, s[8:9]
	s_nop 0
	s_nop 0
	v_cndmask_b32_e64 v201, v127, v115, s[8:9]
	v_cndmask_b32_e64 v202, v126, v114, s[8:9]
	v_cndmask_b32_e64 v203, v125, v113, s[8:9]
	v_cndmask_b32_e64 v204, v124, v112, s[8:9]
	s_nop 0
	s_nop 0
	s_nop 0
	s_nop 0
	v_cndmask_b32_e64 v193, v131, v119, s[8:9]
	v_cndmask_b32_e64 v198, v130, v118, s[8:9]
	s_nop 0
	s_nop 0
	v_mov_b32_dpp v177, v200 quad_perm:[1,0,3,2] row_mask:0xf bank_mask:0xf
	v_mov_b32_dpp v181, v199 quad_perm:[1,0,3,2] row_mask:0xf bank_mask:0xf
	v_mov_b32_dpp v189, v204 quad_perm:[1,0,3,2] row_mask:0xf bank_mask:0xf
	v_mov_b32_dpp v191, v203 quad_perm:[1,0,3,2] row_mask:0xf bank_mask:0xf
	v_mov_b32_dpp v190, v202 quad_perm:[1,0,3,2] row_mask:0xf bank_mask:0xf
	v_mov_b32_dpp v192, v201 quad_perm:[1,0,3,2] row_mask:0xf bank_mask:0xf
	v_mov_b32_dpp v179, v198 quad_perm:[1,0,3,2] row_mask:0xf bank_mask:0xf
	v_mov_b32_dpp v188, v193 quad_perm:[1,0,3,2] row_mask:0xf bank_mask:0xf
	v_cndmask_b32_e64 v129, v181, v129, s[8:9]
	v_cndmask_b32_e64 v128, v177, v128, s[8:9]
	v_cndmask_b32_e64 v125, v191, v125, s[8:9]
	v_cndmask_b32_e64 v124, v189, v124, s[8:9]
	v_cndmask_b32_e64 v127, v192, v127, s[8:9]
	v_cndmask_b32_e64 v126, v190, v126, s[8:9]
	v_and_b32_e32 v206, 64, v187
	v_cndmask_b32_e64 v131, v188, v131, s[8:9]
	v_cndmask_b32_e64 v130, v179, v130, s[8:9]
	v_xor_b32_e32 v205, 16, v187
	v_add_u32_e32 v193, 64, v206
	v_cmp_lt_i32_e32 vcc, v205, v193
	s_lshl_b64 s[52:53], s[56:57], 17
	v_lshl_add_u64 v[198:199], v[166:167], 0, s[52:53]
	v_cndmask_b32_e32 v210, v187, v205, vcc
	s_ashr_i32 s59, s58, 31
	v_add_u32_e32 v246, 0x4000, v164
	v_add_u32_e32 v247, 0x4800, v164
	global_load_dwordx4 v[230:233], v246, s[54:55]
	global_load_dwordx4 v[234:237], v246, s[54:55] offset:128
	global_load_dwordx4 v[238:241], v247, s[54:55]
	global_load_dwordx4 v[242:245], v247, s[54:55] offset:128
	s_waitcnt vmcnt(11)
	v_lshlrev_b32_e32 v200, 16, v194
	v_and_b32_e32 v201, 0xffff0000, v194
	v_lshlrev_b32_e32 v202, 16, v196
	v_and_b32_e32 v203, 0xffff0000, v196
	v_lshlrev_b32_e32 v196, 16, v197
	v_and_b32_e32 v197, 0xffff0000, v197
	v_lshlrev_b32_e32 v194, 16, v195
	v_and_b32_e32 v195, 0xffff0000, v195
	v_pk_fma_f32 v[128:129], v[200:201], s[18:19], v[128:129] op_sel_hi:[1,0,1]
	v_pk_fma_f32 v[126:127], v[196:197], s[18:19], v[126:127] op_sel_hi:[1,0,1]
	v_pk_fma_f32 v[124:125], v[202:203], s[18:19], v[124:125] op_sel_hi:[1,0,1]
	v_pk_fma_f32 v[130:131], v[194:195], s[18:19], v[130:131] op_sel_hi:[1,0,1]
	v_cvt_pk_bf16_f32 v194, v128, v129
	s_nop 0
	v_cvt_pk_bf16_f32 v195, v130, v131
	v_cvt_pk_bf16_f32 v196, v124, v125
	v_cvt_pk_bf16_f32 v197, v126, v127
	v_lshlrev_b32_e32 v124, 16, v194
	v_and_b32_e32 v126, 0xffff0000, v194
	v_lshlrev_b32_e32 v128, 16, v195
	v_and_b32_e32 v200, 0xffff0000, v195
	v_lshlrev_b32_e32 v202, 16, v196
	v_and_b32_e32 v204, 0xffff0000, v196
	v_lshlrev_b32_e32 v206, 16, v197
	v_and_b32_e32 v208, 0xffff0000, v197
	v_mul_f32_e32 v125, v124, v124
	v_mul_f32_e32 v127, v126, v126
	v_mul_f32_e32 v129, v128, v128
	v_mul_f32_e32 v201, v200, v200
	v_mul_f32_e32 v203, v202, v202
	v_mul_f32_e32 v205, v204, v204
	v_mul_f32_e32 v207, v206, v206
	v_mul_f32_e32 v209, v208, v208
	v_pk_add_f32 v[124:125], v[124:125], v[126:127]
	v_pk_add_f32 v[126:127], v[128:129], v[200:201]
	v_pk_add_f32 v[128:129], v[206:207], v[208:209]
	v_pk_add_f32 v[124:125], v[124:125], v[126:127]
	v_pk_add_f32 v[126:127], v[202:203], v[204:205]
	v_lshlrev_b32_e32 v130, 2, v210
	v_pk_add_f32 v[126:127], v[126:127], v[128:129]
	v_xor_b32_e32 v128, 32, v187
	v_pk_add_f32 v[124:125], v[124:125], v[126:127]
	s_nop 0
	s_nop 0
	v_cmp_lt_i32_e32 vcc, v128, v193
	v_mov_b32_dpp v126, v124 quad_perm:[1,0,3,2] row_mask:0xf bank_mask:0xf
	v_mov_b32_dpp v127, v125 quad_perm:[1,0,3,2] row_mask:0xf bank_mask:0xf
	v_pk_add_f32 v[124:125], v[124:125], v[126:127]
	ds_bpermute_b32 v126, v130, v124
	ds_bpermute_b32 v127, v130, v125
	v_cndmask_b32_e32 v128, v187, v128, vcc
	v_lshlrev_b32_e32 v131, 2, v128
	global_store_dwordx4 v164, v[194:197], s[54:55]
	s_waitcnt lgkmcnt(0)
	v_pk_add_f32 v[126:127], v[124:125], v[126:127]
	ds_bpermute_b32 v128, v131, v126
	ds_bpermute_b32 v129, v131, v127
	v_lshl_add_u64 v[124:125], s[58:59], 3, v[198:199]
	v_lshl_add_u64 v[124:125], v[124:125], 0, s[14:15]
	s_and_saveexec_b64 s[52:53], s[10:11]
	s_waitcnt lgkmcnt(0)
	v_pk_add_f32 v[126:127], v[126:127], v[128:129]
	global_store_dwordx2 v[124:125], v[126:127], off

; __device__ __forceinline__ u32x4 pack8f(f32x4 a, f32x4 b) { u32x4 w; w.x = cvt_pk_bf16(a[0], a[1]); w.y = cvt_pk_bf16(a[2], a[3]); w.z = cvt_pk_bf16(b[0], b[1]); w.w = cvt_pk_bf16(b[2], b[3]); return w; }
;     __device__ __forceinline__ void operator()(const f32x4 (&acc)[2][2][4][2], const Unit& u, int wr, int wc, int fr, int fq, const EpiCtx& X) const {
;     ...
;             for (int m = 0; m < 4; ++m) {
;                 const int rl = ai * HALF + m * 16; const unsigned off = lo + (unsigned)(rl * 64) * 2u;
;                 const f32x4 o0a = acc[ai][0][m][0], o0b = acc[ai][0][m][1], o1a = acc[ai][1][m][0], o1b = acc[ai][1][m][1];
;                 const f32x4 ra_ = dpp_swap1(odd ? o0a : o1a), rb_ = dpp_swap1(odd ? o0b : o1b);
;                 const f32x4 pa[2] = {odd ? ra_ : o0a, odd ? o1a : ra_}, pb[2] = {odd ? rb_ : o0b, odd ? o1b : rb_};
; #pragma unroll
;                 for (int q = 0; q < 2; ++q) {
;                     const u32x4 w0 = raw[2 * m + q];
;                     const f32x4 r0 = (f32x4){bf_lo(w0.x), bf_hi(w0.x), bf_lo(w0.y), bf_hi(w0.y)}, r1 = (f32x4){bf_lo(w0.z), bf_hi(w0.z), bf_lo(w0.w), bf_hi(w0.w)};
;                     f32x4 y0, y1;
;                     if (RESN) { const f32x2 t = tbl[rl + q]; const float mu = t.x, ra = t.y * ALPHA; y0 = (r0 - mu) * ra * g0 + b0 + pa[q]; y1 = (r1 - mu) * ra * g1 + b1 + pb[q]; }
;                     else { y0 = r0 * ALPHA + pa[q]; y1 = r1 * ALPHA + pb[q]; }
;                     { const u32x4 w = pack8f(y0, y1); *(u32x4*)(xb + off + q * 128) = w;
;                         y0 = (f32x4){bf_lo(w.x), bf_hi(w.x), bf_lo(w.y), bf_hi(w.y)}; y1 = (f32x4){bf_lo(w.z), bf_hi(w.z), bf_lo(w.w), bf_hi(w.w)}; }
;                     float sa = ((y0[0] + y0[1]) + (y0[2] + y0[3])) + ((y1[0] + y1[1]) + (y1[2] + y1[3]));
;                     float sb = ((y0[0] * y0[0] + y0[1] * y0[1]) + (y0[2] * y0[2] + y0[3] * y0[3])) + ((y1[0] * y1[0] + y1[1] * y1[1]) + (y1[2] * y1[2] + y1[3] * y1[3]));
;                     sa += dpp_x1(sa);
;                     sb += dpp_x1(sb);
;                     sa += __shfl_xor(sa, 16); sa += __shfl_xor(sa, 32); sb += __shfl_xor(sb, 16); sb += __shfl_xor(sb, 32);
;                     if (fq == 0 && !odd) ps[(size_t)(rl + q) * 64] = (f32x2){sa, sb};
.LBB0_586:
	s_or_b64 exec, exec, s[52:53]
	s_waitcnt lgkmcnt(1)
	v_cndmask_b32_e64 v114, v108, v100, s[8:9]
	s_nop 0
	v_cndmask_b32_e64 v113, v109, v101, s[8:9]
	s_waitcnt lgkmcnt(0)
	v_cndmask_b32_e64 v115, v110, v102, s[8:9]
	v_mov_b32_dpp v112, v114 quad_perm:[1,0,3,2] row_mask:0xf bank_mask:0xf
	s_nop 0
	v_cndmask_b32_e64 v116, v111, v103, s[8:9]
	v_cndmask_b32_e64 v118, v104, v96, s[8:9]
	v_mov_b32_dpp v114, v113 quad_perm:[1,0,3,2] row_mask:0xf bank_mask:0xf
	s_nop 0
	v_cndmask_b32_e64 v117, v105, v97, s[8:9]
	v_cndmask_b32_e64 v119, v106, v98, s[8:9]
	v_mov_b32_dpp v113, v115 quad_perm:[1,0,3,2] row_mask:0xf bank_mask:0xf
	s_nop 0
	v_cndmask_b32_e64 v126, v107, v99, s[8:9]
	v_cndmask_b32_e64 v109, v114, v109, s[8:9]
	v_mov_b32_dpp v115, v116 quad_perm:[1,0,3,2] row_mask:0xf bank_mask:0xf
	s_nop 0
	v_cndmask_b32_e64 v108, v112, v108, s[8:9]
	v_cndmask_b32_e64 v111, v115, v111, s[8:9]
	v_mov_b32_dpp v116, v118 quad_perm:[1,0,3,2] row_mask:0xf bank_mask:0xf
	s_nop 0
	v_cndmask_b32_e64 v110, v113, v110, s[8:9]
	v_cndmask_b32_e64 v104, v116, v104, s[8:9]
	v_mov_b32_dpp v118, v117 quad_perm:[1,0,3,2] row_mask:0xf bank_mask:0xf
	s_nop 0
	v_cndmask_b32_e64 v105, v118, v105, s[8:9]
	s_waitcnt vmcnt(13)
	v_and_b32_e32 v127, 0xffff0000, v148
	v_mov_b32_dpp v117, v119 quad_perm:[1,0,3,2] row_mask:0xf bank_mask:0xf
	s_nop 0
	v_cndmask_b32_e64 v106, v117, v106, s[8:9]
	v_lshlrev_b32_e32 v128, 16, v149
	v_mov_b32_dpp v119, v126 quad_perm:[1,0,3,2] row_mask:0xf bank_mask:0xf
	v_cndmask_b32_e64 v107, v119, v107, s[8:9]
	v_lshlrev_b32_e32 v126, 16, v148
	v_and_b32_e32 v129, 0xffff0000, v149
	v_lshlrev_b32_e32 v148, 16, v150
	v_and_b32_e32 v149, 0xffff0000, v150
	v_lshlrev_b32_e32 v150, 16, v151
	v_and_b32_e32 v151, 0xffff0000, v151
	v_pk_fma_f32 v[110:111], v[128:129], s[18:19], v[110:111] op_sel_hi:[1,0,1]
	v_pk_fma_f32 v[108:109], v[126:127], s[18:19], v[108:109] op_sel_hi:[1,0,1]
	v_pk_fma_f32 v[106:107], v[150:151], s[18:19], v[106:107] op_sel_hi:[1,0,1]
	v_pk_fma_f32 v[104:105], v[148:149], s[18:19], v[104:105] op_sel_hi:[1,0,1]
	v_cvt_pk_bf16_f32 v126, v108, v109
	v_cvt_pk_bf16_f32 v127, v110, v111
	v_mov_b32_e32 v181, v165
	v_cvt_pk_bf16_f32 v128, v104, v105
	v_cvt_pk_bf16_f32 v129, v106, v107
	v_lshlrev_b32_e32 v104, 16, v126
	v_and_b32_e32 v106, 0xffff0000, v126
	v_lshlrev_b32_e32 v108, 16, v127
	v_and_b32_e32 v110, 0xffff0000, v127
	v_lshlrev_b32_e32 v148, 16, v128
	v_and_b32_e32 v150, 0xffff0000, v128
	v_lshlrev_b32_e32 v152, 16, v129
	v_and_b32_e32 v154, 0xffff0000, v129
	v_mul_f32_e32 v105, v104, v104
	v_mul_f32_e32 v107, v106, v106
	v_mul_f32_e32 v109, v108, v108
	v_mul_f32_e32 v111, v110, v110
	v_mul_f32_e32 v149, v148, v148
	v_mul_f32_e32 v151, v150, v150
	v_mul_f32_e32 v153, v152, v152
	v_mul_f32_e32 v155, v154, v154
	v_pk_add_f32 v[104:105], v[104:105], v[106:107]
	v_pk_add_f32 v[106:107], v[108:109], v[110:111]
	v_pk_add_f32 v[108:109], v[152:153], v[154:155]
	v_pk_add_f32 v[104:105], v[104:105], v[106:107]
	v_pk_add_f32 v[106:107], v[148:149], v[150:151]
	s_nop 0
	v_pk_add_f32 v[106:107], v[106:107], v[108:109]
	s_nop 0
	v_pk_add_f32 v[104:105], v[104:105], v[106:107]
	v_mov_b32_e32 v106, v165
	v_mov_b32_e32 v107, v165
	s_nop 0
	v_mov_b32_dpp v106, v104 quad_perm:[1,0,3,2] row_mask:0xf bank_mask:0xf
	v_mov_b32_dpp v107, v105 quad_perm:[1,0,3,2] row_mask:0xf bank_mask:0xf
	v_pk_add_f32 v[104:105], v[104:105], v[106:107]
	ds_bpermute_b32 v106, v130, v104
	ds_bpermute_b32 v107, v130, v105
	s_waitcnt lgkmcnt(0)
	v_pk_add_f32 v[106:107], v[104:105], v[106:107]
	ds_bpermute_b32 v108, v131, v106
	ds_bpermute_b32 v109, v131, v107
	v_lshl_add_u64 v[104:105], s[54:55], 0, v[180:181]
	global_store_dwordx4 v[104:105], v[126:129], off
	s_and_saveexec_b64 s[56:57], s[10:11]
	s_waitcnt lgkmcnt(0)
	v_pk_add_f32 v[106:107], v[106:107], v[108:109]
	v_add_co_u32_e32 v108, vcc, 0x2000, v124
	s_nop 1
	v_addc_co_u32_e32 v109, vcc, 0, v125, vcc
	global_store_dwordx2 v[108:109], v[106:107], off

; __device__ __forceinline__ u32x4 pack8f(f32x4 a, f32x4 b) { u32x4 w; w.x = cvt_pk_bf16(a[0], a[1]); w.y = cvt_pk_bf16(a[2], a[3]); w.z = cvt_pk_bf16(b[0], b[1]); w.w = cvt_pk_bf16(b[2], b[3]); return w; }
;     __device__ __forceinline__ void operator()(const f32x4 (&acc)[2][2][4][2], const Unit& u, int wr, int wc, int fr, int fq, const EpiCtx& X) const {
;     ...
;             for (int m = 0; m < 4; ++m) {
;                 const int rl = ai * HALF + m * 16; const unsigned off = lo + (unsigned)(rl * 64) * 2u;
;                 const f32x4 o0a = acc[ai][0][m][0], o0b = acc[ai][0][m][1], o1a = acc[ai][1][m][0], o1b = acc[ai][1][m][1];
;                 const f32x4 ra_ = dpp_swap1(odd ? o0a : o1a), rb_ = dpp_swap1(odd ? o0b : o1b);
;                 const f32x4 pa[2] = {odd ? ra_ : o0a, odd ? o1a : ra_}, pb[2] = {odd ? rb_ : o0b, odd ? o1b : rb_};
; #pragma unroll
;                 for (int q = 0; q < 2; ++q) {
;                     const u32x4 w0 = raw[2 * m + q];
;                     const f32x4 r0 = (f32x4){bf_lo(w0.x), bf_hi(w0.x), bf_lo(w0.y), bf_hi(w0.y)}, r1 = (f32x4){bf_lo(w0.z), bf_hi(w0.z), bf_lo(w0.w), bf_hi(w0.w)};
;                     f32x4 y0, y1;
;                     if (RESN) { const f32x2 t = tbl[rl + q]; const float mu = t.x, ra = t.y * ALPHA; y0 = (r0 - mu) * ra * g0 + b0 + pa[q]; y1 = (r1 - mu) * ra * g1 + b1 + pb[q]; }
;                     else { y0 = r0 * ALPHA + pa[q]; y1 = r1 * ALPHA + pb[q]; }
;                     { const u32x4 w = pack8f(y0, y1); *(u32x4*)(xb + off + q * 128) = w;
;                         y0 = (f32x4){bf_lo(w.x), bf_hi(w.x), bf_lo(w.y), bf_hi(w.y)}; y1 = (f32x4){bf_lo(w.z), bf_hi(w.z), bf_lo(w.w), bf_hi(w.w)}; }
;                     float sa = ((y0[0] + y0[1]) + (y0[2] + y0[3])) + ((y1[0] + y1[1]) + (y1[2] + y1[3]));
;                     float sb = ((y0[0] * y0[0] + y0[1] * y0[1]) + (y0[2] * y0[2] + y0[3] * y0[3])) + ((y1[0] * y1[0] + y1[1] * y1[1]) + (y1[2] * y1[2] + y1[3] * y1[3]));
;                     sa += dpp_x1(sa);
;                     sb += dpp_x1(sb);
;                     sa += __shfl_xor(sa, 16); sa += __shfl_xor(sa, 32); sb += __shfl_xor(sb, 16); sb += __shfl_xor(sb, 32);
;                     if (fq == 0 && !odd) ps[(size_t)(rl + q) * 64] = (f32x2){sa, sb};
.LBB0_590:
	s_or_b64 exec, exec, s[56:57]
	s_waitcnt lgkmcnt(1)
	v_cndmask_b32_e64 v98, v92, v84, s[8:9]
	s_nop 0
	v_cndmask_b32_e64 v97, v93, v85, s[8:9]
	s_waitcnt lgkmcnt(0)
	v_cndmask_b32_e64 v99, v94, v86, s[8:9]
	v_mov_b32_dpp v96, v98 quad_perm:[1,0,3,2] row_mask:0xf bank_mask:0xf
	s_nop 0
	v_cndmask_b32_e64 v100, v95, v87, s[8:9]
	v_cndmask_b32_e64 v102, v88, v80, s[8:9]
	v_mov_b32_dpp v98, v97 quad_perm:[1,0,3,2] row_mask:0xf bank_mask:0xf
	s_nop 0
	v_cndmask_b32_e64 v101, v89, v81, s[8:9]
	v_cndmask_b32_e64 v103, v90, v82, s[8:9]
	v_mov_b32_dpp v97, v99 quad_perm:[1,0,3,2] row_mask:0xf bank_mask:0xf
	s_nop 0
	v_cndmask_b32_e64 v104, v91, v83, s[8:9]
	v_cndmask_b32_e64 v93, v98, v93, s[8:9]
	v_mov_b32_dpp v99, v100 quad_perm:[1,0,3,2] row_mask:0xf bank_mask:0xf
	s_nop 0
	v_cndmask_b32_e64 v92, v96, v92, s[8:9]
	v_cndmask_b32_e64 v95, v99, v95, s[8:9]
	v_mov_b32_dpp v100, v102 quad_perm:[1,0,3,2] row_mask:0xf bank_mask:0xf
	s_nop 0
	v_cndmask_b32_e64 v94, v97, v94, s[8:9]
	v_cndmask_b32_e64 v88, v100, v88, s[8:9]
	v_mov_b32_dpp v102, v101 quad_perm:[1,0,3,2] row_mask:0xf bank_mask:0xf
	s_nop 0
	v_cndmask_b32_e64 v89, v102, v89, s[8:9]
	s_waitcnt vmcnt(15)
	v_and_b32_e32 v105, 0xffff0000, v140
	v_mov_b32_dpp v101, v103 quad_perm:[1,0,3,2] row_mask:0xf bank_mask:0xf
	s_nop 0
	v_cndmask_b32_e64 v90, v101, v90, s[8:9]
	v_lshlrev_b32_e32 v106, 16, v141
	v_mov_b32_dpp v103, v104 quad_perm:[1,0,3,2] row_mask:0xf bank_mask:0xf
	v_cndmask_b32_e64 v91, v103, v91, s[8:9]
	v_lshlrev_b32_e32 v104, 16, v140
	v_and_b32_e32 v107, 0xffff0000, v141
	v_lshlrev_b32_e32 v108, 16, v142
	v_and_b32_e32 v109, 0xffff0000, v142
	v_lshlrev_b32_e32 v110, 16, v143
	v_and_b32_e32 v111, 0xffff0000, v143
	v_pk_fma_f32 v[94:95], v[106:107], s[18:19], v[94:95] op_sel_hi:[1,0,1]
	v_pk_fma_f32 v[92:93], v[104:105], s[18:19], v[92:93] op_sel_hi:[1,0,1]
	v_pk_fma_f32 v[90:91], v[110:111], s[18:19], v[90:91] op_sel_hi:[1,0,1]
	v_pk_fma_f32 v[88:89], v[108:109], s[18:19], v[88:89] op_sel_hi:[1,0,1]
	v_cvt_pk_bf16_f32 v104, v92, v93
	v_cvt_pk_bf16_f32 v105, v94, v95
	v_mov_b32_e32 v179, v165
	v_cvt_pk_bf16_f32 v106, v88, v89
	v_cvt_pk_bf16_f32 v107, v90, v91
	v_lshlrev_b32_e32 v88, 16, v104
	v_and_b32_e32 v90, 0xffff0000, v104
	v_lshlrev_b32_e32 v92, 16, v105
	v_and_b32_e32 v94, 0xffff0000, v105
	v_lshlrev_b32_e32 v108, 16, v106
	v_and_b32_e32 v110, 0xffff0000, v106
	v_lshlrev_b32_e32 v112, 16, v107
	v_and_b32_e32 v114, 0xffff0000, v107
	v_mul_f32_e32 v89, v88, v88
	v_mul_f32_e32 v91, v90, v90
	v_mul_f32_e32 v93, v92, v92
	v_mul_f32_e32 v95, v94, v94
	v_mul_f32_e32 v109, v108, v108
	v_mul_f32_e32 v111, v110, v110
	v_mul_f32_e32 v113, v112, v112
	v_mul_f32_e32 v115, v114, v114
	v_pk_add_f32 v[88:89], v[88:89], v[90:91]
	v_pk_add_f32 v[90:91], v[92:93], v[94:95]
	v_pk_add_f32 v[92:93], v[112:113], v[114:115]
	v_pk_add_f32 v[88:89], v[88:89], v[90:91]
	v_pk_add_f32 v[90:91], v[108:109], v[110:111]
	s_nop 0
	v_pk_add_f32 v[90:91], v[90:91], v[92:93]
	s_nop 0
	v_pk_add_f32 v[88:89], v[88:89], v[90:91]
	v_mov_b32_e32 v90, v165
	v_mov_b32_e32 v91, v165
	s_nop 0
	v_mov_b32_dpp v90, v88 quad_perm:[1,0,3,2] row_mask:0xf bank_mask:0xf
	v_mov_b32_dpp v91, v89 quad_perm:[1,0,3,2] row_mask:0xf bank_mask:0xf
	v_pk_add_f32 v[88:89], v[88:89], v[90:91]
	ds_bpermute_b32 v90, v130, v88
	ds_bpermute_b32 v91, v130, v89
	s_waitcnt lgkmcnt(0)
	v_pk_add_f32 v[90:91], v[88:89], v[90:91]
	ds_bpermute_b32 v92, v131, v90
	ds_bpermute_b32 v93, v131, v91
	v_lshl_add_u64 v[88:89], s[54:55], 0, v[178:179]
	global_store_dwordx4 v[88:89], v[104:107], off
	s_and_saveexec_b64 s[56:57], s[10:11]
	s_waitcnt lgkmcnt(0)
	v_pk_add_f32 v[90:91], v[90:91], v[92:93]
	v_add_co_u32_e32 v92, vcc, 0x4000, v124
	s_nop 1
	v_addc_co_u32_e32 v93, vcc, 0, v125, vcc
	global_store_dwordx2 v[92:93], v[90:91], off

; __device__ __forceinline__ u32x4 pack8f(f32x4 a, f32x4 b) { u32x4 w; w.x = cvt_pk_bf16(a[0], a[1]); w.y = cvt_pk_bf16(a[2], a[3]); w.z = cvt_pk_bf16(b[0], b[1]); w.w = cvt_pk_bf16(b[2], b[3]); return w; }
;     __device__ __forceinline__ void operator()(const f32x4 (&acc)[2][2][4][2], const Unit& u, int wr, int wc, int fr, int fq, const EpiCtx& X) const {
;     ...
;             for (int m = 0; m < 4; ++m) {
;                 const int rl = ai * HALF + m * 16; const unsigned off = lo + (unsigned)(rl * 64) * 2u;
;                 const f32x4 o0a = acc[ai][0][m][0], o0b = acc[ai][0][m][1], o1a = acc[ai][1][m][0], o1b = acc[ai][1][m][1];
;                 const f32x4 ra_ = dpp_swap1(odd ? o0a : o1a), rb_ = dpp_swap1(odd ? o0b : o1b);
;                 const f32x4 pa[2] = {odd ? ra_ : o0a, odd ? o1a : ra_}, pb[2] = {odd ? rb_ : o0b, odd ? o1b : rb_};
; #pragma unroll
;                 for (int q = 0; q < 2; ++q) {
;                     const u32x4 w0 = raw[2 * m + q];
;                     const f32x4 r0 = (f32x4){bf_lo(w0.x), bf_hi(w0.x), bf_lo(w0.y), bf_hi(w0.y)}, r1 = (f32x4){bf_lo(w0.z), bf_hi(w0.z), bf_lo(w0.w), bf_hi(w0.w)};
;                     f32x4 y0, y1;
;                     if (RESN) { const f32x2 t = tbl[rl + q]; const float mu = t.x, ra = t.y * ALPHA; y0 = (r0 - mu) * ra * g0 + b0 + pa[q]; y1 = (r1 - mu) * ra * g1 + b1 + pb[q]; }
;                     else { y0 = r0 * ALPHA + pa[q]; y1 = r1 * ALPHA + pb[q]; }
;                     { const u32x4 w = pack8f(y0, y1); *(u32x4*)(xb + off + q * 128) = w;
;                         y0 = (f32x4){bf_lo(w.x), bf_hi(w.x), bf_lo(w.y), bf_hi(w.y)}; y1 = (f32x4){bf_lo(w.z), bf_hi(w.z), bf_lo(w.w), bf_hi(w.w)}; }
;                     float sa = ((y0[0] + y0[1]) + (y0[2] + y0[3])) + ((y1[0] + y1[1]) + (y1[2] + y1[3]));
;                     float sb = ((y0[0] * y0[0] + y0[1] * y0[1]) + (y0[2] * y0[2] + y0[3] * y0[3])) + ((y1[0] * y1[0] + y1[1] * y1[1]) + (y1[2] * y1[2] + y1[3] * y1[3]));
;                     sa += dpp_x1(sa);
;                     sb += dpp_x1(sb);
;                     sa += __shfl_xor(sa, 16); sa += __shfl_xor(sa, 32); sb += __shfl_xor(sb, 16); sb += __shfl_xor(sb, 32);
;                     if (fq == 0 && !odd) ps[(size_t)(rl + q) * 64] = (f32x2){sa, sb};
.LBB0_594:
	s_or_b64 exec, exec, s[56:57]
	s_waitcnt lgkmcnt(1)
	v_cndmask_b32_e64 v82, v76, v68, s[8:9]
	s_nop 0
	v_cndmask_b32_e64 v81, v77, v69, s[8:9]
	s_waitcnt lgkmcnt(0)
	v_cndmask_b32_e64 v83, v78, v70, s[8:9]
	v_mov_b32_dpp v80, v82 quad_perm:[1,0,3,2] row_mask:0xf bank_mask:0xf
	s_nop 0
	v_cndmask_b32_e64 v84, v79, v71, s[8:9]
	v_cndmask_b32_e64 v86, v72, v64, s[8:9]
	v_mov_b32_dpp v82, v81 quad_perm:[1,0,3,2] row_mask:0xf bank_mask:0xf
	s_nop 0
	v_cndmask_b32_e64 v85, v73, v65, s[8:9]
	v_cndmask_b32_e64 v87, v74, v66, s[8:9]
	v_mov_b32_dpp v81, v83 quad_perm:[1,0,3,2] row_mask:0xf bank_mask:0xf
	s_nop 0
	v_cndmask_b32_e64 v88, v75, v67, s[8:9]
	v_cndmask_b32_e64 v77, v82, v77, s[8:9]
	v_mov_b32_dpp v83, v84 quad_perm:[1,0,3,2] row_mask:0xf bank_mask:0xf
	s_nop 0
	v_cndmask_b32_e64 v76, v80, v76, s[8:9]
	v_cndmask_b32_e64 v79, v83, v79, s[8:9]
	v_mov_b32_dpp v84, v86 quad_perm:[1,0,3,2] row_mask:0xf bank_mask:0xf
	s_nop 0
	v_cndmask_b32_e64 v78, v81, v78, s[8:9]
	v_cndmask_b32_e64 v72, v84, v72, s[8:9]
	v_mov_b32_dpp v86, v85 quad_perm:[1,0,3,2] row_mask:0xf bank_mask:0xf
	s_nop 0
	v_cndmask_b32_e64 v73, v86, v73, s[8:9]
	s_waitcnt vmcnt(17)
	v_and_b32_e32 v89, 0xffff0000, v132
	v_mov_b32_dpp v85, v87 quad_perm:[1,0,3,2] row_mask:0xf bank_mask:0xf
	s_nop 0
	v_cndmask_b32_e64 v74, v85, v74, s[8:9]
	v_lshlrev_b32_e32 v90, 16, v133
	v_mov_b32_dpp v87, v88 quad_perm:[1,0,3,2] row_mask:0xf bank_mask:0xf
	v_cndmask_b32_e64 v75, v87, v75, s[8:9]
	v_lshlrev_b32_e32 v88, 16, v132
	v_and_b32_e32 v91, 0xffff0000, v133
	v_lshlrev_b32_e32 v92, 16, v134
	v_and_b32_e32 v93, 0xffff0000, v134
	v_lshlrev_b32_e32 v94, 16, v135
	v_and_b32_e32 v95, 0xffff0000, v135
	v_pk_fma_f32 v[78:79], v[90:91], s[18:19], v[78:79] op_sel_hi:[1,0,1]
	v_pk_fma_f32 v[76:77], v[88:89], s[18:19], v[76:77] op_sel_hi:[1,0,1]
	v_pk_fma_f32 v[74:75], v[94:95], s[18:19], v[74:75] op_sel_hi:[1,0,1]
	v_pk_fma_f32 v[72:73], v[92:93], s[18:19], v[72:73] op_sel_hi:[1,0,1]
	v_cvt_pk_bf16_f32 v88, v76, v77
	v_cvt_pk_bf16_f32 v89, v78, v79
	v_mov_b32_e32 v177, v165
	v_cvt_pk_bf16_f32 v90, v72, v73
	v_cvt_pk_bf16_f32 v91, v74, v75
	v_lshlrev_b32_e32 v72, 16, v88
	v_and_b32_e32 v74, 0xffff0000, v88
	v_lshlrev_b32_e32 v76, 16, v89
	v_and_b32_e32 v78, 0xffff0000, v89
	v_lshlrev_b32_e32 v92, 16, v90
	v_and_b32_e32 v94, 0xffff0000, v90
	v_lshlrev_b32_e32 v96, 16, v91
	v_and_b32_e32 v98, 0xffff0000, v91
	v_mul_f32_e32 v73, v72, v72
	v_mul_f32_e32 v75, v74, v74
	v_mul_f32_e32 v77, v76, v76
	v_mul_f32_e32 v79, v78, v78
	v_mul_f32_e32 v93, v92, v92
	v_mul_f32_e32 v95, v94, v94
	v_mul_f32_e32 v97, v96, v96
	v_mul_f32_e32 v99, v98, v98
	v_pk_add_f32 v[72:73], v[72:73], v[74:75]
	v_pk_add_f32 v[74:75], v[76:77], v[78:79]
	v_pk_add_f32 v[76:77], v[96:97], v[98:99]
	v_pk_add_f32 v[72:73], v[72:73], v[74:75]
	v_pk_add_f32 v[74:75], v[92:93], v[94:95]
	s_nop 0
	v_pk_add_f32 v[74:75], v[74:75], v[76:77]
	s_nop 0
	v_pk_add_f32 v[72:73], v[72:73], v[74:75]
	v_mov_b32_e32 v74, v165
	v_mov_b32_e32 v75, v165
	s_nop 0
	v_mov_b32_dpp v74, v72 quad_perm:[1,0,3,2] row_mask:0xf bank_mask:0xf
	v_mov_b32_dpp v75, v73 quad_perm:[1,0,3,2] row_mask:0xf bank_mask:0xf
	v_pk_add_f32 v[72:73], v[72:73], v[74:75]
	ds_bpermute_b32 v74, v130, v72
	ds_bpermute_b32 v75, v130, v73
	s_waitcnt lgkmcnt(0)
	v_pk_add_f32 v[74:75], v[72:73], v[74:75]
	ds_bpermute_b32 v76, v131, v74
	ds_bpermute_b32 v77, v131, v75
	v_lshl_add_u64 v[72:73], s[54:55], 0, v[176:177]
	global_store_dwordx4 v[72:73], v[88:91], off
	s_and_saveexec_b64 s[56:57], s[10:11]
	s_waitcnt lgkmcnt(0)
	v_pk_add_f32 v[74:75], v[74:75], v[76:77]
	v_add_co_u32_e32 v76, vcc, 0x6000, v124
	s_nop 1
	v_addc_co_u32_e32 v77, vcc, 0, v125, vcc
	global_store_dwordx2 v[76:77], v[74:75], off

;     __device__ __forceinline__ void operator()(const f32x4 (&acc)[2][2][4][2], const Unit& u, int wr, int wc, int fr, int fq, const EpiCtx& X) const {
;     ...
;             for (int m = 0; m < 4; ++m) { const unsigned off = lo + (unsigned)((ai * HALF + m * 16) * 64) * 2u; raw[2 * m] = *(const u32x4*)(xb + off); raw[2 * m + 1] = *(const u32x4*)(xb + off + 128); }
; #pragma unroll
;             for (int m = 0; m < 4; ++m) {
;                 const int rl = ai * HALF + m * 16; const unsigned off = lo + (unsigned)(rl * 64) * 2u;
;                 const f32x4 o0a = acc[ai][0][m][0], o0b = acc[ai][0][m][1], o1a = acc[ai][1][m][0], o1b = acc[ai][1][m][1];
;                 const f32x4 ra_ = dpp_swap1(odd ? o0a : o1a), rb_ = dpp_swap1(odd ? o0b : o1b);
;                 const f32x4 pa[2] = {odd ? ra_ : o0a, odd ? o1a : ra_}, pb[2] = {odd ? rb_ : o0b, odd ? o1b : rb_};
; #pragma unroll
;                 for (int q = 0; q < 2; ++q) {
;                     const u32x4 w0 = raw[2 * m + q];
;                     const f32x4 r0 = (f32x4){bf_lo(w0.x), bf_hi(w0.x), bf_lo(w0.y), bf_hi(w0.y)}, r1 = (f32x4){bf_lo(w0.z), bf_hi(w0.z), bf_lo(w0.w), bf_hi(w0.w)};
;                     f32x4 y0, y1;
;                     if (RESN) { const f32x2 t = tbl[rl + q]; const float mu = t.x, ra = t.y * ALPHA; y0 = (r0 - mu) * ra * g0 + b0 + pa[q]; y1 = (r1 - mu) * ra * g1 + b1 + pb[q]; }
;                     else { y0 = r0 * ALPHA + pa[q]; y1 = r1 * ALPHA + pb[q]; }
;                     { const u32x4 w = pack8f(y0, y1); *(u32x4*)(xb + off + q * 128) = w;
;                         y0 = (f32x4){bf_lo(w.x), bf_hi(w.x), bf_lo(w.y), bf_hi(w.y)}; y1 = (f32x4){bf_lo(w.z), bf_hi(w.z), bf_lo(w.w), bf_hi(w.w)}; }
;                     float sa = ((y0[0] + y0[1]) + (y0[2] + y0[3])) + ((y1[0] + y1[1]) + (y1[2] + y1[3]));
;                     float sb = ((y0[0] * y0[0] + y0[1] * y0[1]) + (y0[2] * y0[2] + y0[3] * y0[3])) + ((y1[0] * y1[0] + y1[1] * y1[1]) + (y1[2] * y1[2] + y1[3] * y1[3]));
;                     sa += dpp_x1(sa);
;                     sb += dpp_x1(sb);
;                     sa += __shfl_xor(sa, 16); sa += __shfl_xor(sa, 32); sb += __shfl_xor(sb, 16); sb += __shfl_xor(sb, 32);
;                     if (fq == 0 && !odd) ps[(size_t)(rl + q) * 64] = (f32x2){sa, sb};
.LBB0_598:
	s_or_b64 exec, exec, s[56:57]
	v_add_u32_e32 v96, 0x4000, v164
	s_waitcnt vmcnt(16)
	v_mov_b32_e32 v104, v230
	v_mov_b32_e32 v105, v231
	v_mov_b32_e32 v106, v232
	v_mov_b32_e32 v107, v233
	v_add_u32_e32 v94, 0x4800, v164
	v_add_u32_e32 v92, 0x5000, v164
	v_add_u32_e32 v164, 0x5800, v164
	v_mov_b32_e32 v88, v234
	v_mov_b32_e32 v89, v235
	v_mov_b32_e32 v90, v236
	v_mov_b32_e32 v91, v237
	v_mov_b32_e32 v84, v238
	v_mov_b32_e32 v85, v239
	v_mov_b32_e32 v86, v240
	v_mov_b32_e32 v87, v241
	v_mov_b32_e32 v80, v242
	v_mov_b32_e32 v81, v243
	v_mov_b32_e32 v82, v244
	v_mov_b32_e32 v83, v245
	global_load_dwordx4 v[76:79], v92, s[54:55]
	global_load_dwordx4 v[72:75], v92, s[54:55] offset:128
	global_load_dwordx4 v[68:71], v164, s[54:55]
	s_waitcnt lgkmcnt(0)
	global_load_dwordx4 v[64:67], v164, s[54:55] offset:128
	v_cndmask_b32_e64 v103, v63, v55, s[8:9]
	v_cndmask_b32_e64 v110, v62, v54, s[8:9]
	v_cndmask_b32_e64 v111, v61, v53, s[8:9]
	v_cndmask_b32_e64 v112, v60, v52, s[8:9]
	s_nop 0
	s_nop 0
	s_nop 0
	s_nop 0
	v_cndmask_b32_e64 v113, v59, v51, s[8:9]
	v_cndmask_b32_e64 v114, v58, v50, s[8:9]
	v_cndmask_b32_e64 v115, v57, v49, s[8:9]
	v_cndmask_b32_e64 v116, v56, v48, s[8:9]
	s_nop 0
	s_nop 0
	s_nop 0
	s_nop 0
	v_mov_b32_dpp v93, v112 quad_perm:[1,0,3,2] row_mask:0xf bank_mask:0xf
	v_mov_b32_dpp v97, v111 quad_perm:[1,0,3,2] row_mask:0xf bank_mask:0xf
	v_mov_b32_dpp v95, v110 quad_perm:[1,0,3,2] row_mask:0xf bank_mask:0xf
	v_mov_b32_dpp v98, v103 quad_perm:[1,0,3,2] row_mask:0xf bank_mask:0xf
	v_mov_b32_dpp v99, v116 quad_perm:[1,0,3,2] row_mask:0xf bank_mask:0xf
	v_mov_b32_dpp v101, v115 quad_perm:[1,0,3,2] row_mask:0xf bank_mask:0xf
	v_mov_b32_dpp v100, v114 quad_perm:[1,0,3,2] row_mask:0xf bank_mask:0xf
	v_mov_b32_dpp v102, v113 quad_perm:[1,0,3,2] row_mask:0xf bank_mask:0xf
	v_cndmask_b32_e64 v61, v97, v61, s[8:9]
	v_cndmask_b32_e64 v60, v93, v60, s[8:9]
	v_cndmask_b32_e64 v63, v98, v63, s[8:9]
	v_cndmask_b32_e64 v62, v95, v62, s[8:9]
	v_cndmask_b32_e64 v57, v101, v57, s[8:9]
	v_cndmask_b32_e64 v56, v99, v56, s[8:9]
	v_cndmask_b32_e64 v59, v102, v59, s[8:9]
	v_cndmask_b32_e64 v58, v100, v58, s[8:9]
	v_mov_b32_e32 v108, v165
	v_mov_b32_e32 v109, v165
	v_lshlrev_b32_e32 v110, 16, v104
	v_and_b32_e32 v111, 0xffff0000, v104
	v_lshlrev_b32_e32 v104, 16, v105
	v_and_b32_e32 v105, 0xffff0000, v105
	v_lshlrev_b32_e32 v112, 16, v106
	v_and_b32_e32 v113, 0xffff0000, v106
	v_lshlrev_b32_e32 v106, 16, v107
	v_and_b32_e32 v107, 0xffff0000, v107
	v_pk_fma_f32 v[62:63], v[104:105], s[18:19], v[62:63] op_sel_hi:[1,0,1]
	v_pk_fma_f32 v[60:61], v[110:111], s[18:19], v[60:61] op_sel_hi:[1,0,1]
	v_pk_fma_f32 v[58:59], v[106:107], s[18:19], v[58:59] op_sel_hi:[1,0,1]
	v_pk_fma_f32 v[56:57], v[112:113], s[18:19], v[56:57] op_sel_hi:[1,0,1]
	v_cvt_pk_bf16_f32 v60, v60, v61
	v_cvt_pk_bf16_f32 v61, v62, v63
	s_nop 0
	v_cvt_pk_bf16_f32 v62, v56, v57
	v_cvt_pk_bf16_f32 v63, v58, v59
	v_lshlrev_b32_e32 v56, 16, v60
	v_and_b32_e32 v58, 0xffff0000, v60
	v_lshlrev_b32_e32 v104, 16, v61
	v_and_b32_e32 v106, 0xffff0000, v61
	v_lshlrev_b32_e32 v110, 16, v62
	v_and_b32_e32 v112, 0xffff0000, v62
	v_lshlrev_b32_e32 v114, 16, v63
	v_and_b32_e32 v116, 0xffff0000, v63
	v_mul_f32_e32 v57, v56, v56
	v_mul_f32_e32 v59, v58, v58
	v_mul_f32_e32 v105, v104, v104
	v_mul_f32_e32 v107, v106, v106
	v_mul_f32_e32 v111, v110, v110
	v_mul_f32_e32 v113, v112, v112
	v_mul_f32_e32 v115, v114, v114
	v_mul_f32_e32 v117, v116, v116
	v_pk_add_f32 v[56:57], v[56:57], v[58:59]
	v_pk_add_f32 v[58:59], v[104:105], v[106:107]
	v_pk_add_f32 v[104:105], v[110:111], v[112:113]
	v_pk_add_f32 v[106:107], v[114:115], v[116:117]
	v_pk_add_f32 v[56:57], v[56:57], v[58:59]
	v_pk_add_f32 v[58:59], v[104:105], v[106:107]
	global_store_dwordx4 v96, v[60:63], s[54:55]
	v_pk_add_f32 v[56:57], v[56:57], v[58:59]
	s_nop 1
	v_mov_b32_dpp v108, v56 quad_perm:[1,0,3,2] row_mask:0xf bank_mask:0xf
	v_mov_b32_dpp v109, v57 quad_perm:[1,0,3,2] row_mask:0xf bank_mask:0xf
	v_pk_add_f32 v[56:57], v[56:57], v[108:109]
	ds_bpermute_b32 v58, v130, v56
	ds_bpermute_b32 v59, v130, v57
	s_waitcnt lgkmcnt(0)
	v_pk_add_f32 v[56:57], v[56:57], v[58:59]
	ds_bpermute_b32 v58, v131, v56
	ds_bpermute_b32 v59, v131, v57
	s_and_saveexec_b64 s[56:57], s[10:11]
	s_cbranch_execz .LBB0_600
	s_waitcnt lgkmcnt(0)
	v_pk_add_f32 v[56:57], v[56:57], v[58:59]
	v_add_co_u32_e32 v58, vcc, 0x10000, v124
	s_nop 1
	v_addc_co_u32_e32 v59, vcc, 0, v125, vcc
	global_store_dwordx2 v[58:59], v[56:57], off

; __device__ __forceinline__ u32x4 pack8f(f32x4 a, f32x4 b) { u32x4 w; w.x = cvt_pk_bf16(a[0], a[1]); w.y = cvt_pk_bf16(a[2], a[3]); w.z = cvt_pk_bf16(b[0], b[1]); w.w = cvt_pk_bf16(b[2], b[3]); return w; }
;     __device__ __forceinline__ void operator()(const f32x4 (&acc)[2][2][4][2], const Unit& u, int wr, int wc, int fr, int fq, const EpiCtx& X) const {
;     ...
;             for (int m = 0; m < 4; ++m) {
;                 const int rl = ai * HALF + m * 16; const unsigned off = lo + (unsigned)(rl * 64) * 2u;
;                 const f32x4 o0a = acc[ai][0][m][0], o0b = acc[ai][0][m][1], o1a = acc[ai][1][m][0], o1b = acc[ai][1][m][1];
;                 const f32x4 ra_ = dpp_swap1(odd ? o0a : o1a), rb_ = dpp_swap1(odd ? o0b : o1b);
;                 const f32x4 pa[2] = {odd ? ra_ : o0a, odd ? o1a : ra_}, pb[2] = {odd ? rb_ : o0b, odd ? o1b : rb_};
; #pragma unroll
;                 for (int q = 0; q < 2; ++q) {
;                     const u32x4 w0 = raw[2 * m + q];
;                     const f32x4 r0 = (f32x4){bf_lo(w0.x), bf_hi(w0.x), bf_lo(w0.y), bf_hi(w0.y)}, r1 = (f32x4){bf_lo(w0.z), bf_hi(w0.z), bf_lo(w0.w), bf_hi(w0.w)};
;                     f32x4 y0, y1;
;                     if (RESN) { const f32x2 t = tbl[rl + q]; const float mu = t.x, ra = t.y * ALPHA; y0 = (r0 - mu) * ra * g0 + b0 + pa[q]; y1 = (r1 - mu) * ra * g1 + b1 + pb[q]; }
;                     else { y0 = r0 * ALPHA + pa[q]; y1 = r1 * ALPHA + pb[q]; }
;                     { const u32x4 w = pack8f(y0, y1); *(u32x4*)(xb + off + q * 128) = w;
;                         y0 = (f32x4){bf_lo(w.x), bf_hi(w.x), bf_lo(w.y), bf_hi(w.y)}; y1 = (f32x4){bf_lo(w.z), bf_hi(w.z), bf_lo(w.w), bf_hi(w.w)}; }
;                     float sa = ((y0[0] + y0[1]) + (y0[2] + y0[3])) + ((y1[0] + y1[1]) + (y1[2] + y1[3]));
;                     float sb = ((y0[0] * y0[0] + y0[1] * y0[1]) + (y0[2] * y0[2] + y0[3] * y0[3])) + ((y1[0] * y1[0] + y1[1] * y1[1]) + (y1[2] * y1[2] + y1[3] * y1[3]));
;                     sa += dpp_x1(sa);
;                     sb += dpp_x1(sb);
;                     sa += __shfl_xor(sa, 16); sa += __shfl_xor(sa, 32); sb += __shfl_xor(sb, 16); sb += __shfl_xor(sb, 32);
;                     if (fq == 0 && !odd) ps[(size_t)(rl + q) * 64] = (f32x2){sa, sb};
.LBB0_602:
	s_or_b64 exec, exec, s[56:57]
	s_waitcnt lgkmcnt(1)
	v_cndmask_b32_e64 v50, v44, v36, s[8:9]
	s_nop 0
	v_cndmask_b32_e64 v49, v45, v37, s[8:9]
	s_waitcnt lgkmcnt(0)
	v_cndmask_b32_e64 v51, v46, v38, s[8:9]
	v_mov_b32_dpp v48, v50 quad_perm:[1,0,3,2] row_mask:0xf bank_mask:0xf
	s_nop 0
	v_cndmask_b32_e64 v52, v47, v39, s[8:9]
	v_cndmask_b32_e64 v54, v40, v32, s[8:9]
	v_mov_b32_dpp v50, v49 quad_perm:[1,0,3,2] row_mask:0xf bank_mask:0xf
	s_nop 0
	v_cndmask_b32_e64 v53, v41, v33, s[8:9]
	v_cndmask_b32_e64 v55, v42, v34, s[8:9]
	v_mov_b32_dpp v49, v51 quad_perm:[1,0,3,2] row_mask:0xf bank_mask:0xf
	s_nop 0
	v_cndmask_b32_e64 v56, v43, v35, s[8:9]
	v_cndmask_b32_e64 v45, v50, v45, s[8:9]
	v_mov_b32_dpp v51, v52 quad_perm:[1,0,3,2] row_mask:0xf bank_mask:0xf
	s_nop 0
	v_cndmask_b32_e64 v44, v48, v44, s[8:9]
	v_cndmask_b32_e64 v47, v51, v47, s[8:9]
	v_mov_b32_dpp v52, v54 quad_perm:[1,0,3,2] row_mask:0xf bank_mask:0xf
	s_nop 0
	v_cndmask_b32_e64 v46, v49, v46, s[8:9]
	v_cndmask_b32_e64 v40, v52, v40, s[8:9]
	v_mov_b32_dpp v54, v53 quad_perm:[1,0,3,2] row_mask:0xf bank_mask:0xf
	s_nop 0
	v_cndmask_b32_e64 v41, v54, v41, s[8:9]
	v_and_b32_e32 v57, 0xffff0000, v84
	v_mov_b32_dpp v53, v55 quad_perm:[1,0,3,2] row_mask:0xf bank_mask:0xf
	s_nop 0
	v_cndmask_b32_e64 v42, v53, v42, s[8:9]
	v_lshlrev_b32_e32 v58, 16, v85
	v_mov_b32_dpp v55, v56 quad_perm:[1,0,3,2] row_mask:0xf bank_mask:0xf
	v_cndmask_b32_e64 v43, v55, v43, s[8:9]
	v_lshlrev_b32_e32 v56, 16, v84
	v_and_b32_e32 v59, 0xffff0000, v85
	v_lshlrev_b32_e32 v60, 16, v86
	v_and_b32_e32 v61, 0xffff0000, v86
	v_lshlrev_b32_e32 v62, 16, v87
	v_and_b32_e32 v63, 0xffff0000, v87
	v_pk_fma_f32 v[46:47], v[58:59], s[18:19], v[46:47] op_sel_hi:[1,0,1]
	v_pk_fma_f32 v[44:45], v[56:57], s[18:19], v[44:45] op_sel_hi:[1,0,1]
	v_pk_fma_f32 v[42:43], v[62:63], s[18:19], v[42:43] op_sel_hi:[1,0,1]
	v_pk_fma_f32 v[40:41], v[60:61], s[18:19], v[40:41] op_sel_hi:[1,0,1]
	v_cvt_pk_bf16_f32 v56, v44, v45
	v_cvt_pk_bf16_f32 v57, v46, v47
	v_mov_b32_e32 v95, v165
	v_cvt_pk_bf16_f32 v58, v40, v41
	v_cvt_pk_bf16_f32 v59, v42, v43
	v_lshlrev_b32_e32 v40, 16, v56
	v_and_b32_e32 v42, 0xffff0000, v56
	v_lshlrev_b32_e32 v44, 16, v57
	v_and_b32_e32 v46, 0xffff0000, v57
	v_lshlrev_b32_e32 v60, 16, v58
	v_and_b32_e32 v62, 0xffff0000, v58
	v_lshlrev_b32_e32 v84, 16, v59
	v_and_b32_e32 v86, 0xffff0000, v59
	v_mul_f32_e32 v41, v40, v40
	v_mul_f32_e32 v43, v42, v42
	v_mul_f32_e32 v45, v44, v44
	v_mul_f32_e32 v47, v46, v46
	v_mul_f32_e32 v61, v60, v60
	v_mul_f32_e32 v63, v62, v62
	v_mul_f32_e32 v85, v84, v84
	v_mul_f32_e32 v87, v86, v86
	v_pk_add_f32 v[40:41], v[40:41], v[42:43]
	v_pk_add_f32 v[42:43], v[44:45], v[46:47]
	v_pk_add_f32 v[44:45], v[84:85], v[86:87]
	v_pk_add_f32 v[40:41], v[40:41], v[42:43]
	v_pk_add_f32 v[42:43], v[60:61], v[62:63]
	s_nop 0
	v_pk_add_f32 v[42:43], v[42:43], v[44:45]
	s_nop 0
	v_pk_add_f32 v[40:41], v[40:41], v[42:43]
	v_mov_b32_e32 v42, v165
	v_mov_b32_e32 v43, v165
	s_nop 0
	v_mov_b32_dpp v42, v40 quad_perm:[1,0,3,2] row_mask:0xf bank_mask:0xf
	v_mov_b32_dpp v43, v41 quad_perm:[1,0,3,2] row_mask:0xf bank_mask:0xf
	v_pk_add_f32 v[40:41], v[40:41], v[42:43]
	ds_bpermute_b32 v42, v130, v40
	ds_bpermute_b32 v43, v130, v41
	s_waitcnt lgkmcnt(0)
	v_pk_add_f32 v[42:43], v[40:41], v[42:43]
	ds_bpermute_b32 v44, v131, v42
	ds_bpermute_b32 v45, v131, v43
	v_lshl_add_u64 v[40:41], s[54:55], 0, v[94:95]
	global_store_dwordx4 v[40:41], v[56:59], off
	s_and_saveexec_b64 s[56:57], s[10:11]
	s_cbranch_execz .LBB0_604
	s_waitcnt lgkmcnt(0)
	v_pk_add_f32 v[42:43], v[42:43], v[44:45]
	v_add_co_u32_e32 v44, vcc, 0x12000, v124
	s_nop 1
	v_addc_co_u32_e32 v45, vcc, 0, v125, vcc
	global_store_dwordx2 v[44:45], v[42:43], off

; __device__ __forceinline__ u32x4 pack8f(f32x4 a, f32x4 b) { u32x4 w; w.x = cvt_pk_bf16(a[0], a[1]); w.y = cvt_pk_bf16(a[2], a[3]); w.z = cvt_pk_bf16(b[0], b[1]); w.w = cvt_pk_bf16(b[2], b[3]); return w; }
;     __device__ __forceinline__ void operator()(const f32x4 (&acc)[2][2][4][2], const Unit& u, int wr, int wc, int fr, int fq, const EpiCtx& X) const {
;     ...
;             for (int m = 0; m < 4; ++m) {
;                 const int rl = ai * HALF + m * 16; const unsigned off = lo + (unsigned)(rl * 64) * 2u;
;                 const f32x4 o0a = acc[ai][0][m][0], o0b = acc[ai][0][m][1], o1a = acc[ai][1][m][0], o1b = acc[ai][1][m][1];
;                 const f32x4 ra_ = dpp_swap1(odd ? o0a : o1a), rb_ = dpp_swap1(odd ? o0b : o1b);
;                 const f32x4 pa[2] = {odd ? ra_ : o0a, odd ? o1a : ra_}, pb[2] = {odd ? rb_ : o0b, odd ? o1b : rb_};
; #pragma unroll
;                 for (int q = 0; q < 2; ++q) {
;                     const u32x4 w0 = raw[2 * m + q];
;                     const f32x4 r0 = (f32x4){bf_lo(w0.x), bf_hi(w0.x), bf_lo(w0.y), bf_hi(w0.y)}, r1 = (f32x4){bf_lo(w0.z), bf_hi(w0.z), bf_lo(w0.w), bf_hi(w0.w)};
;                     f32x4 y0, y1;
;                     if (RESN) { const f32x2 t = tbl[rl + q]; const float mu = t.x, ra = t.y * ALPHA; y0 = (r0 - mu) * ra * g0 + b0 + pa[q]; y1 = (r1 - mu) * ra * g1 + b1 + pb[q]; }
;                     else { y0 = r0 * ALPHA + pa[q]; y1 = r1 * ALPHA + pb[q]; }
;                     { const u32x4 w = pack8f(y0, y1); *(u32x4*)(xb + off + q * 128) = w;
;                         y0 = (f32x4){bf_lo(w.x), bf_hi(w.x), bf_lo(w.y), bf_hi(w.y)}; y1 = (f32x4){bf_lo(w.z), bf_hi(w.z), bf_lo(w.w), bf_hi(w.w)}; }
;                     float sa = ((y0[0] + y0[1]) + (y0[2] + y0[3])) + ((y1[0] + y1[1]) + (y1[2] + y1[3]));
;                     float sb = ((y0[0] * y0[0] + y0[1] * y0[1]) + (y0[2] * y0[2] + y0[3] * y0[3])) + ((y1[0] * y1[0] + y1[1] * y1[1]) + (y1[2] * y1[2] + y1[3] * y1[3]));
;                     sa += dpp_x1(sa);
;                     sb += dpp_x1(sb);
;                     sa += __shfl_xor(sa, 16); sa += __shfl_xor(sa, 32); sb += __shfl_xor(sb, 16); sb += __shfl_xor(sb, 32);
;                     if (fq == 0 && !odd) ps[(size_t)(rl + q) * 64] = (f32x2){sa, sb};
.LBB0_606:
	s_or_b64 exec, exec, s[56:57]
	s_waitcnt lgkmcnt(1)
	v_cndmask_b32_e64 v34, v28, v20, s[8:9]
	s_nop 0
	v_cndmask_b32_e64 v33, v29, v21, s[8:9]
	s_waitcnt lgkmcnt(0)
	v_cndmask_b32_e64 v35, v30, v22, s[8:9]
	v_mov_b32_dpp v32, v34 quad_perm:[1,0,3,2] row_mask:0xf bank_mask:0xf
	s_nop 0
	v_cndmask_b32_e64 v36, v31, v23, s[8:9]
	v_cndmask_b32_e64 v38, v24, v16, s[8:9]
	v_mov_b32_dpp v34, v33 quad_perm:[1,0,3,2] row_mask:0xf bank_mask:0xf
	s_nop 0
	v_cndmask_b32_e64 v37, v25, v17, s[8:9]
	v_cndmask_b32_e64 v39, v26, v18, s[8:9]
	v_mov_b32_dpp v33, v35 quad_perm:[1,0,3,2] row_mask:0xf bank_mask:0xf
	s_nop 0
	v_cndmask_b32_e64 v40, v27, v19, s[8:9]
	v_cndmask_b32_e64 v29, v34, v29, s[8:9]
	v_mov_b32_dpp v35, v36 quad_perm:[1,0,3,2] row_mask:0xf bank_mask:0xf
	s_nop 0
	v_cndmask_b32_e64 v28, v32, v28, s[8:9]
	v_cndmask_b32_e64 v31, v35, v31, s[8:9]
	v_mov_b32_dpp v36, v38 quad_perm:[1,0,3,2] row_mask:0xf bank_mask:0xf
	s_nop 0
	v_cndmask_b32_e64 v30, v33, v30, s[8:9]
	v_cndmask_b32_e64 v24, v36, v24, s[8:9]
	v_mov_b32_dpp v38, v37 quad_perm:[1,0,3,2] row_mask:0xf bank_mask:0xf
	s_nop 0
	v_cndmask_b32_e64 v25, v38, v25, s[8:9]
	s_waitcnt vmcnt(11)
	v_and_b32_e32 v41, 0xffff0000, v76
	v_mov_b32_dpp v37, v39 quad_perm:[1,0,3,2] row_mask:0xf bank_mask:0xf
	s_nop 0
	v_cndmask_b32_e64 v26, v37, v26, s[8:9]
	v_lshlrev_b32_e32 v42, 16, v77
	v_mov_b32_dpp v39, v40 quad_perm:[1,0,3,2] row_mask:0xf bank_mask:0xf
	v_cndmask_b32_e64 v27, v39, v27, s[8:9]
	v_lshlrev_b32_e32 v40, 16, v76
	v_and_b32_e32 v43, 0xffff0000, v77
	v_lshlrev_b32_e32 v44, 16, v78
	v_and_b32_e32 v45, 0xffff0000, v78
	v_lshlrev_b32_e32 v46, 16, v79
	v_and_b32_e32 v47, 0xffff0000, v79
	v_pk_fma_f32 v[30:31], v[42:43], s[18:19], v[30:31] op_sel_hi:[1,0,1]
	v_pk_fma_f32 v[28:29], v[40:41], s[18:19], v[28:29] op_sel_hi:[1,0,1]
	v_pk_fma_f32 v[26:27], v[46:47], s[18:19], v[26:27] op_sel_hi:[1,0,1]
	v_pk_fma_f32 v[24:25], v[44:45], s[18:19], v[24:25] op_sel_hi:[1,0,1]
	v_cvt_pk_bf16_f32 v40, v28, v29
	v_cvt_pk_bf16_f32 v41, v30, v31
	v_mov_b32_e32 v93, v165
	v_cvt_pk_bf16_f32 v42, v24, v25
	v_cvt_pk_bf16_f32 v43, v26, v27
	v_lshlrev_b32_e32 v24, 16, v40
	v_and_b32_e32 v26, 0xffff0000, v40
	v_lshlrev_b32_e32 v28, 16, v41
	v_and_b32_e32 v30, 0xffff0000, v41
	v_lshlrev_b32_e32 v44, 16, v42
	v_and_b32_e32 v46, 0xffff0000, v42
	v_lshlrev_b32_e32 v48, 16, v43
	v_and_b32_e32 v50, 0xffff0000, v43
	v_mul_f32_e32 v25, v24, v24
	v_mul_f32_e32 v27, v26, v26
	v_mul_f32_e32 v29, v28, v28
	v_mul_f32_e32 v31, v30, v30
	v_mul_f32_e32 v45, v44, v44
	v_mul_f32_e32 v47, v46, v46
	v_mul_f32_e32 v49, v48, v48
	v_mul_f32_e32 v51, v50, v50
	v_pk_add_f32 v[24:25], v[24:25], v[26:27]
	v_pk_add_f32 v[26:27], v[28:29], v[30:31]
	v_pk_add_f32 v[28:29], v[48:49], v[50:51]
	v_pk_add_f32 v[24:25], v[24:25], v[26:27]
	v_pk_add_f32 v[26:27], v[44:45], v[46:47]
	s_nop 0
	v_pk_add_f32 v[26:27], v[26:27], v[28:29]
	s_nop 0
	v_pk_add_f32 v[24:25], v[24:25], v[26:27]
	v_mov_b32_e32 v26, v165
	v_mov_b32_e32 v27, v165
	s_nop 0
	v_mov_b32_dpp v26, v24 quad_perm:[1,0,3,2] row_mask:0xf bank_mask:0xf
	v_mov_b32_dpp v27, v25 quad_perm:[1,0,3,2] row_mask:0xf bank_mask:0xf
	v_pk_add_f32 v[24:25], v[24:25], v[26:27]
	ds_bpermute_b32 v26, v130, v24
	ds_bpermute_b32 v27, v130, v25
	s_waitcnt lgkmcnt(0)
	v_pk_add_f32 v[26:27], v[24:25], v[26:27]
	ds_bpermute_b32 v28, v131, v26
	ds_bpermute_b32 v29, v131, v27
	v_lshl_add_u64 v[24:25], s[54:55], 0, v[92:93]
	global_store_dwordx4 v[24:25], v[40:43], off
	s_and_saveexec_b64 s[56:57], s[10:11]
	s_cbranch_execz .LBB0_608
	s_waitcnt lgkmcnt(0)
	v_pk_add_f32 v[26:27], v[26:27], v[28:29]
	v_add_co_u32_e32 v28, vcc, 0x14000, v124
	s_nop 1
	v_addc_co_u32_e32 v29, vcc, 0, v125, vcc
	global_store_dwordx2 v[28:29], v[26:27], off

; __device__ __forceinline__ u32x4 pack8f(f32x4 a, f32x4 b) { u32x4 w; w.x = cvt_pk_bf16(a[0], a[1]); w.y = cvt_pk_bf16(a[2], a[3]); w.z = cvt_pk_bf16(b[0], b[1]); w.w = cvt_pk_bf16(b[2], b[3]); return w; }
;     __device__ __forceinline__ void operator()(const f32x4 (&acc)[2][2][4][2], const Unit& u, int wr, int wc, int fr, int fq, const EpiCtx& X) const {
;     ...
;             for (int m = 0; m < 4; ++m) {
;                 const int rl = ai * HALF + m * 16; const unsigned off = lo + (unsigned)(rl * 64) * 2u;
;                 const f32x4 o0a = acc[ai][0][m][0], o0b = acc[ai][0][m][1], o1a = acc[ai][1][m][0], o1b = acc[ai][1][m][1];
;                 const f32x4 ra_ = dpp_swap1(odd ? o0a : o1a), rb_ = dpp_swap1(odd ? o0b : o1b);
;                 const f32x4 pa[2] = {odd ? ra_ : o0a, odd ? o1a : ra_}, pb[2] = {odd ? rb_ : o0b, odd ? o1b : rb_};
; #pragma unroll
;                 for (int q = 0; q < 2; ++q) {
;                     const u32x4 w0 = raw[2 * m + q];
;                     const f32x4 r0 = (f32x4){bf_lo(w0.x), bf_hi(w0.x), bf_lo(w0.y), bf_hi(w0.y)}, r1 = (f32x4){bf_lo(w0.z), bf_hi(w0.z), bf_lo(w0.w), bf_hi(w0.w)};
;                     f32x4 y0, y1;
;                     if (RESN) { const f32x2 t = tbl[rl + q]; const float mu = t.x, ra = t.y * ALPHA; y0 = (r0 - mu) * ra * g0 + b0 + pa[q]; y1 = (r1 - mu) * ra * g1 + b1 + pb[q]; }
;                     else { y0 = r0 * ALPHA + pa[q]; y1 = r1 * ALPHA + pb[q]; }
;                     { const u32x4 w = pack8f(y0, y1); *(u32x4*)(xb + off + q * 128) = w;
;                         y0 = (f32x4){bf_lo(w.x), bf_hi(w.x), bf_lo(w.y), bf_hi(w.y)}; y1 = (f32x4){bf_lo(w.z), bf_hi(w.z), bf_lo(w.w), bf_hi(w.w)}; }
;                     float sa = ((y0[0] + y0[1]) + (y0[2] + y0[3])) + ((y1[0] + y1[1]) + (y1[2] + y1[3]));
;                     float sb = ((y0[0] * y0[0] + y0[1] * y0[1]) + (y0[2] * y0[2] + y0[3] * y0[3])) + ((y1[0] * y1[0] + y1[1] * y1[1]) + (y1[2] * y1[2] + y1[3] * y1[3]));
;                     sa += dpp_x1(sa);
;                     sb += dpp_x1(sb);
;                     sa += __shfl_xor(sa, 16); sa += __shfl_xor(sa, 32); sb += __shfl_xor(sb, 16); sb += __shfl_xor(sb, 32);
;                     if (fq == 0 && !odd) ps[(size_t)(rl + q) * 64] = (f32x2){sa, sb};
.LBB0_610:
	s_or_b64 exec, exec, s[56:57]
	s_waitcnt lgkmcnt(1)
	v_cndmask_b32_e64 v18, v12, v4, s[8:9]
	s_nop 0
	v_cndmask_b32_e64 v17, v13, v5, s[8:9]
	s_waitcnt lgkmcnt(0)
	v_cndmask_b32_e64 v19, v14, v6, s[8:9]
	v_mov_b32_dpp v16, v18 quad_perm:[1,0,3,2] row_mask:0xf bank_mask:0xf
	s_nop 0
	v_cndmask_b32_e64 v20, v15, v7, s[8:9]
	v_cndmask_b32_e64 v22, v8, v0, s[8:9]
	v_mov_b32_dpp v18, v17 quad_perm:[1,0,3,2] row_mask:0xf bank_mask:0xf
	s_nop 0
	v_cndmask_b32_e64 v21, v9, v1, s[8:9]
	v_cndmask_b32_e64 v23, v10, v2, s[8:9]
	v_mov_b32_dpp v17, v19 quad_perm:[1,0,3,2] row_mask:0xf bank_mask:0xf
	s_nop 0
	v_cndmask_b32_e64 v24, v11, v3, s[8:9]
	v_cndmask_b32_e64 v13, v18, v13, s[8:9]
	v_mov_b32_dpp v19, v20 quad_perm:[1,0,3,2] row_mask:0xf bank_mask:0xf
	s_nop 0
	v_cndmask_b32_e64 v12, v16, v12, s[8:9]
	v_cndmask_b32_e64 v15, v19, v15, s[8:9]
	v_mov_b32_dpp v20, v22 quad_perm:[1,0,3,2] row_mask:0xf bank_mask:0xf
	s_nop 0
	v_cndmask_b32_e64 v14, v17, v14, s[8:9]
	v_cndmask_b32_e64 v8, v20, v8, s[8:9]
	v_mov_b32_dpp v22, v21 quad_perm:[1,0,3,2] row_mask:0xf bank_mask:0xf
	s_nop 0
	v_cndmask_b32_e64 v9, v22, v9, s[8:9]
	s_waitcnt vmcnt(13)
	v_and_b32_e32 v25, 0xffff0000, v68
	v_mov_b32_dpp v21, v23 quad_perm:[1,0,3,2] row_mask:0xf bank_mask:0xf
	s_nop 0
	v_cndmask_b32_e64 v10, v21, v10, s[8:9]
	v_lshlrev_b32_e32 v26, 16, v69
	v_mov_b32_dpp v23, v24 quad_perm:[1,0,3,2] row_mask:0xf bank_mask:0xf
	v_cndmask_b32_e64 v11, v23, v11, s[8:9]
	v_lshlrev_b32_e32 v24, 16, v68
	v_and_b32_e32 v27, 0xffff0000, v69
	v_lshlrev_b32_e32 v28, 16, v70
	v_and_b32_e32 v29, 0xffff0000, v70
	v_lshlrev_b32_e32 v30, 16, v71
	v_and_b32_e32 v31, 0xffff0000, v71
	v_pk_fma_f32 v[14:15], v[26:27], s[18:19], v[14:15] op_sel_hi:[1,0,1]
	v_pk_fma_f32 v[12:13], v[24:25], s[18:19], v[12:13] op_sel_hi:[1,0,1]
	v_pk_fma_f32 v[10:11], v[30:31], s[18:19], v[10:11] op_sel_hi:[1,0,1]
	v_pk_fma_f32 v[8:9], v[28:29], s[18:19], v[8:9] op_sel_hi:[1,0,1]
	v_cvt_pk_bf16_f32 v24, v12, v13
	v_cvt_pk_bf16_f32 v25, v14, v15
	s_nop 0
	v_cvt_pk_bf16_f32 v26, v8, v9
	v_cvt_pk_bf16_f32 v27, v10, v11
	v_lshlrev_b32_e32 v8, 16, v24
	v_and_b32_e32 v10, 0xffff0000, v24
	v_lshlrev_b32_e32 v12, 16, v25
	v_and_b32_e32 v14, 0xffff0000, v25
	v_lshlrev_b32_e32 v28, 16, v26
	v_and_b32_e32 v30, 0xffff0000, v26
	v_lshlrev_b32_e32 v32, 16, v27
	v_and_b32_e32 v34, 0xffff0000, v27
	v_mul_f32_e32 v9, v8, v8
	v_mul_f32_e32 v11, v10, v10
	v_mul_f32_e32 v13, v12, v12
	v_mul_f32_e32 v15, v14, v14
	v_mul_f32_e32 v29, v28, v28
	v_mul_f32_e32 v31, v30, v30
	v_mul_f32_e32 v33, v32, v32
	v_mul_f32_e32 v35, v34, v34
	v_pk_add_f32 v[8:9], v[8:9], v[10:11]
	v_pk_add_f32 v[10:11], v[12:13], v[14:15]
	v_pk_add_f32 v[12:13], v[32:33], v[34:35]
	v_pk_add_f32 v[8:9], v[8:9], v[10:11]
	v_pk_add_f32 v[10:11], v[28:29], v[30:31]
	s_nop 0
	v_pk_add_f32 v[10:11], v[10:11], v[12:13]
	s_nop 0
	v_pk_add_f32 v[8:9], v[8:9], v[10:11]
	v_mov_b32_e32 v10, v165
	v_mov_b32_e32 v11, v165
	s_nop 0
	v_mov_b32_dpp v10, v8 quad_perm:[1,0,3,2] row_mask:0xf bank_mask:0xf
	v_mov_b32_dpp v11, v9 quad_perm:[1,0,3,2] row_mask:0xf bank_mask:0xf
	v_pk_add_f32 v[8:9], v[8:9], v[10:11]
	ds_bpermute_b32 v10, v130, v8
	ds_bpermute_b32 v11, v130, v9
	s_waitcnt lgkmcnt(0)
	v_pk_add_f32 v[10:11], v[8:9], v[10:11]
	ds_bpermute_b32 v12, v131, v10
	ds_bpermute_b32 v13, v131, v11
	v_lshl_add_u64 v[8:9], s[54:55], 0, v[164:165]
	global_store_dwordx4 v[8:9], v[24:27], off
	s_and_saveexec_b64 s[54:55], s[10:11]
	s_cbranch_execz .LBB0_612
	s_waitcnt lgkmcnt(0)
	v_pk_add_f32 v[10:11], v[10:11], v[12:13]
	v_add_co_u32_e32 v12, vcc, 0x16000, v124
	s_nop 1
	v_addc_co_u32_e32 v13, vcc, 0, v125, vcc
	global_store_dwordx2 v[12:13], v[10:11], off

; #define LAS __attribute__((address_space(3)))
; #define EPI_OPAQUE(x) asm volatile("" : "+v"(x))
;     __device__ __forceinline__ float pre(const Unit& u, int tid) const { return (tid < 256 ? sv : tv)[u.pn * BM + (tid & 255)]; }
;     __device__ __forceinline__ float pre(const Unit& u, int tid) const { return (tid < 256 ? sv : tv)[u.pn * BM + (tid & 255)]; }
;     __device__ __forceinline__ void operator()(const f32x4 (&acc)[2][2][4][2], const Unit& u, int wr, int wc, int fr, int fq, const EpiCtx& X) const {
;     ...
;         LAS float* stb = (LAS float*)(X.lds + STB_OFF);
;         stb[X.tid] = X.pre;
;         asm volatile("s_waitcnt lgkmcnt(0)" ::: "memory"); __builtin_amdgcn_s_barrier(); asm volatile("" ::: "memory");
;         const bool odd = fr & 1; const int fe = fr - (fr & 1), o32 = (fr & 1) * 32;
;         constexpr int RP = BLK ? 64 : LDC;
;         char* base = BLK ? (char*)(O + (size_t)u.pm * BM * LDC + (size_t)(u.pn * 4 + wc) * (BM * 64)) : (char*)(O + (size_t)u.pm * BM * LDC + u.pn * BM);
;         unsigned lo = (unsigned)((wr * 64 + fe) * RP + (BLK ? 0 : wc * 64) + o32 + 8 * fq) * 2u; EPI_OPAQUE(lo);
;         const LAS f32x2* tbl = (const LAS f32x2*)(X.lds + TBL_OFF) + wr * 64 + fe;
;         const LAS f32x4* sp = (const LAS f32x4*)(stb + wc * 64 + o32 + 8 * fq);
;         const f32x4 sa = sp[0], sb = sp[1], ta = sp[64], tb = sp[65];
;     ...
;         EPI_PIECES({ const unsigned off = lo + (unsigned)(rl * RP) * 2u; LN_ONE(p1a, p1b, rl, off); LN_ONE(p2a, p2b, rl + 1, off + RP * 2); })
.LBB0_714:
	v_cndmask_b32_e64 v171, v127, v119, s[14:15]
	v_cndmask_b32_e64 v172, v126, v118, s[14:15]
	v_cndmask_b32_e64 v173, v125, v117, s[14:15]
	v_cndmask_b32_e64 v174, v124, v116, s[14:15]
	s_nop 0
	s_nop 0
	s_nop 0
	s_nop 0
	v_mov_b32_dpp v180, v174 quad_perm:[1,0,3,2] row_mask:0xf bank_mask:0xf
	v_mov_b32_dpp v181, v173 quad_perm:[1,0,3,2] row_mask:0xf bank_mask:0xf
	v_mov_b32_dpp v178, v172 quad_perm:[1,0,3,2] row_mask:0xf bank_mask:0xf
	v_mov_b32_dpp v179, v171 quad_perm:[1,0,3,2] row_mask:0xf bank_mask:0xf
	v_cndmask_b32_e64 v171, v123, v115, s[14:15]
	v_cndmask_b32_e64 v172, v122, v114, s[14:15]
	v_cndmask_b32_e64 v173, v121, v113, s[14:15]
	v_cndmask_b32_e64 v174, v120, v112, s[14:15]
	s_nop 0
	s_nop 0
	s_nop 0
	s_nop 0
	s_waitcnt vmcnt(16)
	ds_write_b32 v162, v169
	v_mov_b32_e32 v170, v163
	v_mov_b32_dpp v182, v174 quad_perm:[1,0,3,2] row_mask:0xf bank_mask:0xf
	v_mov_b32_dpp v183, v173 quad_perm:[1,0,3,2] row_mask:0xf bank_mask:0xf
	v_mov_b32_dpp v184, v172 quad_perm:[1,0,3,2] row_mask:0xf bank_mask:0xf
	v_mov_b32_dpp v185, v171 quad_perm:[1,0,3,2] row_mask:0xf bank_mask:0xf
	s_waitcnt lgkmcnt(0)
	s_barrier
	s_waitcnt lgkmcnt(1)
	ds_read_b128 v[132:135], v165 offset:16
	ds_read_b128 v[136:139], v165 offset:1024
	ds_read_b128 v[128:131], v165 offset:1040
	v_cndmask_b32_e64 v173, v185, v123, s[14:15]
	v_cndmask_b32_e64 v172, v184, v122, s[14:15]
	v_cndmask_b32_e64 v175, v183, v121, s[14:15]
	v_cndmask_b32_e64 v174, v182, v120, s[14:15]
	ds_read_b128 v[120:123], v165
	ds_read_b64 v[176:177], v164
	v_cndmask_b32_e64 v125, v181, v125, s[14:15]
	v_cndmask_b32_e64 v124, v180, v124, s[14:15]
	v_cndmask_b32_e64 v127, v179, v127, s[14:15]
	v_cndmask_b32_e64 v126, v178, v126, s[14:15]
	v_cndmask_b32_e64 v179, v119, v179, s[14:15]
	v_cndmask_b32_e64 v178, v118, v178, s[14:15]
	v_cndmask_b32_e64 v181, v117, v181, s[14:15]
	v_cndmask_b32_e64 v180, v116, v180, s[14:15]
	s_waitcnt lgkmcnt(0)
	v_pk_fma_f32 v[118:119], v[120:121], v[176:177], v[124:125] op_sel_hi:[1,0,1] neg_lo:[1,0,0] neg_hi:[1,0,0]
	v_xor_b32_e32 v117, 0x80000000, v123
	v_xor_b32_e32 v116, 0x80000000, v122
	v_pk_fma_f32 v[122:123], v[116:117], v[176:177], v[126:127] op_sel_hi:[1,0,1]
	v_pk_fma_f32 v[124:125], v[176:177], v[118:119], v[136:137] op_sel:[1,0,0]
	v_pk_fma_f32 v[126:127], v[132:133], v[176:177], v[174:175] op_sel_hi:[1,0,1] neg_lo:[1,0,0] neg_hi:[1,0,0]
	v_xor_b32_e32 v119, 0x80000000, v135
	v_xor_b32_e32 v118, 0x80000000, v134
	v_pk_fma_f32 v[122:123], v[176:177], v[122:123], v[138:139] op_sel:[1,0,0]
	v_pk_fma_f32 v[134:135], v[118:119], v[176:177], v[172:173] op_sel_hi:[1,0,1]
	v_pk_fma_f32 v[126:127], v[176:177], v[126:127], v[128:129] op_sel:[1,0,0]
	s_lshl_b64 s[18:19], s[60:61], 23
	v_pk_fma_f32 v[134:135], v[176:177], v[134:135], v[130:131] op_sel:[1,0,0]
	v_max_f32_e32 v124, 0, v124
	v_max_f32_e32 v126, 0, v126
	v_max_f32_e32 v125, 0, v125
	v_max_f32_e32 v127, 0, v127
	v_max_f32_e32 v122, 0, v122
	s_add_u32 s25, s45, s18
	v_mul_f32_e32 v124, v124, v124
	v_mul_f32_e32 v126, v126, v126
	v_mul_f32_e32 v125, v125, v125
	v_mul_f32_e32 v127, v127, v127
	v_max_f32_e32 v134, 0, v134
	v_mul_f32_e32 v171, v122, v122
	v_max_f32_e32 v122, 0, v123
	v_max_f32_e32 v123, 0, v135
	s_addc_u32 s27, s46, s19
	s_lshl_b32 s18, s68, 2
	v_mul_f32_e32 v134, v134, v134
	v_mul_f32_e32 v135, v122, v122
	v_mul_f32_e32 v172, v123, v123
	v_cvt_pk_bf16_f32 v122, v124, v125
	v_cvt_pk_bf16_f32 v123, v171, v135
	v_cvt_pk_bf16_f32 v124, v126, v127
	v_cvt_pk_bf16_f32 v125, v134, v172
	ds_read_b64 v[126:127], v164 offset:8
	s_or_b32 s18, s18, s41
	s_ashr_i32 s19, s18, 31
	s_lshl_b64 s[18:19], s[18:19], 15
	s_add_u32 s18, s25, s18
	v_cndmask_b32_e64 v113, v113, v183, s[14:15]
	v_cndmask_b32_e64 v112, v112, v182, s[14:15]
	s_addc_u32 s19, s27, s19
	v_cndmask_b32_e64 v115, v115, v185, s[14:15]
	v_cndmask_b32_e64 v114, v114, v184, s[14:15]
	s_waitcnt lgkmcnt(0)
	v_pk_fma_f32 v[112:113], v[132:133], v[126:127], v[112:113] op_sel_hi:[1,0,1] neg_lo:[1,0,0] neg_hi:[1,0,0]
	global_store_dwordx4 v170, v[122:125], s[18:19] nt
	v_pk_fma_f32 v[114:115], v[118:119], v[126:127], v[114:115] op_sel_hi:[1,0,1]
	v_pk_fma_f32 v[112:113], v[126:127], v[112:113], v[128:129] op_sel:[1,0,0]
	v_pk_fma_f32 v[122:123], v[120:121], v[126:127], v[180:181] op_sel_hi:[1,0,1] neg_lo:[1,0,0] neg_hi:[1,0,0]
	v_pk_fma_f32 v[124:125], v[116:117], v[126:127], v[178:179] op_sel_hi:[1,0,1]
	v_pk_fma_f32 v[122:123], v[126:127], v[122:123], v[136:137] op_sel:[1,0,0]
	v_pk_fma_f32 v[124:125], v[126:127], v[124:125], v[138:139] op_sel:[1,0,0]
	v_pk_fma_f32 v[114:115], v[126:127], v[114:115], v[130:131] op_sel:[1,0,0]
	v_max_f32_e32 v112, 0, v112
	v_max_f32_e32 v113, 0, v113
	v_max_f32_e32 v122, 0, v122
	v_mul_f32_e32 v126, v112, v112
	v_max_f32_e32 v112, 0, v123
	v_mul_f32_e32 v123, v113, v113
	v_max_f32_e32 v113, 0, v124
	v_max_f32_e32 v114, 0, v114
	v_mul_f32_e32 v122, v122, v122
	v_mul_f32_e32 v112, v112, v112
	v_mul_f32_e32 v113, v113, v113
	v_mul_f32_e32 v124, v114, v114
	v_max_f32_e32 v114, 0, v125
	v_max_f32_e32 v115, 0, v115
	v_mul_f32_e32 v114, v114, v114
	v_mul_f32_e32 v115, v115, v115
	v_cvt_pk_bf16_f32 v112, v122, v112
	v_cvt_pk_bf16_f32 v113, v113, v114
	v_add_u32_e32 v122, 0x80, v170
	v_cvt_pk_bf16_f32 v114, v126, v123
	v_cvt_pk_bf16_f32 v115, v124, v115
	global_store_dwordx4 v122, v[112:115], s[18:19] nt
	ds_read_b64 v[112:113], v164 offset:128
	v_cndmask_b32_e64 v123, v108, v100, s[14:15]
	s_nop 0
	v_cndmask_b32_e64 v127, v104, v96, s[14:15]
	s_nop 0
	v_cndmask_b32_e64 v122, v109, v101, s[14:15]
	v_mov_b32_dpp v124, v123 quad_perm:[1,0,3,2] row_mask:0xf bank_mask:0xf
	s_nop 0
	v_cndmask_b32_e64 v126, v105, v97, s[14:15]
	v_mov_b32_dpp v134, v127 quad_perm:[1,0,3,2] row_mask:0xf bank_mask:0xf
	s_nop 0
	v_cndmask_b32_e64 v115, v110, v102, s[14:15]
	v_mov_b32_dpp v123, v122 quad_perm:[1,0,3,2] row_mask:0xf bank_mask:0xf
	s_nop 0
	v_mov_b32_dpp v127, v126 quad_perm:[1,0,3,2] row_mask:0xf bank_mask:0xf
	v_cndmask_b32_e64 v114, v111, v103, s[14:15]
	v_mov_b32_dpp v122, v115 quad_perm:[1,0,3,2] row_mask:0xf bank_mask:0xf
	s_nop 0
	v_cndmask_b32_e64 v125, v106, v98, s[14:15]
	s_nop 0
	v_cndmask_b32_e64 v105, v127, v105, s[14:15]
	v_cndmask_b32_e64 v104, v134, v104, s[14:15]
	v_mov_b32_dpp v115, v114 quad_perm:[1,0,3,2] row_mask:0xf bank_mask:0xf
	v_cndmask_b32_e64 v114, v107, v99, s[14:15]
	v_mov_b32_dpp v126, v125 quad_perm:[1,0,3,2] row_mask:0xf bank_mask:0xf
	s_nop 0
	s_waitcnt lgkmcnt(0)
; __device__ __forceinline__ float dpp_x1(float x) { return __builtin_bit_cast(float, __builtin_amdgcn_update_dpp(0, __builtin_bit_cast(int, x), 0xB1, 0xF, 0xF, false)); }
; __device__ __forceinline__ f32x4 dpp_swap1(f32x4 v) { f32x4 r; r[0] = dpp_x1(v[0]); r[1] = dpp_x1(v[1]); r[2] = dpp_x1(v[2]); r[3] = dpp_x1(v[3]); return r; }
;     __device__ __forceinline__ void operator()(const f32x4 (&acc)[2][2][4][2], const Unit& u, int wr, int wc, int fr, int fq, const EpiCtx& X) const {
;     ...
;         EPI_PIECES({ const unsigned off = lo + (unsigned)(rl * RP) * 2u; LN_ONE(p1a, p1b, rl, off); LN_ONE(p2a, p2b, rl + 1, off + RP * 2); })
	v_pk_fma_f32 v[104:105], v[132:133], v[112:113], v[104:105] op_sel_hi:[1,0,1] neg_lo:[1,0,0] neg_hi:[1,0,0]
	v_cndmask_b32_e64 v111, v115, v111, s[14:15]
	v_mov_b32_dpp v125, v114 quad_perm:[1,0,3,2] row_mask:0xf bank_mask:0xf
	v_cndmask_b32_e64 v110, v122, v110, s[14:15]
	v_cndmask_b32_e64 v109, v123, v109, s[14:15]
	v_cndmask_b32_e64 v108, v124, v108, s[14:15]
	v_pk_fma_f32 v[104:105], v[112:113], v[104:105], v[128:129] op_sel:[1,0,0]
	v_cndmask_b32_e64 v107, v125, v107, s[14:15]
	v_cndmask_b32_e64 v106, v126, v106, s[14:15]
	v_cndmask_b32_e64 v103, v103, v115, s[14:15]
	v_cndmask_b32_e64 v115, v101, v123, s[14:15]
	v_cndmask_b32_e64 v114, v100, v124, s[14:15]
	v_pk_fma_f32 v[100:101], v[120:121], v[112:113], v[108:109] op_sel_hi:[1,0,1] neg_lo:[1,0,0] neg_hi:[1,0,0]
	v_pk_fma_f32 v[108:109], v[116:117], v[112:113], v[110:111] op_sel_hi:[1,0,1]
	v_max_f32_e32 v104, 0, v104
	v_pk_fma_f32 v[108:109], v[112:113], v[108:109], v[138:139] op_sel:[1,0,0]
	v_pk_fma_f32 v[106:107], v[118:119], v[112:113], v[106:107] op_sel_hi:[1,0,1]
	v_mul_f32_e32 v110, v104, v104
	v_max_f32_e32 v104, 0, v105
	v_pk_fma_f32 v[100:101], v[112:113], v[100:101], v[136:137] op_sel:[1,0,0]
	v_pk_fma_f32 v[106:107], v[112:113], v[106:107], v[130:131] op_sel:[1,0,0]
	v_mul_f32_e32 v111, v104, v104
	v_max_f32_e32 v104, 0, v108
	v_max_f32_e32 v100, 0, v100
	v_max_f32_e32 v101, 0, v101
	v_max_f32_e32 v105, 0, v106
	v_mul_f32_e32 v106, v104, v104
	v_max_f32_e32 v104, 0, v109
	v_mul_f32_e32 v100, v100, v100
	v_mul_f32_e32 v101, v101, v101
	v_mul_f32_e32 v108, v105, v105
	v_max_f32_e32 v105, 0, v107
	v_mul_f32_e32 v107, v104, v104
	v_mul_f32_e32 v109, v105, v105
	v_cndmask_b32_e64 v105, v99, v125, s[14:15]
	v_cndmask_b32_e64 v104, v98, v126, s[14:15]
	v_cvt_pk_bf16_f32 v98, v100, v101
	v_cvt_pk_bf16_f32 v99, v106, v107
	v_cvt_pk_bf16_f32 v100, v110, v111
	v_cvt_pk_bf16_f32 v101, v108, v109
	ds_read_b64 v[106:107], v164 offset:136
	v_cndmask_b32_e64 v97, v97, v127, s[14:15]
	v_cndmask_b32_e64 v96, v96, v134, s[14:15]
	v_cndmask_b32_e64 v102, v102, v122, s[14:15]
	v_add_u32_e32 v108, 0x800, v170
	s_waitcnt lgkmcnt(0)
	v_pk_fma_f32 v[96:97], v[132:133], v[106:107], v[96:97] op_sel_hi:[1,0,1] neg_lo:[1,0,0] neg_hi:[1,0,0]
	global_store_dwordx4 v108, v[98:101], s[18:19] nt
	v_pk_fma_f32 v[96:97], v[106:107], v[96:97], v[128:129] op_sel:[1,0,0]
	s_andn2_b64 vcc, exec, s[16:17]
	v_pk_fma_f32 v[98:99], v[120:121], v[106:107], v[114:115] op_sel_hi:[1,0,1] neg_lo:[1,0,0] neg_hi:[1,0,0]
	v_pk_fma_f32 v[100:101], v[116:117], v[106:107], v[102:103] op_sel_hi:[1,0,1]
	v_pk_fma_f32 v[102:103], v[118:119], v[106:107], v[104:105] op_sel_hi:[1,0,1]
	v_pk_fma_f32 v[100:101], v[106:107], v[100:101], v[138:139] op_sel:[1,0,0]
	v_pk_fma_f32 v[98:99], v[106:107], v[98:99], v[136:137] op_sel:[1,0,0]
	v_pk_fma_f32 v[102:103], v[106:107], v[102:103], v[130:131] op_sel:[1,0,0]
	v_max_f32_e32 v96, 0, v96
	v_max_f32_e32 v97, 0, v97
	v_max_f32_e32 v98, 0, v98
	v_mul_f32_e32 v104, v96, v96
	v_max_f32_e32 v96, 0, v99
	v_mul_f32_e32 v99, v97, v97
	v_max_f32_e32 v97, 0, v100
	v_max_f32_e32 v100, 0, v102
	v_mul_f32_e32 v98, v98, v98
	v_mul_f32_e32 v96, v96, v96
	v_mul_f32_e32 v97, v97, v97
	v_mul_f32_e32 v100, v100, v100
	v_max_f32_e32 v101, 0, v101
	v_max_f32_e32 v102, 0, v103
	v_mul_f32_e32 v101, v101, v101
	v_mul_f32_e32 v102, v102, v102
	v_cvt_pk_bf16_f32 v96, v98, v96
	v_cvt_pk_bf16_f32 v97, v97, v101
	v_cvt_pk_bf16_f32 v98, v104, v99
	v_cvt_pk_bf16_f32 v99, v100, v102
	v_add_u32_e32 v100, 0x880, v170
	global_store_dwordx4 v100, v[96:99], s[18:19] nt
	s_nop 0
	v_cndmask_b32_e64 v103, v88, v80, s[14:15]
	v_cndmask_b32_e64 v99, v92, v84, s[14:15]
	v_cndmask_b32_e64 v98, v93, v85, s[14:15]
	s_nop 0
	v_mov_b32_dpp v100, v99 quad_perm:[1,0,3,2] row_mask:0xf bank_mask:0xf
	s_nop 0
	v_cndmask_b32_e64 v96, v95, v87, s[14:15]
	v_cndmask_b32_e64 v97, v94, v86, s[14:15]
	v_mov_b32_dpp v99, v98 quad_perm:[1,0,3,2] row_mask:0xf bank_mask:0xf
	s_nop 0
	s_nop 0
	v_cndmask_b32_e64 v102, v89, v81, s[14:15]
	v_mov_b32_dpp v104, v103 quad_perm:[1,0,3,2] row_mask:0xf bank_mask:0xf
	s_nop 0
	v_mov_b32_dpp v98, v97 quad_perm:[1,0,3,2] row_mask:0xf bank_mask:0xf
	v_mov_b32_dpp v101, v96 quad_perm:[1,0,3,2] row_mask:0xf bank_mask:0xf
	v_cndmask_b32_e64 v96, v91, v83, s[14:15]
	v_cndmask_b32_e64 v97, v90, v82, s[14:15]
	v_mov_b32_dpp v103, v102 quad_perm:[1,0,3,2] row_mask:0xf bank_mask:0xf
	s_nop 0
	s_nop 0
	v_cndmask_b32_e64 v89, v103, v89, s[14:15]
	v_mov_b32_dpp v102, v97 quad_perm:[1,0,3,2] row_mask:0xf bank_mask:0xf
	v_mov_b32_dpp v105, v96 quad_perm:[1,0,3,2] row_mask:0xf bank_mask:0xf
	ds_read_b64 v[96:97], v164 offset:256
	v_cndmask_b32_e64 v88, v104, v88, s[14:15]
	v_cndmask_b32_e64 v95, v101, v95, s[14:15]
	v_cndmask_b32_e64 v94, v98, v94, s[14:15]
	v_cndmask_b32_e64 v93, v99, v93, s[14:15]
	s_waitcnt lgkmcnt(0)
; __device__ __forceinline__ float dpp_x1(float x) { return __builtin_bit_cast(float, __builtin_amdgcn_update_dpp(0, __builtin_bit_cast(int, x), 0xB1, 0xF, 0xF, false)); }
; __device__ __forceinline__ f32x4 dpp_swap1(f32x4 v) { f32x4 r; r[0] = dpp_x1(v[0]); r[1] = dpp_x1(v[1]); r[2] = dpp_x1(v[2]); r[3] = dpp_x1(v[3]); return r; }
;     __device__ __forceinline__ void operator()(const f32x4 (&acc)[2][2][4][2], const Unit& u, int wr, int wc, int fr, int fq, const EpiCtx& X) const {
;     ...
;         EPI_PIECES({ const unsigned off = lo + (unsigned)(rl * RP) * 2u; LN_ONE(p1a, p1b, rl, off); LN_ONE(p2a, p2b, rl + 1, off + RP * 2); })
	v_pk_fma_f32 v[88:89], v[132:133], v[96:97], v[88:89] op_sel_hi:[1,0,1] neg_lo:[1,0,0] neg_hi:[1,0,0]
	v_cndmask_b32_e64 v92, v100, v92, s[14:15]
	v_pk_fma_f32 v[88:89], v[96:97], v[88:89], v[128:129] op_sel:[1,0,0]
	v_cndmask_b32_e64 v91, v105, v91, s[14:15]
	v_cndmask_b32_e64 v90, v102, v90, s[14:15]
	v_cndmask_b32_e64 v86, v86, v98, s[14:15]
	v_cndmask_b32_e64 v99, v85, v99, s[14:15]
	v_cndmask_b32_e64 v98, v84, v100, s[14:15]
	v_pk_fma_f32 v[84:85], v[120:121], v[96:97], v[92:93] op_sel_hi:[1,0,1] neg_lo:[1,0,0] neg_hi:[1,0,0]
	v_pk_fma_f32 v[92:93], v[116:117], v[96:97], v[94:95] op_sel_hi:[1,0,1]
	v_max_f32_e32 v88, 0, v88
	v_pk_fma_f32 v[92:93], v[96:97], v[92:93], v[138:139] op_sel:[1,0,0]
	v_pk_fma_f32 v[90:91], v[118:119], v[96:97], v[90:91] op_sel_hi:[1,0,1]
	v_mul_f32_e32 v94, v88, v88
	v_max_f32_e32 v88, 0, v89
	v_pk_fma_f32 v[84:85], v[96:97], v[84:85], v[136:137] op_sel:[1,0,0]
	v_pk_fma_f32 v[90:91], v[96:97], v[90:91], v[130:131] op_sel:[1,0,0]
	v_mul_f32_e32 v95, v88, v88
	v_max_f32_e32 v88, 0, v92
	v_max_f32_e32 v84, 0, v84
	v_max_f32_e32 v85, 0, v85
	v_max_f32_e32 v89, 0, v90
	v_mul_f32_e32 v90, v88, v88
	v_max_f32_e32 v88, 0, v93
	v_mul_f32_e32 v84, v84, v84
	v_mul_f32_e32 v85, v85, v85
	v_mul_f32_e32 v92, v89, v89
	v_max_f32_e32 v89, 0, v91
	v_mul_f32_e32 v91, v88, v88
	v_mul_f32_e32 v93, v89, v89
	v_cndmask_b32_e64 v89, v83, v105, s[14:15]
	v_cndmask_b32_e64 v88, v82, v102, s[14:15]
	v_cvt_pk_bf16_f32 v82, v84, v85
	v_cvt_pk_bf16_f32 v83, v90, v91
	v_cvt_pk_bf16_f32 v84, v94, v95
	v_cvt_pk_bf16_f32 v85, v92, v93
	ds_read_b64 v[90:91], v164 offset:264
	v_cndmask_b32_e64 v81, v81, v103, s[14:15]
	v_cndmask_b32_e64 v80, v80, v104, s[14:15]
	v_cndmask_b32_e64 v87, v87, v101, s[14:15]
	v_add_u32_e32 v92, 0x1000, v170
	s_waitcnt lgkmcnt(0)
	v_pk_fma_f32 v[80:81], v[132:133], v[90:91], v[80:81] op_sel_hi:[1,0,1] neg_lo:[1,0,0] neg_hi:[1,0,0]
	global_store_dwordx4 v92, v[82:85], s[18:19] nt
	v_pk_fma_f32 v[80:81], v[90:91], v[80:81], v[128:129] op_sel:[1,0,0]
	s_mov_b64 s[16:17], -1
	v_pk_fma_f32 v[82:83], v[120:121], v[90:91], v[98:99] op_sel_hi:[1,0,1] neg_lo:[1,0,0] neg_hi:[1,0,0]
	v_pk_fma_f32 v[84:85], v[116:117], v[90:91], v[86:87] op_sel_hi:[1,0,1]
	v_pk_fma_f32 v[86:87], v[118:119], v[90:91], v[88:89] op_sel_hi:[1,0,1]
	v_pk_fma_f32 v[84:85], v[90:91], v[84:85], v[138:139] op_sel:[1,0,0]
	v_pk_fma_f32 v[82:83], v[90:91], v[82:83], v[136:137] op_sel:[1,0,0]
	v_pk_fma_f32 v[86:87], v[90:91], v[86:87], v[130:131] op_sel:[1,0,0]
	v_max_f32_e32 v80, 0, v80
	v_max_f32_e32 v81, 0, v81
	v_max_f32_e32 v82, 0, v82
	v_mul_f32_e32 v88, v80, v80
	v_max_f32_e32 v80, 0, v83
	v_mul_f32_e32 v83, v81, v81
	v_max_f32_e32 v81, 0, v84
	v_max_f32_e32 v84, 0, v86
	v_mul_f32_e32 v82, v82, v82
	v_mul_f32_e32 v80, v80, v80
	v_mul_f32_e32 v81, v81, v81
	v_mul_f32_e32 v84, v84, v84
	v_max_f32_e32 v85, 0, v85
	v_max_f32_e32 v86, 0, v87
	v_mul_f32_e32 v85, v85, v85
	v_mul_f32_e32 v86, v86, v86
	v_cvt_pk_bf16_f32 v80, v82, v80
	v_cvt_pk_bf16_f32 v81, v81, v85
	v_cvt_pk_bf16_f32 v82, v88, v83
	v_cvt_pk_bf16_f32 v83, v84, v86
	v_add_u32_e32 v84, 0x1080, v170
	global_store_dwordx4 v84, v[80:83], s[18:19] nt
	ds_read_b64 v[80:81], v164 offset:384
	v_cndmask_b32_e64 v85, v76, v68, s[14:15]
	s_nop 0
	v_cndmask_b32_e64 v89, v72, v64, s[14:15]
	s_nop 0
	v_cndmask_b32_e64 v84, v77, v69, s[14:15]
	v_mov_b32_dpp v86, v85 quad_perm:[1,0,3,2] row_mask:0xf bank_mask:0xf
	s_nop 0
	v_cndmask_b32_e64 v88, v73, v65, s[14:15]
	v_mov_b32_dpp v90, v89 quad_perm:[1,0,3,2] row_mask:0xf bank_mask:0xf
	s_nop 0
	v_cndmask_b32_e64 v83, v78, v70, s[14:15]
	v_mov_b32_dpp v85, v84 quad_perm:[1,0,3,2] row_mask:0xf bank_mask:0xf
	s_nop 0
	v_mov_b32_dpp v89, v88 quad_perm:[1,0,3,2] row_mask:0xf bank_mask:0xf
	v_cndmask_b32_e64 v82, v79, v71, s[14:15]
	v_mov_b32_dpp v84, v83 quad_perm:[1,0,3,2] row_mask:0xf bank_mask:0xf
	s_nop 0
	v_cndmask_b32_e64 v87, v74, v66, s[14:15]
	s_nop 0
	v_cndmask_b32_e64 v73, v89, v73, s[14:15]
	v_cndmask_b32_e64 v72, v90, v72, s[14:15]
	v_mov_b32_dpp v83, v82 quad_perm:[1,0,3,2] row_mask:0xf bank_mask:0xf
	v_cndmask_b32_e64 v82, v75, v67, s[14:15]
	v_mov_b32_dpp v88, v87 quad_perm:[1,0,3,2] row_mask:0xf bank_mask:0xf
	s_nop 0
	s_waitcnt lgkmcnt(0)
	v_pk_fma_f32 v[72:73], v[132:133], v[80:81], v[72:73] op_sel_hi:[1,0,1] neg_lo:[1,0,0] neg_hi:[1,0,0]
	v_cndmask_b32_e64 v79, v83, v79, s[14:15]
	v_mov_b32_dpp v87, v82 quad_perm:[1,0,3,2] row_mask:0xf bank_mask:0xf
	v_cndmask_b32_e64 v78, v84, v78, s[14:15]
	v_cndmask_b32_e64 v77, v85, v77, s[14:15]
	v_cndmask_b32_e64 v76, v86, v76, s[14:15]
	v_pk_fma_f32 v[72:73], v[80:81], v[72:73], v[128:129] op_sel:[1,0,0]
	v_cndmask_b32_e64 v75, v87, v75, s[14:15]
	v_cndmask_b32_e64 v74, v88, v74, s[14:15]
	v_cndmask_b32_e64 v71, v71, v83, s[14:15]
	v_cndmask_b32_e64 v83, v69, v85, s[14:15]
	v_cndmask_b32_e64 v82, v68, v86, s[14:15]
	v_pk_fma_f32 v[68:69], v[120:121], v[80:81], v[76:77] op_sel_hi:[1,0,1] neg_lo:[1,0,0] neg_hi:[1,0,0]
	v_pk_fma_f32 v[76:77], v[116:117], v[80:81], v[78:79] op_sel_hi:[1,0,1]
	v_max_f32_e32 v72, 0, v72
	v_pk_fma_f32 v[76:77], v[80:81], v[76:77], v[138:139] op_sel:[1,0,0]
	v_pk_fma_f32 v[74:75], v[118:119], v[80:81], v[74:75] op_sel_hi:[1,0,1]
	v_mul_f32_e32 v78, v72, v72
	v_max_f32_e32 v72, 0, v73
	v_pk_fma_f32 v[68:69], v[80:81], v[68:69], v[136:137] op_sel:[1,0,0]
	v_pk_fma_f32 v[74:75], v[80:81], v[74:75], v[130:131] op_sel:[1,0,0]
	v_mul_f32_e32 v79, v72, v72
	v_max_f32_e32 v72, 0, v76
	v_max_f32_e32 v68, 0, v68
	v_max_f32_e32 v69, 0, v69
	v_max_f32_e32 v73, 0, v74
	v_mul_f32_e32 v74, v72, v72
	v_max_f32_e32 v72, 0, v77
	v_mul_f32_e32 v68, v68, v68
	v_mul_f32_e32 v69, v69, v69
	v_mul_f32_e32 v76, v73, v73
	v_max_f32_e32 v73, 0, v75
	v_mul_f32_e32 v75, v72, v72
	v_mul_f32_e32 v77, v73, v73
	v_cndmask_b32_e64 v73, v67, v87, s[14:15]
	v_cndmask_b32_e64 v72, v66, v88, s[14:15]
	v_cvt_pk_bf16_f32 v66, v68, v69
	v_cvt_pk_bf16_f32 v67, v74, v75
	v_cvt_pk_bf16_f32 v68, v78, v79
	v_cvt_pk_bf16_f32 v69, v76, v77
	ds_read_b64 v[74:75], v164 offset:392
	v_cndmask_b32_e64 v65, v65, v89, s[14:15]
	v_cndmask_b32_e64 v64, v64, v90, s[14:15]
	v_cndmask_b32_e64 v70, v70, v84, s[14:15]
	v_add_u32_e32 v76, 0x1800, v170
	s_waitcnt lgkmcnt(0)
; __device__ __forceinline__ float dpp_x1(float x) { return __builtin_bit_cast(float, __builtin_amdgcn_update_dpp(0, __builtin_bit_cast(int, x), 0xB1, 0xF, 0xF, false)); }
; __device__ __forceinline__ f32x4 dpp_swap1(f32x4 v) { f32x4 r; r[0] = dpp_x1(v[0]); r[1] = dpp_x1(v[1]); r[2] = dpp_x1(v[2]); r[3] = dpp_x1(v[3]); return r; }
;     __device__ __forceinline__ void operator()(const f32x4 (&acc)[2][2][4][2], const Unit& u, int wr, int wc, int fr, int fq, const EpiCtx& X) const {
;     ...
;         EPI_PIECES({ const unsigned off = lo + (unsigned)(rl * RP) * 2u; LN_ONE(p1a, p1b, rl, off); LN_ONE(p2a, p2b, rl + 1, off + RP * 2); })
	v_pk_fma_f32 v[64:65], v[132:133], v[74:75], v[64:65] op_sel_hi:[1,0,1] neg_lo:[1,0,0] neg_hi:[1,0,0]
	global_store_dwordx4 v76, v[66:69], s[18:19] nt
	v_pk_fma_f32 v[64:65], v[74:75], v[64:65], v[128:129] op_sel:[1,0,0]
	s_nop 0
	v_pk_fma_f32 v[66:67], v[120:121], v[74:75], v[82:83] op_sel_hi:[1,0,1] neg_lo:[1,0,0] neg_hi:[1,0,0]
	v_pk_fma_f32 v[68:69], v[116:117], v[74:75], v[70:71] op_sel_hi:[1,0,1]
	v_pk_fma_f32 v[70:71], v[118:119], v[74:75], v[72:73] op_sel_hi:[1,0,1]
	v_pk_fma_f32 v[68:69], v[74:75], v[68:69], v[138:139] op_sel:[1,0,0]
	v_pk_fma_f32 v[66:67], v[74:75], v[66:67], v[136:137] op_sel:[1,0,0]
	v_pk_fma_f32 v[70:71], v[74:75], v[70:71], v[130:131] op_sel:[1,0,0]
	v_max_f32_e32 v64, 0, v64
	v_max_f32_e32 v65, 0, v65
	v_max_f32_e32 v66, 0, v66
	v_mul_f32_e32 v72, v64, v64
	v_max_f32_e32 v64, 0, v67
	v_mul_f32_e32 v67, v65, v65
	v_max_f32_e32 v65, 0, v68
	v_max_f32_e32 v68, 0, v70
	v_mul_f32_e32 v66, v66, v66
	v_mul_f32_e32 v64, v64, v64
	v_mul_f32_e32 v65, v65, v65
	v_mul_f32_e32 v68, v68, v68
	v_max_f32_e32 v69, 0, v69
	v_max_f32_e32 v70, 0, v71
	v_mul_f32_e32 v69, v69, v69
	v_mul_f32_e32 v70, v70, v70
	v_cvt_pk_bf16_f32 v64, v66, v64
	v_cvt_pk_bf16_f32 v65, v65, v69
	v_cvt_pk_bf16_f32 v66, v72, v67
	v_cvt_pk_bf16_f32 v67, v68, v70
	v_add_u32_e32 v68, 0x1880, v170
	global_store_dwordx4 v68, v[64:67], s[18:19] nt
	s_nop 0
	v_cndmask_b32_e64 v71, v56, v48, s[14:15]
	v_cndmask_b32_e64 v67, v60, v52, s[14:15]
	v_cndmask_b32_e64 v66, v61, v53, s[14:15]
	s_nop 0
	v_mov_b32_dpp v68, v67 quad_perm:[1,0,3,2] row_mask:0xf bank_mask:0xf
	s_nop 0
	v_cndmask_b32_e64 v64, v63, v55, s[14:15]
	v_cndmask_b32_e64 v65, v62, v54, s[14:15]
	v_mov_b32_dpp v67, v66 quad_perm:[1,0,3,2] row_mask:0xf bank_mask:0xf
	s_nop 0
	s_nop 0
	v_cndmask_b32_e64 v70, v57, v49, s[14:15]
	v_mov_b32_dpp v72, v71 quad_perm:[1,0,3,2] row_mask:0xf bank_mask:0xf
	s_nop 0
	v_mov_b32_dpp v66, v65 quad_perm:[1,0,3,2] row_mask:0xf bank_mask:0xf
	v_mov_b32_dpp v69, v64 quad_perm:[1,0,3,2] row_mask:0xf bank_mask:0xf
	v_cndmask_b32_e64 v64, v59, v51, s[14:15]
	v_cndmask_b32_e64 v65, v58, v50, s[14:15]
	v_mov_b32_dpp v71, v70 quad_perm:[1,0,3,2] row_mask:0xf bank_mask:0xf
	s_nop 0
	s_nop 0
	v_cndmask_b32_e64 v57, v71, v57, s[14:15]
	v_mov_b32_dpp v70, v65 quad_perm:[1,0,3,2] row_mask:0xf bank_mask:0xf
	v_mov_b32_dpp v73, v64 quad_perm:[1,0,3,2] row_mask:0xf bank_mask:0xf
	ds_read_b64 v[64:65], v164 offset:1024
	v_cndmask_b32_e64 v56, v72, v56, s[14:15]
	v_cndmask_b32_e64 v63, v69, v63, s[14:15]
	v_cndmask_b32_e64 v62, v66, v62, s[14:15]
	v_cndmask_b32_e64 v61, v67, v61, s[14:15]
	s_waitcnt lgkmcnt(0)
	v_pk_fma_f32 v[56:57], v[132:133], v[64:65], v[56:57] op_sel_hi:[1,0,1] neg_lo:[1,0,0] neg_hi:[1,0,0]
	v_cndmask_b32_e64 v60, v68, v60, s[14:15]
	v_pk_fma_f32 v[56:57], v[64:65], v[56:57], v[128:129] op_sel:[1,0,0]
	v_cndmask_b32_e64 v59, v73, v59, s[14:15]
	v_cndmask_b32_e64 v58, v70, v58, s[14:15]
	v_cndmask_b32_e64 v54, v54, v66, s[14:15]
	v_cndmask_b32_e64 v67, v53, v67, s[14:15]
	v_cndmask_b32_e64 v66, v52, v68, s[14:15]
	v_pk_fma_f32 v[52:53], v[120:121], v[64:65], v[60:61] op_sel_hi:[1,0,1] neg_lo:[1,0,0] neg_hi:[1,0,0]
	v_pk_fma_f32 v[60:61], v[116:117], v[64:65], v[62:63] op_sel_hi:[1,0,1]
	v_max_f32_e32 v56, 0, v56
	v_pk_fma_f32 v[60:61], v[64:65], v[60:61], v[138:139] op_sel:[1,0,0]
	v_pk_fma_f32 v[58:59], v[118:119], v[64:65], v[58:59] op_sel_hi:[1,0,1]
	v_mul_f32_e32 v62, v56, v56
	v_max_f32_e32 v56, 0, v57
	v_pk_fma_f32 v[52:53], v[64:65], v[52:53], v[136:137] op_sel:[1,0,0]
	v_pk_fma_f32 v[58:59], v[64:65], v[58:59], v[130:131] op_sel:[1,0,0]
	v_mul_f32_e32 v63, v56, v56
	v_max_f32_e32 v56, 0, v60
	v_max_f32_e32 v52, 0, v52
	v_max_f32_e32 v53, 0, v53
	v_max_f32_e32 v57, 0, v58
	v_mul_f32_e32 v58, v56, v56
	v_max_f32_e32 v56, 0, v61
	v_mul_f32_e32 v52, v52, v52
	v_mul_f32_e32 v53, v53, v53
	v_mul_f32_e32 v60, v57, v57
	v_max_f32_e32 v57, 0, v59
	v_mul_f32_e32 v59, v56, v56
	v_mul_f32_e32 v61, v57, v57
	v_cndmask_b32_e64 v57, v51, v73, s[14:15]
	v_cndmask_b32_e64 v56, v50, v70, s[14:15]
	v_cvt_pk_bf16_f32 v50, v52, v53
	v_cvt_pk_bf16_f32 v51, v58, v59
	v_cvt_pk_bf16_f32 v52, v62, v63
	v_cvt_pk_bf16_f32 v53, v60, v61
	ds_read_b64 v[58:59], v164 offset:1032
	v_cndmask_b32_e64 v49, v49, v71, s[14:15]
	v_cndmask_b32_e64 v48, v48, v72, s[14:15]
	v_cndmask_b32_e64 v55, v55, v69, s[14:15]
	v_add_u32_e32 v60, 0x4000, v170
	s_waitcnt lgkmcnt(0)
	v_pk_fma_f32 v[48:49], v[132:133], v[58:59], v[48:49] op_sel_hi:[1,0,1] neg_lo:[1,0,0] neg_hi:[1,0,0]
	global_store_dwordx4 v60, v[50:53], s[18:19] nt
	v_pk_fma_f32 v[48:49], v[58:59], v[48:49], v[128:129] op_sel:[1,0,0]
	s_nop 0
	v_pk_fma_f32 v[50:51], v[120:121], v[58:59], v[66:67] op_sel_hi:[1,0,1] neg_lo:[1,0,0] neg_hi:[1,0,0]
	v_pk_fma_f32 v[52:53], v[116:117], v[58:59], v[54:55] op_sel_hi:[1,0,1]
	v_pk_fma_f32 v[54:55], v[118:119], v[58:59], v[56:57] op_sel_hi:[1,0,1]
	v_pk_fma_f32 v[52:53], v[58:59], v[52:53], v[138:139] op_sel:[1,0,0]
	v_pk_fma_f32 v[50:51], v[58:59], v[50:51], v[136:137] op_sel:[1,0,0]
	v_pk_fma_f32 v[54:55], v[58:59], v[54:55], v[130:131] op_sel:[1,0,0]
	v_max_f32_e32 v48, 0, v48
	v_max_f32_e32 v49, 0, v49
	v_max_f32_e32 v50, 0, v50
	v_mul_f32_e32 v56, v48, v48
	v_max_f32_e32 v48, 0, v51
	v_mul_f32_e32 v51, v49, v49
	v_max_f32_e32 v49, 0, v52
	v_max_f32_e32 v52, 0, v54
	v_mul_f32_e32 v50, v50, v50
	v_mul_f32_e32 v48, v48, v48
	v_mul_f32_e32 v49, v49, v49
	v_mul_f32_e32 v52, v52, v52
	v_max_f32_e32 v53, 0, v53
	v_max_f32_e32 v54, 0, v55
	v_mul_f32_e32 v53, v53, v53
	v_mul_f32_e32 v54, v54, v54
	v_cvt_pk_bf16_f32 v48, v50, v48
	v_cvt_pk_bf16_f32 v49, v49, v53
	v_cvt_pk_bf16_f32 v50, v56, v51
	v_cvt_pk_bf16_f32 v51, v52, v54
	v_add_u32_e32 v52, 0x4080, v170
	global_store_dwordx4 v52, v[48:51], s[18:19] nt
	ds_read_b64 v[48:49], v164 offset:1152
	v_cndmask_b32_e64 v53, v44, v36, s[14:15]
	s_nop 0
	v_cndmask_b32_e64 v57, v40, v32, s[14:15]
	s_nop 0
	v_cndmask_b32_e64 v52, v45, v37, s[14:15]
	v_mov_b32_dpp v54, v53 quad_perm:[1,0,3,2] row_mask:0xf bank_mask:0xf
	s_nop 0
	v_cndmask_b32_e64 v56, v41, v33, s[14:15]
	v_mov_b32_dpp v58, v57 quad_perm:[1,0,3,2] row_mask:0xf bank_mask:0xf
	s_nop 0
	v_cndmask_b32_e64 v51, v46, v38, s[14:15]
	v_mov_b32_dpp v53, v52 quad_perm:[1,0,3,2] row_mask:0xf bank_mask:0xf
	s_nop 0
	v_mov_b32_dpp v57, v56 quad_perm:[1,0,3,2] row_mask:0xf bank_mask:0xf
	v_cndmask_b32_e64 v50, v47, v39, s[14:15]
	v_mov_b32_dpp v52, v51 quad_perm:[1,0,3,2] row_mask:0xf bank_mask:0xf
	s_nop 0
	v_cndmask_b32_e64 v55, v42, v34, s[14:15]
	s_nop 0
	v_cndmask_b32_e64 v41, v57, v41, s[14:15]
	v_cndmask_b32_e64 v40, v58, v40, s[14:15]
	v_mov_b32_dpp v51, v50 quad_perm:[1,0,3,2] row_mask:0xf bank_mask:0xf
	v_cndmask_b32_e64 v50, v43, v35, s[14:15]
	v_mov_b32_dpp v56, v55 quad_perm:[1,0,3,2] row_mask:0xf bank_mask:0xf
	s_nop 0
	s_waitcnt lgkmcnt(0)
; __device__ __forceinline__ float dpp_x1(float x) { return __builtin_bit_cast(float, __builtin_amdgcn_update_dpp(0, __builtin_bit_cast(int, x), 0xB1, 0xF, 0xF, false)); }
; __device__ __forceinline__ f32x4 dpp_swap1(f32x4 v) { f32x4 r; r[0] = dpp_x1(v[0]); r[1] = dpp_x1(v[1]); r[2] = dpp_x1(v[2]); r[3] = dpp_x1(v[3]); return r; }
;     __device__ __forceinline__ void operator()(const f32x4 (&acc)[2][2][4][2], const Unit& u, int wr, int wc, int fr, int fq, const EpiCtx& X) const {
;     ...
;         EPI_PIECES({ const unsigned off = lo + (unsigned)(rl * RP) * 2u; LN_ONE(p1a, p1b, rl, off); LN_ONE(p2a, p2b, rl + 1, off + RP * 2); })
	v_pk_fma_f32 v[40:41], v[132:133], v[48:49], v[40:41] op_sel_hi:[1,0,1] neg_lo:[1,0,0] neg_hi:[1,0,0]
	v_cndmask_b32_e64 v47, v51, v47, s[14:15]
	v_mov_b32_dpp v55, v50 quad_perm:[1,0,3,2] row_mask:0xf bank_mask:0xf
	v_cndmask_b32_e64 v46, v52, v46, s[14:15]
	v_cndmask_b32_e64 v45, v53, v45, s[14:15]
	v_cndmask_b32_e64 v44, v54, v44, s[14:15]
	v_pk_fma_f32 v[40:41], v[48:49], v[40:41], v[128:129] op_sel:[1,0,0]
	v_cndmask_b32_e64 v43, v55, v43, s[14:15]
	v_cndmask_b32_e64 v42, v56, v42, s[14:15]
	v_cndmask_b32_e64 v39, v39, v51, s[14:15]
	v_cndmask_b32_e64 v51, v37, v53, s[14:15]
	v_cndmask_b32_e64 v50, v36, v54, s[14:15]
	v_pk_fma_f32 v[36:37], v[120:121], v[48:49], v[44:45] op_sel_hi:[1,0,1] neg_lo:[1,0,0] neg_hi:[1,0,0]
	v_pk_fma_f32 v[44:45], v[116:117], v[48:49], v[46:47] op_sel_hi:[1,0,1]
	v_max_f32_e32 v40, 0, v40
	v_pk_fma_f32 v[44:45], v[48:49], v[44:45], v[138:139] op_sel:[1,0,0]
	v_pk_fma_f32 v[42:43], v[118:119], v[48:49], v[42:43] op_sel_hi:[1,0,1]
	v_mul_f32_e32 v46, v40, v40
	v_max_f32_e32 v40, 0, v41
	v_pk_fma_f32 v[36:37], v[48:49], v[36:37], v[136:137] op_sel:[1,0,0]
	v_pk_fma_f32 v[42:43], v[48:49], v[42:43], v[130:131] op_sel:[1,0,0]
	v_mul_f32_e32 v47, v40, v40
	v_max_f32_e32 v40, 0, v44
	v_max_f32_e32 v36, 0, v36
	v_max_f32_e32 v37, 0, v37
	v_max_f32_e32 v41, 0, v42
	v_mul_f32_e32 v42, v40, v40
	v_max_f32_e32 v40, 0, v45
	v_mul_f32_e32 v36, v36, v36
	v_mul_f32_e32 v37, v37, v37
	v_mul_f32_e32 v44, v41, v41
	v_max_f32_e32 v41, 0, v43
	v_mul_f32_e32 v43, v40, v40
	v_mul_f32_e32 v45, v41, v41
	v_cndmask_b32_e64 v41, v35, v55, s[14:15]
	v_cndmask_b32_e64 v40, v34, v56, s[14:15]
	v_cvt_pk_bf16_f32 v34, v36, v37
	v_cvt_pk_bf16_f32 v35, v42, v43
	v_cvt_pk_bf16_f32 v36, v46, v47
	v_cvt_pk_bf16_f32 v37, v44, v45
	ds_read_b64 v[42:43], v164 offset:1160
	v_cndmask_b32_e64 v33, v33, v57, s[14:15]
	v_cndmask_b32_e64 v32, v32, v58, s[14:15]
	v_cndmask_b32_e64 v38, v38, v52, s[14:15]
	v_add_u32_e32 v44, 0x4800, v170
	s_waitcnt lgkmcnt(0)
	v_pk_fma_f32 v[32:33], v[132:133], v[42:43], v[32:33] op_sel_hi:[1,0,1] neg_lo:[1,0,0] neg_hi:[1,0,0]
	global_store_dwordx4 v44, v[34:37], s[18:19] nt
	v_pk_fma_f32 v[32:33], v[42:43], v[32:33], v[128:129] op_sel:[1,0,0]
	s_nop 0
	v_pk_fma_f32 v[34:35], v[120:121], v[42:43], v[50:51] op_sel_hi:[1,0,1] neg_lo:[1,0,0] neg_hi:[1,0,0]
	v_pk_fma_f32 v[36:37], v[116:117], v[42:43], v[38:39] op_sel_hi:[1,0,1]
	v_pk_fma_f32 v[38:39], v[118:119], v[42:43], v[40:41] op_sel_hi:[1,0,1]
	v_pk_fma_f32 v[36:37], v[42:43], v[36:37], v[138:139] op_sel:[1,0,0]
	v_pk_fma_f32 v[34:35], v[42:43], v[34:35], v[136:137] op_sel:[1,0,0]
	v_pk_fma_f32 v[38:39], v[42:43], v[38:39], v[130:131] op_sel:[1,0,0]
	v_max_f32_e32 v32, 0, v32
	v_max_f32_e32 v33, 0, v33
	v_max_f32_e32 v34, 0, v34
	v_mul_f32_e32 v40, v32, v32
	v_max_f32_e32 v32, 0, v35
	v_mul_f32_e32 v35, v33, v33
	v_max_f32_e32 v33, 0, v36
	v_max_f32_e32 v36, 0, v38
	v_mul_f32_e32 v34, v34, v34
	v_mul_f32_e32 v32, v32, v32
	v_mul_f32_e32 v33, v33, v33
	v_mul_f32_e32 v36, v36, v36
	v_max_f32_e32 v37, 0, v37
	v_max_f32_e32 v38, 0, v39
	v_mul_f32_e32 v37, v37, v37
	v_mul_f32_e32 v38, v38, v38
	v_cvt_pk_bf16_f32 v32, v34, v32
	v_cvt_pk_bf16_f32 v33, v33, v37
	v_cvt_pk_bf16_f32 v34, v40, v35
	v_cvt_pk_bf16_f32 v35, v36, v38
	v_add_u32_e32 v36, 0x4880, v170
	global_store_dwordx4 v36, v[32:35], s[18:19] nt
	s_nop 0
	v_cndmask_b32_e64 v39, v24, v16, s[14:15]
	v_cndmask_b32_e64 v35, v28, v20, s[14:15]
	v_cndmask_b32_e64 v34, v29, v21, s[14:15]
	s_nop 0
	v_mov_b32_dpp v36, v35 quad_perm:[1,0,3,2] row_mask:0xf bank_mask:0xf
	s_nop 0
	v_cndmask_b32_e64 v32, v31, v23, s[14:15]
	v_cndmask_b32_e64 v33, v30, v22, s[14:15]
	v_mov_b32_dpp v35, v34 quad_perm:[1,0,3,2] row_mask:0xf bank_mask:0xf
	s_nop 0
	s_nop 0
	v_cndmask_b32_e64 v38, v25, v17, s[14:15]
	v_mov_b32_dpp v40, v39 quad_perm:[1,0,3,2] row_mask:0xf bank_mask:0xf
	s_nop 0
	v_mov_b32_dpp v34, v33 quad_perm:[1,0,3,2] row_mask:0xf bank_mask:0xf
	v_mov_b32_dpp v37, v32 quad_perm:[1,0,3,2] row_mask:0xf bank_mask:0xf
	v_cndmask_b32_e64 v32, v27, v19, s[14:15]
	v_cndmask_b32_e64 v33, v26, v18, s[14:15]
	v_mov_b32_dpp v39, v38 quad_perm:[1,0,3,2] row_mask:0xf bank_mask:0xf
	s_nop 0
	s_nop 0
	v_cndmask_b32_e64 v25, v39, v25, s[14:15]
	v_mov_b32_dpp v38, v33 quad_perm:[1,0,3,2] row_mask:0xf bank_mask:0xf
	v_mov_b32_dpp v41, v32 quad_perm:[1,0,3,2] row_mask:0xf bank_mask:0xf
	ds_read_b64 v[32:33], v164 offset:1280
	v_cndmask_b32_e64 v24, v40, v24, s[14:15]
	v_cndmask_b32_e64 v31, v37, v31, s[14:15]
	v_cndmask_b32_e64 v30, v34, v30, s[14:15]
	v_cndmask_b32_e64 v29, v35, v29, s[14:15]
	s_waitcnt lgkmcnt(0)
	v_pk_fma_f32 v[24:25], v[132:133], v[32:33], v[24:25] op_sel_hi:[1,0,1] neg_lo:[1,0,0] neg_hi:[1,0,0]
	v_cndmask_b32_e64 v28, v36, v28, s[14:15]
	v_pk_fma_f32 v[24:25], v[32:33], v[24:25], v[128:129] op_sel:[1,0,0]
	v_cndmask_b32_e64 v27, v41, v27, s[14:15]
	v_cndmask_b32_e64 v26, v38, v26, s[14:15]
	v_cndmask_b32_e64 v22, v22, v34, s[14:15]
	v_cndmask_b32_e64 v35, v21, v35, s[14:15]
	v_cndmask_b32_e64 v34, v20, v36, s[14:15]
	v_pk_fma_f32 v[20:21], v[120:121], v[32:33], v[28:29] op_sel_hi:[1,0,1] neg_lo:[1,0,0] neg_hi:[1,0,0]
	v_pk_fma_f32 v[28:29], v[116:117], v[32:33], v[30:31] op_sel_hi:[1,0,1]
	v_max_f32_e32 v24, 0, v24
	v_pk_fma_f32 v[28:29], v[32:33], v[28:29], v[138:139] op_sel:[1,0,0]
	v_pk_fma_f32 v[26:27], v[118:119], v[32:33], v[26:27] op_sel_hi:[1,0,1]
	v_mul_f32_e32 v30, v24, v24
	v_max_f32_e32 v24, 0, v25
	v_pk_fma_f32 v[20:21], v[32:33], v[20:21], v[136:137] op_sel:[1,0,0]
	v_pk_fma_f32 v[26:27], v[32:33], v[26:27], v[130:131] op_sel:[1,0,0]
	v_mul_f32_e32 v31, v24, v24
	v_max_f32_e32 v24, 0, v28
	v_max_f32_e32 v20, 0, v20
	v_max_f32_e32 v21, 0, v21
	v_max_f32_e32 v25, 0, v26
	v_mul_f32_e32 v26, v24, v24
	v_max_f32_e32 v24, 0, v29
	v_mul_f32_e32 v20, v20, v20
	v_mul_f32_e32 v21, v21, v21
	v_mul_f32_e32 v28, v25, v25
	v_max_f32_e32 v25, 0, v27
	v_mul_f32_e32 v27, v24, v24
	v_mul_f32_e32 v29, v25, v25
	v_cndmask_b32_e64 v25, v19, v41, s[14:15]
	v_cndmask_b32_e64 v24, v18, v38, s[14:15]
	v_cvt_pk_bf16_f32 v18, v20, v21
	v_cvt_pk_bf16_f32 v19, v26, v27
	v_cvt_pk_bf16_f32 v20, v30, v31
	v_cvt_pk_bf16_f32 v21, v28, v29
	ds_read_b64 v[26:27], v164 offset:1288
	v_cndmask_b32_e64 v17, v17, v39, s[14:15]
	v_cndmask_b32_e64 v16, v16, v40, s[14:15]
	v_cndmask_b32_e64 v23, v23, v37, s[14:15]
	v_add_u32_e32 v28, 0x5000, v170
	s_waitcnt lgkmcnt(0)
; __device__ __forceinline__ float dpp_x1(float x) { return __builtin_bit_cast(float, __builtin_amdgcn_update_dpp(0, __builtin_bit_cast(int, x), 0xB1, 0xF, 0xF, false)); }
; __device__ __forceinline__ f32x4 dpp_swap1(f32x4 v) { f32x4 r; r[0] = dpp_x1(v[0]); r[1] = dpp_x1(v[1]); r[2] = dpp_x1(v[2]); r[3] = dpp_x1(v[3]); return r; }
;     __device__ __forceinline__ void operator()(const f32x4 (&acc)[2][2][4][2], const Unit& u, int wr, int wc, int fr, int fq, const EpiCtx& X) const {
;     ...
;         EPI_PIECES({ const unsigned off = lo + (unsigned)(rl * RP) * 2u; LN_ONE(p1a, p1b, rl, off); LN_ONE(p2a, p2b, rl + 1, off + RP * 2); })
	v_pk_fma_f32 v[16:17], v[132:133], v[26:27], v[16:17] op_sel_hi:[1,0,1] neg_lo:[1,0,0] neg_hi:[1,0,0]
	global_store_dwordx4 v28, v[18:21], s[18:19] nt
	v_pk_fma_f32 v[16:17], v[26:27], v[16:17], v[128:129] op_sel:[1,0,0]
	s_nop 0
	v_pk_fma_f32 v[18:19], v[120:121], v[26:27], v[34:35] op_sel_hi:[1,0,1] neg_lo:[1,0,0] neg_hi:[1,0,0]
	v_pk_fma_f32 v[20:21], v[116:117], v[26:27], v[22:23] op_sel_hi:[1,0,1]
	v_pk_fma_f32 v[22:23], v[118:119], v[26:27], v[24:25] op_sel_hi:[1,0,1]
	v_pk_fma_f32 v[20:21], v[26:27], v[20:21], v[138:139] op_sel:[1,0,0]
	v_pk_fma_f32 v[18:19], v[26:27], v[18:19], v[136:137] op_sel:[1,0,0]
	v_pk_fma_f32 v[22:23], v[26:27], v[22:23], v[130:131] op_sel:[1,0,0]
	v_max_f32_e32 v16, 0, v16
	v_max_f32_e32 v17, 0, v17
	v_max_f32_e32 v18, 0, v18
	v_mul_f32_e32 v24, v16, v16
	v_max_f32_e32 v16, 0, v19
	v_mul_f32_e32 v19, v17, v17
	v_max_f32_e32 v17, 0, v20
	v_max_f32_e32 v20, 0, v22
	v_mul_f32_e32 v18, v18, v18
	v_mul_f32_e32 v16, v16, v16
	v_mul_f32_e32 v17, v17, v17
	v_mul_f32_e32 v20, v20, v20
	v_max_f32_e32 v21, 0, v21
	v_max_f32_e32 v22, 0, v23
	v_mul_f32_e32 v21, v21, v21
	v_mul_f32_e32 v22, v22, v22
	v_cvt_pk_bf16_f32 v16, v18, v16
	v_cvt_pk_bf16_f32 v17, v17, v21
	v_cvt_pk_bf16_f32 v18, v24, v19
	v_cvt_pk_bf16_f32 v19, v20, v22
	v_add_u32_e32 v20, 0x5080, v170
	global_store_dwordx4 v20, v[16:19], s[18:19] nt
	ds_read_b64 v[16:17], v164 offset:1408
	v_cndmask_b32_e64 v21, v12, v4, s[14:15]
	s_nop 0
	v_cndmask_b32_e64 v25, v8, v0, s[14:15]
	s_nop 0
	v_cndmask_b32_e64 v20, v13, v5, s[14:15]
	v_mov_b32_dpp v22, v21 quad_perm:[1,0,3,2] row_mask:0xf bank_mask:0xf
	s_nop 0
	v_cndmask_b32_e64 v24, v9, v1, s[14:15]
	v_mov_b32_dpp v26, v25 quad_perm:[1,0,3,2] row_mask:0xf bank_mask:0xf
	s_nop 0
	v_cndmask_b32_e64 v19, v14, v6, s[14:15]
	v_mov_b32_dpp v21, v20 quad_perm:[1,0,3,2] row_mask:0xf bank_mask:0xf
	s_nop 0
	v_mov_b32_dpp v25, v24 quad_perm:[1,0,3,2] row_mask:0xf bank_mask:0xf
	v_cndmask_b32_e64 v18, v15, v7, s[14:15]
	v_mov_b32_dpp v20, v19 quad_perm:[1,0,3,2] row_mask:0xf bank_mask:0xf
	s_nop 0
	v_cndmask_b32_e64 v23, v10, v2, s[14:15]
	s_nop 0
	v_cndmask_b32_e64 v9, v25, v9, s[14:15]
	v_cndmask_b32_e64 v8, v26, v8, s[14:15]
	v_mov_b32_dpp v19, v18 quad_perm:[1,0,3,2] row_mask:0xf bank_mask:0xf
	v_cndmask_b32_e64 v18, v11, v3, s[14:15]
	v_mov_b32_dpp v24, v23 quad_perm:[1,0,3,2] row_mask:0xf bank_mask:0xf
	s_nop 0
	s_waitcnt lgkmcnt(0)
	v_pk_fma_f32 v[8:9], v[132:133], v[16:17], v[8:9] op_sel_hi:[1,0,1] neg_lo:[1,0,0] neg_hi:[1,0,0]
	v_cndmask_b32_e64 v15, v19, v15, s[14:15]
	v_mov_b32_dpp v23, v18 quad_perm:[1,0,3,2] row_mask:0xf bank_mask:0xf
	v_cndmask_b32_e64 v14, v20, v14, s[14:15]
	v_cndmask_b32_e64 v13, v21, v13, s[14:15]
	v_cndmask_b32_e64 v12, v22, v12, s[14:15]
	v_pk_fma_f32 v[8:9], v[16:17], v[8:9], v[128:129] op_sel:[1,0,0]
	v_cndmask_b32_e64 v11, v23, v11, s[14:15]
	v_cndmask_b32_e64 v10, v24, v10, s[14:15]
	v_cndmask_b32_e64 v7, v7, v19, s[14:15]
	v_cndmask_b32_e64 v19, v5, v21, s[14:15]
	v_cndmask_b32_e64 v18, v4, v22, s[14:15]
	v_pk_fma_f32 v[4:5], v[120:121], v[16:17], v[12:13] op_sel_hi:[1,0,1] neg_lo:[1,0,0] neg_hi:[1,0,0]
	v_pk_fma_f32 v[12:13], v[116:117], v[16:17], v[14:15] op_sel_hi:[1,0,1]
	v_max_f32_e32 v8, 0, v8
	v_pk_fma_f32 v[12:13], v[16:17], v[12:13], v[138:139] op_sel:[1,0,0]
	v_pk_fma_f32 v[10:11], v[118:119], v[16:17], v[10:11] op_sel_hi:[1,0,1]
	v_mul_f32_e32 v14, v8, v8
	v_max_f32_e32 v8, 0, v9
	v_pk_fma_f32 v[4:5], v[16:17], v[4:5], v[136:137] op_sel:[1,0,0]
	v_pk_fma_f32 v[10:11], v[16:17], v[10:11], v[130:131] op_sel:[1,0,0]
	v_mul_f32_e32 v15, v8, v8
	v_max_f32_e32 v8, 0, v12
	v_max_f32_e32 v4, 0, v4
	v_max_f32_e32 v5, 0, v5
	v_max_f32_e32 v9, 0, v10
	v_mul_f32_e32 v10, v8, v8
	v_max_f32_e32 v8, 0, v13
	v_mul_f32_e32 v4, v4, v4
	v_mul_f32_e32 v5, v5, v5
	v_mul_f32_e32 v12, v9, v9
	v_max_f32_e32 v9, 0, v11
	v_mul_f32_e32 v11, v8, v8
	v_mul_f32_e32 v13, v9, v9
	v_cndmask_b32_e64 v9, v3, v23, s[14:15]
	v_cndmask_b32_e64 v8, v2, v24, s[14:15]
	v_cvt_pk_bf16_f32 v2, v4, v5
	v_cvt_pk_bf16_f32 v3, v10, v11
	v_cvt_pk_bf16_f32 v4, v14, v15
	v_cvt_pk_bf16_f32 v5, v12, v13
	ds_read_b64 v[10:11], v164 offset:1416
	v_cndmask_b32_e64 v1, v1, v25, s[14:15]
	v_cndmask_b32_e64 v0, v0, v26, s[14:15]
	v_cndmask_b32_e64 v6, v6, v20, s[14:15]
	v_add_u32_e32 v12, 0x5800, v170
	s_waitcnt lgkmcnt(0)
	v_pk_fma_f32 v[0:1], v[132:133], v[10:11], v[0:1] op_sel_hi:[1,0,1] neg_lo:[1,0,0] neg_hi:[1,0,0]
	global_store_dwordx4 v12, v[2:5], s[18:19] nt
	v_pk_fma_f32 v[0:1], v[10:11], v[0:1], v[128:129] op_sel:[1,0,0]
	s_nop 0
	v_pk_fma_f32 v[2:3], v[120:121], v[10:11], v[18:19] op_sel_hi:[1,0,1] neg_lo:[1,0,0] neg_hi:[1,0,0]
	v_pk_fma_f32 v[4:5], v[116:117], v[10:11], v[6:7] op_sel_hi:[1,0,1]
	v_pk_fma_f32 v[6:7], v[118:119], v[10:11], v[8:9] op_sel_hi:[1,0,1]
	v_pk_fma_f32 v[4:5], v[10:11], v[4:5], v[138:139] op_sel:[1,0,0]
	v_pk_fma_f32 v[2:3], v[10:11], v[2:3], v[136:137] op_sel:[1,0,0]
	v_pk_fma_f32 v[6:7], v[10:11], v[6:7], v[130:131] op_sel:[1,0,0]
	v_max_f32_e32 v0, 0, v0
	v_max_f32_e32 v1, 0, v1
	v_max_f32_e32 v2, 0, v2
	v_mul_f32_e32 v8, v0, v0
	v_max_f32_e32 v0, 0, v3
	v_mul_f32_e32 v3, v1, v1
	v_max_f32_e32 v1, 0, v4
	v_max_f32_e32 v4, 0, v6
	v_mul_f32_e32 v2, v2, v2
	v_mul_f32_e32 v0, v0, v0
	v_mul_f32_e32 v1, v1, v1
	v_mul_f32_e32 v4, v4, v4
	v_max_f32_e32 v5, 0, v5
	v_max_f32_e32 v6, 0, v7
	v_mul_f32_e32 v5, v5, v5
	v_mul_f32_e32 v6, v6, v6
	v_cvt_pk_bf16_f32 v0, v2, v0
	v_cvt_pk_bf16_f32 v1, v1, v5
	v_cvt_pk_bf16_f32 v2, v8, v3
	v_cvt_pk_bf16_f32 v3, v4, v6
	v_add_u32_e32 v4, 0x5880, v170
	global_store_dwordx4 v4, v[0:3], s[18:19] nt
	s_cbranch_vccnz .LBB0_679
	s_and_b64 vcc, exec, s[8:9]
	s_cbranch_vccnz .LBB0_678
	s_barrier
	s_branch .LBB0_678

; #define LAS __attribute__((address_space(3)))
;     __device__ __forceinline__ void operator()(const f32x4 (&acc)[2][2][4][2], const Unit& u, int wr, int wc, int fr, int fq, const EpiCtx& X) const {
;     ...
;         char* yb = nullptr; char* xb = (char*)(XB + (size_t)u.pm * BM * DM + (size_t)(u.pn * 4 + wc) * (BM * 64));
;         unsigned lo = (unsigned)((wr * 64 + fe) * 64 + o32 + 8 * fq) * 2u; EPI_OPAQUE(lo);
;         const int col = u.pn * BM + wc * 64 + o32 + 8 * fq;
;         f32x4 g0, g1, b0, b1;
;         if (RESN) { ensure_tbl(PSp, sidp, u.pm, X);
;             g0 = *(const f32x4*)(gp + col); g1 = *(const f32x4*)(gp + col + 4); b0 = *(const f32x4*)(bp + col) * ALPHA; b1 = *(const f32x4*)(bp + col + 4) * ALPHA; }
;         const LAS f32x2* tbl = (const LAS f32x2*)(X.lds + TBL_OFF) + wr * 64 + fe;
;         f32x2* ps = PSn + ((size_t)u.pm * BM + wr * 64 + fe) * 64 + u.pn * 4 + wc;
; #pragma unroll
;         for (int ai = 0; ai < 2; ++ai) {
;             u32x4 raw[8];
; #pragma unroll
;             for (int m = 0; m < 4; ++m) { const unsigned off = lo + (unsigned)((ai * HALF + m * 16) * 64) * 2u; raw[2 * m] = *(const u32x4*)(xb + off); raw[2 * m + 1] = *(const u32x4*)(xb + off + 128); }
; #pragma unroll
;             for (int m = 0; m < 4; ++m) {
;                 const int rl = ai * HALF + m * 16; const unsigned off = lo + (unsigned)(rl * 64) * 2u;
;                 const f32x4 o0a = acc[ai][0][m][0], o0b = acc[ai][0][m][1], o1a = acc[ai][1][m][0], o1b = acc[ai][1][m][1];
;                 const f32x4 ra_ = dpp_swap1(odd ? o0a : o1a), rb_ = dpp_swap1(odd ? o0b : o1b);
;                 const f32x4 pa[2] = {odd ? ra_ : o0a, odd ? o1a : ra_}, pb[2] = {odd ? rb_ : o0b, odd ? o1b : rb_};
; #pragma unroll
;                 for (int q = 0; q < 2; ++q) {
;                     const u32x4 w0 = raw[2 * m + q];
;                     const f32x4 r0 = (f32x4){bf_lo(w0.x), bf_hi(w0.x), bf_lo(w0.y), bf_hi(w0.y)}, r1 = (f32x4){bf_lo(w0.z), bf_hi(w0.z), bf_lo(w0.w), bf_hi(w0.w)};
;                     f32x4 y0, y1;
;                     if (RESN) { const f32x2 t = tbl[rl + q]; const float mu = t.x, ra = t.y * ALPHA; y0 = (r0 - mu) * ra * g0 + b0 + pa[q]; y1 = (r1 - mu) * ra * g1 + b1 + pb[q]; }
;                     else { y0 = r0 * ALPHA + pa[q]; y1 = r1 * ALPHA + pb[q]; }
;                     { const u32x4 w = pack8f(y0, y1); *(u32x4*)(xb + off + q * 128) = w;
.LBB0_816:
	s_lshl_b64 s[4:5], s[70:71], 21
	s_add_u32 s20, s57, s4
	s_addc_u32 s21, s59, s5
	s_lshl_b32 s70, s68, 2
	s_or_b32 s4, s70, s41
	s_ashr_i32 s5, s4, 31
	v_lshl_add_u32 v72, s68, 8, v200
	v_ashrrev_i32_e32 v73, 31, v72
	s_lshl_b64 s[4:5], s[4:5], 15
	v_lshlrev_b64 v[72:73], 2, v[72:73]
	s_add_u32 s20, s20, s4
	v_lshl_add_u64 v[74:75], s[26:27], 0, v[72:73]
	s_addc_u32 s21, s21, s5
	global_load_dwordx4 v[194:197], v[74:75], off offset:16
	global_load_dwordx4 v[178:181], v[74:75], off
	global_load_dwordx4 v[214:217], v164, s[20:21]
	v_lshl_add_u64 v[72:73], s[24:25], 0, v[72:73]
	s_waitcnt lgkmcnt(0)
	global_load_dwordx4 v[76:79], v[72:73], off
	s_nop 0
	global_load_dwordx4 v[72:75], v[72:73], off offset:16
	v_cndmask_b32_e64 v136, v135, v127, s[10:11]
	v_cndmask_b32_e64 v137, v134, v126, s[10:11]
	v_cndmask_b32_e64 v138, v133, v125, s[10:11]
	v_cndmask_b32_e64 v139, v132, v124, s[10:11]
	s_nop 0
	s_nop 0
	s_nop 0
	s_nop 0
	v_cndmask_b32_e64 v140, v131, v123, s[10:11]
	v_cndmask_b32_e64 v141, v130, v122, s[10:11]
	v_cndmask_b32_e64 v142, v129, v121, s[10:11]
	v_cndmask_b32_e64 v143, v128, v120, s[10:11]
	s_nop 0
	s_nop 0
	s_nop 0
	s_nop 0
	v_mov_b32_dpp v189, v139 quad_perm:[1,0,3,2] row_mask:0xf bank_mask:0xf
	v_mov_b32_dpp v193, v138 quad_perm:[1,0,3,2] row_mask:0xf bank_mask:0xf
	v_mov_b32_dpp v191, v137 quad_perm:[1,0,3,2] row_mask:0xf bank_mask:0xf
	v_mov_b32_dpp v209, v136 quad_perm:[1,0,3,2] row_mask:0xf bank_mask:0xf
	v_mov_b32_dpp v210, v143 quad_perm:[1,0,3,2] row_mask:0xf bank_mask:0xf
	v_mov_b32_dpp v212, v142 quad_perm:[1,0,3,2] row_mask:0xf bank_mask:0xf
	v_mov_b32_dpp v211, v141 quad_perm:[1,0,3,2] row_mask:0xf bank_mask:0xf
	v_mov_b32_dpp v213, v140 quad_perm:[1,0,3,2] row_mask:0xf bank_mask:0xf
	v_add_u32_e32 v192, 0x800, v164
	v_add_u32_e32 v190, 0x1000, v164
	v_add_u32_e32 v188, 0x1800, v164
	ds_read_b64 v[218:219], v201
	v_cndmask_b32_e64 v221, v193, v133, s[10:11]
	v_cndmask_b32_e64 v220, v189, v132, s[10:11]
	v_cndmask_b32_e64 v223, v209, v135, s[10:11]
	v_cndmask_b32_e64 v222, v191, v134, s[10:11]
	v_cndmask_b32_e64 v225, v212, v129, s[10:11]
	v_cndmask_b32_e64 v224, v210, v128, s[10:11]
	v_cndmask_b32_e64 v227, v213, v131, s[10:11]
	v_cndmask_b32_e64 v226, v211, v130, s[10:11]
	global_load_dwordx4 v[152:155], v164, s[20:21] offset:128
	global_load_dwordx4 v[148:151], v192, s[20:21]
	global_load_dwordx4 v[144:147], v192, s[20:21] offset:128
	global_load_dwordx4 v[140:143], v190, s[20:21]
	global_load_dwordx4 v[136:139], v190, s[20:21] offset:128
	global_load_dwordx4 v[132:135], v188, s[20:21]
	global_load_dwordx4 v[128:131], v188, s[20:21] offset:128
	s_waitcnt lgkmcnt(0)
	v_mul_f32_e32 v208, 0x3fb504f3, v219
	v_lshl_add_u64 v[186:187], v[166:167], 0, s[72:73]
	s_ashr_i32 s71, s70, 31
	v_lshl_add_u64 v[186:187], s[70:71], 3, v[186:187]
	v_lshl_add_u64 v[186:187], v[186:187], 0, s[22:23]
	v_add_u32_e32 v246, 0x4000, v164
	v_add_u32_e32 v247, 0x4800, v164
	global_load_dwordx4 v[230:233], v246, s[20:21]
	global_load_dwordx4 v[234:237], v246, s[20:21] offset:128
	global_load_dwordx4 v[238:241], v247, s[20:21]
	global_load_dwordx4 v[242:245], v247, s[20:21] offset:128
	s_waitcnt vmcnt(14)
	v_pk_mul_f32 v[182:183], v[180:181], s[58:59] op_sel_hi:[1,0]
	v_pk_mul_f32 v[184:185], v[178:179], s[58:59] op_sel_hi:[1,0]
	v_pk_mul_f32 v[178:179], v[196:197], s[58:59] op_sel_hi:[1,0]
	v_pk_mul_f32 v[180:181], v[194:195], s[58:59] op_sel_hi:[1,0]
	s_waitcnt vmcnt(13)
	v_lshlrev_b32_e32 v194, 16, v214
	v_and_b32_e32 v195, 0xffff0000, v214
	v_lshlrev_b32_e32 v196, 16, v215
	v_and_b32_e32 v197, 0xffff0000, v215
	v_lshlrev_b32_e32 v207, 16, v216
	v_and_b32_e32 v214, 0xffff0000, v216
	v_lshlrev_b32_e32 v216, 16, v217
	v_and_b32_e32 v217, 0xffff0000, v217
	v_sub_f32_e32 v195, v195, v218
	v_sub_f32_e32 v194, v194, v218
	v_sub_f32_e32 v197, v197, v218
	v_sub_f32_e32 v196, v196, v218
	v_sub_f32_e32 v215, v214, v218
	v_sub_f32_e32 v214, v207, v218
	v_sub_f32_e32 v217, v217, v218
	v_sub_f32_e32 v216, v216, v218
	v_pk_mul_f32 v[196:197], v[196:197], v[208:209] op_sel_hi:[1,0]
	v_pk_mul_f32 v[194:195], v[194:195], v[208:209] op_sel_hi:[1,0]
	v_pk_mul_f32 v[216:217], v[216:217], v[208:209] op_sel_hi:[1,0]
	v_pk_mul_f32 v[214:215], v[214:215], v[208:209] op_sel_hi:[1,0]
	s_waitcnt vmcnt(12)
	v_pk_fma_f32 v[194:195], v[76:77], v[194:195], v[184:185]
	v_pk_fma_f32 v[196:197], v[78:79], v[196:197], v[182:183]
	s_waitcnt vmcnt(11)
	v_pk_fma_f32 v[214:215], v[72:73], v[214:215], v[180:181]
	v_pk_fma_f32 v[216:217], v[74:75], v[216:217], v[178:179]
	v_pk_add_f32 v[196:197], v[222:223], v[196:197]
	v_pk_add_f32 v[194:195], v[220:221], v[194:195]
	v_pk_add_f32 v[218:219], v[226:227], v[216:217]
	v_pk_add_f32 v[216:217], v[224:225], v[214:215]
	v_cvt_pk_bf16_f32 v214, v194, v195
	v_cvt_pk_bf16_f32 v215, v196, v197
	v_and_b32_e32 v208, 64, v206
	v_cvt_pk_bf16_f32 v216, v216, v217
	v_cvt_pk_bf16_f32 v217, v218, v219
	v_lshlrev_b32_e32 v194, 16, v214
	v_and_b32_e32 v196, 0xffff0000, v214
	v_lshlrev_b32_e32 v218, 16, v215
	v_and_b32_e32 v220, 0xffff0000, v215
	v_lshlrev_b32_e32 v222, 16, v216
	v_and_b32_e32 v224, 0xffff0000, v216
	v_lshlrev_b32_e32 v226, 16, v217
	v_and_b32_e32 v228, 0xffff0000, v217
	v_mul_f32_e32 v195, v194, v194
	v_mul_f32_e32 v197, v196, v196
	v_mul_f32_e32 v219, v218, v218
	v_mul_f32_e32 v221, v220, v220
	v_mul_f32_e32 v223, v222, v222
	v_mul_f32_e32 v225, v224, v224
	v_mul_f32_e32 v227, v226, v226
	v_mul_f32_e32 v229, v228, v228
	v_pk_add_f32 v[194:195], v[194:195], v[196:197]
	v_pk_add_f32 v[196:197], v[218:219], v[220:221]
	v_pk_add_f32 v[218:219], v[226:227], v[228:229]
	v_pk_add_f32 v[194:195], v[194:195], v[196:197]
	v_pk_add_f32 v[196:197], v[222:223], v[224:225]
	v_xor_b32_e32 v207, 16, v206
	v_add_u32_e32 v208, 64, v208
	v_pk_add_f32 v[196:197], v[196:197], v[218:219]
	v_cmp_lt_i32_e32 vcc, v207, v208
	v_pk_add_f32 v[194:195], v[194:195], v[196:197]
	s_nop 0
	s_nop 0
	v_cndmask_b32_e32 v207, v206, v207, vcc
	v_mov_b32_dpp v196, v194 quad_perm:[1,0,3,2] row_mask:0xf bank_mask:0xf
	v_mov_b32_dpp v197, v195 quad_perm:[1,0,3,2] row_mask:0xf bank_mask:0xf
	v_lshlrev_b32_e32 v207, 2, v207
	v_pk_add_f32 v[194:195], v[194:195], v[196:197]
	ds_bpermute_b32 v196, v207, v194
	ds_bpermute_b32 v197, v207, v195
	v_xor_b32_e32 v218, 32, v206
	v_cmp_lt_i32_e32 vcc, v218, v208
	global_store_dwordx4 v164, v[214:217], s[20:21]
	s_waitcnt lgkmcnt(0)
	v_pk_add_f32 v[194:195], v[194:195], v[196:197]
	v_cndmask_b32_e32 v208, v206, v218, vcc
	v_lshlrev_b32_e32 v208, 2, v208
	ds_bpermute_b32 v196, v208, v194
	ds_bpermute_b32 v197, v208, v195
	s_and_saveexec_b64 s[52:53], s[16:17]
	s_waitcnt lgkmcnt(0)
	v_pk_add_f32 v[194:195], v[194:195], v[196:197]
	global_store_dwordx2 v[186:187], v[194:195], off

; __device__ __forceinline__ u32x4 pack8f(f32x4 a, f32x4 b) { u32x4 w; w.x = cvt_pk_bf16(a[0], a[1]); w.y = cvt_pk_bf16(a[2], a[3]); w.z = cvt_pk_bf16(b[0], b[1]); w.w = cvt_pk_bf16(b[2], b[3]); return w; }
;     __device__ __forceinline__ void operator()(const f32x4 (&acc)[2][2][4][2], const Unit& u, int wr, int wc, int fr, int fq, const EpiCtx& X) const {
;     ...
;             for (int m = 0; m < 4; ++m) {
;                 const int rl = ai * HALF + m * 16; const unsigned off = lo + (unsigned)(rl * 64) * 2u;
;                 const f32x4 o0a = acc[ai][0][m][0], o0b = acc[ai][0][m][1], o1a = acc[ai][1][m][0], o1b = acc[ai][1][m][1];
;                 const f32x4 ra_ = dpp_swap1(odd ? o0a : o1a), rb_ = dpp_swap1(odd ? o0b : o1b);
;                 const f32x4 pa[2] = {odd ? ra_ : o0a, odd ? o1a : ra_}, pb[2] = {odd ? rb_ : o0b, odd ? o1b : rb_};
; #pragma unroll
;                 for (int q = 0; q < 2; ++q) {
;                     const u32x4 w0 = raw[2 * m + q];
;                     const f32x4 r0 = (f32x4){bf_lo(w0.x), bf_hi(w0.x), bf_lo(w0.y), bf_hi(w0.y)}, r1 = (f32x4){bf_lo(w0.z), bf_hi(w0.z), bf_lo(w0.w), bf_hi(w0.w)};
;                     f32x4 y0, y1;
;                     if (RESN) { const f32x2 t = tbl[rl + q]; const float mu = t.x, ra = t.y * ALPHA; y0 = (r0 - mu) * ra * g0 + b0 + pa[q]; y1 = (r1 - mu) * ra * g1 + b1 + pb[q]; }
;                     else { y0 = r0 * ALPHA + pa[q]; y1 = r1 * ALPHA + pb[q]; }
;                     { const u32x4 w = pack8f(y0, y1); *(u32x4*)(xb + off + q * 128) = w;
;                         y0 = (f32x4){bf_lo(w.x), bf_hi(w.x), bf_lo(w.y), bf_hi(w.y)}; y1 = (f32x4){bf_lo(w.z), bf_hi(w.z), bf_lo(w.w), bf_hi(w.w)}; }
;                     float sa = ((y0[0] + y0[1]) + (y0[2] + y0[3])) + ((y1[0] + y1[1]) + (y1[2] + y1[3]));
;                     float sb = ((y0[0] * y0[0] + y0[1] * y0[1]) + (y0[2] * y0[2] + y0[3] * y0[3])) + ((y1[0] * y1[0] + y1[1] * y1[1]) + (y1[2] * y1[2] + y1[3] * y1[3]));
;                     sa += dpp_x1(sa);
;                     sb += dpp_x1(sb);
;                     sa += __shfl_xor(sa, 16); sa += __shfl_xor(sa, 32); sb += __shfl_xor(sb, 16); sb += __shfl_xor(sb, 32);
;                     if (fq == 0 && !odd) ps[(size_t)(rl + q) * 64] = (f32x2){sa, sb};
.LBB0_820:
	s_or_b64 exec, exec, s[52:53]
	s_waitcnt lgkmcnt(1)
	v_cndmask_b32_e64 v122, v116, v108, s[10:11]
	s_nop 0
	v_cndmask_b32_e64 v121, v117, v109, s[10:11]
	s_waitcnt lgkmcnt(0)
	v_cndmask_b32_e64 v123, v118, v110, s[10:11]
	v_mov_b32_dpp v120, v122 quad_perm:[1,0,3,2] row_mask:0xf bank_mask:0xf
	s_nop 0
	v_cndmask_b32_e64 v124, v119, v111, s[10:11]
	v_cndmask_b32_e64 v126, v112, v104, s[10:11]
	v_mov_b32_dpp v122, v121 quad_perm:[1,0,3,2] row_mask:0xf bank_mask:0xf
	s_nop 0
	v_cndmask_b32_e64 v125, v113, v105, s[10:11]
	v_cndmask_b32_e64 v127, v114, v106, s[10:11]
	v_mov_b32_dpp v121, v123 quad_perm:[1,0,3,2] row_mask:0xf bank_mask:0xf
	s_nop 0
	v_cndmask_b32_e64 v152, v115, v107, s[10:11]
	s_waitcnt vmcnt(13)
	v_and_b32_e32 v153, 0xffff0000, v148
	v_mov_b32_dpp v123, v124 quad_perm:[1,0,3,2] row_mask:0xf bank_mask:0xf
	s_nop 0
	v_lshlrev_b32_e32 v154, 16, v149
	v_and_b32_e32 v155, 0xffff0000, v149
	v_mov_b32_dpp v124, v126 quad_perm:[1,0,3,2] row_mask:0xf bank_mask:0xf
	s_nop 0
	v_lshlrev_b32_e32 v189, 16, v150
	v_and_b32_e32 v191, 0xffff0000, v150
	v_mov_b32_dpp v126, v125 quad_perm:[1,0,3,2] row_mask:0xf bank_mask:0xf
	s_nop 0
	v_lshlrev_b32_e32 v193, 16, v151
	v_and_b32_e32 v151, 0xffff0000, v151
	v_mov_b32_dpp v125, v127 quad_perm:[1,0,3,2] row_mask:0xf bank_mask:0xf
	s_nop 0
	v_cndmask_b32_e64 v117, v122, v117, s[10:11]
	v_cndmask_b32_e64 v116, v120, v116, s[10:11]
	v_mov_b32_dpp v127, v152 quad_perm:[1,0,3,2] row_mask:0xf bank_mask:0xf
	v_lshlrev_b32_e32 v152, 16, v148
	ds_read_b64 v[148:149], v201 offset:128
	v_cndmask_b32_e64 v119, v123, v119, s[10:11]
	v_cndmask_b32_e64 v118, v121, v118, s[10:11]
	v_cndmask_b32_e64 v113, v126, v113, s[10:11]
	v_cndmask_b32_e64 v112, v124, v112, s[10:11]
	s_waitcnt lgkmcnt(0)
	v_mul_f32_e32 v150, 0x3fb504f3, v149
	v_sub_f32_e32 v153, v153, v148
	v_sub_f32_e32 v152, v152, v148
	v_pk_mul_f32 v[152:153], v[152:153], v[150:151] op_sel_hi:[1,0]
	v_sub_f32_e32 v155, v155, v148
	v_pk_fma_f32 v[152:153], v[76:77], v[152:153], v[184:185]
	v_sub_f32_e32 v154, v154, v148
	v_pk_add_f32 v[116:117], v[116:117], v[152:153]
	v_sub_f32_e32 v153, v191, v148
	v_sub_f32_e32 v152, v189, v148
	v_sub_f32_e32 v149, v151, v148
	v_sub_f32_e32 v148, v193, v148
	v_pk_mul_f32 v[154:155], v[154:155], v[150:151] op_sel_hi:[1,0]
	v_pk_mul_f32 v[148:149], v[148:149], v[150:151] op_sel_hi:[1,0]
	v_pk_mul_f32 v[150:151], v[152:153], v[150:151] op_sel_hi:[1,0]
	v_cndmask_b32_e64 v115, v127, v115, s[10:11]
	v_cndmask_b32_e64 v114, v125, v114, s[10:11]
	v_pk_fma_f32 v[154:155], v[78:79], v[154:155], v[182:183]
	v_pk_fma_f32 v[150:151], v[72:73], v[150:151], v[180:181]
	v_pk_fma_f32 v[148:149], v[74:75], v[148:149], v[178:179]
	v_pk_add_f32 v[118:119], v[118:119], v[154:155]
	v_pk_add_f32 v[114:115], v[114:115], v[148:149]
	v_pk_add_f32 v[112:113], v[112:113], v[150:151]
	v_cvt_pk_bf16_f32 v148, v116, v117
	v_cvt_pk_bf16_f32 v149, v118, v119
	v_mov_b32_e32 v193, v165
	v_cvt_pk_bf16_f32 v150, v112, v113
	v_cvt_pk_bf16_f32 v151, v114, v115
	v_lshlrev_b32_e32 v112, 16, v148
	v_and_b32_e32 v114, 0xffff0000, v148
	v_lshlrev_b32_e32 v116, 16, v149
	v_and_b32_e32 v118, 0xffff0000, v149
	v_lshlrev_b32_e32 v152, 16, v150
	v_and_b32_e32 v154, 0xffff0000, v150
	v_lshlrev_b32_e32 v194, 16, v151
	v_and_b32_e32 v196, 0xffff0000, v151
	v_mul_f32_e32 v113, v112, v112
	v_mul_f32_e32 v115, v114, v114
	v_mul_f32_e32 v117, v116, v116
	v_mul_f32_e32 v119, v118, v118
	v_mul_f32_e32 v153, v152, v152
	v_mul_f32_e32 v155, v154, v154
	v_mul_f32_e32 v195, v194, v194
	v_mul_f32_e32 v197, v196, v196
	v_pk_add_f32 v[112:113], v[112:113], v[114:115]
	v_pk_add_f32 v[114:115], v[116:117], v[118:119]
	v_pk_add_f32 v[116:117], v[194:195], v[196:197]
	v_pk_add_f32 v[112:113], v[112:113], v[114:115]
	v_pk_add_f32 v[114:115], v[152:153], v[154:155]
	s_nop 0
	v_pk_add_f32 v[114:115], v[114:115], v[116:117]
	s_nop 0
	v_pk_add_f32 v[112:113], v[112:113], v[114:115]
	v_mov_b32_e32 v114, v165
	v_mov_b32_e32 v115, v165
	s_nop 0
	v_mov_b32_dpp v114, v112 quad_perm:[1,0,3,2] row_mask:0xf bank_mask:0xf
	v_mov_b32_dpp v115, v113 quad_perm:[1,0,3,2] row_mask:0xf bank_mask:0xf
	v_pk_add_f32 v[112:113], v[112:113], v[114:115]
	ds_bpermute_b32 v114, v207, v112
	ds_bpermute_b32 v115, v207, v113
	s_waitcnt lgkmcnt(0)
	v_pk_add_f32 v[114:115], v[112:113], v[114:115]
	ds_bpermute_b32 v116, v208, v114
	ds_bpermute_b32 v117, v208, v115
	v_lshl_add_u64 v[112:113], s[20:21], 0, v[192:193]
	global_store_dwordx4 v[112:113], v[148:151], off
	s_and_saveexec_b64 s[68:69], s[16:17]
	s_waitcnt lgkmcnt(0)
	v_pk_add_f32 v[114:115], v[114:115], v[116:117]
	v_add_co_u32_e32 v116, vcc, 0x2000, v186
	s_nop 1
	v_addc_co_u32_e32 v117, vcc, 0, v187, vcc
	global_store_dwordx2 v[116:117], v[114:115], off

; __device__ __forceinline__ float dpp_x1(float x) { return __builtin_bit_cast(float, __builtin_amdgcn_update_dpp(0, __builtin_bit_cast(int, x), 0xB1, 0xF, 0xF, false)); }
; __device__ __forceinline__ f32x4 dpp_swap1(f32x4 v) { f32x4 r; r[0] = dpp_x1(v[0]); r[1] = dpp_x1(v[1]); r[2] = dpp_x1(v[2]); r[3] = dpp_x1(v[3]); return r; }
;     __device__ __forceinline__ void operator()(const f32x4 (&acc)[2][2][4][2], const Unit& u, int wr, int wc, int fr, int fq, const EpiCtx& X) const {
;     ...
;             for (int m = 0; m < 4; ++m) {
;                 const int rl = ai * HALF + m * 16; const unsigned off = lo + (unsigned)(rl * 64) * 2u;
;                 const f32x4 o0a = acc[ai][0][m][0], o0b = acc[ai][0][m][1], o1a = acc[ai][1][m][0], o1b = acc[ai][1][m][1];
;                 const f32x4 ra_ = dpp_swap1(odd ? o0a : o1a), rb_ = dpp_swap1(odd ? o0b : o1b);
;                 const f32x4 pa[2] = {odd ? ra_ : o0a, odd ? o1a : ra_}, pb[2] = {odd ? rb_ : o0b, odd ? o1b : rb_};
; #pragma unroll
;                 for (int q = 0; q < 2; ++q) {
;                     const u32x4 w0 = raw[2 * m + q];
;                     const f32x4 r0 = (f32x4){bf_lo(w0.x), bf_hi(w0.x), bf_lo(w0.y), bf_hi(w0.y)}, r1 = (f32x4){bf_lo(w0.z), bf_hi(w0.z), bf_lo(w0.w), bf_hi(w0.w)};
;                     f32x4 y0, y1;
;                     if (RESN) { const f32x2 t = tbl[rl + q]; const float mu = t.x, ra = t.y * ALPHA; y0 = (r0 - mu) * ra * g0 + b0 + pa[q]; y1 = (r1 - mu) * ra * g1 + b1 + pb[q]; }
;                     else { y0 = r0 * ALPHA + pa[q]; y1 = r1 * ALPHA + pb[q]; }
;                     { const u32x4 w = pack8f(y0, y1); *(u32x4*)(xb + off + q * 128) = w;
;                         y0 = (f32x4){bf_lo(w.x), bf_hi(w.x), bf_lo(w.y), bf_hi(w.y)}; y1 = (f32x4){bf_lo(w.z), bf_hi(w.z), bf_lo(w.w), bf_hi(w.w)}; }
;                     float sa = ((y0[0] + y0[1]) + (y0[2] + y0[3])) + ((y1[0] + y1[1]) + (y1[2] + y1[3]));
;                     float sb = ((y0[0] * y0[0] + y0[1] * y0[1]) + (y0[2] * y0[2] + y0[3] * y0[3])) + ((y1[0] * y1[0] + y1[1] * y1[1]) + (y1[2] * y1[2] + y1[3] * y1[3]));
;                     sa += dpp_x1(sa);
;                     sb += dpp_x1(sb);
;                     sa += __shfl_xor(sa, 16); sa += __shfl_xor(sa, 32); sb += __shfl_xor(sb, 16); sb += __shfl_xor(sb, 32);
;                     if (fq == 0 && !odd) ps[(size_t)(rl + q) * 64] = (f32x2){sa, sb};
.LBB0_824:
	s_or_b64 exec, exec, s[68:69]
	s_waitcnt lgkmcnt(1)
	v_cndmask_b32_e64 v106, v100, v92, s[10:11]
	s_nop 0
	v_cndmask_b32_e64 v105, v101, v93, s[10:11]
	s_waitcnt lgkmcnt(0)
	v_cndmask_b32_e64 v107, v102, v94, s[10:11]
	v_mov_b32_dpp v104, v106 quad_perm:[1,0,3,2] row_mask:0xf bank_mask:0xf
	s_nop 0
	v_cndmask_b32_e64 v108, v103, v95, s[10:11]
	v_cndmask_b32_e64 v110, v96, v88, s[10:11]
	v_mov_b32_dpp v106, v105 quad_perm:[1,0,3,2] row_mask:0xf bank_mask:0xf
	s_nop 0
	v_cndmask_b32_e64 v109, v97, v89, s[10:11]
	v_cndmask_b32_e64 v111, v98, v90, s[10:11]
	v_mov_b32_dpp v105, v107 quad_perm:[1,0,3,2] row_mask:0xf bank_mask:0xf
	s_nop 0
	v_cndmask_b32_e64 v112, v99, v91, s[10:11]
	s_waitcnt vmcnt(15)
	v_lshlrev_b32_e32 v115, 16, v140
	v_mov_b32_dpp v107, v108 quad_perm:[1,0,3,2] row_mask:0xf bank_mask:0xf
	s_nop 0
	v_and_b32_e32 v116, 0xffff0000, v140
	v_cndmask_b32_e64 v101, v106, v101, s[10:11]
	v_mov_b32_dpp v108, v110 quad_perm:[1,0,3,2] row_mask:0xf bank_mask:0xf
	s_nop 0
	v_cndmask_b32_e64 v100, v104, v100, s[10:11]
	v_lshlrev_b32_e32 v118, 16, v141
	v_mov_b32_dpp v110, v109 quad_perm:[1,0,3,2] row_mask:0xf bank_mask:0xf
	s_nop 0
	v_and_b32_e32 v119, 0xffff0000, v141
	v_lshlrev_b32_e32 v120, 16, v142
	v_mov_b32_dpp v109, v111 quad_perm:[1,0,3,2] row_mask:0xf bank_mask:0xf
	s_nop 0
	v_and_b32_e32 v121, 0xffff0000, v142
	v_lshlrev_b32_e32 v122, 16, v143
	v_mov_b32_dpp v111, v112 quad_perm:[1,0,3,2] row_mask:0xf bank_mask:0xf
	ds_read_b64 v[112:113], v201 offset:256
	v_and_b32_e32 v123, 0xffff0000, v143
	v_cndmask_b32_e64 v103, v107, v103, s[10:11]
	v_cndmask_b32_e64 v102, v105, v102, s[10:11]
	v_cndmask_b32_e64 v97, v110, v97, s[10:11]
	s_waitcnt lgkmcnt(0)
	v_mul_f32_e32 v114, 0x3fb504f3, v113
	v_sub_f32_e32 v117, v116, v112
	v_sub_f32_e32 v116, v115, v112
	v_pk_mul_f32 v[116:117], v[116:117], v[114:115] op_sel_hi:[1,0]
	v_sub_f32_e32 v119, v119, v112
	v_pk_fma_f32 v[116:117], v[76:77], v[116:117], v[184:185]
	v_sub_f32_e32 v118, v118, v112
	v_pk_add_f32 v[100:101], v[100:101], v[116:117]
	v_sub_f32_e32 v117, v121, v112
	v_sub_f32_e32 v116, v120, v112
	v_sub_f32_e32 v113, v123, v112
	v_sub_f32_e32 v112, v122, v112
	v_pk_mul_f32 v[118:119], v[118:119], v[114:115] op_sel_hi:[1,0]
	v_pk_mul_f32 v[112:113], v[112:113], v[114:115] op_sel_hi:[1,0]
	v_pk_mul_f32 v[114:115], v[116:117], v[114:115] op_sel_hi:[1,0]
	v_cndmask_b32_e64 v96, v108, v96, s[10:11]
	v_cndmask_b32_e64 v99, v111, v99, s[10:11]
	v_cndmask_b32_e64 v98, v109, v98, s[10:11]
	v_pk_fma_f32 v[118:119], v[78:79], v[118:119], v[182:183]
	v_pk_fma_f32 v[114:115], v[72:73], v[114:115], v[180:181]
	v_pk_fma_f32 v[112:113], v[74:75], v[112:113], v[178:179]
	v_pk_add_f32 v[102:103], v[102:103], v[118:119]
	v_pk_add_f32 v[98:99], v[98:99], v[112:113]
	v_pk_add_f32 v[96:97], v[96:97], v[114:115]
	v_cvt_pk_bf16_f32 v112, v100, v101
	v_cvt_pk_bf16_f32 v113, v102, v103
	v_mov_b32_e32 v191, v165
	v_cvt_pk_bf16_f32 v114, v96, v97
	v_cvt_pk_bf16_f32 v115, v98, v99
	v_lshlrev_b32_e32 v96, 16, v112
	v_and_b32_e32 v98, 0xffff0000, v112
	v_lshlrev_b32_e32 v100, 16, v113
	v_and_b32_e32 v102, 0xffff0000, v113
	v_lshlrev_b32_e32 v116, 16, v114
	v_and_b32_e32 v118, 0xffff0000, v114
	v_lshlrev_b32_e32 v120, 16, v115
	v_and_b32_e32 v122, 0xffff0000, v115
	v_mul_f32_e32 v97, v96, v96
	v_mul_f32_e32 v99, v98, v98
	v_mul_f32_e32 v101, v100, v100
	v_mul_f32_e32 v103, v102, v102
	v_mul_f32_e32 v117, v116, v116
	v_mul_f32_e32 v119, v118, v118
	v_mul_f32_e32 v121, v120, v120
	v_mul_f32_e32 v123, v122, v122
	v_pk_add_f32 v[96:97], v[96:97], v[98:99]
	v_pk_add_f32 v[98:99], v[100:101], v[102:103]
	v_pk_add_f32 v[100:101], v[120:121], v[122:123]
	v_pk_add_f32 v[96:97], v[96:97], v[98:99]
	v_pk_add_f32 v[98:99], v[116:117], v[118:119]
	s_nop 0
	v_pk_add_f32 v[98:99], v[98:99], v[100:101]
	s_nop 0
	v_pk_add_f32 v[96:97], v[96:97], v[98:99]
	v_mov_b32_e32 v98, v165
	v_mov_b32_e32 v99, v165
	s_nop 0
	v_mov_b32_dpp v98, v96 quad_perm:[1,0,3,2] row_mask:0xf bank_mask:0xf
	v_mov_b32_dpp v99, v97 quad_perm:[1,0,3,2] row_mask:0xf bank_mask:0xf
	v_pk_add_f32 v[96:97], v[96:97], v[98:99]
	ds_bpermute_b32 v98, v207, v96
	ds_bpermute_b32 v99, v207, v97
	s_waitcnt lgkmcnt(0)
	v_pk_add_f32 v[98:99], v[96:97], v[98:99]
	ds_bpermute_b32 v100, v208, v98
	ds_bpermute_b32 v101, v208, v99
	v_lshl_add_u64 v[96:97], s[20:21], 0, v[190:191]
	global_store_dwordx4 v[96:97], v[112:115], off
	s_and_saveexec_b64 s[68:69], s[16:17]
	s_waitcnt lgkmcnt(0)
	v_pk_add_f32 v[98:99], v[98:99], v[100:101]
	v_add_co_u32_e32 v100, vcc, 0x4000, v186
	s_nop 1
	v_addc_co_u32_e32 v101, vcc, 0, v187, vcc
	global_store_dwordx2 v[100:101], v[98:99], off

; __device__ __forceinline__ float dpp_x1(float x) { return __builtin_bit_cast(float, __builtin_amdgcn_update_dpp(0, __builtin_bit_cast(int, x), 0xB1, 0xF, 0xF, false)); }
; __device__ __forceinline__ f32x4 dpp_swap1(f32x4 v) { f32x4 r; r[0] = dpp_x1(v[0]); r[1] = dpp_x1(v[1]); r[2] = dpp_x1(v[2]); r[3] = dpp_x1(v[3]); return r; }
;     __device__ __forceinline__ void operator()(const f32x4 (&acc)[2][2][4][2], const Unit& u, int wr, int wc, int fr, int fq, const EpiCtx& X) const {
;     ...
;             for (int m = 0; m < 4; ++m) {
;                 const int rl = ai * HALF + m * 16; const unsigned off = lo + (unsigned)(rl * 64) * 2u;
;                 const f32x4 o0a = acc[ai][0][m][0], o0b = acc[ai][0][m][1], o1a = acc[ai][1][m][0], o1b = acc[ai][1][m][1];
;                 const f32x4 ra_ = dpp_swap1(odd ? o0a : o1a), rb_ = dpp_swap1(odd ? o0b : o1b);
;                 const f32x4 pa[2] = {odd ? ra_ : o0a, odd ? o1a : ra_}, pb[2] = {odd ? rb_ : o0b, odd ? o1b : rb_};
; #pragma unroll
;                 for (int q = 0; q < 2; ++q) {
;                     const u32x4 w0 = raw[2 * m + q];
;                     const f32x4 r0 = (f32x4){bf_lo(w0.x), bf_hi(w0.x), bf_lo(w0.y), bf_hi(w0.y)}, r1 = (f32x4){bf_lo(w0.z), bf_hi(w0.z), bf_lo(w0.w), bf_hi(w0.w)};
;                     f32x4 y0, y1;
;                     if (RESN) { const f32x2 t = tbl[rl + q]; const float mu = t.x, ra = t.y * ALPHA; y0 = (r0 - mu) * ra * g0 + b0 + pa[q]; y1 = (r1 - mu) * ra * g1 + b1 + pb[q]; }
;                     else { y0 = r0 * ALPHA + pa[q]; y1 = r1 * ALPHA + pb[q]; }
;                     { const u32x4 w = pack8f(y0, y1); *(u32x4*)(xb + off + q * 128) = w;
;                         y0 = (f32x4){bf_lo(w.x), bf_hi(w.x), bf_lo(w.y), bf_hi(w.y)}; y1 = (f32x4){bf_lo(w.z), bf_hi(w.z), bf_lo(w.w), bf_hi(w.w)}; }
;                     float sa = ((y0[0] + y0[1]) + (y0[2] + y0[3])) + ((y1[0] + y1[1]) + (y1[2] + y1[3]));
;                     float sb = ((y0[0] * y0[0] + y0[1] * y0[1]) + (y0[2] * y0[2] + y0[3] * y0[3])) + ((y1[0] * y1[0] + y1[1] * y1[1]) + (y1[2] * y1[2] + y1[3] * y1[3]));
;                     sa += dpp_x1(sa);
;                     sb += dpp_x1(sb);
;                     sa += __shfl_xor(sa, 16); sa += __shfl_xor(sa, 32); sb += __shfl_xor(sb, 16); sb += __shfl_xor(sb, 32);
;                     if (fq == 0 && !odd) ps[(size_t)(rl + q) * 64] = (f32x2){sa, sb};
.LBB0_828:
	s_or_b64 exec, exec, s[68:69]
	s_waitcnt lgkmcnt(1)
	v_cndmask_b32_e64 v90, v84, v68, s[10:11]
	s_nop 0
	v_cndmask_b32_e64 v89, v85, v69, s[10:11]
	s_waitcnt lgkmcnt(0)
	v_cndmask_b32_e64 v91, v86, v70, s[10:11]
	v_mov_b32_dpp v88, v90 quad_perm:[1,0,3,2] row_mask:0xf bank_mask:0xf
	s_nop 0
	v_cndmask_b32_e64 v92, v87, v71, s[10:11]
	v_cndmask_b32_e64 v94, v80, v64, s[10:11]
	v_mov_b32_dpp v90, v89 quad_perm:[1,0,3,2] row_mask:0xf bank_mask:0xf
	s_nop 0
	v_cndmask_b32_e64 v93, v81, v65, s[10:11]
	v_cndmask_b32_e64 v95, v82, v66, s[10:11]
	v_mov_b32_dpp v89, v91 quad_perm:[1,0,3,2] row_mask:0xf bank_mask:0xf
	s_nop 0
	v_cndmask_b32_e64 v96, v83, v67, s[10:11]
	s_waitcnt vmcnt(17)
	v_lshlrev_b32_e32 v99, 16, v132
	v_mov_b32_dpp v91, v92 quad_perm:[1,0,3,2] row_mask:0xf bank_mask:0xf
	s_nop 0
	v_and_b32_e32 v100, 0xffff0000, v132
	v_cndmask_b32_e64 v85, v90, v85, s[10:11]
	v_mov_b32_dpp v92, v94 quad_perm:[1,0,3,2] row_mask:0xf bank_mask:0xf
	s_nop 0
	v_cndmask_b32_e64 v84, v88, v84, s[10:11]
	v_lshlrev_b32_e32 v102, 16, v133
	v_mov_b32_dpp v94, v93 quad_perm:[1,0,3,2] row_mask:0xf bank_mask:0xf
	s_nop 0
	v_and_b32_e32 v103, 0xffff0000, v133
	v_lshlrev_b32_e32 v104, 16, v134
	v_mov_b32_dpp v93, v95 quad_perm:[1,0,3,2] row_mask:0xf bank_mask:0xf
	s_nop 0
	v_and_b32_e32 v105, 0xffff0000, v134
	v_lshlrev_b32_e32 v106, 16, v135
	v_mov_b32_dpp v95, v96 quad_perm:[1,0,3,2] row_mask:0xf bank_mask:0xf
	ds_read_b64 v[96:97], v201 offset:384
	v_and_b32_e32 v107, 0xffff0000, v135
	v_cndmask_b32_e64 v87, v91, v87, s[10:11]
	v_cndmask_b32_e64 v86, v89, v86, s[10:11]
	v_cndmask_b32_e64 v81, v94, v81, s[10:11]
	s_waitcnt lgkmcnt(0)
	v_mul_f32_e32 v98, 0x3fb504f3, v97
	v_sub_f32_e32 v101, v100, v96
	v_sub_f32_e32 v100, v99, v96
	v_pk_mul_f32 v[100:101], v[100:101], v[98:99] op_sel_hi:[1,0]
	v_sub_f32_e32 v103, v103, v96
	v_pk_fma_f32 v[100:101], v[76:77], v[100:101], v[184:185]
	v_sub_f32_e32 v102, v102, v96
	v_pk_add_f32 v[84:85], v[84:85], v[100:101]
	v_sub_f32_e32 v101, v105, v96
	v_sub_f32_e32 v100, v104, v96
	v_sub_f32_e32 v97, v107, v96
	v_sub_f32_e32 v96, v106, v96
	v_pk_mul_f32 v[102:103], v[102:103], v[98:99] op_sel_hi:[1,0]
	v_pk_mul_f32 v[96:97], v[96:97], v[98:99] op_sel_hi:[1,0]
	v_pk_mul_f32 v[98:99], v[100:101], v[98:99] op_sel_hi:[1,0]
	v_cndmask_b32_e64 v80, v92, v80, s[10:11]
	v_cndmask_b32_e64 v83, v95, v83, s[10:11]
	v_cndmask_b32_e64 v82, v93, v82, s[10:11]
	v_pk_fma_f32 v[102:103], v[78:79], v[102:103], v[182:183]
	v_pk_fma_f32 v[98:99], v[72:73], v[98:99], v[180:181]
	v_pk_fma_f32 v[96:97], v[74:75], v[96:97], v[178:179]
	v_pk_add_f32 v[86:87], v[86:87], v[102:103]
	v_pk_add_f32 v[82:83], v[82:83], v[96:97]
	v_pk_add_f32 v[80:81], v[80:81], v[98:99]
	v_cvt_pk_bf16_f32 v96, v84, v85
	v_cvt_pk_bf16_f32 v97, v86, v87
	v_mov_b32_e32 v189, v165
	v_cvt_pk_bf16_f32 v98, v80, v81
	v_cvt_pk_bf16_f32 v99, v82, v83
	v_lshlrev_b32_e32 v80, 16, v96
	v_and_b32_e32 v82, 0xffff0000, v96
	v_lshlrev_b32_e32 v84, 16, v97
	v_and_b32_e32 v86, 0xffff0000, v97
	v_lshlrev_b32_e32 v100, 16, v98
	v_and_b32_e32 v102, 0xffff0000, v98
	v_lshlrev_b32_e32 v104, 16, v99
	v_and_b32_e32 v106, 0xffff0000, v99
	v_mul_f32_e32 v81, v80, v80
	v_mul_f32_e32 v83, v82, v82
	v_mul_f32_e32 v85, v84, v84
	v_mul_f32_e32 v87, v86, v86
	v_mul_f32_e32 v101, v100, v100
	v_mul_f32_e32 v103, v102, v102
	v_mul_f32_e32 v105, v104, v104
	v_mul_f32_e32 v107, v106, v106
	v_pk_add_f32 v[80:81], v[80:81], v[82:83]
	v_pk_add_f32 v[82:83], v[84:85], v[86:87]
	v_pk_add_f32 v[84:85], v[104:105], v[106:107]
	v_pk_add_f32 v[80:81], v[80:81], v[82:83]
	v_pk_add_f32 v[82:83], v[100:101], v[102:103]
	s_nop 0
	v_pk_add_f32 v[82:83], v[82:83], v[84:85]
	s_nop 0
	v_pk_add_f32 v[80:81], v[80:81], v[82:83]
	v_mov_b32_e32 v82, v165
	v_mov_b32_e32 v83, v165
	s_nop 0
	v_mov_b32_dpp v82, v80 quad_perm:[1,0,3,2] row_mask:0xf bank_mask:0xf
	v_mov_b32_dpp v83, v81 quad_perm:[1,0,3,2] row_mask:0xf bank_mask:0xf
	v_pk_add_f32 v[80:81], v[80:81], v[82:83]
	ds_bpermute_b32 v82, v207, v80
	ds_bpermute_b32 v83, v207, v81
	s_waitcnt lgkmcnt(0)
	v_pk_add_f32 v[82:83], v[80:81], v[82:83]
	ds_bpermute_b32 v84, v208, v82
	ds_bpermute_b32 v85, v208, v83
	v_lshl_add_u64 v[80:81], s[20:21], 0, v[188:189]
	global_store_dwordx4 v[80:81], v[96:99], off
	s_and_saveexec_b64 s[68:69], s[16:17]
	s_waitcnt lgkmcnt(0)
	v_pk_add_f32 v[82:83], v[82:83], v[84:85]
	v_add_co_u32_e32 v84, vcc, 0x6000, v186
	s_nop 1
	v_addc_co_u32_e32 v85, vcc, 0, v187, vcc
	global_store_dwordx2 v[84:85], v[82:83], off

;     __device__ __forceinline__ void operator()(const f32x4 (&acc)[2][2][4][2], const Unit& u, int wr, int wc, int fr, int fq, const EpiCtx& X) const {
;     ...
;             for (int m = 0; m < 4; ++m) { const unsigned off = lo + (unsigned)((ai * HALF + m * 16) * 64) * 2u; raw[2 * m] = *(const u32x4*)(xb + off); raw[2 * m + 1] = *(const u32x4*)(xb + off + 128); }
; #pragma unroll
;             for (int m = 0; m < 4; ++m) {
;                 const int rl = ai * HALF + m * 16; const unsigned off = lo + (unsigned)(rl * 64) * 2u;
;                 const f32x4 o0a = acc[ai][0][m][0], o0b = acc[ai][0][m][1], o1a = acc[ai][1][m][0], o1b = acc[ai][1][m][1];
;                 const f32x4 ra_ = dpp_swap1(odd ? o0a : o1a), rb_ = dpp_swap1(odd ? o0b : o1b);
;                 const f32x4 pa[2] = {odd ? ra_ : o0a, odd ? o1a : ra_}, pb[2] = {odd ? rb_ : o0b, odd ? o1b : rb_};
; #pragma unroll
;                 for (int q = 0; q < 2; ++q) {
;                     const u32x4 w0 = raw[2 * m + q];
;                     const f32x4 r0 = (f32x4){bf_lo(w0.x), bf_hi(w0.x), bf_lo(w0.y), bf_hi(w0.y)}, r1 = (f32x4){bf_lo(w0.z), bf_hi(w0.z), bf_lo(w0.w), bf_hi(w0.w)};
;                     f32x4 y0, y1;
;                     if (RESN) { const f32x2 t = tbl[rl + q]; const float mu = t.x, ra = t.y * ALPHA; y0 = (r0 - mu) * ra * g0 + b0 + pa[q]; y1 = (r1 - mu) * ra * g1 + b1 + pb[q]; }
;                     else { y0 = r0 * ALPHA + pa[q]; y1 = r1 * ALPHA + pb[q]; }
;                     { const u32x4 w = pack8f(y0, y1); *(u32x4*)(xb + off + q * 128) = w;
;                         y0 = (f32x4){bf_lo(w.x), bf_hi(w.x), bf_lo(w.y), bf_hi(w.y)}; y1 = (f32x4){bf_lo(w.z), bf_hi(w.z), bf_lo(w.w), bf_hi(w.w)}; }
;                     float sa = ((y0[0] + y0[1]) + (y0[2] + y0[3])) + ((y1[0] + y1[1]) + (y1[2] + y1[3]));
;                     float sb = ((y0[0] * y0[0] + y0[1] * y0[1]) + (y0[2] * y0[2] + y0[3] * y0[3])) + ((y1[0] * y1[0] + y1[1] * y1[1]) + (y1[2] * y1[2] + y1[3] * y1[3]));
;                     sa += dpp_x1(sa);
;                     sb += dpp_x1(sb);
;                     sa += __shfl_xor(sa, 16); sa += __shfl_xor(sa, 32); sb += __shfl_xor(sb, 16); sb += __shfl_xor(sb, 32);
;                     if (fq == 0 && !odd) ps[(size_t)(rl + q) * 64] = (f32x2){sa, sb};
.LBB0_832:
	s_or_b64 exec, exec, s[68:69]
	v_add_u32_e32 v104, 0x4000, v164
	s_waitcnt vmcnt(16)
	v_mov_b32_e32 v112, v230
	v_mov_b32_e32 v113, v231
	v_mov_b32_e32 v114, v232
	v_mov_b32_e32 v115, v233
	v_add_u32_e32 v102, 0x4800, v164
	v_add_u32_e32 v100, 0x5000, v164
	v_add_u32_e32 v164, 0x5800, v164
	v_mov_b32_e32 v96, v234
	v_mov_b32_e32 v97, v235
	v_mov_b32_e32 v98, v236
	v_mov_b32_e32 v99, v237
	v_mov_b32_e32 v92, v238
	v_mov_b32_e32 v93, v239
	v_mov_b32_e32 v94, v240
	v_mov_b32_e32 v95, v241
	v_mov_b32_e32 v88, v242
	v_mov_b32_e32 v89, v243
	v_mov_b32_e32 v90, v244
	v_mov_b32_e32 v91, v245
	global_load_dwordx4 v[84:87], v100, s[20:21]
	global_load_dwordx4 v[80:83], v100, s[20:21] offset:128
	global_load_dwordx4 v[68:71], v164, s[20:21]
	s_waitcnt lgkmcnt(0)
	global_load_dwordx4 v[64:67], v164, s[20:21] offset:128
	v_cndmask_b32_e64 v116, v62, v54, s[10:11]
	v_cndmask_b32_e64 v117, v61, v53, s[10:11]
	s_nop 0
	s_nop 0
	v_cndmask_b32_e64 v111, v63, v55, s[10:11]
	v_mov_b32_dpp v105, v117 quad_perm:[1,0,3,2] row_mask:0xf bank_mask:0xf
	v_mov_b32_dpp v103, v116 quad_perm:[1,0,3,2] row_mask:0xf bank_mask:0xf
	ds_read_b64 v[116:117], v201 offset:1024
	v_cndmask_b32_e64 v118, v60, v52, s[10:11]
	s_nop 0
	s_nop 0
	v_cndmask_b32_e64 v119, v59, v51, s[10:11]
	v_cndmask_b32_e64 v120, v58, v50, s[10:11]
	v_cndmask_b32_e64 v121, v57, v49, s[10:11]
	v_cndmask_b32_e64 v122, v56, v48, s[10:11]
	s_nop 0
	s_nop 0
	s_nop 0
	s_nop 0
	v_mov_b32_dpp v101, v118 quad_perm:[1,0,3,2] row_mask:0xf bank_mask:0xf
	v_mov_b32_dpp v106, v111 quad_perm:[1,0,3,2] row_mask:0xf bank_mask:0xf
	v_mov_b32_dpp v107, v122 quad_perm:[1,0,3,2] row_mask:0xf bank_mask:0xf
	v_mov_b32_dpp v109, v121 quad_perm:[1,0,3,2] row_mask:0xf bank_mask:0xf
	v_mov_b32_dpp v108, v120 quad_perm:[1,0,3,2] row_mask:0xf bank_mask:0xf
	v_mov_b32_dpp v110, v119 quad_perm:[1,0,3,2] row_mask:0xf bank_mask:0xf
	s_waitcnt lgkmcnt(0)
	v_mul_f32_e32 v118, 0x3fb504f3, v117
	v_cndmask_b32_e64 v61, v105, v61, s[10:11]
	v_cndmask_b32_e64 v60, v101, v60, s[10:11]
	v_cndmask_b32_e64 v63, v106, v63, s[10:11]
	v_cndmask_b32_e64 v62, v103, v62, s[10:11]
	v_cndmask_b32_e64 v57, v109, v57, s[10:11]
	v_cndmask_b32_e64 v56, v107, v56, s[10:11]
	v_cndmask_b32_e64 v59, v110, v59, s[10:11]
	v_cndmask_b32_e64 v58, v108, v58, s[10:11]
	v_lshlrev_b32_e32 v111, 16, v112
	v_and_b32_e32 v112, 0xffff0000, v112
	v_lshlrev_b32_e32 v117, 16, v113
	v_and_b32_e32 v119, 0xffff0000, v113
	v_lshlrev_b32_e32 v120, 16, v114
	v_and_b32_e32 v121, 0xffff0000, v114
	v_lshlrev_b32_e32 v122, 16, v115
	v_and_b32_e32 v123, 0xffff0000, v115
	v_sub_f32_e32 v113, v112, v116
	v_sub_f32_e32 v112, v111, v116
	v_sub_f32_e32 v115, v119, v116
	v_sub_f32_e32 v114, v117, v116
	v_sub_f32_e32 v121, v121, v116
	v_sub_f32_e32 v120, v120, v116
	v_sub_f32_e32 v117, v123, v116
	v_sub_f32_e32 v116, v122, v116
	v_pk_mul_f32 v[114:115], v[114:115], v[118:119] op_sel_hi:[1,0]
	v_pk_mul_f32 v[112:113], v[112:113], v[118:119] op_sel_hi:[1,0]
	v_pk_mul_f32 v[116:117], v[116:117], v[118:119] op_sel_hi:[1,0]
	v_pk_mul_f32 v[118:119], v[120:121], v[118:119] op_sel_hi:[1,0]
	v_pk_fma_f32 v[112:113], v[76:77], v[112:113], v[184:185]
	v_pk_fma_f32 v[114:115], v[78:79], v[114:115], v[182:183]
	v_pk_fma_f32 v[118:119], v[72:73], v[118:119], v[180:181]
	v_pk_fma_f32 v[116:117], v[74:75], v[116:117], v[178:179]
	v_pk_add_f32 v[62:63], v[62:63], v[114:115]
	v_pk_add_f32 v[60:61], v[60:61], v[112:113]
	v_pk_add_f32 v[58:59], v[58:59], v[116:117]
	v_pk_add_f32 v[56:57], v[56:57], v[118:119]
	v_cvt_pk_bf16_f32 v60, v60, v61
	v_cvt_pk_bf16_f32 v61, v62, v63
	s_nop 0
	v_cvt_pk_bf16_f32 v62, v56, v57
	v_cvt_pk_bf16_f32 v63, v58, v59
	v_lshlrev_b32_e32 v56, 16, v60
	v_and_b32_e32 v58, 0xffff0000, v60
	v_lshlrev_b32_e32 v112, 16, v61
	v_and_b32_e32 v114, 0xffff0000, v61
	v_lshlrev_b32_e32 v116, 16, v62
	v_and_b32_e32 v118, 0xffff0000, v62
	v_lshlrev_b32_e32 v120, 16, v63
	v_and_b32_e32 v122, 0xffff0000, v63
	v_mul_f32_e32 v57, v56, v56
	v_mul_f32_e32 v59, v58, v58
	v_mul_f32_e32 v113, v112, v112
	v_mul_f32_e32 v115, v114, v114
	v_mul_f32_e32 v117, v116, v116
	v_mul_f32_e32 v119, v118, v118
	v_mul_f32_e32 v121, v120, v120
	v_mul_f32_e32 v123, v122, v122
	v_pk_add_f32 v[56:57], v[56:57], v[58:59]
	v_pk_add_f32 v[58:59], v[112:113], v[114:115]
	v_pk_add_f32 v[112:113], v[120:121], v[122:123]
	v_pk_add_f32 v[56:57], v[56:57], v[58:59]
	v_pk_add_f32 v[58:59], v[116:117], v[118:119]
	global_store_dwordx4 v104, v[60:63], s[20:21]
	v_pk_add_f32 v[58:59], v[58:59], v[112:113]
	s_nop 0
	v_pk_add_f32 v[56:57], v[56:57], v[58:59]
	v_mov_b32_e32 v58, v165
	v_mov_b32_e32 v59, v165
	s_nop 0
	v_mov_b32_dpp v58, v56 quad_perm:[1,0,3,2] row_mask:0xf bank_mask:0xf
	v_mov_b32_dpp v59, v57 quad_perm:[1,0,3,2] row_mask:0xf bank_mask:0xf
	v_pk_add_f32 v[56:57], v[56:57], v[58:59]
	ds_bpermute_b32 v58, v207, v56
	ds_bpermute_b32 v59, v207, v57
	s_waitcnt lgkmcnt(0)
	v_pk_add_f32 v[56:57], v[56:57], v[58:59]
	ds_bpermute_b32 v58, v208, v56
	ds_bpermute_b32 v59, v208, v57
	s_and_saveexec_b64 s[68:69], s[16:17]
	s_cbranch_execz .LBB0_834
	s_waitcnt lgkmcnt(0)
	v_pk_add_f32 v[56:57], v[56:57], v[58:59]
	v_add_co_u32_e32 v58, vcc, 0x10000, v186
	s_nop 1
	v_addc_co_u32_e32 v59, vcc, 0, v187, vcc
	global_store_dwordx2 v[58:59], v[56:57], off

; __device__ __forceinline__ float dpp_x1(float x) { return __builtin_bit_cast(float, __builtin_amdgcn_update_dpp(0, __builtin_bit_cast(int, x), 0xB1, 0xF, 0xF, false)); }
; __device__ __forceinline__ f32x4 dpp_swap1(f32x4 v) { f32x4 r; r[0] = dpp_x1(v[0]); r[1] = dpp_x1(v[1]); r[2] = dpp_x1(v[2]); r[3] = dpp_x1(v[3]); return r; }
;     __device__ __forceinline__ void operator()(const f32x4 (&acc)[2][2][4][2], const Unit& u, int wr, int wc, int fr, int fq, const EpiCtx& X) const {
;     ...
;             for (int m = 0; m < 4; ++m) {
;                 const int rl = ai * HALF + m * 16; const unsigned off = lo + (unsigned)(rl * 64) * 2u;
;                 const f32x4 o0a = acc[ai][0][m][0], o0b = acc[ai][0][m][1], o1a = acc[ai][1][m][0], o1b = acc[ai][1][m][1];
;                 const f32x4 ra_ = dpp_swap1(odd ? o0a : o1a), rb_ = dpp_swap1(odd ? o0b : o1b);
;                 const f32x4 pa[2] = {odd ? ra_ : o0a, odd ? o1a : ra_}, pb[2] = {odd ? rb_ : o0b, odd ? o1b : rb_};
; #pragma unroll
;                 for (int q = 0; q < 2; ++q) {
;                     const u32x4 w0 = raw[2 * m + q];
;                     const f32x4 r0 = (f32x4){bf_lo(w0.x), bf_hi(w0.x), bf_lo(w0.y), bf_hi(w0.y)}, r1 = (f32x4){bf_lo(w0.z), bf_hi(w0.z), bf_lo(w0.w), bf_hi(w0.w)};
;                     f32x4 y0, y1;
;                     if (RESN) { const f32x2 t = tbl[rl + q]; const float mu = t.x, ra = t.y * ALPHA; y0 = (r0 - mu) * ra * g0 + b0 + pa[q]; y1 = (r1 - mu) * ra * g1 + b1 + pb[q]; }
;                     else { y0 = r0 * ALPHA + pa[q]; y1 = r1 * ALPHA + pb[q]; }
;                     { const u32x4 w = pack8f(y0, y1); *(u32x4*)(xb + off + q * 128) = w;
;                         y0 = (f32x4){bf_lo(w.x), bf_hi(w.x), bf_lo(w.y), bf_hi(w.y)}; y1 = (f32x4){bf_lo(w.z), bf_hi(w.z), bf_lo(w.w), bf_hi(w.w)}; }
;                     float sa = ((y0[0] + y0[1]) + (y0[2] + y0[3])) + ((y1[0] + y1[1]) + (y1[2] + y1[3]));
;                     float sb = ((y0[0] * y0[0] + y0[1] * y0[1]) + (y0[2] * y0[2] + y0[3] * y0[3])) + ((y1[0] * y1[0] + y1[1] * y1[1]) + (y1[2] * y1[2] + y1[3] * y1[3]));
;                     sa += dpp_x1(sa);
;                     sb += dpp_x1(sb);
;                     sa += __shfl_xor(sa, 16); sa += __shfl_xor(sa, 32); sb += __shfl_xor(sb, 16); sb += __shfl_xor(sb, 32);
;                     if (fq == 0 && !odd) ps[(size_t)(rl + q) * 64] = (f32x2){sa, sb};
.LBB0_836:
	s_or_b64 exec, exec, s[68:69]
	s_waitcnt lgkmcnt(1)
	v_cndmask_b32_e64 v50, v44, v36, s[10:11]
	s_nop 0
	v_cndmask_b32_e64 v49, v45, v37, s[10:11]
	s_waitcnt lgkmcnt(0)
	v_cndmask_b32_e64 v51, v46, v38, s[10:11]
	v_mov_b32_dpp v48, v50 quad_perm:[1,0,3,2] row_mask:0xf bank_mask:0xf
	s_nop 0
	v_cndmask_b32_e64 v52, v47, v39, s[10:11]
	v_cndmask_b32_e64 v54, v40, v32, s[10:11]
	v_mov_b32_dpp v50, v49 quad_perm:[1,0,3,2] row_mask:0xf bank_mask:0xf
	s_nop 0
	v_cndmask_b32_e64 v53, v41, v33, s[10:11]
	v_cndmask_b32_e64 v55, v42, v34, s[10:11]
	v_mov_b32_dpp v49, v51 quad_perm:[1,0,3,2] row_mask:0xf bank_mask:0xf
	s_nop 0
	v_cndmask_b32_e64 v56, v43, v35, s[10:11]
	v_lshlrev_b32_e32 v59, 16, v92
	v_mov_b32_dpp v51, v52 quad_perm:[1,0,3,2] row_mask:0xf bank_mask:0xf
	s_nop 0
	v_and_b32_e32 v60, 0xffff0000, v92
	v_cndmask_b32_e64 v45, v50, v45, s[10:11]
	v_mov_b32_dpp v52, v54 quad_perm:[1,0,3,2] row_mask:0xf bank_mask:0xf
	s_nop 0
	v_cndmask_b32_e64 v44, v48, v44, s[10:11]
	v_lshlrev_b32_e32 v62, 16, v93
	v_mov_b32_dpp v54, v53 quad_perm:[1,0,3,2] row_mask:0xf bank_mask:0xf
	s_nop 0
	v_and_b32_e32 v63, 0xffff0000, v93
	v_lshlrev_b32_e32 v92, 16, v94
	v_mov_b32_dpp v53, v55 quad_perm:[1,0,3,2] row_mask:0xf bank_mask:0xf
	s_nop 0
	v_and_b32_e32 v93, 0xffff0000, v94
	v_lshlrev_b32_e32 v94, 16, v95
	v_mov_b32_dpp v55, v56 quad_perm:[1,0,3,2] row_mask:0xf bank_mask:0xf
	ds_read_b64 v[56:57], v201 offset:1152
	v_and_b32_e32 v95, 0xffff0000, v95
	v_cndmask_b32_e64 v47, v51, v47, s[10:11]
	v_cndmask_b32_e64 v46, v49, v46, s[10:11]
	v_cndmask_b32_e64 v41, v54, v41, s[10:11]
	s_waitcnt lgkmcnt(0)
	v_mul_f32_e32 v58, 0x3fb504f3, v57
	v_sub_f32_e32 v61, v60, v56
	v_sub_f32_e32 v60, v59, v56
	v_pk_mul_f32 v[60:61], v[60:61], v[58:59] op_sel_hi:[1,0]
	v_sub_f32_e32 v63, v63, v56
	v_pk_fma_f32 v[60:61], v[76:77], v[60:61], v[184:185]
	v_sub_f32_e32 v62, v62, v56
	v_pk_add_f32 v[44:45], v[44:45], v[60:61]
	v_sub_f32_e32 v61, v93, v56
	v_sub_f32_e32 v60, v92, v56
	v_sub_f32_e32 v57, v95, v56
	v_sub_f32_e32 v56, v94, v56
	v_pk_mul_f32 v[62:63], v[62:63], v[58:59] op_sel_hi:[1,0]
	v_pk_mul_f32 v[56:57], v[56:57], v[58:59] op_sel_hi:[1,0]
	v_pk_mul_f32 v[58:59], v[60:61], v[58:59] op_sel_hi:[1,0]
	v_cndmask_b32_e64 v40, v52, v40, s[10:11]
	v_cndmask_b32_e64 v43, v55, v43, s[10:11]
	v_cndmask_b32_e64 v42, v53, v42, s[10:11]
	v_pk_fma_f32 v[62:63], v[78:79], v[62:63], v[182:183]
	v_pk_fma_f32 v[58:59], v[72:73], v[58:59], v[180:181]
	v_pk_fma_f32 v[56:57], v[74:75], v[56:57], v[178:179]
	v_pk_add_f32 v[46:47], v[46:47], v[62:63]
	v_pk_add_f32 v[42:43], v[42:43], v[56:57]
	v_pk_add_f32 v[40:41], v[40:41], v[58:59]
	v_cvt_pk_bf16_f32 v56, v44, v45
	v_cvt_pk_bf16_f32 v57, v46, v47
	v_mov_b32_e32 v103, v165
	v_cvt_pk_bf16_f32 v58, v40, v41
	v_cvt_pk_bf16_f32 v59, v42, v43
	v_lshlrev_b32_e32 v40, 16, v56
	v_and_b32_e32 v42, 0xffff0000, v56
	v_lshlrev_b32_e32 v44, 16, v57
	v_and_b32_e32 v46, 0xffff0000, v57
	v_lshlrev_b32_e32 v60, 16, v58
	v_and_b32_e32 v62, 0xffff0000, v58
	v_lshlrev_b32_e32 v92, 16, v59
	v_and_b32_e32 v94, 0xffff0000, v59
	v_mul_f32_e32 v41, v40, v40
	v_mul_f32_e32 v43, v42, v42
	v_mul_f32_e32 v45, v44, v44
	v_mul_f32_e32 v47, v46, v46
	v_mul_f32_e32 v61, v60, v60
	v_mul_f32_e32 v63, v62, v62
	v_mul_f32_e32 v93, v92, v92
	v_mul_f32_e32 v95, v94, v94
	v_pk_add_f32 v[40:41], v[40:41], v[42:43]
	v_pk_add_f32 v[42:43], v[44:45], v[46:47]
	v_pk_add_f32 v[44:45], v[92:93], v[94:95]
	v_pk_add_f32 v[40:41], v[40:41], v[42:43]
	v_pk_add_f32 v[42:43], v[60:61], v[62:63]
	s_nop 0
	v_pk_add_f32 v[42:43], v[42:43], v[44:45]
	s_nop 0
	v_pk_add_f32 v[40:41], v[40:41], v[42:43]
	v_mov_b32_e32 v42, v165
	v_mov_b32_e32 v43, v165
	s_nop 0
	v_mov_b32_dpp v42, v40 quad_perm:[1,0,3,2] row_mask:0xf bank_mask:0xf
	v_mov_b32_dpp v43, v41 quad_perm:[1,0,3,2] row_mask:0xf bank_mask:0xf
	v_pk_add_f32 v[40:41], v[40:41], v[42:43]
	ds_bpermute_b32 v42, v207, v40
	ds_bpermute_b32 v43, v207, v41
	s_waitcnt lgkmcnt(0)
	v_pk_add_f32 v[42:43], v[40:41], v[42:43]
	ds_bpermute_b32 v44, v208, v42
	ds_bpermute_b32 v45, v208, v43
	v_lshl_add_u64 v[40:41], s[20:21], 0, v[102:103]
	global_store_dwordx4 v[40:41], v[56:59], off
	s_and_saveexec_b64 s[68:69], s[16:17]
	s_cbranch_execz .LBB0_838
	s_waitcnt lgkmcnt(0)
	v_pk_add_f32 v[42:43], v[42:43], v[44:45]
	v_add_co_u32_e32 v44, vcc, 0x12000, v186
	s_nop 1
	v_addc_co_u32_e32 v45, vcc, 0, v187, vcc
	global_store_dwordx2 v[44:45], v[42:43], off

; __device__ __forceinline__ float dpp_x1(float x) { return __builtin_bit_cast(float, __builtin_amdgcn_update_dpp(0, __builtin_bit_cast(int, x), 0xB1, 0xF, 0xF, false)); }
; __device__ __forceinline__ f32x4 dpp_swap1(f32x4 v) { f32x4 r; r[0] = dpp_x1(v[0]); r[1] = dpp_x1(v[1]); r[2] = dpp_x1(v[2]); r[3] = dpp_x1(v[3]); return r; }
;     __device__ __forceinline__ void operator()(const f32x4 (&acc)[2][2][4][2], const Unit& u, int wr, int wc, int fr, int fq, const EpiCtx& X) const {
;     ...
;             for (int m = 0; m < 4; ++m) {
;                 const int rl = ai * HALF + m * 16; const unsigned off = lo + (unsigned)(rl * 64) * 2u;
;                 const f32x4 o0a = acc[ai][0][m][0], o0b = acc[ai][0][m][1], o1a = acc[ai][1][m][0], o1b = acc[ai][1][m][1];
;                 const f32x4 ra_ = dpp_swap1(odd ? o0a : o1a), rb_ = dpp_swap1(odd ? o0b : o1b);
;                 const f32x4 pa[2] = {odd ? ra_ : o0a, odd ? o1a : ra_}, pb[2] = {odd ? rb_ : o0b, odd ? o1b : rb_};
; #pragma unroll
;                 for (int q = 0; q < 2; ++q) {
;                     const u32x4 w0 = raw[2 * m + q];
;                     const f32x4 r0 = (f32x4){bf_lo(w0.x), bf_hi(w0.x), bf_lo(w0.y), bf_hi(w0.y)}, r1 = (f32x4){bf_lo(w0.z), bf_hi(w0.z), bf_lo(w0.w), bf_hi(w0.w)};
;                     f32x4 y0, y1;
;                     if (RESN) { const f32x2 t = tbl[rl + q]; const float mu = t.x, ra = t.y * ALPHA; y0 = (r0 - mu) * ra * g0 + b0 + pa[q]; y1 = (r1 - mu) * ra * g1 + b1 + pb[q]; }
;                     else { y0 = r0 * ALPHA + pa[q]; y1 = r1 * ALPHA + pb[q]; }
;                     { const u32x4 w = pack8f(y0, y1); *(u32x4*)(xb + off + q * 128) = w;
;                         y0 = (f32x4){bf_lo(w.x), bf_hi(w.x), bf_lo(w.y), bf_hi(w.y)}; y1 = (f32x4){bf_lo(w.z), bf_hi(w.z), bf_lo(w.w), bf_hi(w.w)}; }
;                     float sa = ((y0[0] + y0[1]) + (y0[2] + y0[3])) + ((y1[0] + y1[1]) + (y1[2] + y1[3]));
;                     float sb = ((y0[0] * y0[0] + y0[1] * y0[1]) + (y0[2] * y0[2] + y0[3] * y0[3])) + ((y1[0] * y1[0] + y1[1] * y1[1]) + (y1[2] * y1[2] + y1[3] * y1[3]));
;                     sa += dpp_x1(sa);
;                     sb += dpp_x1(sb);
;                     sa += __shfl_xor(sa, 16); sa += __shfl_xor(sa, 32); sb += __shfl_xor(sb, 16); sb += __shfl_xor(sb, 32);
;                     if (fq == 0 && !odd) ps[(size_t)(rl + q) * 64] = (f32x2){sa, sb};
.LBB0_840:
	s_or_b64 exec, exec, s[68:69]
	s_waitcnt lgkmcnt(1)
	v_cndmask_b32_e64 v34, v28, v20, s[10:11]
	s_nop 0
	v_cndmask_b32_e64 v33, v29, v21, s[10:11]
	s_waitcnt lgkmcnt(0)
	v_cndmask_b32_e64 v35, v30, v22, s[10:11]
	v_mov_b32_dpp v32, v34 quad_perm:[1,0,3,2] row_mask:0xf bank_mask:0xf
	s_nop 0
	v_cndmask_b32_e64 v36, v31, v23, s[10:11]
	v_cndmask_b32_e64 v38, v24, v16, s[10:11]
	v_mov_b32_dpp v34, v33 quad_perm:[1,0,3,2] row_mask:0xf bank_mask:0xf
	s_nop 0
	v_cndmask_b32_e64 v37, v25, v17, s[10:11]
	v_cndmask_b32_e64 v39, v26, v18, s[10:11]
	v_mov_b32_dpp v33, v35 quad_perm:[1,0,3,2] row_mask:0xf bank_mask:0xf
	s_nop 0
	v_cndmask_b32_e64 v40, v27, v19, s[10:11]
	s_waitcnt vmcnt(11)
	v_lshlrev_b32_e32 v43, 16, v84
	v_mov_b32_dpp v35, v36 quad_perm:[1,0,3,2] row_mask:0xf bank_mask:0xf
	s_nop 0
	v_and_b32_e32 v44, 0xffff0000, v84
	v_cndmask_b32_e64 v29, v34, v29, s[10:11]
	v_mov_b32_dpp v36, v38 quad_perm:[1,0,3,2] row_mask:0xf bank_mask:0xf
	s_nop 0
	v_cndmask_b32_e64 v28, v32, v28, s[10:11]
	v_lshlrev_b32_e32 v46, 16, v85
	v_mov_b32_dpp v38, v37 quad_perm:[1,0,3,2] row_mask:0xf bank_mask:0xf
	s_nop 0
	v_and_b32_e32 v47, 0xffff0000, v85
	v_lshlrev_b32_e32 v48, 16, v86
	v_mov_b32_dpp v37, v39 quad_perm:[1,0,3,2] row_mask:0xf bank_mask:0xf
	s_nop 0
	v_and_b32_e32 v49, 0xffff0000, v86
	v_lshlrev_b32_e32 v50, 16, v87
	v_mov_b32_dpp v39, v40 quad_perm:[1,0,3,2] row_mask:0xf bank_mask:0xf
	ds_read_b64 v[40:41], v201 offset:1280
	v_and_b32_e32 v51, 0xffff0000, v87
	v_cndmask_b32_e64 v31, v35, v31, s[10:11]
	v_cndmask_b32_e64 v30, v33, v30, s[10:11]
	v_cndmask_b32_e64 v25, v38, v25, s[10:11]
	s_waitcnt lgkmcnt(0)
	v_mul_f32_e32 v42, 0x3fb504f3, v41
	v_sub_f32_e32 v45, v44, v40
	v_sub_f32_e32 v44, v43, v40
	v_pk_mul_f32 v[44:45], v[44:45], v[42:43] op_sel_hi:[1,0]
	v_sub_f32_e32 v47, v47, v40
	v_pk_fma_f32 v[44:45], v[76:77], v[44:45], v[184:185]
	v_sub_f32_e32 v46, v46, v40
	v_pk_add_f32 v[28:29], v[28:29], v[44:45]
	v_sub_f32_e32 v45, v49, v40
	v_sub_f32_e32 v44, v48, v40
	v_sub_f32_e32 v41, v51, v40
	v_sub_f32_e32 v40, v50, v40
	v_pk_mul_f32 v[46:47], v[46:47], v[42:43] op_sel_hi:[1,0]
	v_pk_mul_f32 v[40:41], v[40:41], v[42:43] op_sel_hi:[1,0]
	v_pk_mul_f32 v[42:43], v[44:45], v[42:43] op_sel_hi:[1,0]
	v_cndmask_b32_e64 v24, v36, v24, s[10:11]
	v_cndmask_b32_e64 v27, v39, v27, s[10:11]
	v_cndmask_b32_e64 v26, v37, v26, s[10:11]
	v_pk_fma_f32 v[46:47], v[78:79], v[46:47], v[182:183]
	v_pk_fma_f32 v[42:43], v[72:73], v[42:43], v[180:181]
	v_pk_fma_f32 v[40:41], v[74:75], v[40:41], v[178:179]
	v_pk_add_f32 v[30:31], v[30:31], v[46:47]
	v_pk_add_f32 v[26:27], v[26:27], v[40:41]
	v_pk_add_f32 v[24:25], v[24:25], v[42:43]
	v_cvt_pk_bf16_f32 v40, v28, v29
	v_cvt_pk_bf16_f32 v41, v30, v31
	v_mov_b32_e32 v101, v165
	v_cvt_pk_bf16_f32 v42, v24, v25
	v_cvt_pk_bf16_f32 v43, v26, v27
	v_lshlrev_b32_e32 v24, 16, v40
	v_and_b32_e32 v26, 0xffff0000, v40
	v_lshlrev_b32_e32 v28, 16, v41
	v_and_b32_e32 v30, 0xffff0000, v41
	v_lshlrev_b32_e32 v44, 16, v42
	v_and_b32_e32 v46, 0xffff0000, v42
	v_lshlrev_b32_e32 v48, 16, v43
	v_and_b32_e32 v50, 0xffff0000, v43
	v_mul_f32_e32 v25, v24, v24
	v_mul_f32_e32 v27, v26, v26
	v_mul_f32_e32 v29, v28, v28
	v_mul_f32_e32 v31, v30, v30
	v_mul_f32_e32 v45, v44, v44
	v_mul_f32_e32 v47, v46, v46
	v_mul_f32_e32 v49, v48, v48
	v_mul_f32_e32 v51, v50, v50
	v_pk_add_f32 v[24:25], v[24:25], v[26:27]
	v_pk_add_f32 v[26:27], v[28:29], v[30:31]
	v_pk_add_f32 v[28:29], v[48:49], v[50:51]
	v_pk_add_f32 v[24:25], v[24:25], v[26:27]
	v_pk_add_f32 v[26:27], v[44:45], v[46:47]
	s_nop 0
	v_pk_add_f32 v[26:27], v[26:27], v[28:29]
	s_nop 0
	v_pk_add_f32 v[24:25], v[24:25], v[26:27]
	v_mov_b32_e32 v26, v165
	v_mov_b32_e32 v27, v165
	s_nop 0
	v_mov_b32_dpp v26, v24 quad_perm:[1,0,3,2] row_mask:0xf bank_mask:0xf
	v_mov_b32_dpp v27, v25 quad_perm:[1,0,3,2] row_mask:0xf bank_mask:0xf
	v_pk_add_f32 v[24:25], v[24:25], v[26:27]
	ds_bpermute_b32 v26, v207, v24
	ds_bpermute_b32 v27, v207, v25
	s_waitcnt lgkmcnt(0)
	v_pk_add_f32 v[26:27], v[24:25], v[26:27]
	ds_bpermute_b32 v28, v208, v26
	ds_bpermute_b32 v29, v208, v27
	v_lshl_add_u64 v[24:25], s[20:21], 0, v[100:101]
	global_store_dwordx4 v[24:25], v[40:43], off
	s_and_saveexec_b64 s[68:69], s[16:17]
	s_cbranch_execz .LBB0_842
	s_waitcnt lgkmcnt(0)
	v_pk_add_f32 v[26:27], v[26:27], v[28:29]
	v_add_co_u32_e32 v28, vcc, 0x14000, v186
	s_nop 1
	v_addc_co_u32_e32 v29, vcc, 0, v187, vcc
	global_store_dwordx2 v[28:29], v[26:27], off

; __device__ __forceinline__ float dpp_x1(float x) { return __builtin_bit_cast(float, __builtin_amdgcn_update_dpp(0, __builtin_bit_cast(int, x), 0xB1, 0xF, 0xF, false)); }
; __device__ __forceinline__ f32x4 dpp_swap1(f32x4 v) { f32x4 r; r[0] = dpp_x1(v[0]); r[1] = dpp_x1(v[1]); r[2] = dpp_x1(v[2]); r[3] = dpp_x1(v[3]); return r; }
;     __device__ __forceinline__ void operator()(const f32x4 (&acc)[2][2][4][2], const Unit& u, int wr, int wc, int fr, int fq, const EpiCtx& X) const {
;     ...
;             for (int m = 0; m < 4; ++m) {
;                 const int rl = ai * HALF + m * 16; const unsigned off = lo + (unsigned)(rl * 64) * 2u;
;                 const f32x4 o0a = acc[ai][0][m][0], o0b = acc[ai][0][m][1], o1a = acc[ai][1][m][0], o1b = acc[ai][1][m][1];
;                 const f32x4 ra_ = dpp_swap1(odd ? o0a : o1a), rb_ = dpp_swap1(odd ? o0b : o1b);
;                 const f32x4 pa[2] = {odd ? ra_ : o0a, odd ? o1a : ra_}, pb[2] = {odd ? rb_ : o0b, odd ? o1b : rb_};
; #pragma unroll
;                 for (int q = 0; q < 2; ++q) {
;                     const u32x4 w0 = raw[2 * m + q];
;                     const f32x4 r0 = (f32x4){bf_lo(w0.x), bf_hi(w0.x), bf_lo(w0.y), bf_hi(w0.y)}, r1 = (f32x4){bf_lo(w0.z), bf_hi(w0.z), bf_lo(w0.w), bf_hi(w0.w)};
;                     f32x4 y0, y1;
;                     if (RESN) { const f32x2 t = tbl[rl + q]; const float mu = t.x, ra = t.y * ALPHA; y0 = (r0 - mu) * ra * g0 + b0 + pa[q]; y1 = (r1 - mu) * ra * g1 + b1 + pb[q]; }
;                     else { y0 = r0 * ALPHA + pa[q]; y1 = r1 * ALPHA + pb[q]; }
;                     { const u32x4 w = pack8f(y0, y1); *(u32x4*)(xb + off + q * 128) = w;
;                         y0 = (f32x4){bf_lo(w.x), bf_hi(w.x), bf_lo(w.y), bf_hi(w.y)}; y1 = (f32x4){bf_lo(w.z), bf_hi(w.z), bf_lo(w.w), bf_hi(w.w)}; }
;                     float sa = ((y0[0] + y0[1]) + (y0[2] + y0[3])) + ((y1[0] + y1[1]) + (y1[2] + y1[3]));
;                     float sb = ((y0[0] * y0[0] + y0[1] * y0[1]) + (y0[2] * y0[2] + y0[3] * y0[3])) + ((y1[0] * y1[0] + y1[1] * y1[1]) + (y1[2] * y1[2] + y1[3] * y1[3]));
;                     sa += dpp_x1(sa);
;                     sb += dpp_x1(sb);
;                     sa += __shfl_xor(sa, 16); sa += __shfl_xor(sa, 32); sb += __shfl_xor(sb, 16); sb += __shfl_xor(sb, 32);
;                     if (fq == 0 && !odd) ps[(size_t)(rl + q) * 64] = (f32x2){sa, sb};
.LBB0_844:
	s_or_b64 exec, exec, s[68:69]
	s_waitcnt lgkmcnt(1)
	v_cndmask_b32_e64 v18, v12, v4, s[10:11]
	s_nop 0
	v_cndmask_b32_e64 v17, v13, v5, s[10:11]
	s_waitcnt lgkmcnt(0)
	v_cndmask_b32_e64 v19, v14, v6, s[10:11]
	v_mov_b32_dpp v16, v18 quad_perm:[1,0,3,2] row_mask:0xf bank_mask:0xf
	s_nop 0
	v_cndmask_b32_e64 v20, v15, v7, s[10:11]
	v_cndmask_b32_e64 v22, v8, v0, s[10:11]
	v_mov_b32_dpp v18, v17 quad_perm:[1,0,3,2] row_mask:0xf bank_mask:0xf
	s_nop 0
	v_cndmask_b32_e64 v21, v9, v1, s[10:11]
	v_cndmask_b32_e64 v23, v10, v2, s[10:11]
	v_mov_b32_dpp v17, v19 quad_perm:[1,0,3,2] row_mask:0xf bank_mask:0xf
	s_nop 0
	v_cndmask_b32_e64 v24, v11, v3, s[10:11]
	s_waitcnt vmcnt(13)
	v_lshlrev_b32_e32 v27, 16, v68
	v_mov_b32_dpp v19, v20 quad_perm:[1,0,3,2] row_mask:0xf bank_mask:0xf
	s_nop 0
	v_and_b32_e32 v28, 0xffff0000, v68
	v_cndmask_b32_e64 v13, v18, v13, s[10:11]
	v_mov_b32_dpp v20, v22 quad_perm:[1,0,3,2] row_mask:0xf bank_mask:0xf
	s_nop 0
	v_cndmask_b32_e64 v12, v16, v12, s[10:11]
	v_lshlrev_b32_e32 v30, 16, v69
	v_mov_b32_dpp v22, v21 quad_perm:[1,0,3,2] row_mask:0xf bank_mask:0xf
	s_nop 0
	v_and_b32_e32 v31, 0xffff0000, v69
	v_lshlrev_b32_e32 v32, 16, v70
	v_mov_b32_dpp v21, v23 quad_perm:[1,0,3,2] row_mask:0xf bank_mask:0xf
	s_nop 0
	v_and_b32_e32 v33, 0xffff0000, v70
	v_lshlrev_b32_e32 v34, 16, v71
	v_mov_b32_dpp v23, v24 quad_perm:[1,0,3,2] row_mask:0xf bank_mask:0xf
	ds_read_b64 v[24:25], v201 offset:1408
	v_and_b32_e32 v35, 0xffff0000, v71
	v_cndmask_b32_e64 v15, v19, v15, s[10:11]
	v_cndmask_b32_e64 v14, v17, v14, s[10:11]
	v_cndmask_b32_e64 v9, v22, v9, s[10:11]
	s_waitcnt lgkmcnt(0)
	v_mul_f32_e32 v26, 0x3fb504f3, v25
	v_sub_f32_e32 v29, v28, v24
	v_sub_f32_e32 v28, v27, v24
	v_pk_mul_f32 v[28:29], v[28:29], v[26:27] op_sel_hi:[1,0]
	v_sub_f32_e32 v31, v31, v24
	v_pk_fma_f32 v[28:29], v[76:77], v[28:29], v[184:185]
	v_sub_f32_e32 v30, v30, v24
	v_pk_add_f32 v[12:13], v[12:13], v[28:29]
	v_sub_f32_e32 v29, v33, v24
	v_sub_f32_e32 v28, v32, v24
	v_sub_f32_e32 v25, v35, v24
	v_sub_f32_e32 v24, v34, v24
	v_pk_mul_f32 v[30:31], v[30:31], v[26:27] op_sel_hi:[1,0]
	v_pk_mul_f32 v[24:25], v[24:25], v[26:27] op_sel_hi:[1,0]
	v_pk_mul_f32 v[26:27], v[28:29], v[26:27] op_sel_hi:[1,0]
	v_cndmask_b32_e64 v8, v20, v8, s[10:11]
	v_cndmask_b32_e64 v11, v23, v11, s[10:11]
	v_cndmask_b32_e64 v10, v21, v10, s[10:11]
	v_pk_fma_f32 v[30:31], v[78:79], v[30:31], v[182:183]
	v_pk_fma_f32 v[26:27], v[72:73], v[26:27], v[180:181]
	v_pk_fma_f32 v[24:25], v[74:75], v[24:25], v[178:179]
	v_pk_add_f32 v[14:15], v[14:15], v[30:31]
	v_pk_add_f32 v[10:11], v[10:11], v[24:25]
	v_pk_add_f32 v[8:9], v[8:9], v[26:27]
	v_cvt_pk_bf16_f32 v24, v12, v13
	v_cvt_pk_bf16_f32 v25, v14, v15
	s_nop 0
	v_cvt_pk_bf16_f32 v26, v8, v9
	v_cvt_pk_bf16_f32 v27, v10, v11
	v_lshlrev_b32_e32 v8, 16, v24
	v_and_b32_e32 v10, 0xffff0000, v24
	v_lshlrev_b32_e32 v12, 16, v25
	v_and_b32_e32 v14, 0xffff0000, v25
	v_lshlrev_b32_e32 v28, 16, v26
	v_and_b32_e32 v30, 0xffff0000, v26
	v_lshlrev_b32_e32 v32, 16, v27
	v_and_b32_e32 v34, 0xffff0000, v27
	v_mul_f32_e32 v9, v8, v8
	v_mul_f32_e32 v11, v10, v10
	v_mul_f32_e32 v13, v12, v12
	v_mul_f32_e32 v15, v14, v14
	v_mul_f32_e32 v29, v28, v28
	v_mul_f32_e32 v31, v30, v30
	v_mul_f32_e32 v33, v32, v32
	v_mul_f32_e32 v35, v34, v34
	v_pk_add_f32 v[8:9], v[8:9], v[10:11]
	v_pk_add_f32 v[10:11], v[12:13], v[14:15]
	v_pk_add_f32 v[12:13], v[32:33], v[34:35]
	v_pk_add_f32 v[8:9], v[8:9], v[10:11]
	v_pk_add_f32 v[10:11], v[28:29], v[30:31]
	s_nop 0
	v_pk_add_f32 v[10:11], v[10:11], v[12:13]
	s_nop 0
	v_pk_add_f32 v[8:9], v[8:9], v[10:11]
	v_mov_b32_e32 v10, v165
	v_mov_b32_e32 v11, v165
	s_nop 0
	v_mov_b32_dpp v10, v8 quad_perm:[1,0,3,2] row_mask:0xf bank_mask:0xf
	v_mov_b32_dpp v11, v9 quad_perm:[1,0,3,2] row_mask:0xf bank_mask:0xf
	v_pk_add_f32 v[8:9], v[8:9], v[10:11]
	ds_bpermute_b32 v10, v207, v8
	ds_bpermute_b32 v11, v207, v9
	s_waitcnt lgkmcnt(0)
	v_pk_add_f32 v[10:11], v[8:9], v[10:11]
	ds_bpermute_b32 v12, v208, v10
	ds_bpermute_b32 v13, v208, v11
	v_lshl_add_u64 v[8:9], s[20:21], 0, v[164:165]
	global_store_dwordx4 v[8:9], v[24:27], off
	s_and_saveexec_b64 s[20:21], s[16:17]
	s_cbranch_execz .LBB0_846
	s_waitcnt lgkmcnt(0)
	v_pk_add_f32 v[10:11], v[10:11], v[12:13]
	v_add_co_u32_e32 v12, vcc, 0x16000, v186
	s_nop 1
	v_addc_co_u32_e32 v13, vcc, 0, v187, vcc
	global_store_dwordx2 v[12:13], v[10:11], off

; #define LAS __attribute__((address_space(3)))
; #define EPI_OPAQUE(x) asm volatile("" : "+v"(x))
;     __device__ __forceinline__ float pre(const Unit& u, int tid) const { return (tid < 256 ? sv : tv)[u.pn * BM + (tid & 255)]; }
;     __device__ __forceinline__ float pre(const Unit& u, int tid) const { return (tid < 256 ? sv : tv)[u.pn * BM + (tid & 255)]; }
; __device__ __forceinline__ float dpp_x1(float x) { return __builtin_bit_cast(float, __builtin_amdgcn_update_dpp(0, __builtin_bit_cast(int, x), 0xB1, 0xF, 0xF, false)); }
; __device__ __forceinline__ f32x4 dpp_swap1(f32x4 v) { f32x4 r; r[0] = dpp_x1(v[0]); r[1] = dpp_x1(v[1]); r[2] = dpp_x1(v[2]); r[3] = dpp_x1(v[3]); return r; }
;     __device__ __forceinline__ void operator()(const f32x4 (&acc)[2][2][4][2], const Unit& u, int wr, int wc, int fr, int fq, const EpiCtx& X) const {
;     ...
;         LAS float* stb = (LAS float*)(X.lds + STB_OFF);
;         stb[X.tid] = X.pre;
;         asm volatile("s_waitcnt lgkmcnt(0)" ::: "memory"); __builtin_amdgcn_s_barrier(); asm volatile("" ::: "memory");
;         const bool odd = fr & 1; const int fe = fr - (fr & 1), o32 = (fr & 1) * 32;
;         constexpr int RP = BLK ? 64 : LDC;
;         char* base = BLK ? (char*)(O + (size_t)u.pm * BM * LDC + (size_t)(u.pn * 4 + wc) * (BM * 64)) : (char*)(O + (size_t)u.pm * BM * LDC + u.pn * BM);
;         unsigned lo = (unsigned)((wr * 64 + fe) * RP + (BLK ? 0 : wc * 64) + o32 + 8 * fq) * 2u; EPI_OPAQUE(lo);
;         const LAS f32x2* tbl = (const LAS f32x2*)(X.lds + TBL_OFF) + wr * 64 + fe;
;         const LAS f32x4* sp = (const LAS f32x4*)(stb + wc * 64 + o32 + 8 * fq);
;         const f32x4 sa = sp[0], sb = sp[1], ta = sp[64], tb = sp[65];
;     ...
;         EPI_PIECES({ const unsigned off = lo + (unsigned)(rl * RP) * 2u; LN_ONE(p1a, p1b, rl, off); LN_ONE(p2a, p2b, rl + 1, off + RP * 2); })
.LBB0_975:
	v_cndmask_b32_e64 v185, v124, v116, s[14:15]
	s_nop 0
	v_cndmask_b32_e64 v184, v125, v117, s[14:15]
	v_cndmask_b32_e64 v189, v120, v112, s[14:15]
	v_mov_b32_dpp v186, v185 quad_perm:[1,0,3,2] row_mask:0xf bank_mask:0xf
	s_nop 0
	s_nop 0
	v_cndmask_b32_e64 v183, v126, v118, s[14:15]
	v_mov_b32_dpp v185, v184 quad_perm:[1,0,3,2] row_mask:0xf bank_mask:0xf
	s_nop 0
	v_cndmask_b32_e64 v188, v121, v113, s[14:15]
	v_mov_b32_dpp v190, v189 quad_perm:[1,0,3,2] row_mask:0xf bank_mask:0xf
	s_nop 0
	v_cndmask_b32_e64 v182, v127, v119, s[14:15]
	v_mov_b32_dpp v184, v183 quad_perm:[1,0,3,2] row_mask:0xf bank_mask:0xf
	s_nop 0
	v_cndmask_b32_e64 v187, v122, v114, s[14:15]
	v_mov_b32_dpp v189, v188 quad_perm:[1,0,3,2] row_mask:0xf bank_mask:0xf
	s_nop 0
	s_waitcnt vmcnt(16)
	ds_write_b32 v171, v181
	v_mov_b32_e32 v152, v174
	v_mov_b32_dpp v183, v182 quad_perm:[1,0,3,2] row_mask:0xf bank_mask:0xf
	v_cndmask_b32_e64 v182, v123, v115, s[14:15]
	v_mov_b32_dpp v188, v187 quad_perm:[1,0,3,2] row_mask:0xf bank_mask:0xf
	s_nop 0
	s_waitcnt lgkmcnt(0)
	s_barrier
	ds_read_b128 v[136:139], v176
	s_waitcnt lgkmcnt(2)
	ds_read_b128 v[132:135], v176 offset:16
	ds_read_b128 v[140:143], v176 offset:1024
	ds_read_b128 v[128:131], v176 offset:1040
	v_mov_b32_dpp v187, v182 quad_perm:[1,0,3,2] row_mask:0xf bank_mask:0xf
	v_cndmask_b32_e64 v126, v184, v126, s[14:15]
	v_cndmask_b32_e64 v125, v185, v125, s[14:15]
	v_cndmask_b32_e64 v182, v118, v184, s[14:15]
	v_cndmask_b32_e64 v185, v117, v185, s[14:15]
	v_cndmask_b32_e64 v184, v116, v186, s[14:15]
	ds_read_b64 v[116:117], v175
	s_mul_i32 s5, s64, 0x600000
	s_mul_hi_i32 s4, s64, 0x600000
	s_add_u32 s18, s77, s5
	v_cndmask_b32_e64 v124, v186, v124, s[14:15]
	s_addc_u32 s19, s78, s4
	s_ashr_i32 s67, s66, 31
	v_cndmask_b32_e64 v123, v187, v123, s[14:15]
	v_cndmask_b32_e64 v187, v115, v187, s[14:15]
	v_cndmask_b32_e64 v186, v114, v188, s[14:15]
	s_waitcnt lgkmcnt(0)
	v_pk_fma_f32 v[114:115], v[136:137], v[116:117], v[124:125] op_sel_hi:[1,0,1] neg_lo:[1,0,0] neg_hi:[1,0,0]
	s_lshl_b64 s[4:5], s[66:67], 1
	v_cndmask_b32_e64 v127, v183, v127, s[14:15]
	v_cndmask_b32_e64 v122, v188, v122, s[14:15]
	v_cndmask_b32_e64 v121, v189, v121, s[14:15]
	v_cndmask_b32_e64 v120, v190, v120, s[14:15]
	v_cndmask_b32_e64 v189, v113, v189, s[14:15]
	v_cndmask_b32_e64 v188, v112, v190, s[14:15]
	v_xor_b32_e32 v113, 0x80000000, v139
	v_xor_b32_e32 v112, 0x80000000, v138
	v_pk_fma_f32 v[124:125], v[116:117], v[114:115], v[140:141] op_sel:[1,0,0]
	v_xor_b32_e32 v115, 0x80000000, v135
	v_xor_b32_e32 v114, 0x80000000, v134
	s_add_u32 s18, s18, s4
	v_cndmask_b32_e64 v183, v119, v183, s[14:15]
	v_pk_fma_f32 v[118:119], v[112:113], v[116:117], v[126:127] op_sel_hi:[1,0,1]
	v_pk_fma_f32 v[120:121], v[132:133], v[116:117], v[120:121] op_sel_hi:[1,0,1] neg_lo:[1,0,0] neg_hi:[1,0,0]
	v_pk_fma_f32 v[122:123], v[114:115], v[116:117], v[122:123] op_sel_hi:[1,0,1]
	s_addc_u32 s19, s19, s5
	v_pk_fma_f32 v[118:119], v[116:117], v[118:119], v[142:143] op_sel:[1,0,0]
	v_pk_fma_f32 v[122:123], v[116:117], v[122:123], v[130:131] op_sel:[1,0,0]
	v_pk_fma_f32 v[120:121], v[116:117], v[120:121], v[128:129] op_sel:[1,0,0]
	v_cvt_pk_bf16_f32 v116, v124, v125
	v_cvt_pk_bf16_f32 v117, v118, v119
	v_mov_b32_e32 v126, 0
	v_cvt_pk_bf16_f32 v118, v120, v121
	v_cvt_pk_bf16_f32 v119, v122, v123
	global_store_dwordx4 v152, v[116:119], s[18:19]
	ds_read_b64 v[116:117], v175 offset:8
	s_waitcnt lgkmcnt(0)
	v_pk_fma_f32 v[120:121], v[112:113], v[116:117], v[182:183] op_sel_hi:[1,0,1]
	v_pk_fma_f32 v[118:119], v[136:137], v[116:117], v[184:185] op_sel_hi:[1,0,1] neg_lo:[1,0,0] neg_hi:[1,0,0]
	v_pk_fma_f32 v[120:121], v[116:117], v[120:121], v[142:143] op_sel:[1,0,0]
	v_pk_fma_f32 v[122:123], v[132:133], v[116:117], v[188:189] op_sel_hi:[1,0,1] neg_lo:[1,0,0] neg_hi:[1,0,0]
	v_pk_fma_f32 v[124:125], v[114:115], v[116:117], v[186:187] op_sel_hi:[1,0,1]
	v_pk_fma_f32 v[118:119], v[116:117], v[118:119], v[140:141] op_sel:[1,0,0]
	v_pk_fma_f32 v[124:125], v[116:117], v[124:125], v[130:131] op_sel:[1,0,0]
	v_pk_fma_f32 v[122:123], v[116:117], v[122:123], v[128:129] op_sel:[1,0,0]
	v_cvt_pk_bf16_f32 v116, v118, v119
	v_cvt_pk_bf16_f32 v117, v120, v121
	v_add_u32_e32 v120, 0x6000, v152
	v_cvt_pk_bf16_f32 v118, v122, v123
	v_cvt_pk_bf16_f32 v119, v124, v125
	global_store_dwordx4 v120, v[116:119], s[18:19]
	ds_read_b64 v[116:117], v175 offset:128
	v_cndmask_b32_e64 v121, v108, v100, s[14:15]
	s_nop 0
	v_cndmask_b32_e64 v120, v109, v101, s[14:15]
	v_cndmask_b32_e64 v125, v104, v96, s[14:15]
	v_mov_b32_dpp v122, v121 quad_perm:[1,0,3,2] row_mask:0xf bank_mask:0xf
	s_nop 0
	v_cndmask_b32_e64 v119, v110, v102, s[14:15]
	v_cndmask_b32_e64 v124, v105, v97, s[14:15]
	v_mov_b32_dpp v121, v120 quad_perm:[1,0,3,2] row_mask:0xf bank_mask:0xf
	s_nop 0
	v_mov_b32_dpp v126, v125 quad_perm:[1,0,3,2] row_mask:0xf bank_mask:0xf
	s_nop 0
	v_cndmask_b32_e64 v118, v111, v103, s[14:15]
	v_mov_b32_dpp v120, v119 quad_perm:[1,0,3,2] row_mask:0xf bank_mask:0xf
	s_nop 0
	v_cndmask_b32_e64 v123, v106, v98, s[14:15]
	v_mov_b32_dpp v125, v124 quad_perm:[1,0,3,2] row_mask:0xf bank_mask:0xf
	s_nop 0
	v_mov_b32_dpp v119, v118 quad_perm:[1,0,3,2] row_mask:0xf bank_mask:0xf
	v_cndmask_b32_e64 v118, v107, v99, s[14:15]
	v_mov_b32_dpp v124, v123 quad_perm:[1,0,3,2] row_mask:0xf bank_mask:0xf
	s_nop 0
	v_cndmask_b32_e64 v109, v121, v109, s[14:15]
	v_cndmask_b32_e64 v108, v122, v108, s[14:15]
	v_mov_b32_dpp v123, v118 quad_perm:[1,0,3,2] row_mask:0xf bank_mask:0xf
	v_cndmask_b32_e64 v111, v119, v111, s[14:15]
	v_cndmask_b32_e64 v110, v120, v110, s[14:15]
	v_cndmask_b32_e64 v102, v102, v120, s[14:15]
	v_cndmask_b32_e64 v101, v101, v121, s[14:15]
	v_cndmask_b32_e64 v121, v97, v125, s[14:15]
	v_cndmask_b32_e64 v120, v96, v126, s[14:15]
	s_waitcnt lgkmcnt(0)
;     __device__ __forceinline__ void operator()(const f32x4 (&acc)[2][2][4][2], const Unit& u, int wr, int wc, int fr, int fq, const EpiCtx& X) const {
;     ...
;         EPI_PIECES({ const unsigned off = lo + (unsigned)(rl * RP) * 2u; LN_ONE(p1a, p1b, rl, off); LN_ONE(p2a, p2b, rl + 1, off + RP * 2); })
	v_pk_fma_f32 v[96:97], v[136:137], v[116:117], v[108:109] op_sel_hi:[1,0,1] neg_lo:[1,0,0] neg_hi:[1,0,0]
	v_cndmask_b32_e64 v107, v123, v107, s[14:15]
	v_cndmask_b32_e64 v106, v124, v106, s[14:15]
	v_cndmask_b32_e64 v105, v125, v105, s[14:15]
	v_cndmask_b32_e64 v104, v126, v104, s[14:15]
	v_cndmask_b32_e64 v103, v103, v119, s[14:15]
	v_cndmask_b32_e64 v119, v99, v123, s[14:15]
	v_cndmask_b32_e64 v118, v98, v124, s[14:15]
	v_pk_fma_f32 v[98:99], v[112:113], v[116:117], v[110:111] op_sel_hi:[1,0,1]
	v_pk_fma_f32 v[96:97], v[116:117], v[96:97], v[140:141] op_sel:[1,0,0]
	v_cndmask_b32_e64 v100, v100, v122, s[14:15]
	v_add_u32_e32 v122, 0x60000, v152
	v_pk_fma_f32 v[98:99], v[116:117], v[98:99], v[142:143] op_sel:[1,0,0]
	v_pk_fma_f32 v[104:105], v[132:133], v[116:117], v[104:105] op_sel_hi:[1,0,1] neg_lo:[1,0,0] neg_hi:[1,0,0]
	v_pk_fma_f32 v[106:107], v[114:115], v[116:117], v[106:107] op_sel_hi:[1,0,1]
	v_cvt_pk_bf16_f32 v96, v96, v97
	v_cvt_pk_bf16_f32 v97, v98, v99
	v_pk_fma_f32 v[104:105], v[116:117], v[104:105], v[128:129] op_sel:[1,0,0]
	v_pk_fma_f32 v[106:107], v[116:117], v[106:107], v[130:131] op_sel:[1,0,0]
	v_cvt_pk_bf16_f32 v98, v104, v105
	s_nop 0
	v_cvt_pk_bf16_f32 v99, v106, v107
	global_store_dwordx4 v122, v[96:99], s[18:19]
	ds_read_b64 v[96:97], v175 offset:136
	s_waitcnt lgkmcnt(0)
	v_pk_fma_f32 v[104:105], v[114:115], v[96:97], v[118:119] op_sel_hi:[1,0,1]
	v_pk_fma_f32 v[98:99], v[136:137], v[96:97], v[100:101] op_sel_hi:[1,0,1] neg_lo:[1,0,0] neg_hi:[1,0,0]
	v_pk_fma_f32 v[100:101], v[112:113], v[96:97], v[102:103] op_sel_hi:[1,0,1]
	v_pk_fma_f32 v[98:99], v[96:97], v[98:99], v[140:141] op_sel:[1,0,0]
	v_pk_fma_f32 v[100:101], v[96:97], v[100:101], v[142:143] op_sel:[1,0,0]
	v_pk_fma_f32 v[102:103], v[132:133], v[96:97], v[120:121] op_sel_hi:[1,0,1] neg_lo:[1,0,0] neg_hi:[1,0,0]
	v_pk_fma_f32 v[104:105], v[96:97], v[104:105], v[130:131] op_sel:[1,0,0]
	v_pk_fma_f32 v[102:103], v[96:97], v[102:103], v[128:129] op_sel:[1,0,0]
	v_cvt_pk_bf16_f32 v96, v98, v99
	v_cvt_pk_bf16_f32 v97, v100, v101
	v_add_u32_e32 v100, 0x66000, v152
	v_cvt_pk_bf16_f32 v98, v102, v103
	v_cvt_pk_bf16_f32 v99, v104, v105
	global_store_dwordx4 v100, v[96:99], s[18:19]
	s_nop 0
	v_cndmask_b32_e64 v103, v88, v80, s[14:15]
	v_cndmask_b32_e64 v99, v92, v84, s[14:15]
	v_cndmask_b32_e64 v98, v93, v85, s[14:15]
	s_nop 0
	v_mov_b32_dpp v100, v99 quad_perm:[1,0,3,2] row_mask:0xf bank_mask:0xf
	s_nop 0
	v_cndmask_b32_e64 v97, v94, v86, s[14:15]
	v_cndmask_b32_e64 v102, v89, v81, s[14:15]
	v_mov_b32_dpp v99, v98 quad_perm:[1,0,3,2] row_mask:0xf bank_mask:0xf
	s_nop 0
	v_mov_b32_dpp v104, v103 quad_perm:[1,0,3,2] row_mask:0xf bank_mask:0xf
	s_nop 0
	v_mov_b32_dpp v98, v97 quad_perm:[1,0,3,2] row_mask:0xf bank_mask:0xf
	v_cndmask_b32_e64 v94, v98, v94, s[14:15]
	v_mov_b32_dpp v103, v102 quad_perm:[1,0,3,2] row_mask:0xf bank_mask:0xf
	v_cndmask_b32_e64 v93, v99, v93, s[14:15]
	v_cndmask_b32_e64 v86, v86, v98, s[14:15]
	v_cndmask_b32_e64 v85, v85, v99, s[14:15]
	v_cndmask_b32_e64 v99, v81, v103, s[14:15]
	v_cndmask_b32_e64 v98, v80, v104, s[14:15]
	ds_read_b64 v[80:81], v175 offset:256
	v_cndmask_b32_e64 v96, v95, v87, s[14:15]
	s_nop 0
	v_cndmask_b32_e64 v101, v90, v82, s[14:15]
	s_nop 0
	v_mov_b32_dpp v97, v96 quad_perm:[1,0,3,2] row_mask:0xf bank_mask:0xf
	v_cndmask_b32_e64 v96, v91, v83, s[14:15]
	v_mov_b32_dpp v102, v101 quad_perm:[1,0,3,2] row_mask:0xf bank_mask:0xf
	s_nop 0
	v_cndmask_b32_e64 v95, v97, v95, s[14:15]
	v_cndmask_b32_e64 v92, v100, v92, s[14:15]
	v_mov_b32_dpp v101, v96 quad_perm:[1,0,3,2] row_mask:0xf bank_mask:0xf
	v_cndmask_b32_e64 v91, v101, v91, s[14:15]
	v_cndmask_b32_e64 v90, v102, v90, s[14:15]
	v_cndmask_b32_e64 v89, v103, v89, s[14:15]
	v_cndmask_b32_e64 v88, v104, v88, s[14:15]
	v_cndmask_b32_e64 v87, v87, v97, s[14:15]
	v_cndmask_b32_e64 v97, v83, v101, s[14:15]
	v_cndmask_b32_e64 v96, v82, v102, s[14:15]
	s_waitcnt lgkmcnt(0)
	v_pk_fma_f32 v[82:83], v[136:137], v[80:81], v[92:93] op_sel_hi:[1,0,1] neg_lo:[1,0,0] neg_hi:[1,0,0]
	v_pk_fma_f32 v[92:93], v[112:113], v[80:81], v[94:95] op_sel_hi:[1,0,1]
	v_pk_fma_f32 v[88:89], v[132:133], v[80:81], v[88:89] op_sel_hi:[1,0,1] neg_lo:[1,0,0] neg_hi:[1,0,0]
	v_pk_fma_f32 v[90:91], v[114:115], v[80:81], v[90:91] op_sel_hi:[1,0,1]
	v_cndmask_b32_e64 v84, v84, v100, s[14:15]
	v_add_u32_e32 v100, 0xc0000, v152
	v_pk_fma_f32 v[92:93], v[80:81], v[92:93], v[142:143] op_sel:[1,0,0]
	v_pk_fma_f32 v[82:83], v[80:81], v[82:83], v[140:141] op_sel:[1,0,0]
	v_pk_fma_f32 v[90:91], v[80:81], v[90:91], v[130:131] op_sel:[1,0,0]
	v_pk_fma_f32 v[88:89], v[80:81], v[88:89], v[128:129] op_sel:[1,0,0]
	v_cvt_pk_bf16_f32 v80, v82, v83
	v_cvt_pk_bf16_f32 v81, v92, v93
	s_nop 0
	v_cvt_pk_bf16_f32 v82, v88, v89
	v_cvt_pk_bf16_f32 v83, v90, v91
	global_store_dwordx4 v100, v[80:83], s[18:19]
	ds_read_b64 v[80:81], v175 offset:264
	s_nop 0
	s_waitcnt lgkmcnt(0)
;     __device__ __forceinline__ void operator()(const f32x4 (&acc)[2][2][4][2], const Unit& u, int wr, int wc, int fr, int fq, const EpiCtx& X) const {
;     ...
;         EPI_PIECES({ const unsigned off = lo + (unsigned)(rl * RP) * 2u; LN_ONE(p1a, p1b, rl, off); LN_ONE(p2a, p2b, rl + 1, off + RP * 2); })
	v_pk_fma_f32 v[82:83], v[136:137], v[80:81], v[84:85] op_sel_hi:[1,0,1] neg_lo:[1,0,0] neg_hi:[1,0,0]
	v_pk_fma_f32 v[84:85], v[112:113], v[80:81], v[86:87] op_sel_hi:[1,0,1]
	v_pk_fma_f32 v[86:87], v[132:133], v[80:81], v[98:99] op_sel_hi:[1,0,1] neg_lo:[1,0,0] neg_hi:[1,0,0]
	v_pk_fma_f32 v[84:85], v[80:81], v[84:85], v[142:143] op_sel:[1,0,0]
	v_pk_fma_f32 v[88:89], v[114:115], v[80:81], v[96:97] op_sel_hi:[1,0,1]
	v_pk_fma_f32 v[82:83], v[80:81], v[82:83], v[140:141] op_sel:[1,0,0]
	v_pk_fma_f32 v[88:89], v[80:81], v[88:89], v[130:131] op_sel:[1,0,0]
	v_pk_fma_f32 v[86:87], v[80:81], v[86:87], v[128:129] op_sel:[1,0,0]
	v_cvt_pk_bf16_f32 v80, v82, v83
	v_cvt_pk_bf16_f32 v81, v84, v85
	v_add_u32_e32 v84, 0xc6000, v152
	v_cvt_pk_bf16_f32 v82, v86, v87
	v_cvt_pk_bf16_f32 v83, v88, v89
	global_store_dwordx4 v84, v[80:83], s[18:19]
	ds_read_b64 v[80:81], v175 offset:384
	v_cndmask_b32_e64 v85, v76, v68, s[14:15]
	s_nop 0
	v_cndmask_b32_e64 v84, v77, v69, s[14:15]
	v_cndmask_b32_e64 v89, v72, v64, s[14:15]
	v_mov_b32_dpp v86, v85 quad_perm:[1,0,3,2] row_mask:0xf bank_mask:0xf
	s_nop 0
	v_cndmask_b32_e64 v83, v78, v70, s[14:15]
	v_cndmask_b32_e64 v88, v73, v65, s[14:15]
	v_mov_b32_dpp v85, v84 quad_perm:[1,0,3,2] row_mask:0xf bank_mask:0xf
	s_nop 0
	v_mov_b32_dpp v90, v89 quad_perm:[1,0,3,2] row_mask:0xf bank_mask:0xf
	s_nop 0
	v_cndmask_b32_e64 v82, v79, v71, s[14:15]
	v_mov_b32_dpp v84, v83 quad_perm:[1,0,3,2] row_mask:0xf bank_mask:0xf
	s_nop 0
	v_cndmask_b32_e64 v87, v74, v66, s[14:15]
	v_mov_b32_dpp v89, v88 quad_perm:[1,0,3,2] row_mask:0xf bank_mask:0xf
	s_nop 0
	v_mov_b32_dpp v83, v82 quad_perm:[1,0,3,2] row_mask:0xf bank_mask:0xf
	v_cndmask_b32_e64 v82, v75, v67, s[14:15]
	v_mov_b32_dpp v88, v87 quad_perm:[1,0,3,2] row_mask:0xf bank_mask:0xf
	s_nop 0
	v_cndmask_b32_e64 v77, v85, v77, s[14:15]
	v_cndmask_b32_e64 v76, v86, v76, s[14:15]
	v_mov_b32_dpp v87, v82 quad_perm:[1,0,3,2] row_mask:0xf bank_mask:0xf
	v_cndmask_b32_e64 v79, v83, v79, s[14:15]
	v_cndmask_b32_e64 v78, v84, v78, s[14:15]
	v_cndmask_b32_e64 v70, v70, v84, s[14:15]
	v_cndmask_b32_e64 v69, v69, v85, s[14:15]
	v_cndmask_b32_e64 v85, v65, v89, s[14:15]
	v_cndmask_b32_e64 v84, v64, v90, s[14:15]
	s_waitcnt lgkmcnt(0)
	v_pk_fma_f32 v[64:65], v[136:137], v[80:81], v[76:77] op_sel_hi:[1,0,1] neg_lo:[1,0,0] neg_hi:[1,0,0]
	v_cndmask_b32_e64 v75, v87, v75, s[14:15]
	v_cndmask_b32_e64 v74, v88, v74, s[14:15]
	v_cndmask_b32_e64 v73, v89, v73, s[14:15]
	v_cndmask_b32_e64 v72, v90, v72, s[14:15]
	v_cndmask_b32_e64 v71, v71, v83, s[14:15]
	v_cndmask_b32_e64 v83, v67, v87, s[14:15]
	v_cndmask_b32_e64 v82, v66, v88, s[14:15]
	v_pk_fma_f32 v[66:67], v[112:113], v[80:81], v[78:79] op_sel_hi:[1,0,1]
	v_pk_fma_f32 v[64:65], v[80:81], v[64:65], v[140:141] op_sel:[1,0,0]
	v_cndmask_b32_e64 v68, v68, v86, s[14:15]
	v_add_u32_e32 v86, 0x120000, v152
	v_pk_fma_f32 v[66:67], v[80:81], v[66:67], v[142:143] op_sel:[1,0,0]
	v_pk_fma_f32 v[72:73], v[132:133], v[80:81], v[72:73] op_sel_hi:[1,0,1] neg_lo:[1,0,0] neg_hi:[1,0,0]
	v_pk_fma_f32 v[74:75], v[114:115], v[80:81], v[74:75] op_sel_hi:[1,0,1]
	v_cvt_pk_bf16_f32 v64, v64, v65
	v_cvt_pk_bf16_f32 v65, v66, v67
	v_pk_fma_f32 v[72:73], v[80:81], v[72:73], v[128:129] op_sel:[1,0,0]
	v_pk_fma_f32 v[74:75], v[80:81], v[74:75], v[130:131] op_sel:[1,0,0]
	v_cvt_pk_bf16_f32 v66, v72, v73
	s_nop 0
	v_cvt_pk_bf16_f32 v67, v74, v75
	global_store_dwordx4 v86, v[64:67], s[18:19]
	ds_read_b64 v[64:65], v175 offset:392
	s_waitcnt lgkmcnt(0)
	v_pk_fma_f32 v[72:73], v[114:115], v[64:65], v[82:83] op_sel_hi:[1,0,1]
	v_pk_fma_f32 v[66:67], v[136:137], v[64:65], v[68:69] op_sel_hi:[1,0,1] neg_lo:[1,0,0] neg_hi:[1,0,0]
	v_pk_fma_f32 v[68:69], v[112:113], v[64:65], v[70:71] op_sel_hi:[1,0,1]
	v_pk_fma_f32 v[66:67], v[64:65], v[66:67], v[140:141] op_sel:[1,0,0]
	v_pk_fma_f32 v[68:69], v[64:65], v[68:69], v[142:143] op_sel:[1,0,0]
	v_pk_fma_f32 v[70:71], v[132:133], v[64:65], v[84:85] op_sel_hi:[1,0,1] neg_lo:[1,0,0] neg_hi:[1,0,0]
	v_pk_fma_f32 v[72:73], v[64:65], v[72:73], v[130:131] op_sel:[1,0,0]
	v_pk_fma_f32 v[70:71], v[64:65], v[70:71], v[128:129] op_sel:[1,0,0]
	v_cvt_pk_bf16_f32 v64, v66, v67
	v_cvt_pk_bf16_f32 v65, v68, v69
	v_add_u32_e32 v68, 0x126000, v152
	v_cvt_pk_bf16_f32 v66, v70, v71
	v_cvt_pk_bf16_f32 v67, v72, v73
	global_store_dwordx4 v68, v[64:67], s[18:19]
	s_nop 0
	v_cndmask_b32_e64 v71, v56, v48, s[14:15]
	v_cndmask_b32_e64 v67, v60, v52, s[14:15]
	v_cndmask_b32_e64 v66, v61, v53, s[14:15]
	s_nop 0
	v_mov_b32_dpp v68, v67 quad_perm:[1,0,3,2] row_mask:0xf bank_mask:0xf
	s_nop 0
	v_cndmask_b32_e64 v65, v62, v54, s[14:15]
	v_cndmask_b32_e64 v70, v57, v49, s[14:15]
	v_mov_b32_dpp v67, v66 quad_perm:[1,0,3,2] row_mask:0xf bank_mask:0xf
	s_nop 0
	v_mov_b32_dpp v72, v71 quad_perm:[1,0,3,2] row_mask:0xf bank_mask:0xf
	s_nop 0
	v_mov_b32_dpp v66, v65 quad_perm:[1,0,3,2] row_mask:0xf bank_mask:0xf
	v_cndmask_b32_e64 v62, v66, v62, s[14:15]
	v_mov_b32_dpp v71, v70 quad_perm:[1,0,3,2] row_mask:0xf bank_mask:0xf
	v_cndmask_b32_e64 v61, v67, v61, s[14:15]
	v_cndmask_b32_e64 v54, v54, v66, s[14:15]
	v_cndmask_b32_e64 v53, v53, v67, s[14:15]
	v_cndmask_b32_e64 v67, v49, v71, s[14:15]
	v_cndmask_b32_e64 v66, v48, v72, s[14:15]
	ds_read_b64 v[48:49], v175 offset:1024
	v_cndmask_b32_e64 v64, v63, v55, s[14:15]
	s_nop 0
	v_cndmask_b32_e64 v69, v58, v50, s[14:15]
	s_nop 0
	v_mov_b32_dpp v65, v64 quad_perm:[1,0,3,2] row_mask:0xf bank_mask:0xf
	v_cndmask_b32_e64 v64, v59, v51, s[14:15]
	v_mov_b32_dpp v70, v69 quad_perm:[1,0,3,2] row_mask:0xf bank_mask:0xf
	s_nop 0
	v_cndmask_b32_e64 v63, v65, v63, s[14:15]
	v_cndmask_b32_e64 v60, v68, v60, s[14:15]
	v_mov_b32_dpp v69, v64 quad_perm:[1,0,3,2] row_mask:0xf bank_mask:0xf
	v_cndmask_b32_e64 v59, v69, v59, s[14:15]
	v_cndmask_b32_e64 v58, v70, v58, s[14:15]
	v_cndmask_b32_e64 v57, v71, v57, s[14:15]
	v_cndmask_b32_e64 v56, v72, v56, s[14:15]
	v_cndmask_b32_e64 v55, v55, v65, s[14:15]
	v_cndmask_b32_e64 v65, v51, v69, s[14:15]
	v_cndmask_b32_e64 v64, v50, v70, s[14:15]
	s_waitcnt lgkmcnt(0)
;     __device__ __forceinline__ void operator()(const f32x4 (&acc)[2][2][4][2], const Unit& u, int wr, int wc, int fr, int fq, const EpiCtx& X) const {
;     ...
;         EPI_PIECES({ const unsigned off = lo + (unsigned)(rl * RP) * 2u; LN_ONE(p1a, p1b, rl, off); LN_ONE(p2a, p2b, rl + 1, off + RP * 2); })
	v_pk_fma_f32 v[50:51], v[136:137], v[48:49], v[60:61] op_sel_hi:[1,0,1] neg_lo:[1,0,0] neg_hi:[1,0,0]
	v_pk_fma_f32 v[60:61], v[112:113], v[48:49], v[62:63] op_sel_hi:[1,0,1]
	v_pk_fma_f32 v[56:57], v[132:133], v[48:49], v[56:57] op_sel_hi:[1,0,1] neg_lo:[1,0,0] neg_hi:[1,0,0]
	v_pk_fma_f32 v[58:59], v[114:115], v[48:49], v[58:59] op_sel_hi:[1,0,1]
	v_cndmask_b32_e64 v52, v52, v68, s[14:15]
	v_add_u32_e32 v68, 0x300000, v152
	v_pk_fma_f32 v[60:61], v[48:49], v[60:61], v[142:143] op_sel:[1,0,0]
	v_pk_fma_f32 v[50:51], v[48:49], v[50:51], v[140:141] op_sel:[1,0,0]
	v_pk_fma_f32 v[58:59], v[48:49], v[58:59], v[130:131] op_sel:[1,0,0]
	v_pk_fma_f32 v[56:57], v[48:49], v[56:57], v[128:129] op_sel:[1,0,0]
	v_cvt_pk_bf16_f32 v48, v50, v51
	v_cvt_pk_bf16_f32 v49, v60, v61
	s_nop 0
	v_cvt_pk_bf16_f32 v50, v56, v57
	v_cvt_pk_bf16_f32 v51, v58, v59
	global_store_dwordx4 v68, v[48:51], s[18:19]
	ds_read_b64 v[48:49], v175 offset:1032
	s_nop 0
	s_waitcnt lgkmcnt(0)
	v_pk_fma_f32 v[50:51], v[136:137], v[48:49], v[52:53] op_sel_hi:[1,0,1] neg_lo:[1,0,0] neg_hi:[1,0,0]
	v_pk_fma_f32 v[52:53], v[112:113], v[48:49], v[54:55] op_sel_hi:[1,0,1]
	v_pk_fma_f32 v[54:55], v[132:133], v[48:49], v[66:67] op_sel_hi:[1,0,1] neg_lo:[1,0,0] neg_hi:[1,0,0]
	v_pk_fma_f32 v[52:53], v[48:49], v[52:53], v[142:143] op_sel:[1,0,0]
	v_pk_fma_f32 v[56:57], v[114:115], v[48:49], v[64:65] op_sel_hi:[1,0,1]
	v_pk_fma_f32 v[50:51], v[48:49], v[50:51], v[140:141] op_sel:[1,0,0]
	v_pk_fma_f32 v[56:57], v[48:49], v[56:57], v[130:131] op_sel:[1,0,0]
	v_pk_fma_f32 v[54:55], v[48:49], v[54:55], v[128:129] op_sel:[1,0,0]
	v_cvt_pk_bf16_f32 v48, v50, v51
	v_cvt_pk_bf16_f32 v49, v52, v53
	v_add_u32_e32 v52, 0x306000, v152
	v_cvt_pk_bf16_f32 v50, v54, v55
	v_cvt_pk_bf16_f32 v51, v56, v57
	global_store_dwordx4 v52, v[48:51], s[18:19]
	ds_read_b64 v[48:49], v175 offset:1152
	v_cndmask_b32_e64 v53, v44, v36, s[14:15]
	s_nop 0
	v_cndmask_b32_e64 v52, v45, v37, s[14:15]
	v_cndmask_b32_e64 v57, v40, v32, s[14:15]
	v_mov_b32_dpp v54, v53 quad_perm:[1,0,3,2] row_mask:0xf bank_mask:0xf
	s_nop 0
	v_cndmask_b32_e64 v51, v46, v38, s[14:15]
	v_cndmask_b32_e64 v56, v41, v33, s[14:15]
	v_mov_b32_dpp v53, v52 quad_perm:[1,0,3,2] row_mask:0xf bank_mask:0xf
	s_nop 0
	v_mov_b32_dpp v58, v57 quad_perm:[1,0,3,2] row_mask:0xf bank_mask:0xf
	s_nop 0
	v_cndmask_b32_e64 v50, v47, v39, s[14:15]
	v_mov_b32_dpp v52, v51 quad_perm:[1,0,3,2] row_mask:0xf bank_mask:0xf
	s_nop 0
	v_cndmask_b32_e64 v55, v42, v34, s[14:15]
	v_mov_b32_dpp v57, v56 quad_perm:[1,0,3,2] row_mask:0xf bank_mask:0xf
	s_nop 0
	v_mov_b32_dpp v51, v50 quad_perm:[1,0,3,2] row_mask:0xf bank_mask:0xf
	v_cndmask_b32_e64 v50, v43, v35, s[14:15]
	v_mov_b32_dpp v56, v55 quad_perm:[1,0,3,2] row_mask:0xf bank_mask:0xf
	s_nop 0
	v_cndmask_b32_e64 v45, v53, v45, s[14:15]
	v_cndmask_b32_e64 v44, v54, v44, s[14:15]
	v_mov_b32_dpp v55, v50 quad_perm:[1,0,3,2] row_mask:0xf bank_mask:0xf
	v_cndmask_b32_e64 v47, v51, v47, s[14:15]
	v_cndmask_b32_e64 v46, v52, v46, s[14:15]
	v_cndmask_b32_e64 v38, v38, v52, s[14:15]
	v_cndmask_b32_e64 v37, v37, v53, s[14:15]
	v_cndmask_b32_e64 v53, v33, v57, s[14:15]
	v_cndmask_b32_e64 v52, v32, v58, s[14:15]
	s_waitcnt lgkmcnt(0)
	v_pk_fma_f32 v[32:33], v[136:137], v[48:49], v[44:45] op_sel_hi:[1,0,1] neg_lo:[1,0,0] neg_hi:[1,0,0]
	v_cndmask_b32_e64 v43, v55, v43, s[14:15]
	v_cndmask_b32_e64 v42, v56, v42, s[14:15]
	v_cndmask_b32_e64 v41, v57, v41, s[14:15]
	v_cndmask_b32_e64 v40, v58, v40, s[14:15]
	v_cndmask_b32_e64 v39, v39, v51, s[14:15]
	v_cndmask_b32_e64 v51, v35, v55, s[14:15]
	v_cndmask_b32_e64 v50, v34, v56, s[14:15]
	v_pk_fma_f32 v[34:35], v[112:113], v[48:49], v[46:47] op_sel_hi:[1,0,1]
	v_pk_fma_f32 v[32:33], v[48:49], v[32:33], v[140:141] op_sel:[1,0,0]
	v_cndmask_b32_e64 v36, v36, v54, s[14:15]
	v_add_u32_e32 v54, 0x360000, v152
	v_pk_fma_f32 v[34:35], v[48:49], v[34:35], v[142:143] op_sel:[1,0,0]
	v_pk_fma_f32 v[40:41], v[132:133], v[48:49], v[40:41] op_sel_hi:[1,0,1] neg_lo:[1,0,0] neg_hi:[1,0,0]
	v_pk_fma_f32 v[42:43], v[114:115], v[48:49], v[42:43] op_sel_hi:[1,0,1]
	v_cvt_pk_bf16_f32 v32, v32, v33
	v_cvt_pk_bf16_f32 v33, v34, v35
	v_pk_fma_f32 v[40:41], v[48:49], v[40:41], v[128:129] op_sel:[1,0,0]
	v_pk_fma_f32 v[42:43], v[48:49], v[42:43], v[130:131] op_sel:[1,0,0]
	v_cvt_pk_bf16_f32 v34, v40, v41
	s_nop 0
	v_cvt_pk_bf16_f32 v35, v42, v43
	global_store_dwordx4 v54, v[32:35], s[18:19]
	ds_read_b64 v[32:33], v175 offset:1160
	s_waitcnt lgkmcnt(0)
;     __device__ __forceinline__ void operator()(const f32x4 (&acc)[2][2][4][2], const Unit& u, int wr, int wc, int fr, int fq, const EpiCtx& X) const {
;     ...
;         EPI_PIECES({ const unsigned off = lo + (unsigned)(rl * RP) * 2u; LN_ONE(p1a, p1b, rl, off); LN_ONE(p2a, p2b, rl + 1, off + RP * 2); })
	v_pk_fma_f32 v[40:41], v[114:115], v[32:33], v[50:51] op_sel_hi:[1,0,1]
	v_pk_fma_f32 v[34:35], v[136:137], v[32:33], v[36:37] op_sel_hi:[1,0,1] neg_lo:[1,0,0] neg_hi:[1,0,0]
	v_pk_fma_f32 v[36:37], v[112:113], v[32:33], v[38:39] op_sel_hi:[1,0,1]
	v_pk_fma_f32 v[34:35], v[32:33], v[34:35], v[140:141] op_sel:[1,0,0]
	v_pk_fma_f32 v[36:37], v[32:33], v[36:37], v[142:143] op_sel:[1,0,0]
	v_pk_fma_f32 v[38:39], v[132:133], v[32:33], v[52:53] op_sel_hi:[1,0,1] neg_lo:[1,0,0] neg_hi:[1,0,0]
	v_pk_fma_f32 v[40:41], v[32:33], v[40:41], v[130:131] op_sel:[1,0,0]
	v_pk_fma_f32 v[38:39], v[32:33], v[38:39], v[128:129] op_sel:[1,0,0]
	v_cvt_pk_bf16_f32 v32, v34, v35
	v_cvt_pk_bf16_f32 v33, v36, v37
	v_add_u32_e32 v36, 0x366000, v152
	v_cvt_pk_bf16_f32 v34, v38, v39
	v_cvt_pk_bf16_f32 v35, v40, v41
	global_store_dwordx4 v36, v[32:35], s[18:19]
	s_nop 0
	v_cndmask_b32_e64 v39, v24, v16, s[14:15]
	v_cndmask_b32_e64 v35, v28, v20, s[14:15]
	v_cndmask_b32_e64 v34, v29, v21, s[14:15]
	s_nop 0
	v_mov_b32_dpp v36, v35 quad_perm:[1,0,3,2] row_mask:0xf bank_mask:0xf
	s_nop 0
	v_cndmask_b32_e64 v33, v30, v22, s[14:15]
	v_cndmask_b32_e64 v38, v25, v17, s[14:15]
	v_mov_b32_dpp v35, v34 quad_perm:[1,0,3,2] row_mask:0xf bank_mask:0xf
	s_nop 0
	v_mov_b32_dpp v40, v39 quad_perm:[1,0,3,2] row_mask:0xf bank_mask:0xf
	s_nop 0
	v_mov_b32_dpp v34, v33 quad_perm:[1,0,3,2] row_mask:0xf bank_mask:0xf
	v_cndmask_b32_e64 v30, v34, v30, s[14:15]
	v_mov_b32_dpp v39, v38 quad_perm:[1,0,3,2] row_mask:0xf bank_mask:0xf
	v_cndmask_b32_e64 v29, v35, v29, s[14:15]
	v_cndmask_b32_e64 v22, v22, v34, s[14:15]
	v_cndmask_b32_e64 v21, v21, v35, s[14:15]
	v_cndmask_b32_e64 v35, v17, v39, s[14:15]
	v_cndmask_b32_e64 v34, v16, v40, s[14:15]
	ds_read_b64 v[16:17], v175 offset:1280
	v_cndmask_b32_e64 v32, v31, v23, s[14:15]
	s_nop 0
	v_cndmask_b32_e64 v37, v26, v18, s[14:15]
	s_nop 0
	v_mov_b32_dpp v33, v32 quad_perm:[1,0,3,2] row_mask:0xf bank_mask:0xf
	v_cndmask_b32_e64 v32, v27, v19, s[14:15]
	v_mov_b32_dpp v38, v37 quad_perm:[1,0,3,2] row_mask:0xf bank_mask:0xf
	s_nop 0
	v_cndmask_b32_e64 v31, v33, v31, s[14:15]
	v_cndmask_b32_e64 v28, v36, v28, s[14:15]
	v_mov_b32_dpp v37, v32 quad_perm:[1,0,3,2] row_mask:0xf bank_mask:0xf
	v_cndmask_b32_e64 v27, v37, v27, s[14:15]
	v_cndmask_b32_e64 v26, v38, v26, s[14:15]
	v_cndmask_b32_e64 v25, v39, v25, s[14:15]
	v_cndmask_b32_e64 v24, v40, v24, s[14:15]
	v_cndmask_b32_e64 v23, v23, v33, s[14:15]
	v_cndmask_b32_e64 v33, v19, v37, s[14:15]
	v_cndmask_b32_e64 v32, v18, v38, s[14:15]
	s_waitcnt lgkmcnt(0)
	v_pk_fma_f32 v[18:19], v[136:137], v[16:17], v[28:29] op_sel_hi:[1,0,1] neg_lo:[1,0,0] neg_hi:[1,0,0]
	v_pk_fma_f32 v[28:29], v[112:113], v[16:17], v[30:31] op_sel_hi:[1,0,1]
	v_pk_fma_f32 v[24:25], v[132:133], v[16:17], v[24:25] op_sel_hi:[1,0,1] neg_lo:[1,0,0] neg_hi:[1,0,0]
	v_pk_fma_f32 v[26:27], v[114:115], v[16:17], v[26:27] op_sel_hi:[1,0,1]
	v_cndmask_b32_e64 v20, v20, v36, s[14:15]
	v_add_u32_e32 v36, 0x3c0000, v152
	v_pk_fma_f32 v[28:29], v[16:17], v[28:29], v[142:143] op_sel:[1,0,0]
	v_pk_fma_f32 v[18:19], v[16:17], v[18:19], v[140:141] op_sel:[1,0,0]
	v_pk_fma_f32 v[26:27], v[16:17], v[26:27], v[130:131] op_sel:[1,0,0]
	v_pk_fma_f32 v[24:25], v[16:17], v[24:25], v[128:129] op_sel:[1,0,0]
	v_cvt_pk_bf16_f32 v16, v18, v19
	v_cvt_pk_bf16_f32 v17, v28, v29
	s_nop 0
	v_cvt_pk_bf16_f32 v18, v24, v25
	v_cvt_pk_bf16_f32 v19, v26, v27
	global_store_dwordx4 v36, v[16:19], s[18:19]
	ds_read_b64 v[16:17], v175 offset:1288
	s_nop 0
	s_waitcnt lgkmcnt(0)
;     __device__ __forceinline__ void operator()(const f32x4 (&acc)[2][2][4][2], const Unit& u, int wr, int wc, int fr, int fq, const EpiCtx& X) const {
;     ...
;         EPI_PIECES({ const unsigned off = lo + (unsigned)(rl * RP) * 2u; LN_ONE(p1a, p1b, rl, off); LN_ONE(p2a, p2b, rl + 1, off + RP * 2); })
	v_pk_fma_f32 v[18:19], v[136:137], v[16:17], v[20:21] op_sel_hi:[1,0,1] neg_lo:[1,0,0] neg_hi:[1,0,0]
	v_pk_fma_f32 v[20:21], v[112:113], v[16:17], v[22:23] op_sel_hi:[1,0,1]
	v_pk_fma_f32 v[22:23], v[132:133], v[16:17], v[34:35] op_sel_hi:[1,0,1] neg_lo:[1,0,0] neg_hi:[1,0,0]
	v_pk_fma_f32 v[20:21], v[16:17], v[20:21], v[142:143] op_sel:[1,0,0]
	v_pk_fma_f32 v[24:25], v[114:115], v[16:17], v[32:33] op_sel_hi:[1,0,1]
	v_pk_fma_f32 v[18:19], v[16:17], v[18:19], v[140:141] op_sel:[1,0,0]
	v_pk_fma_f32 v[24:25], v[16:17], v[24:25], v[130:131] op_sel:[1,0,0]
	v_pk_fma_f32 v[22:23], v[16:17], v[22:23], v[128:129] op_sel:[1,0,0]
	v_cvt_pk_bf16_f32 v16, v18, v19
	v_cvt_pk_bf16_f32 v17, v20, v21
	v_add_u32_e32 v20, 0x3c6000, v152
	v_cvt_pk_bf16_f32 v18, v22, v23
	v_cvt_pk_bf16_f32 v19, v24, v25
	global_store_dwordx4 v20, v[16:19], s[18:19]
	ds_read_b64 v[16:17], v175 offset:1408
	v_cndmask_b32_e64 v21, v12, v4, s[14:15]
	s_nop 0
	v_cndmask_b32_e64 v20, v13, v5, s[14:15]
	v_cndmask_b32_e64 v25, v8, v0, s[14:15]
	v_mov_b32_dpp v22, v21 quad_perm:[1,0,3,2] row_mask:0xf bank_mask:0xf
	s_nop 0
	v_cndmask_b32_e64 v19, v14, v6, s[14:15]
	v_cndmask_b32_e64 v24, v9, v1, s[14:15]
	v_mov_b32_dpp v21, v20 quad_perm:[1,0,3,2] row_mask:0xf bank_mask:0xf
	s_nop 0
	v_mov_b32_dpp v26, v25 quad_perm:[1,0,3,2] row_mask:0xf bank_mask:0xf
	s_nop 0
	v_cndmask_b32_e64 v18, v15, v7, s[14:15]
	v_mov_b32_dpp v20, v19 quad_perm:[1,0,3,2] row_mask:0xf bank_mask:0xf
	s_nop 0
	v_cndmask_b32_e64 v23, v10, v2, s[14:15]
	v_mov_b32_dpp v25, v24 quad_perm:[1,0,3,2] row_mask:0xf bank_mask:0xf
	s_nop 0
	v_mov_b32_dpp v19, v18 quad_perm:[1,0,3,2] row_mask:0xf bank_mask:0xf
	v_cndmask_b32_e64 v18, v11, v3, s[14:15]
	v_mov_b32_dpp v24, v23 quad_perm:[1,0,3,2] row_mask:0xf bank_mask:0xf
	s_nop 0
	v_cndmask_b32_e64 v13, v21, v13, s[14:15]
	v_cndmask_b32_e64 v12, v22, v12, s[14:15]
	v_mov_b32_dpp v23, v18 quad_perm:[1,0,3,2] row_mask:0xf bank_mask:0xf
	v_cndmask_b32_e64 v15, v19, v15, s[14:15]
	v_cndmask_b32_e64 v14, v20, v14, s[14:15]
	v_cndmask_b32_e64 v6, v6, v20, s[14:15]
	v_cndmask_b32_e64 v5, v5, v21, s[14:15]
	v_cndmask_b32_e64 v21, v1, v25, s[14:15]
	v_cndmask_b32_e64 v20, v0, v26, s[14:15]
	s_waitcnt lgkmcnt(0)
	v_pk_fma_f32 v[0:1], v[136:137], v[16:17], v[12:13] op_sel_hi:[1,0,1] neg_lo:[1,0,0] neg_hi:[1,0,0]
	v_cndmask_b32_e64 v11, v23, v11, s[14:15]
	v_cndmask_b32_e64 v10, v24, v10, s[14:15]
	v_cndmask_b32_e64 v9, v25, v9, s[14:15]
	v_cndmask_b32_e64 v8, v26, v8, s[14:15]
	v_cndmask_b32_e64 v7, v7, v19, s[14:15]
	v_cndmask_b32_e64 v19, v3, v23, s[14:15]
	v_cndmask_b32_e64 v18, v2, v24, s[14:15]
	v_pk_fma_f32 v[2:3], v[112:113], v[16:17], v[14:15] op_sel_hi:[1,0,1]
	v_pk_fma_f32 v[0:1], v[16:17], v[0:1], v[140:141] op_sel:[1,0,0]
	v_cndmask_b32_e64 v4, v4, v22, s[14:15]
	v_add_u32_e32 v22, 0x420000, v152
	v_pk_fma_f32 v[2:3], v[16:17], v[2:3], v[142:143] op_sel:[1,0,0]
	v_pk_fma_f32 v[8:9], v[132:133], v[16:17], v[8:9] op_sel_hi:[1,0,1] neg_lo:[1,0,0] neg_hi:[1,0,0]
	v_pk_fma_f32 v[10:11], v[114:115], v[16:17], v[10:11] op_sel_hi:[1,0,1]
	v_cvt_pk_bf16_f32 v0, v0, v1
	v_cvt_pk_bf16_f32 v1, v2, v3
	v_pk_fma_f32 v[8:9], v[16:17], v[8:9], v[128:129] op_sel:[1,0,0]
	v_pk_fma_f32 v[10:11], v[16:17], v[10:11], v[130:131] op_sel:[1,0,0]
	v_cvt_pk_bf16_f32 v2, v8, v9
	s_nop 0
	v_cvt_pk_bf16_f32 v3, v10, v11
	global_store_dwordx4 v22, v[0:3], s[18:19]
	ds_read_b64 v[0:1], v175 offset:1416
	s_waitcnt lgkmcnt(0)
	v_pk_fma_f32 v[8:9], v[114:115], v[0:1], v[18:19] op_sel_hi:[1,0,1]
	v_pk_fma_f32 v[2:3], v[136:137], v[0:1], v[4:5] op_sel_hi:[1,0,1] neg_lo:[1,0,0] neg_hi:[1,0,0]
	v_pk_fma_f32 v[4:5], v[112:113], v[0:1], v[6:7] op_sel_hi:[1,0,1]
	v_pk_fma_f32 v[6:7], v[132:133], v[0:1], v[20:21] op_sel_hi:[1,0,1] neg_lo:[1,0,0] neg_hi:[1,0,0]
	v_pk_fma_f32 v[4:5], v[0:1], v[4:5], v[142:143] op_sel:[1,0,0]
	v_pk_fma_f32 v[2:3], v[0:1], v[2:3], v[140:141] op_sel:[1,0,0]
	v_pk_fma_f32 v[8:9], v[0:1], v[8:9], v[130:131] op_sel:[1,0,0]
	v_pk_fma_f32 v[6:7], v[0:1], v[6:7], v[128:129] op_sel:[1,0,0]
	v_cvt_pk_bf16_f32 v0, v2, v3
	v_cvt_pk_bf16_f32 v1, v4, v5
	v_add_u32_e32 v4, 0x426000, v152
	v_cvt_pk_bf16_f32 v2, v6, v7
	v_cvt_pk_bf16_f32 v3, v8, v9
	global_store_dwordx4 v4, v[0:3], s[18:19]
	s_andn2_b64 vcc, exec, s[16:17]
	s_mov_b64 s[16:17], -1
	s_cbranch_vccnz .LBB0_916

; #define LAS __attribute__((address_space(3)))
;     __device__ __forceinline__ void operator()(const f32x4 (&acc)[2][2][4][2], const Unit& u, int wr, int wc, int fr, int fq, const EpiCtx& X) const {
;     ...
;         char* yb = nullptr; char* xb = (char*)(XB + (size_t)u.pm * BM * DM + (size_t)(u.pn * 4 + wc) * (BM * 64));
;         unsigned lo = (unsigned)((wr * 64 + fe) * 64 + o32 + 8 * fq) * 2u; EPI_OPAQUE(lo);
;         const int col = u.pn * BM + wc * 64 + o32 + 8 * fq;
;         f32x4 g0, g1, b0, b1;
;         if (RESN) { ensure_tbl(PSp, sidp, u.pm, X);
;             g0 = *(const f32x4*)(gp + col); g1 = *(const f32x4*)(gp + col + 4); b0 = *(const f32x4*)(bp + col) * ALPHA; b1 = *(const f32x4*)(bp + col + 4) * ALPHA; }
;         const LAS f32x2* tbl = (const LAS f32x2*)(X.lds + TBL_OFF) + wr * 64 + fe;
;         f32x2* ps = PSn + ((size_t)u.pm * BM + wr * 64 + fe) * 64 + u.pn * 4 + wc;
; #pragma unroll
;         for (int ai = 0; ai < 2; ++ai) {
;             u32x4 raw[8];
; #pragma unroll
;             for (int m = 0; m < 4; ++m) { const unsigned off = lo + (unsigned)((ai * HALF + m * 16) * 64) * 2u; raw[2 * m] = *(const u32x4*)(xb + off); raw[2 * m + 1] = *(const u32x4*)(xb + off + 128); }
; #pragma unroll
;             for (int m = 0; m < 4; ++m) {
;                 const int rl = ai * HALF + m * 16; const unsigned off = lo + (unsigned)(rl * 64) * 2u;
;                 const f32x4 o0a = acc[ai][0][m][0], o0b = acc[ai][0][m][1], o1a = acc[ai][1][m][0], o1b = acc[ai][1][m][1];
;                 const f32x4 ra_ = dpp_swap1(odd ? o0a : o1a), rb_ = dpp_swap1(odd ? o0b : o1b);
;                 const f32x4 pa[2] = {odd ? ra_ : o0a, odd ? o1a : ra_}, pb[2] = {odd ? rb_ : o0b, odd ? o1b : rb_};
; #pragma unroll
;                 for (int q = 0; q < 2; ++q) {
;                     const u32x4 w0 = raw[2 * m + q];
;                     const f32x4 r0 = (f32x4){bf_lo(w0.x), bf_hi(w0.x), bf_lo(w0.y), bf_hi(w0.y)}, r1 = (f32x4){bf_lo(w0.z), bf_hi(w0.z), bf_lo(w0.w), bf_hi(w0.w)};
;                     f32x4 y0, y1;
;                     if (RESN) { const f32x2 t = tbl[rl + q]; const float mu = t.x, ra = t.y * ALPHA; y0 = (r0 - mu) * ra * g0 + b0 + pa[q]; y1 = (r1 - mu) * ra * g1 + b1 + pb[q]; }
;                     else { y0 = r0 * ALPHA + pa[q]; y1 = r1 * ALPHA + pb[q]; }
;                     { const u32x4 w = pack8f(y0, y1); *(u32x4*)(xb + off + q * 128) = w;
.LBB0_1463:
	s_lshl_b64 s[4:5], s[66:67], 21
	s_add_u32 s20, s51, s4
	s_addc_u32 s21, s53, s5
	s_lshl_b32 s66, s64, 2
	s_or_b32 s4, s66, s41
	s_ashr_i32 s5, s4, 31
	v_lshl_add_u32 v72, s64, 8, v200
	v_ashrrev_i32_e32 v73, 31, v72
	s_lshl_b64 s[4:5], s[4:5], 15
	v_lshlrev_b64 v[72:73], 2, v[72:73]
	s_add_u32 s20, s20, s4
	v_lshl_add_u64 v[74:75], s[26:27], 0, v[72:73]
	s_addc_u32 s21, s21, s5
	global_load_dwordx4 v[194:197], v[74:75], off offset:16
	global_load_dwordx4 v[178:181], v[74:75], off
	global_load_dwordx4 v[214:217], v164, s[20:21]
	v_lshl_add_u64 v[72:73], s[24:25], 0, v[72:73]
	s_waitcnt lgkmcnt(0)
	global_load_dwordx4 v[76:79], v[72:73], off
	s_nop 0
	global_load_dwordx4 v[72:75], v[72:73], off offset:16
	v_cndmask_b32_e64 v136, v135, v127, s[10:11]
	v_cndmask_b32_e64 v137, v134, v126, s[10:11]
	v_cndmask_b32_e64 v138, v133, v125, s[10:11]
	v_cndmask_b32_e64 v139, v132, v124, s[10:11]
	s_nop 0
	s_nop 0
	s_nop 0
	s_nop 0
	v_cndmask_b32_e64 v140, v131, v123, s[10:11]
	v_cndmask_b32_e64 v141, v130, v122, s[10:11]
	v_cndmask_b32_e64 v142, v129, v121, s[10:11]
	v_cndmask_b32_e64 v143, v128, v120, s[10:11]
	s_nop 0
	s_nop 0
	s_nop 0
	s_nop 0
	v_mov_b32_dpp v189, v139 quad_perm:[1,0,3,2] row_mask:0xf bank_mask:0xf
	v_mov_b32_dpp v193, v138 quad_perm:[1,0,3,2] row_mask:0xf bank_mask:0xf
	v_mov_b32_dpp v191, v137 quad_perm:[1,0,3,2] row_mask:0xf bank_mask:0xf
	v_mov_b32_dpp v209, v136 quad_perm:[1,0,3,2] row_mask:0xf bank_mask:0xf
	v_mov_b32_dpp v210, v143 quad_perm:[1,0,3,2] row_mask:0xf bank_mask:0xf
	v_mov_b32_dpp v212, v142 quad_perm:[1,0,3,2] row_mask:0xf bank_mask:0xf
	v_mov_b32_dpp v211, v141 quad_perm:[1,0,3,2] row_mask:0xf bank_mask:0xf
	v_mov_b32_dpp v213, v140 quad_perm:[1,0,3,2] row_mask:0xf bank_mask:0xf
	v_add_u32_e32 v192, 0x800, v164
	v_add_u32_e32 v190, 0x1000, v164
	v_add_u32_e32 v188, 0x1800, v164
	ds_read_b64 v[218:219], v201
	v_cndmask_b32_e64 v221, v193, v133, s[10:11]
	v_cndmask_b32_e64 v220, v189, v132, s[10:11]
	v_cndmask_b32_e64 v223, v209, v135, s[10:11]
	v_cndmask_b32_e64 v222, v191, v134, s[10:11]
	v_cndmask_b32_e64 v225, v212, v129, s[10:11]
	v_cndmask_b32_e64 v224, v210, v128, s[10:11]
	v_cndmask_b32_e64 v227, v213, v131, s[10:11]
	v_cndmask_b32_e64 v226, v211, v130, s[10:11]
	global_load_dwordx4 v[152:155], v164, s[20:21] offset:128
	global_load_dwordx4 v[148:151], v192, s[20:21]
	global_load_dwordx4 v[144:147], v192, s[20:21] offset:128
	global_load_dwordx4 v[140:143], v190, s[20:21]
	global_load_dwordx4 v[136:139], v190, s[20:21] offset:128
	global_load_dwordx4 v[132:135], v188, s[20:21]
	global_load_dwordx4 v[128:131], v188, s[20:21] offset:128
	s_waitcnt lgkmcnt(0)
	v_mul_f32_e32 v208, 0x3fb504f3, v219
	v_lshl_add_u64 v[186:187], v[166:167], 0, s[68:69]
	s_ashr_i32 s67, s66, 31
	v_lshl_add_u64 v[186:187], s[66:67], 3, v[186:187]
	v_lshl_add_u64 v[186:187], v[186:187], 0, s[22:23]
	v_add_u32_e32 v246, 0x4000, v164
	v_add_u32_e32 v247, 0x4800, v164
	global_load_dwordx4 v[230:233], v246, s[20:21]
	global_load_dwordx4 v[234:237], v246, s[20:21] offset:128
	global_load_dwordx4 v[238:241], v247, s[20:21]
	global_load_dwordx4 v[242:245], v247, s[20:21] offset:128
	s_waitcnt vmcnt(14)
	v_pk_mul_f32 v[182:183], v[180:181], s[52:53] op_sel_hi:[1,0]
	v_pk_mul_f32 v[184:185], v[178:179], s[52:53] op_sel_hi:[1,0]
	v_pk_mul_f32 v[178:179], v[196:197], s[52:53] op_sel_hi:[1,0]
	v_pk_mul_f32 v[180:181], v[194:195], s[52:53] op_sel_hi:[1,0]
	s_waitcnt vmcnt(13)
	v_lshlrev_b32_e32 v194, 16, v214
	v_and_b32_e32 v195, 0xffff0000, v214
	v_lshlrev_b32_e32 v196, 16, v215
	v_and_b32_e32 v197, 0xffff0000, v215
	v_lshlrev_b32_e32 v207, 16, v216
	v_and_b32_e32 v214, 0xffff0000, v216
	v_lshlrev_b32_e32 v216, 16, v217
	v_and_b32_e32 v217, 0xffff0000, v217
	v_sub_f32_e32 v195, v195, v218
	v_sub_f32_e32 v194, v194, v218
	v_sub_f32_e32 v197, v197, v218
	v_sub_f32_e32 v196, v196, v218
	v_sub_f32_e32 v215, v214, v218
	v_sub_f32_e32 v214, v207, v218
	v_sub_f32_e32 v217, v217, v218
	v_sub_f32_e32 v216, v216, v218
	v_pk_mul_f32 v[196:197], v[196:197], v[208:209] op_sel_hi:[1,0]
	v_pk_mul_f32 v[194:195], v[194:195], v[208:209] op_sel_hi:[1,0]
	v_pk_mul_f32 v[216:217], v[216:217], v[208:209] op_sel_hi:[1,0]
	v_pk_mul_f32 v[214:215], v[214:215], v[208:209] op_sel_hi:[1,0]
	s_waitcnt vmcnt(12)
	v_pk_fma_f32 v[194:195], v[76:77], v[194:195], v[184:185]
	v_pk_fma_f32 v[196:197], v[78:79], v[196:197], v[182:183]
	s_waitcnt vmcnt(11)
	v_pk_fma_f32 v[214:215], v[72:73], v[214:215], v[180:181]
	v_pk_fma_f32 v[216:217], v[74:75], v[216:217], v[178:179]
	v_pk_add_f32 v[196:197], v[222:223], v[196:197]
	v_pk_add_f32 v[194:195], v[220:221], v[194:195]
	v_pk_add_f32 v[218:219], v[226:227], v[216:217]
	v_pk_add_f32 v[216:217], v[224:225], v[214:215]
	v_cvt_pk_bf16_f32 v214, v194, v195
	v_cvt_pk_bf16_f32 v215, v196, v197
	v_and_b32_e32 v208, 64, v206
	v_cvt_pk_bf16_f32 v216, v216, v217
	v_cvt_pk_bf16_f32 v217, v218, v219
	v_lshlrev_b32_e32 v194, 16, v214
	v_and_b32_e32 v196, 0xffff0000, v214
	v_lshlrev_b32_e32 v218, 16, v215
	v_and_b32_e32 v220, 0xffff0000, v215
	v_lshlrev_b32_e32 v222, 16, v216
	v_and_b32_e32 v224, 0xffff0000, v216
	v_lshlrev_b32_e32 v226, 16, v217
	v_and_b32_e32 v228, 0xffff0000, v217
	v_mul_f32_e32 v195, v194, v194
	v_mul_f32_e32 v197, v196, v196
	v_mul_f32_e32 v219, v218, v218
	v_mul_f32_e32 v221, v220, v220
	v_mul_f32_e32 v223, v222, v222
	v_mul_f32_e32 v225, v224, v224
	v_mul_f32_e32 v227, v226, v226
	v_mul_f32_e32 v229, v228, v228
	v_pk_add_f32 v[194:195], v[194:195], v[196:197]
	v_pk_add_f32 v[196:197], v[218:219], v[220:221]
	v_pk_add_f32 v[218:219], v[226:227], v[228:229]
	v_pk_add_f32 v[194:195], v[194:195], v[196:197]
	v_pk_add_f32 v[196:197], v[222:223], v[224:225]
	v_xor_b32_e32 v207, 16, v206
	v_add_u32_e32 v208, 64, v208
	v_pk_add_f32 v[196:197], v[196:197], v[218:219]
	v_cmp_lt_i32_e32 vcc, v207, v208
	v_pk_add_f32 v[194:195], v[194:195], v[196:197]
	s_nop 0
	s_nop 0
	v_cndmask_b32_e32 v207, v206, v207, vcc
	v_mov_b32_dpp v196, v194 quad_perm:[1,0,3,2] row_mask:0xf bank_mask:0xf
	v_mov_b32_dpp v197, v195 quad_perm:[1,0,3,2] row_mask:0xf bank_mask:0xf
	v_lshlrev_b32_e32 v207, 2, v207
	v_pk_add_f32 v[194:195], v[194:195], v[196:197]
	ds_bpermute_b32 v196, v207, v194
	ds_bpermute_b32 v197, v207, v195
	v_xor_b32_e32 v218, 32, v206
	v_cmp_lt_i32_e32 vcc, v218, v208
	global_store_dwordx4 v164, v[214:217], s[20:21]
	s_waitcnt lgkmcnt(0)
	v_pk_add_f32 v[194:195], v[194:195], v[196:197]
	v_cndmask_b32_e32 v208, v206, v218, vcc
	v_lshlrev_b32_e32 v208, 2, v208
	ds_bpermute_b32 v196, v208, v194
	ds_bpermute_b32 v197, v208, v195
	s_and_saveexec_b64 s[64:65], s[16:17]
	s_waitcnt lgkmcnt(0)
	v_pk_add_f32 v[194:195], v[194:195], v[196:197]
	global_store_dwordx2 v[186:187], v[194:195], off

; __device__ __forceinline__ float dpp_x1(float x) { return __builtin_bit_cast(float, __builtin_amdgcn_update_dpp(0, __builtin_bit_cast(int, x), 0xB1, 0xF, 0xF, false)); }
; __device__ __forceinline__ f32x4 dpp_swap1(f32x4 v) { f32x4 r; r[0] = dpp_x1(v[0]); r[1] = dpp_x1(v[1]); r[2] = dpp_x1(v[2]); r[3] = dpp_x1(v[3]); return r; }
;     __device__ __forceinline__ void operator()(const f32x4 (&acc)[2][2][4][2], const Unit& u, int wr, int wc, int fr, int fq, const EpiCtx& X) const {
;     ...
;             for (int m = 0; m < 4; ++m) {
;                 const int rl = ai * HALF + m * 16; const unsigned off = lo + (unsigned)(rl * 64) * 2u;
;                 const f32x4 o0a = acc[ai][0][m][0], o0b = acc[ai][0][m][1], o1a = acc[ai][1][m][0], o1b = acc[ai][1][m][1];
;                 const f32x4 ra_ = dpp_swap1(odd ? o0a : o1a), rb_ = dpp_swap1(odd ? o0b : o1b);
;                 const f32x4 pa[2] = {odd ? ra_ : o0a, odd ? o1a : ra_}, pb[2] = {odd ? rb_ : o0b, odd ? o1b : rb_};
; #pragma unroll
;                 for (int q = 0; q < 2; ++q) {
;                     const u32x4 w0 = raw[2 * m + q];
;                     const f32x4 r0 = (f32x4){bf_lo(w0.x), bf_hi(w0.x), bf_lo(w0.y), bf_hi(w0.y)}, r1 = (f32x4){bf_lo(w0.z), bf_hi(w0.z), bf_lo(w0.w), bf_hi(w0.w)};
;                     f32x4 y0, y1;
;                     if (RESN) { const f32x2 t = tbl[rl + q]; const float mu = t.x, ra = t.y * ALPHA; y0 = (r0 - mu) * ra * g0 + b0 + pa[q]; y1 = (r1 - mu) * ra * g1 + b1 + pb[q]; }
;                     else { y0 = r0 * ALPHA + pa[q]; y1 = r1 * ALPHA + pb[q]; }
;                     { const u32x4 w = pack8f(y0, y1); *(u32x4*)(xb + off + q * 128) = w;
;                         y0 = (f32x4){bf_lo(w.x), bf_hi(w.x), bf_lo(w.y), bf_hi(w.y)}; y1 = (f32x4){bf_lo(w.z), bf_hi(w.z), bf_lo(w.w), bf_hi(w.w)}; }
;                     float sa = ((y0[0] + y0[1]) + (y0[2] + y0[3])) + ((y1[0] + y1[1]) + (y1[2] + y1[3]));
;                     float sb = ((y0[0] * y0[0] + y0[1] * y0[1]) + (y0[2] * y0[2] + y0[3] * y0[3])) + ((y1[0] * y1[0] + y1[1] * y1[1]) + (y1[2] * y1[2] + y1[3] * y1[3]));
;                     sa += dpp_x1(sa);
;                     sb += dpp_x1(sb);
;                     sa += __shfl_xor(sa, 16); sa += __shfl_xor(sa, 32); sb += __shfl_xor(sb, 16); sb += __shfl_xor(sb, 32);
;                     if (fq == 0 && !odd) ps[(size_t)(rl + q) * 64] = (f32x2){sa, sb};
.LBB0_1467:
	s_or_b64 exec, exec, s[64:65]
	s_waitcnt lgkmcnt(1)
	v_cndmask_b32_e64 v122, v116, v108, s[10:11]
	s_nop 0
	v_cndmask_b32_e64 v121, v117, v109, s[10:11]
	s_waitcnt lgkmcnt(0)
	v_cndmask_b32_e64 v123, v118, v110, s[10:11]
	v_mov_b32_dpp v120, v122 quad_perm:[1,0,3,2] row_mask:0xf bank_mask:0xf
	s_nop 0
	v_cndmask_b32_e64 v124, v119, v111, s[10:11]
	v_cndmask_b32_e64 v126, v112, v104, s[10:11]
	v_mov_b32_dpp v122, v121 quad_perm:[1,0,3,2] row_mask:0xf bank_mask:0xf
	s_nop 0
	v_cndmask_b32_e64 v125, v113, v105, s[10:11]
	v_cndmask_b32_e64 v127, v114, v106, s[10:11]
	v_mov_b32_dpp v121, v123 quad_perm:[1,0,3,2] row_mask:0xf bank_mask:0xf
	s_nop 0
	v_cndmask_b32_e64 v152, v115, v107, s[10:11]
	s_waitcnt vmcnt(13)
	v_and_b32_e32 v153, 0xffff0000, v148
	v_mov_b32_dpp v123, v124 quad_perm:[1,0,3,2] row_mask:0xf bank_mask:0xf
	s_nop 0
	v_lshlrev_b32_e32 v154, 16, v149
	v_and_b32_e32 v155, 0xffff0000, v149
	v_mov_b32_dpp v124, v126 quad_perm:[1,0,3,2] row_mask:0xf bank_mask:0xf
	s_nop 0
	v_lshlrev_b32_e32 v189, 16, v150
	v_and_b32_e32 v191, 0xffff0000, v150
	v_mov_b32_dpp v126, v125 quad_perm:[1,0,3,2] row_mask:0xf bank_mask:0xf
	s_nop 0
	v_lshlrev_b32_e32 v193, 16, v151
	v_and_b32_e32 v151, 0xffff0000, v151
	v_mov_b32_dpp v125, v127 quad_perm:[1,0,3,2] row_mask:0xf bank_mask:0xf
	s_nop 0
	v_cndmask_b32_e64 v117, v122, v117, s[10:11]
	v_cndmask_b32_e64 v116, v120, v116, s[10:11]
	v_mov_b32_dpp v127, v152 quad_perm:[1,0,3,2] row_mask:0xf bank_mask:0xf
	v_lshlrev_b32_e32 v152, 16, v148
	ds_read_b64 v[148:149], v201 offset:128
	v_cndmask_b32_e64 v119, v123, v119, s[10:11]
	v_cndmask_b32_e64 v118, v121, v118, s[10:11]
	v_cndmask_b32_e64 v113, v126, v113, s[10:11]
	v_cndmask_b32_e64 v112, v124, v112, s[10:11]
	s_waitcnt lgkmcnt(0)
	v_mul_f32_e32 v150, 0x3fb504f3, v149
	v_sub_f32_e32 v153, v153, v148
	v_sub_f32_e32 v152, v152, v148
	v_pk_mul_f32 v[152:153], v[152:153], v[150:151] op_sel_hi:[1,0]
	v_sub_f32_e32 v155, v155, v148
	v_pk_fma_f32 v[152:153], v[76:77], v[152:153], v[184:185]
	v_sub_f32_e32 v154, v154, v148
	v_pk_add_f32 v[116:117], v[116:117], v[152:153]
	v_sub_f32_e32 v153, v191, v148
	v_sub_f32_e32 v152, v189, v148
	v_sub_f32_e32 v149, v151, v148
	v_sub_f32_e32 v148, v193, v148
	v_pk_mul_f32 v[154:155], v[154:155], v[150:151] op_sel_hi:[1,0]
	v_pk_mul_f32 v[148:149], v[148:149], v[150:151] op_sel_hi:[1,0]
	v_pk_mul_f32 v[150:151], v[152:153], v[150:151] op_sel_hi:[1,0]
	v_cndmask_b32_e64 v115, v127, v115, s[10:11]
	v_cndmask_b32_e64 v114, v125, v114, s[10:11]
	v_pk_fma_f32 v[154:155], v[78:79], v[154:155], v[182:183]
	v_pk_fma_f32 v[150:151], v[72:73], v[150:151], v[180:181]
	v_pk_fma_f32 v[148:149], v[74:75], v[148:149], v[178:179]
	v_pk_add_f32 v[118:119], v[118:119], v[154:155]
	v_pk_add_f32 v[114:115], v[114:115], v[148:149]
	v_pk_add_f32 v[112:113], v[112:113], v[150:151]
	v_cvt_pk_bf16_f32 v148, v116, v117
	v_cvt_pk_bf16_f32 v149, v118, v119
	v_mov_b32_e32 v193, v165
	v_cvt_pk_bf16_f32 v150, v112, v113
	v_cvt_pk_bf16_f32 v151, v114, v115
	v_lshlrev_b32_e32 v112, 16, v148
	v_and_b32_e32 v114, 0xffff0000, v148
	v_lshlrev_b32_e32 v116, 16, v149
	v_and_b32_e32 v118, 0xffff0000, v149
	v_lshlrev_b32_e32 v152, 16, v150
	v_and_b32_e32 v154, 0xffff0000, v150
	v_lshlrev_b32_e32 v194, 16, v151
	v_and_b32_e32 v196, 0xffff0000, v151
	v_mul_f32_e32 v113, v112, v112
	v_mul_f32_e32 v115, v114, v114
	v_mul_f32_e32 v117, v116, v116
	v_mul_f32_e32 v119, v118, v118
	v_mul_f32_e32 v153, v152, v152
	v_mul_f32_e32 v155, v154, v154
	v_mul_f32_e32 v195, v194, v194
	v_mul_f32_e32 v197, v196, v196
	v_pk_add_f32 v[112:113], v[112:113], v[114:115]
	v_pk_add_f32 v[114:115], v[116:117], v[118:119]
	v_pk_add_f32 v[116:117], v[194:195], v[196:197]
	v_pk_add_f32 v[112:113], v[112:113], v[114:115]
	v_pk_add_f32 v[114:115], v[152:153], v[154:155]
	s_nop 0
	v_pk_add_f32 v[114:115], v[114:115], v[116:117]
	s_nop 0
	v_pk_add_f32 v[112:113], v[112:113], v[114:115]
	v_mov_b32_e32 v114, v165
	v_mov_b32_e32 v115, v165
	s_nop 0
	v_mov_b32_dpp v114, v112 quad_perm:[1,0,3,2] row_mask:0xf bank_mask:0xf
	v_mov_b32_dpp v115, v113 quad_perm:[1,0,3,2] row_mask:0xf bank_mask:0xf
	v_pk_add_f32 v[112:113], v[112:113], v[114:115]
	ds_bpermute_b32 v114, v207, v112
	ds_bpermute_b32 v115, v207, v113
	s_waitcnt lgkmcnt(0)
	v_pk_add_f32 v[114:115], v[112:113], v[114:115]
	ds_bpermute_b32 v116, v208, v114
	ds_bpermute_b32 v117, v208, v115
	v_lshl_add_u64 v[112:113], s[20:21], 0, v[192:193]
	global_store_dwordx4 v[112:113], v[148:151], off
	s_and_saveexec_b64 s[64:65], s[16:17]
	s_waitcnt lgkmcnt(0)
	v_pk_add_f32 v[114:115], v[114:115], v[116:117]
	v_add_co_u32_e32 v116, vcc, 0x2000, v186
	s_nop 1
	v_addc_co_u32_e32 v117, vcc, 0, v187, vcc
	global_store_dwordx2 v[116:117], v[114:115], off

; __device__ __forceinline__ float dpp_x1(float x) { return __builtin_bit_cast(float, __builtin_amdgcn_update_dpp(0, __builtin_bit_cast(int, x), 0xB1, 0xF, 0xF, false)); }
; __device__ __forceinline__ f32x4 dpp_swap1(f32x4 v) { f32x4 r; r[0] = dpp_x1(v[0]); r[1] = dpp_x1(v[1]); r[2] = dpp_x1(v[2]); r[3] = dpp_x1(v[3]); return r; }
;     __device__ __forceinline__ void operator()(const f32x4 (&acc)[2][2][4][2], const Unit& u, int wr, int wc, int fr, int fq, const EpiCtx& X) const {
;     ...
;             for (int m = 0; m < 4; ++m) {
;                 const int rl = ai * HALF + m * 16; const unsigned off = lo + (unsigned)(rl * 64) * 2u;
;                 const f32x4 o0a = acc[ai][0][m][0], o0b = acc[ai][0][m][1], o1a = acc[ai][1][m][0], o1b = acc[ai][1][m][1];
;                 const f32x4 ra_ = dpp_swap1(odd ? o0a : o1a), rb_ = dpp_swap1(odd ? o0b : o1b);
;                 const f32x4 pa[2] = {odd ? ra_ : o0a, odd ? o1a : ra_}, pb[2] = {odd ? rb_ : o0b, odd ? o1b : rb_};
; #pragma unroll
;                 for (int q = 0; q < 2; ++q) {
;                     const u32x4 w0 = raw[2 * m + q];
;                     const f32x4 r0 = (f32x4){bf_lo(w0.x), bf_hi(w0.x), bf_lo(w0.y), bf_hi(w0.y)}, r1 = (f32x4){bf_lo(w0.z), bf_hi(w0.z), bf_lo(w0.w), bf_hi(w0.w)};
;                     f32x4 y0, y1;
;                     if (RESN) { const f32x2 t = tbl[rl + q]; const float mu = t.x, ra = t.y * ALPHA; y0 = (r0 - mu) * ra * g0 + b0 + pa[q]; y1 = (r1 - mu) * ra * g1 + b1 + pb[q]; }
;                     else { y0 = r0 * ALPHA + pa[q]; y1 = r1 * ALPHA + pb[q]; }
;                     { const u32x4 w = pack8f(y0, y1); *(u32x4*)(xb + off + q * 128) = w;
;                         y0 = (f32x4){bf_lo(w.x), bf_hi(w.x), bf_lo(w.y), bf_hi(w.y)}; y1 = (f32x4){bf_lo(w.z), bf_hi(w.z), bf_lo(w.w), bf_hi(w.w)}; }
;                     float sa = ((y0[0] + y0[1]) + (y0[2] + y0[3])) + ((y1[0] + y1[1]) + (y1[2] + y1[3]));
;                     float sb = ((y0[0] * y0[0] + y0[1] * y0[1]) + (y0[2] * y0[2] + y0[3] * y0[3])) + ((y1[0] * y1[0] + y1[1] * y1[1]) + (y1[2] * y1[2] + y1[3] * y1[3]));
;                     sa += dpp_x1(sa);
;                     sb += dpp_x1(sb);
;                     sa += __shfl_xor(sa, 16); sa += __shfl_xor(sa, 32); sb += __shfl_xor(sb, 16); sb += __shfl_xor(sb, 32);
;                     if (fq == 0 && !odd) ps[(size_t)(rl + q) * 64] = (f32x2){sa, sb};
.LBB0_1471:
	s_or_b64 exec, exec, s[64:65]
	s_waitcnt lgkmcnt(1)
	v_cndmask_b32_e64 v106, v100, v92, s[10:11]
	s_nop 0
	v_cndmask_b32_e64 v105, v101, v93, s[10:11]
	s_waitcnt lgkmcnt(0)
	v_cndmask_b32_e64 v107, v102, v94, s[10:11]
	v_mov_b32_dpp v104, v106 quad_perm:[1,0,3,2] row_mask:0xf bank_mask:0xf
	s_nop 0
	v_cndmask_b32_e64 v108, v103, v95, s[10:11]
	v_cndmask_b32_e64 v110, v96, v88, s[10:11]
	v_mov_b32_dpp v106, v105 quad_perm:[1,0,3,2] row_mask:0xf bank_mask:0xf
	s_nop 0
	v_cndmask_b32_e64 v109, v97, v89, s[10:11]
	v_cndmask_b32_e64 v111, v98, v90, s[10:11]
	v_mov_b32_dpp v105, v107 quad_perm:[1,0,3,2] row_mask:0xf bank_mask:0xf
	s_nop 0
	v_cndmask_b32_e64 v112, v99, v91, s[10:11]
	s_waitcnt vmcnt(15)
	v_lshlrev_b32_e32 v115, 16, v140
	v_mov_b32_dpp v107, v108 quad_perm:[1,0,3,2] row_mask:0xf bank_mask:0xf
	s_nop 0
	v_and_b32_e32 v116, 0xffff0000, v140
	v_cndmask_b32_e64 v101, v106, v101, s[10:11]
	v_mov_b32_dpp v108, v110 quad_perm:[1,0,3,2] row_mask:0xf bank_mask:0xf
	s_nop 0
	v_cndmask_b32_e64 v100, v104, v100, s[10:11]
	v_lshlrev_b32_e32 v118, 16, v141
	v_mov_b32_dpp v110, v109 quad_perm:[1,0,3,2] row_mask:0xf bank_mask:0xf
	s_nop 0
	v_and_b32_e32 v119, 0xffff0000, v141
	v_lshlrev_b32_e32 v120, 16, v142
	v_mov_b32_dpp v109, v111 quad_perm:[1,0,3,2] row_mask:0xf bank_mask:0xf
	s_nop 0
	v_and_b32_e32 v121, 0xffff0000, v142
	v_lshlrev_b32_e32 v122, 16, v143
	v_mov_b32_dpp v111, v112 quad_perm:[1,0,3,2] row_mask:0xf bank_mask:0xf
	ds_read_b64 v[112:113], v201 offset:256
	v_and_b32_e32 v123, 0xffff0000, v143
	v_cndmask_b32_e64 v103, v107, v103, s[10:11]
	v_cndmask_b32_e64 v102, v105, v102, s[10:11]
	v_cndmask_b32_e64 v97, v110, v97, s[10:11]
	s_waitcnt lgkmcnt(0)
	v_mul_f32_e32 v114, 0x3fb504f3, v113
	v_sub_f32_e32 v117, v116, v112
	v_sub_f32_e32 v116, v115, v112
	v_pk_mul_f32 v[116:117], v[116:117], v[114:115] op_sel_hi:[1,0]
	v_sub_f32_e32 v119, v119, v112
	v_pk_fma_f32 v[116:117], v[76:77], v[116:117], v[184:185]
	v_sub_f32_e32 v118, v118, v112
	v_pk_add_f32 v[100:101], v[100:101], v[116:117]
	v_sub_f32_e32 v117, v121, v112
	v_sub_f32_e32 v116, v120, v112
	v_sub_f32_e32 v113, v123, v112
	v_sub_f32_e32 v112, v122, v112
	v_pk_mul_f32 v[118:119], v[118:119], v[114:115] op_sel_hi:[1,0]
	v_pk_mul_f32 v[112:113], v[112:113], v[114:115] op_sel_hi:[1,0]
	v_pk_mul_f32 v[114:115], v[116:117], v[114:115] op_sel_hi:[1,0]
	v_cndmask_b32_e64 v96, v108, v96, s[10:11]
	v_cndmask_b32_e64 v99, v111, v99, s[10:11]
	v_cndmask_b32_e64 v98, v109, v98, s[10:11]
	v_pk_fma_f32 v[118:119], v[78:79], v[118:119], v[182:183]
	v_pk_fma_f32 v[114:115], v[72:73], v[114:115], v[180:181]
	v_pk_fma_f32 v[112:113], v[74:75], v[112:113], v[178:179]
	v_pk_add_f32 v[102:103], v[102:103], v[118:119]
	v_pk_add_f32 v[98:99], v[98:99], v[112:113]
	v_pk_add_f32 v[96:97], v[96:97], v[114:115]
	v_cvt_pk_bf16_f32 v112, v100, v101
	v_cvt_pk_bf16_f32 v113, v102, v103
	v_mov_b32_e32 v191, v165
	v_cvt_pk_bf16_f32 v114, v96, v97
	v_cvt_pk_bf16_f32 v115, v98, v99
	v_lshlrev_b32_e32 v96, 16, v112
	v_and_b32_e32 v98, 0xffff0000, v112
	v_lshlrev_b32_e32 v100, 16, v113
	v_and_b32_e32 v102, 0xffff0000, v113
	v_lshlrev_b32_e32 v116, 16, v114
	v_and_b32_e32 v118, 0xffff0000, v114
	v_lshlrev_b32_e32 v120, 16, v115
	v_and_b32_e32 v122, 0xffff0000, v115
	v_mul_f32_e32 v97, v96, v96
	v_mul_f32_e32 v99, v98, v98
	v_mul_f32_e32 v101, v100, v100
	v_mul_f32_e32 v103, v102, v102
	v_mul_f32_e32 v117, v116, v116
	v_mul_f32_e32 v119, v118, v118
	v_mul_f32_e32 v121, v120, v120
	v_mul_f32_e32 v123, v122, v122
	v_pk_add_f32 v[96:97], v[96:97], v[98:99]
	v_pk_add_f32 v[98:99], v[100:101], v[102:103]
	v_pk_add_f32 v[100:101], v[120:121], v[122:123]
	v_pk_add_f32 v[96:97], v[96:97], v[98:99]
	v_pk_add_f32 v[98:99], v[116:117], v[118:119]
	s_nop 0
	v_pk_add_f32 v[98:99], v[98:99], v[100:101]
	s_nop 0
	v_pk_add_f32 v[96:97], v[96:97], v[98:99]
	v_mov_b32_e32 v98, v165
	v_mov_b32_e32 v99, v165
	s_nop 0
	v_mov_b32_dpp v98, v96 quad_perm:[1,0,3,2] row_mask:0xf bank_mask:0xf
	v_mov_b32_dpp v99, v97 quad_perm:[1,0,3,2] row_mask:0xf bank_mask:0xf
	v_pk_add_f32 v[96:97], v[96:97], v[98:99]
	ds_bpermute_b32 v98, v207, v96
	ds_bpermute_b32 v99, v207, v97
	s_waitcnt lgkmcnt(0)
	v_pk_add_f32 v[98:99], v[96:97], v[98:99]
	ds_bpermute_b32 v100, v208, v98
	ds_bpermute_b32 v101, v208, v99
	v_lshl_add_u64 v[96:97], s[20:21], 0, v[190:191]
	global_store_dwordx4 v[96:97], v[112:115], off
	s_and_saveexec_b64 s[64:65], s[16:17]
	s_waitcnt lgkmcnt(0)
	v_pk_add_f32 v[98:99], v[98:99], v[100:101]
	v_add_co_u32_e32 v100, vcc, 0x4000, v186
	s_nop 1
	v_addc_co_u32_e32 v101, vcc, 0, v187, vcc
	global_store_dwordx2 v[100:101], v[98:99], off

; __device__ __forceinline__ float dpp_x1(float x) { return __builtin_bit_cast(float, __builtin_amdgcn_update_dpp(0, __builtin_bit_cast(int, x), 0xB1, 0xF, 0xF, false)); }
; __device__ __forceinline__ f32x4 dpp_swap1(f32x4 v) { f32x4 r; r[0] = dpp_x1(v[0]); r[1] = dpp_x1(v[1]); r[2] = dpp_x1(v[2]); r[3] = dpp_x1(v[3]); return r; }
;     __device__ __forceinline__ void operator()(const f32x4 (&acc)[2][2][4][2], const Unit& u, int wr, int wc, int fr, int fq, const EpiCtx& X) const {
;     ...
;             for (int m = 0; m < 4; ++m) {
;                 const int rl = ai * HALF + m * 16; const unsigned off = lo + (unsigned)(rl * 64) * 2u;
;                 const f32x4 o0a = acc[ai][0][m][0], o0b = acc[ai][0][m][1], o1a = acc[ai][1][m][0], o1b = acc[ai][1][m][1];
;                 const f32x4 ra_ = dpp_swap1(odd ? o0a : o1a), rb_ = dpp_swap1(odd ? o0b : o1b);
;                 const f32x4 pa[2] = {odd ? ra_ : o0a, odd ? o1a : ra_}, pb[2] = {odd ? rb_ : o0b, odd ? o1b : rb_};
; #pragma unroll
;                 for (int q = 0; q < 2; ++q) {
;                     const u32x4 w0 = raw[2 * m + q];
;                     const f32x4 r0 = (f32x4){bf_lo(w0.x), bf_hi(w0.x), bf_lo(w0.y), bf_hi(w0.y)}, r1 = (f32x4){bf_lo(w0.z), bf_hi(w0.z), bf_lo(w0.w), bf_hi(w0.w)};
;                     f32x4 y0, y1;
;                     if (RESN) { const f32x2 t = tbl[rl + q]; const float mu = t.x, ra = t.y * ALPHA; y0 = (r0 - mu) * ra * g0 + b0 + pa[q]; y1 = (r1 - mu) * ra * g1 + b1 + pb[q]; }
;                     else { y0 = r0 * ALPHA + pa[q]; y1 = r1 * ALPHA + pb[q]; }
;                     { const u32x4 w = pack8f(y0, y1); *(u32x4*)(xb + off + q * 128) = w;
;                         y0 = (f32x4){bf_lo(w.x), bf_hi(w.x), bf_lo(w.y), bf_hi(w.y)}; y1 = (f32x4){bf_lo(w.z), bf_hi(w.z), bf_lo(w.w), bf_hi(w.w)}; }
;                     float sa = ((y0[0] + y0[1]) + (y0[2] + y0[3])) + ((y1[0] + y1[1]) + (y1[2] + y1[3]));
;                     float sb = ((y0[0] * y0[0] + y0[1] * y0[1]) + (y0[2] * y0[2] + y0[3] * y0[3])) + ((y1[0] * y1[0] + y1[1] * y1[1]) + (y1[2] * y1[2] + y1[3] * y1[3]));
;                     sa += dpp_x1(sa);
;                     sb += dpp_x1(sb);
;                     sa += __shfl_xor(sa, 16); sa += __shfl_xor(sa, 32); sb += __shfl_xor(sb, 16); sb += __shfl_xor(sb, 32);
;                     if (fq == 0 && !odd) ps[(size_t)(rl + q) * 64] = (f32x2){sa, sb};
.LBB0_1475:
	s_or_b64 exec, exec, s[64:65]
	s_waitcnt lgkmcnt(1)
	v_cndmask_b32_e64 v90, v84, v68, s[10:11]
	s_nop 0
	v_cndmask_b32_e64 v89, v85, v69, s[10:11]
	s_waitcnt lgkmcnt(0)
	v_cndmask_b32_e64 v91, v86, v70, s[10:11]
	v_mov_b32_dpp v88, v90 quad_perm:[1,0,3,2] row_mask:0xf bank_mask:0xf
	s_nop 0
	v_cndmask_b32_e64 v92, v87, v71, s[10:11]
	v_cndmask_b32_e64 v94, v80, v64, s[10:11]
	v_mov_b32_dpp v90, v89 quad_perm:[1,0,3,2] row_mask:0xf bank_mask:0xf
	s_nop 0
	v_cndmask_b32_e64 v93, v81, v65, s[10:11]
	v_cndmask_b32_e64 v95, v82, v66, s[10:11]
	v_mov_b32_dpp v89, v91 quad_perm:[1,0,3,2] row_mask:0xf bank_mask:0xf
	s_nop 0
	v_cndmask_b32_e64 v96, v83, v67, s[10:11]
	s_waitcnt vmcnt(17)
	v_lshlrev_b32_e32 v99, 16, v132
	v_mov_b32_dpp v91, v92 quad_perm:[1,0,3,2] row_mask:0xf bank_mask:0xf
	s_nop 0
	v_and_b32_e32 v100, 0xffff0000, v132
	v_cndmask_b32_e64 v85, v90, v85, s[10:11]
	v_mov_b32_dpp v92, v94 quad_perm:[1,0,3,2] row_mask:0xf bank_mask:0xf
	s_nop 0
	v_cndmask_b32_e64 v84, v88, v84, s[10:11]
	v_lshlrev_b32_e32 v102, 16, v133
	v_mov_b32_dpp v94, v93 quad_perm:[1,0,3,2] row_mask:0xf bank_mask:0xf
	s_nop 0
	v_and_b32_e32 v103, 0xffff0000, v133
	v_lshlrev_b32_e32 v104, 16, v134
	v_mov_b32_dpp v93, v95 quad_perm:[1,0,3,2] row_mask:0xf bank_mask:0xf
	s_nop 0
	v_and_b32_e32 v105, 0xffff0000, v134
	v_lshlrev_b32_e32 v106, 16, v135
	v_mov_b32_dpp v95, v96 quad_perm:[1,0,3,2] row_mask:0xf bank_mask:0xf
	ds_read_b64 v[96:97], v201 offset:384
	v_and_b32_e32 v107, 0xffff0000, v135
	v_cndmask_b32_e64 v87, v91, v87, s[10:11]
	v_cndmask_b32_e64 v86, v89, v86, s[10:11]
	v_cndmask_b32_e64 v81, v94, v81, s[10:11]
	s_waitcnt lgkmcnt(0)
	v_mul_f32_e32 v98, 0x3fb504f3, v97
	v_sub_f32_e32 v101, v100, v96
	v_sub_f32_e32 v100, v99, v96
	v_pk_mul_f32 v[100:101], v[100:101], v[98:99] op_sel_hi:[1,0]
	v_sub_f32_e32 v103, v103, v96
	v_pk_fma_f32 v[100:101], v[76:77], v[100:101], v[184:185]
	v_sub_f32_e32 v102, v102, v96
	v_pk_add_f32 v[84:85], v[84:85], v[100:101]
	v_sub_f32_e32 v101, v105, v96
	v_sub_f32_e32 v100, v104, v96
	v_sub_f32_e32 v97, v107, v96
	v_sub_f32_e32 v96, v106, v96
	v_pk_mul_f32 v[102:103], v[102:103], v[98:99] op_sel_hi:[1,0]
	v_pk_mul_f32 v[96:97], v[96:97], v[98:99] op_sel_hi:[1,0]
	v_pk_mul_f32 v[98:99], v[100:101], v[98:99] op_sel_hi:[1,0]
	v_cndmask_b32_e64 v80, v92, v80, s[10:11]
	v_cndmask_b32_e64 v83, v95, v83, s[10:11]
	v_cndmask_b32_e64 v82, v93, v82, s[10:11]
	v_pk_fma_f32 v[102:103], v[78:79], v[102:103], v[182:183]
	v_pk_fma_f32 v[98:99], v[72:73], v[98:99], v[180:181]
	v_pk_fma_f32 v[96:97], v[74:75], v[96:97], v[178:179]
	v_pk_add_f32 v[86:87], v[86:87], v[102:103]
	v_pk_add_f32 v[82:83], v[82:83], v[96:97]
	v_pk_add_f32 v[80:81], v[80:81], v[98:99]
	v_cvt_pk_bf16_f32 v96, v84, v85
	v_cvt_pk_bf16_f32 v97, v86, v87
	v_mov_b32_e32 v189, v165
	v_cvt_pk_bf16_f32 v98, v80, v81
	v_cvt_pk_bf16_f32 v99, v82, v83
	v_lshlrev_b32_e32 v80, 16, v96
	v_and_b32_e32 v82, 0xffff0000, v96
	v_lshlrev_b32_e32 v84, 16, v97
	v_and_b32_e32 v86, 0xffff0000, v97
	v_lshlrev_b32_e32 v100, 16, v98
	v_and_b32_e32 v102, 0xffff0000, v98
	v_lshlrev_b32_e32 v104, 16, v99
	v_and_b32_e32 v106, 0xffff0000, v99
	v_mul_f32_e32 v81, v80, v80
	v_mul_f32_e32 v83, v82, v82
	v_mul_f32_e32 v85, v84, v84
	v_mul_f32_e32 v87, v86, v86
	v_mul_f32_e32 v101, v100, v100
	v_mul_f32_e32 v103, v102, v102
	v_mul_f32_e32 v105, v104, v104
	v_mul_f32_e32 v107, v106, v106
	v_pk_add_f32 v[80:81], v[80:81], v[82:83]
	v_pk_add_f32 v[82:83], v[84:85], v[86:87]
	v_pk_add_f32 v[84:85], v[104:105], v[106:107]
	v_pk_add_f32 v[80:81], v[80:81], v[82:83]
	v_pk_add_f32 v[82:83], v[100:101], v[102:103]
	s_nop 0
	v_pk_add_f32 v[82:83], v[82:83], v[84:85]
	s_nop 0
	v_pk_add_f32 v[80:81], v[80:81], v[82:83]
	v_mov_b32_e32 v82, v165
	v_mov_b32_e32 v83, v165
	s_nop 0
	v_mov_b32_dpp v82, v80 quad_perm:[1,0,3,2] row_mask:0xf bank_mask:0xf
	v_mov_b32_dpp v83, v81 quad_perm:[1,0,3,2] row_mask:0xf bank_mask:0xf
	v_pk_add_f32 v[80:81], v[80:81], v[82:83]
	ds_bpermute_b32 v82, v207, v80
	ds_bpermute_b32 v83, v207, v81
	s_waitcnt lgkmcnt(0)
	v_pk_add_f32 v[82:83], v[80:81], v[82:83]
	ds_bpermute_b32 v84, v208, v82
	ds_bpermute_b32 v85, v208, v83
	v_lshl_add_u64 v[80:81], s[20:21], 0, v[188:189]
	global_store_dwordx4 v[80:81], v[96:99], off
	s_and_saveexec_b64 s[64:65], s[16:17]
	s_waitcnt lgkmcnt(0)
	v_pk_add_f32 v[82:83], v[82:83], v[84:85]
	v_add_co_u32_e32 v84, vcc, 0x6000, v186
	s_nop 1
	v_addc_co_u32_e32 v85, vcc, 0, v187, vcc
	global_store_dwordx2 v[84:85], v[82:83], off

;     __device__ __forceinline__ void operator()(const f32x4 (&acc)[2][2][4][2], const Unit& u, int wr, int wc, int fr, int fq, const EpiCtx& X) const {
;     ...
;             for (int m = 0; m < 4; ++m) { const unsigned off = lo + (unsigned)((ai * HALF + m * 16) * 64) * 2u; raw[2 * m] = *(const u32x4*)(xb + off); raw[2 * m + 1] = *(const u32x4*)(xb + off + 128); }
; #pragma unroll
;             for (int m = 0; m < 4; ++m) {
;                 const int rl = ai * HALF + m * 16; const unsigned off = lo + (unsigned)(rl * 64) * 2u;
;                 const f32x4 o0a = acc[ai][0][m][0], o0b = acc[ai][0][m][1], o1a = acc[ai][1][m][0], o1b = acc[ai][1][m][1];
;                 const f32x4 ra_ = dpp_swap1(odd ? o0a : o1a), rb_ = dpp_swap1(odd ? o0b : o1b);
;                 const f32x4 pa[2] = {odd ? ra_ : o0a, odd ? o1a : ra_}, pb[2] = {odd ? rb_ : o0b, odd ? o1b : rb_};
; #pragma unroll
;                 for (int q = 0; q < 2; ++q) {
;                     const u32x4 w0 = raw[2 * m + q];
;                     const f32x4 r0 = (f32x4){bf_lo(w0.x), bf_hi(w0.x), bf_lo(w0.y), bf_hi(w0.y)}, r1 = (f32x4){bf_lo(w0.z), bf_hi(w0.z), bf_lo(w0.w), bf_hi(w0.w)};
;                     f32x4 y0, y1;
;                     if (RESN) { const f32x2 t = tbl[rl + q]; const float mu = t.x, ra = t.y * ALPHA; y0 = (r0 - mu) * ra * g0 + b0 + pa[q]; y1 = (r1 - mu) * ra * g1 + b1 + pb[q]; }
;                     else { y0 = r0 * ALPHA + pa[q]; y1 = r1 * ALPHA + pb[q]; }
;                     { const u32x4 w = pack8f(y0, y1); *(u32x4*)(xb + off + q * 128) = w;
;                         y0 = (f32x4){bf_lo(w.x), bf_hi(w.x), bf_lo(w.y), bf_hi(w.y)}; y1 = (f32x4){bf_lo(w.z), bf_hi(w.z), bf_lo(w.w), bf_hi(w.w)}; }
;                     float sa = ((y0[0] + y0[1]) + (y0[2] + y0[3])) + ((y1[0] + y1[1]) + (y1[2] + y1[3]));
;                     float sb = ((y0[0] * y0[0] + y0[1] * y0[1]) + (y0[2] * y0[2] + y0[3] * y0[3])) + ((y1[0] * y1[0] + y1[1] * y1[1]) + (y1[2] * y1[2] + y1[3] * y1[3]));
;                     sa += dpp_x1(sa);
;                     sb += dpp_x1(sb);
;                     sa += __shfl_xor(sa, 16); sa += __shfl_xor(sa, 32); sb += __shfl_xor(sb, 16); sb += __shfl_xor(sb, 32);
;                     if (fq == 0 && !odd) ps[(size_t)(rl + q) * 64] = (f32x2){sa, sb};
.LBB0_1479:
	s_or_b64 exec, exec, s[64:65]
	v_add_u32_e32 v104, 0x4000, v164
	s_waitcnt vmcnt(16)
	v_mov_b32_e32 v112, v230
	v_mov_b32_e32 v113, v231
	v_mov_b32_e32 v114, v232
	v_mov_b32_e32 v115, v233
	v_add_u32_e32 v102, 0x4800, v164
	v_add_u32_e32 v100, 0x5000, v164
	v_add_u32_e32 v164, 0x5800, v164
	v_mov_b32_e32 v96, v234
	v_mov_b32_e32 v97, v235
	v_mov_b32_e32 v98, v236
	v_mov_b32_e32 v99, v237
	v_mov_b32_e32 v92, v238
	v_mov_b32_e32 v93, v239
	v_mov_b32_e32 v94, v240
	v_mov_b32_e32 v95, v241
	v_mov_b32_e32 v88, v242
	v_mov_b32_e32 v89, v243
	v_mov_b32_e32 v90, v244
	v_mov_b32_e32 v91, v245
	global_load_dwordx4 v[84:87], v100, s[20:21]
	global_load_dwordx4 v[80:83], v100, s[20:21] offset:128
	global_load_dwordx4 v[68:71], v164, s[20:21]
	s_waitcnt lgkmcnt(0)
	global_load_dwordx4 v[64:67], v164, s[20:21] offset:128
	v_cndmask_b32_e64 v116, v62, v54, s[10:11]
	v_cndmask_b32_e64 v117, v61, v53, s[10:11]
	s_nop 0
	s_nop 0
	v_cndmask_b32_e64 v111, v63, v55, s[10:11]
	v_mov_b32_dpp v105, v117 quad_perm:[1,0,3,2] row_mask:0xf bank_mask:0xf
	v_mov_b32_dpp v103, v116 quad_perm:[1,0,3,2] row_mask:0xf bank_mask:0xf
	ds_read_b64 v[116:117], v201 offset:1024
	v_cndmask_b32_e64 v118, v60, v52, s[10:11]
	s_nop 0
	s_nop 0
	v_cndmask_b32_e64 v119, v59, v51, s[10:11]
	v_cndmask_b32_e64 v120, v58, v50, s[10:11]
	v_cndmask_b32_e64 v121, v57, v49, s[10:11]
	v_cndmask_b32_e64 v122, v56, v48, s[10:11]
	s_nop 0
	s_nop 0
	s_nop 0
	s_nop 0
	v_mov_b32_dpp v101, v118 quad_perm:[1,0,3,2] row_mask:0xf bank_mask:0xf
	v_mov_b32_dpp v106, v111 quad_perm:[1,0,3,2] row_mask:0xf bank_mask:0xf
	v_mov_b32_dpp v107, v122 quad_perm:[1,0,3,2] row_mask:0xf bank_mask:0xf
	v_mov_b32_dpp v109, v121 quad_perm:[1,0,3,2] row_mask:0xf bank_mask:0xf
	v_mov_b32_dpp v108, v120 quad_perm:[1,0,3,2] row_mask:0xf bank_mask:0xf
	v_mov_b32_dpp v110, v119 quad_perm:[1,0,3,2] row_mask:0xf bank_mask:0xf
	s_waitcnt lgkmcnt(0)
	v_mul_f32_e32 v118, 0x3fb504f3, v117
	v_cndmask_b32_e64 v61, v105, v61, s[10:11]
	v_cndmask_b32_e64 v60, v101, v60, s[10:11]
	v_cndmask_b32_e64 v63, v106, v63, s[10:11]
	v_cndmask_b32_e64 v62, v103, v62, s[10:11]
	v_cndmask_b32_e64 v57, v109, v57, s[10:11]
	v_cndmask_b32_e64 v56, v107, v56, s[10:11]
	v_cndmask_b32_e64 v59, v110, v59, s[10:11]
	v_cndmask_b32_e64 v58, v108, v58, s[10:11]
	v_lshlrev_b32_e32 v111, 16, v112
	v_and_b32_e32 v112, 0xffff0000, v112
	v_lshlrev_b32_e32 v117, 16, v113
	v_and_b32_e32 v119, 0xffff0000, v113
	v_lshlrev_b32_e32 v120, 16, v114
	v_and_b32_e32 v121, 0xffff0000, v114
	v_lshlrev_b32_e32 v122, 16, v115
	v_and_b32_e32 v123, 0xffff0000, v115
	v_sub_f32_e32 v113, v112, v116
	v_sub_f32_e32 v112, v111, v116
	v_sub_f32_e32 v115, v119, v116
	v_sub_f32_e32 v114, v117, v116
	v_sub_f32_e32 v121, v121, v116
	v_sub_f32_e32 v120, v120, v116
	v_sub_f32_e32 v117, v123, v116
	v_sub_f32_e32 v116, v122, v116
	v_pk_mul_f32 v[114:115], v[114:115], v[118:119] op_sel_hi:[1,0]
	v_pk_mul_f32 v[112:113], v[112:113], v[118:119] op_sel_hi:[1,0]
	v_pk_mul_f32 v[116:117], v[116:117], v[118:119] op_sel_hi:[1,0]
	v_pk_mul_f32 v[118:119], v[120:121], v[118:119] op_sel_hi:[1,0]
	v_pk_fma_f32 v[112:113], v[76:77], v[112:113], v[184:185]
	v_pk_fma_f32 v[114:115], v[78:79], v[114:115], v[182:183]
	v_pk_fma_f32 v[118:119], v[72:73], v[118:119], v[180:181]
	v_pk_fma_f32 v[116:117], v[74:75], v[116:117], v[178:179]
	v_pk_add_f32 v[62:63], v[62:63], v[114:115]
	v_pk_add_f32 v[60:61], v[60:61], v[112:113]
	v_pk_add_f32 v[58:59], v[58:59], v[116:117]
	v_pk_add_f32 v[56:57], v[56:57], v[118:119]
	v_cvt_pk_bf16_f32 v60, v60, v61
	v_cvt_pk_bf16_f32 v61, v62, v63
	s_nop 0
	v_cvt_pk_bf16_f32 v62, v56, v57
	v_cvt_pk_bf16_f32 v63, v58, v59
	v_lshlrev_b32_e32 v56, 16, v60
	v_and_b32_e32 v58, 0xffff0000, v60
	v_lshlrev_b32_e32 v112, 16, v61
	v_and_b32_e32 v114, 0xffff0000, v61
	v_lshlrev_b32_e32 v116, 16, v62
	v_and_b32_e32 v118, 0xffff0000, v62
	v_lshlrev_b32_e32 v120, 16, v63
	v_and_b32_e32 v122, 0xffff0000, v63
	v_mul_f32_e32 v57, v56, v56
	v_mul_f32_e32 v59, v58, v58
	v_mul_f32_e32 v113, v112, v112
	v_mul_f32_e32 v115, v114, v114
	v_mul_f32_e32 v117, v116, v116
	v_mul_f32_e32 v119, v118, v118
	v_mul_f32_e32 v121, v120, v120
	v_mul_f32_e32 v123, v122, v122
	v_pk_add_f32 v[56:57], v[56:57], v[58:59]
	v_pk_add_f32 v[58:59], v[112:113], v[114:115]
	v_pk_add_f32 v[112:113], v[120:121], v[122:123]
	v_pk_add_f32 v[56:57], v[56:57], v[58:59]
	v_pk_add_f32 v[58:59], v[116:117], v[118:119]
	global_store_dwordx4 v104, v[60:63], s[20:21]
	v_pk_add_f32 v[58:59], v[58:59], v[112:113]
	s_nop 0
	v_pk_add_f32 v[56:57], v[56:57], v[58:59]
	v_mov_b32_e32 v58, v165
	v_mov_b32_e32 v59, v165
	s_nop 0
	v_mov_b32_dpp v58, v56 quad_perm:[1,0,3,2] row_mask:0xf bank_mask:0xf
	v_mov_b32_dpp v59, v57 quad_perm:[1,0,3,2] row_mask:0xf bank_mask:0xf
	v_pk_add_f32 v[56:57], v[56:57], v[58:59]
	ds_bpermute_b32 v58, v207, v56
	ds_bpermute_b32 v59, v207, v57
	s_waitcnt lgkmcnt(0)
	v_pk_add_f32 v[56:57], v[56:57], v[58:59]
	ds_bpermute_b32 v58, v208, v56
	ds_bpermute_b32 v59, v208, v57
	s_and_saveexec_b64 s[64:65], s[16:17]
	s_cbranch_execz .LBB0_1481
	s_waitcnt lgkmcnt(0)
	v_pk_add_f32 v[56:57], v[56:57], v[58:59]
	v_add_co_u32_e32 v58, vcc, 0x10000, v186
	s_nop 1
	v_addc_co_u32_e32 v59, vcc, 0, v187, vcc
	global_store_dwordx2 v[58:59], v[56:57], off

; __device__ __forceinline__ float dpp_x1(float x) { return __builtin_bit_cast(float, __builtin_amdgcn_update_dpp(0, __builtin_bit_cast(int, x), 0xB1, 0xF, 0xF, false)); }
; __device__ __forceinline__ f32x4 dpp_swap1(f32x4 v) { f32x4 r; r[0] = dpp_x1(v[0]); r[1] = dpp_x1(v[1]); r[2] = dpp_x1(v[2]); r[3] = dpp_x1(v[3]); return r; }
;     __device__ __forceinline__ void operator()(const f32x4 (&acc)[2][2][4][2], const Unit& u, int wr, int wc, int fr, int fq, const EpiCtx& X) const {
;     ...
;             for (int m = 0; m < 4; ++m) {
;                 const int rl = ai * HALF + m * 16; const unsigned off = lo + (unsigned)(rl * 64) * 2u;
;                 const f32x4 o0a = acc[ai][0][m][0], o0b = acc[ai][0][m][1], o1a = acc[ai][1][m][0], o1b = acc[ai][1][m][1];
;                 const f32x4 ra_ = dpp_swap1(odd ? o0a : o1a), rb_ = dpp_swap1(odd ? o0b : o1b);
;                 const f32x4 pa[2] = {odd ? ra_ : o0a, odd ? o1a : ra_}, pb[2] = {odd ? rb_ : o0b, odd ? o1b : rb_};
; #pragma unroll
;                 for (int q = 0; q < 2; ++q) {
;                     const u32x4 w0 = raw[2 * m + q];
;                     const f32x4 r0 = (f32x4){bf_lo(w0.x), bf_hi(w0.x), bf_lo(w0.y), bf_hi(w0.y)}, r1 = (f32x4){bf_lo(w0.z), bf_hi(w0.z), bf_lo(w0.w), bf_hi(w0.w)};
;                     f32x4 y0, y1;
;                     if (RESN) { const f32x2 t = tbl[rl + q]; const float mu = t.x, ra = t.y * ALPHA; y0 = (r0 - mu) * ra * g0 + b0 + pa[q]; y1 = (r1 - mu) * ra * g1 + b1 + pb[q]; }
;                     else { y0 = r0 * ALPHA + pa[q]; y1 = r1 * ALPHA + pb[q]; }
;                     { const u32x4 w = pack8f(y0, y1); *(u32x4*)(xb + off + q * 128) = w;
;                         y0 = (f32x4){bf_lo(w.x), bf_hi(w.x), bf_lo(w.y), bf_hi(w.y)}; y1 = (f32x4){bf_lo(w.z), bf_hi(w.z), bf_lo(w.w), bf_hi(w.w)}; }
;                     float sa = ((y0[0] + y0[1]) + (y0[2] + y0[3])) + ((y1[0] + y1[1]) + (y1[2] + y1[3]));
;                     float sb = ((y0[0] * y0[0] + y0[1] * y0[1]) + (y0[2] * y0[2] + y0[3] * y0[3])) + ((y1[0] * y1[0] + y1[1] * y1[1]) + (y1[2] * y1[2] + y1[3] * y1[3]));
;                     sa += dpp_x1(sa);
;                     sb += dpp_x1(sb);
;                     sa += __shfl_xor(sa, 16); sa += __shfl_xor(sa, 32); sb += __shfl_xor(sb, 16); sb += __shfl_xor(sb, 32);
;                     if (fq == 0 && !odd) ps[(size_t)(rl + q) * 64] = (f32x2){sa, sb};
.LBB0_1483:
	s_or_b64 exec, exec, s[64:65]
	s_waitcnt lgkmcnt(1)
	v_cndmask_b32_e64 v50, v44, v36, s[10:11]
	s_nop 0
	v_cndmask_b32_e64 v49, v45, v37, s[10:11]
	s_waitcnt lgkmcnt(0)
	v_cndmask_b32_e64 v51, v46, v38, s[10:11]
	v_mov_b32_dpp v48, v50 quad_perm:[1,0,3,2] row_mask:0xf bank_mask:0xf
	s_nop 0
	v_cndmask_b32_e64 v52, v47, v39, s[10:11]
	v_cndmask_b32_e64 v54, v40, v32, s[10:11]
	v_mov_b32_dpp v50, v49 quad_perm:[1,0,3,2] row_mask:0xf bank_mask:0xf
	s_nop 0
	v_cndmask_b32_e64 v53, v41, v33, s[10:11]
	v_cndmask_b32_e64 v55, v42, v34, s[10:11]
	v_mov_b32_dpp v49, v51 quad_perm:[1,0,3,2] row_mask:0xf bank_mask:0xf
	s_nop 0
	v_cndmask_b32_e64 v56, v43, v35, s[10:11]
	v_lshlrev_b32_e32 v59, 16, v92
	v_mov_b32_dpp v51, v52 quad_perm:[1,0,3,2] row_mask:0xf bank_mask:0xf
	s_nop 0
	v_and_b32_e32 v60, 0xffff0000, v92
	v_cndmask_b32_e64 v45, v50, v45, s[10:11]
	v_mov_b32_dpp v52, v54 quad_perm:[1,0,3,2] row_mask:0xf bank_mask:0xf
	s_nop 0
	v_cndmask_b32_e64 v44, v48, v44, s[10:11]
	v_lshlrev_b32_e32 v62, 16, v93
	v_mov_b32_dpp v54, v53 quad_perm:[1,0,3,2] row_mask:0xf bank_mask:0xf
	s_nop 0
	v_and_b32_e32 v63, 0xffff0000, v93
	v_lshlrev_b32_e32 v92, 16, v94
	v_mov_b32_dpp v53, v55 quad_perm:[1,0,3,2] row_mask:0xf bank_mask:0xf
	s_nop 0
	v_and_b32_e32 v93, 0xffff0000, v94
	v_lshlrev_b32_e32 v94, 16, v95
	v_mov_b32_dpp v55, v56 quad_perm:[1,0,3,2] row_mask:0xf bank_mask:0xf
	ds_read_b64 v[56:57], v201 offset:1152
	v_and_b32_e32 v95, 0xffff0000, v95
	v_cndmask_b32_e64 v47, v51, v47, s[10:11]
	v_cndmask_b32_e64 v46, v49, v46, s[10:11]
	v_cndmask_b32_e64 v41, v54, v41, s[10:11]
	s_waitcnt lgkmcnt(0)
	v_mul_f32_e32 v58, 0x3fb504f3, v57
	v_sub_f32_e32 v61, v60, v56
	v_sub_f32_e32 v60, v59, v56
	v_pk_mul_f32 v[60:61], v[60:61], v[58:59] op_sel_hi:[1,0]
	v_sub_f32_e32 v63, v63, v56
	v_pk_fma_f32 v[60:61], v[76:77], v[60:61], v[184:185]
	v_sub_f32_e32 v62, v62, v56
	v_pk_add_f32 v[44:45], v[44:45], v[60:61]
	v_sub_f32_e32 v61, v93, v56
	v_sub_f32_e32 v60, v92, v56
	v_sub_f32_e32 v57, v95, v56
	v_sub_f32_e32 v56, v94, v56
	v_pk_mul_f32 v[62:63], v[62:63], v[58:59] op_sel_hi:[1,0]
	v_pk_mul_f32 v[56:57], v[56:57], v[58:59] op_sel_hi:[1,0]
	v_pk_mul_f32 v[58:59], v[60:61], v[58:59] op_sel_hi:[1,0]
	v_cndmask_b32_e64 v40, v52, v40, s[10:11]
	v_cndmask_b32_e64 v43, v55, v43, s[10:11]
	v_cndmask_b32_e64 v42, v53, v42, s[10:11]
	v_pk_fma_f32 v[62:63], v[78:79], v[62:63], v[182:183]
	v_pk_fma_f32 v[58:59], v[72:73], v[58:59], v[180:181]
	v_pk_fma_f32 v[56:57], v[74:75], v[56:57], v[178:179]
	v_pk_add_f32 v[46:47], v[46:47], v[62:63]
	v_pk_add_f32 v[42:43], v[42:43], v[56:57]
	v_pk_add_f32 v[40:41], v[40:41], v[58:59]
	v_cvt_pk_bf16_f32 v56, v44, v45
	v_cvt_pk_bf16_f32 v57, v46, v47
	v_mov_b32_e32 v103, v165
	v_cvt_pk_bf16_f32 v58, v40, v41
	v_cvt_pk_bf16_f32 v59, v42, v43
	v_lshlrev_b32_e32 v40, 16, v56
	v_and_b32_e32 v42, 0xffff0000, v56
	v_lshlrev_b32_e32 v44, 16, v57
	v_and_b32_e32 v46, 0xffff0000, v57
	v_lshlrev_b32_e32 v60, 16, v58
	v_and_b32_e32 v62, 0xffff0000, v58
	v_lshlrev_b32_e32 v92, 16, v59
	v_and_b32_e32 v94, 0xffff0000, v59
	v_mul_f32_e32 v41, v40, v40
	v_mul_f32_e32 v43, v42, v42
	v_mul_f32_e32 v45, v44, v44
	v_mul_f32_e32 v47, v46, v46
	v_mul_f32_e32 v61, v60, v60
	v_mul_f32_e32 v63, v62, v62
	v_mul_f32_e32 v93, v92, v92
	v_mul_f32_e32 v95, v94, v94
	v_pk_add_f32 v[40:41], v[40:41], v[42:43]
	v_pk_add_f32 v[42:43], v[44:45], v[46:47]
	v_pk_add_f32 v[44:45], v[92:93], v[94:95]
	v_pk_add_f32 v[40:41], v[40:41], v[42:43]
	v_pk_add_f32 v[42:43], v[60:61], v[62:63]
	s_nop 0
	v_pk_add_f32 v[42:43], v[42:43], v[44:45]
	s_nop 0
	v_pk_add_f32 v[40:41], v[40:41], v[42:43]
	v_mov_b32_e32 v42, v165
	v_mov_b32_e32 v43, v165
	s_nop 0
	v_mov_b32_dpp v42, v40 quad_perm:[1,0,3,2] row_mask:0xf bank_mask:0xf
	v_mov_b32_dpp v43, v41 quad_perm:[1,0,3,2] row_mask:0xf bank_mask:0xf
	v_pk_add_f32 v[40:41], v[40:41], v[42:43]
	ds_bpermute_b32 v42, v207, v40
	ds_bpermute_b32 v43, v207, v41
	s_waitcnt lgkmcnt(0)
	v_pk_add_f32 v[42:43], v[40:41], v[42:43]
	ds_bpermute_b32 v44, v208, v42
	ds_bpermute_b32 v45, v208, v43
	v_lshl_add_u64 v[40:41], s[20:21], 0, v[102:103]
	global_store_dwordx4 v[40:41], v[56:59], off
	s_and_saveexec_b64 s[64:65], s[16:17]
	s_cbranch_execz .LBB0_1485
	s_waitcnt lgkmcnt(0)
	v_pk_add_f32 v[42:43], v[42:43], v[44:45]
	v_add_co_u32_e32 v44, vcc, 0x12000, v186
	s_nop 1
	v_addc_co_u32_e32 v45, vcc, 0, v187, vcc
	global_store_dwordx2 v[44:45], v[42:43], off

; __device__ __forceinline__ float dpp_x1(float x) { return __builtin_bit_cast(float, __builtin_amdgcn_update_dpp(0, __builtin_bit_cast(int, x), 0xB1, 0xF, 0xF, false)); }
; __device__ __forceinline__ f32x4 dpp_swap1(f32x4 v) { f32x4 r; r[0] = dpp_x1(v[0]); r[1] = dpp_x1(v[1]); r[2] = dpp_x1(v[2]); r[3] = dpp_x1(v[3]); return r; }
;     __device__ __forceinline__ void operator()(const f32x4 (&acc)[2][2][4][2], const Unit& u, int wr, int wc, int fr, int fq, const EpiCtx& X) const {
;     ...
;             for (int m = 0; m < 4; ++m) {
;                 const int rl = ai * HALF + m * 16; const unsigned off = lo + (unsigned)(rl * 64) * 2u;
;                 const f32x4 o0a = acc[ai][0][m][0], o0b = acc[ai][0][m][1], o1a = acc[ai][1][m][0], o1b = acc[ai][1][m][1];
;                 const f32x4 ra_ = dpp_swap1(odd ? o0a : o1a), rb_ = dpp_swap1(odd ? o0b : o1b);
;                 const f32x4 pa[2] = {odd ? ra_ : o0a, odd ? o1a : ra_}, pb[2] = {odd ? rb_ : o0b, odd ? o1b : rb_};
; #pragma unroll
;                 for (int q = 0; q < 2; ++q) {
;                     const u32x4 w0 = raw[2 * m + q];
;                     const f32x4 r0 = (f32x4){bf_lo(w0.x), bf_hi(w0.x), bf_lo(w0.y), bf_hi(w0.y)}, r1 = (f32x4){bf_lo(w0.z), bf_hi(w0.z), bf_lo(w0.w), bf_hi(w0.w)};
;                     f32x4 y0, y1;
;                     if (RESN) { const f32x2 t = tbl[rl + q]; const float mu = t.x, ra = t.y * ALPHA; y0 = (r0 - mu) * ra * g0 + b0 + pa[q]; y1 = (r1 - mu) * ra * g1 + b1 + pb[q]; }
;                     else { y0 = r0 * ALPHA + pa[q]; y1 = r1 * ALPHA + pb[q]; }
;                     { const u32x4 w = pack8f(y0, y1); *(u32x4*)(xb + off + q * 128) = w;
;                         y0 = (f32x4){bf_lo(w.x), bf_hi(w.x), bf_lo(w.y), bf_hi(w.y)}; y1 = (f32x4){bf_lo(w.z), bf_hi(w.z), bf_lo(w.w), bf_hi(w.w)}; }
;                     float sa = ((y0[0] + y0[1]) + (y0[2] + y0[3])) + ((y1[0] + y1[1]) + (y1[2] + y1[3]));
;                     float sb = ((y0[0] * y0[0] + y0[1] * y0[1]) + (y0[2] * y0[2] + y0[3] * y0[3])) + ((y1[0] * y1[0] + y1[1] * y1[1]) + (y1[2] * y1[2] + y1[3] * y1[3]));
;                     sa += dpp_x1(sa);
;                     sb += dpp_x1(sb);
;                     sa += __shfl_xor(sa, 16); sa += __shfl_xor(sa, 32); sb += __shfl_xor(sb, 16); sb += __shfl_xor(sb, 32);
;                     if (fq == 0 && !odd) ps[(size_t)(rl + q) * 64] = (f32x2){sa, sb};
.LBB0_1487:
	s_or_b64 exec, exec, s[64:65]
	s_waitcnt lgkmcnt(1)
	v_cndmask_b32_e64 v34, v28, v20, s[10:11]
	s_nop 0
	v_cndmask_b32_e64 v33, v29, v21, s[10:11]
	s_waitcnt lgkmcnt(0)
	v_cndmask_b32_e64 v35, v30, v22, s[10:11]
	v_mov_b32_dpp v32, v34 quad_perm:[1,0,3,2] row_mask:0xf bank_mask:0xf
	s_nop 0
	v_cndmask_b32_e64 v36, v31, v23, s[10:11]
	v_cndmask_b32_e64 v38, v24, v16, s[10:11]
	v_mov_b32_dpp v34, v33 quad_perm:[1,0,3,2] row_mask:0xf bank_mask:0xf
	s_nop 0
	v_cndmask_b32_e64 v37, v25, v17, s[10:11]
	v_cndmask_b32_e64 v39, v26, v18, s[10:11]
	v_mov_b32_dpp v33, v35 quad_perm:[1,0,3,2] row_mask:0xf bank_mask:0xf
	s_nop 0
	v_cndmask_b32_e64 v40, v27, v19, s[10:11]
	s_waitcnt vmcnt(11)
	v_lshlrev_b32_e32 v43, 16, v84
	v_mov_b32_dpp v35, v36 quad_perm:[1,0,3,2] row_mask:0xf bank_mask:0xf
	s_nop 0
	v_and_b32_e32 v44, 0xffff0000, v84
	v_cndmask_b32_e64 v29, v34, v29, s[10:11]
	v_mov_b32_dpp v36, v38 quad_perm:[1,0,3,2] row_mask:0xf bank_mask:0xf
	s_nop 0
	v_cndmask_b32_e64 v28, v32, v28, s[10:11]
	v_lshlrev_b32_e32 v46, 16, v85
	v_mov_b32_dpp v38, v37 quad_perm:[1,0,3,2] row_mask:0xf bank_mask:0xf
	s_nop 0
	v_and_b32_e32 v47, 0xffff0000, v85
	v_lshlrev_b32_e32 v48, 16, v86
	v_mov_b32_dpp v37, v39 quad_perm:[1,0,3,2] row_mask:0xf bank_mask:0xf
	s_nop 0
	v_and_b32_e32 v49, 0xffff0000, v86
	v_lshlrev_b32_e32 v50, 16, v87
	v_mov_b32_dpp v39, v40 quad_perm:[1,0,3,2] row_mask:0xf bank_mask:0xf
	ds_read_b64 v[40:41], v201 offset:1280
	v_and_b32_e32 v51, 0xffff0000, v87
	v_cndmask_b32_e64 v31, v35, v31, s[10:11]
	v_cndmask_b32_e64 v30, v33, v30, s[10:11]
	v_cndmask_b32_e64 v25, v38, v25, s[10:11]
	s_waitcnt lgkmcnt(0)
	v_mul_f32_e32 v42, 0x3fb504f3, v41
	v_sub_f32_e32 v45, v44, v40
	v_sub_f32_e32 v44, v43, v40
	v_pk_mul_f32 v[44:45], v[44:45], v[42:43] op_sel_hi:[1,0]
	v_sub_f32_e32 v47, v47, v40
	v_pk_fma_f32 v[44:45], v[76:77], v[44:45], v[184:185]
	v_sub_f32_e32 v46, v46, v40
	v_pk_add_f32 v[28:29], v[28:29], v[44:45]
	v_sub_f32_e32 v45, v49, v40
	v_sub_f32_e32 v44, v48, v40
	v_sub_f32_e32 v41, v51, v40
	v_sub_f32_e32 v40, v50, v40
	v_pk_mul_f32 v[46:47], v[46:47], v[42:43] op_sel_hi:[1,0]
	v_pk_mul_f32 v[40:41], v[40:41], v[42:43] op_sel_hi:[1,0]
	v_pk_mul_f32 v[42:43], v[44:45], v[42:43] op_sel_hi:[1,0]
	v_cndmask_b32_e64 v24, v36, v24, s[10:11]
	v_cndmask_b32_e64 v27, v39, v27, s[10:11]
	v_cndmask_b32_e64 v26, v37, v26, s[10:11]
	v_pk_fma_f32 v[46:47], v[78:79], v[46:47], v[182:183]
	v_pk_fma_f32 v[42:43], v[72:73], v[42:43], v[180:181]
	v_pk_fma_f32 v[40:41], v[74:75], v[40:41], v[178:179]
	v_pk_add_f32 v[30:31], v[30:31], v[46:47]
	v_pk_add_f32 v[26:27], v[26:27], v[40:41]
	v_pk_add_f32 v[24:25], v[24:25], v[42:43]
	v_cvt_pk_bf16_f32 v40, v28, v29
	v_cvt_pk_bf16_f32 v41, v30, v31
	v_mov_b32_e32 v101, v165
	v_cvt_pk_bf16_f32 v42, v24, v25
	v_cvt_pk_bf16_f32 v43, v26, v27
	v_lshlrev_b32_e32 v24, 16, v40
	v_and_b32_e32 v26, 0xffff0000, v40
	v_lshlrev_b32_e32 v28, 16, v41
	v_and_b32_e32 v30, 0xffff0000, v41
	v_lshlrev_b32_e32 v44, 16, v42
	v_and_b32_e32 v46, 0xffff0000, v42
	v_lshlrev_b32_e32 v48, 16, v43
	v_and_b32_e32 v50, 0xffff0000, v43
	v_mul_f32_e32 v25, v24, v24
	v_mul_f32_e32 v27, v26, v26
	v_mul_f32_e32 v29, v28, v28
	v_mul_f32_e32 v31, v30, v30
	v_mul_f32_e32 v45, v44, v44
	v_mul_f32_e32 v47, v46, v46
	v_mul_f32_e32 v49, v48, v48
	v_mul_f32_e32 v51, v50, v50
	v_pk_add_f32 v[24:25], v[24:25], v[26:27]
	v_pk_add_f32 v[26:27], v[28:29], v[30:31]
	v_pk_add_f32 v[28:29], v[48:49], v[50:51]
	v_pk_add_f32 v[24:25], v[24:25], v[26:27]
	v_pk_add_f32 v[26:27], v[44:45], v[46:47]
	s_nop 0
	v_pk_add_f32 v[26:27], v[26:27], v[28:29]
	s_nop 0
	v_pk_add_f32 v[24:25], v[24:25], v[26:27]
	v_mov_b32_e32 v26, v165
	v_mov_b32_e32 v27, v165
	s_nop 0
	v_mov_b32_dpp v26, v24 quad_perm:[1,0,3,2] row_mask:0xf bank_mask:0xf
	v_mov_b32_dpp v27, v25 quad_perm:[1,0,3,2] row_mask:0xf bank_mask:0xf
	v_pk_add_f32 v[24:25], v[24:25], v[26:27]
	ds_bpermute_b32 v26, v207, v24
	ds_bpermute_b32 v27, v207, v25
	s_waitcnt lgkmcnt(0)
	v_pk_add_f32 v[26:27], v[24:25], v[26:27]
	ds_bpermute_b32 v28, v208, v26
	ds_bpermute_b32 v29, v208, v27
	v_lshl_add_u64 v[24:25], s[20:21], 0, v[100:101]
	global_store_dwordx4 v[24:25], v[40:43], off
	s_and_saveexec_b64 s[64:65], s[16:17]
	s_cbranch_execz .LBB0_1489
	s_waitcnt lgkmcnt(0)
	v_pk_add_f32 v[26:27], v[26:27], v[28:29]
	v_add_co_u32_e32 v28, vcc, 0x14000, v186
	s_nop 1
	v_addc_co_u32_e32 v29, vcc, 0, v187, vcc
	global_store_dwordx2 v[28:29], v[26:27], off

; __device__ __forceinline__ float dpp_x1(float x) { return __builtin_bit_cast(float, __builtin_amdgcn_update_dpp(0, __builtin_bit_cast(int, x), 0xB1, 0xF, 0xF, false)); }
; __device__ __forceinline__ f32x4 dpp_swap1(f32x4 v) { f32x4 r; r[0] = dpp_x1(v[0]); r[1] = dpp_x1(v[1]); r[2] = dpp_x1(v[2]); r[3] = dpp_x1(v[3]); return r; }
;     __device__ __forceinline__ void operator()(const f32x4 (&acc)[2][2][4][2], const Unit& u, int wr, int wc, int fr, int fq, const EpiCtx& X) const {
;     ...
;             for (int m = 0; m < 4; ++m) {
;                 const int rl = ai * HALF + m * 16; const unsigned off = lo + (unsigned)(rl * 64) * 2u;
;                 const f32x4 o0a = acc[ai][0][m][0], o0b = acc[ai][0][m][1], o1a = acc[ai][1][m][0], o1b = acc[ai][1][m][1];
;                 const f32x4 ra_ = dpp_swap1(odd ? o0a : o1a), rb_ = dpp_swap1(odd ? o0b : o1b);
;                 const f32x4 pa[2] = {odd ? ra_ : o0a, odd ? o1a : ra_}, pb[2] = {odd ? rb_ : o0b, odd ? o1b : rb_};
; #pragma unroll
;                 for (int q = 0; q < 2; ++q) {
;                     const u32x4 w0 = raw[2 * m + q];
;                     const f32x4 r0 = (f32x4){bf_lo(w0.x), bf_hi(w0.x), bf_lo(w0.y), bf_hi(w0.y)}, r1 = (f32x4){bf_lo(w0.z), bf_hi(w0.z), bf_lo(w0.w), bf_hi(w0.w)};
;                     f32x4 y0, y1;
;                     if (RESN) { const f32x2 t = tbl[rl + q]; const float mu = t.x, ra = t.y * ALPHA; y0 = (r0 - mu) * ra * g0 + b0 + pa[q]; y1 = (r1 - mu) * ra * g1 + b1 + pb[q]; }
;                     else { y0 = r0 * ALPHA + pa[q]; y1 = r1 * ALPHA + pb[q]; }
;                     { const u32x4 w = pack8f(y0, y1); *(u32x4*)(xb + off + q * 128) = w;
;                         y0 = (f32x4){bf_lo(w.x), bf_hi(w.x), bf_lo(w.y), bf_hi(w.y)}; y1 = (f32x4){bf_lo(w.z), bf_hi(w.z), bf_lo(w.w), bf_hi(w.w)}; }
;                     float sa = ((y0[0] + y0[1]) + (y0[2] + y0[3])) + ((y1[0] + y1[1]) + (y1[2] + y1[3]));
;                     float sb = ((y0[0] * y0[0] + y0[1] * y0[1]) + (y0[2] * y0[2] + y0[3] * y0[3])) + ((y1[0] * y1[0] + y1[1] * y1[1]) + (y1[2] * y1[2] + y1[3] * y1[3]));
;                     sa += dpp_x1(sa);
;                     sb += dpp_x1(sb);
;                     sa += __shfl_xor(sa, 16); sa += __shfl_xor(sa, 32); sb += __shfl_xor(sb, 16); sb += __shfl_xor(sb, 32);
;                     if (fq == 0 && !odd) ps[(size_t)(rl + q) * 64] = (f32x2){sa, sb};
.LBB0_1491:
	s_or_b64 exec, exec, s[64:65]
	s_waitcnt lgkmcnt(1)
	v_cndmask_b32_e64 v18, v12, v4, s[10:11]
	s_nop 0
	v_cndmask_b32_e64 v17, v13, v5, s[10:11]
	s_waitcnt lgkmcnt(0)
	v_cndmask_b32_e64 v19, v14, v6, s[10:11]
	v_mov_b32_dpp v16, v18 quad_perm:[1,0,3,2] row_mask:0xf bank_mask:0xf
	s_nop 0
	v_cndmask_b32_e64 v20, v15, v7, s[10:11]
	v_cndmask_b32_e64 v22, v8, v0, s[10:11]
	v_mov_b32_dpp v18, v17 quad_perm:[1,0,3,2] row_mask:0xf bank_mask:0xf
	s_nop 0
	v_cndmask_b32_e64 v21, v9, v1, s[10:11]
	v_cndmask_b32_e64 v23, v10, v2, s[10:11]
	v_mov_b32_dpp v17, v19 quad_perm:[1,0,3,2] row_mask:0xf bank_mask:0xf
	s_nop 0
	v_cndmask_b32_e64 v24, v11, v3, s[10:11]
	s_waitcnt vmcnt(13)
	v_lshlrev_b32_e32 v27, 16, v68
	v_mov_b32_dpp v19, v20 quad_perm:[1,0,3,2] row_mask:0xf bank_mask:0xf
	s_nop 0
	v_and_b32_e32 v28, 0xffff0000, v68
	v_cndmask_b32_e64 v13, v18, v13, s[10:11]
	v_mov_b32_dpp v20, v22 quad_perm:[1,0,3,2] row_mask:0xf bank_mask:0xf
	s_nop 0
	v_cndmask_b32_e64 v12, v16, v12, s[10:11]
	v_lshlrev_b32_e32 v30, 16, v69
	v_mov_b32_dpp v22, v21 quad_perm:[1,0,3,2] row_mask:0xf bank_mask:0xf
	s_nop 0
	v_and_b32_e32 v31, 0xffff0000, v69
	v_lshlrev_b32_e32 v32, 16, v70
	v_mov_b32_dpp v21, v23 quad_perm:[1,0,3,2] row_mask:0xf bank_mask:0xf
	s_nop 0
	v_and_b32_e32 v33, 0xffff0000, v70
	v_lshlrev_b32_e32 v34, 16, v71
	v_mov_b32_dpp v23, v24 quad_perm:[1,0,3,2] row_mask:0xf bank_mask:0xf
	ds_read_b64 v[24:25], v201 offset:1408
	v_and_b32_e32 v35, 0xffff0000, v71
	v_cndmask_b32_e64 v15, v19, v15, s[10:11]
	v_cndmask_b32_e64 v14, v17, v14, s[10:11]
	v_cndmask_b32_e64 v9, v22, v9, s[10:11]
	s_waitcnt lgkmcnt(0)
	v_mul_f32_e32 v26, 0x3fb504f3, v25
	v_sub_f32_e32 v29, v28, v24
	v_sub_f32_e32 v28, v27, v24
	v_pk_mul_f32 v[28:29], v[28:29], v[26:27] op_sel_hi:[1,0]
	v_sub_f32_e32 v31, v31, v24
	v_pk_fma_f32 v[28:29], v[76:77], v[28:29], v[184:185]
	v_sub_f32_e32 v30, v30, v24
	v_pk_add_f32 v[12:13], v[12:13], v[28:29]
	v_sub_f32_e32 v29, v33, v24
	v_sub_f32_e32 v28, v32, v24
	v_sub_f32_e32 v25, v35, v24
	v_sub_f32_e32 v24, v34, v24
	v_pk_mul_f32 v[30:31], v[30:31], v[26:27] op_sel_hi:[1,0]
	v_pk_mul_f32 v[24:25], v[24:25], v[26:27] op_sel_hi:[1,0]
	v_pk_mul_f32 v[26:27], v[28:29], v[26:27] op_sel_hi:[1,0]
	v_cndmask_b32_e64 v8, v20, v8, s[10:11]
	v_cndmask_b32_e64 v11, v23, v11, s[10:11]
	v_cndmask_b32_e64 v10, v21, v10, s[10:11]
	v_pk_fma_f32 v[30:31], v[78:79], v[30:31], v[182:183]
	v_pk_fma_f32 v[26:27], v[72:73], v[26:27], v[180:181]
	v_pk_fma_f32 v[24:25], v[74:75], v[24:25], v[178:179]
	v_pk_add_f32 v[14:15], v[14:15], v[30:31]
	v_pk_add_f32 v[10:11], v[10:11], v[24:25]
	v_pk_add_f32 v[8:9], v[8:9], v[26:27]
	v_cvt_pk_bf16_f32 v24, v12, v13
	v_cvt_pk_bf16_f32 v25, v14, v15
	s_nop 0
	v_cvt_pk_bf16_f32 v26, v8, v9
	v_cvt_pk_bf16_f32 v27, v10, v11
	v_lshlrev_b32_e32 v8, 16, v24
	v_and_b32_e32 v10, 0xffff0000, v24
	v_lshlrev_b32_e32 v12, 16, v25
	v_and_b32_e32 v14, 0xffff0000, v25
	v_lshlrev_b32_e32 v28, 16, v26
	v_and_b32_e32 v30, 0xffff0000, v26
	v_lshlrev_b32_e32 v32, 16, v27
	v_and_b32_e32 v34, 0xffff0000, v27
	v_mul_f32_e32 v9, v8, v8
	v_mul_f32_e32 v11, v10, v10
	v_mul_f32_e32 v13, v12, v12
	v_mul_f32_e32 v15, v14, v14
	v_mul_f32_e32 v29, v28, v28
	v_mul_f32_e32 v31, v30, v30
	v_mul_f32_e32 v33, v32, v32
	v_mul_f32_e32 v35, v34, v34
	v_pk_add_f32 v[8:9], v[8:9], v[10:11]
	v_pk_add_f32 v[10:11], v[12:13], v[14:15]
	v_pk_add_f32 v[12:13], v[32:33], v[34:35]
	v_pk_add_f32 v[8:9], v[8:9], v[10:11]
	v_pk_add_f32 v[10:11], v[28:29], v[30:31]
	s_nop 0
	v_pk_add_f32 v[10:11], v[10:11], v[12:13]
	s_nop 0
	v_pk_add_f32 v[8:9], v[8:9], v[10:11]
	v_mov_b32_e32 v10, v165
	v_mov_b32_e32 v11, v165
	s_nop 0
	v_mov_b32_dpp v10, v8 quad_perm:[1,0,3,2] row_mask:0xf bank_mask:0xf
	v_mov_b32_dpp v11, v9 quad_perm:[1,0,3,2] row_mask:0xf bank_mask:0xf
	v_pk_add_f32 v[8:9], v[8:9], v[10:11]
	ds_bpermute_b32 v10, v207, v8
	ds_bpermute_b32 v11, v207, v9
	s_waitcnt lgkmcnt(0)
	v_pk_add_f32 v[10:11], v[8:9], v[10:11]
	ds_bpermute_b32 v12, v208, v10
	ds_bpermute_b32 v13, v208, v11
	v_lshl_add_u64 v[8:9], s[20:21], 0, v[164:165]
	global_store_dwordx4 v[8:9], v[24:27], off
	s_and_saveexec_b64 s[20:21], s[16:17]
	s_cbranch_execz .LBB0_1493
	s_waitcnt lgkmcnt(0)
	v_pk_add_f32 v[10:11], v[10:11], v[12:13]
	v_add_co_u32_e32 v12, vcc, 0x16000, v186
	s_nop 1
	v_addc_co_u32_e32 v13, vcc, 0, v187, vcc
	global_store_dwordx2 v[12:13], v[10:11], off

; #define LAS __attribute__((address_space(3)))
; #define EPI_OPAQUE(x) asm volatile("" : "+v"(x))
;     __device__ __forceinline__ float pre(const Unit& u, int tid) const { return (tid < 256 ? sv : tv)[u.pn * BM + (tid & 255)]; }
;     __device__ __forceinline__ float pre(const Unit& u, int tid) const { return (tid < 256 ? sv : tv)[u.pn * BM + (tid & 255)]; }
; __device__ __forceinline__ float dpp_x1(float x) { return __builtin_bit_cast(float, __builtin_amdgcn_update_dpp(0, __builtin_bit_cast(int, x), 0xB1, 0xF, 0xF, false)); }
; __device__ __forceinline__ f32x4 dpp_swap1(f32x4 v) { f32x4 r; r[0] = dpp_x1(v[0]); r[1] = dpp_x1(v[1]); r[2] = dpp_x1(v[2]); r[3] = dpp_x1(v[3]); return r; }
;     __device__ __forceinline__ void operator()(const f32x4 (&acc)[2][2][4][2], const Unit& u, int wr, int wc, int fr, int fq, const EpiCtx& X) const {
;     ...
;         LAS float* stb = (LAS float*)(X.lds + STB_OFF);
;         stb[X.tid] = X.pre;
;         asm volatile("s_waitcnt lgkmcnt(0)" ::: "memory"); __builtin_amdgcn_s_barrier(); asm volatile("" ::: "memory");
;         const bool odd = fr & 1; const int fe = fr - (fr & 1), o32 = (fr & 1) * 32;
;         constexpr int RP = BLK ? 64 : LDC;
;         char* base = BLK ? (char*)(O + (size_t)u.pm * BM * LDC + (size_t)(u.pn * 4 + wc) * (BM * 64)) : (char*)(O + (size_t)u.pm * BM * LDC + u.pn * BM);
;         unsigned lo = (unsigned)((wr * 64 + fe) * RP + (BLK ? 0 : wc * 64) + o32 + 8 * fq) * 2u; EPI_OPAQUE(lo);
;         const LAS f32x2* tbl = (const LAS f32x2*)(X.lds + TBL_OFF) + wr * 64 + fe;
;         const LAS f32x4* sp = (const LAS f32x4*)(stb + wc * 64 + o32 + 8 * fq);
;         const f32x4 sa = sp[0], sb = sp[1], ta = sp[64], tb = sp[65];
;     ...
;         EPI_PIECES({ const unsigned off = lo + (unsigned)(rl * RP) * 2u; LN_ONE(p1a, p1b, rl, off); LN_ONE(p2a, p2b, rl + 1, off + RP * 2); })
.LBB0_1595:
	v_cndmask_b32_e64 v171, v127, v119, s[12:13]
	v_cndmask_b32_e64 v172, v126, v118, s[12:13]
	v_cndmask_b32_e64 v173, v125, v117, s[12:13]
	v_cndmask_b32_e64 v174, v124, v116, s[12:13]
	s_nop 0
	s_nop 0
	s_nop 0
	s_nop 0
	v_mov_b32_dpp v180, v174 quad_perm:[1,0,3,2] row_mask:0xf bank_mask:0xf
	v_mov_b32_dpp v181, v173 quad_perm:[1,0,3,2] row_mask:0xf bank_mask:0xf
	v_mov_b32_dpp v178, v172 quad_perm:[1,0,3,2] row_mask:0xf bank_mask:0xf
	v_mov_b32_dpp v179, v171 quad_perm:[1,0,3,2] row_mask:0xf bank_mask:0xf
	v_cndmask_b32_e64 v171, v123, v115, s[12:13]
	v_cndmask_b32_e64 v172, v122, v114, s[12:13]
	v_cndmask_b32_e64 v173, v121, v113, s[12:13]
	v_cndmask_b32_e64 v174, v120, v112, s[12:13]
	s_nop 0
	s_nop 0
	s_nop 0
	s_nop 0
	s_waitcnt vmcnt(16)
	ds_write_b32 v162, v169
	v_mov_b32_e32 v170, v163
	v_mov_b32_dpp v182, v174 quad_perm:[1,0,3,2] row_mask:0xf bank_mask:0xf
	v_mov_b32_dpp v183, v173 quad_perm:[1,0,3,2] row_mask:0xf bank_mask:0xf
	v_mov_b32_dpp v184, v172 quad_perm:[1,0,3,2] row_mask:0xf bank_mask:0xf
	v_mov_b32_dpp v185, v171 quad_perm:[1,0,3,2] row_mask:0xf bank_mask:0xf
	s_waitcnt lgkmcnt(0)
	s_barrier
	s_waitcnt lgkmcnt(1)
	ds_read_b128 v[132:135], v165 offset:16
	ds_read_b128 v[136:139], v165 offset:1024
	ds_read_b128 v[128:131], v165 offset:1040
	v_cndmask_b32_e64 v173, v185, v123, s[12:13]
	v_cndmask_b32_e64 v172, v184, v122, s[12:13]
	v_cndmask_b32_e64 v175, v183, v121, s[12:13]
	v_cndmask_b32_e64 v174, v182, v120, s[12:13]
	ds_read_b128 v[120:123], v165
	ds_read_b64 v[176:177], v164
	v_cndmask_b32_e64 v125, v181, v125, s[12:13]
	v_cndmask_b32_e64 v124, v180, v124, s[12:13]
	v_cndmask_b32_e64 v127, v179, v127, s[12:13]
	v_cndmask_b32_e64 v126, v178, v126, s[12:13]
	v_cndmask_b32_e64 v179, v119, v179, s[12:13]
	v_cndmask_b32_e64 v178, v118, v178, s[12:13]
	v_cndmask_b32_e64 v181, v117, v181, s[12:13]
	v_cndmask_b32_e64 v180, v116, v180, s[12:13]
	s_waitcnt lgkmcnt(0)
	v_pk_fma_f32 v[118:119], v[120:121], v[176:177], v[124:125] op_sel_hi:[1,0,1] neg_lo:[1,0,0] neg_hi:[1,0,0]
	v_xor_b32_e32 v117, 0x80000000, v123
	v_xor_b32_e32 v116, 0x80000000, v122
	v_pk_fma_f32 v[122:123], v[116:117], v[176:177], v[126:127] op_sel_hi:[1,0,1]
	v_pk_fma_f32 v[124:125], v[176:177], v[118:119], v[136:137] op_sel:[1,0,0]
	v_pk_fma_f32 v[126:127], v[132:133], v[176:177], v[174:175] op_sel_hi:[1,0,1] neg_lo:[1,0,0] neg_hi:[1,0,0]
	v_xor_b32_e32 v119, 0x80000000, v135
	v_xor_b32_e32 v118, 0x80000000, v134
	v_pk_fma_f32 v[122:123], v[176:177], v[122:123], v[138:139] op_sel:[1,0,0]
	v_pk_fma_f32 v[134:135], v[118:119], v[176:177], v[172:173] op_sel_hi:[1,0,1]
	v_pk_fma_f32 v[126:127], v[176:177], v[126:127], v[128:129] op_sel:[1,0,0]
	s_lshl_b64 s[16:17], s[52:53], 23
	v_pk_fma_f32 v[134:135], v[176:177], v[134:135], v[130:131] op_sel:[1,0,0]
	v_max_f32_e32 v124, 0, v124
	v_max_f32_e32 v126, 0, v126
	v_max_f32_e32 v125, 0, v125
	v_max_f32_e32 v127, 0, v127
	v_max_f32_e32 v122, 0, v122
	s_add_u32 s25, s46, s16
	v_mul_f32_e32 v124, v124, v124
	v_mul_f32_e32 v126, v126, v126
	v_mul_f32_e32 v125, v125, v125
	v_mul_f32_e32 v127, v127, v127
	v_max_f32_e32 v134, 0, v134
	v_mul_f32_e32 v171, v122, v122
	v_max_f32_e32 v122, 0, v123
	v_max_f32_e32 v123, 0, v135
	s_addc_u32 s27, s47, s17
	s_lshl_b32 s16, s67, 2
	v_mul_f32_e32 v134, v134, v134
	v_mul_f32_e32 v135, v122, v122
	v_mul_f32_e32 v172, v123, v123
	v_cvt_pk_bf16_f32 v122, v124, v125
	v_cvt_pk_bf16_f32 v123, v171, v135
	v_cvt_pk_bf16_f32 v124, v126, v127
	v_cvt_pk_bf16_f32 v125, v134, v172
	ds_read_b64 v[126:127], v164 offset:8
	s_or_b32 s16, s16, s41
	s_ashr_i32 s17, s16, 31
	s_lshl_b64 s[16:17], s[16:17], 15
	s_add_u32 s16, s25, s16
	v_cndmask_b32_e64 v113, v113, v183, s[12:13]
	v_cndmask_b32_e64 v112, v112, v182, s[12:13]
	s_addc_u32 s17, s27, s17
	v_cndmask_b32_e64 v115, v115, v185, s[12:13]
	v_cndmask_b32_e64 v114, v114, v184, s[12:13]
	s_waitcnt lgkmcnt(0)
	v_pk_fma_f32 v[112:113], v[132:133], v[126:127], v[112:113] op_sel_hi:[1,0,1] neg_lo:[1,0,0] neg_hi:[1,0,0]
	global_store_dwordx4 v170, v[122:125], s[16:17] nt
	v_pk_fma_f32 v[114:115], v[118:119], v[126:127], v[114:115] op_sel_hi:[1,0,1]
	v_pk_fma_f32 v[112:113], v[126:127], v[112:113], v[128:129] op_sel:[1,0,0]
	v_pk_fma_f32 v[122:123], v[120:121], v[126:127], v[180:181] op_sel_hi:[1,0,1] neg_lo:[1,0,0] neg_hi:[1,0,0]
	v_pk_fma_f32 v[124:125], v[116:117], v[126:127], v[178:179] op_sel_hi:[1,0,1]
	v_pk_fma_f32 v[122:123], v[126:127], v[122:123], v[136:137] op_sel:[1,0,0]
	v_pk_fma_f32 v[124:125], v[126:127], v[124:125], v[138:139] op_sel:[1,0,0]
	v_pk_fma_f32 v[114:115], v[126:127], v[114:115], v[130:131] op_sel:[1,0,0]
	v_max_f32_e32 v112, 0, v112
	v_max_f32_e32 v113, 0, v113
	v_max_f32_e32 v122, 0, v122
	v_mul_f32_e32 v126, v112, v112
	v_max_f32_e32 v112, 0, v123
	v_mul_f32_e32 v123, v113, v113
	v_max_f32_e32 v113, 0, v124
	v_max_f32_e32 v114, 0, v114
	v_mul_f32_e32 v122, v122, v122
	v_mul_f32_e32 v112, v112, v112
	v_mul_f32_e32 v113, v113, v113
	v_mul_f32_e32 v124, v114, v114
	v_max_f32_e32 v114, 0, v125
	v_max_f32_e32 v115, 0, v115
	v_mul_f32_e32 v114, v114, v114
	v_mul_f32_e32 v115, v115, v115
	v_cvt_pk_bf16_f32 v112, v122, v112
	v_cvt_pk_bf16_f32 v113, v113, v114
	v_add_u32_e32 v122, 0x80, v170
	v_cvt_pk_bf16_f32 v114, v126, v123
	v_cvt_pk_bf16_f32 v115, v124, v115
	global_store_dwordx4 v122, v[112:115], s[16:17] nt
	ds_read_b64 v[112:113], v164 offset:128
	v_cndmask_b32_e64 v123, v108, v100, s[12:13]
	s_nop 0
	v_cndmask_b32_e64 v127, v104, v96, s[12:13]
	s_nop 0
	v_cndmask_b32_e64 v122, v109, v101, s[12:13]
	v_mov_b32_dpp v124, v123 quad_perm:[1,0,3,2] row_mask:0xf bank_mask:0xf
	s_nop 0
	v_cndmask_b32_e64 v126, v105, v97, s[12:13]
	v_mov_b32_dpp v134, v127 quad_perm:[1,0,3,2] row_mask:0xf bank_mask:0xf
	s_nop 0
	v_cndmask_b32_e64 v115, v110, v102, s[12:13]
	v_mov_b32_dpp v123, v122 quad_perm:[1,0,3,2] row_mask:0xf bank_mask:0xf
	s_nop 0
	v_mov_b32_dpp v127, v126 quad_perm:[1,0,3,2] row_mask:0xf bank_mask:0xf
	v_cndmask_b32_e64 v114, v111, v103, s[12:13]
	v_mov_b32_dpp v122, v115 quad_perm:[1,0,3,2] row_mask:0xf bank_mask:0xf
	s_nop 0
	v_cndmask_b32_e64 v125, v106, v98, s[12:13]
	s_nop 0
	v_cndmask_b32_e64 v105, v127, v105, s[12:13]
	v_cndmask_b32_e64 v104, v134, v104, s[12:13]
	v_mov_b32_dpp v115, v114 quad_perm:[1,0,3,2] row_mask:0xf bank_mask:0xf
	v_cndmask_b32_e64 v114, v107, v99, s[12:13]
	v_mov_b32_dpp v126, v125 quad_perm:[1,0,3,2] row_mask:0xf bank_mask:0xf
	s_nop 0
	s_waitcnt lgkmcnt(0)
;     __device__ __forceinline__ void operator()(const f32x4 (&acc)[2][2][4][2], const Unit& u, int wr, int wc, int fr, int fq, const EpiCtx& X) const {
;     ...
;         EPI_PIECES({ const unsigned off = lo + (unsigned)(rl * RP) * 2u; LN_ONE(p1a, p1b, rl, off); LN_ONE(p2a, p2b, rl + 1, off + RP * 2); })
	v_pk_fma_f32 v[104:105], v[132:133], v[112:113], v[104:105] op_sel_hi:[1,0,1] neg_lo:[1,0,0] neg_hi:[1,0,0]
	v_cndmask_b32_e64 v111, v115, v111, s[12:13]
	v_mov_b32_dpp v125, v114 quad_perm:[1,0,3,2] row_mask:0xf bank_mask:0xf
	v_cndmask_b32_e64 v110, v122, v110, s[12:13]
	v_cndmask_b32_e64 v109, v123, v109, s[12:13]
	v_cndmask_b32_e64 v108, v124, v108, s[12:13]
	v_pk_fma_f32 v[104:105], v[112:113], v[104:105], v[128:129] op_sel:[1,0,0]
	v_cndmask_b32_e64 v107, v125, v107, s[12:13]
	v_cndmask_b32_e64 v106, v126, v106, s[12:13]
	v_cndmask_b32_e64 v103, v103, v115, s[12:13]
	v_cndmask_b32_e64 v115, v101, v123, s[12:13]
	v_cndmask_b32_e64 v114, v100, v124, s[12:13]
	v_pk_fma_f32 v[100:101], v[120:121], v[112:113], v[108:109] op_sel_hi:[1,0,1] neg_lo:[1,0,0] neg_hi:[1,0,0]
	v_pk_fma_f32 v[108:109], v[116:117], v[112:113], v[110:111] op_sel_hi:[1,0,1]
	v_max_f32_e32 v104, 0, v104
	v_pk_fma_f32 v[108:109], v[112:113], v[108:109], v[138:139] op_sel:[1,0,0]
	v_pk_fma_f32 v[106:107], v[118:119], v[112:113], v[106:107] op_sel_hi:[1,0,1]
	v_mul_f32_e32 v110, v104, v104
	v_max_f32_e32 v104, 0, v105
	v_pk_fma_f32 v[100:101], v[112:113], v[100:101], v[136:137] op_sel:[1,0,0]
	v_pk_fma_f32 v[106:107], v[112:113], v[106:107], v[130:131] op_sel:[1,0,0]
	v_mul_f32_e32 v111, v104, v104
	v_max_f32_e32 v104, 0, v108
	v_max_f32_e32 v100, 0, v100
	v_max_f32_e32 v101, 0, v101
	v_max_f32_e32 v105, 0, v106
	v_mul_f32_e32 v106, v104, v104
	v_max_f32_e32 v104, 0, v109
	v_mul_f32_e32 v100, v100, v100
	v_mul_f32_e32 v101, v101, v101
	v_mul_f32_e32 v108, v105, v105
	v_max_f32_e32 v105, 0, v107
	v_mul_f32_e32 v107, v104, v104
	v_mul_f32_e32 v109, v105, v105
	v_cndmask_b32_e64 v105, v99, v125, s[12:13]
	v_cndmask_b32_e64 v104, v98, v126, s[12:13]
	v_cvt_pk_bf16_f32 v98, v100, v101
	v_cvt_pk_bf16_f32 v99, v106, v107
	v_cvt_pk_bf16_f32 v100, v110, v111
	v_cvt_pk_bf16_f32 v101, v108, v109
	ds_read_b64 v[106:107], v164 offset:136
	v_cndmask_b32_e64 v97, v97, v127, s[12:13]
	v_cndmask_b32_e64 v96, v96, v134, s[12:13]
	v_cndmask_b32_e64 v102, v102, v122, s[12:13]
	v_add_u32_e32 v108, 0x800, v170
	s_waitcnt lgkmcnt(0)
	v_pk_fma_f32 v[96:97], v[132:133], v[106:107], v[96:97] op_sel_hi:[1,0,1] neg_lo:[1,0,0] neg_hi:[1,0,0]
	global_store_dwordx4 v108, v[98:101], s[16:17] nt
	v_pk_fma_f32 v[96:97], v[106:107], v[96:97], v[128:129] op_sel:[1,0,0]
	s_andn2_b64 vcc, exec, s[14:15]
	v_pk_fma_f32 v[98:99], v[120:121], v[106:107], v[114:115] op_sel_hi:[1,0,1] neg_lo:[1,0,0] neg_hi:[1,0,0]
	v_pk_fma_f32 v[100:101], v[116:117], v[106:107], v[102:103] op_sel_hi:[1,0,1]
	v_pk_fma_f32 v[102:103], v[118:119], v[106:107], v[104:105] op_sel_hi:[1,0,1]
	v_pk_fma_f32 v[100:101], v[106:107], v[100:101], v[138:139] op_sel:[1,0,0]
	v_pk_fma_f32 v[98:99], v[106:107], v[98:99], v[136:137] op_sel:[1,0,0]
	v_pk_fma_f32 v[102:103], v[106:107], v[102:103], v[130:131] op_sel:[1,0,0]
	v_max_f32_e32 v96, 0, v96
	v_max_f32_e32 v97, 0, v97
	v_max_f32_e32 v98, 0, v98
	v_mul_f32_e32 v104, v96, v96
	v_max_f32_e32 v96, 0, v99
	v_mul_f32_e32 v99, v97, v97
	v_max_f32_e32 v97, 0, v100
	v_max_f32_e32 v100, 0, v102
	v_mul_f32_e32 v98, v98, v98
	v_mul_f32_e32 v96, v96, v96
	v_mul_f32_e32 v97, v97, v97
	v_mul_f32_e32 v100, v100, v100
	v_max_f32_e32 v101, 0, v101
	v_max_f32_e32 v102, 0, v103
	v_mul_f32_e32 v101, v101, v101
	v_mul_f32_e32 v102, v102, v102
	v_cvt_pk_bf16_f32 v96, v98, v96
	v_cvt_pk_bf16_f32 v97, v97, v101
	v_cvt_pk_bf16_f32 v98, v104, v99
	v_cvt_pk_bf16_f32 v99, v100, v102
	v_add_u32_e32 v100, 0x880, v170
	global_store_dwordx4 v100, v[96:99], s[16:17] nt
	s_nop 0
	v_cndmask_b32_e64 v103, v88, v80, s[12:13]
	v_cndmask_b32_e64 v99, v92, v84, s[12:13]
	v_cndmask_b32_e64 v98, v93, v85, s[12:13]
	s_nop 0
	v_mov_b32_dpp v100, v99 quad_perm:[1,0,3,2] row_mask:0xf bank_mask:0xf
	s_nop 0
	v_cndmask_b32_e64 v96, v95, v87, s[12:13]
	v_cndmask_b32_e64 v97, v94, v86, s[12:13]
	v_mov_b32_dpp v99, v98 quad_perm:[1,0,3,2] row_mask:0xf bank_mask:0xf
	s_nop 0
	s_nop 0
	v_cndmask_b32_e64 v102, v89, v81, s[12:13]
	v_mov_b32_dpp v104, v103 quad_perm:[1,0,3,2] row_mask:0xf bank_mask:0xf
	s_nop 0
	v_mov_b32_dpp v98, v97 quad_perm:[1,0,3,2] row_mask:0xf bank_mask:0xf
	v_mov_b32_dpp v101, v96 quad_perm:[1,0,3,2] row_mask:0xf bank_mask:0xf
	v_cndmask_b32_e64 v96, v91, v83, s[12:13]
	v_cndmask_b32_e64 v97, v90, v82, s[12:13]
	v_mov_b32_dpp v103, v102 quad_perm:[1,0,3,2] row_mask:0xf bank_mask:0xf
	s_nop 0
	s_nop 0
	v_cndmask_b32_e64 v89, v103, v89, s[12:13]
	v_mov_b32_dpp v102, v97 quad_perm:[1,0,3,2] row_mask:0xf bank_mask:0xf
	v_mov_b32_dpp v105, v96 quad_perm:[1,0,3,2] row_mask:0xf bank_mask:0xf
	ds_read_b64 v[96:97], v164 offset:256
	v_cndmask_b32_e64 v88, v104, v88, s[12:13]
	v_cndmask_b32_e64 v95, v101, v95, s[12:13]
	v_cndmask_b32_e64 v94, v98, v94, s[12:13]
	v_cndmask_b32_e64 v93, v99, v93, s[12:13]
	s_waitcnt lgkmcnt(0)
;     __device__ __forceinline__ void operator()(const f32x4 (&acc)[2][2][4][2], const Unit& u, int wr, int wc, int fr, int fq, const EpiCtx& X) const {
;     ...
;         EPI_PIECES({ const unsigned off = lo + (unsigned)(rl * RP) * 2u; LN_ONE(p1a, p1b, rl, off); LN_ONE(p2a, p2b, rl + 1, off + RP * 2); })
	v_pk_fma_f32 v[88:89], v[132:133], v[96:97], v[88:89] op_sel_hi:[1,0,1] neg_lo:[1,0,0] neg_hi:[1,0,0]
	v_cndmask_b32_e64 v92, v100, v92, s[12:13]
	v_pk_fma_f32 v[88:89], v[96:97], v[88:89], v[128:129] op_sel:[1,0,0]
	v_cndmask_b32_e64 v91, v105, v91, s[12:13]
	v_cndmask_b32_e64 v90, v102, v90, s[12:13]
	v_cndmask_b32_e64 v86, v86, v98, s[12:13]
	v_cndmask_b32_e64 v99, v85, v99, s[12:13]
	v_cndmask_b32_e64 v98, v84, v100, s[12:13]
	v_pk_fma_f32 v[84:85], v[120:121], v[96:97], v[92:93] op_sel_hi:[1,0,1] neg_lo:[1,0,0] neg_hi:[1,0,0]
	v_pk_fma_f32 v[92:93], v[116:117], v[96:97], v[94:95] op_sel_hi:[1,0,1]
	v_max_f32_e32 v88, 0, v88
	v_pk_fma_f32 v[92:93], v[96:97], v[92:93], v[138:139] op_sel:[1,0,0]
	v_pk_fma_f32 v[90:91], v[118:119], v[96:97], v[90:91] op_sel_hi:[1,0,1]
	v_mul_f32_e32 v94, v88, v88
	v_max_f32_e32 v88, 0, v89
	v_pk_fma_f32 v[84:85], v[96:97], v[84:85], v[136:137] op_sel:[1,0,0]
	v_pk_fma_f32 v[90:91], v[96:97], v[90:91], v[130:131] op_sel:[1,0,0]
	v_mul_f32_e32 v95, v88, v88
	v_max_f32_e32 v88, 0, v92
	v_max_f32_e32 v84, 0, v84
	v_max_f32_e32 v85, 0, v85
	v_max_f32_e32 v89, 0, v90
	v_mul_f32_e32 v90, v88, v88
	v_max_f32_e32 v88, 0, v93
	v_mul_f32_e32 v84, v84, v84
	v_mul_f32_e32 v85, v85, v85
	v_mul_f32_e32 v92, v89, v89
	v_max_f32_e32 v89, 0, v91
	v_mul_f32_e32 v91, v88, v88
	v_mul_f32_e32 v93, v89, v89
	v_cndmask_b32_e64 v89, v83, v105, s[12:13]
	v_cndmask_b32_e64 v88, v82, v102, s[12:13]
	v_cvt_pk_bf16_f32 v82, v84, v85
	v_cvt_pk_bf16_f32 v83, v90, v91
	v_cvt_pk_bf16_f32 v84, v94, v95
	v_cvt_pk_bf16_f32 v85, v92, v93
	ds_read_b64 v[90:91], v164 offset:264
	v_cndmask_b32_e64 v81, v81, v103, s[12:13]
	v_cndmask_b32_e64 v80, v80, v104, s[12:13]
	v_cndmask_b32_e64 v87, v87, v101, s[12:13]
	v_add_u32_e32 v92, 0x1000, v170
	s_waitcnt lgkmcnt(0)
	v_pk_fma_f32 v[80:81], v[132:133], v[90:91], v[80:81] op_sel_hi:[1,0,1] neg_lo:[1,0,0] neg_hi:[1,0,0]
	global_store_dwordx4 v92, v[82:85], s[16:17] nt
	v_pk_fma_f32 v[80:81], v[90:91], v[80:81], v[128:129] op_sel:[1,0,0]
	s_mov_b64 s[14:15], -1
	v_pk_fma_f32 v[82:83], v[120:121], v[90:91], v[98:99] op_sel_hi:[1,0,1] neg_lo:[1,0,0] neg_hi:[1,0,0]
	v_pk_fma_f32 v[84:85], v[116:117], v[90:91], v[86:87] op_sel_hi:[1,0,1]
	v_pk_fma_f32 v[86:87], v[118:119], v[90:91], v[88:89] op_sel_hi:[1,0,1]
	v_pk_fma_f32 v[84:85], v[90:91], v[84:85], v[138:139] op_sel:[1,0,0]
	v_pk_fma_f32 v[82:83], v[90:91], v[82:83], v[136:137] op_sel:[1,0,0]
	v_pk_fma_f32 v[86:87], v[90:91], v[86:87], v[130:131] op_sel:[1,0,0]
	v_max_f32_e32 v80, 0, v80
	v_max_f32_e32 v81, 0, v81
	v_max_f32_e32 v82, 0, v82
	v_mul_f32_e32 v88, v80, v80
	v_max_f32_e32 v80, 0, v83
	v_mul_f32_e32 v83, v81, v81
	v_max_f32_e32 v81, 0, v84
	v_max_f32_e32 v84, 0, v86
	v_mul_f32_e32 v82, v82, v82
	v_mul_f32_e32 v80, v80, v80
	v_mul_f32_e32 v81, v81, v81
	v_mul_f32_e32 v84, v84, v84
	v_max_f32_e32 v85, 0, v85
	v_max_f32_e32 v86, 0, v87
	v_mul_f32_e32 v85, v85, v85
	v_mul_f32_e32 v86, v86, v86
	v_cvt_pk_bf16_f32 v80, v82, v80
	v_cvt_pk_bf16_f32 v81, v81, v85
	v_cvt_pk_bf16_f32 v82, v88, v83
	v_cvt_pk_bf16_f32 v83, v84, v86
	v_add_u32_e32 v84, 0x1080, v170
	global_store_dwordx4 v84, v[80:83], s[16:17] nt
	ds_read_b64 v[80:81], v164 offset:384
	v_cndmask_b32_e64 v85, v76, v68, s[12:13]
	s_nop 0
	v_cndmask_b32_e64 v89, v72, v64, s[12:13]
	s_nop 0
	v_cndmask_b32_e64 v84, v77, v69, s[12:13]
	v_mov_b32_dpp v86, v85 quad_perm:[1,0,3,2] row_mask:0xf bank_mask:0xf
	s_nop 0
	v_cndmask_b32_e64 v88, v73, v65, s[12:13]
	v_mov_b32_dpp v90, v89 quad_perm:[1,0,3,2] row_mask:0xf bank_mask:0xf
	s_nop 0
	v_cndmask_b32_e64 v83, v78, v70, s[12:13]
	v_mov_b32_dpp v85, v84 quad_perm:[1,0,3,2] row_mask:0xf bank_mask:0xf
	s_nop 0
	v_mov_b32_dpp v89, v88 quad_perm:[1,0,3,2] row_mask:0xf bank_mask:0xf
	v_cndmask_b32_e64 v82, v79, v71, s[12:13]
	v_mov_b32_dpp v84, v83 quad_perm:[1,0,3,2] row_mask:0xf bank_mask:0xf
	s_nop 0
	v_cndmask_b32_e64 v87, v74, v66, s[12:13]
	s_nop 0
	v_cndmask_b32_e64 v73, v89, v73, s[12:13]
	v_cndmask_b32_e64 v72, v90, v72, s[12:13]
	v_mov_b32_dpp v83, v82 quad_perm:[1,0,3,2] row_mask:0xf bank_mask:0xf
	v_cndmask_b32_e64 v82, v75, v67, s[12:13]
	v_mov_b32_dpp v88, v87 quad_perm:[1,0,3,2] row_mask:0xf bank_mask:0xf
	s_nop 0
	s_waitcnt lgkmcnt(0)
	v_pk_fma_f32 v[72:73], v[132:133], v[80:81], v[72:73] op_sel_hi:[1,0,1] neg_lo:[1,0,0] neg_hi:[1,0,0]
	v_cndmask_b32_e64 v79, v83, v79, s[12:13]
	v_mov_b32_dpp v87, v82 quad_perm:[1,0,3,2] row_mask:0xf bank_mask:0xf
	v_cndmask_b32_e64 v78, v84, v78, s[12:13]
	v_cndmask_b32_e64 v77, v85, v77, s[12:13]
	v_cndmask_b32_e64 v76, v86, v76, s[12:13]
	v_pk_fma_f32 v[72:73], v[80:81], v[72:73], v[128:129] op_sel:[1,0,0]
	v_cndmask_b32_e64 v75, v87, v75, s[12:13]
	v_cndmask_b32_e64 v74, v88, v74, s[12:13]
	v_cndmask_b32_e64 v71, v71, v83, s[12:13]
	v_cndmask_b32_e64 v83, v69, v85, s[12:13]
	v_cndmask_b32_e64 v82, v68, v86, s[12:13]
	v_pk_fma_f32 v[68:69], v[120:121], v[80:81], v[76:77] op_sel_hi:[1,0,1] neg_lo:[1,0,0] neg_hi:[1,0,0]
	v_pk_fma_f32 v[76:77], v[116:117], v[80:81], v[78:79] op_sel_hi:[1,0,1]
	v_max_f32_e32 v72, 0, v72
	v_pk_fma_f32 v[76:77], v[80:81], v[76:77], v[138:139] op_sel:[1,0,0]
	v_pk_fma_f32 v[74:75], v[118:119], v[80:81], v[74:75] op_sel_hi:[1,0,1]
	v_mul_f32_e32 v78, v72, v72
	v_max_f32_e32 v72, 0, v73
	v_pk_fma_f32 v[68:69], v[80:81], v[68:69], v[136:137] op_sel:[1,0,0]
	v_pk_fma_f32 v[74:75], v[80:81], v[74:75], v[130:131] op_sel:[1,0,0]
	v_mul_f32_e32 v79, v72, v72
	v_max_f32_e32 v72, 0, v76
	v_max_f32_e32 v68, 0, v68
	v_max_f32_e32 v69, 0, v69
	v_max_f32_e32 v73, 0, v74
	v_mul_f32_e32 v74, v72, v72
	v_max_f32_e32 v72, 0, v77
	v_mul_f32_e32 v68, v68, v68
	v_mul_f32_e32 v69, v69, v69
	v_mul_f32_e32 v76, v73, v73
	v_max_f32_e32 v73, 0, v75
	v_mul_f32_e32 v75, v72, v72
	v_mul_f32_e32 v77, v73, v73
	v_cndmask_b32_e64 v73, v67, v87, s[12:13]
	v_cndmask_b32_e64 v72, v66, v88, s[12:13]
	v_cvt_pk_bf16_f32 v66, v68, v69
	v_cvt_pk_bf16_f32 v67, v74, v75
	v_cvt_pk_bf16_f32 v68, v78, v79
	v_cvt_pk_bf16_f32 v69, v76, v77
	ds_read_b64 v[74:75], v164 offset:392
	v_cndmask_b32_e64 v65, v65, v89, s[12:13]
	v_cndmask_b32_e64 v64, v64, v90, s[12:13]
	v_cndmask_b32_e64 v70, v70, v84, s[12:13]
	v_add_u32_e32 v76, 0x1800, v170
	s_waitcnt lgkmcnt(0)
;     __device__ __forceinline__ void operator()(const f32x4 (&acc)[2][2][4][2], const Unit& u, int wr, int wc, int fr, int fq, const EpiCtx& X) const {
;     ...
;         EPI_PIECES({ const unsigned off = lo + (unsigned)(rl * RP) * 2u; LN_ONE(p1a, p1b, rl, off); LN_ONE(p2a, p2b, rl + 1, off + RP * 2); })
	v_pk_fma_f32 v[64:65], v[132:133], v[74:75], v[64:65] op_sel_hi:[1,0,1] neg_lo:[1,0,0] neg_hi:[1,0,0]
	global_store_dwordx4 v76, v[66:69], s[16:17] nt
	v_pk_fma_f32 v[64:65], v[74:75], v[64:65], v[128:129] op_sel:[1,0,0]
	s_nop 0
	v_pk_fma_f32 v[66:67], v[120:121], v[74:75], v[82:83] op_sel_hi:[1,0,1] neg_lo:[1,0,0] neg_hi:[1,0,0]
	v_pk_fma_f32 v[68:69], v[116:117], v[74:75], v[70:71] op_sel_hi:[1,0,1]
	v_pk_fma_f32 v[70:71], v[118:119], v[74:75], v[72:73] op_sel_hi:[1,0,1]
	v_pk_fma_f32 v[68:69], v[74:75], v[68:69], v[138:139] op_sel:[1,0,0]
	v_pk_fma_f32 v[66:67], v[74:75], v[66:67], v[136:137] op_sel:[1,0,0]
	v_pk_fma_f32 v[70:71], v[74:75], v[70:71], v[130:131] op_sel:[1,0,0]
	v_max_f32_e32 v64, 0, v64
	v_max_f32_e32 v65, 0, v65
	v_max_f32_e32 v66, 0, v66
	v_mul_f32_e32 v72, v64, v64
	v_max_f32_e32 v64, 0, v67
	v_mul_f32_e32 v67, v65, v65
	v_max_f32_e32 v65, 0, v68
	v_max_f32_e32 v68, 0, v70
	v_mul_f32_e32 v66, v66, v66
	v_mul_f32_e32 v64, v64, v64
	v_mul_f32_e32 v65, v65, v65
	v_mul_f32_e32 v68, v68, v68
	v_max_f32_e32 v69, 0, v69
	v_max_f32_e32 v70, 0, v71
	v_mul_f32_e32 v69, v69, v69
	v_mul_f32_e32 v70, v70, v70
	v_cvt_pk_bf16_f32 v64, v66, v64
	v_cvt_pk_bf16_f32 v65, v65, v69
	v_cvt_pk_bf16_f32 v66, v72, v67
	v_cvt_pk_bf16_f32 v67, v68, v70
	v_add_u32_e32 v68, 0x1880, v170
	global_store_dwordx4 v68, v[64:67], s[16:17] nt
	s_nop 0
	v_cndmask_b32_e64 v71, v56, v48, s[12:13]
	v_cndmask_b32_e64 v67, v60, v52, s[12:13]
	v_cndmask_b32_e64 v66, v61, v53, s[12:13]
	s_nop 0
	v_mov_b32_dpp v68, v67 quad_perm:[1,0,3,2] row_mask:0xf bank_mask:0xf
	s_nop 0
	v_cndmask_b32_e64 v64, v63, v55, s[12:13]
	v_cndmask_b32_e64 v65, v62, v54, s[12:13]
	v_mov_b32_dpp v67, v66 quad_perm:[1,0,3,2] row_mask:0xf bank_mask:0xf
	s_nop 0
	s_nop 0
	v_cndmask_b32_e64 v70, v57, v49, s[12:13]
	v_mov_b32_dpp v72, v71 quad_perm:[1,0,3,2] row_mask:0xf bank_mask:0xf
	s_nop 0
	v_mov_b32_dpp v66, v65 quad_perm:[1,0,3,2] row_mask:0xf bank_mask:0xf
	v_mov_b32_dpp v69, v64 quad_perm:[1,0,3,2] row_mask:0xf bank_mask:0xf
	v_cndmask_b32_e64 v64, v59, v51, s[12:13]
	v_cndmask_b32_e64 v65, v58, v50, s[12:13]
	v_mov_b32_dpp v71, v70 quad_perm:[1,0,3,2] row_mask:0xf bank_mask:0xf
	s_nop 0
	s_nop 0
	v_cndmask_b32_e64 v57, v71, v57, s[12:13]
	v_mov_b32_dpp v70, v65 quad_perm:[1,0,3,2] row_mask:0xf bank_mask:0xf
	v_mov_b32_dpp v73, v64 quad_perm:[1,0,3,2] row_mask:0xf bank_mask:0xf
	ds_read_b64 v[64:65], v164 offset:1024
	v_cndmask_b32_e64 v56, v72, v56, s[12:13]
	v_cndmask_b32_e64 v63, v69, v63, s[12:13]
	v_cndmask_b32_e64 v62, v66, v62, s[12:13]
	v_cndmask_b32_e64 v61, v67, v61, s[12:13]
	s_waitcnt lgkmcnt(0)
	v_pk_fma_f32 v[56:57], v[132:133], v[64:65], v[56:57] op_sel_hi:[1,0,1] neg_lo:[1,0,0] neg_hi:[1,0,0]
	v_cndmask_b32_e64 v60, v68, v60, s[12:13]
	v_pk_fma_f32 v[56:57], v[64:65], v[56:57], v[128:129] op_sel:[1,0,0]
	v_cndmask_b32_e64 v59, v73, v59, s[12:13]
	v_cndmask_b32_e64 v58, v70, v58, s[12:13]
	v_cndmask_b32_e64 v54, v54, v66, s[12:13]
	v_cndmask_b32_e64 v67, v53, v67, s[12:13]
	v_cndmask_b32_e64 v66, v52, v68, s[12:13]
	v_pk_fma_f32 v[52:53], v[120:121], v[64:65], v[60:61] op_sel_hi:[1,0,1] neg_lo:[1,0,0] neg_hi:[1,0,0]
	v_pk_fma_f32 v[60:61], v[116:117], v[64:65], v[62:63] op_sel_hi:[1,0,1]
	v_max_f32_e32 v56, 0, v56
	v_pk_fma_f32 v[60:61], v[64:65], v[60:61], v[138:139] op_sel:[1,0,0]
	v_pk_fma_f32 v[58:59], v[118:119], v[64:65], v[58:59] op_sel_hi:[1,0,1]
	v_mul_f32_e32 v62, v56, v56
	v_max_f32_e32 v56, 0, v57
	v_pk_fma_f32 v[52:53], v[64:65], v[52:53], v[136:137] op_sel:[1,0,0]
	v_pk_fma_f32 v[58:59], v[64:65], v[58:59], v[130:131] op_sel:[1,0,0]
	v_mul_f32_e32 v63, v56, v56
	v_max_f32_e32 v56, 0, v60
	v_max_f32_e32 v52, 0, v52
	v_max_f32_e32 v53, 0, v53
	v_max_f32_e32 v57, 0, v58
	v_mul_f32_e32 v58, v56, v56
	v_max_f32_e32 v56, 0, v61
	v_mul_f32_e32 v52, v52, v52
	v_mul_f32_e32 v53, v53, v53
	v_mul_f32_e32 v60, v57, v57
	v_max_f32_e32 v57, 0, v59
	v_mul_f32_e32 v59, v56, v56
	v_mul_f32_e32 v61, v57, v57
	v_cndmask_b32_e64 v57, v51, v73, s[12:13]
	v_cndmask_b32_e64 v56, v50, v70, s[12:13]
	v_cvt_pk_bf16_f32 v50, v52, v53
	v_cvt_pk_bf16_f32 v51, v58, v59
	v_cvt_pk_bf16_f32 v52, v62, v63
	v_cvt_pk_bf16_f32 v53, v60, v61
	ds_read_b64 v[58:59], v164 offset:1032
	v_cndmask_b32_e64 v49, v49, v71, s[12:13]
	v_cndmask_b32_e64 v48, v48, v72, s[12:13]
	v_cndmask_b32_e64 v55, v55, v69, s[12:13]
	v_add_u32_e32 v60, 0x4000, v170
	s_waitcnt lgkmcnt(0)
	v_pk_fma_f32 v[48:49], v[132:133], v[58:59], v[48:49] op_sel_hi:[1,0,1] neg_lo:[1,0,0] neg_hi:[1,0,0]
	global_store_dwordx4 v60, v[50:53], s[16:17] nt
	v_pk_fma_f32 v[48:49], v[58:59], v[48:49], v[128:129] op_sel:[1,0,0]
	s_nop 0
	v_pk_fma_f32 v[50:51], v[120:121], v[58:59], v[66:67] op_sel_hi:[1,0,1] neg_lo:[1,0,0] neg_hi:[1,0,0]
	v_pk_fma_f32 v[52:53], v[116:117], v[58:59], v[54:55] op_sel_hi:[1,0,1]
	v_pk_fma_f32 v[54:55], v[118:119], v[58:59], v[56:57] op_sel_hi:[1,0,1]
	v_pk_fma_f32 v[52:53], v[58:59], v[52:53], v[138:139] op_sel:[1,0,0]
	v_pk_fma_f32 v[50:51], v[58:59], v[50:51], v[136:137] op_sel:[1,0,0]
	v_pk_fma_f32 v[54:55], v[58:59], v[54:55], v[130:131] op_sel:[1,0,0]
	v_max_f32_e32 v48, 0, v48
	v_max_f32_e32 v49, 0, v49
	v_max_f32_e32 v50, 0, v50
	v_mul_f32_e32 v56, v48, v48
	v_max_f32_e32 v48, 0, v51
	v_mul_f32_e32 v51, v49, v49
	v_max_f32_e32 v49, 0, v52
	v_max_f32_e32 v52, 0, v54
	v_mul_f32_e32 v50, v50, v50
	v_mul_f32_e32 v48, v48, v48
	v_mul_f32_e32 v49, v49, v49
	v_mul_f32_e32 v52, v52, v52
	v_max_f32_e32 v53, 0, v53
	v_max_f32_e32 v54, 0, v55
	v_mul_f32_e32 v53, v53, v53
	v_mul_f32_e32 v54, v54, v54
	v_cvt_pk_bf16_f32 v48, v50, v48
	v_cvt_pk_bf16_f32 v49, v49, v53
	v_cvt_pk_bf16_f32 v50, v56, v51
	v_cvt_pk_bf16_f32 v51, v52, v54
	v_add_u32_e32 v52, 0x4080, v170
	global_store_dwordx4 v52, v[48:51], s[16:17] nt
	ds_read_b64 v[48:49], v164 offset:1152
	v_cndmask_b32_e64 v53, v44, v36, s[12:13]
	s_nop 0
	v_cndmask_b32_e64 v57, v40, v32, s[12:13]
	s_nop 0
	v_cndmask_b32_e64 v52, v45, v37, s[12:13]
	v_mov_b32_dpp v54, v53 quad_perm:[1,0,3,2] row_mask:0xf bank_mask:0xf
	s_nop 0
	v_cndmask_b32_e64 v56, v41, v33, s[12:13]
	v_mov_b32_dpp v58, v57 quad_perm:[1,0,3,2] row_mask:0xf bank_mask:0xf
	s_nop 0
	v_cndmask_b32_e64 v51, v46, v38, s[12:13]
	v_mov_b32_dpp v53, v52 quad_perm:[1,0,3,2] row_mask:0xf bank_mask:0xf
	s_nop 0
	v_mov_b32_dpp v57, v56 quad_perm:[1,0,3,2] row_mask:0xf bank_mask:0xf
	v_cndmask_b32_e64 v50, v47, v39, s[12:13]
	v_mov_b32_dpp v52, v51 quad_perm:[1,0,3,2] row_mask:0xf bank_mask:0xf
	s_nop 0
	v_cndmask_b32_e64 v55, v42, v34, s[12:13]
	s_nop 0
	v_cndmask_b32_e64 v41, v57, v41, s[12:13]
	v_cndmask_b32_e64 v40, v58, v40, s[12:13]
	v_mov_b32_dpp v51, v50 quad_perm:[1,0,3,2] row_mask:0xf bank_mask:0xf
	v_cndmask_b32_e64 v50, v43, v35, s[12:13]
	v_mov_b32_dpp v56, v55 quad_perm:[1,0,3,2] row_mask:0xf bank_mask:0xf
	s_nop 0
	s_waitcnt lgkmcnt(0)
;     __device__ __forceinline__ void operator()(const f32x4 (&acc)[2][2][4][2], const Unit& u, int wr, int wc, int fr, int fq, const EpiCtx& X) const {
;     ...
;         EPI_PIECES({ const unsigned off = lo + (unsigned)(rl * RP) * 2u; LN_ONE(p1a, p1b, rl, off); LN_ONE(p2a, p2b, rl + 1, off + RP * 2); })
	v_pk_fma_f32 v[40:41], v[132:133], v[48:49], v[40:41] op_sel_hi:[1,0,1] neg_lo:[1,0,0] neg_hi:[1,0,0]
	v_cndmask_b32_e64 v47, v51, v47, s[12:13]
	v_mov_b32_dpp v55, v50 quad_perm:[1,0,3,2] row_mask:0xf bank_mask:0xf
	v_cndmask_b32_e64 v46, v52, v46, s[12:13]
	v_cndmask_b32_e64 v45, v53, v45, s[12:13]
	v_cndmask_b32_e64 v44, v54, v44, s[12:13]
	v_pk_fma_f32 v[40:41], v[48:49], v[40:41], v[128:129] op_sel:[1,0,0]
	v_cndmask_b32_e64 v43, v55, v43, s[12:13]
	v_cndmask_b32_e64 v42, v56, v42, s[12:13]
	v_cndmask_b32_e64 v39, v39, v51, s[12:13]
	v_cndmask_b32_e64 v51, v37, v53, s[12:13]
	v_cndmask_b32_e64 v50, v36, v54, s[12:13]
	v_pk_fma_f32 v[36:37], v[120:121], v[48:49], v[44:45] op_sel_hi:[1,0,1] neg_lo:[1,0,0] neg_hi:[1,0,0]
	v_pk_fma_f32 v[44:45], v[116:117], v[48:49], v[46:47] op_sel_hi:[1,0,1]
	v_max_f32_e32 v40, 0, v40
	v_pk_fma_f32 v[44:45], v[48:49], v[44:45], v[138:139] op_sel:[1,0,0]
	v_pk_fma_f32 v[42:43], v[118:119], v[48:49], v[42:43] op_sel_hi:[1,0,1]
	v_mul_f32_e32 v46, v40, v40
	v_max_f32_e32 v40, 0, v41
	v_pk_fma_f32 v[36:37], v[48:49], v[36:37], v[136:137] op_sel:[1,0,0]
	v_pk_fma_f32 v[42:43], v[48:49], v[42:43], v[130:131] op_sel:[1,0,0]
	v_mul_f32_e32 v47, v40, v40
	v_max_f32_e32 v40, 0, v44
	v_max_f32_e32 v36, 0, v36
	v_max_f32_e32 v37, 0, v37
	v_max_f32_e32 v41, 0, v42
	v_mul_f32_e32 v42, v40, v40
	v_max_f32_e32 v40, 0, v45
	v_mul_f32_e32 v36, v36, v36
	v_mul_f32_e32 v37, v37, v37
	v_mul_f32_e32 v44, v41, v41
	v_max_f32_e32 v41, 0, v43
	v_mul_f32_e32 v43, v40, v40
	v_mul_f32_e32 v45, v41, v41
	v_cndmask_b32_e64 v41, v35, v55, s[12:13]
	v_cndmask_b32_e64 v40, v34, v56, s[12:13]
	v_cvt_pk_bf16_f32 v34, v36, v37
	v_cvt_pk_bf16_f32 v35, v42, v43
	v_cvt_pk_bf16_f32 v36, v46, v47
	v_cvt_pk_bf16_f32 v37, v44, v45
	ds_read_b64 v[42:43], v164 offset:1160
	v_cndmask_b32_e64 v33, v33, v57, s[12:13]
	v_cndmask_b32_e64 v32, v32, v58, s[12:13]
	v_cndmask_b32_e64 v38, v38, v52, s[12:13]
	v_add_u32_e32 v44, 0x4800, v170
	s_waitcnt lgkmcnt(0)
	v_pk_fma_f32 v[32:33], v[132:133], v[42:43], v[32:33] op_sel_hi:[1,0,1] neg_lo:[1,0,0] neg_hi:[1,0,0]
	global_store_dwordx4 v44, v[34:37], s[16:17] nt
	v_pk_fma_f32 v[32:33], v[42:43], v[32:33], v[128:129] op_sel:[1,0,0]
	s_nop 0
	v_pk_fma_f32 v[34:35], v[120:121], v[42:43], v[50:51] op_sel_hi:[1,0,1] neg_lo:[1,0,0] neg_hi:[1,0,0]
	v_pk_fma_f32 v[36:37], v[116:117], v[42:43], v[38:39] op_sel_hi:[1,0,1]
	v_pk_fma_f32 v[38:39], v[118:119], v[42:43], v[40:41] op_sel_hi:[1,0,1]
	v_pk_fma_f32 v[36:37], v[42:43], v[36:37], v[138:139] op_sel:[1,0,0]
	v_pk_fma_f32 v[34:35], v[42:43], v[34:35], v[136:137] op_sel:[1,0,0]
	v_pk_fma_f32 v[38:39], v[42:43], v[38:39], v[130:131] op_sel:[1,0,0]
	v_max_f32_e32 v32, 0, v32
	v_max_f32_e32 v33, 0, v33
	v_max_f32_e32 v34, 0, v34
	v_mul_f32_e32 v40, v32, v32
	v_max_f32_e32 v32, 0, v35
	v_mul_f32_e32 v35, v33, v33
	v_max_f32_e32 v33, 0, v36
	v_max_f32_e32 v36, 0, v38
	v_mul_f32_e32 v34, v34, v34
	v_mul_f32_e32 v32, v32, v32
	v_mul_f32_e32 v33, v33, v33
	v_mul_f32_e32 v36, v36, v36
	v_max_f32_e32 v37, 0, v37
	v_max_f32_e32 v38, 0, v39
	v_mul_f32_e32 v37, v37, v37
	v_mul_f32_e32 v38, v38, v38
	v_cvt_pk_bf16_f32 v32, v34, v32
	v_cvt_pk_bf16_f32 v33, v33, v37
	v_cvt_pk_bf16_f32 v34, v40, v35
	v_cvt_pk_bf16_f32 v35, v36, v38
	v_add_u32_e32 v36, 0x4880, v170
	global_store_dwordx4 v36, v[32:35], s[16:17] nt
	s_nop 0
	v_cndmask_b32_e64 v39, v24, v16, s[12:13]
	v_cndmask_b32_e64 v35, v28, v20, s[12:13]
	v_cndmask_b32_e64 v34, v29, v21, s[12:13]
	s_nop 0
	v_mov_b32_dpp v36, v35 quad_perm:[1,0,3,2] row_mask:0xf bank_mask:0xf
	s_nop 0
	v_cndmask_b32_e64 v32, v31, v23, s[12:13]
	v_cndmask_b32_e64 v33, v30, v22, s[12:13]
	v_mov_b32_dpp v35, v34 quad_perm:[1,0,3,2] row_mask:0xf bank_mask:0xf
	s_nop 0
	s_nop 0
	v_cndmask_b32_e64 v38, v25, v17, s[12:13]
	v_mov_b32_dpp v40, v39 quad_perm:[1,0,3,2] row_mask:0xf bank_mask:0xf
	s_nop 0
	v_mov_b32_dpp v34, v33 quad_perm:[1,0,3,2] row_mask:0xf bank_mask:0xf
	v_mov_b32_dpp v37, v32 quad_perm:[1,0,3,2] row_mask:0xf bank_mask:0xf
	v_cndmask_b32_e64 v32, v27, v19, s[12:13]
	v_cndmask_b32_e64 v33, v26, v18, s[12:13]
	v_mov_b32_dpp v39, v38 quad_perm:[1,0,3,2] row_mask:0xf bank_mask:0xf
	s_nop 0
	s_nop 0
	v_cndmask_b32_e64 v25, v39, v25, s[12:13]
	v_mov_b32_dpp v38, v33 quad_perm:[1,0,3,2] row_mask:0xf bank_mask:0xf
	v_mov_b32_dpp v41, v32 quad_perm:[1,0,3,2] row_mask:0xf bank_mask:0xf
	ds_read_b64 v[32:33], v164 offset:1280
	v_cndmask_b32_e64 v24, v40, v24, s[12:13]
	v_cndmask_b32_e64 v31, v37, v31, s[12:13]
	v_cndmask_b32_e64 v30, v34, v30, s[12:13]
	v_cndmask_b32_e64 v29, v35, v29, s[12:13]
	s_waitcnt lgkmcnt(0)
	v_pk_fma_f32 v[24:25], v[132:133], v[32:33], v[24:25] op_sel_hi:[1,0,1] neg_lo:[1,0,0] neg_hi:[1,0,0]
	v_cndmask_b32_e64 v28, v36, v28, s[12:13]
	v_pk_fma_f32 v[24:25], v[32:33], v[24:25], v[128:129] op_sel:[1,0,0]
	v_cndmask_b32_e64 v27, v41, v27, s[12:13]
	v_cndmask_b32_e64 v26, v38, v26, s[12:13]
	v_cndmask_b32_e64 v22, v22, v34, s[12:13]
	v_cndmask_b32_e64 v35, v21, v35, s[12:13]
	v_cndmask_b32_e64 v34, v20, v36, s[12:13]
	v_pk_fma_f32 v[20:21], v[120:121], v[32:33], v[28:29] op_sel_hi:[1,0,1] neg_lo:[1,0,0] neg_hi:[1,0,0]
	v_pk_fma_f32 v[28:29], v[116:117], v[32:33], v[30:31] op_sel_hi:[1,0,1]
	v_max_f32_e32 v24, 0, v24
	v_pk_fma_f32 v[28:29], v[32:33], v[28:29], v[138:139] op_sel:[1,0,0]
	v_pk_fma_f32 v[26:27], v[118:119], v[32:33], v[26:27] op_sel_hi:[1,0,1]
	v_mul_f32_e32 v30, v24, v24
	v_max_f32_e32 v24, 0, v25
	v_pk_fma_f32 v[20:21], v[32:33], v[20:21], v[136:137] op_sel:[1,0,0]
	v_pk_fma_f32 v[26:27], v[32:33], v[26:27], v[130:131] op_sel:[1,0,0]
	v_mul_f32_e32 v31, v24, v24
	v_max_f32_e32 v24, 0, v28
	v_max_f32_e32 v20, 0, v20
	v_max_f32_e32 v21, 0, v21
	v_max_f32_e32 v25, 0, v26
	v_mul_f32_e32 v26, v24, v24
	v_max_f32_e32 v24, 0, v29
	v_mul_f32_e32 v20, v20, v20
	v_mul_f32_e32 v21, v21, v21
	v_mul_f32_e32 v28, v25, v25
	v_max_f32_e32 v25, 0, v27
	v_mul_f32_e32 v27, v24, v24
	v_mul_f32_e32 v29, v25, v25
	v_cndmask_b32_e64 v25, v19, v41, s[12:13]
	v_cndmask_b32_e64 v24, v18, v38, s[12:13]
	v_cvt_pk_bf16_f32 v18, v20, v21
	v_cvt_pk_bf16_f32 v19, v26, v27
	v_cvt_pk_bf16_f32 v20, v30, v31
	v_cvt_pk_bf16_f32 v21, v28, v29
	ds_read_b64 v[26:27], v164 offset:1288
	v_cndmask_b32_e64 v17, v17, v39, s[12:13]
	v_cndmask_b32_e64 v16, v16, v40, s[12:13]
	v_cndmask_b32_e64 v23, v23, v37, s[12:13]
	v_add_u32_e32 v28, 0x5000, v170
	s_waitcnt lgkmcnt(0)
;     __device__ __forceinline__ void operator()(const f32x4 (&acc)[2][2][4][2], const Unit& u, int wr, int wc, int fr, int fq, const EpiCtx& X) const {
;     ...
;         EPI_PIECES({ const unsigned off = lo + (unsigned)(rl * RP) * 2u; LN_ONE(p1a, p1b, rl, off); LN_ONE(p2a, p2b, rl + 1, off + RP * 2); })
	v_pk_fma_f32 v[16:17], v[132:133], v[26:27], v[16:17] op_sel_hi:[1,0,1] neg_lo:[1,0,0] neg_hi:[1,0,0]
	global_store_dwordx4 v28, v[18:21], s[16:17] nt
	v_pk_fma_f32 v[16:17], v[26:27], v[16:17], v[128:129] op_sel:[1,0,0]
	s_nop 0
	v_pk_fma_f32 v[18:19], v[120:121], v[26:27], v[34:35] op_sel_hi:[1,0,1] neg_lo:[1,0,0] neg_hi:[1,0,0]
	v_pk_fma_f32 v[20:21], v[116:117], v[26:27], v[22:23] op_sel_hi:[1,0,1]
	v_pk_fma_f32 v[22:23], v[118:119], v[26:27], v[24:25] op_sel_hi:[1,0,1]
	v_pk_fma_f32 v[20:21], v[26:27], v[20:21], v[138:139] op_sel:[1,0,0]
	v_pk_fma_f32 v[18:19], v[26:27], v[18:19], v[136:137] op_sel:[1,0,0]
	v_pk_fma_f32 v[22:23], v[26:27], v[22:23], v[130:131] op_sel:[1,0,0]
	v_max_f32_e32 v16, 0, v16
	v_max_f32_e32 v17, 0, v17
	v_max_f32_e32 v18, 0, v18
	v_mul_f32_e32 v24, v16, v16
	v_max_f32_e32 v16, 0, v19
	v_mul_f32_e32 v19, v17, v17
	v_max_f32_e32 v17, 0, v20
	v_max_f32_e32 v20, 0, v22
	v_mul_f32_e32 v18, v18, v18
	v_mul_f32_e32 v16, v16, v16
	v_mul_f32_e32 v17, v17, v17
	v_mul_f32_e32 v20, v20, v20
	v_max_f32_e32 v21, 0, v21
	v_max_f32_e32 v22, 0, v23
	v_mul_f32_e32 v21, v21, v21
	v_mul_f32_e32 v22, v22, v22
	v_cvt_pk_bf16_f32 v16, v18, v16
	v_cvt_pk_bf16_f32 v17, v17, v21
	v_cvt_pk_bf16_f32 v18, v24, v19
	v_cvt_pk_bf16_f32 v19, v20, v22
	v_add_u32_e32 v20, 0x5080, v170
	global_store_dwordx4 v20, v[16:19], s[16:17] nt
	ds_read_b64 v[16:17], v164 offset:1408
	v_cndmask_b32_e64 v21, v12, v4, s[12:13]
	s_nop 0
	v_cndmask_b32_e64 v25, v8, v0, s[12:13]
	s_nop 0
	v_cndmask_b32_e64 v20, v13, v5, s[12:13]
	v_mov_b32_dpp v22, v21 quad_perm:[1,0,3,2] row_mask:0xf bank_mask:0xf
	s_nop 0
	v_cndmask_b32_e64 v24, v9, v1, s[12:13]
	v_mov_b32_dpp v26, v25 quad_perm:[1,0,3,2] row_mask:0xf bank_mask:0xf
	s_nop 0
	v_cndmask_b32_e64 v19, v14, v6, s[12:13]
	v_mov_b32_dpp v21, v20 quad_perm:[1,0,3,2] row_mask:0xf bank_mask:0xf
	s_nop 0
	v_mov_b32_dpp v25, v24 quad_perm:[1,0,3,2] row_mask:0xf bank_mask:0xf
	v_cndmask_b32_e64 v18, v15, v7, s[12:13]
	v_mov_b32_dpp v20, v19 quad_perm:[1,0,3,2] row_mask:0xf bank_mask:0xf
	s_nop 0
	v_cndmask_b32_e64 v23, v10, v2, s[12:13]
	s_nop 0
	v_cndmask_b32_e64 v9, v25, v9, s[12:13]
	v_cndmask_b32_e64 v8, v26, v8, s[12:13]
	v_mov_b32_dpp v19, v18 quad_perm:[1,0,3,2] row_mask:0xf bank_mask:0xf
	v_cndmask_b32_e64 v18, v11, v3, s[12:13]
	v_mov_b32_dpp v24, v23 quad_perm:[1,0,3,2] row_mask:0xf bank_mask:0xf
	s_nop 0
	s_waitcnt lgkmcnt(0)
	v_pk_fma_f32 v[8:9], v[132:133], v[16:17], v[8:9] op_sel_hi:[1,0,1] neg_lo:[1,0,0] neg_hi:[1,0,0]
	v_cndmask_b32_e64 v15, v19, v15, s[12:13]
	v_mov_b32_dpp v23, v18 quad_perm:[1,0,3,2] row_mask:0xf bank_mask:0xf
	v_cndmask_b32_e64 v14, v20, v14, s[12:13]
	v_cndmask_b32_e64 v13, v21, v13, s[12:13]
	v_cndmask_b32_e64 v12, v22, v12, s[12:13]
	v_pk_fma_f32 v[8:9], v[16:17], v[8:9], v[128:129] op_sel:[1,0,0]
	v_cndmask_b32_e64 v11, v23, v11, s[12:13]
	v_cndmask_b32_e64 v10, v24, v10, s[12:13]
	v_cndmask_b32_e64 v7, v7, v19, s[12:13]
	v_cndmask_b32_e64 v19, v5, v21, s[12:13]
	v_cndmask_b32_e64 v18, v4, v22, s[12:13]
	v_pk_fma_f32 v[4:5], v[120:121], v[16:17], v[12:13] op_sel_hi:[1,0,1] neg_lo:[1,0,0] neg_hi:[1,0,0]
	v_pk_fma_f32 v[12:13], v[116:117], v[16:17], v[14:15] op_sel_hi:[1,0,1]
	v_max_f32_e32 v8, 0, v8
	v_pk_fma_f32 v[12:13], v[16:17], v[12:13], v[138:139] op_sel:[1,0,0]
	v_pk_fma_f32 v[10:11], v[118:119], v[16:17], v[10:11] op_sel_hi:[1,0,1]
	v_mul_f32_e32 v14, v8, v8
	v_max_f32_e32 v8, 0, v9
	v_pk_fma_f32 v[4:5], v[16:17], v[4:5], v[136:137] op_sel:[1,0,0]
	v_pk_fma_f32 v[10:11], v[16:17], v[10:11], v[130:131] op_sel:[1,0,0]
	v_mul_f32_e32 v15, v8, v8
	v_max_f32_e32 v8, 0, v12
	v_max_f32_e32 v4, 0, v4
	v_max_f32_e32 v5, 0, v5
	v_max_f32_e32 v9, 0, v10
	v_mul_f32_e32 v10, v8, v8
	v_max_f32_e32 v8, 0, v13
	v_mul_f32_e32 v4, v4, v4
	v_mul_f32_e32 v5, v5, v5
	v_mul_f32_e32 v12, v9, v9
	v_max_f32_e32 v9, 0, v11
	v_mul_f32_e32 v11, v8, v8
	v_mul_f32_e32 v13, v9, v9
	v_cndmask_b32_e64 v9, v3, v23, s[12:13]
	v_cndmask_b32_e64 v8, v2, v24, s[12:13]
	v_cvt_pk_bf16_f32 v2, v4, v5
	v_cvt_pk_bf16_f32 v3, v10, v11
	v_cvt_pk_bf16_f32 v4, v14, v15
	v_cvt_pk_bf16_f32 v5, v12, v13
	ds_read_b64 v[10:11], v164 offset:1416
	v_cndmask_b32_e64 v1, v1, v25, s[12:13]
	v_cndmask_b32_e64 v0, v0, v26, s[12:13]
	v_cndmask_b32_e64 v6, v6, v20, s[12:13]
	v_add_u32_e32 v12, 0x5800, v170
	s_waitcnt lgkmcnt(0)
	v_pk_fma_f32 v[0:1], v[132:133], v[10:11], v[0:1] op_sel_hi:[1,0,1] neg_lo:[1,0,0] neg_hi:[1,0,0]
	global_store_dwordx4 v12, v[2:5], s[16:17] nt
	v_pk_fma_f32 v[0:1], v[10:11], v[0:1], v[128:129] op_sel:[1,0,0]
	s_nop 0
	v_pk_fma_f32 v[2:3], v[120:121], v[10:11], v[18:19] op_sel_hi:[1,0,1] neg_lo:[1,0,0] neg_hi:[1,0,0]
	v_pk_fma_f32 v[4:5], v[116:117], v[10:11], v[6:7] op_sel_hi:[1,0,1]
	v_pk_fma_f32 v[6:7], v[118:119], v[10:11], v[8:9] op_sel_hi:[1,0,1]
	v_pk_fma_f32 v[4:5], v[10:11], v[4:5], v[138:139] op_sel:[1,0,0]
	v_pk_fma_f32 v[2:3], v[10:11], v[2:3], v[136:137] op_sel:[1,0,0]
	v_pk_fma_f32 v[6:7], v[10:11], v[6:7], v[130:131] op_sel:[1,0,0]
	v_max_f32_e32 v0, 0, v0
	v_max_f32_e32 v1, 0, v1
	v_max_f32_e32 v2, 0, v2
	v_mul_f32_e32 v8, v0, v0
	v_max_f32_e32 v0, 0, v3
	v_mul_f32_e32 v3, v1, v1
	v_max_f32_e32 v1, 0, v4
	v_max_f32_e32 v4, 0, v6
	v_mul_f32_e32 v2, v2, v2
	v_mul_f32_e32 v0, v0, v0
	v_mul_f32_e32 v1, v1, v1
	v_mul_f32_e32 v4, v4, v4
	v_max_f32_e32 v5, 0, v5
	v_max_f32_e32 v6, 0, v7
	v_mul_f32_e32 v5, v5, v5
	v_mul_f32_e32 v6, v6, v6
	v_cvt_pk_bf16_f32 v0, v2, v0
	v_cvt_pk_bf16_f32 v1, v1, v5
	v_cvt_pk_bf16_f32 v2, v8, v3
	v_cvt_pk_bf16_f32 v3, v4, v6
	v_add_u32_e32 v4, 0x5880, v170
	global_store_dwordx4 v4, v[0:3], s[16:17] nt
	s_cbranch_vccnz .LBB0_1560
	s_and_b64 vcc, exec, s[6:7]
	s_cbranch_vccnz .LBB0_1559
	s_barrier
	s_branch .LBB0_1559

; #define LAS __attribute__((address_space(3)))
;     __device__ __forceinline__ void operator()(const f32x4 (&acc)[2][2][4][2], const Unit& u, int wr, int wc, int fr, int fq, const EpiCtx& X) const {
;     ...
;         char* yb = nullptr; char* xb = (char*)(XB + (size_t)u.pm * BM * DM + (size_t)(u.pn * 4 + wc) * (BM * 64));
;         unsigned lo = (unsigned)((wr * 64 + fe) * 64 + o32 + 8 * fq) * 2u; EPI_OPAQUE(lo);
;         const int col = u.pn * BM + wc * 64 + o32 + 8 * fq;
;         f32x4 g0, g1, b0, b1;
;         if (RESN) { ensure_tbl(PSp, sidp, u.pm, X);
;             g0 = *(const f32x4*)(gp + col); g1 = *(const f32x4*)(gp + col + 4); b0 = *(const f32x4*)(bp + col) * ALPHA; b1 = *(const f32x4*)(bp + col + 4) * ALPHA; }
;         const LAS f32x2* tbl = (const LAS f32x2*)(X.lds + TBL_OFF) + wr * 64 + fe;
;         f32x2* ps = PSn + ((size_t)u.pm * BM + wr * 64 + fe) * 64 + u.pn * 4 + wc;
; #pragma unroll
;         for (int ai = 0; ai < 2; ++ai) {
;             u32x4 raw[8];
; #pragma unroll
;             for (int m = 0; m < 4; ++m) { const unsigned off = lo + (unsigned)((ai * HALF + m * 16) * 64) * 2u; raw[2 * m] = *(const u32x4*)(xb + off); raw[2 * m + 1] = *(const u32x4*)(xb + off + 128); }
; #pragma unroll
;             for (int m = 0; m < 4; ++m) {
;                 const int rl = ai * HALF + m * 16; const unsigned off = lo + (unsigned)(rl * 64) * 2u;
;                 const f32x4 o0a = acc[ai][0][m][0], o0b = acc[ai][0][m][1], o1a = acc[ai][1][m][0], o1b = acc[ai][1][m][1];
;                 const f32x4 ra_ = dpp_swap1(odd ? o0a : o1a), rb_ = dpp_swap1(odd ? o0b : o1b);
;                 const f32x4 pa[2] = {odd ? ra_ : o0a, odd ? o1a : ra_}, pb[2] = {odd ? rb_ : o0b, odd ? o1b : rb_};
; #pragma unroll
;                 for (int q = 0; q < 2; ++q) {
;                     const u32x4 w0 = raw[2 * m + q];
;                     const f32x4 r0 = (f32x4){bf_lo(w0.x), bf_hi(w0.x), bf_lo(w0.y), bf_hi(w0.y)}, r1 = (f32x4){bf_lo(w0.z), bf_hi(w0.z), bf_lo(w0.w), bf_hi(w0.w)};
;                     f32x4 y0, y1;
;                     if (RESN) { const f32x2 t = tbl[rl + q]; const float mu = t.x, ra = t.y * ALPHA; y0 = (r0 - mu) * ra * g0 + b0 + pa[q]; y1 = (r1 - mu) * ra * g1 + b1 + pb[q]; }
;                     else { y0 = r0 * ALPHA + pa[q]; y1 = r1 * ALPHA + pb[q]; }
;                     { const u32x4 w = pack8f(y0, y1); *(u32x4*)(xb + off + q * 128) = w;
.LBB0_1697:
	s_lshl_b64 s[16:17], s[58:59], 21
	s_add_u32 s35, s31, s16
	s_addc_u32 s38, s68, s17
	s_lshl_b32 s58, s56, 2
	s_or_b32 s16, s58, s41
	s_ashr_i32 s17, s16, 31
	v_lshl_add_u32 v72, s56, 8, v200
	v_ashrrev_i32_e32 v73, 31, v72
	s_lshl_b64 s[16:17], s[16:17], 15
	v_lshlrev_b64 v[72:73], 2, v[72:73]
	s_add_u32 s16, s35, s16
	v_lshl_add_u64 v[74:75], s[26:27], 0, v[72:73]
	s_addc_u32 s17, s38, s17
	global_load_dwordx4 v[194:197], v[74:75], off offset:16
	global_load_dwordx4 v[178:181], v[74:75], off
	global_load_dwordx4 v[214:217], v164, s[16:17]
	v_lshl_add_u64 v[72:73], s[24:25], 0, v[72:73]
	s_waitcnt lgkmcnt(0)
	global_load_dwordx4 v[76:79], v[72:73], off
	s_nop 0
	global_load_dwordx4 v[72:75], v[72:73], off offset:16
	v_cndmask_b32_e64 v136, v135, v127, s[6:7]
	v_cndmask_b32_e64 v137, v134, v126, s[6:7]
	v_cndmask_b32_e64 v138, v133, v125, s[6:7]
	v_cndmask_b32_e64 v139, v132, v124, s[6:7]
	s_nop 0
	s_nop 0
	s_nop 0
	s_nop 0
	v_cndmask_b32_e64 v140, v131, v123, s[6:7]
	v_cndmask_b32_e64 v141, v130, v122, s[6:7]
	v_cndmask_b32_e64 v142, v129, v121, s[6:7]
	v_cndmask_b32_e64 v143, v128, v120, s[6:7]
	s_nop 0
	s_nop 0
	s_nop 0
	s_nop 0
	v_mov_b32_dpp v189, v139 quad_perm:[1,0,3,2] row_mask:0xf bank_mask:0xf
	v_mov_b32_dpp v193, v138 quad_perm:[1,0,3,2] row_mask:0xf bank_mask:0xf
	v_mov_b32_dpp v191, v137 quad_perm:[1,0,3,2] row_mask:0xf bank_mask:0xf
	v_mov_b32_dpp v209, v136 quad_perm:[1,0,3,2] row_mask:0xf bank_mask:0xf
	v_mov_b32_dpp v210, v143 quad_perm:[1,0,3,2] row_mask:0xf bank_mask:0xf
	v_mov_b32_dpp v212, v142 quad_perm:[1,0,3,2] row_mask:0xf bank_mask:0xf
	v_mov_b32_dpp v211, v141 quad_perm:[1,0,3,2] row_mask:0xf bank_mask:0xf
	v_mov_b32_dpp v213, v140 quad_perm:[1,0,3,2] row_mask:0xf bank_mask:0xf
	v_add_u32_e32 v192, 0x800, v164
	v_add_u32_e32 v190, 0x1000, v164
	v_add_u32_e32 v188, 0x1800, v164
	ds_read_b64 v[218:219], v201
	v_cndmask_b32_e64 v221, v193, v133, s[6:7]
	v_cndmask_b32_e64 v220, v189, v132, s[6:7]
	v_cndmask_b32_e64 v223, v209, v135, s[6:7]
	v_cndmask_b32_e64 v222, v191, v134, s[6:7]
	v_cndmask_b32_e64 v225, v212, v129, s[6:7]
	v_cndmask_b32_e64 v224, v210, v128, s[6:7]
	v_cndmask_b32_e64 v227, v213, v131, s[6:7]
	v_cndmask_b32_e64 v226, v211, v130, s[6:7]
	global_load_dwordx4 v[152:155], v164, s[16:17] offset:128
	global_load_dwordx4 v[148:151], v192, s[16:17]
	global_load_dwordx4 v[144:147], v192, s[16:17] offset:128
	global_load_dwordx4 v[140:143], v190, s[16:17]
	global_load_dwordx4 v[136:139], v190, s[16:17] offset:128
	global_load_dwordx4 v[132:135], v188, s[16:17]
	global_load_dwordx4 v[128:131], v188, s[16:17] offset:128
	s_waitcnt lgkmcnt(0)
	v_mul_f32_e32 v208, 0x3fb504f3, v219
	v_lshl_add_u64 v[186:187], v[166:167], 0, s[60:61]
	s_ashr_i32 s59, s58, 31
	v_lshl_add_u64 v[186:187], s[58:59], 3, v[186:187]
	v_lshl_add_u64 v[186:187], v[186:187], 0, s[20:21]
	v_add_u32_e32 v246, 0x4000, v164
	v_add_u32_e32 v247, 0x4800, v164
	global_load_dwordx4 v[230:233], v246, s[16:17]
	global_load_dwordx4 v[234:237], v246, s[16:17] offset:128
	global_load_dwordx4 v[238:241], v247, s[16:17]
	global_load_dwordx4 v[242:245], v247, s[16:17] offset:128
	s_waitcnt vmcnt(14)
	v_pk_mul_f32 v[182:183], v[180:181], s[46:47] op_sel_hi:[1,0]
	v_pk_mul_f32 v[184:185], v[178:179], s[46:47] op_sel_hi:[1,0]
	v_pk_mul_f32 v[178:179], v[196:197], s[46:47] op_sel_hi:[1,0]
	v_pk_mul_f32 v[180:181], v[194:195], s[46:47] op_sel_hi:[1,0]
	s_waitcnt vmcnt(13)
	v_lshlrev_b32_e32 v194, 16, v214
	v_and_b32_e32 v195, 0xffff0000, v214
	v_lshlrev_b32_e32 v196, 16, v215
	v_and_b32_e32 v197, 0xffff0000, v215
	v_lshlrev_b32_e32 v207, 16, v216
	v_and_b32_e32 v214, 0xffff0000, v216
	v_lshlrev_b32_e32 v216, 16, v217
	v_and_b32_e32 v217, 0xffff0000, v217
	v_sub_f32_e32 v195, v195, v218
	v_sub_f32_e32 v194, v194, v218
	v_sub_f32_e32 v197, v197, v218
	v_sub_f32_e32 v196, v196, v218
	v_sub_f32_e32 v215, v214, v218
	v_sub_f32_e32 v214, v207, v218
	v_sub_f32_e32 v217, v217, v218
	v_sub_f32_e32 v216, v216, v218
	v_pk_mul_f32 v[196:197], v[196:197], v[208:209] op_sel_hi:[1,0]
	v_pk_mul_f32 v[194:195], v[194:195], v[208:209] op_sel_hi:[1,0]
	v_pk_mul_f32 v[216:217], v[216:217], v[208:209] op_sel_hi:[1,0]
	v_pk_mul_f32 v[214:215], v[214:215], v[208:209] op_sel_hi:[1,0]
	s_waitcnt vmcnt(12)
	v_pk_fma_f32 v[194:195], v[76:77], v[194:195], v[184:185]
	v_pk_fma_f32 v[196:197], v[78:79], v[196:197], v[182:183]
	s_waitcnt vmcnt(11)
	v_pk_fma_f32 v[214:215], v[72:73], v[214:215], v[180:181]
	v_pk_fma_f32 v[216:217], v[74:75], v[216:217], v[178:179]
	v_pk_add_f32 v[196:197], v[222:223], v[196:197]
	v_pk_add_f32 v[194:195], v[220:221], v[194:195]
	v_pk_add_f32 v[218:219], v[226:227], v[216:217]
	v_pk_add_f32 v[216:217], v[224:225], v[214:215]
	v_cvt_pk_bf16_f32 v214, v194, v195
	v_cvt_pk_bf16_f32 v215, v196, v197
	v_and_b32_e32 v208, 64, v206
	v_cvt_pk_bf16_f32 v216, v216, v217
	v_cvt_pk_bf16_f32 v217, v218, v219
	v_lshlrev_b32_e32 v194, 16, v214
	v_and_b32_e32 v196, 0xffff0000, v214
	v_lshlrev_b32_e32 v218, 16, v215
	v_and_b32_e32 v220, 0xffff0000, v215
	v_lshlrev_b32_e32 v222, 16, v216
	v_and_b32_e32 v224, 0xffff0000, v216
	v_lshlrev_b32_e32 v226, 16, v217
	v_and_b32_e32 v228, 0xffff0000, v217
	v_mul_f32_e32 v195, v194, v194
	v_mul_f32_e32 v197, v196, v196
	v_mul_f32_e32 v219, v218, v218
	v_mul_f32_e32 v221, v220, v220
	v_mul_f32_e32 v223, v222, v222
	v_mul_f32_e32 v225, v224, v224
	v_mul_f32_e32 v227, v226, v226
	v_mul_f32_e32 v229, v228, v228
	v_pk_add_f32 v[194:195], v[194:195], v[196:197]
	v_pk_add_f32 v[196:197], v[218:219], v[220:221]
	v_pk_add_f32 v[218:219], v[226:227], v[228:229]
	v_pk_add_f32 v[194:195], v[194:195], v[196:197]
	v_pk_add_f32 v[196:197], v[222:223], v[224:225]
	v_xor_b32_e32 v207, 16, v206
	v_add_u32_e32 v208, 64, v208
	v_pk_add_f32 v[196:197], v[196:197], v[218:219]
	v_cmp_lt_i32_e32 vcc, v207, v208
	v_pk_add_f32 v[194:195], v[194:195], v[196:197]
	s_nop 0
	s_nop 0
	v_cndmask_b32_e32 v207, v206, v207, vcc
	v_mov_b32_dpp v196, v194 quad_perm:[1,0,3,2] row_mask:0xf bank_mask:0xf
	v_mov_b32_dpp v197, v195 quad_perm:[1,0,3,2] row_mask:0xf bank_mask:0xf
	v_lshlrev_b32_e32 v207, 2, v207
	v_pk_add_f32 v[194:195], v[194:195], v[196:197]
	ds_bpermute_b32 v196, v207, v194
	ds_bpermute_b32 v197, v207, v195
	v_xor_b32_e32 v218, 32, v206
	v_cmp_lt_i32_e32 vcc, v218, v208
	global_store_dwordx4 v164, v[214:217], s[16:17]
	s_waitcnt lgkmcnt(0)
	v_pk_add_f32 v[194:195], v[194:195], v[196:197]
	v_cndmask_b32_e32 v208, v206, v218, vcc
	v_lshlrev_b32_e32 v208, 2, v208
	ds_bpermute_b32 v196, v208, v194
	ds_bpermute_b32 v197, v208, v195
	s_and_saveexec_b64 s[56:57], s[12:13]
	s_waitcnt lgkmcnt(0)
	v_pk_add_f32 v[194:195], v[194:195], v[196:197]
	global_store_dwordx2 v[186:187], v[194:195], off

; __device__ __forceinline__ u32x4 pack8f(f32x4 a, f32x4 b) { u32x4 w; w.x = cvt_pk_bf16(a[0], a[1]); w.y = cvt_pk_bf16(a[2], a[3]); w.z = cvt_pk_bf16(b[0], b[1]); w.w = cvt_pk_bf16(b[2], b[3]); return w; }
;     __device__ __forceinline__ void operator()(const f32x4 (&acc)[2][2][4][2], const Unit& u, int wr, int wc, int fr, int fq, const EpiCtx& X) const {
;     ...
;             for (int m = 0; m < 4; ++m) {
;                 const int rl = ai * HALF + m * 16; const unsigned off = lo + (unsigned)(rl * 64) * 2u;
;                 const f32x4 o0a = acc[ai][0][m][0], o0b = acc[ai][0][m][1], o1a = acc[ai][1][m][0], o1b = acc[ai][1][m][1];
;                 const f32x4 ra_ = dpp_swap1(odd ? o0a : o1a), rb_ = dpp_swap1(odd ? o0b : o1b);
;                 const f32x4 pa[2] = {odd ? ra_ : o0a, odd ? o1a : ra_}, pb[2] = {odd ? rb_ : o0b, odd ? o1b : rb_};
; #pragma unroll
;                 for (int q = 0; q < 2; ++q) {
;                     const u32x4 w0 = raw[2 * m + q];
;                     const f32x4 r0 = (f32x4){bf_lo(w0.x), bf_hi(w0.x), bf_lo(w0.y), bf_hi(w0.y)}, r1 = (f32x4){bf_lo(w0.z), bf_hi(w0.z), bf_lo(w0.w), bf_hi(w0.w)};
;                     f32x4 y0, y1;
;                     if (RESN) { const f32x2 t = tbl[rl + q]; const float mu = t.x, ra = t.y * ALPHA; y0 = (r0 - mu) * ra * g0 + b0 + pa[q]; y1 = (r1 - mu) * ra * g1 + b1 + pb[q]; }
;                     else { y0 = r0 * ALPHA + pa[q]; y1 = r1 * ALPHA + pb[q]; }
;                     { const u32x4 w = pack8f(y0, y1); *(u32x4*)(xb + off + q * 128) = w;
;                         y0 = (f32x4){bf_lo(w.x), bf_hi(w.x), bf_lo(w.y), bf_hi(w.y)}; y1 = (f32x4){bf_lo(w.z), bf_hi(w.z), bf_lo(w.w), bf_hi(w.w)}; }
;                     float sa = ((y0[0] + y0[1]) + (y0[2] + y0[3])) + ((y1[0] + y1[1]) + (y1[2] + y1[3]));
;                     float sb = ((y0[0] * y0[0] + y0[1] * y0[1]) + (y0[2] * y0[2] + y0[3] * y0[3])) + ((y1[0] * y1[0] + y1[1] * y1[1]) + (y1[2] * y1[2] + y1[3] * y1[3]));
;                     sa += dpp_x1(sa);
;                     sb += dpp_x1(sb);
;                     sa += __shfl_xor(sa, 16); sa += __shfl_xor(sa, 32); sb += __shfl_xor(sb, 16); sb += __shfl_xor(sb, 32);
;                     if (fq == 0 && !odd) ps[(size_t)(rl + q) * 64] = (f32x2){sa, sb};
.LBB0_1701:
	s_or_b64 exec, exec, s[56:57]
	s_waitcnt lgkmcnt(1)
	v_cndmask_b32_e64 v122, v116, v108, s[6:7]
	s_nop 0
	v_cndmask_b32_e64 v121, v117, v109, s[6:7]
	s_waitcnt lgkmcnt(0)
	v_cndmask_b32_e64 v123, v118, v110, s[6:7]
	v_mov_b32_dpp v120, v122 quad_perm:[1,0,3,2] row_mask:0xf bank_mask:0xf
	s_nop 0
	v_cndmask_b32_e64 v124, v119, v111, s[6:7]
	v_cndmask_b32_e64 v126, v112, v104, s[6:7]
	v_mov_b32_dpp v122, v121 quad_perm:[1,0,3,2] row_mask:0xf bank_mask:0xf
	s_nop 0
	v_cndmask_b32_e64 v125, v113, v105, s[6:7]
	v_cndmask_b32_e64 v127, v114, v106, s[6:7]
	v_mov_b32_dpp v121, v123 quad_perm:[1,0,3,2] row_mask:0xf bank_mask:0xf
	s_nop 0
	v_cndmask_b32_e64 v152, v115, v107, s[6:7]
	s_waitcnt vmcnt(13)
	v_and_b32_e32 v153, 0xffff0000, v148
	v_mov_b32_dpp v123, v124 quad_perm:[1,0,3,2] row_mask:0xf bank_mask:0xf
	s_nop 0
	v_lshlrev_b32_e32 v154, 16, v149
	v_and_b32_e32 v155, 0xffff0000, v149
	v_mov_b32_dpp v124, v126 quad_perm:[1,0,3,2] row_mask:0xf bank_mask:0xf
	s_nop 0
	v_lshlrev_b32_e32 v189, 16, v150
	v_and_b32_e32 v191, 0xffff0000, v150
	v_mov_b32_dpp v126, v125 quad_perm:[1,0,3,2] row_mask:0xf bank_mask:0xf
	s_nop 0
	v_lshlrev_b32_e32 v193, 16, v151
	v_and_b32_e32 v151, 0xffff0000, v151
	v_mov_b32_dpp v125, v127 quad_perm:[1,0,3,2] row_mask:0xf bank_mask:0xf
	s_nop 0
	v_cndmask_b32_e64 v117, v122, v117, s[6:7]
	v_cndmask_b32_e64 v116, v120, v116, s[6:7]
	v_mov_b32_dpp v127, v152 quad_perm:[1,0,3,2] row_mask:0xf bank_mask:0xf
	v_lshlrev_b32_e32 v152, 16, v148
	ds_read_b64 v[148:149], v201 offset:128
	v_cndmask_b32_e64 v119, v123, v119, s[6:7]
	v_cndmask_b32_e64 v118, v121, v118, s[6:7]
	v_cndmask_b32_e64 v113, v126, v113, s[6:7]
	v_cndmask_b32_e64 v112, v124, v112, s[6:7]
	s_waitcnt lgkmcnt(0)
	v_mul_f32_e32 v150, 0x3fb504f3, v149
	v_sub_f32_e32 v153, v153, v148
	v_sub_f32_e32 v152, v152, v148
	v_pk_mul_f32 v[152:153], v[152:153], v[150:151] op_sel_hi:[1,0]
	v_sub_f32_e32 v155, v155, v148
	v_pk_fma_f32 v[152:153], v[76:77], v[152:153], v[184:185]
	v_sub_f32_e32 v154, v154, v148
	v_pk_add_f32 v[116:117], v[116:117], v[152:153]
	v_sub_f32_e32 v153, v191, v148
	v_sub_f32_e32 v152, v189, v148
	v_sub_f32_e32 v149, v151, v148
	v_sub_f32_e32 v148, v193, v148
	v_pk_mul_f32 v[154:155], v[154:155], v[150:151] op_sel_hi:[1,0]
	v_pk_mul_f32 v[148:149], v[148:149], v[150:151] op_sel_hi:[1,0]
	v_pk_mul_f32 v[150:151], v[152:153], v[150:151] op_sel_hi:[1,0]
	v_cndmask_b32_e64 v115, v127, v115, s[6:7]
	v_cndmask_b32_e64 v114, v125, v114, s[6:7]
	v_pk_fma_f32 v[154:155], v[78:79], v[154:155], v[182:183]
	v_pk_fma_f32 v[150:151], v[72:73], v[150:151], v[180:181]
	v_pk_fma_f32 v[148:149], v[74:75], v[148:149], v[178:179]
	v_pk_add_f32 v[118:119], v[118:119], v[154:155]
	v_pk_add_f32 v[114:115], v[114:115], v[148:149]
	v_pk_add_f32 v[112:113], v[112:113], v[150:151]
	v_cvt_pk_bf16_f32 v148, v116, v117
	v_cvt_pk_bf16_f32 v149, v118, v119
	v_mov_b32_e32 v193, v165
	v_cvt_pk_bf16_f32 v150, v112, v113
	v_cvt_pk_bf16_f32 v151, v114, v115
	v_lshlrev_b32_e32 v112, 16, v148
	v_and_b32_e32 v114, 0xffff0000, v148
	v_lshlrev_b32_e32 v116, 16, v149
	v_and_b32_e32 v118, 0xffff0000, v149
	v_lshlrev_b32_e32 v152, 16, v150
	v_and_b32_e32 v154, 0xffff0000, v150
	v_lshlrev_b32_e32 v194, 16, v151
	v_and_b32_e32 v196, 0xffff0000, v151
	v_mul_f32_e32 v113, v112, v112
	v_mul_f32_e32 v115, v114, v114
	v_mul_f32_e32 v117, v116, v116
	v_mul_f32_e32 v119, v118, v118
	v_mul_f32_e32 v153, v152, v152
	v_mul_f32_e32 v155, v154, v154
	v_mul_f32_e32 v195, v194, v194
	v_mul_f32_e32 v197, v196, v196
	v_pk_add_f32 v[112:113], v[112:113], v[114:115]
	v_pk_add_f32 v[114:115], v[116:117], v[118:119]
	v_pk_add_f32 v[116:117], v[194:195], v[196:197]
	v_pk_add_f32 v[112:113], v[112:113], v[114:115]
	v_pk_add_f32 v[114:115], v[152:153], v[154:155]
	s_nop 0
	v_pk_add_f32 v[114:115], v[114:115], v[116:117]
	s_nop 0
	v_pk_add_f32 v[112:113], v[112:113], v[114:115]
	v_mov_b32_e32 v114, v165
	v_mov_b32_e32 v115, v165
	s_nop 0
	v_mov_b32_dpp v114, v112 quad_perm:[1,0,3,2] row_mask:0xf bank_mask:0xf
	v_mov_b32_dpp v115, v113 quad_perm:[1,0,3,2] row_mask:0xf bank_mask:0xf
	v_pk_add_f32 v[112:113], v[112:113], v[114:115]
	ds_bpermute_b32 v114, v207, v112
	ds_bpermute_b32 v115, v207, v113
	s_waitcnt lgkmcnt(0)
	v_pk_add_f32 v[114:115], v[112:113], v[114:115]
	ds_bpermute_b32 v116, v208, v114
	ds_bpermute_b32 v117, v208, v115
	v_lshl_add_u64 v[112:113], s[16:17], 0, v[192:193]
	global_store_dwordx4 v[112:113], v[148:151], off
	s_and_saveexec_b64 s[56:57], s[12:13]
	s_waitcnt lgkmcnt(0)
	v_pk_add_f32 v[114:115], v[114:115], v[116:117]
	v_add_co_u32_e32 v116, vcc, 0x2000, v186
	s_nop 1
	v_addc_co_u32_e32 v117, vcc, 0, v187, vcc
	global_store_dwordx2 v[116:117], v[114:115], off

; __device__ __forceinline__ u32x4 pack8f(f32x4 a, f32x4 b) { u32x4 w; w.x = cvt_pk_bf16(a[0], a[1]); w.y = cvt_pk_bf16(a[2], a[3]); w.z = cvt_pk_bf16(b[0], b[1]); w.w = cvt_pk_bf16(b[2], b[3]); return w; }
;     __device__ __forceinline__ void operator()(const f32x4 (&acc)[2][2][4][2], const Unit& u, int wr, int wc, int fr, int fq, const EpiCtx& X) const {
;     ...
;             for (int m = 0; m < 4; ++m) {
;                 const int rl = ai * HALF + m * 16; const unsigned off = lo + (unsigned)(rl * 64) * 2u;
;                 const f32x4 o0a = acc[ai][0][m][0], o0b = acc[ai][0][m][1], o1a = acc[ai][1][m][0], o1b = acc[ai][1][m][1];
;                 const f32x4 ra_ = dpp_swap1(odd ? o0a : o1a), rb_ = dpp_swap1(odd ? o0b : o1b);
;                 const f32x4 pa[2] = {odd ? ra_ : o0a, odd ? o1a : ra_}, pb[2] = {odd ? rb_ : o0b, odd ? o1b : rb_};
; #pragma unroll
;                 for (int q = 0; q < 2; ++q) {
;                     const u32x4 w0 = raw[2 * m + q];
;                     const f32x4 r0 = (f32x4){bf_lo(w0.x), bf_hi(w0.x), bf_lo(w0.y), bf_hi(w0.y)}, r1 = (f32x4){bf_lo(w0.z), bf_hi(w0.z), bf_lo(w0.w), bf_hi(w0.w)};
;                     f32x4 y0, y1;
;                     if (RESN) { const f32x2 t = tbl[rl + q]; const float mu = t.x, ra = t.y * ALPHA; y0 = (r0 - mu) * ra * g0 + b0 + pa[q]; y1 = (r1 - mu) * ra * g1 + b1 + pb[q]; }
;                     else { y0 = r0 * ALPHA + pa[q]; y1 = r1 * ALPHA + pb[q]; }
;                     { const u32x4 w = pack8f(y0, y1); *(u32x4*)(xb + off + q * 128) = w;
;                         y0 = (f32x4){bf_lo(w.x), bf_hi(w.x), bf_lo(w.y), bf_hi(w.y)}; y1 = (f32x4){bf_lo(w.z), bf_hi(w.z), bf_lo(w.w), bf_hi(w.w)}; }
;                     float sa = ((y0[0] + y0[1]) + (y0[2] + y0[3])) + ((y1[0] + y1[1]) + (y1[2] + y1[3]));
;                     float sb = ((y0[0] * y0[0] + y0[1] * y0[1]) + (y0[2] * y0[2] + y0[3] * y0[3])) + ((y1[0] * y1[0] + y1[1] * y1[1]) + (y1[2] * y1[2] + y1[3] * y1[3]));
;                     sa += dpp_x1(sa);
;                     sb += dpp_x1(sb);
;                     sa += __shfl_xor(sa, 16); sa += __shfl_xor(sa, 32); sb += __shfl_xor(sb, 16); sb += __shfl_xor(sb, 32);
;                     if (fq == 0 && !odd) ps[(size_t)(rl + q) * 64] = (f32x2){sa, sb};
.LBB0_1705:
	s_or_b64 exec, exec, s[56:57]
	s_waitcnt lgkmcnt(1)
	v_cndmask_b32_e64 v106, v100, v92, s[6:7]
	s_nop 0
	v_cndmask_b32_e64 v105, v101, v93, s[6:7]
	s_waitcnt lgkmcnt(0)
	v_cndmask_b32_e64 v107, v102, v94, s[6:7]
	v_mov_b32_dpp v104, v106 quad_perm:[1,0,3,2] row_mask:0xf bank_mask:0xf
	s_nop 0
	v_cndmask_b32_e64 v108, v103, v95, s[6:7]
	v_cndmask_b32_e64 v110, v96, v88, s[6:7]
	v_mov_b32_dpp v106, v105 quad_perm:[1,0,3,2] row_mask:0xf bank_mask:0xf
	s_nop 0
	v_cndmask_b32_e64 v109, v97, v89, s[6:7]
	v_cndmask_b32_e64 v111, v98, v90, s[6:7]
	v_mov_b32_dpp v105, v107 quad_perm:[1,0,3,2] row_mask:0xf bank_mask:0xf
	s_nop 0
	v_cndmask_b32_e64 v112, v99, v91, s[6:7]
	s_waitcnt vmcnt(15)
	v_lshlrev_b32_e32 v115, 16, v140
	v_mov_b32_dpp v107, v108 quad_perm:[1,0,3,2] row_mask:0xf bank_mask:0xf
	s_nop 0
	v_and_b32_e32 v116, 0xffff0000, v140
	v_cndmask_b32_e64 v101, v106, v101, s[6:7]
	v_mov_b32_dpp v108, v110 quad_perm:[1,0,3,2] row_mask:0xf bank_mask:0xf
	s_nop 0
	v_cndmask_b32_e64 v100, v104, v100, s[6:7]
	v_lshlrev_b32_e32 v118, 16, v141
	v_mov_b32_dpp v110, v109 quad_perm:[1,0,3,2] row_mask:0xf bank_mask:0xf
	s_nop 0
	v_and_b32_e32 v119, 0xffff0000, v141
	v_lshlrev_b32_e32 v120, 16, v142
	v_mov_b32_dpp v109, v111 quad_perm:[1,0,3,2] row_mask:0xf bank_mask:0xf
	s_nop 0
	v_and_b32_e32 v121, 0xffff0000, v142
	v_lshlrev_b32_e32 v122, 16, v143
	v_mov_b32_dpp v111, v112 quad_perm:[1,0,3,2] row_mask:0xf bank_mask:0xf
	ds_read_b64 v[112:113], v201 offset:256
	v_and_b32_e32 v123, 0xffff0000, v143
	v_cndmask_b32_e64 v103, v107, v103, s[6:7]
	v_cndmask_b32_e64 v102, v105, v102, s[6:7]
	v_cndmask_b32_e64 v97, v110, v97, s[6:7]
	s_waitcnt lgkmcnt(0)
	v_mul_f32_e32 v114, 0x3fb504f3, v113
	v_sub_f32_e32 v117, v116, v112
	v_sub_f32_e32 v116, v115, v112
	v_pk_mul_f32 v[116:117], v[116:117], v[114:115] op_sel_hi:[1,0]
	v_sub_f32_e32 v119, v119, v112
	v_pk_fma_f32 v[116:117], v[76:77], v[116:117], v[184:185]
	v_sub_f32_e32 v118, v118, v112
	v_pk_add_f32 v[100:101], v[100:101], v[116:117]
	v_sub_f32_e32 v117, v121, v112
	v_sub_f32_e32 v116, v120, v112
	v_sub_f32_e32 v113, v123, v112
	v_sub_f32_e32 v112, v122, v112
	v_pk_mul_f32 v[118:119], v[118:119], v[114:115] op_sel_hi:[1,0]
	v_pk_mul_f32 v[112:113], v[112:113], v[114:115] op_sel_hi:[1,0]
	v_pk_mul_f32 v[114:115], v[116:117], v[114:115] op_sel_hi:[1,0]
	v_cndmask_b32_e64 v96, v108, v96, s[6:7]
	v_cndmask_b32_e64 v99, v111, v99, s[6:7]
	v_cndmask_b32_e64 v98, v109, v98, s[6:7]
	v_pk_fma_f32 v[118:119], v[78:79], v[118:119], v[182:183]
	v_pk_fma_f32 v[114:115], v[72:73], v[114:115], v[180:181]
	v_pk_fma_f32 v[112:113], v[74:75], v[112:113], v[178:179]
	v_pk_add_f32 v[102:103], v[102:103], v[118:119]
	v_pk_add_f32 v[98:99], v[98:99], v[112:113]
	v_pk_add_f32 v[96:97], v[96:97], v[114:115]
	v_cvt_pk_bf16_f32 v112, v100, v101
	v_cvt_pk_bf16_f32 v113, v102, v103
	v_mov_b32_e32 v191, v165
	v_cvt_pk_bf16_f32 v114, v96, v97
	v_cvt_pk_bf16_f32 v115, v98, v99
	v_lshlrev_b32_e32 v96, 16, v112
	v_and_b32_e32 v98, 0xffff0000, v112
	v_lshlrev_b32_e32 v100, 16, v113
	v_and_b32_e32 v102, 0xffff0000, v113
	v_lshlrev_b32_e32 v116, 16, v114
	v_and_b32_e32 v118, 0xffff0000, v114
	v_lshlrev_b32_e32 v120, 16, v115
	v_and_b32_e32 v122, 0xffff0000, v115
	v_mul_f32_e32 v97, v96, v96
	v_mul_f32_e32 v99, v98, v98
	v_mul_f32_e32 v101, v100, v100
	v_mul_f32_e32 v103, v102, v102
	v_mul_f32_e32 v117, v116, v116
	v_mul_f32_e32 v119, v118, v118
	v_mul_f32_e32 v121, v120, v120
	v_mul_f32_e32 v123, v122, v122
	v_pk_add_f32 v[96:97], v[96:97], v[98:99]
	v_pk_add_f32 v[98:99], v[100:101], v[102:103]
	v_pk_add_f32 v[100:101], v[120:121], v[122:123]
	v_pk_add_f32 v[96:97], v[96:97], v[98:99]
	v_pk_add_f32 v[98:99], v[116:117], v[118:119]
	s_nop 0
	v_pk_add_f32 v[98:99], v[98:99], v[100:101]
	s_nop 0
	v_pk_add_f32 v[96:97], v[96:97], v[98:99]
	v_mov_b32_e32 v98, v165
	v_mov_b32_e32 v99, v165
	s_nop 0
	v_mov_b32_dpp v98, v96 quad_perm:[1,0,3,2] row_mask:0xf bank_mask:0xf
	v_mov_b32_dpp v99, v97 quad_perm:[1,0,3,2] row_mask:0xf bank_mask:0xf
	v_pk_add_f32 v[96:97], v[96:97], v[98:99]
	ds_bpermute_b32 v98, v207, v96
	ds_bpermute_b32 v99, v207, v97
	s_waitcnt lgkmcnt(0)
	v_pk_add_f32 v[98:99], v[96:97], v[98:99]
	ds_bpermute_b32 v100, v208, v98
	ds_bpermute_b32 v101, v208, v99
	v_lshl_add_u64 v[96:97], s[16:17], 0, v[190:191]
	global_store_dwordx4 v[96:97], v[112:115], off
	s_and_saveexec_b64 s[56:57], s[12:13]
	s_waitcnt lgkmcnt(0)
	v_pk_add_f32 v[98:99], v[98:99], v[100:101]
	v_add_co_u32_e32 v100, vcc, 0x4000, v186
	s_nop 1
	v_addc_co_u32_e32 v101, vcc, 0, v187, vcc
	global_store_dwordx2 v[100:101], v[98:99], off

; __device__ __forceinline__ u32x4 pack8f(f32x4 a, f32x4 b) { u32x4 w; w.x = cvt_pk_bf16(a[0], a[1]); w.y = cvt_pk_bf16(a[2], a[3]); w.z = cvt_pk_bf16(b[0], b[1]); w.w = cvt_pk_bf16(b[2], b[3]); return w; }
;     __device__ __forceinline__ void operator()(const f32x4 (&acc)[2][2][4][2], const Unit& u, int wr, int wc, int fr, int fq, const EpiCtx& X) const {
;     ...
;             for (int m = 0; m < 4; ++m) {
;                 const int rl = ai * HALF + m * 16; const unsigned off = lo + (unsigned)(rl * 64) * 2u;
;                 const f32x4 o0a = acc[ai][0][m][0], o0b = acc[ai][0][m][1], o1a = acc[ai][1][m][0], o1b = acc[ai][1][m][1];
;                 const f32x4 ra_ = dpp_swap1(odd ? o0a : o1a), rb_ = dpp_swap1(odd ? o0b : o1b);
;                 const f32x4 pa[2] = {odd ? ra_ : o0a, odd ? o1a : ra_}, pb[2] = {odd ? rb_ : o0b, odd ? o1b : rb_};
; #pragma unroll
;                 for (int q = 0; q < 2; ++q) {
;                     const u32x4 w0 = raw[2 * m + q];
;                     const f32x4 r0 = (f32x4){bf_lo(w0.x), bf_hi(w0.x), bf_lo(w0.y), bf_hi(w0.y)}, r1 = (f32x4){bf_lo(w0.z), bf_hi(w0.z), bf_lo(w0.w), bf_hi(w0.w)};
;                     f32x4 y0, y1;
;                     if (RESN) { const f32x2 t = tbl[rl + q]; const float mu = t.x, ra = t.y * ALPHA; y0 = (r0 - mu) * ra * g0 + b0 + pa[q]; y1 = (r1 - mu) * ra * g1 + b1 + pb[q]; }
;                     else { y0 = r0 * ALPHA + pa[q]; y1 = r1 * ALPHA + pb[q]; }
;                     { const u32x4 w = pack8f(y0, y1); *(u32x4*)(xb + off + q * 128) = w;
;                         y0 = (f32x4){bf_lo(w.x), bf_hi(w.x), bf_lo(w.y), bf_hi(w.y)}; y1 = (f32x4){bf_lo(w.z), bf_hi(w.z), bf_lo(w.w), bf_hi(w.w)}; }
;                     float sa = ((y0[0] + y0[1]) + (y0[2] + y0[3])) + ((y1[0] + y1[1]) + (y1[2] + y1[3]));
;                     float sb = ((y0[0] * y0[0] + y0[1] * y0[1]) + (y0[2] * y0[2] + y0[3] * y0[3])) + ((y1[0] * y1[0] + y1[1] * y1[1]) + (y1[2] * y1[2] + y1[3] * y1[3]));
;                     sa += dpp_x1(sa);
;                     sb += dpp_x1(sb);
;                     sa += __shfl_xor(sa, 16); sa += __shfl_xor(sa, 32); sb += __shfl_xor(sb, 16); sb += __shfl_xor(sb, 32);
;                     if (fq == 0 && !odd) ps[(size_t)(rl + q) * 64] = (f32x2){sa, sb};
.LBB0_1709:
	s_or_b64 exec, exec, s[56:57]
	s_waitcnt lgkmcnt(1)
	v_cndmask_b32_e64 v90, v84, v68, s[6:7]
	s_nop 0
	v_cndmask_b32_e64 v89, v85, v69, s[6:7]
	s_waitcnt lgkmcnt(0)
	v_cndmask_b32_e64 v91, v86, v70, s[6:7]
	v_mov_b32_dpp v88, v90 quad_perm:[1,0,3,2] row_mask:0xf bank_mask:0xf
	s_nop 0
	v_cndmask_b32_e64 v92, v87, v71, s[6:7]
	v_cndmask_b32_e64 v94, v80, v64, s[6:7]
	v_mov_b32_dpp v90, v89 quad_perm:[1,0,3,2] row_mask:0xf bank_mask:0xf
	s_nop 0
	v_cndmask_b32_e64 v93, v81, v65, s[6:7]
	v_cndmask_b32_e64 v95, v82, v66, s[6:7]
	v_mov_b32_dpp v89, v91 quad_perm:[1,0,3,2] row_mask:0xf bank_mask:0xf
	s_nop 0
	v_cndmask_b32_e64 v96, v83, v67, s[6:7]
	s_waitcnt vmcnt(17)
	v_lshlrev_b32_e32 v99, 16, v132
	v_mov_b32_dpp v91, v92 quad_perm:[1,0,3,2] row_mask:0xf bank_mask:0xf
	s_nop 0
	v_and_b32_e32 v100, 0xffff0000, v132
	v_cndmask_b32_e64 v85, v90, v85, s[6:7]
	v_mov_b32_dpp v92, v94 quad_perm:[1,0,3,2] row_mask:0xf bank_mask:0xf
	s_nop 0
	v_cndmask_b32_e64 v84, v88, v84, s[6:7]
	v_lshlrev_b32_e32 v102, 16, v133
	v_mov_b32_dpp v94, v93 quad_perm:[1,0,3,2] row_mask:0xf bank_mask:0xf
	s_nop 0
	v_and_b32_e32 v103, 0xffff0000, v133
	v_lshlrev_b32_e32 v104, 16, v134
	v_mov_b32_dpp v93, v95 quad_perm:[1,0,3,2] row_mask:0xf bank_mask:0xf
	s_nop 0
	v_and_b32_e32 v105, 0xffff0000, v134
	v_lshlrev_b32_e32 v106, 16, v135
	v_mov_b32_dpp v95, v96 quad_perm:[1,0,3,2] row_mask:0xf bank_mask:0xf
	ds_read_b64 v[96:97], v201 offset:384
	v_and_b32_e32 v107, 0xffff0000, v135
	v_cndmask_b32_e64 v87, v91, v87, s[6:7]
	v_cndmask_b32_e64 v86, v89, v86, s[6:7]
	v_cndmask_b32_e64 v81, v94, v81, s[6:7]
	s_waitcnt lgkmcnt(0)
	v_mul_f32_e32 v98, 0x3fb504f3, v97
	v_sub_f32_e32 v101, v100, v96
	v_sub_f32_e32 v100, v99, v96
	v_pk_mul_f32 v[100:101], v[100:101], v[98:99] op_sel_hi:[1,0]
	v_sub_f32_e32 v103, v103, v96
	v_pk_fma_f32 v[100:101], v[76:77], v[100:101], v[184:185]
	v_sub_f32_e32 v102, v102, v96
	v_pk_add_f32 v[84:85], v[84:85], v[100:101]
	v_sub_f32_e32 v101, v105, v96
	v_sub_f32_e32 v100, v104, v96
	v_sub_f32_e32 v97, v107, v96
	v_sub_f32_e32 v96, v106, v96
	v_pk_mul_f32 v[102:103], v[102:103], v[98:99] op_sel_hi:[1,0]
	v_pk_mul_f32 v[96:97], v[96:97], v[98:99] op_sel_hi:[1,0]
	v_pk_mul_f32 v[98:99], v[100:101], v[98:99] op_sel_hi:[1,0]
	v_cndmask_b32_e64 v80, v92, v80, s[6:7]
	v_cndmask_b32_e64 v83, v95, v83, s[6:7]
	v_cndmask_b32_e64 v82, v93, v82, s[6:7]
	v_pk_fma_f32 v[102:103], v[78:79], v[102:103], v[182:183]
	v_pk_fma_f32 v[98:99], v[72:73], v[98:99], v[180:181]
	v_pk_fma_f32 v[96:97], v[74:75], v[96:97], v[178:179]
	v_pk_add_f32 v[86:87], v[86:87], v[102:103]
	v_pk_add_f32 v[82:83], v[82:83], v[96:97]
	v_pk_add_f32 v[80:81], v[80:81], v[98:99]
	v_cvt_pk_bf16_f32 v96, v84, v85
	v_cvt_pk_bf16_f32 v97, v86, v87
	v_mov_b32_e32 v189, v165
	v_cvt_pk_bf16_f32 v98, v80, v81
	v_cvt_pk_bf16_f32 v99, v82, v83
	v_lshlrev_b32_e32 v80, 16, v96
	v_and_b32_e32 v82, 0xffff0000, v96
	v_lshlrev_b32_e32 v84, 16, v97
	v_and_b32_e32 v86, 0xffff0000, v97
	v_lshlrev_b32_e32 v100, 16, v98
	v_and_b32_e32 v102, 0xffff0000, v98
	v_lshlrev_b32_e32 v104, 16, v99
	v_and_b32_e32 v106, 0xffff0000, v99
	v_mul_f32_e32 v81, v80, v80
	v_mul_f32_e32 v83, v82, v82
	v_mul_f32_e32 v85, v84, v84
	v_mul_f32_e32 v87, v86, v86
	v_mul_f32_e32 v101, v100, v100
	v_mul_f32_e32 v103, v102, v102
	v_mul_f32_e32 v105, v104, v104
	v_mul_f32_e32 v107, v106, v106
	v_pk_add_f32 v[80:81], v[80:81], v[82:83]
	v_pk_add_f32 v[82:83], v[84:85], v[86:87]
	v_pk_add_f32 v[84:85], v[104:105], v[106:107]
	v_pk_add_f32 v[80:81], v[80:81], v[82:83]
	v_pk_add_f32 v[82:83], v[100:101], v[102:103]
	s_nop 0
	v_pk_add_f32 v[82:83], v[82:83], v[84:85]
	s_nop 0
	v_pk_add_f32 v[80:81], v[80:81], v[82:83]
	v_mov_b32_e32 v82, v165
	v_mov_b32_e32 v83, v165
	s_nop 0
	v_mov_b32_dpp v82, v80 quad_perm:[1,0,3,2] row_mask:0xf bank_mask:0xf
	v_mov_b32_dpp v83, v81 quad_perm:[1,0,3,2] row_mask:0xf bank_mask:0xf
	v_pk_add_f32 v[80:81], v[80:81], v[82:83]
	ds_bpermute_b32 v82, v207, v80
	ds_bpermute_b32 v83, v207, v81
	s_waitcnt lgkmcnt(0)
	v_pk_add_f32 v[82:83], v[80:81], v[82:83]
	ds_bpermute_b32 v84, v208, v82
	ds_bpermute_b32 v85, v208, v83
	v_lshl_add_u64 v[80:81], s[16:17], 0, v[188:189]
	global_store_dwordx4 v[80:81], v[96:99], off
	s_and_saveexec_b64 s[56:57], s[12:13]
	s_waitcnt lgkmcnt(0)
	v_pk_add_f32 v[82:83], v[82:83], v[84:85]
	v_add_co_u32_e32 v84, vcc, 0x6000, v186
	s_nop 1
	v_addc_co_u32_e32 v85, vcc, 0, v187, vcc
	global_store_dwordx2 v[84:85], v[82:83], off

;     __device__ __forceinline__ void operator()(const f32x4 (&acc)[2][2][4][2], const Unit& u, int wr, int wc, int fr, int fq, const EpiCtx& X) const {
;     ...
;         for (int ai = 0; ai < 2; ++ai) {
;             u32x4 raw[8];
; #pragma unroll
;             for (int m = 0; m < 4; ++m) { const unsigned off = lo + (unsigned)((ai * HALF + m * 16) * 64) * 2u; raw[2 * m] = *(const u32x4*)(xb + off); raw[2 * m + 1] = *(const u32x4*)(xb + off + 128); }
; #pragma unroll
;             for (int m = 0; m < 4; ++m) {
;                 const int rl = ai * HALF + m * 16; const unsigned off = lo + (unsigned)(rl * 64) * 2u;
;                 const f32x4 o0a = acc[ai][0][m][0], o0b = acc[ai][0][m][1], o1a = acc[ai][1][m][0], o1b = acc[ai][1][m][1];
;                 const f32x4 ra_ = dpp_swap1(odd ? o0a : o1a), rb_ = dpp_swap1(odd ? o0b : o1b);
;                 const f32x4 pa[2] = {odd ? ra_ : o0a, odd ? o1a : ra_}, pb[2] = {odd ? rb_ : o0b, odd ? o1b : rb_};
; #pragma unroll
;                 for (int q = 0; q < 2; ++q) {
;                     const u32x4 w0 = raw[2 * m + q];
;                     const f32x4 r0 = (f32x4){bf_lo(w0.x), bf_hi(w0.x), bf_lo(w0.y), bf_hi(w0.y)}, r1 = (f32x4){bf_lo(w0.z), bf_hi(w0.z), bf_lo(w0.w), bf_hi(w0.w)};
;                     f32x4 y0, y1;
;                     if (RESN) { const f32x2 t = tbl[rl + q]; const float mu = t.x, ra = t.y * ALPHA; y0 = (r0 - mu) * ra * g0 + b0 + pa[q]; y1 = (r1 - mu) * ra * g1 + b1 + pb[q]; }
;                     else { y0 = r0 * ALPHA + pa[q]; y1 = r1 * ALPHA + pb[q]; }
;                     { const u32x4 w = pack8f(y0, y1); *(u32x4*)(xb + off + q * 128) = w;
;                         y0 = (f32x4){bf_lo(w.x), bf_hi(w.x), bf_lo(w.y), bf_hi(w.y)}; y1 = (f32x4){bf_lo(w.z), bf_hi(w.z), bf_lo(w.w), bf_hi(w.w)}; }
;                     float sa = ((y0[0] + y0[1]) + (y0[2] + y0[3])) + ((y1[0] + y1[1]) + (y1[2] + y1[3]));
;                     float sb = ((y0[0] * y0[0] + y0[1] * y0[1]) + (y0[2] * y0[2] + y0[3] * y0[3])) + ((y1[0] * y1[0] + y1[1] * y1[1]) + (y1[2] * y1[2] + y1[3] * y1[3]));
;                     sa += dpp_x1(sa);
;                     sb += dpp_x1(sb);
;                     sa += __shfl_xor(sa, 16); sa += __shfl_xor(sa, 32); sb += __shfl_xor(sb, 16); sb += __shfl_xor(sb, 32);
;                     if (fq == 0 && !odd) ps[(size_t)(rl + q) * 64] = (f32x2){sa, sb};
.LBB0_1713:
	s_or_b64 exec, exec, s[56:57]
	v_add_u32_e32 v104, 0x4000, v164
	s_waitcnt vmcnt(16)
	v_mov_b32_e32 v112, v230
	v_mov_b32_e32 v113, v231
	v_mov_b32_e32 v114, v232
	v_mov_b32_e32 v115, v233
	v_add_u32_e32 v102, 0x4800, v164
	v_add_u32_e32 v100, 0x5000, v164
	v_add_u32_e32 v164, 0x5800, v164
	v_mov_b32_e32 v96, v234
	v_mov_b32_e32 v97, v235
	v_mov_b32_e32 v98, v236
	v_mov_b32_e32 v99, v237
	v_mov_b32_e32 v92, v238
	v_mov_b32_e32 v93, v239
	v_mov_b32_e32 v94, v240
	v_mov_b32_e32 v95, v241
	v_mov_b32_e32 v88, v242
	v_mov_b32_e32 v89, v243
	v_mov_b32_e32 v90, v244
	v_mov_b32_e32 v91, v245
	global_load_dwordx4 v[84:87], v100, s[16:17]
	global_load_dwordx4 v[80:83], v100, s[16:17] offset:128
	global_load_dwordx4 v[68:71], v164, s[16:17]
	s_waitcnt lgkmcnt(0)
	global_load_dwordx4 v[64:67], v164, s[16:17] offset:128
	v_cndmask_b32_e64 v116, v62, v54, s[6:7]
	v_cndmask_b32_e64 v117, v61, v53, s[6:7]
	s_nop 0
	s_nop 0
	v_cndmask_b32_e64 v111, v63, v55, s[6:7]
	v_mov_b32_dpp v105, v117 quad_perm:[1,0,3,2] row_mask:0xf bank_mask:0xf
	v_mov_b32_dpp v103, v116 quad_perm:[1,0,3,2] row_mask:0xf bank_mask:0xf
	ds_read_b64 v[116:117], v201 offset:1024
	v_cndmask_b32_e64 v118, v60, v52, s[6:7]
	s_nop 0
	s_nop 0
	v_cndmask_b32_e64 v119, v59, v51, s[6:7]
	v_cndmask_b32_e64 v120, v58, v50, s[6:7]
	v_cndmask_b32_e64 v121, v57, v49, s[6:7]
	v_cndmask_b32_e64 v122, v56, v48, s[6:7]
	s_nop 0
	s_nop 0
	s_nop 0
	s_nop 0
	v_mov_b32_dpp v101, v118 quad_perm:[1,0,3,2] row_mask:0xf bank_mask:0xf
	v_mov_b32_dpp v106, v111 quad_perm:[1,0,3,2] row_mask:0xf bank_mask:0xf
	v_mov_b32_dpp v107, v122 quad_perm:[1,0,3,2] row_mask:0xf bank_mask:0xf
	v_mov_b32_dpp v109, v121 quad_perm:[1,0,3,2] row_mask:0xf bank_mask:0xf
	v_mov_b32_dpp v108, v120 quad_perm:[1,0,3,2] row_mask:0xf bank_mask:0xf
	v_mov_b32_dpp v110, v119 quad_perm:[1,0,3,2] row_mask:0xf bank_mask:0xf
	s_waitcnt lgkmcnt(0)
	v_mul_f32_e32 v118, 0x3fb504f3, v117
	v_cndmask_b32_e64 v61, v105, v61, s[6:7]
	v_cndmask_b32_e64 v60, v101, v60, s[6:7]
	v_cndmask_b32_e64 v63, v106, v63, s[6:7]
	v_cndmask_b32_e64 v62, v103, v62, s[6:7]
	v_cndmask_b32_e64 v57, v109, v57, s[6:7]
	v_cndmask_b32_e64 v56, v107, v56, s[6:7]
	v_cndmask_b32_e64 v59, v110, v59, s[6:7]
	v_cndmask_b32_e64 v58, v108, v58, s[6:7]
	v_lshlrev_b32_e32 v111, 16, v112
	v_and_b32_e32 v112, 0xffff0000, v112
	v_lshlrev_b32_e32 v117, 16, v113
	v_and_b32_e32 v119, 0xffff0000, v113
	v_lshlrev_b32_e32 v120, 16, v114
	v_and_b32_e32 v121, 0xffff0000, v114
	v_lshlrev_b32_e32 v122, 16, v115
	v_and_b32_e32 v123, 0xffff0000, v115
	v_sub_f32_e32 v113, v112, v116
	v_sub_f32_e32 v112, v111, v116
	v_sub_f32_e32 v115, v119, v116
	v_sub_f32_e32 v114, v117, v116
	v_sub_f32_e32 v121, v121, v116
	v_sub_f32_e32 v120, v120, v116
	v_sub_f32_e32 v117, v123, v116
	v_sub_f32_e32 v116, v122, v116
	v_pk_mul_f32 v[114:115], v[114:115], v[118:119] op_sel_hi:[1,0]
	v_pk_mul_f32 v[112:113], v[112:113], v[118:119] op_sel_hi:[1,0]
	v_pk_mul_f32 v[116:117], v[116:117], v[118:119] op_sel_hi:[1,0]
	v_pk_mul_f32 v[118:119], v[120:121], v[118:119] op_sel_hi:[1,0]
	v_pk_fma_f32 v[112:113], v[76:77], v[112:113], v[184:185]
	v_pk_fma_f32 v[114:115], v[78:79], v[114:115], v[182:183]
	v_pk_fma_f32 v[118:119], v[72:73], v[118:119], v[180:181]
	v_pk_fma_f32 v[116:117], v[74:75], v[116:117], v[178:179]
	v_pk_add_f32 v[62:63], v[62:63], v[114:115]
	v_pk_add_f32 v[60:61], v[60:61], v[112:113]
	v_pk_add_f32 v[58:59], v[58:59], v[116:117]
	v_pk_add_f32 v[56:57], v[56:57], v[118:119]
	v_cvt_pk_bf16_f32 v60, v60, v61
	v_cvt_pk_bf16_f32 v61, v62, v63
	s_nop 0
	v_cvt_pk_bf16_f32 v62, v56, v57
	v_cvt_pk_bf16_f32 v63, v58, v59
	v_lshlrev_b32_e32 v56, 16, v60
	v_and_b32_e32 v58, 0xffff0000, v60
	v_lshlrev_b32_e32 v112, 16, v61
	v_and_b32_e32 v114, 0xffff0000, v61
	v_lshlrev_b32_e32 v116, 16, v62
	v_and_b32_e32 v118, 0xffff0000, v62
	v_lshlrev_b32_e32 v120, 16, v63
	v_and_b32_e32 v122, 0xffff0000, v63
	v_mul_f32_e32 v57, v56, v56
	v_mul_f32_e32 v59, v58, v58
	v_mul_f32_e32 v113, v112, v112
	v_mul_f32_e32 v115, v114, v114
	v_mul_f32_e32 v117, v116, v116
	v_mul_f32_e32 v119, v118, v118
	v_mul_f32_e32 v121, v120, v120
	v_mul_f32_e32 v123, v122, v122
	v_pk_add_f32 v[56:57], v[56:57], v[58:59]
	v_pk_add_f32 v[58:59], v[112:113], v[114:115]
	v_pk_add_f32 v[112:113], v[120:121], v[122:123]
	v_pk_add_f32 v[56:57], v[56:57], v[58:59]
	v_pk_add_f32 v[58:59], v[116:117], v[118:119]
	global_store_dwordx4 v104, v[60:63], s[16:17]
	v_pk_add_f32 v[58:59], v[58:59], v[112:113]
	s_nop 0
	v_pk_add_f32 v[56:57], v[56:57], v[58:59]
	v_mov_b32_e32 v58, v165
	v_mov_b32_e32 v59, v165
	s_nop 0
	v_mov_b32_dpp v58, v56 quad_perm:[1,0,3,2] row_mask:0xf bank_mask:0xf
	v_mov_b32_dpp v59, v57 quad_perm:[1,0,3,2] row_mask:0xf bank_mask:0xf
	v_pk_add_f32 v[56:57], v[56:57], v[58:59]
	ds_bpermute_b32 v58, v207, v56
	ds_bpermute_b32 v59, v207, v57
	s_waitcnt lgkmcnt(0)
	v_pk_add_f32 v[56:57], v[56:57], v[58:59]
	ds_bpermute_b32 v58, v208, v56
	ds_bpermute_b32 v59, v208, v57
	s_and_saveexec_b64 s[56:57], s[12:13]
	s_cbranch_execz .LBB0_1715
	s_waitcnt lgkmcnt(0)
	v_pk_add_f32 v[56:57], v[56:57], v[58:59]
	v_add_co_u32_e32 v58, vcc, 0x10000, v186
	s_nop 1
	v_addc_co_u32_e32 v59, vcc, 0, v187, vcc
	global_store_dwordx2 v[58:59], v[56:57], off

; __device__ __forceinline__ u32x4 pack8f(f32x4 a, f32x4 b) { u32x4 w; w.x = cvt_pk_bf16(a[0], a[1]); w.y = cvt_pk_bf16(a[2], a[3]); w.z = cvt_pk_bf16(b[0], b[1]); w.w = cvt_pk_bf16(b[2], b[3]); return w; }
;     __device__ __forceinline__ void operator()(const f32x4 (&acc)[2][2][4][2], const Unit& u, int wr, int wc, int fr, int fq, const EpiCtx& X) const {
;     ...
;             for (int m = 0; m < 4; ++m) {
;                 const int rl = ai * HALF + m * 16; const unsigned off = lo + (unsigned)(rl * 64) * 2u;
;                 const f32x4 o0a = acc[ai][0][m][0], o0b = acc[ai][0][m][1], o1a = acc[ai][1][m][0], o1b = acc[ai][1][m][1];
;                 const f32x4 ra_ = dpp_swap1(odd ? o0a : o1a), rb_ = dpp_swap1(odd ? o0b : o1b);
;                 const f32x4 pa[2] = {odd ? ra_ : o0a, odd ? o1a : ra_}, pb[2] = {odd ? rb_ : o0b, odd ? o1b : rb_};
; #pragma unroll
;                 for (int q = 0; q < 2; ++q) {
;                     const u32x4 w0 = raw[2 * m + q];
;                     const f32x4 r0 = (f32x4){bf_lo(w0.x), bf_hi(w0.x), bf_lo(w0.y), bf_hi(w0.y)}, r1 = (f32x4){bf_lo(w0.z), bf_hi(w0.z), bf_lo(w0.w), bf_hi(w0.w)};
;                     f32x4 y0, y1;
;                     if (RESN) { const f32x2 t = tbl[rl + q]; const float mu = t.x, ra = t.y * ALPHA; y0 = (r0 - mu) * ra * g0 + b0 + pa[q]; y1 = (r1 - mu) * ra * g1 + b1 + pb[q]; }
;                     else { y0 = r0 * ALPHA + pa[q]; y1 = r1 * ALPHA + pb[q]; }
;                     { const u32x4 w = pack8f(y0, y1); *(u32x4*)(xb + off + q * 128) = w;
;                         y0 = (f32x4){bf_lo(w.x), bf_hi(w.x), bf_lo(w.y), bf_hi(w.y)}; y1 = (f32x4){bf_lo(w.z), bf_hi(w.z), bf_lo(w.w), bf_hi(w.w)}; }
;                     float sa = ((y0[0] + y0[1]) + (y0[2] + y0[3])) + ((y1[0] + y1[1]) + (y1[2] + y1[3]));
;                     float sb = ((y0[0] * y0[0] + y0[1] * y0[1]) + (y0[2] * y0[2] + y0[3] * y0[3])) + ((y1[0] * y1[0] + y1[1] * y1[1]) + (y1[2] * y1[2] + y1[3] * y1[3]));
;                     sa += dpp_x1(sa);
;                     sb += dpp_x1(sb);
;                     sa += __shfl_xor(sa, 16); sa += __shfl_xor(sa, 32); sb += __shfl_xor(sb, 16); sb += __shfl_xor(sb, 32);
;                     if (fq == 0 && !odd) ps[(size_t)(rl + q) * 64] = (f32x2){sa, sb};
.LBB0_1717:
	s_or_b64 exec, exec, s[56:57]
	s_waitcnt lgkmcnt(1)
	v_cndmask_b32_e64 v50, v44, v36, s[6:7]
	s_nop 0
	v_cndmask_b32_e64 v49, v45, v37, s[6:7]
	s_waitcnt lgkmcnt(0)
	v_cndmask_b32_e64 v51, v46, v38, s[6:7]
	v_mov_b32_dpp v48, v50 quad_perm:[1,0,3,2] row_mask:0xf bank_mask:0xf
	s_nop 0
	v_cndmask_b32_e64 v52, v47, v39, s[6:7]
	v_cndmask_b32_e64 v54, v40, v32, s[6:7]
	v_mov_b32_dpp v50, v49 quad_perm:[1,0,3,2] row_mask:0xf bank_mask:0xf
	s_nop 0
	v_cndmask_b32_e64 v53, v41, v33, s[6:7]
	v_cndmask_b32_e64 v55, v42, v34, s[6:7]
	v_mov_b32_dpp v49, v51 quad_perm:[1,0,3,2] row_mask:0xf bank_mask:0xf
	s_nop 0
	v_cndmask_b32_e64 v56, v43, v35, s[6:7]
	v_lshlrev_b32_e32 v59, 16, v92
	v_mov_b32_dpp v51, v52 quad_perm:[1,0,3,2] row_mask:0xf bank_mask:0xf
	s_nop 0
	v_and_b32_e32 v60, 0xffff0000, v92
	v_cndmask_b32_e64 v45, v50, v45, s[6:7]
	v_mov_b32_dpp v52, v54 quad_perm:[1,0,3,2] row_mask:0xf bank_mask:0xf
	s_nop 0
	v_cndmask_b32_e64 v44, v48, v44, s[6:7]
	v_lshlrev_b32_e32 v62, 16, v93
	v_mov_b32_dpp v54, v53 quad_perm:[1,0,3,2] row_mask:0xf bank_mask:0xf
	s_nop 0
	v_and_b32_e32 v63, 0xffff0000, v93
	v_lshlrev_b32_e32 v92, 16, v94
	v_mov_b32_dpp v53, v55 quad_perm:[1,0,3,2] row_mask:0xf bank_mask:0xf
	s_nop 0
	v_and_b32_e32 v93, 0xffff0000, v94
	v_lshlrev_b32_e32 v94, 16, v95
	v_mov_b32_dpp v55, v56 quad_perm:[1,0,3,2] row_mask:0xf bank_mask:0xf
	ds_read_b64 v[56:57], v201 offset:1152
	v_and_b32_e32 v95, 0xffff0000, v95
	v_cndmask_b32_e64 v47, v51, v47, s[6:7]
	v_cndmask_b32_e64 v46, v49, v46, s[6:7]
	v_cndmask_b32_e64 v41, v54, v41, s[6:7]
	s_waitcnt lgkmcnt(0)
	v_mul_f32_e32 v58, 0x3fb504f3, v57
	v_sub_f32_e32 v61, v60, v56
	v_sub_f32_e32 v60, v59, v56
	v_pk_mul_f32 v[60:61], v[60:61], v[58:59] op_sel_hi:[1,0]
	v_sub_f32_e32 v63, v63, v56
	v_pk_fma_f32 v[60:61], v[76:77], v[60:61], v[184:185]
	v_sub_f32_e32 v62, v62, v56
	v_pk_add_f32 v[44:45], v[44:45], v[60:61]
	v_sub_f32_e32 v61, v93, v56
	v_sub_f32_e32 v60, v92, v56
	v_sub_f32_e32 v57, v95, v56
	v_sub_f32_e32 v56, v94, v56
	v_pk_mul_f32 v[62:63], v[62:63], v[58:59] op_sel_hi:[1,0]
	v_pk_mul_f32 v[56:57], v[56:57], v[58:59] op_sel_hi:[1,0]
	v_pk_mul_f32 v[58:59], v[60:61], v[58:59] op_sel_hi:[1,0]
	v_cndmask_b32_e64 v40, v52, v40, s[6:7]
	v_cndmask_b32_e64 v43, v55, v43, s[6:7]
	v_cndmask_b32_e64 v42, v53, v42, s[6:7]
	v_pk_fma_f32 v[62:63], v[78:79], v[62:63], v[182:183]
	v_pk_fma_f32 v[58:59], v[72:73], v[58:59], v[180:181]
	v_pk_fma_f32 v[56:57], v[74:75], v[56:57], v[178:179]
	v_pk_add_f32 v[46:47], v[46:47], v[62:63]
	v_pk_add_f32 v[42:43], v[42:43], v[56:57]
	v_pk_add_f32 v[40:41], v[40:41], v[58:59]
	v_cvt_pk_bf16_f32 v56, v44, v45
	v_cvt_pk_bf16_f32 v57, v46, v47
	v_mov_b32_e32 v103, v165
	v_cvt_pk_bf16_f32 v58, v40, v41
	v_cvt_pk_bf16_f32 v59, v42, v43
	v_lshlrev_b32_e32 v40, 16, v56
	v_and_b32_e32 v42, 0xffff0000, v56
	v_lshlrev_b32_e32 v44, 16, v57
	v_and_b32_e32 v46, 0xffff0000, v57
	v_lshlrev_b32_e32 v60, 16, v58
	v_and_b32_e32 v62, 0xffff0000, v58
	v_lshlrev_b32_e32 v92, 16, v59
	v_and_b32_e32 v94, 0xffff0000, v59
	v_mul_f32_e32 v41, v40, v40
	v_mul_f32_e32 v43, v42, v42
	v_mul_f32_e32 v45, v44, v44
	v_mul_f32_e32 v47, v46, v46
	v_mul_f32_e32 v61, v60, v60
	v_mul_f32_e32 v63, v62, v62
	v_mul_f32_e32 v93, v92, v92
	v_mul_f32_e32 v95, v94, v94
	v_pk_add_f32 v[40:41], v[40:41], v[42:43]
	v_pk_add_f32 v[42:43], v[44:45], v[46:47]
	v_pk_add_f32 v[44:45], v[92:93], v[94:95]
	v_pk_add_f32 v[40:41], v[40:41], v[42:43]
	v_pk_add_f32 v[42:43], v[60:61], v[62:63]
	s_nop 0
	v_pk_add_f32 v[42:43], v[42:43], v[44:45]
	s_nop 0
	v_pk_add_f32 v[40:41], v[40:41], v[42:43]
	v_mov_b32_e32 v42, v165
	v_mov_b32_e32 v43, v165
	s_nop 0
	v_mov_b32_dpp v42, v40 quad_perm:[1,0,3,2] row_mask:0xf bank_mask:0xf
	v_mov_b32_dpp v43, v41 quad_perm:[1,0,3,2] row_mask:0xf bank_mask:0xf
	v_pk_add_f32 v[40:41], v[40:41], v[42:43]
	ds_bpermute_b32 v42, v207, v40
	ds_bpermute_b32 v43, v207, v41
	s_waitcnt lgkmcnt(0)
	v_pk_add_f32 v[42:43], v[40:41], v[42:43]
	ds_bpermute_b32 v44, v208, v42
	ds_bpermute_b32 v45, v208, v43
	v_lshl_add_u64 v[40:41], s[16:17], 0, v[102:103]
	global_store_dwordx4 v[40:41], v[56:59], off
	s_and_saveexec_b64 s[56:57], s[12:13]
	s_cbranch_execz .LBB0_1719
	s_waitcnt lgkmcnt(0)
	v_pk_add_f32 v[42:43], v[42:43], v[44:45]
	v_add_co_u32_e32 v44, vcc, 0x12000, v186
	s_nop 1
	v_addc_co_u32_e32 v45, vcc, 0, v187, vcc
	global_store_dwordx2 v[44:45], v[42:43], off

; __device__ __forceinline__ u32x4 pack8f(f32x4 a, f32x4 b) { u32x4 w; w.x = cvt_pk_bf16(a[0], a[1]); w.y = cvt_pk_bf16(a[2], a[3]); w.z = cvt_pk_bf16(b[0], b[1]); w.w = cvt_pk_bf16(b[2], b[3]); return w; }
;     __device__ __forceinline__ void operator()(const f32x4 (&acc)[2][2][4][2], const Unit& u, int wr, int wc, int fr, int fq, const EpiCtx& X) const {
;     ...
;             for (int m = 0; m < 4; ++m) {
;                 const int rl = ai * HALF + m * 16; const unsigned off = lo + (unsigned)(rl * 64) * 2u;
;                 const f32x4 o0a = acc[ai][0][m][0], o0b = acc[ai][0][m][1], o1a = acc[ai][1][m][0], o1b = acc[ai][1][m][1];
;                 const f32x4 ra_ = dpp_swap1(odd ? o0a : o1a), rb_ = dpp_swap1(odd ? o0b : o1b);
;                 const f32x4 pa[2] = {odd ? ra_ : o0a, odd ? o1a : ra_}, pb[2] = {odd ? rb_ : o0b, odd ? o1b : rb_};
; #pragma unroll
;                 for (int q = 0; q < 2; ++q) {
;                     const u32x4 w0 = raw[2 * m + q];
;                     const f32x4 r0 = (f32x4){bf_lo(w0.x), bf_hi(w0.x), bf_lo(w0.y), bf_hi(w0.y)}, r1 = (f32x4){bf_lo(w0.z), bf_hi(w0.z), bf_lo(w0.w), bf_hi(w0.w)};
;                     f32x4 y0, y1;
;                     if (RESN) { const f32x2 t = tbl[rl + q]; const float mu = t.x, ra = t.y * ALPHA; y0 = (r0 - mu) * ra * g0 + b0 + pa[q]; y1 = (r1 - mu) * ra * g1 + b1 + pb[q]; }
;                     else { y0 = r0 * ALPHA + pa[q]; y1 = r1 * ALPHA + pb[q]; }
;                     { const u32x4 w = pack8f(y0, y1); *(u32x4*)(xb + off + q * 128) = w;
;                         y0 = (f32x4){bf_lo(w.x), bf_hi(w.x), bf_lo(w.y), bf_hi(w.y)}; y1 = (f32x4){bf_lo(w.z), bf_hi(w.z), bf_lo(w.w), bf_hi(w.w)}; }
;                     float sa = ((y0[0] + y0[1]) + (y0[2] + y0[3])) + ((y1[0] + y1[1]) + (y1[2] + y1[3]));
;                     float sb = ((y0[0] * y0[0] + y0[1] * y0[1]) + (y0[2] * y0[2] + y0[3] * y0[3])) + ((y1[0] * y1[0] + y1[1] * y1[1]) + (y1[2] * y1[2] + y1[3] * y1[3]));
;                     sa += dpp_x1(sa);
;                     sb += dpp_x1(sb);
;                     sa += __shfl_xor(sa, 16); sa += __shfl_xor(sa, 32); sb += __shfl_xor(sb, 16); sb += __shfl_xor(sb, 32);
;                     if (fq == 0 && !odd) ps[(size_t)(rl + q) * 64] = (f32x2){sa, sb};
.LBB0_1721:
	s_or_b64 exec, exec, s[56:57]
	s_waitcnt lgkmcnt(1)
	v_cndmask_b32_e64 v34, v28, v20, s[6:7]
	s_nop 0
	v_cndmask_b32_e64 v33, v29, v21, s[6:7]
	s_waitcnt lgkmcnt(0)
	v_cndmask_b32_e64 v35, v30, v22, s[6:7]
	v_mov_b32_dpp v32, v34 quad_perm:[1,0,3,2] row_mask:0xf bank_mask:0xf
	s_nop 0
	v_cndmask_b32_e64 v36, v31, v23, s[6:7]
	v_cndmask_b32_e64 v38, v24, v16, s[6:7]
	v_mov_b32_dpp v34, v33 quad_perm:[1,0,3,2] row_mask:0xf bank_mask:0xf
	s_nop 0
	v_cndmask_b32_e64 v37, v25, v17, s[6:7]
	v_cndmask_b32_e64 v39, v26, v18, s[6:7]
	v_mov_b32_dpp v33, v35 quad_perm:[1,0,3,2] row_mask:0xf bank_mask:0xf
	s_nop 0
	v_cndmask_b32_e64 v40, v27, v19, s[6:7]
	s_waitcnt vmcnt(11)
	v_lshlrev_b32_e32 v43, 16, v84
	v_mov_b32_dpp v35, v36 quad_perm:[1,0,3,2] row_mask:0xf bank_mask:0xf
	s_nop 0
	v_and_b32_e32 v44, 0xffff0000, v84
	v_cndmask_b32_e64 v29, v34, v29, s[6:7]
	v_mov_b32_dpp v36, v38 quad_perm:[1,0,3,2] row_mask:0xf bank_mask:0xf
	s_nop 0
	v_cndmask_b32_e64 v28, v32, v28, s[6:7]
	v_lshlrev_b32_e32 v46, 16, v85
	v_mov_b32_dpp v38, v37 quad_perm:[1,0,3,2] row_mask:0xf bank_mask:0xf
	s_nop 0
	v_and_b32_e32 v47, 0xffff0000, v85
	v_lshlrev_b32_e32 v48, 16, v86
	v_mov_b32_dpp v37, v39 quad_perm:[1,0,3,2] row_mask:0xf bank_mask:0xf
	s_nop 0
	v_and_b32_e32 v49, 0xffff0000, v86
	v_lshlrev_b32_e32 v50, 16, v87
	v_mov_b32_dpp v39, v40 quad_perm:[1,0,3,2] row_mask:0xf bank_mask:0xf
	ds_read_b64 v[40:41], v201 offset:1280
	v_and_b32_e32 v51, 0xffff0000, v87
	v_cndmask_b32_e64 v31, v35, v31, s[6:7]
	v_cndmask_b32_e64 v30, v33, v30, s[6:7]
	v_cndmask_b32_e64 v25, v38, v25, s[6:7]
	s_waitcnt lgkmcnt(0)
	v_mul_f32_e32 v42, 0x3fb504f3, v41
	v_sub_f32_e32 v45, v44, v40
	v_sub_f32_e32 v44, v43, v40
	v_pk_mul_f32 v[44:45], v[44:45], v[42:43] op_sel_hi:[1,0]
	v_sub_f32_e32 v47, v47, v40
	v_pk_fma_f32 v[44:45], v[76:77], v[44:45], v[184:185]
	v_sub_f32_e32 v46, v46, v40
	v_pk_add_f32 v[28:29], v[28:29], v[44:45]
	v_sub_f32_e32 v45, v49, v40
	v_sub_f32_e32 v44, v48, v40
	v_sub_f32_e32 v41, v51, v40
	v_sub_f32_e32 v40, v50, v40
	v_pk_mul_f32 v[46:47], v[46:47], v[42:43] op_sel_hi:[1,0]
	v_pk_mul_f32 v[40:41], v[40:41], v[42:43] op_sel_hi:[1,0]
	v_pk_mul_f32 v[42:43], v[44:45], v[42:43] op_sel_hi:[1,0]
	v_cndmask_b32_e64 v24, v36, v24, s[6:7]
	v_cndmask_b32_e64 v27, v39, v27, s[6:7]
	v_cndmask_b32_e64 v26, v37, v26, s[6:7]
	v_pk_fma_f32 v[46:47], v[78:79], v[46:47], v[182:183]
	v_pk_fma_f32 v[42:43], v[72:73], v[42:43], v[180:181]
	v_pk_fma_f32 v[40:41], v[74:75], v[40:41], v[178:179]
	v_pk_add_f32 v[30:31], v[30:31], v[46:47]
	v_pk_add_f32 v[26:27], v[26:27], v[40:41]
	v_pk_add_f32 v[24:25], v[24:25], v[42:43]
	v_cvt_pk_bf16_f32 v40, v28, v29
	v_cvt_pk_bf16_f32 v41, v30, v31
	v_mov_b32_e32 v101, v165
	v_cvt_pk_bf16_f32 v42, v24, v25
	v_cvt_pk_bf16_f32 v43, v26, v27
	v_lshlrev_b32_e32 v24, 16, v40
	v_and_b32_e32 v26, 0xffff0000, v40
	v_lshlrev_b32_e32 v28, 16, v41
	v_and_b32_e32 v30, 0xffff0000, v41
	v_lshlrev_b32_e32 v44, 16, v42
	v_and_b32_e32 v46, 0xffff0000, v42
	v_lshlrev_b32_e32 v48, 16, v43
	v_and_b32_e32 v50, 0xffff0000, v43
	v_mul_f32_e32 v25, v24, v24
	v_mul_f32_e32 v27, v26, v26
	v_mul_f32_e32 v29, v28, v28
	v_mul_f32_e32 v31, v30, v30
	v_mul_f32_e32 v45, v44, v44
	v_mul_f32_e32 v47, v46, v46
	v_mul_f32_e32 v49, v48, v48
	v_mul_f32_e32 v51, v50, v50
	v_pk_add_f32 v[24:25], v[24:25], v[26:27]
	v_pk_add_f32 v[26:27], v[28:29], v[30:31]
	v_pk_add_f32 v[28:29], v[48:49], v[50:51]
	v_pk_add_f32 v[24:25], v[24:25], v[26:27]
	v_pk_add_f32 v[26:27], v[44:45], v[46:47]
	s_nop 0
	v_pk_add_f32 v[26:27], v[26:27], v[28:29]
	s_nop 0
	v_pk_add_f32 v[24:25], v[24:25], v[26:27]
	v_mov_b32_e32 v26, v165
	v_mov_b32_e32 v27, v165
	s_nop 0
	v_mov_b32_dpp v26, v24 quad_perm:[1,0,3,2] row_mask:0xf bank_mask:0xf
	v_mov_b32_dpp v27, v25 quad_perm:[1,0,3,2] row_mask:0xf bank_mask:0xf
	v_pk_add_f32 v[24:25], v[24:25], v[26:27]
	ds_bpermute_b32 v26, v207, v24
	ds_bpermute_b32 v27, v207, v25
	s_waitcnt lgkmcnt(0)
	v_pk_add_f32 v[26:27], v[24:25], v[26:27]
	ds_bpermute_b32 v28, v208, v26
	ds_bpermute_b32 v29, v208, v27
	v_lshl_add_u64 v[24:25], s[16:17], 0, v[100:101]
	global_store_dwordx4 v[24:25], v[40:43], off
	s_and_saveexec_b64 s[56:57], s[12:13]
	s_cbranch_execz .LBB0_1723
	s_waitcnt lgkmcnt(0)
	v_pk_add_f32 v[26:27], v[26:27], v[28:29]
	v_add_co_u32_e32 v28, vcc, 0x14000, v186
	s_nop 1
	v_addc_co_u32_e32 v29, vcc, 0, v187, vcc
	global_store_dwordx2 v[28:29], v[26:27], off

; __device__ __forceinline__ u32x4 pack8f(f32x4 a, f32x4 b) { u32x4 w; w.x = cvt_pk_bf16(a[0], a[1]); w.y = cvt_pk_bf16(a[2], a[3]); w.z = cvt_pk_bf16(b[0], b[1]); w.w = cvt_pk_bf16(b[2], b[3]); return w; }
;     __device__ __forceinline__ void operator()(const f32x4 (&acc)[2][2][4][2], const Unit& u, int wr, int wc, int fr, int fq, const EpiCtx& X) const {
;     ...
;             for (int m = 0; m < 4; ++m) {
;                 const int rl = ai * HALF + m * 16; const unsigned off = lo + (unsigned)(rl * 64) * 2u;
;                 const f32x4 o0a = acc[ai][0][m][0], o0b = acc[ai][0][m][1], o1a = acc[ai][1][m][0], o1b = acc[ai][1][m][1];
;                 const f32x4 ra_ = dpp_swap1(odd ? o0a : o1a), rb_ = dpp_swap1(odd ? o0b : o1b);
;                 const f32x4 pa[2] = {odd ? ra_ : o0a, odd ? o1a : ra_}, pb[2] = {odd ? rb_ : o0b, odd ? o1b : rb_};
; #pragma unroll
;                 for (int q = 0; q < 2; ++q) {
;                     const u32x4 w0 = raw[2 * m + q];
;                     const f32x4 r0 = (f32x4){bf_lo(w0.x), bf_hi(w0.x), bf_lo(w0.y), bf_hi(w0.y)}, r1 = (f32x4){bf_lo(w0.z), bf_hi(w0.z), bf_lo(w0.w), bf_hi(w0.w)};
;                     f32x4 y0, y1;
;                     if (RESN) { const f32x2 t = tbl[rl + q]; const float mu = t.x, ra = t.y * ALPHA; y0 = (r0 - mu) * ra * g0 + b0 + pa[q]; y1 = (r1 - mu) * ra * g1 + b1 + pb[q]; }
;                     else { y0 = r0 * ALPHA + pa[q]; y1 = r1 * ALPHA + pb[q]; }
;                     { const u32x4 w = pack8f(y0, y1); *(u32x4*)(xb + off + q * 128) = w;
;                         y0 = (f32x4){bf_lo(w.x), bf_hi(w.x), bf_lo(w.y), bf_hi(w.y)}; y1 = (f32x4){bf_lo(w.z), bf_hi(w.z), bf_lo(w.w), bf_hi(w.w)}; }
;                     float sa = ((y0[0] + y0[1]) + (y0[2] + y0[3])) + ((y1[0] + y1[1]) + (y1[2] + y1[3]));
;                     float sb = ((y0[0] * y0[0] + y0[1] * y0[1]) + (y0[2] * y0[2] + y0[3] * y0[3])) + ((y1[0] * y1[0] + y1[1] * y1[1]) + (y1[2] * y1[2] + y1[3] * y1[3]));
;                     sa += dpp_x1(sa);
;                     sb += dpp_x1(sb);
;                     sa += __shfl_xor(sa, 16); sa += __shfl_xor(sa, 32); sb += __shfl_xor(sb, 16); sb += __shfl_xor(sb, 32);
;                     if (fq == 0 && !odd) ps[(size_t)(rl + q) * 64] = (f32x2){sa, sb};
.LBB0_1725:
	s_or_b64 exec, exec, s[56:57]
	s_waitcnt lgkmcnt(1)
	v_cndmask_b32_e64 v18, v12, v4, s[6:7]
	s_nop 0
	v_cndmask_b32_e64 v17, v13, v5, s[6:7]
	s_waitcnt lgkmcnt(0)
	v_cndmask_b32_e64 v19, v14, v6, s[6:7]
	v_mov_b32_dpp v16, v18 quad_perm:[1,0,3,2] row_mask:0xf bank_mask:0xf
	s_nop 0
	v_cndmask_b32_e64 v20, v15, v7, s[6:7]
	v_cndmask_b32_e64 v22, v8, v0, s[6:7]
	v_mov_b32_dpp v18, v17 quad_perm:[1,0,3,2] row_mask:0xf bank_mask:0xf
	s_nop 0
	v_cndmask_b32_e64 v21, v9, v1, s[6:7]
	v_cndmask_b32_e64 v23, v10, v2, s[6:7]
	v_mov_b32_dpp v17, v19 quad_perm:[1,0,3,2] row_mask:0xf bank_mask:0xf
	s_nop 0
	v_cndmask_b32_e64 v24, v11, v3, s[6:7]
	s_waitcnt vmcnt(13)
	v_lshlrev_b32_e32 v27, 16, v68
	v_mov_b32_dpp v19, v20 quad_perm:[1,0,3,2] row_mask:0xf bank_mask:0xf
	s_nop 0
	v_and_b32_e32 v28, 0xffff0000, v68
	v_cndmask_b32_e64 v13, v18, v13, s[6:7]
	v_mov_b32_dpp v20, v22 quad_perm:[1,0,3,2] row_mask:0xf bank_mask:0xf
	s_nop 0
	v_cndmask_b32_e64 v12, v16, v12, s[6:7]
	v_lshlrev_b32_e32 v30, 16, v69
	v_mov_b32_dpp v22, v21 quad_perm:[1,0,3,2] row_mask:0xf bank_mask:0xf
	s_nop 0
	v_and_b32_e32 v31, 0xffff0000, v69
	v_lshlrev_b32_e32 v32, 16, v70
	v_mov_b32_dpp v21, v23 quad_perm:[1,0,3,2] row_mask:0xf bank_mask:0xf
	s_nop 0
	v_and_b32_e32 v33, 0xffff0000, v70
	v_lshlrev_b32_e32 v34, 16, v71
	v_mov_b32_dpp v23, v24 quad_perm:[1,0,3,2] row_mask:0xf bank_mask:0xf
	ds_read_b64 v[24:25], v201 offset:1408
	v_and_b32_e32 v35, 0xffff0000, v71
	v_cndmask_b32_e64 v15, v19, v15, s[6:7]
	v_cndmask_b32_e64 v14, v17, v14, s[6:7]
	v_cndmask_b32_e64 v9, v22, v9, s[6:7]
	s_waitcnt lgkmcnt(0)
	v_mul_f32_e32 v26, 0x3fb504f3, v25
	v_sub_f32_e32 v29, v28, v24
	v_sub_f32_e32 v28, v27, v24
	v_pk_mul_f32 v[28:29], v[28:29], v[26:27] op_sel_hi:[1,0]
	v_sub_f32_e32 v31, v31, v24
	v_pk_fma_f32 v[28:29], v[76:77], v[28:29], v[184:185]
	v_sub_f32_e32 v30, v30, v24
	v_pk_add_f32 v[12:13], v[12:13], v[28:29]
	v_sub_f32_e32 v29, v33, v24
	v_sub_f32_e32 v28, v32, v24
	v_sub_f32_e32 v25, v35, v24
	v_sub_f32_e32 v24, v34, v24
	v_pk_mul_f32 v[30:31], v[30:31], v[26:27] op_sel_hi:[1,0]
	v_pk_mul_f32 v[24:25], v[24:25], v[26:27] op_sel_hi:[1,0]
	v_pk_mul_f32 v[26:27], v[28:29], v[26:27] op_sel_hi:[1,0]
	v_cndmask_b32_e64 v8, v20, v8, s[6:7]
	v_cndmask_b32_e64 v11, v23, v11, s[6:7]
	v_cndmask_b32_e64 v10, v21, v10, s[6:7]
	v_pk_fma_f32 v[30:31], v[78:79], v[30:31], v[182:183]
	v_pk_fma_f32 v[26:27], v[72:73], v[26:27], v[180:181]
	v_pk_fma_f32 v[24:25], v[74:75], v[24:25], v[178:179]
	v_pk_add_f32 v[14:15], v[14:15], v[30:31]
	v_pk_add_f32 v[10:11], v[10:11], v[24:25]
	v_pk_add_f32 v[8:9], v[8:9], v[26:27]
	v_cvt_pk_bf16_f32 v24, v12, v13
	v_cvt_pk_bf16_f32 v25, v14, v15
	s_nop 0
	v_cvt_pk_bf16_f32 v26, v8, v9
	v_cvt_pk_bf16_f32 v27, v10, v11
	v_lshlrev_b32_e32 v8, 16, v24
	v_and_b32_e32 v10, 0xffff0000, v24
	v_lshlrev_b32_e32 v12, 16, v25
	v_and_b32_e32 v14, 0xffff0000, v25
	v_lshlrev_b32_e32 v28, 16, v26
	v_and_b32_e32 v30, 0xffff0000, v26
	v_lshlrev_b32_e32 v32, 16, v27
	v_and_b32_e32 v34, 0xffff0000, v27
	v_mul_f32_e32 v9, v8, v8
	v_mul_f32_e32 v11, v10, v10
	v_mul_f32_e32 v13, v12, v12
	v_mul_f32_e32 v15, v14, v14
	v_mul_f32_e32 v29, v28, v28
	v_mul_f32_e32 v31, v30, v30
	v_mul_f32_e32 v33, v32, v32
	v_mul_f32_e32 v35, v34, v34
	v_pk_add_f32 v[8:9], v[8:9], v[10:11]
	v_pk_add_f32 v[10:11], v[12:13], v[14:15]
	v_pk_add_f32 v[12:13], v[32:33], v[34:35]
	v_pk_add_f32 v[8:9], v[8:9], v[10:11]
	v_pk_add_f32 v[10:11], v[28:29], v[30:31]
	s_nop 0
	v_pk_add_f32 v[10:11], v[10:11], v[12:13]
	s_nop 0
	v_pk_add_f32 v[8:9], v[8:9], v[10:11]
	v_mov_b32_e32 v10, v165
	v_mov_b32_e32 v11, v165
	s_nop 0
	v_mov_b32_dpp v10, v8 quad_perm:[1,0,3,2] row_mask:0xf bank_mask:0xf
	v_mov_b32_dpp v11, v9 quad_perm:[1,0,3,2] row_mask:0xf bank_mask:0xf
	v_pk_add_f32 v[8:9], v[8:9], v[10:11]
	ds_bpermute_b32 v10, v207, v8
	ds_bpermute_b32 v11, v207, v9
	s_waitcnt lgkmcnt(0)
	v_pk_add_f32 v[10:11], v[8:9], v[10:11]
	ds_bpermute_b32 v12, v208, v10
	ds_bpermute_b32 v13, v208, v11
	v_lshl_add_u64 v[8:9], s[16:17], 0, v[164:165]
	global_store_dwordx4 v[8:9], v[24:27], off
	s_and_saveexec_b64 s[16:17], s[12:13]
	s_cbranch_execz .LBB0_1727
	s_waitcnt lgkmcnt(0)
	v_pk_add_f32 v[10:11], v[10:11], v[12:13]
	v_add_co_u32_e32 v12, vcc, 0x16000, v186
	s_nop 1
	v_addc_co_u32_e32 v13, vcc, 0, v187, vcc
	global_store_dwordx2 v[12:13], v[10:11], off
